# prep ada GEMV + fp6 convert loads batched, expert gather pipelined, routing key loads batched, GEMM0 rope epilogue loads batched (11 of 16 blocks), attn Q cache
# speedup vs baseline: 1.0389x; 1.0389x over previous
; DI unsigned enc_e2m3(float x, float scale) {
;   const float a = fminf(fabsf(x) * scale, 7.5f);
;   float c;
;   if (a < 2.f) c = rintf(a * 8.f);
;   else if (a < 4.f) c = 16.f + rintf((a - 2.f) * 4.f);
;   else c = 24.f + rintf((a - 4.f) * 2.f);
; DI void job_convert6(const float* __restrict__ src, unsigned char* __restrict__ dst, int row0, float scale) {
;     ...
;   for (int i = 0; i < 4; ++i) {
;     const int row = row0 + wid * 4 + i;
;     const float* sp = src + (size_t)row * 2048 + lane * 16;
;     unsigned w[7] = {0u, 0u, 0u, 0u, 0u, 0u, 0u};
; #pragma unroll
;     for (int c = 0; c < 2; ++c)
; #pragma unroll
;       for (int q = 0; q < 4; ++q) {
;         const f32x4 v = *(const f32x4*)(sp + c * 1024 + q * 4);
; #pragma unroll
;         for (int e = 0; e < 4; ++e) {
;           const int j = c * 16 + q * 4 + e;
;           const unsigned code = enc_e2m3(v[e], scale);
.LBB0_59:
	v_lshl_add_u64 v[52:53], v[50:51], 0, s[8:9]
	v_add_co_u32_e32 v164, vcc, 0x1000, v52
	s_nop 1
	v_addc_co_u32_e32 v165, vcc, 0, v53, vcc
	global_load_dwordx4 v[100:103], v[164:165], off offset:-4096
	global_load_dwordx4 v[104:107], v[164:165], off offset:-4080
	global_load_dwordx4 v[108:111], v[164:165], off offset:-4064
	global_load_dwordx4 v[112:115], v[164:165], off offset:-4048
	global_load_dwordx4 v[116:119], v[164:165], off
	global_load_dwordx4 v[120:123], v[164:165], off offset:16
	global_load_dwordx4 v[124:127], v[164:165], off offset:32
	global_load_dwordx4 v[128:131], v[164:165], off offset:48
	v_add_co_u32_e32 v164, vcc, 0x3000, v52
	s_nop 1
	v_addc_co_u32_e32 v165, vcc, 0, v53, vcc
	global_load_dwordx4 v[132:135], v[164:165], off offset:-4096
	global_load_dwordx4 v[136:139], v[164:165], off offset:-4080
	global_load_dwordx4 v[140:143], v[164:165], off offset:-4064
	global_load_dwordx4 v[144:147], v[164:165], off offset:-4048
	global_load_dwordx4 v[148:151], v[164:165], off
	global_load_dwordx4 v[152:155], v[164:165], off offset:16
	global_load_dwordx4 v[156:159], v[164:165], off offset:32
	global_load_dwordx4 v[160:163], v[164:165], off offset:48
	s_waitcnt vmcnt(15)
	v_mov_b32_e32 v0, v100
	v_mov_b32_e32 v1, v101
	v_mov_b32_e32 v2, v102
	v_mov_b32_e32 v3, v103
	v_mul_f32_e64 v4, |v0|, s7
	v_min_f32_e32 v4, 0x40f00000, v4
	v_cmp_ngt_f32_e32 vcc, 2.0, v4
	s_and_saveexec_b64 s[10:11], vcc
	s_xor_b64 s[10:11], exec, s[10:11]
	s_cbranch_execz .LBB0_65
	v_cmp_ngt_f32_e32 vcc, 4.0, v4
	s_and_saveexec_b64 s[12:13], vcc
	s_xor_b64 s[12:13], exec, s[12:13]
	v_add_f32_e32 v4, -4.0, v4
	v_add_f32_e32 v4, v4, v4
	v_rndne_f32_e32 v4, v4
	v_add_f32_e32 v54, 0x41c00000, v4
	s_andn2_saveexec_b64 s[12:13], s[12:13]
	v_add_f32_e32 v4, -2.0, v4
	v_mul_f32_e32 v4, 4.0, v4
	v_rndne_f32_e32 v4, v4
	v_add_f32_e32 v54, 0x41800000, v4
	s_or_b64 exec, exec, s[12:13]

; DI unsigned enc_e2m3(float x, float scale) {
;   const float a = fminf(fabsf(x) * scale, 7.5f);
;   float c;
;   if (a < 2.f) c = rintf(a * 8.f);
;   else if (a < 4.f) c = 16.f + rintf((a - 2.f) * 4.f);
;   else c = 24.f + rintf((a - 4.f) * 2.f);
; DI void job_convert6(const float* __restrict__ src, unsigned char* __restrict__ dst, int row0, float scale) {
;     ...
;         const f32x4 v = *(const f32x4*)(sp + c * 1024 + q * 4);
; #pragma unroll
;         for (int e = 0; e < 4; ++e) {
;           const int j = c * 16 + q * 4 + e;
;           const unsigned code = enc_e2m3(v[e], scale);
.LBB0_89:
	s_andn2_saveexec_b64 s[10:11], s[10:11]
	v_mul_f32_e32 v4, 0x41000000, v4
	v_rndne_f32_e32 v57, v4
	s_or_b64 exec, exec, s[10:11]
	s_waitcnt vmcnt(14)
	v_mov_b32_e32 v4, v104
	v_mov_b32_e32 v5, v105
	v_mov_b32_e32 v6, v106
	v_mov_b32_e32 v7, v107
	v_mul_f32_e64 v8, |v4|, s7
	v_min_f32_e32 v8, 0x40f00000, v8
	v_cmp_ngt_f32_e32 vcc, 2.0, v8
	s_and_saveexec_b64 s[10:11], vcc
	s_xor_b64 s[10:11], exec, s[10:11]
	s_cbranch_execz .LBB0_97
	v_cmp_ngt_f32_e32 vcc, 4.0, v8
	s_and_saveexec_b64 s[12:13], vcc
	s_xor_b64 s[12:13], exec, s[12:13]
	v_add_f32_e32 v8, -4.0, v8
	v_add_f32_e32 v8, v8, v8
	v_rndne_f32_e32 v8, v8
	v_add_f32_e32 v68, 0x41c00000, v8
	s_andn2_saveexec_b64 s[12:13], s[12:13]
	v_add_f32_e32 v8, -2.0, v8
	v_mul_f32_e32 v8, 4.0, v8
	v_rndne_f32_e32 v8, v8
	v_add_f32_e32 v68, 0x41800000, v8
	s_or_b64 exec, exec, s[12:13]

; DI unsigned enc_e2m3(float x, float scale) {
;   const float a = fminf(fabsf(x) * scale, 7.5f);
;   float c;
;   if (a < 2.f) c = rintf(a * 8.f);
;   else if (a < 4.f) c = 16.f + rintf((a - 2.f) * 4.f);
;   else c = 24.f + rintf((a - 4.f) * 2.f);
; DI void job_convert6(const float* __restrict__ src, unsigned char* __restrict__ dst, int row0, float scale) {
;     ...
;         const f32x4 v = *(const f32x4*)(sp + c * 1024 + q * 4);
; #pragma unroll
;         for (int e = 0; e < 4; ++e) {
;           const int j = c * 16 + q * 4 + e;
;           const unsigned code = enc_e2m3(v[e], scale);
.LBB0_121:
	s_andn2_saveexec_b64 s[10:11], s[10:11]
	v_mul_f32_e32 v8, 0x41000000, v8
	v_rndne_f32_e32 v71, v8
	s_or_b64 exec, exec, s[10:11]
	s_waitcnt vmcnt(13)
	v_mov_b32_e32 v8, v108
	v_mov_b32_e32 v9, v109
	v_mov_b32_e32 v10, v110
	v_mov_b32_e32 v11, v111
	v_mul_f32_e64 v12, |v8|, s7
	v_min_f32_e32 v12, 0x40f00000, v12
	v_cmp_ngt_f32_e32 vcc, 2.0, v12
	s_and_saveexec_b64 s[10:11], vcc
	s_xor_b64 s[10:11], exec, s[10:11]
	s_cbranch_execz .LBB0_129
	v_cmp_ngt_f32_e32 vcc, 4.0, v12
	s_and_saveexec_b64 s[12:13], vcc
	s_xor_b64 s[12:13], exec, s[12:13]
	v_add_f32_e32 v12, -4.0, v12
	v_add_f32_e32 v12, v12, v12
	v_rndne_f32_e32 v12, v12
	v_add_f32_e32 v72, 0x41c00000, v12
	s_andn2_saveexec_b64 s[12:13], s[12:13]
	v_add_f32_e32 v12, -2.0, v12
	v_mul_f32_e32 v12, 4.0, v12
	v_rndne_f32_e32 v12, v12
	v_add_f32_e32 v72, 0x41800000, v12
	s_or_b64 exec, exec, s[12:13]

; DI unsigned enc_e2m3(float x, float scale) {
;   const float a = fminf(fabsf(x) * scale, 7.5f);
;   float c;
;   if (a < 2.f) c = rintf(a * 8.f);
;   else if (a < 4.f) c = 16.f + rintf((a - 2.f) * 4.f);
;   else c = 24.f + rintf((a - 4.f) * 2.f);
; DI void job_convert6(const float* __restrict__ src, unsigned char* __restrict__ dst, int row0, float scale) {
;     ...
;         const f32x4 v = *(const f32x4*)(sp + c * 1024 + q * 4);
; #pragma unroll
;         for (int e = 0; e < 4; ++e) {
;           const int j = c * 16 + q * 4 + e;
;           const unsigned code = enc_e2m3(v[e], scale);
.LBB0_153:
	s_andn2_saveexec_b64 s[10:11], s[10:11]
	v_mul_f32_e32 v12, 0x41000000, v12
	v_rndne_f32_e32 v75, v12
	s_or_b64 exec, exec, s[10:11]
	s_waitcnt vmcnt(12)
	v_mov_b32_e32 v12, v112
	v_mov_b32_e32 v13, v113
	v_mov_b32_e32 v14, v114
	v_mov_b32_e32 v15, v115
	v_mul_f32_e64 v16, |v12|, s7
	v_min_f32_e32 v16, 0x40f00000, v16
	v_cmp_ngt_f32_e32 vcc, 2.0, v16
	s_and_saveexec_b64 s[10:11], vcc
	s_xor_b64 s[10:11], exec, s[10:11]
	s_cbranch_execz .LBB0_161
	v_cmp_ngt_f32_e32 vcc, 4.0, v16
	s_and_saveexec_b64 s[12:13], vcc
	s_xor_b64 s[12:13], exec, s[12:13]
	v_add_f32_e32 v16, -4.0, v16
	v_add_f32_e32 v16, v16, v16
	v_rndne_f32_e32 v16, v16
	v_add_f32_e32 v76, 0x41c00000, v16
	s_andn2_saveexec_b64 s[12:13], s[12:13]
	v_add_f32_e32 v16, -2.0, v16
	v_mul_f32_e32 v16, 4.0, v16
	v_rndne_f32_e32 v16, v16
	v_add_f32_e32 v76, 0x41800000, v16
	s_or_b64 exec, exec, s[12:13]

; DI unsigned enc_e2m3(float x, float scale) {
;   const float a = fminf(fabsf(x) * scale, 7.5f);
;   float c;
;   if (a < 2.f) c = rintf(a * 8.f);
;   else if (a < 4.f) c = 16.f + rintf((a - 2.f) * 4.f);
;   else c = 24.f + rintf((a - 4.f) * 2.f);
; DI void job_convert6(const float* __restrict__ src, unsigned char* __restrict__ dst, int row0, float scale) {
;     ...
;         const f32x4 v = *(const f32x4*)(sp + c * 1024 + q * 4);
; #pragma unroll
;         for (int e = 0; e < 4; ++e) {
;           const int j = c * 16 + q * 4 + e;
;           const unsigned code = enc_e2m3(v[e], scale);
.LBB0_185:
	s_andn2_saveexec_b64 s[10:11], s[10:11]
	v_mul_f32_e32 v16, 0x41000000, v16
	v_rndne_f32_e32 v79, v16
	s_or_b64 exec, exec, s[10:11]
	v_add_co_u32_e32 v16, vcc, 0x1000, v52
	s_nop 1
	v_addc_co_u32_e32 v17, vcc, 0, v53, vcc
	s_waitcnt vmcnt(11)
	v_mov_b32_e32 v16, v116
	v_mov_b32_e32 v17, v117
	v_mov_b32_e32 v18, v118
	v_mov_b32_e32 v19, v119
	v_mul_f32_e64 v20, |v16|, s7
	v_min_f32_e32 v20, 0x40f00000, v20
	v_cmp_ngt_f32_e32 vcc, 2.0, v20
	s_and_saveexec_b64 s[10:11], vcc
	s_xor_b64 s[10:11], exec, s[10:11]
	s_cbranch_execz .LBB0_193
	v_cmp_ngt_f32_e32 vcc, 4.0, v20
	s_and_saveexec_b64 s[12:13], vcc
	s_xor_b64 s[12:13], exec, s[12:13]
	v_add_f32_e32 v20, -4.0, v20
	v_add_f32_e32 v20, v20, v20
	v_rndne_f32_e32 v20, v20
	v_add_f32_e32 v80, 0x41c00000, v20
	s_andn2_saveexec_b64 s[12:13], s[12:13]
	v_add_f32_e32 v20, -2.0, v20
	v_mul_f32_e32 v20, 4.0, v20
	v_rndne_f32_e32 v20, v20
	v_add_f32_e32 v80, 0x41800000, v20
	s_or_b64 exec, exec, s[12:13]

; DI unsigned enc_e2m3(float x, float scale) {
;   const float a = fminf(fabsf(x) * scale, 7.5f);
;   float c;
;   if (a < 2.f) c = rintf(a * 8.f);
;   else if (a < 4.f) c = 16.f + rintf((a - 2.f) * 4.f);
;   else c = 24.f + rintf((a - 4.f) * 2.f);
; DI void job_convert6(const float* __restrict__ src, unsigned char* __restrict__ dst, int row0, float scale) {
;     ...
;         const f32x4 v = *(const f32x4*)(sp + c * 1024 + q * 4);
; #pragma unroll
;         for (int e = 0; e < 4; ++e) {
;           const int j = c * 16 + q * 4 + e;
;           const unsigned code = enc_e2m3(v[e], scale);
.LBB0_217:
	s_andn2_saveexec_b64 s[10:11], s[10:11]
	v_mul_f32_e32 v20, 0x41000000, v20
	v_rndne_f32_e32 v83, v20
	s_or_b64 exec, exec, s[10:11]
	v_add_co_u32_e32 v20, vcc, 0x1000, v52
	s_nop 1
	v_addc_co_u32_e32 v21, vcc, 0, v53, vcc
	s_waitcnt vmcnt(10)
	v_mov_b32_e32 v20, v120
	v_mov_b32_e32 v21, v121
	v_mov_b32_e32 v22, v122
	v_mov_b32_e32 v23, v123
	v_mul_f32_e64 v24, |v20|, s7
	v_min_f32_e32 v24, 0x40f00000, v24
	v_cmp_ngt_f32_e32 vcc, 2.0, v24
	s_and_saveexec_b64 s[10:11], vcc
	s_xor_b64 s[10:11], exec, s[10:11]
	s_cbranch_execz .LBB0_225
	v_cmp_ngt_f32_e32 vcc, 4.0, v24
	s_and_saveexec_b64 s[12:13], vcc
	s_xor_b64 s[12:13], exec, s[12:13]
	v_add_f32_e32 v24, -4.0, v24
	v_add_f32_e32 v24, v24, v24
	v_rndne_f32_e32 v24, v24
	v_add_f32_e32 v84, 0x41c00000, v24
	s_andn2_saveexec_b64 s[12:13], s[12:13]
	v_add_f32_e32 v24, -2.0, v24
	v_mul_f32_e32 v24, 4.0, v24
	v_rndne_f32_e32 v24, v24
	v_add_f32_e32 v84, 0x41800000, v24
	s_or_b64 exec, exec, s[12:13]

; DI unsigned enc_e2m3(float x, float scale) {
;   const float a = fminf(fabsf(x) * scale, 7.5f);
;   float c;
;   if (a < 2.f) c = rintf(a * 8.f);
;   else if (a < 4.f) c = 16.f + rintf((a - 2.f) * 4.f);
;   else c = 24.f + rintf((a - 4.f) * 2.f);
; DI void job_convert6(const float* __restrict__ src, unsigned char* __restrict__ dst, int row0, float scale) {
;     ...
;         const f32x4 v = *(const f32x4*)(sp + c * 1024 + q * 4);
; #pragma unroll
;         for (int e = 0; e < 4; ++e) {
;           const int j = c * 16 + q * 4 + e;
;           const unsigned code = enc_e2m3(v[e], scale);
.LBB0_249:
	s_andn2_saveexec_b64 s[10:11], s[10:11]
	v_mul_f32_e32 v24, 0x41000000, v24
	v_rndne_f32_e32 v87, v24
	s_or_b64 exec, exec, s[10:11]
	v_add_co_u32_e32 v24, vcc, 0x1000, v52
	s_nop 1
	v_addc_co_u32_e32 v25, vcc, 0, v53, vcc
	s_waitcnt vmcnt(9)
	v_mov_b32_e32 v24, v124
	v_mov_b32_e32 v25, v125
	v_mov_b32_e32 v26, v126
	v_mov_b32_e32 v27, v127
	v_mul_f32_e64 v28, |v24|, s7
	v_min_f32_e32 v28, 0x40f00000, v28
	v_cmp_ngt_f32_e32 vcc, 2.0, v28
	s_and_saveexec_b64 s[10:11], vcc
	s_xor_b64 s[10:11], exec, s[10:11]
	s_cbranch_execz .LBB0_257
	v_cmp_ngt_f32_e32 vcc, 4.0, v28
	s_and_saveexec_b64 s[12:13], vcc
	s_xor_b64 s[12:13], exec, s[12:13]
	v_add_f32_e32 v28, -4.0, v28
	v_add_f32_e32 v28, v28, v28
	v_rndne_f32_e32 v28, v28
	v_add_f32_e32 v88, 0x41c00000, v28
	s_andn2_saveexec_b64 s[12:13], s[12:13]
	v_add_f32_e32 v28, -2.0, v28
	v_mul_f32_e32 v28, 4.0, v28
	v_rndne_f32_e32 v28, v28
	v_add_f32_e32 v88, 0x41800000, v28
	s_or_b64 exec, exec, s[12:13]

; DI unsigned enc_e2m3(float x, float scale) {
;   const float a = fminf(fabsf(x) * scale, 7.5f);
;   float c;
;   if (a < 2.f) c = rintf(a * 8.f);
;   else if (a < 4.f) c = 16.f + rintf((a - 2.f) * 4.f);
;   else c = 24.f + rintf((a - 4.f) * 2.f);
; DI void job_convert6(const float* __restrict__ src, unsigned char* __restrict__ dst, int row0, float scale) {
;     ...
;         const f32x4 v = *(const f32x4*)(sp + c * 1024 + q * 4);
; #pragma unroll
;         for (int e = 0; e < 4; ++e) {
;           const int j = c * 16 + q * 4 + e;
;           const unsigned code = enc_e2m3(v[e], scale);
.LBB0_281:
	s_andn2_saveexec_b64 s[10:11], s[10:11]
	v_mul_f32_e32 v28, 0x41000000, v28
	v_rndne_f32_e32 v92, v28
	s_or_b64 exec, exec, s[10:11]
	v_add_co_u32_e32 v28, vcc, 0x1000, v52
	s_nop 1
	v_addc_co_u32_e32 v29, vcc, 0, v53, vcc
	s_waitcnt vmcnt(8)
	v_mov_b32_e32 v28, v128
	v_mov_b32_e32 v29, v129
	v_mov_b32_e32 v30, v130
	v_mov_b32_e32 v31, v131
	v_mul_f32_e64 v90, |v28|, s7
	v_min_f32_e32 v90, 0x40f00000, v90
	v_cmp_ngt_f32_e32 vcc, 2.0, v90
	s_and_saveexec_b64 s[10:11], vcc
	s_xor_b64 s[10:11], exec, s[10:11]
	s_cbranch_execz .LBB0_289
	v_cmp_ngt_f32_e32 vcc, 4.0, v90
	s_and_saveexec_b64 s[12:13], vcc
	s_xor_b64 s[12:13], exec, s[12:13]
	v_add_f32_e32 v90, -4.0, v90
	v_add_f32_e32 v90, v90, v90
	v_rndne_f32_e32 v90, v90
	v_add_f32_e32 v93, 0x41c00000, v90
	s_andn2_saveexec_b64 s[12:13], s[12:13]
	v_add_f32_e32 v90, -2.0, v90
	v_mul_f32_e32 v90, 4.0, v90
	v_rndne_f32_e32 v90, v90
	v_add_f32_e32 v93, 0x41800000, v90
	s_or_b64 exec, exec, s[12:13]

; DI unsigned enc_e2m3(float x, float scale) {
;   const float a = fminf(fabsf(x) * scale, 7.5f);
;   float c;
;   if (a < 2.f) c = rintf(a * 8.f);
;   else if (a < 4.f) c = 16.f + rintf((a - 2.f) * 4.f);
;   else c = 24.f + rintf((a - 4.f) * 2.f);
;   unsigned ci = (unsigned)c; ci = ci > 31u ? 31u : ci;
;   return ci | ((__float_as_uint(x) >> 31) << 5);
; DI void job_convert6(const float* __restrict__ src, unsigned char* __restrict__ dst, int row0, float scale) {
;     ...
;         for (int e = 0; e < 4; ++e) {
;           const int j = c * 16 + q * 4 + e;
;           const unsigned code = enc_e2m3(v[e], scale);
;           const int bit = 6 * j, wi = bit >> 5, sh = bit & 31;
;           w[wi] |= code << sh;
;           if (sh > 26) w[wi + 1] |= code >> (32 - sh);
;         }
;       }
;     unsigned char* dp = dst + (size_t)row * 1536;
;     *(u32x4*)(dp + lane * 16) = u32x4{w[0], w[1], w[2], w[3]};
;     *(u32x2*)(dp + 1024 + lane * 8) = u32x2{w[4], w[5]};
.LBB0_313:
	s_andn2_saveexec_b64 s[10:11], s[10:11]
	v_mul_f32_e32 v90, 0x41000000, v96
	v_rndne_f32_e32 v90, v90
	s_or_b64 exec, exec, s[10:11]
	v_cvt_u32_f32_e32 v91, v91
	v_cvt_u32_f32_e32 v92, v92
	v_lshrrev_b32_e32 v26, 26, v26
	v_lshrrev_b32_e32 v27, 26, v27
	v_min_u32_e32 v91, 31, v91
	v_and_or_b32 v26, v26, 32, v91
	v_min_u32_e32 v92, 31, v92
	v_lshrrev_b32_e32 v26, 4, v26
	v_and_or_b32 v27, v27, 32, v92
	v_lshl_or_b32 v26, v27, 2, v26
	v_cvt_u32_f32_e32 v27, v93
	v_lshrrev_b32_e32 v28, 26, v28
	v_lshrrev_b32_e32 v21, 26, v21
	v_lshrrev_b32_e32 v22, 26, v22
	v_min_u32_e32 v27, 31, v27
	v_and_or_b32 v27, v28, 32, v27
	v_lshl_or_b32 v26, v27, 8, v26
	v_cvt_u32_f32_e32 v27, v94
	v_lshrrev_b32_e32 v28, 26, v29
	v_lshrrev_b32_e32 v23, 26, v23
	v_lshrrev_b32_e32 v16, 26, v16
	v_min_u32_e32 v27, 31, v27
	v_and_or_b32 v27, v28, 32, v27
	v_lshl_or_b32 v26, v27, 14, v26
	v_cvt_u32_f32_e32 v27, v95
	v_lshrrev_b32_e32 v28, 26, v30
	v_lshrrev_b32_e32 v17, 26, v17
	v_lshrrev_b32_e32 v18, 26, v18
	v_min_u32_e32 v27, 31, v27
	v_and_or_b32 v27, v28, 32, v27
	v_lshl_or_b32 v26, v27, 20, v26
	v_cvt_u32_f32_e32 v27, v85
	v_cvt_u32_f32_e32 v28, v86
	v_lshrrev_b32_e32 v10, 26, v10
	v_lshrrev_b32_e32 v11, 26, v11
	v_min_u32_e32 v27, 31, v27
	v_and_or_b32 v21, v21, 32, v27
	v_min_u32_e32 v28, 31, v28
	v_lshrrev_b32_e32 v21, 2, v21
	v_and_or_b32 v22, v22, 32, v28
	v_lshl_or_b32 v21, v22, 4, v21
	v_cvt_u32_f32_e32 v22, v87
	v_lshrrev_b32_e32 v12, 26, v12
	v_lshrrev_b32_e32 v5, 26, v5
	v_lshrrev_b32_e32 v6, 26, v6
	v_min_u32_e32 v22, 31, v22
	v_and_or_b32 v22, v23, 32, v22
	v_lshl_or_b32 v21, v22, 10, v21
	v_cvt_u32_f32_e32 v22, v88
	v_lshrrev_b32_e32 v23, 26, v24
	v_lshrrev_b32_e32 v7, 26, v7
	v_lshrrev_b32_e32 v0, 26, v0
	v_min_u32_e32 v22, 31, v22
	v_and_or_b32 v22, v23, 32, v22
	v_lshl_or_b32 v21, v22, 16, v21
	v_cvt_u32_f32_e32 v22, v89
	v_lshrrev_b32_e32 v23, 26, v25
	v_lshrrev_b32_e32 v1, 26, v1
	v_lshrrev_b32_e32 v2, 26, v2
	v_min_u32_e32 v22, 31, v22
	v_and_or_b32 v22, v23, 32, v22
	v_lshl_or_b32 v21, v22, 22, v21
	v_lshl_or_b32 v22, v91, 28, v21
	v_cvt_u32_f32_e32 v21, v80
	v_min_u32_e32 v21, 31, v21
	v_and_or_b32 v16, v16, 32, v21
	v_cvt_u32_f32_e32 v21, v81
	v_min_u32_e32 v21, 31, v21
	v_and_or_b32 v17, v17, 32, v21
	v_lshl_or_b32 v16, v17, 6, v16
	v_cvt_u32_f32_e32 v17, v82
	v_min_u32_e32 v17, 31, v17
	v_and_or_b32 v17, v18, 32, v17
	v_lshl_or_b32 v16, v17, 12, v16
	v_cvt_u32_f32_e32 v17, v83
	v_lshrrev_b32_e32 v18, 26, v19
	v_min_u32_e32 v17, 31, v17
	v_and_or_b32 v17, v18, 32, v17
	v_lshl_or_b32 v16, v17, 18, v16
	v_cvt_u32_f32_e32 v17, v84
	v_lshrrev_b32_e32 v18, 26, v20
	v_min_u32_e32 v17, 31, v17
	v_and_or_b32 v17, v18, 32, v17
	v_lshl_or_b32 v16, v17, 24, v16
	v_cvt_u32_f32_e32 v17, v74
	v_cvt_u32_f32_e32 v18, v75
	v_min_u32_e32 v17, 31, v17
	v_and_or_b32 v10, v10, 32, v17
	v_min_u32_e32 v18, 31, v18
	v_lshrrev_b32_e32 v10, 4, v10
	v_and_or_b32 v11, v11, 32, v18
	v_lshl_or_b32 v10, v11, 2, v10
	v_cvt_u32_f32_e32 v11, v76
	v_min_u32_e32 v11, 31, v11
	v_and_or_b32 v11, v12, 32, v11
	v_lshl_or_b32 v10, v11, 8, v10
	v_cvt_u32_f32_e32 v11, v77
	v_lshrrev_b32_e32 v12, 26, v13
	v_min_u32_e32 v11, 31, v11
	v_and_or_b32 v11, v12, 32, v11
	v_lshl_or_b32 v10, v11, 14, v10
	v_cvt_u32_f32_e32 v11, v78
	v_lshrrev_b32_e32 v12, 26, v14
	v_min_u32_e32 v11, 31, v11
	v_and_or_b32 v11, v12, 32, v11
	v_lshl_or_b32 v10, v11, 20, v10
	v_cvt_u32_f32_e32 v11, v69
	v_cvt_u32_f32_e32 v12, v70
	v_min_u32_e32 v11, 31, v11
	v_and_or_b32 v5, v5, 32, v11
	v_min_u32_e32 v12, 31, v12
	v_lshrrev_b32_e32 v5, 2, v5
	v_and_or_b32 v6, v6, 32, v12
	v_lshl_or_b32 v5, v6, 4, v5
	v_cvt_u32_f32_e32 v6, v71
	v_min_u32_e32 v6, 31, v6
	v_and_or_b32 v6, v7, 32, v6
	v_lshl_or_b32 v5, v6, 10, v5
	v_cvt_u32_f32_e32 v6, v72
	v_lshrrev_b32_e32 v7, 26, v8
	v_min_u32_e32 v6, 31, v6
	v_and_or_b32 v6, v7, 32, v6
	v_lshl_or_b32 v5, v6, 16, v5
	v_cvt_u32_f32_e32 v6, v73
	v_lshrrev_b32_e32 v7, 26, v9
	v_min_u32_e32 v6, 31, v6
	v_and_or_b32 v6, v7, 32, v6
	v_lshl_or_b32 v5, v6, 22, v5
	v_cvt_u32_f32_e32 v6, v54
	v_min_u32_e32 v6, 31, v6
	v_and_or_b32 v0, v0, 32, v6
	v_cvt_u32_f32_e32 v6, v55
	v_min_u32_e32 v6, 31, v6
	v_and_or_b32 v1, v1, 32, v6
	v_lshl_or_b32 v0, v1, 6, v0
	v_cvt_u32_f32_e32 v1, v56
	v_min_u32_e32 v1, 31, v1
	v_and_or_b32 v1, v2, 32, v1
	v_lshl_or_b32 v0, v1, 12, v0
	v_cvt_u32_f32_e32 v1, v57
	v_lshrrev_b32_e32 v2, 26, v3
	v_and_b32_e32 v3, 0x80000000, v15
	v_lshl_add_u64 v[56:57], v[48:49], 0, v[46:47]
	v_min_u32_e32 v1, 31, v1
	v_and_or_b32 v1, v2, 32, v1
	v_lshl_or_b32 v0, v1, 18, v0
	v_cvt_u32_f32_e32 v1, v68
	v_lshrrev_b32_e32 v2, 26, v4
	v_and_b32_e32 v4, 0x80000000, v31
	v_min_u32_e32 v1, 31, v1
	v_and_or_b32 v1, v2, 32, v1
	v_lshl_or_b32 v0, v1, 24, v0
	v_lshl_or_b32 v1, v17, 28, v5
	v_cvt_u32_f32_e32 v5, v90
	v_cvt_u32_f32_e32 v2, v79
	v_lshl_or_b32 v0, v11, 30, v0
	v_min_u32_e32 v5, 31, v5
	v_lshlrev_b32_e32 v5, 26, v5
	v_min_u32_e32 v2, 31, v2
	v_or3_b32 v23, v5, v4, v26
	v_lshl_add_u64 v[4:5], v[48:49], 0, v[32:33]
	v_lshlrev_b32_e32 v2, 26, v2
	v_add_co_u32_e32 v54, vcc, s4, v4
	v_or3_b32 v2, v2, v3, v10
	v_lshl_or_b32 v3, v27, 30, v16
	v_addc_co_u32_e32 v55, vcc, 0, v5, vcc
	global_store_dwordx4 v[54:55], v[0:3], off
	s_nop 1
	v_add_co_u32_e32 v0, vcc, 0x3000000, v56
	s_nop 1
	v_addc_co_u32_e32 v1, vcc, 0, v57, vcc
	global_store_dwordx2 v[0:1], v[22:23], off offset:1024
	v_add_co_u32_e32 v0, vcc, 0x2000, v52
	s_nop 1
	v_addc_co_u32_e32 v1, vcc, 0, v53, vcc
	s_waitcnt vmcnt(9)
	v_mov_b32_e32 v0, v132
	v_mov_b32_e32 v1, v133
	v_mov_b32_e32 v2, v134
	v_mov_b32_e32 v3, v135
	v_mul_f32_e64 v4, |v0|, s7
	v_min_f32_e32 v4, 0x40f00000, v4
	v_cmp_ngt_f32_e32 vcc, 2.0, v4
	s_and_saveexec_b64 s[10:11], vcc
	s_xor_b64 s[10:11], exec, s[10:11]
	s_cbranch_execz .LBB0_321
	v_cmp_ngt_f32_e32 vcc, 4.0, v4
	s_and_saveexec_b64 s[12:13], vcc
	s_xor_b64 s[12:13], exec, s[12:13]
	v_add_f32_e32 v4, -4.0, v4
	v_add_f32_e32 v4, v4, v4
	v_rndne_f32_e32 v4, v4
	v_add_f32_e32 v68, 0x41c00000, v4
	s_andn2_saveexec_b64 s[12:13], s[12:13]
	v_add_f32_e32 v4, -2.0, v4
	v_mul_f32_e32 v4, 4.0, v4
	v_rndne_f32_e32 v4, v4
	v_add_f32_e32 v68, 0x41800000, v4
	s_or_b64 exec, exec, s[12:13]

; DI unsigned enc_e2m3(float x, float scale) {
;   const float a = fminf(fabsf(x) * scale, 7.5f);
;   float c;
;   if (a < 2.f) c = rintf(a * 8.f);
;   else if (a < 4.f) c = 16.f + rintf((a - 2.f) * 4.f);
;   else c = 24.f + rintf((a - 4.f) * 2.f);
; DI void job_convert6(const float* __restrict__ src, unsigned char* __restrict__ dst, int row0, float scale) {
;     ...
;         const f32x4 v = *(const f32x4*)(sp + c * 1024 + q * 4);
; #pragma unroll
;         for (int e = 0; e < 4; ++e) {
;           const int j = c * 16 + q * 4 + e;
;           const unsigned code = enc_e2m3(v[e], scale);
.LBB0_345:
	s_andn2_saveexec_b64 s[10:11], s[10:11]
	v_mul_f32_e32 v4, 0x41000000, v4
	v_rndne_f32_e32 v71, v4
	s_or_b64 exec, exec, s[10:11]
	v_add_co_u32_e32 v4, vcc, 0x2000, v52
	s_nop 1
	v_addc_co_u32_e32 v5, vcc, 0, v53, vcc
	s_waitcnt vmcnt(8)
	v_mov_b32_e32 v4, v136
	v_mov_b32_e32 v5, v137
	v_mov_b32_e32 v6, v138
	v_mov_b32_e32 v7, v139
	v_mul_f32_e64 v8, |v4|, s7
	v_min_f32_e32 v8, 0x40f00000, v8
	v_cmp_ngt_f32_e32 vcc, 2.0, v8
	s_and_saveexec_b64 s[10:11], vcc
	s_xor_b64 s[10:11], exec, s[10:11]
	s_cbranch_execz .LBB0_353
	v_cmp_ngt_f32_e32 vcc, 4.0, v8
	s_and_saveexec_b64 s[12:13], vcc
	s_xor_b64 s[12:13], exec, s[12:13]
	v_add_f32_e32 v8, -4.0, v8
	v_add_f32_e32 v8, v8, v8
	v_rndne_f32_e32 v8, v8
	v_add_f32_e32 v72, 0x41c00000, v8
	s_andn2_saveexec_b64 s[12:13], s[12:13]
	v_add_f32_e32 v8, -2.0, v8
	v_mul_f32_e32 v8, 4.0, v8
	v_rndne_f32_e32 v8, v8
	v_add_f32_e32 v72, 0x41800000, v8
	s_or_b64 exec, exec, s[12:13]

; DI unsigned enc_e2m3(float x, float scale) {
;   const float a = fminf(fabsf(x) * scale, 7.5f);
;   float c;
;   if (a < 2.f) c = rintf(a * 8.f);
;   else if (a < 4.f) c = 16.f + rintf((a - 2.f) * 4.f);
;   else c = 24.f + rintf((a - 4.f) * 2.f);
; DI void job_convert6(const float* __restrict__ src, unsigned char* __restrict__ dst, int row0, float scale) {
;     ...
;         const f32x4 v = *(const f32x4*)(sp + c * 1024 + q * 4);
; #pragma unroll
;         for (int e = 0; e < 4; ++e) {
;           const int j = c * 16 + q * 4 + e;
;           const unsigned code = enc_e2m3(v[e], scale);
.LBB0_377:
	s_andn2_saveexec_b64 s[10:11], s[10:11]
	v_mul_f32_e32 v8, 0x41000000, v8
	v_rndne_f32_e32 v75, v8
	s_or_b64 exec, exec, s[10:11]
	v_add_co_u32_e32 v8, vcc, 0x2000, v52
	s_nop 1
	v_addc_co_u32_e32 v9, vcc, 0, v53, vcc
	s_waitcnt vmcnt(7)
	v_mov_b32_e32 v8, v140
	v_mov_b32_e32 v9, v141
	v_mov_b32_e32 v10, v142
	v_mov_b32_e32 v11, v143
	v_mul_f32_e64 v12, |v8|, s7
	v_min_f32_e32 v12, 0x40f00000, v12
	v_cmp_ngt_f32_e32 vcc, 2.0, v12
	s_and_saveexec_b64 s[10:11], vcc
	s_xor_b64 s[10:11], exec, s[10:11]
	s_cbranch_execz .LBB0_385
	v_cmp_ngt_f32_e32 vcc, 4.0, v12
	s_and_saveexec_b64 s[12:13], vcc
	s_xor_b64 s[12:13], exec, s[12:13]
	v_add_f32_e32 v12, -4.0, v12
	v_add_f32_e32 v12, v12, v12
	v_rndne_f32_e32 v12, v12
	v_add_f32_e32 v76, 0x41c00000, v12
	s_andn2_saveexec_b64 s[12:13], s[12:13]
	v_add_f32_e32 v12, -2.0, v12
	v_mul_f32_e32 v12, 4.0, v12
	v_rndne_f32_e32 v12, v12
	v_add_f32_e32 v76, 0x41800000, v12
	s_or_b64 exec, exec, s[12:13]

; DI unsigned enc_e2m3(float x, float scale) {
;   const float a = fminf(fabsf(x) * scale, 7.5f);
;   float c;
;   if (a < 2.f) c = rintf(a * 8.f);
;   else if (a < 4.f) c = 16.f + rintf((a - 2.f) * 4.f);
;   else c = 24.f + rintf((a - 4.f) * 2.f);
; DI void job_convert6(const float* __restrict__ src, unsigned char* __restrict__ dst, int row0, float scale) {
;     ...
;         const f32x4 v = *(const f32x4*)(sp + c * 1024 + q * 4);
; #pragma unroll
;         for (int e = 0; e < 4; ++e) {
;           const int j = c * 16 + q * 4 + e;
;           const unsigned code = enc_e2m3(v[e], scale);
.LBB0_409:
	s_andn2_saveexec_b64 s[10:11], s[10:11]
	v_mul_f32_e32 v12, 0x41000000, v12
	v_rndne_f32_e32 v79, v12
	s_or_b64 exec, exec, s[10:11]
	v_add_co_u32_e32 v12, vcc, 0x2000, v52
	s_nop 1
	v_addc_co_u32_e32 v13, vcc, 0, v53, vcc
	s_waitcnt vmcnt(6)
	v_mov_b32_e32 v12, v144
	v_mov_b32_e32 v13, v145
	v_mov_b32_e32 v14, v146
	v_mov_b32_e32 v15, v147
	v_mul_f32_e64 v16, |v12|, s7
	v_min_f32_e32 v16, 0x40f00000, v16
	v_cmp_ngt_f32_e32 vcc, 2.0, v16
	s_and_saveexec_b64 s[10:11], vcc
	s_xor_b64 s[10:11], exec, s[10:11]
	s_cbranch_execz .LBB0_417
	v_cmp_ngt_f32_e32 vcc, 4.0, v16
	s_and_saveexec_b64 s[12:13], vcc
	s_xor_b64 s[12:13], exec, s[12:13]
	v_add_f32_e32 v16, -4.0, v16
	v_add_f32_e32 v16, v16, v16
	v_rndne_f32_e32 v16, v16
	v_add_f32_e32 v80, 0x41c00000, v16
	s_andn2_saveexec_b64 s[12:13], s[12:13]
	v_add_f32_e32 v16, -2.0, v16
	v_mul_f32_e32 v16, 4.0, v16
	v_rndne_f32_e32 v16, v16
	v_add_f32_e32 v80, 0x41800000, v16
	s_or_b64 exec, exec, s[12:13]

; DI unsigned enc_e2m3(float x, float scale) {
;   const float a = fminf(fabsf(x) * scale, 7.5f);
;   float c;
;   if (a < 2.f) c = rintf(a * 8.f);
;   else if (a < 4.f) c = 16.f + rintf((a - 2.f) * 4.f);
;   else c = 24.f + rintf((a - 4.f) * 2.f);
; DI void job_convert6(const float* __restrict__ src, unsigned char* __restrict__ dst, int row0, float scale) {
;     ...
;         const f32x4 v = *(const f32x4*)(sp + c * 1024 + q * 4);
; #pragma unroll
;         for (int e = 0; e < 4; ++e) {
;           const int j = c * 16 + q * 4 + e;
;           const unsigned code = enc_e2m3(v[e], scale);
.LBB0_441:
	s_andn2_saveexec_b64 s[10:11], s[10:11]
	v_mul_f32_e32 v16, 0x41000000, v16
	v_rndne_f32_e32 v82, v16
	s_or_b64 exec, exec, s[10:11]
	v_add_co_u32_e32 v16, vcc, 0x3000, v52
	s_nop 1
	v_addc_co_u32_e32 v17, vcc, 0, v53, vcc
	s_waitcnt vmcnt(5)
	v_mov_b32_e32 v16, v148
	v_mov_b32_e32 v17, v149
	v_mov_b32_e32 v18, v150
	v_mov_b32_e32 v19, v151
	v_mul_f32_e64 v20, |v16|, s7
	v_min_f32_e32 v20, 0x40f00000, v20
	v_cmp_ngt_f32_e32 vcc, 2.0, v20
	s_and_saveexec_b64 s[10:11], vcc
	s_xor_b64 s[10:11], exec, s[10:11]
	s_cbranch_execz .LBB0_449
	v_cmp_ngt_f32_e32 vcc, 4.0, v20
	s_and_saveexec_b64 s[12:13], vcc
	s_xor_b64 s[12:13], exec, s[12:13]
	v_add_f32_e32 v20, -4.0, v20
	v_add_f32_e32 v20, v20, v20
	v_rndne_f32_e32 v20, v20
	v_add_f32_e32 v84, 0x41c00000, v20
	s_andn2_saveexec_b64 s[12:13], s[12:13]
	v_add_f32_e32 v20, -2.0, v20
	v_mul_f32_e32 v20, 4.0, v20
	v_rndne_f32_e32 v20, v20
	v_add_f32_e32 v84, 0x41800000, v20
	s_or_b64 exec, exec, s[12:13]

; DI unsigned enc_e2m3(float x, float scale) {
;   const float a = fminf(fabsf(x) * scale, 7.5f);
;   float c;
;   if (a < 2.f) c = rintf(a * 8.f);
;   else if (a < 4.f) c = 16.f + rintf((a - 2.f) * 4.f);
;   else c = 24.f + rintf((a - 4.f) * 2.f);
; DI void job_convert6(const float* __restrict__ src, unsigned char* __restrict__ dst, int row0, float scale) {
;     ...
;         const f32x4 v = *(const f32x4*)(sp + c * 1024 + q * 4);
; #pragma unroll
;         for (int e = 0; e < 4; ++e) {
;           const int j = c * 16 + q * 4 + e;
;           const unsigned code = enc_e2m3(v[e], scale);
.LBB0_473:
	s_andn2_saveexec_b64 s[10:11], s[10:11]
	v_mul_f32_e32 v20, 0x41000000, v20
	v_rndne_f32_e32 v87, v20
	s_or_b64 exec, exec, s[10:11]
	v_add_co_u32_e32 v20, vcc, 0x3000, v52
	s_nop 1
	v_addc_co_u32_e32 v21, vcc, 0, v53, vcc
	s_waitcnt vmcnt(4)
	v_mov_b32_e32 v20, v152
	v_mov_b32_e32 v21, v153
	v_mov_b32_e32 v22, v154
	v_mov_b32_e32 v23, v155
	v_mul_f32_e64 v24, |v20|, s7
	v_min_f32_e32 v24, 0x40f00000, v24
	v_cmp_ngt_f32_e32 vcc, 2.0, v24
	s_and_saveexec_b64 s[10:11], vcc
	s_xor_b64 s[10:11], exec, s[10:11]
	s_cbranch_execz .LBB0_481
	v_cmp_ngt_f32_e32 vcc, 4.0, v24
	s_and_saveexec_b64 s[12:13], vcc
	s_xor_b64 s[12:13], exec, s[12:13]
	v_add_f32_e32 v24, -4.0, v24
	v_add_f32_e32 v24, v24, v24
	v_rndne_f32_e32 v24, v24
	v_add_f32_e32 v88, 0x41c00000, v24
	s_andn2_saveexec_b64 s[12:13], s[12:13]
	v_add_f32_e32 v24, -2.0, v24
	v_mul_f32_e32 v24, 4.0, v24
	v_rndne_f32_e32 v24, v24
	v_add_f32_e32 v88, 0x41800000, v24
	s_or_b64 exec, exec, s[12:13]

; DI unsigned enc_e2m3(float x, float scale) {
;   const float a = fminf(fabsf(x) * scale, 7.5f);
;   float c;
;   if (a < 2.f) c = rintf(a * 8.f);
;   else if (a < 4.f) c = 16.f + rintf((a - 2.f) * 4.f);
;   else c = 24.f + rintf((a - 4.f) * 2.f);
; DI void job_convert6(const float* __restrict__ src, unsigned char* __restrict__ dst, int row0, float scale) {
;     ...
;         const f32x4 v = *(const f32x4*)(sp + c * 1024 + q * 4);
; #pragma unroll
;         for (int e = 0; e < 4; ++e) {
;           const int j = c * 16 + q * 4 + e;
;           const unsigned code = enc_e2m3(v[e], scale);
.LBB0_505:
	s_andn2_saveexec_b64 s[10:11], s[10:11]
	v_mul_f32_e32 v24, 0x41000000, v24
	v_rndne_f32_e32 v91, v24
	s_or_b64 exec, exec, s[10:11]
	v_add_co_u32_e32 v24, vcc, 0x3000, v52
	s_nop 1
	v_addc_co_u32_e32 v25, vcc, 0, v53, vcc
	s_waitcnt vmcnt(3)
	v_mov_b32_e32 v24, v156
	v_mov_b32_e32 v25, v157
	v_mov_b32_e32 v26, v158
	v_mov_b32_e32 v27, v159
	v_mul_f32_e64 v28, |v24|, s7
	v_min_f32_e32 v28, 0x40f00000, v28
	v_cmp_ngt_f32_e32 vcc, 2.0, v28
	s_and_saveexec_b64 s[10:11], vcc
	s_xor_b64 s[10:11], exec, s[10:11]
	s_cbranch_execz .LBB0_513
	v_cmp_ngt_f32_e32 vcc, 4.0, v28
	s_and_saveexec_b64 s[12:13], vcc
	s_xor_b64 s[12:13], exec, s[12:13]
	v_add_f32_e32 v28, -4.0, v28
	v_add_f32_e32 v28, v28, v28
	v_rndne_f32_e32 v28, v28
	v_add_f32_e32 v92, 0x41c00000, v28
	s_andn2_saveexec_b64 s[12:13], s[12:13]
	v_add_f32_e32 v28, -2.0, v28
	v_mul_f32_e32 v28, 4.0, v28
	v_rndne_f32_e32 v28, v28
	v_add_f32_e32 v92, 0x41800000, v28
	s_or_b64 exec, exec, s[12:13]

; DI unsigned enc_e2m3(float x, float scale) {
;   const float a = fminf(fabsf(x) * scale, 7.5f);
;   float c;
;   if (a < 2.f) c = rintf(a * 8.f);
;   else if (a < 4.f) c = 16.f + rintf((a - 2.f) * 4.f);
;   else c = 24.f + rintf((a - 4.f) * 2.f);
; DI void job_convert6(const float* __restrict__ src, unsigned char* __restrict__ dst, int row0, float scale) {
;     ...
;         const f32x4 v = *(const f32x4*)(sp + c * 1024 + q * 4);
; #pragma unroll
;         for (int e = 0; e < 4; ++e) {
;           const int j = c * 16 + q * 4 + e;
;           const unsigned code = enc_e2m3(v[e], scale);
.LBB0_537:
	s_andn2_saveexec_b64 s[10:11], s[10:11]
	v_mul_f32_e32 v28, 0x41000000, v28
	v_rndne_f32_e32 v95, v28
	s_or_b64 exec, exec, s[10:11]
	v_add_co_u32_e32 v28, vcc, 0x3000, v52
	s_nop 1
	v_addc_co_u32_e32 v29, vcc, 0, v53, vcc
	s_waitcnt vmcnt(2)
	v_mov_b32_e32 v28, v160
	v_mov_b32_e32 v29, v161
	v_mov_b32_e32 v30, v162
	v_mov_b32_e32 v31, v163
	v_mul_f32_e64 v52, |v28|, s7
	v_min_f32_e32 v52, 0x40f00000, v52
	v_cmp_ngt_f32_e32 vcc, 2.0, v52
	s_and_saveexec_b64 s[10:11], vcc
	s_xor_b64 s[10:11], exec, s[10:11]
	s_cbranch_execz .LBB0_545
	v_cmp_ngt_f32_e32 vcc, 4.0, v52
	s_and_saveexec_b64 s[12:13], vcc
	s_xor_b64 s[12:13], exec, s[12:13]
	v_add_f32_e32 v52, -4.0, v52
	v_add_f32_e32 v52, v52, v52
	v_rndne_f32_e32 v52, v52
	v_add_f32_e32 v53, 0x41c00000, v52
	s_andn2_saveexec_b64 s[12:13], s[12:13]
	v_add_f32_e32 v52, -2.0, v52
	v_mul_f32_e32 v52, 4.0, v52
	v_rndne_f32_e32 v52, v52
	v_add_f32_e32 v53, 0x41800000, v52
	s_or_b64 exec, exec, s[12:13]

; DI unsigned enc_e2m3(float x, float scale) {
;   const float a = fminf(fabsf(x) * scale, 7.5f);
;   float c;
;   if (a < 2.f) c = rintf(a * 8.f);
;   else if (a < 4.f) c = 16.f + rintf((a - 2.f) * 4.f);
;   else c = 24.f + rintf((a - 4.f) * 2.f);
; DI void job_convert6(const float* __restrict__ src, unsigned char* __restrict__ dst, int row0, float scale) {
;     ...
;   for (int i = 0; i < 4; ++i) {
;     const int row = row0 + wid * 4 + i;
;     const float* sp = src + (size_t)row * 2048 + lane * 16;
;     unsigned w[7] = {0u, 0u, 0u, 0u, 0u, 0u, 0u};
; #pragma unroll
;     for (int c = 0; c < 2; ++c)
; #pragma unroll
;       for (int q = 0; q < 4; ++q) {
;         const f32x4 v = *(const f32x4*)(sp + c * 1024 + q * 4);
; #pragma unroll
;         for (int e = 0; e < 4; ++e) {
;           const int j = c * 16 + q * 4 + e;
;           const unsigned code = enc_e2m3(v[e], scale);
.LBB0_575:
	v_lshl_add_u64 v[52:53], v[48:49], 0, s[8:9]
	v_add_co_u32_e32 v164, vcc, 0x1000, v52
	s_nop 1
	v_addc_co_u32_e32 v165, vcc, 0, v53, vcc
	global_load_dwordx4 v[100:103], v[164:165], off offset:-4096
	global_load_dwordx4 v[104:107], v[164:165], off offset:-4080
	global_load_dwordx4 v[108:111], v[164:165], off offset:-4064
	global_load_dwordx4 v[112:115], v[164:165], off offset:-4048
	global_load_dwordx4 v[116:119], v[164:165], off
	global_load_dwordx4 v[120:123], v[164:165], off offset:16
	global_load_dwordx4 v[124:127], v[164:165], off offset:32
	global_load_dwordx4 v[128:131], v[164:165], off offset:48
	v_add_co_u32_e32 v164, vcc, 0x3000, v52
	s_nop 1
	v_addc_co_u32_e32 v165, vcc, 0, v53, vcc
	global_load_dwordx4 v[132:135], v[164:165], off offset:-4096
	global_load_dwordx4 v[136:139], v[164:165], off offset:-4080
	global_load_dwordx4 v[140:143], v[164:165], off offset:-4064
	global_load_dwordx4 v[144:147], v[164:165], off offset:-4048
	global_load_dwordx4 v[148:151], v[164:165], off
	global_load_dwordx4 v[152:155], v[164:165], off offset:16
	global_load_dwordx4 v[156:159], v[164:165], off offset:32
	global_load_dwordx4 v[160:163], v[164:165], off offset:48
	s_waitcnt vmcnt(15)
	v_mov_b32_e32 v4, v100
	v_mov_b32_e32 v5, v101
	v_mov_b32_e32 v6, v102
	v_mov_b32_e32 v7, v103
	v_mul_f32_e64 v0, |v4|, s5
	v_min_f32_e32 v0, 0x40f00000, v0
	v_cmp_ngt_f32_e32 vcc, 2.0, v0
	s_and_saveexec_b64 s[10:11], vcc
	s_xor_b64 s[10:11], exec, s[10:11]
	s_cbranch_execz .LBB0_581
	v_cmp_ngt_f32_e32 vcc, 4.0, v0
	s_and_saveexec_b64 s[12:13], vcc
	s_xor_b64 s[12:13], exec, s[12:13]
	v_add_f32_e32 v0, -4.0, v0
	v_add_f32_e32 v0, v0, v0
	v_rndne_f32_e32 v0, v0
	v_add_f32_e32 v32, 0x41c00000, v0
	s_andn2_saveexec_b64 s[12:13], s[12:13]
	v_add_f32_e32 v0, -2.0, v0
	v_mul_f32_e32 v0, 4.0, v0
	v_rndne_f32_e32 v0, v0
	v_add_f32_e32 v32, 0x41800000, v0
	s_or_b64 exec, exec, s[12:13]

; DI unsigned enc_e2m3(float x, float scale) {
;   const float a = fminf(fabsf(x) * scale, 7.5f);
;   float c;
;   if (a < 2.f) c = rintf(a * 8.f);
;   else if (a < 4.f) c = 16.f + rintf((a - 2.f) * 4.f);
;   else c = 24.f + rintf((a - 4.f) * 2.f);
; DI void job_convert6(const float* __restrict__ src, unsigned char* __restrict__ dst, int row0, float scale) {
;     ...
;         const f32x4 v = *(const f32x4*)(sp + c * 1024 + q * 4);
; #pragma unroll
;         for (int e = 0; e < 4; ++e) {
;           const int j = c * 16 + q * 4 + e;
;           const unsigned code = enc_e2m3(v[e], scale);
.LBB0_605:
	s_andn2_saveexec_b64 s[10:11], s[10:11]
	v_mul_f32_e32 v0, 0x41000000, v0
	v_rndne_f32_e32 v56, v0
	s_or_b64 exec, exec, s[10:11]
	s_waitcnt vmcnt(14)
	v_mov_b32_e32 v8, v104
	v_mov_b32_e32 v9, v105
	v_mov_b32_e32 v10, v106
	v_mov_b32_e32 v11, v107
	v_mul_f32_e64 v0, |v8|, s5
	v_min_f32_e32 v0, 0x40f00000, v0
	v_cmp_ngt_f32_e32 vcc, 2.0, v0
	s_and_saveexec_b64 s[10:11], vcc
	s_xor_b64 s[10:11], exec, s[10:11]
	s_cbranch_execz .LBB0_613
	v_cmp_ngt_f32_e32 vcc, 4.0, v0
	s_and_saveexec_b64 s[12:13], vcc
	s_xor_b64 s[12:13], exec, s[12:13]
	v_add_f32_e32 v0, -4.0, v0
	v_add_f32_e32 v0, v0, v0
	v_rndne_f32_e32 v0, v0
	v_add_f32_e32 v57, 0x41c00000, v0
	s_andn2_saveexec_b64 s[12:13], s[12:13]
	v_add_f32_e32 v0, -2.0, v0
	v_mul_f32_e32 v0, 4.0, v0
	v_rndne_f32_e32 v0, v0
	v_add_f32_e32 v57, 0x41800000, v0
	s_or_b64 exec, exec, s[12:13]

; DI unsigned enc_e2m3(float x, float scale) {
;   const float a = fminf(fabsf(x) * scale, 7.5f);
;   float c;
;   if (a < 2.f) c = rintf(a * 8.f);
;   else if (a < 4.f) c = 16.f + rintf((a - 2.f) * 4.f);
;   else c = 24.f + rintf((a - 4.f) * 2.f);
; DI void job_convert6(const float* __restrict__ src, unsigned char* __restrict__ dst, int row0, float scale) {
;     ...
;         const f32x4 v = *(const f32x4*)(sp + c * 1024 + q * 4);
; #pragma unroll
;         for (int e = 0; e < 4; ++e) {
;           const int j = c * 16 + q * 4 + e;
;           const unsigned code = enc_e2m3(v[e], scale);
.LBB0_637:
	s_andn2_saveexec_b64 s[10:11], s[10:11]
	v_mul_f32_e32 v0, 0x41000000, v0
	v_rndne_f32_e32 v70, v0
	s_or_b64 exec, exec, s[10:11]
	s_waitcnt vmcnt(13)
	v_mov_b32_e32 v12, v108
	v_mov_b32_e32 v13, v109
	v_mov_b32_e32 v14, v110
	v_mov_b32_e32 v15, v111
	v_mul_f32_e64 v0, |v12|, s5
	v_min_f32_e32 v0, 0x40f00000, v0
	v_cmp_ngt_f32_e32 vcc, 2.0, v0
	s_and_saveexec_b64 s[10:11], vcc
	s_xor_b64 s[10:11], exec, s[10:11]
	s_cbranch_execz .LBB0_645
	v_cmp_ngt_f32_e32 vcc, 4.0, v0
	s_and_saveexec_b64 s[12:13], vcc
	s_xor_b64 s[12:13], exec, s[12:13]
	v_add_f32_e32 v0, -4.0, v0
	v_add_f32_e32 v0, v0, v0
	v_rndne_f32_e32 v0, v0
	v_add_f32_e32 v71, 0x41c00000, v0
	s_andn2_saveexec_b64 s[12:13], s[12:13]
	v_add_f32_e32 v0, -2.0, v0
	v_mul_f32_e32 v0, 4.0, v0
	v_rndne_f32_e32 v0, v0
	v_add_f32_e32 v71, 0x41800000, v0
	s_or_b64 exec, exec, s[12:13]

; DI unsigned enc_e2m3(float x, float scale) {
;   const float a = fminf(fabsf(x) * scale, 7.5f);
;   float c;
;   if (a < 2.f) c = rintf(a * 8.f);
;   else if (a < 4.f) c = 16.f + rintf((a - 2.f) * 4.f);
;   else c = 24.f + rintf((a - 4.f) * 2.f);
; DI void job_convert6(const float* __restrict__ src, unsigned char* __restrict__ dst, int row0, float scale) {
;     ...
;         const f32x4 v = *(const f32x4*)(sp + c * 1024 + q * 4);
; #pragma unroll
;         for (int e = 0; e < 4; ++e) {
;           const int j = c * 16 + q * 4 + e;
;           const unsigned code = enc_e2m3(v[e], scale);
.LBB0_669:
	s_andn2_saveexec_b64 s[10:11], s[10:11]
	v_mul_f32_e32 v0, 0x41000000, v0
	v_rndne_f32_e32 v74, v0
	s_or_b64 exec, exec, s[10:11]
	s_waitcnt vmcnt(12)
	v_mov_b32_e32 v16, v112
	v_mov_b32_e32 v17, v113
	v_mov_b32_e32 v18, v114
	v_mov_b32_e32 v19, v115
	v_mul_f32_e64 v0, |v16|, s5
	v_min_f32_e32 v0, 0x40f00000, v0
	v_cmp_ngt_f32_e32 vcc, 2.0, v0
	s_and_saveexec_b64 s[10:11], vcc
	s_xor_b64 s[10:11], exec, s[10:11]
	s_cbranch_execz .LBB0_677
	v_cmp_ngt_f32_e32 vcc, 4.0, v0
	s_and_saveexec_b64 s[12:13], vcc
	s_xor_b64 s[12:13], exec, s[12:13]
	v_add_f32_e32 v0, -4.0, v0
	v_add_f32_e32 v0, v0, v0
	v_rndne_f32_e32 v0, v0
	v_add_f32_e32 v76, 0x41c00000, v0
	s_andn2_saveexec_b64 s[12:13], s[12:13]
	v_add_f32_e32 v0, -2.0, v0
	v_mul_f32_e32 v0, 4.0, v0
	v_rndne_f32_e32 v0, v0
	v_add_f32_e32 v76, 0x41800000, v0
	s_or_b64 exec, exec, s[12:13]

; DI unsigned enc_e2m3(float x, float scale) {
;   const float a = fminf(fabsf(x) * scale, 7.5f);
;   float c;
;   if (a < 2.f) c = rintf(a * 8.f);
;   else if (a < 4.f) c = 16.f + rintf((a - 2.f) * 4.f);
;   else c = 24.f + rintf((a - 4.f) * 2.f);
; DI void job_convert6(const float* __restrict__ src, unsigned char* __restrict__ dst, int row0, float scale) {
;     ...
;         const f32x4 v = *(const f32x4*)(sp + c * 1024 + q * 4);
; #pragma unroll
;         for (int e = 0; e < 4; ++e) {
;           const int j = c * 16 + q * 4 + e;
;           const unsigned code = enc_e2m3(v[e], scale);
.LBB0_701:
	s_andn2_saveexec_b64 s[10:11], s[10:11]
	v_mul_f32_e32 v0, 0x41000000, v0
	v_rndne_f32_e32 v78, v0
	s_or_b64 exec, exec, s[10:11]
	v_add_co_u32_e32 v0, vcc, 0x1000, v52
	s_nop 1
	v_addc_co_u32_e32 v1, vcc, 0, v53, vcc
	s_waitcnt vmcnt(11)
	v_mov_b32_e32 v0, v116
	v_mov_b32_e32 v1, v117
	v_mov_b32_e32 v2, v118
	v_mov_b32_e32 v3, v119
	v_mul_f32_e64 v20, |v0|, s5
	v_min_f32_e32 v20, 0x40f00000, v20
	v_cmp_ngt_f32_e32 vcc, 2.0, v20
	s_and_saveexec_b64 s[10:11], vcc
	s_xor_b64 s[10:11], exec, s[10:11]
	s_cbranch_execz .LBB0_709
	v_cmp_ngt_f32_e32 vcc, 4.0, v20
	s_and_saveexec_b64 s[12:13], vcc
	s_xor_b64 s[12:13], exec, s[12:13]
	v_add_f32_e32 v20, -4.0, v20
	v_add_f32_e32 v20, v20, v20
	v_rndne_f32_e32 v20, v20
	v_add_f32_e32 v79, 0x41c00000, v20
	s_andn2_saveexec_b64 s[12:13], s[12:13]
	v_add_f32_e32 v20, -2.0, v20
	v_mul_f32_e32 v20, 4.0, v20
	v_rndne_f32_e32 v20, v20
	v_add_f32_e32 v79, 0x41800000, v20
	s_or_b64 exec, exec, s[12:13]

; DI unsigned enc_e2m3(float x, float scale) {
;   const float a = fminf(fabsf(x) * scale, 7.5f);
;   float c;
;   if (a < 2.f) c = rintf(a * 8.f);
;   else if (a < 4.f) c = 16.f + rintf((a - 2.f) * 4.f);
;   else c = 24.f + rintf((a - 4.f) * 2.f);
; DI void job_convert6(const float* __restrict__ src, unsigned char* __restrict__ dst, int row0, float scale) {
;     ...
;         const f32x4 v = *(const f32x4*)(sp + c * 1024 + q * 4);
; #pragma unroll
;         for (int e = 0; e < 4; ++e) {
;           const int j = c * 16 + q * 4 + e;
;           const unsigned code = enc_e2m3(v[e], scale);
.LBB0_733:
	s_andn2_saveexec_b64 s[10:11], s[10:11]
	v_mul_f32_e32 v20, 0x41000000, v20
	v_rndne_f32_e32 v82, v20
	s_or_b64 exec, exec, s[10:11]
	v_add_co_u32_e32 v20, vcc, 0x1000, v52
	s_nop 1
	v_addc_co_u32_e32 v21, vcc, 0, v53, vcc
	s_waitcnt vmcnt(10)
	v_mov_b32_e32 v20, v120
	v_mov_b32_e32 v21, v121
	v_mov_b32_e32 v22, v122
	v_mov_b32_e32 v23, v123
	v_mul_f32_e64 v24, |v20|, s5
	v_min_f32_e32 v24, 0x40f00000, v24
	v_cmp_ngt_f32_e32 vcc, 2.0, v24
	s_and_saveexec_b64 s[10:11], vcc
	s_xor_b64 s[10:11], exec, s[10:11]
	s_cbranch_execz .LBB0_741
	v_cmp_ngt_f32_e32 vcc, 4.0, v24
	s_and_saveexec_b64 s[12:13], vcc
	s_xor_b64 s[12:13], exec, s[12:13]
	v_add_f32_e32 v24, -4.0, v24
	v_add_f32_e32 v24, v24, v24
	v_rndne_f32_e32 v24, v24
	v_add_f32_e32 v83, 0x41c00000, v24
	s_andn2_saveexec_b64 s[12:13], s[12:13]
	v_add_f32_e32 v24, -2.0, v24
	v_mul_f32_e32 v24, 4.0, v24
	v_rndne_f32_e32 v24, v24
	v_add_f32_e32 v83, 0x41800000, v24
	s_or_b64 exec, exec, s[12:13]

; DI unsigned enc_e2m3(float x, float scale) {
;   const float a = fminf(fabsf(x) * scale, 7.5f);
;   float c;
;   if (a < 2.f) c = rintf(a * 8.f);
;   else if (a < 4.f) c = 16.f + rintf((a - 2.f) * 4.f);
;   else c = 24.f + rintf((a - 4.f) * 2.f);
; DI void job_convert6(const float* __restrict__ src, unsigned char* __restrict__ dst, int row0, float scale) {
;     ...
;         const f32x4 v = *(const f32x4*)(sp + c * 1024 + q * 4);
; #pragma unroll
;         for (int e = 0; e < 4; ++e) {
;           const int j = c * 16 + q * 4 + e;
;           const unsigned code = enc_e2m3(v[e], scale);
.LBB0_765:
	s_andn2_saveexec_b64 s[10:11], s[10:11]
	v_mul_f32_e32 v24, 0x41000000, v24
	v_rndne_f32_e32 v86, v24
	s_or_b64 exec, exec, s[10:11]
	v_add_co_u32_e32 v24, vcc, 0x1000, v52
	s_nop 1
	v_addc_co_u32_e32 v25, vcc, 0, v53, vcc
	s_waitcnt vmcnt(9)
	v_mov_b32_e32 v24, v124
	v_mov_b32_e32 v25, v125
	v_mov_b32_e32 v26, v126
	v_mov_b32_e32 v27, v127
	v_mul_f32_e64 v28, |v24|, s5
	v_min_f32_e32 v28, 0x40f00000, v28
	v_cmp_ngt_f32_e32 vcc, 2.0, v28
	s_and_saveexec_b64 s[10:11], vcc
	s_xor_b64 s[10:11], exec, s[10:11]
	s_cbranch_execz .LBB0_773
	v_cmp_ngt_f32_e32 vcc, 4.0, v28
	s_and_saveexec_b64 s[12:13], vcc
	s_xor_b64 s[12:13], exec, s[12:13]
	v_add_f32_e32 v28, -4.0, v28
	v_add_f32_e32 v28, v28, v28
	v_rndne_f32_e32 v28, v28
	v_add_f32_e32 v87, 0x41c00000, v28
	s_andn2_saveexec_b64 s[12:13], s[12:13]
	v_add_f32_e32 v28, -2.0, v28
	v_mul_f32_e32 v28, 4.0, v28
	v_rndne_f32_e32 v28, v28
	v_add_f32_e32 v87, 0x41800000, v28
	s_or_b64 exec, exec, s[12:13]

; DI unsigned enc_e2m3(float x, float scale) {
;   const float a = fminf(fabsf(x) * scale, 7.5f);
;   float c;
;   if (a < 2.f) c = rintf(a * 8.f);
;   else if (a < 4.f) c = 16.f + rintf((a - 2.f) * 4.f);
;   else c = 24.f + rintf((a - 4.f) * 2.f);
; DI void job_convert6(const float* __restrict__ src, unsigned char* __restrict__ dst, int row0, float scale) {
;     ...
;         const f32x4 v = *(const f32x4*)(sp + c * 1024 + q * 4);
; #pragma unroll
;         for (int e = 0; e < 4; ++e) {
;           const int j = c * 16 + q * 4 + e;
;           const unsigned code = enc_e2m3(v[e], scale);
.LBB0_797:
	s_andn2_saveexec_b64 s[10:11], s[10:11]
	v_mul_f32_e32 v28, 0x41000000, v28
	v_rndne_f32_e32 v91, v28
	s_or_b64 exec, exec, s[10:11]
	v_add_co_u32_e32 v28, vcc, 0x1000, v52
	s_nop 1
	v_addc_co_u32_e32 v29, vcc, 0, v53, vcc
	s_waitcnt vmcnt(8)
	v_mov_b32_e32 v28, v128
	v_mov_b32_e32 v29, v129
	v_mov_b32_e32 v30, v130
	v_mov_b32_e32 v31, v131
	v_mul_f32_e64 v90, |v28|, s5
	v_min_f32_e32 v90, 0x40f00000, v90
	v_cmp_ngt_f32_e32 vcc, 2.0, v90
	s_and_saveexec_b64 s[10:11], vcc
	s_xor_b64 s[10:11], exec, s[10:11]
	s_cbranch_execz .LBB0_805
	v_cmp_ngt_f32_e32 vcc, 4.0, v90
	s_and_saveexec_b64 s[12:13], vcc
	s_xor_b64 s[12:13], exec, s[12:13]
	v_add_f32_e32 v90, -4.0, v90
	v_add_f32_e32 v90, v90, v90
	v_rndne_f32_e32 v90, v90
	v_add_f32_e32 v92, 0x41c00000, v90
	s_andn2_saveexec_b64 s[12:13], s[12:13]
	v_add_f32_e32 v90, -2.0, v90
	v_mul_f32_e32 v90, 4.0, v90
	v_rndne_f32_e32 v90, v90
	v_add_f32_e32 v92, 0x41800000, v90
	s_or_b64 exec, exec, s[12:13]

; DI unsigned enc_e2m3(float x, float scale) {
;   const float a = fminf(fabsf(x) * scale, 7.5f);
;   float c;
;   if (a < 2.f) c = rintf(a * 8.f);
;   else if (a < 4.f) c = 16.f + rintf((a - 2.f) * 4.f);
;   else c = 24.f + rintf((a - 4.f) * 2.f);
;   unsigned ci = (unsigned)c; ci = ci > 31u ? 31u : ci;
;   return ci | ((__float_as_uint(x) >> 31) << 5);
; DI void job_convert6(const float* __restrict__ src, unsigned char* __restrict__ dst, int row0, float scale) {
;     ...
;         for (int e = 0; e < 4; ++e) {
;           const int j = c * 16 + q * 4 + e;
;           const unsigned code = enc_e2m3(v[e], scale);
;           const int bit = 6 * j, wi = bit >> 5, sh = bit & 31;
;           w[wi] |= code << sh;
;           if (sh > 26) w[wi + 1] |= code >> (32 - sh);
;         }
;       }
;     unsigned char* dp = dst + (size_t)row * 1536;
;     *(u32x4*)(dp + lane * 16) = u32x4{w[0], w[1], w[2], w[3]};
;     *(u32x2*)(dp + 1024 + lane * 8) = u32x2{w[4], w[5]};
.LBB0_829:
	s_andn2_saveexec_b64 s[10:11], s[10:11]
	v_mul_f32_e32 v90, 0x41000000, v95
	v_rndne_f32_e32 v90, v90
	s_or_b64 exec, exec, s[10:11]
	v_cvt_u32_f32_e32 v89, v89
	v_cvt_u32_f32_e32 v91, v91
	v_cvt_u32_f32_e32 v92, v92
	v_lshrrev_b32_e32 v26, 26, v26
	v_min_u32_e32 v89, 31, v89
	v_min_u32_e32 v91, 31, v91
	v_and_or_b32 v26, v26, 32, v89
	v_lshrrev_b32_e32 v27, 26, v27
	v_lshrrev_b32_e32 v26, 4, v26
	v_and_or_b32 v27, v27, 32, v91
	v_cvt_u32_f32_e32 v91, v93
	v_lshl_or_b32 v26, v27, 2, v26
	v_min_u32_e32 v27, 31, v92
	v_lshrrev_b32_e32 v28, 26, v28
	v_and_or_b32 v27, v28, 32, v27
	v_cvt_u32_f32_e32 v28, v94
	v_lshl_or_b32 v26, v27, 8, v26
	v_min_u32_e32 v27, 31, v91
	v_lshrrev_b32_e32 v29, 26, v29
	v_and_or_b32 v27, v29, 32, v27
	v_lshl_or_b32 v26, v27, 14, v26
	v_min_u32_e32 v27, 31, v28
	v_cvt_u32_f32_e32 v28, v84
	v_lshrrev_b32_e32 v29, 26, v30
	v_and_or_b32 v27, v29, 32, v27
	v_lshl_or_b32 v26, v27, 20, v26
	v_min_u32_e32 v27, 31, v28
	v_cvt_u32_f32_e32 v28, v85
	v_cvt_u32_f32_e32 v29, v86
	v_lshrrev_b32_e32 v21, 26, v21
	v_and_or_b32 v21, v21, 32, v27
	v_min_u32_e32 v28, 31, v28
	v_lshrrev_b32_e32 v22, 26, v22
	v_lshrrev_b32_e32 v21, 2, v21
	v_and_or_b32 v22, v22, 32, v28
	v_cvt_u32_f32_e32 v28, v87
	v_lshl_or_b32 v21, v22, 4, v21
	v_min_u32_e32 v22, 31, v29
	v_lshrrev_b32_e32 v23, 26, v23
	v_and_or_b32 v22, v23, 32, v22
	v_cvt_u32_f32_e32 v23, v88
	v_lshl_or_b32 v21, v22, 10, v21
	v_min_u32_e32 v22, 31, v28
	v_lshrrev_b32_e32 v24, 26, v24
	v_and_or_b32 v22, v24, 32, v22
	v_lshl_or_b32 v21, v22, 16, v21
	v_min_u32_e32 v22, 31, v23
	v_lshrrev_b32_e32 v23, 26, v25
	v_and_or_b32 v22, v23, 32, v22
	v_cvt_u32_f32_e32 v23, v79
	v_lshl_or_b32 v21, v22, 22, v21
	v_lshl_or_b32 v22, v89, 28, v21
	v_cvt_u32_f32_e32 v21, v80
	v_min_u32_e32 v23, 31, v23
	v_lshrrev_b32_e32 v0, 26, v0
	v_and_or_b32 v0, v0, 32, v23
	v_cvt_u32_f32_e32 v23, v81
	v_min_u32_e32 v21, 31, v21
	v_lshrrev_b32_e32 v1, 26, v1
	v_and_or_b32 v1, v1, 32, v21
	v_cvt_u32_f32_e32 v21, v82
	v_lshl_or_b32 v0, v1, 6, v0
	v_min_u32_e32 v1, 31, v23
	v_lshrrev_b32_e32 v2, 26, v2
	v_and_or_b32 v1, v2, 32, v1
	v_cvt_u32_f32_e32 v2, v83
	v_lshl_or_b32 v0, v1, 12, v0
	v_min_u32_e32 v1, 31, v21
	v_lshrrev_b32_e32 v3, 26, v3
	v_and_or_b32 v1, v3, 32, v1
	v_lshl_or_b32 v0, v1, 18, v0
	v_min_u32_e32 v1, 31, v2
	v_cvt_u32_f32_e32 v2, v73
	v_lshrrev_b32_e32 v3, 26, v20
	v_and_or_b32 v1, v3, 32, v1
	v_lshl_or_b32 v20, v1, 24, v0
	v_cvt_u32_f32_e32 v0, v74
	v_min_u32_e32 v21, 31, v2
	v_lshrrev_b32_e32 v1, 26, v14
	v_and_or_b32 v1, v1, 32, v21
	v_lshrrev_b32_e32 v14, 4, v1
	v_min_u32_e32 v0, 31, v0
	v_lshrrev_b32_e32 v1, 26, v15
	v_and_or_b32 v15, v1, 32, v0
	v_add_co_u32_e32 v0, vcc, 0x2000, v52
	v_cvt_u32_f32_e32 v23, v76
	s_nop 0
	v_addc_co_u32_e32 v1, vcc, 0, v53, vcc
	v_lshl_or_b32 v14, v15, 2, v14
	v_min_u32_e32 v15, 31, v23
	v_cvt_u32_f32_e32 v23, v75
	v_lshrrev_b32_e32 v16, 26, v16
	v_and_or_b32 v15, v16, 32, v15
	v_cvt_u32_f32_e32 v16, v77
	v_lshl_or_b32 v14, v15, 8, v14
	v_min_u32_e32 v15, 31, v23
	v_lshrrev_b32_e32 v17, 26, v17
	v_and_or_b32 v15, v17, 32, v15
	v_lshl_or_b32 v14, v15, 14, v14
	v_min_u32_e32 v15, 31, v16
	v_cvt_u32_f32_e32 v16, v68
	v_lshrrev_b32_e32 v17, 26, v18
	v_and_or_b32 v15, v17, 32, v15
	v_lshl_or_b32 v14, v15, 20, v14
	v_min_u32_e32 v15, 31, v16
	v_cvt_u32_f32_e32 v16, v69
	v_cvt_u32_f32_e32 v17, v70
	v_lshrrev_b32_e32 v9, 26, v9
	v_and_or_b32 v9, v9, 32, v15
	v_min_u32_e32 v16, 31, v16
	v_lshrrev_b32_e32 v10, 26, v10
	v_lshrrev_b32_e32 v9, 2, v9
	v_and_or_b32 v10, v10, 32, v16
	v_cvt_u32_f32_e32 v16, v71
	v_lshl_or_b32 v9, v10, 4, v9
	v_min_u32_e32 v10, 31, v17
	v_lshrrev_b32_e32 v11, 26, v11
	v_and_or_b32 v10, v11, 32, v10
	v_cvt_u32_f32_e32 v11, v72
	v_lshl_or_b32 v9, v10, 10, v9
	v_min_u32_e32 v10, 31, v16
	v_lshrrev_b32_e32 v12, 26, v12
	v_and_or_b32 v10, v12, 32, v10
	v_cvt_u32_f32_e32 v12, v32
	v_lshl_or_b32 v9, v10, 16, v9
	v_min_u32_e32 v10, 31, v11
	v_lshrrev_b32_e32 v11, 26, v13
	v_and_or_b32 v10, v11, 32, v10
	v_lshl_or_b32 v9, v10, 22, v9
	v_cvt_u32_f32_e32 v10, v54
	v_min_u32_e32 v11, 31, v12
	v_lshrrev_b32_e32 v4, 26, v4
	v_and_or_b32 v4, v4, 32, v11
	v_cvt_u32_f32_e32 v11, v55
	v_min_u32_e32 v10, 31, v10
	v_lshrrev_b32_e32 v5, 26, v5
	v_and_or_b32 v5, v5, 32, v10
	v_cvt_u32_f32_e32 v10, v56
	v_lshl_or_b32 v4, v5, 6, v4
	v_min_u32_e32 v5, 31, v11
	v_lshrrev_b32_e32 v6, 26, v6
	v_and_or_b32 v5, v6, 32, v5
	v_cvt_u32_f32_e32 v6, v57
	v_lshl_or_b32 v4, v5, 12, v4
	v_min_u32_e32 v5, 31, v10
	v_lshrrev_b32_e32 v7, 26, v7
	v_and_or_b32 v5, v7, 32, v5
	v_lshl_or_b32 v4, v5, 18, v4
	v_min_u32_e32 v5, 31, v6
	v_lshrrev_b32_e32 v6, 26, v8
	v_and_or_b32 v5, v6, 32, v5
	v_cvt_u32_f32_e32 v6, v78
	v_cvt_u32_f32_e32 v8, v90
	v_lshl_or_b32 v4, v5, 24, v4
	v_and_b32_e32 v7, 0x80000000, v19
	v_min_u32_e32 v6, 31, v6
	v_lshlrev_b32_e32 v6, 26, v6
	v_min_u32_e32 v8, 31, v8
	v_lshl_or_b32 v4, v15, 30, v4
	v_lshl_or_b32 v5, v21, 28, v9
	v_or3_b32 v6, v6, v7, v14
	v_lshl_or_b32 v7, v27, 30, v20
	v_and_b32_e32 v9, 0x80000000, v31
	v_lshlrev_b32_e32 v8, 26, v8
	v_or3_b32 v23, v8, v9, v26
	global_store_dwordx4 v[50:51], v[4:7], off
	global_store_dwordx2 v[46:47], v[22:23], off offset:-1536
	s_waitcnt vmcnt(9)
	v_mov_b32_e32 v0, v132
	v_mov_b32_e32 v1, v133
	v_mov_b32_e32 v2, v134
	v_mov_b32_e32 v3, v135
	v_mul_f32_e64 v4, |v0|, s5
	v_min_f32_e32 v4, 0x40f00000, v4
	v_cmp_ngt_f32_e32 vcc, 2.0, v4
	s_and_saveexec_b64 s[10:11], vcc
	s_xor_b64 s[10:11], exec, s[10:11]
	s_cbranch_execz .LBB0_837
	v_cmp_ngt_f32_e32 vcc, 4.0, v4
	s_and_saveexec_b64 s[12:13], vcc
	s_xor_b64 s[12:13], exec, s[12:13]
	v_add_f32_e32 v4, -4.0, v4
	v_add_f32_e32 v4, v4, v4
	v_rndne_f32_e32 v4, v4
	v_add_f32_e32 v32, 0x41c00000, v4
	s_andn2_saveexec_b64 s[12:13], s[12:13]
	v_add_f32_e32 v4, -2.0, v4
	v_mul_f32_e32 v4, 4.0, v4
	v_rndne_f32_e32 v4, v4
	v_add_f32_e32 v32, 0x41800000, v4
	s_or_b64 exec, exec, s[12:13]

; DI unsigned enc_e2m3(float x, float scale) {
;   const float a = fminf(fabsf(x) * scale, 7.5f);
;   float c;
;   if (a < 2.f) c = rintf(a * 8.f);
;   else if (a < 4.f) c = 16.f + rintf((a - 2.f) * 4.f);
;   else c = 24.f + rintf((a - 4.f) * 2.f);
; DI void job_convert6(const float* __restrict__ src, unsigned char* __restrict__ dst, int row0, float scale) {
;     ...
;         const f32x4 v = *(const f32x4*)(sp + c * 1024 + q * 4);
; #pragma unroll
;         for (int e = 0; e < 4; ++e) {
;           const int j = c * 16 + q * 4 + e;
;           const unsigned code = enc_e2m3(v[e], scale);
.LBB0_861:
	s_andn2_saveexec_b64 s[10:11], s[10:11]
	v_mul_f32_e32 v4, 0x41000000, v4
	v_rndne_f32_e32 v56, v4
	s_or_b64 exec, exec, s[10:11]
	v_add_co_u32_e32 v4, vcc, 0x2000, v52
	s_nop 1
	v_addc_co_u32_e32 v5, vcc, 0, v53, vcc
	s_waitcnt vmcnt(8)
	v_mov_b32_e32 v4, v136
	v_mov_b32_e32 v5, v137
	v_mov_b32_e32 v6, v138
	v_mov_b32_e32 v7, v139
	v_mul_f32_e64 v8, |v4|, s5
	v_min_f32_e32 v8, 0x40f00000, v8
	v_cmp_ngt_f32_e32 vcc, 2.0, v8
	s_and_saveexec_b64 s[10:11], vcc
	s_xor_b64 s[10:11], exec, s[10:11]
	s_cbranch_execz .LBB0_869
	v_cmp_ngt_f32_e32 vcc, 4.0, v8
	s_and_saveexec_b64 s[12:13], vcc
	s_xor_b64 s[12:13], exec, s[12:13]
	v_add_f32_e32 v8, -4.0, v8
	v_add_f32_e32 v8, v8, v8
	v_rndne_f32_e32 v8, v8
	v_add_f32_e32 v57, 0x41c00000, v8
	s_andn2_saveexec_b64 s[12:13], s[12:13]
	v_add_f32_e32 v8, -2.0, v8
	v_mul_f32_e32 v8, 4.0, v8
	v_rndne_f32_e32 v8, v8
	v_add_f32_e32 v57, 0x41800000, v8
	s_or_b64 exec, exec, s[12:13]

; DI unsigned enc_e2m3(float x, float scale) {
;   const float a = fminf(fabsf(x) * scale, 7.5f);
;   float c;
;   if (a < 2.f) c = rintf(a * 8.f);
;   else if (a < 4.f) c = 16.f + rintf((a - 2.f) * 4.f);
;   else c = 24.f + rintf((a - 4.f) * 2.f);
; DI void job_convert6(const float* __restrict__ src, unsigned char* __restrict__ dst, int row0, float scale) {
;     ...
;         const f32x4 v = *(const f32x4*)(sp + c * 1024 + q * 4);
; #pragma unroll
;         for (int e = 0; e < 4; ++e) {
;           const int j = c * 16 + q * 4 + e;
;           const unsigned code = enc_e2m3(v[e], scale);
.LBB0_893:
	s_andn2_saveexec_b64 s[10:11], s[10:11]
	v_mul_f32_e32 v8, 0x41000000, v8
	v_rndne_f32_e32 v70, v8
	s_or_b64 exec, exec, s[10:11]
	v_add_co_u32_e32 v8, vcc, 0x2000, v52
	s_nop 1
	v_addc_co_u32_e32 v9, vcc, 0, v53, vcc
	s_waitcnt vmcnt(7)
	v_mov_b32_e32 v8, v140
	v_mov_b32_e32 v9, v141
	v_mov_b32_e32 v10, v142
	v_mov_b32_e32 v11, v143
	v_mul_f32_e64 v12, |v8|, s5
	v_min_f32_e32 v12, 0x40f00000, v12
	v_cmp_ngt_f32_e32 vcc, 2.0, v12
	s_and_saveexec_b64 s[10:11], vcc
	s_xor_b64 s[10:11], exec, s[10:11]
	s_cbranch_execz .LBB0_901
	v_cmp_ngt_f32_e32 vcc, 4.0, v12
	s_and_saveexec_b64 s[12:13], vcc
	s_xor_b64 s[12:13], exec, s[12:13]
	v_add_f32_e32 v12, -4.0, v12
	v_add_f32_e32 v12, v12, v12
	v_rndne_f32_e32 v12, v12
	v_add_f32_e32 v71, 0x41c00000, v12
	s_andn2_saveexec_b64 s[12:13], s[12:13]
	v_add_f32_e32 v12, -2.0, v12
	v_mul_f32_e32 v12, 4.0, v12
	v_rndne_f32_e32 v12, v12
	v_add_f32_e32 v71, 0x41800000, v12
	s_or_b64 exec, exec, s[12:13]

; DI unsigned enc_e2m3(float x, float scale) {
;   const float a = fminf(fabsf(x) * scale, 7.5f);
;   float c;
;   if (a < 2.f) c = rintf(a * 8.f);
;   else if (a < 4.f) c = 16.f + rintf((a - 2.f) * 4.f);
;   else c = 24.f + rintf((a - 4.f) * 2.f);
; DI void job_convert6(const float* __restrict__ src, unsigned char* __restrict__ dst, int row0, float scale) {
;     ...
;         const f32x4 v = *(const f32x4*)(sp + c * 1024 + q * 4);
; #pragma unroll
;         for (int e = 0; e < 4; ++e) {
;           const int j = c * 16 + q * 4 + e;
;           const unsigned code = enc_e2m3(v[e], scale);
.LBB0_925:
	s_andn2_saveexec_b64 s[10:11], s[10:11]
	v_mul_f32_e32 v12, 0x41000000, v12
	v_rndne_f32_e32 v74, v12
	s_or_b64 exec, exec, s[10:11]
	v_add_co_u32_e32 v12, vcc, 0x2000, v52
	s_nop 1
	v_addc_co_u32_e32 v13, vcc, 0, v53, vcc
	s_waitcnt vmcnt(6)
	v_mov_b32_e32 v12, v144
	v_mov_b32_e32 v13, v145
	v_mov_b32_e32 v14, v146
	v_mov_b32_e32 v15, v147
	v_mul_f32_e64 v16, |v12|, s5
	v_min_f32_e32 v16, 0x40f00000, v16
	v_cmp_ngt_f32_e32 vcc, 2.0, v16
	s_and_saveexec_b64 s[10:11], vcc
	s_xor_b64 s[10:11], exec, s[10:11]
	s_cbranch_execz .LBB0_933
	v_cmp_ngt_f32_e32 vcc, 4.0, v16
	s_and_saveexec_b64 s[12:13], vcc
	s_xor_b64 s[12:13], exec, s[12:13]
	v_add_f32_e32 v16, -4.0, v16
	v_add_f32_e32 v16, v16, v16
	v_rndne_f32_e32 v16, v16
	v_add_f32_e32 v75, 0x41c00000, v16
	s_andn2_saveexec_b64 s[12:13], s[12:13]
	v_add_f32_e32 v16, -2.0, v16
	v_mul_f32_e32 v16, 4.0, v16
	v_rndne_f32_e32 v16, v16
	v_add_f32_e32 v75, 0x41800000, v16
	s_or_b64 exec, exec, s[12:13]

; DI unsigned enc_e2m3(float x, float scale) {
;   const float a = fminf(fabsf(x) * scale, 7.5f);
;   float c;
;   if (a < 2.f) c = rintf(a * 8.f);
;   else if (a < 4.f) c = 16.f + rintf((a - 2.f) * 4.f);
;   else c = 24.f + rintf((a - 4.f) * 2.f);
; DI void job_convert6(const float* __restrict__ src, unsigned char* __restrict__ dst, int row0, float scale) {
;     ...
;         const f32x4 v = *(const f32x4*)(sp + c * 1024 + q * 4);
; #pragma unroll
;         for (int e = 0; e < 4; ++e) {
;           const int j = c * 16 + q * 4 + e;
;           const unsigned code = enc_e2m3(v[e], scale);
.LBB0_957:
	s_andn2_saveexec_b64 s[10:11], s[10:11]
	v_mul_f32_e32 v16, 0x41000000, v16
	v_rndne_f32_e32 v77, v16
	s_or_b64 exec, exec, s[10:11]
	v_add_co_u32_e32 v16, vcc, 0x3000, v52
	s_nop 1
	v_addc_co_u32_e32 v17, vcc, 0, v53, vcc
	s_waitcnt vmcnt(5)
	v_mov_b32_e32 v16, v148
	v_mov_b32_e32 v17, v149
	v_mov_b32_e32 v18, v150
	v_mov_b32_e32 v19, v151
	v_mul_f32_e64 v20, |v16|, s5
	v_min_f32_e32 v20, 0x40f00000, v20
	v_cmp_ngt_f32_e32 vcc, 2.0, v20
	s_and_saveexec_b64 s[10:11], vcc
	s_xor_b64 s[10:11], exec, s[10:11]
	s_cbranch_execz .LBB0_965
	v_cmp_ngt_f32_e32 vcc, 4.0, v20
	s_and_saveexec_b64 s[12:13], vcc
	s_xor_b64 s[12:13], exec, s[12:13]
	v_add_f32_e32 v20, -4.0, v20
	v_add_f32_e32 v20, v20, v20
	v_rndne_f32_e32 v20, v20
	v_add_f32_e32 v79, 0x41c00000, v20
	s_andn2_saveexec_b64 s[12:13], s[12:13]
	v_add_f32_e32 v20, -2.0, v20
	v_mul_f32_e32 v20, 4.0, v20
	v_rndne_f32_e32 v20, v20
	v_add_f32_e32 v79, 0x41800000, v20
	s_or_b64 exec, exec, s[12:13]

; DI unsigned enc_e2m3(float x, float scale) {
;   const float a = fminf(fabsf(x) * scale, 7.5f);
;   float c;
;   if (a < 2.f) c = rintf(a * 8.f);
;   else if (a < 4.f) c = 16.f + rintf((a - 2.f) * 4.f);
;   else c = 24.f + rintf((a - 4.f) * 2.f);
; DI void job_convert6(const float* __restrict__ src, unsigned char* __restrict__ dst, int row0, float scale) {
;     ...
;         const f32x4 v = *(const f32x4*)(sp + c * 1024 + q * 4);
; #pragma unroll
;         for (int e = 0; e < 4; ++e) {
;           const int j = c * 16 + q * 4 + e;
;           const unsigned code = enc_e2m3(v[e], scale);
.LBB0_989:
	s_andn2_saveexec_b64 s[10:11], s[10:11]
	v_mul_f32_e32 v20, 0x41000000, v20
	v_rndne_f32_e32 v82, v20
	s_or_b64 exec, exec, s[10:11]
	v_add_co_u32_e32 v20, vcc, 0x3000, v52
	s_nop 1
	v_addc_co_u32_e32 v21, vcc, 0, v53, vcc
	s_waitcnt vmcnt(4)
	v_mov_b32_e32 v20, v152
	v_mov_b32_e32 v21, v153
	v_mov_b32_e32 v22, v154
	v_mov_b32_e32 v23, v155
	v_mul_f32_e64 v24, |v20|, s5
	v_min_f32_e32 v24, 0x40f00000, v24
	v_cmp_ngt_f32_e32 vcc, 2.0, v24
	s_and_saveexec_b64 s[10:11], vcc
	s_xor_b64 s[10:11], exec, s[10:11]
	s_cbranch_execz .LBB0_997
	v_cmp_ngt_f32_e32 vcc, 4.0, v24
	s_and_saveexec_b64 s[12:13], vcc
	s_xor_b64 s[12:13], exec, s[12:13]
	v_add_f32_e32 v24, -4.0, v24
	v_add_f32_e32 v24, v24, v24
	v_rndne_f32_e32 v24, v24
	v_add_f32_e32 v83, 0x41c00000, v24
	s_andn2_saveexec_b64 s[12:13], s[12:13]
	v_add_f32_e32 v24, -2.0, v24
	v_mul_f32_e32 v24, 4.0, v24
	v_rndne_f32_e32 v24, v24
	v_add_f32_e32 v83, 0x41800000, v24
	s_or_b64 exec, exec, s[12:13]

; DI unsigned enc_e2m3(float x, float scale) {
;   const float a = fminf(fabsf(x) * scale, 7.5f);
;   float c;
;   if (a < 2.f) c = rintf(a * 8.f);
;   else if (a < 4.f) c = 16.f + rintf((a - 2.f) * 4.f);
;   else c = 24.f + rintf((a - 4.f) * 2.f);
; DI void job_convert6(const float* __restrict__ src, unsigned char* __restrict__ dst, int row0, float scale) {
;     ...
;         const f32x4 v = *(const f32x4*)(sp + c * 1024 + q * 4);
; #pragma unroll
;         for (int e = 0; e < 4; ++e) {
;           const int j = c * 16 + q * 4 + e;
;           const unsigned code = enc_e2m3(v[e], scale);
.LBB0_1021:
	s_andn2_saveexec_b64 s[10:11], s[10:11]
	v_mul_f32_e32 v24, 0x41000000, v24
	v_rndne_f32_e32 v86, v24
	s_or_b64 exec, exec, s[10:11]
	v_add_co_u32_e32 v24, vcc, 0x3000, v52
	s_nop 1
	v_addc_co_u32_e32 v25, vcc, 0, v53, vcc
	s_waitcnt vmcnt(3)
	v_mov_b32_e32 v24, v156
	v_mov_b32_e32 v25, v157
	v_mov_b32_e32 v26, v158
	v_mov_b32_e32 v27, v159
	v_mul_f32_e64 v28, |v24|, s5
	v_min_f32_e32 v28, 0x40f00000, v28
	v_cmp_ngt_f32_e32 vcc, 2.0, v28
	s_and_saveexec_b64 s[10:11], vcc
	s_xor_b64 s[10:11], exec, s[10:11]
	s_cbranch_execz .LBB0_1029
	v_cmp_ngt_f32_e32 vcc, 4.0, v28
	s_and_saveexec_b64 s[12:13], vcc
	s_xor_b64 s[12:13], exec, s[12:13]
	v_add_f32_e32 v28, -4.0, v28
	v_add_f32_e32 v28, v28, v28
	v_rndne_f32_e32 v28, v28
	v_add_f32_e32 v87, 0x41c00000, v28
	s_andn2_saveexec_b64 s[12:13], s[12:13]
	v_add_f32_e32 v28, -2.0, v28
	v_mul_f32_e32 v28, 4.0, v28
	v_rndne_f32_e32 v28, v28
	v_add_f32_e32 v87, 0x41800000, v28
	s_or_b64 exec, exec, s[12:13]

; DI unsigned enc_e2m3(float x, float scale) {
;   const float a = fminf(fabsf(x) * scale, 7.5f);
;   float c;
;   if (a < 2.f) c = rintf(a * 8.f);
;   else if (a < 4.f) c = 16.f + rintf((a - 2.f) * 4.f);
;   else c = 24.f + rintf((a - 4.f) * 2.f);
; DI void job_convert6(const float* __restrict__ src, unsigned char* __restrict__ dst, int row0, float scale) {
;     ...
;         const f32x4 v = *(const f32x4*)(sp + c * 1024 + q * 4);
; #pragma unroll
;         for (int e = 0; e < 4; ++e) {
;           const int j = c * 16 + q * 4 + e;
;           const unsigned code = enc_e2m3(v[e], scale);
.LBB0_1053:
	s_andn2_saveexec_b64 s[10:11], s[10:11]
	v_mul_f32_e32 v28, 0x41000000, v28
	v_rndne_f32_e32 v90, v28
	s_or_b64 exec, exec, s[10:11]
	v_add_co_u32_e32 v28, vcc, 0x3000, v52
	s_nop 1
	v_addc_co_u32_e32 v29, vcc, 0, v53, vcc
	s_waitcnt vmcnt(2)
	v_mov_b32_e32 v28, v160
	v_mov_b32_e32 v29, v161
	v_mov_b32_e32 v30, v162
	v_mov_b32_e32 v31, v163
	v_mul_f32_e64 v52, |v28|, s5
	v_min_f32_e32 v52, 0x40f00000, v52
	v_cmp_ngt_f32_e32 vcc, 2.0, v52
	s_and_saveexec_b64 s[10:11], vcc
	s_xor_b64 s[10:11], exec, s[10:11]
	s_cbranch_execz .LBB0_1061
	v_cmp_ngt_f32_e32 vcc, 4.0, v52
	s_and_saveexec_b64 s[12:13], vcc
	s_xor_b64 s[12:13], exec, s[12:13]
	v_add_f32_e32 v52, -4.0, v52
	v_add_f32_e32 v52, v52, v52
	v_rndne_f32_e32 v52, v52
	v_add_f32_e32 v53, 0x41c00000, v52
	s_andn2_saveexec_b64 s[12:13], s[12:13]
	v_add_f32_e32 v52, -2.0, v52
	v_mul_f32_e32 v52, 4.0, v52
	v_rndne_f32_e32 v52, v52
	v_add_f32_e32 v53, 0x41800000, v52
	s_or_b64 exec, exec, s[12:13]

; DI void job_ada(const Params& p, int j, char* lds) {
;     ...
;   const int col = tid & 31, kg = tid >> 5;
;   const float* w = p.w_ada + (size_t)layer * 2048 * 12288 + (size_t)(kg * 256) * 12288 + n0 + col;
;   float ax = 0.f, ah = 0.f;
; #pragma unroll 16
;   for (int k = 0; k < 256; ++k) {
;     float wv = w[(size_t)k * 12288];
;     ax += sx[kg * 256 + k] * wv;
;     ah += sh[kg * 256 + k] * wv;
;   }
.LBB0_1108:
	s_or_b64 exec, exec, s[8:9]
	s_mul_hi_i32 s8, s2, 0x2aaaaaab
	s_lshr_b32 s9, s8, 31
	s_ashr_i32 s8, s8, 6
	s_add_i32 s12, s8, s9
	s_mul_i32 s8, s12, 0x180
	s_sub_i32 s8, s2, s8
	s_lshl_b32 s8, s8, 5
	s_mul_i32 s10, s12, 0x6000000
	s_mul_hi_i32 s9, s12, 0x6000000
	s_add_u32 s10, s76, s10
	v_ashrrev_i32_e32 v9, 5, v8
	s_addc_u32 s11, s77, s9
	v_lshlrev_b32_e32 v18, 8, v9
	v_mov_b64_e32 v[0:1], s[10:11]
	v_and_b32_e32 v10, 31, v8
	v_mad_i64_i32 v[0:1], s[10:11], v18, s92, v[0:1]
	s_ashr_i32 s9, s8, 31
	v_lshl_add_u64 v[0:1], s[8:9], 2, v[0:1]
	v_lshlrev_b32_e32 v32, 2, v10
	v_mov_b32_e32 v16, 0
	v_lshl_add_u64 v[12:13], v[0:1], 0, v[32:33]
	v_lshlrev_b32_e32 v19, 10, v9
	s_mov_b64 s[10:11], 0
	v_mov_b32_e32 v17, v16
	s_waitcnt lgkmcnt(0)
	s_mov_b64 s[98:99], 0xc000
	s_barrier
.LBB0_1109:
	v_lshl_add_u64 v[14:15], v[12:13], 0, s[10:11]
	global_load_dword v100, v[14:15], off
	v_lshl_add_u64 v[14:15], v[14:15], 0, s[98:99]
	global_load_dword v101, v[14:15], off
	v_lshl_add_u64 v[14:15], v[14:15], 0, s[98:99]
	global_load_dword v102, v[14:15], off
	v_lshl_add_u64 v[14:15], v[14:15], 0, s[98:99]
	global_load_dword v103, v[14:15], off
	v_lshl_add_u64 v[14:15], v[14:15], 0, s[98:99]
	global_load_dword v104, v[14:15], off
	v_lshl_add_u64 v[14:15], v[14:15], 0, s[98:99]
	global_load_dword v105, v[14:15], off
	v_lshl_add_u64 v[14:15], v[14:15], 0, s[98:99]
	global_load_dword v106, v[14:15], off
	v_lshl_add_u64 v[14:15], v[14:15], 0, s[98:99]
	global_load_dword v107, v[14:15], off
	v_lshl_add_u64 v[14:15], v[14:15], 0, s[98:99]
	global_load_dword v108, v[14:15], off
	v_lshl_add_u64 v[14:15], v[14:15], 0, s[98:99]
	global_load_dword v109, v[14:15], off
	v_lshl_add_u64 v[14:15], v[14:15], 0, s[98:99]
	global_load_dword v110, v[14:15], off
	v_lshl_add_u64 v[14:15], v[14:15], 0, s[98:99]
	global_load_dword v111, v[14:15], off
	v_lshl_add_u64 v[14:15], v[14:15], 0, s[98:99]
	global_load_dword v112, v[14:15], off
	v_lshl_add_u64 v[14:15], v[14:15], 0, s[98:99]
	global_load_dword v113, v[14:15], off
	v_lshl_add_u64 v[14:15], v[14:15], 0, s[98:99]
	global_load_dword v114, v[14:15], off
	v_lshl_add_u64 v[14:15], v[14:15], 0, s[98:99]
	global_load_dword v115, v[14:15], off
	v_lshl_add_u64 v[14:15], v[14:15], 0, s[98:99]
	global_load_dword v116, v[14:15], off
	v_lshl_add_u64 v[14:15], v[14:15], 0, s[98:99]
	global_load_dword v117, v[14:15], off
	v_lshl_add_u64 v[14:15], v[14:15], 0, s[98:99]
	global_load_dword v118, v[14:15], off
	v_lshl_add_u64 v[14:15], v[14:15], 0, s[98:99]
	global_load_dword v119, v[14:15], off
	v_lshl_add_u64 v[14:15], v[14:15], 0, s[98:99]
	global_load_dword v120, v[14:15], off
	v_lshl_add_u64 v[14:15], v[14:15], 0, s[98:99]
	global_load_dword v121, v[14:15], off
	v_lshl_add_u64 v[14:15], v[14:15], 0, s[98:99]
	global_load_dword v122, v[14:15], off
	v_lshl_add_u64 v[14:15], v[14:15], 0, s[98:99]
	global_load_dword v123, v[14:15], off
	v_lshl_add_u64 v[14:15], v[14:15], 0, s[98:99]
	global_load_dword v124, v[14:15], off
	v_lshl_add_u64 v[14:15], v[14:15], 0, s[98:99]
	global_load_dword v125, v[14:15], off
	v_lshl_add_u64 v[14:15], v[14:15], 0, s[98:99]
	global_load_dword v126, v[14:15], off
	v_lshl_add_u64 v[14:15], v[14:15], 0, s[98:99]
	global_load_dword v127, v[14:15], off
	v_lshl_add_u64 v[14:15], v[14:15], 0, s[98:99]
	global_load_dword v128, v[14:15], off
	v_lshl_add_u64 v[14:15], v[14:15], 0, s[98:99]
	global_load_dword v129, v[14:15], off
	v_lshl_add_u64 v[14:15], v[14:15], 0, s[98:99]
	global_load_dword v130, v[14:15], off
	v_lshl_add_u64 v[14:15], v[14:15], 0, s[98:99]
	global_load_dword v131, v[14:15], off
	ds_read_b128 v[132:135], v19
	ds_read_b128 v[136:139], v19 offset:16
	ds_read_b128 v[140:143], v19 offset:32
	ds_read_b128 v[144:147], v19 offset:48
	ds_read_b128 v[148:151], v19 offset:64
	ds_read_b128 v[152:155], v19 offset:80
	ds_read_b128 v[156:159], v19 offset:96
	ds_read_b128 v[160:163], v19 offset:112
	ds_read_b128 v[164:167], v19 offset:8192
	ds_read_b128 v[168:171], v19 offset:8208
	ds_read_b128 v[172:175], v19 offset:8224
	ds_read_b128 v[176:179], v19 offset:8240
	ds_read_b128 v[180:183], v19 offset:8256
	ds_read_b128 v[184:187], v19 offset:8272
	ds_read_b128 v[188:191], v19 offset:8288
	ds_read_b128 v[192:195], v19 offset:8304
	v_add_u32_e32 v19, 128, v19
	s_add_u32 s10, s10, 0x180000
	s_addc_u32 s11, s11, 0
	s_cmp_eq_u32 s10, 0xc00000
	s_waitcnt lgkmcnt(0)
; DI void job_ada(const Params& p, int j, char* lds) {
;     ...
; #pragma unroll 16
;   for (int k = 0; k < 256; ++k) {
;     float wv = w[(size_t)k * 12288];
;     ax += sx[kg * 256 + k] * wv;
;     ah += sh[kg * 256 + k] * wv;
;   }
;   red[kg * 32 + col] = ax;
;   red[256 + kg * 32 + col] = ah;
;   __syncthreads();
;   if (tid < 64) {
;     int v = tid >> 5, cc = tid & 31;
;     float s = 0.f;
; #pragma unroll
;     for (int g = 0; g < 8; ++g) s += red[v * 256 + g * 32 + cc];
;     s += p.b_ada[(size_t)layer * 12288 + n0 + cc];
;     ((float*)(p.ws + OFF_MOD))[(size_t)(layer * 2 + v) * 12288 + n0 + cc] = s;
;   }
	s_waitcnt vmcnt(31)
	v_fmac_f32_e32 v16, v100, v132
	v_fmac_f32_e32 v17, v100, v164
	s_waitcnt vmcnt(30)
	v_fmac_f32_e32 v16, v101, v133
	v_fmac_f32_e32 v17, v101, v165
	s_waitcnt vmcnt(29)
	v_fmac_f32_e32 v16, v102, v134
	v_fmac_f32_e32 v17, v102, v166
	s_waitcnt vmcnt(28)
	v_fmac_f32_e32 v16, v103, v135
	v_fmac_f32_e32 v17, v103, v167
	s_waitcnt vmcnt(27)
	v_fmac_f32_e32 v16, v104, v136
	v_fmac_f32_e32 v17, v104, v168
	s_waitcnt vmcnt(26)
	v_fmac_f32_e32 v16, v105, v137
	v_fmac_f32_e32 v17, v105, v169
	s_waitcnt vmcnt(25)
	v_fmac_f32_e32 v16, v106, v138
	v_fmac_f32_e32 v17, v106, v170
	s_waitcnt vmcnt(24)
	v_fmac_f32_e32 v16, v107, v139
	v_fmac_f32_e32 v17, v107, v171
	s_waitcnt vmcnt(23)
	v_fmac_f32_e32 v16, v108, v140
	v_fmac_f32_e32 v17, v108, v172
	s_waitcnt vmcnt(22)
	v_fmac_f32_e32 v16, v109, v141
	v_fmac_f32_e32 v17, v109, v173
	s_waitcnt vmcnt(21)
	v_fmac_f32_e32 v16, v110, v142
	v_fmac_f32_e32 v17, v110, v174
	s_waitcnt vmcnt(20)
	v_fmac_f32_e32 v16, v111, v143
	v_fmac_f32_e32 v17, v111, v175
	s_waitcnt vmcnt(19)
	v_fmac_f32_e32 v16, v112, v144
	v_fmac_f32_e32 v17, v112, v176
	s_waitcnt vmcnt(18)
	v_fmac_f32_e32 v16, v113, v145
	v_fmac_f32_e32 v17, v113, v177
	s_waitcnt vmcnt(17)
	v_fmac_f32_e32 v16, v114, v146
	v_fmac_f32_e32 v17, v114, v178
	s_waitcnt vmcnt(16)
	v_fmac_f32_e32 v16, v115, v147
	v_fmac_f32_e32 v17, v115, v179
	s_waitcnt vmcnt(15)
	v_fmac_f32_e32 v16, v116, v148
	v_fmac_f32_e32 v17, v116, v180
	s_waitcnt vmcnt(14)
	v_fmac_f32_e32 v16, v117, v149
	v_fmac_f32_e32 v17, v117, v181
	s_waitcnt vmcnt(13)
	v_fmac_f32_e32 v16, v118, v150
	v_fmac_f32_e32 v17, v118, v182
	s_waitcnt vmcnt(12)
	v_fmac_f32_e32 v16, v119, v151
	v_fmac_f32_e32 v17, v119, v183
	s_waitcnt vmcnt(11)
	v_fmac_f32_e32 v16, v120, v152
	v_fmac_f32_e32 v17, v120, v184
	s_waitcnt vmcnt(10)
	v_fmac_f32_e32 v16, v121, v153
	v_fmac_f32_e32 v17, v121, v185
	s_waitcnt vmcnt(9)
	v_fmac_f32_e32 v16, v122, v154
	v_fmac_f32_e32 v17, v122, v186
	s_waitcnt vmcnt(8)
	v_fmac_f32_e32 v16, v123, v155
	v_fmac_f32_e32 v17, v123, v187
	s_waitcnt vmcnt(7)
	v_fmac_f32_e32 v16, v124, v156
	v_fmac_f32_e32 v17, v124, v188
	s_waitcnt vmcnt(6)
	v_fmac_f32_e32 v16, v125, v157
	v_fmac_f32_e32 v17, v125, v189
	s_waitcnt vmcnt(5)
	v_fmac_f32_e32 v16, v126, v158
	v_fmac_f32_e32 v17, v126, v190
	s_waitcnt vmcnt(4)
	v_fmac_f32_e32 v16, v127, v159
	v_fmac_f32_e32 v17, v127, v191
	s_waitcnt vmcnt(3)
	v_fmac_f32_e32 v16, v128, v160
	v_fmac_f32_e32 v17, v128, v192
	s_waitcnt vmcnt(2)
	v_fmac_f32_e32 v16, v129, v161
	v_fmac_f32_e32 v17, v129, v193
	s_waitcnt vmcnt(1)
	v_fmac_f32_e32 v16, v130, v162
	v_fmac_f32_e32 v17, v130, v194
	s_waitcnt vmcnt(0)
	v_fmac_f32_e32 v16, v131, v163
	v_fmac_f32_e32 v17, v131, v195
	s_cbranch_scc0 .LBB0_1109
	s_mov_b32 s10, 0x3fffffe0
	v_and_or_b32 v0, v8, s10, v10
	v_lshlrev_b32_e32 v0, 2, v0
	v_cmp_gt_i32_e32 vcc, 64, v8
	ds_write_b32 v11, v16 offset:16384
	ds_write_b32 v0, v17 offset:17408
	s_waitcnt lgkmcnt(0)
	s_barrier
	s_and_saveexec_b64 s[10:11], vcc
	s_cbranch_execz .LBB0_19
	v_lshlrev_b32_e32 v32, 2, v10
	v_lshl_add_u32 v0, v18, 2, v32
	v_add_u32_e32 v2, 0x4000, v0
	ds_read2_b32 v[0:1], v2 offset1:32
	s_mul_i32 s16, s12, 0xc000
	s_mul_hi_i32 s13, s12, 0xc000
	s_add_u32 s16, s78, s16
	s_addc_u32 s13, s79, s13
	s_waitcnt lgkmcnt(0)
	v_add_f32_e32 v0, 0, v0
	v_add_f32_e32 v3, v0, v1
	ds_read2_b32 v[0:1], v2 offset0:64 offset1:96
	s_lshl_b64 s[8:9], s[8:9], 2
	s_add_u32 s34, s16, s8
	s_addc_u32 s35, s13, s9
	s_waitcnt lgkmcnt(0)
	v_add_f32_e32 v0, v3, v0
	v_add_f32_e32 v3, v0, v1
	ds_read2_b32 v[0:1], v2 offset0:128 offset1:160
	s_waitcnt lgkmcnt(0)
	v_add_f32_e32 v0, v3, v0
	v_add_f32_e32 v3, v0, v1
	ds_read2_b32 v[0:1], v2 offset0:192 offset1:224
	s_waitcnt lgkmcnt(0)
	v_add_f32_e32 v0, v3, v0
	v_add_f32_e32 v0, v0, v1
	global_load_dword v1, v32, s[34:35]
	v_lshl_add_u32 v3, s12, 1, v9
	s_waitcnt vmcnt(0)
	v_add_f32_e32 v2, v0, v1
	v_mov_b64_e32 v[0:1], s[26:27]
	v_mad_i64_i32 v[0:1], s[12:13], v3, s92, v[0:1]
	v_lshl_add_u64 v[0:1], v[0:1], 0, s[8:9]
	v_lshl_add_u64 v[0:1], v[0:1], 0, v[32:33]
	global_store_dword v[0:1], v2, off
	s_branch .LBB0_19

; DI u16 f2bf(float a) { return (u16)(pk2(a, 0.f) & 0xffffu); }
; DI int crow(int i, int h) { return (i & 3) + 8 * (i >> 2) + 4 * h; }
; template <int EPI>
; __device__ __forceinline__ void gemm_tile(const Params& p, int layer, const u16* __restrict__ A, const u16* __restrict__ Bt, int mt, int nt, char* lds) {
;     ...
;         const bool ropeA = gcb < 1024, ropeB = (gcb >= 1536 && gcb < 2816);
;         const bool latent = m0 >= NCTX;
;         if (latent && (ropeA || ropeB)) {
;           int pair, nf; bool userow; const f32x2* tab;
;           if (ropeA) { pair = (gc & 63) >> 1; nf = 16; tab = (const f32x2*)(p.ws + OFF_TABA); }
;           else       { pair = (gc & 127) >> 1; nf = 32; tab = (const f32x2*)(p.ws + OFF_TABB); }
;           userow = pair < nf;
;           const int f = userow ? pair : pair - nf;
; #pragma unroll
;           for (int e = 0; e < 16; ++e) {
;             const int gr = grb + crow(e, h);
;             const int t = gr - NCTX;
;             const int pos = userow ? (t >> 6) : (t & 63);
;             const f32x2 cs = tab[pos * nf + f];
;             const float v = acc[i][j][e];
;             const float o = __shfl_xor(v, 1);
;             const float res = (gc & 1) ? (o * cs[1] + v * cs[0]) : (v * cs[0] - o * cs[1]);
;             P[(size_t)gr * LDP + gc] = f2bf(res);
;           }
.LBB0_1259:
	s_or_b64 exec, exec, s[8:9]
	v_or_b32_e32 v175, 1, v170
	v_or_b32_e32 v173, 2, v170
	v_or_b32_e32 v171, 3, v170
	v_or_b32_e32 v168, 8, v170
	v_or_b32_e32 v166, 9, v170
	v_or_b32_e32 v164, 10, v170
	v_or_b32_e32 v162, 11, v170
	v_or_b32_e32 v160, 16, v170
	v_or_b32_e32 v158, 17, v170
	v_or_b32_e32 v156, 18, v170
	v_or_b32_e32 v154, 19, v170
	v_or_b32_e32 v152, 24, v170
	v_or_b32_e32 v150, 25, v170
	v_or_b32_e32 v148, 26, v170
	v_or_b32_e32 v147, 27, v170
	v_cndmask_b32_e64 v144, 63, 31, s[10:11]
	v_cndmask_b32_e64 v128, v140, v141, s[10:11]
	v_cndmask_b32_e64 v143, 32, 16, s[10:11]
	v_add_u32_e32 v178, 0xffffff00, v130
	v_cndmask_b32_e64 v142, 5, 4, s[10:11]
	v_bitop3_b32 v177, v170, 5, 1 bitop3:0xc8
	v_bitop3_b32 v176, v170, 6, 2 bitop3:0xc8
	v_bitop3_b32 v174, v170, 7, 3 bitop3:0xc8
	v_bitop3_b32 v172, v170, 12, 8 bitop3:0xc8
	v_bitop3_b32 v169, v170, 13, 9 bitop3:0xc8
	v_bitop3_b32 v167, v170, 14, 10 bitop3:0xc8
	v_bitop3_b32 v165, v170, 15, 11 bitop3:0xc8
	v_bitop3_b32 v163, v170, 20, 16 bitop3:0xc8
	v_bitop3_b32 v161, v170, 21, 17 bitop3:0xc8
	v_bitop3_b32 v159, v170, 22, 18 bitop3:0xc8
	v_bitop3_b32 v157, v170, 23, 19 bitop3:0xc8
	v_bitop3_b32 v155, v170, 28, 24 bitop3:0xc8
	v_bitop3_b32 v153, v170, 29, 25 bitop3:0xc8
	v_bitop3_b32 v151, v170, 30, 26 bitop3:0xc8
	v_bitop3_b32 v149, v170, 31, 27 bitop3:0xc8
	s_and_saveexec_b64 s[8:9], s[4:5]
	s_cbranch_execz .LBB0_1261
	s_waitcnt lgkmcnt(0)
	v_lshrrev_b32_e32 v132, 1, v134
	v_and_b32_e32 v135, v132, v144
	v_sub_u32_e32 v179, v135, v143
	v_ashrrev_i32_e32 v186, 6, v178
	v_cmp_lt_u32_e32 vcc, v135, v143
	v_min_u32_e32 v179, v135, v179
	v_lshl_add_u64 v[132:133], s[22:23], 0, v[128:129]
	v_and_b32_e32 v183, 64, v214
	v_xor_b32_e32 v182, 1, v214
	v_add_u32_e32 v183, 64, v183
	v_cmp_lt_i32_e64 s[4:5], v182, v183
	v_ashrrev_i32_e32 v135, 31, v134
	v_and_b32_e32 v187, 1, v134
	v_cndmask_b32_e64 v184, v214, v182, s[4:5]
	v_lshlrev_b32_e32 v188, 2, v184
	v_lshl_add_u64 v[134:135], v[134:135], 1, s[28:29]
	v_cmp_eq_u32_e64 s[4:5], 0, v187
	s_nop 1
	v_cndmask_b32_e32 v190, v136, v186, vcc
	v_lshl_add_u32 v190, v190, v142, v179
	v_ashrrev_i32_e32 v191, 31, v190
	v_lshl_add_u64 v[190:191], v[190:191], 3, v[132:133]
	global_load_dwordx2 v[190:191], v[190:191], off
	ds_bpermute_b32 v240, v188, v112
	v_cndmask_b32_e32 v192, v177, v186, vcc
	v_lshl_add_u32 v192, v192, v142, v179
	v_ashrrev_i32_e32 v193, 31, v192
	v_lshl_add_u64 v[192:193], v[192:193], 3, v[132:133]
	global_load_dwordx2 v[192:193], v[192:193], off
	ds_bpermute_b32 v241, v188, v113
	v_cndmask_b32_e32 v194, v176, v186, vcc
	v_lshl_add_u32 v194, v194, v142, v179
	v_ashrrev_i32_e32 v195, 31, v194
	v_lshl_add_u64 v[194:195], v[194:195], 3, v[132:133]
	global_load_dwordx2 v[194:195], v[194:195], off
	ds_bpermute_b32 v242, v188, v114
	v_cndmask_b32_e32 v196, v174, v186, vcc
	v_lshl_add_u32 v196, v196, v142, v179
	v_ashrrev_i32_e32 v197, 31, v196
	v_lshl_add_u64 v[196:197], v[196:197], 3, v[132:133]
	global_load_dwordx2 v[196:197], v[196:197], off
	ds_bpermute_b32 v243, v188, v115
	v_cndmask_b32_e32 v198, v172, v186, vcc
	v_lshl_add_u32 v198, v198, v142, v179
	v_ashrrev_i32_e32 v199, 31, v198
	v_lshl_add_u64 v[198:199], v[198:199], 3, v[132:133]
	global_load_dwordx2 v[198:199], v[198:199], off
	ds_bpermute_b32 v244, v188, v116
	v_cndmask_b32_e32 v200, v169, v186, vcc
	v_lshl_add_u32 v200, v200, v142, v179
	v_ashrrev_i32_e32 v201, 31, v200
	v_lshl_add_u64 v[200:201], v[200:201], 3, v[132:133]
	global_load_dwordx2 v[200:201], v[200:201], off
	ds_bpermute_b32 v245, v188, v117
	v_cndmask_b32_e32 v202, v167, v186, vcc
	v_lshl_add_u32 v202, v202, v142, v179
	v_ashrrev_i32_e32 v203, 31, v202
	v_lshl_add_u64 v[202:203], v[202:203], 3, v[132:133]
	global_load_dwordx2 v[202:203], v[202:203], off
	ds_bpermute_b32 v246, v188, v118
	v_cndmask_b32_e32 v204, v165, v186, vcc
	v_lshl_add_u32 v204, v204, v142, v179
	v_ashrrev_i32_e32 v205, 31, v204
	v_lshl_add_u64 v[204:205], v[204:205], 3, v[132:133]
	global_load_dwordx2 v[204:205], v[204:205], off
	ds_bpermute_b32 v247, v188, v119
	v_cndmask_b32_e32 v206, v163, v186, vcc
	v_lshl_add_u32 v206, v206, v142, v179
	v_ashrrev_i32_e32 v207, 31, v206
	v_lshl_add_u64 v[206:207], v[206:207], 3, v[132:133]
	global_load_dwordx2 v[206:207], v[206:207], off
	ds_bpermute_b32 v248, v188, v120
	v_cndmask_b32_e32 v208, v161, v186, vcc
	v_lshl_add_u32 v208, v208, v142, v179
	v_ashrrev_i32_e32 v209, 31, v208
	v_lshl_add_u64 v[208:209], v[208:209], 3, v[132:133]
	global_load_dwordx2 v[208:209], v[208:209], off
	ds_bpermute_b32 v249, v188, v121
	v_cndmask_b32_e32 v216, v159, v186, vcc
	v_lshl_add_u32 v216, v216, v142, v179
	v_ashrrev_i32_e32 v217, 31, v216
	v_lshl_add_u64 v[216:217], v[216:217], 3, v[132:133]
	global_load_dwordx2 v[216:217], v[216:217], off
	ds_bpermute_b32 v250, v188, v122
	v_cndmask_b32_e32 v218, v157, v186, vcc
	v_lshl_add_u32 v218, v218, v142, v179
	v_ashrrev_i32_e32 v219, 31, v218
	v_lshl_add_u64 v[218:219], v[218:219], 3, v[132:133]
	global_load_dwordx2 v[218:219], v[218:219], off
	ds_bpermute_b32 v251, v188, v123
	v_cndmask_b32_e32 v220, v155, v186, vcc
	v_lshl_add_u32 v220, v220, v142, v179
	v_ashrrev_i32_e32 v221, 31, v220
	v_lshl_add_u64 v[220:221], v[220:221], 3, v[132:133]
	global_load_dwordx2 v[220:221], v[220:221], off
	ds_bpermute_b32 v252, v188, v124
	v_cndmask_b32_e32 v222, v153, v186, vcc
	v_lshl_add_u32 v222, v222, v142, v179
	v_ashrrev_i32_e32 v223, 31, v222
	v_lshl_add_u64 v[222:223], v[222:223], 3, v[132:133]
	global_load_dwordx2 v[222:223], v[222:223], off
	ds_bpermute_b32 v253, v188, v125
	v_cndmask_b32_e32 v224, v151, v186, vcc
	v_lshl_add_u32 v224, v224, v142, v179
	v_ashrrev_i32_e32 v225, 31, v224
	v_lshl_add_u64 v[224:225], v[224:225], 3, v[132:133]
	global_load_dwordx2 v[224:225], v[224:225], off
	ds_bpermute_b32 v254, v188, v126
	v_cndmask_b32_e32 v226, v149, v186, vcc
	v_lshl_add_u32 v226, v226, v142, v179
	v_ashrrev_i32_e32 v227, 31, v226
	v_lshl_add_u64 v[226:227], v[226:227], 3, v[132:133]
	global_load_dwordx2 v[226:227], v[226:227], off
	ds_bpermute_b32 v255, v188, v127
	s_waitcnt lgkmcnt(0)
; DI u16 f2bf(float a) { return (u16)(pk2(a, 0.f) & 0xffffu); }
; template <int EPI>
; __device__ __forceinline__ void gemm_tile(const Params& p, int layer, const u16* __restrict__ A, const u16* __restrict__ Bt, int mt, int nt, char* lds) {
;     ...
;             const f32x2 cs = tab[pos * nf + f];
;             const float v = acc[i][j][e];
;             const float o = __shfl_xor(v, 1);
;             const float res = (gc & 1) ? (o * cs[1] + v * cs[0]) : (v * cs[0] - o * cs[1]);
;             P[(size_t)gr * LDP + gc] = f2bf(res);
;           }
	s_waitcnt vmcnt(15)
	v_mul_f32_e32 v240, v191, v240
	v_cndmask_b32_e64 v240, v240, -v240, s[4:5]
	v_fmac_f32_e32 v240, v112, v190
	v_cvt_pk_bf16_f32 v240, v240, s0
	v_mad_i64_i32 v[190:191], s[12:13], v170, s95, v[134:135]
	global_store_short v[190:191], v240, off
	s_waitcnt vmcnt(15)
	v_mul_f32_e32 v241, v193, v241
	v_cndmask_b32_e64 v241, v241, -v241, s[4:5]
	v_fmac_f32_e32 v241, v113, v192
	v_cvt_pk_bf16_f32 v241, v241, s0
	v_mad_i64_i32 v[192:193], s[12:13], v175, s95, v[134:135]
	global_store_short v[192:193], v241, off
	s_waitcnt vmcnt(15)
	v_mul_f32_e32 v242, v195, v242
	v_cndmask_b32_e64 v242, v242, -v242, s[4:5]
	v_fmac_f32_e32 v242, v114, v194
	v_cvt_pk_bf16_f32 v242, v242, s0
	v_mad_i64_i32 v[194:195], s[12:13], v173, s95, v[134:135]
	global_store_short v[194:195], v242, off
	s_waitcnt vmcnt(15)
	v_mul_f32_e32 v243, v197, v243
	v_cndmask_b32_e64 v243, v243, -v243, s[4:5]
	v_fmac_f32_e32 v243, v115, v196
	v_cvt_pk_bf16_f32 v243, v243, s0
	v_mad_i64_i32 v[196:197], s[12:13], v171, s95, v[134:135]
	global_store_short v[196:197], v243, off
	s_waitcnt vmcnt(15)
	v_mul_f32_e32 v244, v199, v244
	v_cndmask_b32_e64 v244, v244, -v244, s[4:5]
	v_fmac_f32_e32 v244, v116, v198
	v_cvt_pk_bf16_f32 v244, v244, s0
	v_mad_i64_i32 v[198:199], s[12:13], v168, s95, v[134:135]
	global_store_short v[198:199], v244, off
	s_waitcnt vmcnt(15)
	v_mul_f32_e32 v245, v201, v245
	v_cndmask_b32_e64 v245, v245, -v245, s[4:5]
	v_fmac_f32_e32 v245, v117, v200
	v_cvt_pk_bf16_f32 v245, v245, s0
	v_mad_i64_i32 v[200:201], s[12:13], v166, s95, v[134:135]
	global_store_short v[200:201], v245, off
	s_waitcnt vmcnt(15)
	v_mul_f32_e32 v246, v203, v246
	v_cndmask_b32_e64 v246, v246, -v246, s[4:5]
	v_fmac_f32_e32 v246, v118, v202
	v_cvt_pk_bf16_f32 v246, v246, s0
	v_mad_i64_i32 v[202:203], s[12:13], v164, s95, v[134:135]
	global_store_short v[202:203], v246, off
	s_waitcnt vmcnt(15)
	v_mul_f32_e32 v247, v205, v247
	v_cndmask_b32_e64 v247, v247, -v247, s[4:5]
	v_fmac_f32_e32 v247, v119, v204
	v_cvt_pk_bf16_f32 v247, v247, s0
	v_mad_i64_i32 v[204:205], s[12:13], v162, s95, v[134:135]
	global_store_short v[204:205], v247, off
	s_waitcnt vmcnt(15)
	v_mul_f32_e32 v248, v207, v248
	v_cndmask_b32_e64 v248, v248, -v248, s[4:5]
	v_fmac_f32_e32 v248, v120, v206
	v_cvt_pk_bf16_f32 v248, v248, s0
	v_mad_i64_i32 v[206:207], s[12:13], v160, s95, v[134:135]
	global_store_short v[206:207], v248, off
	s_waitcnt vmcnt(15)
	v_mul_f32_e32 v249, v209, v249
	v_cndmask_b32_e64 v249, v249, -v249, s[4:5]
	v_fmac_f32_e32 v249, v121, v208
	v_cvt_pk_bf16_f32 v249, v249, s0
	v_mad_i64_i32 v[208:209], s[12:13], v158, s95, v[134:135]
	global_store_short v[208:209], v249, off
	s_waitcnt vmcnt(15)
	v_mul_f32_e32 v250, v217, v250
	v_cndmask_b32_e64 v250, v250, -v250, s[4:5]
	v_fmac_f32_e32 v250, v122, v216
	v_cvt_pk_bf16_f32 v250, v250, s0
	v_mad_i64_i32 v[216:217], s[12:13], v156, s95, v[134:135]
	global_store_short v[216:217], v250, off
	s_waitcnt vmcnt(15)
	v_mul_f32_e32 v251, v219, v251
	v_cndmask_b32_e64 v251, v251, -v251, s[4:5]
	v_fmac_f32_e32 v251, v123, v218
	v_cvt_pk_bf16_f32 v251, v251, s0
	v_mad_i64_i32 v[218:219], s[12:13], v154, s95, v[134:135]
	global_store_short v[218:219], v251, off
	s_waitcnt vmcnt(15)
	v_mul_f32_e32 v252, v221, v252
	v_cndmask_b32_e64 v252, v252, -v252, s[4:5]
	v_fmac_f32_e32 v252, v124, v220
	v_cvt_pk_bf16_f32 v252, v252, s0
	v_mad_i64_i32 v[220:221], s[12:13], v152, s95, v[134:135]
	global_store_short v[220:221], v252, off
	s_waitcnt vmcnt(15)
	v_mul_f32_e32 v253, v223, v253
	v_cndmask_b32_e64 v253, v253, -v253, s[4:5]
	v_fmac_f32_e32 v253, v125, v222
	v_cvt_pk_bf16_f32 v253, v253, s0
	v_mad_i64_i32 v[222:223], s[12:13], v150, s95, v[134:135]
	global_store_short v[222:223], v253, off
	s_waitcnt vmcnt(15)
	v_mul_f32_e32 v254, v225, v254
	v_cndmask_b32_e64 v254, v254, -v254, s[4:5]
	v_fmac_f32_e32 v254, v126, v224
	v_cvt_pk_bf16_f32 v254, v254, s0
	v_mad_i64_i32 v[224:225], s[12:13], v148, s95, v[134:135]
	global_store_short v[224:225], v254, off
	s_waitcnt vmcnt(15)
	v_mul_f32_e32 v255, v227, v255
	v_cndmask_b32_e64 v255, v255, -v255, s[4:5]
	v_fmac_f32_e32 v255, v127, v226
	v_cvt_pk_bf16_f32 v255, v255, s0
	v_mad_i64_i32 v[226:227], s[12:13], v147, s95, v[134:135]
	global_store_short v[226:227], v255, off

; DI int crow(int i, int h) { return (i & 3) + 8 * (i >> 2) + 4 * h; }
; template <int EPI>
; __device__ __forceinline__ void gemm_tile(const Params& p, int layer, const u16* __restrict__ A, const u16* __restrict__ Bt, int mt, int nt, char* lds) {
;     ...
;         const bool ropeA = gcb < 1024, ropeB = (gcb >= 1536 && gcb < 2816);
;         const bool latent = m0 >= NCTX;
;         if (latent && (ropeA || ropeB)) {
;           int pair, nf; bool userow; const f32x2* tab;
;           if (ropeA) { pair = (gc & 63) >> 1; nf = 16; tab = (const f32x2*)(p.ws + OFF_TABA); }
;           else       { pair = (gc & 127) >> 1; nf = 32; tab = (const f32x2*)(p.ws + OFF_TABB); }
;           userow = pair < nf;
;           const int f = userow ? pair : pair - nf;
; #pragma unroll
;           for (int e = 0; e < 16; ++e) {
;             const int gr = grb + crow(e, h);
;             const int t = gr - NCTX;
;             const int pos = userow ? (t >> 6) : (t & 63);
;             const f32x2 cs = tab[pos * nf + f];
;             const float v = acc[i][j][e];
;             const float o = __shfl_xor(v, 1);
.LBB0_1275:
	s_or_b64 exec, exec, s[6:7]
	v_cndmask_b32_e64 v123, 63, 31, s[12:13]
	v_cndmask_b32_e64 v112, v140, v141, s[12:13]
	v_cndmask_b32_e64 v122, 32, 16, s[12:13]
	v_cndmask_b32_e64 v120, 5, 4, s[12:13]
	s_and_saveexec_b64 s[8:9], s[16:17]
	s_cbranch_execz .LBB0_1277
	v_lshrrev_b32_e32 v114, 1, v116
	v_mov_b32_e32 v113, v129
	v_and_b32_e32 v117, v114, v123
	v_lshl_add_u64 v[114:115], s[22:23], 0, v[112:113]
	v_sub_u32_e32 v113, v117, v122
	v_ashrrev_i32_e32 v179, 6, v178
	v_cmp_lt_u32_e32 vcc, v117, v122
	v_min_u32_e32 v113, v117, v113
	s_waitcnt lgkmcnt(0)
	v_and_b32_e32 v132, 64, v214
	v_mov_b64_e32 v[118:119], s[28:29]
	v_xor_b32_e32 v134, 1, v214
	v_add_u32_e32 v135, 64, v132
	v_cmp_lt_i32_e64 s[6:7], v134, v135
	v_and_b32_e32 v180, 1, v116
	v_ashrrev_i32_e32 v117, 31, v116
	v_cndmask_b32_e64 v134, v214, v134, s[6:7]
	v_lshlrev_b32_e32 v181, 2, v134
	v_cmp_eq_u32_e64 s[6:7], 0, v180
	v_lshlrev_b64 v[116:117], 1, v[116:117]
	s_nop 1
	v_cndmask_b32_e32 v190, v136, v179, vcc
	v_lshl_add_u32 v190, v190, v120, v113
	v_ashrrev_i32_e32 v191, 31, v190
	v_lshl_add_u64 v[190:191], v[190:191], 3, v[114:115]
	global_load_dwordx2 v[190:191], v[190:191], off
	ds_bpermute_b32 v240, v181, v96
	v_cndmask_b32_e32 v192, v177, v179, vcc
	v_lshl_add_u32 v192, v192, v120, v113
	v_ashrrev_i32_e32 v193, 31, v192
	v_lshl_add_u64 v[192:193], v[192:193], 3, v[114:115]
	global_load_dwordx2 v[192:193], v[192:193], off
	ds_bpermute_b32 v241, v181, v97
	v_cndmask_b32_e32 v194, v176, v179, vcc
	v_lshl_add_u32 v194, v194, v120, v113
	v_ashrrev_i32_e32 v195, 31, v194
	v_lshl_add_u64 v[194:195], v[194:195], 3, v[114:115]
	global_load_dwordx2 v[194:195], v[194:195], off
	ds_bpermute_b32 v242, v181, v98
	v_cndmask_b32_e32 v196, v174, v179, vcc
	v_lshl_add_u32 v196, v196, v120, v113
	v_ashrrev_i32_e32 v197, 31, v196
	v_lshl_add_u64 v[196:197], v[196:197], 3, v[114:115]
	global_load_dwordx2 v[196:197], v[196:197], off
	ds_bpermute_b32 v243, v181, v99
	v_cndmask_b32_e32 v198, v172, v179, vcc
	v_lshl_add_u32 v198, v198, v120, v113
	v_ashrrev_i32_e32 v199, 31, v198
	v_lshl_add_u64 v[198:199], v[198:199], 3, v[114:115]
	global_load_dwordx2 v[198:199], v[198:199], off
	ds_bpermute_b32 v244, v181, v100
	v_cndmask_b32_e32 v200, v169, v179, vcc
	v_lshl_add_u32 v200, v200, v120, v113
	v_ashrrev_i32_e32 v201, 31, v200
	v_lshl_add_u64 v[200:201], v[200:201], 3, v[114:115]
	global_load_dwordx2 v[200:201], v[200:201], off
	ds_bpermute_b32 v245, v181, v101
	v_cndmask_b32_e32 v202, v167, v179, vcc
	v_lshl_add_u32 v202, v202, v120, v113
	v_ashrrev_i32_e32 v203, 31, v202
	v_lshl_add_u64 v[202:203], v[202:203], 3, v[114:115]
	global_load_dwordx2 v[202:203], v[202:203], off
	ds_bpermute_b32 v246, v181, v102
	v_cndmask_b32_e32 v204, v165, v179, vcc
	v_lshl_add_u32 v204, v204, v120, v113
	v_ashrrev_i32_e32 v205, 31, v204
	v_lshl_add_u64 v[204:205], v[204:205], 3, v[114:115]
	global_load_dwordx2 v[204:205], v[204:205], off
	ds_bpermute_b32 v247, v181, v103
	v_cndmask_b32_e32 v206, v163, v179, vcc
	v_lshl_add_u32 v206, v206, v120, v113
	v_ashrrev_i32_e32 v207, 31, v206
	v_lshl_add_u64 v[206:207], v[206:207], 3, v[114:115]
	global_load_dwordx2 v[206:207], v[206:207], off
	ds_bpermute_b32 v248, v181, v104
	v_cndmask_b32_e32 v208, v161, v179, vcc
	v_lshl_add_u32 v208, v208, v120, v113
	v_ashrrev_i32_e32 v209, 31, v208
	v_lshl_add_u64 v[208:209], v[208:209], 3, v[114:115]
	global_load_dwordx2 v[208:209], v[208:209], off
	ds_bpermute_b32 v249, v181, v105
	v_cndmask_b32_e32 v216, v159, v179, vcc
	v_lshl_add_u32 v216, v216, v120, v113
	v_ashrrev_i32_e32 v217, 31, v216
	v_lshl_add_u64 v[216:217], v[216:217], 3, v[114:115]
	global_load_dwordx2 v[216:217], v[216:217], off
	ds_bpermute_b32 v250, v181, v106
	v_cndmask_b32_e32 v218, v157, v179, vcc
	v_lshl_add_u32 v218, v218, v120, v113
	v_ashrrev_i32_e32 v219, 31, v218
	v_lshl_add_u64 v[218:219], v[218:219], 3, v[114:115]
	global_load_dwordx2 v[218:219], v[218:219], off
	ds_bpermute_b32 v251, v181, v107
	v_cndmask_b32_e32 v220, v155, v179, vcc
	v_lshl_add_u32 v220, v220, v120, v113
	v_ashrrev_i32_e32 v221, 31, v220
	v_lshl_add_u64 v[220:221], v[220:221], 3, v[114:115]
	global_load_dwordx2 v[220:221], v[220:221], off
	ds_bpermute_b32 v252, v181, v108
	v_cndmask_b32_e32 v222, v153, v179, vcc
	v_lshl_add_u32 v222, v222, v120, v113
	v_ashrrev_i32_e32 v223, 31, v222
	v_lshl_add_u64 v[222:223], v[222:223], 3, v[114:115]
	global_load_dwordx2 v[222:223], v[222:223], off
	ds_bpermute_b32 v253, v181, v109
	v_cndmask_b32_e32 v224, v151, v179, vcc
	v_lshl_add_u32 v224, v224, v120, v113
	v_ashrrev_i32_e32 v225, 31, v224
	v_lshl_add_u64 v[224:225], v[224:225], 3, v[114:115]
	global_load_dwordx2 v[224:225], v[224:225], off
	ds_bpermute_b32 v254, v181, v110
	v_cndmask_b32_e32 v226, v149, v179, vcc
	v_lshl_add_u32 v226, v226, v120, v113
	v_ashrrev_i32_e32 v227, 31, v226
	v_lshl_add_u64 v[226:227], v[226:227], 3, v[114:115]
	global_load_dwordx2 v[226:227], v[226:227], off
	ds_bpermute_b32 v255, v181, v111
	s_waitcnt lgkmcnt(0)
	s_waitcnt vmcnt(15)
; DI u16 f2bf(float a) { return (u16)(pk2(a, 0.f) & 0xffffu); }
; template <int EPI>
; __device__ __forceinline__ void gemm_tile(const Params& p, int layer, const u16* __restrict__ A, const u16* __restrict__ Bt, int mt, int nt, char* lds) {
;     ...
;             const f32x2 cs = tab[pos * nf + f];
;             const float v = acc[i][j][e];
;             const float o = __shfl_xor(v, 1);
;             const float res = (gc & 1) ? (o * cs[1] + v * cs[0]) : (v * cs[0] - o * cs[1]);
;             P[(size_t)gr * LDP + gc] = f2bf(res);
;           }
	v_mul_f32_e32 v240, v191, v240
	v_cndmask_b32_e64 v240, v240, -v240, s[6:7]
	v_fmac_f32_e32 v240, v96, v190
	v_cvt_pk_bf16_f32 v240, v240, s0
	v_mad_i64_i32 v[190:191], s[16:17], v170, s95, v[118:119]
	v_lshl_add_u64 v[190:191], v[190:191], 0, v[116:117]
	global_store_short v[190:191], v240, off
	s_waitcnt vmcnt(15)
	v_mul_f32_e32 v241, v193, v241
	v_cndmask_b32_e64 v241, v241, -v241, s[6:7]
	v_fmac_f32_e32 v241, v97, v192
	v_cvt_pk_bf16_f32 v241, v241, s0
	v_mad_i64_i32 v[192:193], s[16:17], v175, s95, v[118:119]
	v_lshl_add_u64 v[192:193], v[192:193], 0, v[116:117]
	global_store_short v[192:193], v241, off
	s_waitcnt vmcnt(15)
	v_mul_f32_e32 v242, v195, v242
	v_cndmask_b32_e64 v242, v242, -v242, s[6:7]
	v_fmac_f32_e32 v242, v98, v194
	v_cvt_pk_bf16_f32 v242, v242, s0
	v_mad_i64_i32 v[194:195], s[16:17], v173, s95, v[118:119]
	v_lshl_add_u64 v[194:195], v[194:195], 0, v[116:117]
	global_store_short v[194:195], v242, off
	s_waitcnt vmcnt(15)
	v_mul_f32_e32 v243, v197, v243
	v_cndmask_b32_e64 v243, v243, -v243, s[6:7]
	v_fmac_f32_e32 v243, v99, v196
	v_cvt_pk_bf16_f32 v243, v243, s0
	v_mad_i64_i32 v[196:197], s[16:17], v171, s95, v[118:119]
	v_lshl_add_u64 v[196:197], v[196:197], 0, v[116:117]
	global_store_short v[196:197], v243, off
	s_waitcnt vmcnt(15)
	v_mul_f32_e32 v244, v199, v244
	v_cndmask_b32_e64 v244, v244, -v244, s[6:7]
	v_fmac_f32_e32 v244, v100, v198
	v_cvt_pk_bf16_f32 v244, v244, s0
	v_mad_i64_i32 v[198:199], s[16:17], v168, s95, v[118:119]
	v_lshl_add_u64 v[198:199], v[198:199], 0, v[116:117]
	global_store_short v[198:199], v244, off
	s_waitcnt vmcnt(15)
	v_mul_f32_e32 v245, v201, v245
	v_cndmask_b32_e64 v245, v245, -v245, s[6:7]
	v_fmac_f32_e32 v245, v101, v200
	v_cvt_pk_bf16_f32 v245, v245, s0
	v_mad_i64_i32 v[200:201], s[16:17], v166, s95, v[118:119]
	v_lshl_add_u64 v[200:201], v[200:201], 0, v[116:117]
	global_store_short v[200:201], v245, off
	s_waitcnt vmcnt(15)
	v_mul_f32_e32 v246, v203, v246
	v_cndmask_b32_e64 v246, v246, -v246, s[6:7]
	v_fmac_f32_e32 v246, v102, v202
	v_cvt_pk_bf16_f32 v246, v246, s0
	v_mad_i64_i32 v[202:203], s[16:17], v164, s95, v[118:119]
	v_lshl_add_u64 v[202:203], v[202:203], 0, v[116:117]
	global_store_short v[202:203], v246, off
	s_waitcnt vmcnt(15)
	v_mul_f32_e32 v247, v205, v247
	v_cndmask_b32_e64 v247, v247, -v247, s[6:7]
	v_fmac_f32_e32 v247, v103, v204
	v_cvt_pk_bf16_f32 v247, v247, s0
	v_mad_i64_i32 v[204:205], s[16:17], v162, s95, v[118:119]
	v_lshl_add_u64 v[204:205], v[204:205], 0, v[116:117]
	global_store_short v[204:205], v247, off
	s_waitcnt vmcnt(15)
	v_mul_f32_e32 v248, v207, v248
	v_cndmask_b32_e64 v248, v248, -v248, s[6:7]
	v_fmac_f32_e32 v248, v104, v206
	v_cvt_pk_bf16_f32 v248, v248, s0
	v_mad_i64_i32 v[206:207], s[16:17], v160, s95, v[118:119]
	v_lshl_add_u64 v[206:207], v[206:207], 0, v[116:117]
	global_store_short v[206:207], v248, off
	s_waitcnt vmcnt(15)
	v_mul_f32_e32 v249, v209, v249
	v_cndmask_b32_e64 v249, v249, -v249, s[6:7]
	v_fmac_f32_e32 v249, v105, v208
	v_cvt_pk_bf16_f32 v249, v249, s0
	v_mad_i64_i32 v[208:209], s[16:17], v158, s95, v[118:119]
	v_lshl_add_u64 v[208:209], v[208:209], 0, v[116:117]
	global_store_short v[208:209], v249, off
	s_waitcnt vmcnt(15)
	v_mul_f32_e32 v250, v217, v250
	v_cndmask_b32_e64 v250, v250, -v250, s[6:7]
	v_fmac_f32_e32 v250, v106, v216
	v_cvt_pk_bf16_f32 v250, v250, s0
	v_mad_i64_i32 v[216:217], s[16:17], v156, s95, v[118:119]
	v_lshl_add_u64 v[216:217], v[216:217], 0, v[116:117]
	global_store_short v[216:217], v250, off
	s_waitcnt vmcnt(15)
	v_mul_f32_e32 v251, v219, v251
	v_cndmask_b32_e64 v251, v251, -v251, s[6:7]
	v_fmac_f32_e32 v251, v107, v218
	v_cvt_pk_bf16_f32 v251, v251, s0
	v_mad_i64_i32 v[218:219], s[16:17], v154, s95, v[118:119]
	v_lshl_add_u64 v[218:219], v[218:219], 0, v[116:117]
	global_store_short v[218:219], v251, off
	s_waitcnt vmcnt(15)
	v_mul_f32_e32 v252, v221, v252
	v_cndmask_b32_e64 v252, v252, -v252, s[6:7]
	v_fmac_f32_e32 v252, v108, v220
	v_cvt_pk_bf16_f32 v252, v252, s0
	v_mad_i64_i32 v[220:221], s[16:17], v152, s95, v[118:119]
	v_lshl_add_u64 v[220:221], v[220:221], 0, v[116:117]
	global_store_short v[220:221], v252, off
	s_waitcnt vmcnt(15)
	v_mul_f32_e32 v253, v223, v253
	v_cndmask_b32_e64 v253, v253, -v253, s[6:7]
	v_fmac_f32_e32 v253, v109, v222
	v_cvt_pk_bf16_f32 v253, v253, s0
	v_mad_i64_i32 v[222:223], s[16:17], v150, s95, v[118:119]
	v_lshl_add_u64 v[222:223], v[222:223], 0, v[116:117]
	global_store_short v[222:223], v253, off
	s_waitcnt vmcnt(15)
	v_mul_f32_e32 v254, v225, v254
	v_cndmask_b32_e64 v254, v254, -v254, s[6:7]
	v_fmac_f32_e32 v254, v110, v224
	v_cvt_pk_bf16_f32 v254, v254, s0
	v_mad_i64_i32 v[224:225], s[16:17], v148, s95, v[118:119]
	v_lshl_add_u64 v[224:225], v[224:225], 0, v[116:117]
	global_store_short v[224:225], v254, off
	s_waitcnt vmcnt(15)
	v_mul_f32_e32 v255, v227, v255
	v_cndmask_b32_e64 v255, v255, -v255, s[6:7]
	v_fmac_f32_e32 v255, v111, v226
	v_cvt_pk_bf16_f32 v255, v255, s0
	v_mad_i64_i32 v[226:227], s[16:17], v147, s95, v[118:119]
	v_lshl_add_u64 v[226:227], v[226:227], 0, v[116:117]
	global_store_short v[226:227], v255, off

; DI u16 f2bf(float a) { return (u16)(pk2(a, 0.f) & 0xffffu); }
; DI int crow(int i, int h) { return (i & 3) + 8 * (i >> 2) + 4 * h; }
; template <int EPI>
; __device__ __forceinline__ void gemm_tile(const Params& p, int layer, const u16* __restrict__ A, const u16* __restrict__ Bt, int mt, int nt, char* lds) {
;     ...
;         const bool ropeA = gcb < 1024, ropeB = (gcb >= 1536 && gcb < 2816);
;         const bool latent = m0 >= NCTX;
;         if (latent && (ropeA || ropeB)) {
;           int pair, nf; bool userow; const f32x2* tab;
;           if (ropeA) { pair = (gc & 63) >> 1; nf = 16; tab = (const f32x2*)(p.ws + OFF_TABA); }
;           else       { pair = (gc & 127) >> 1; nf = 32; tab = (const f32x2*)(p.ws + OFF_TABB); }
;           userow = pair < nf;
;           const int f = userow ? pair : pair - nf;
; #pragma unroll
;           for (int e = 0; e < 16; ++e) {
;             const int gr = grb + crow(e, h);
;             const int t = gr - NCTX;
;             const int pos = userow ? (t >> 6) : (t & 63);
;             const f32x2 cs = tab[pos * nf + f];
;             const float v = acc[i][j][e];
;             const float o = __shfl_xor(v, 1);
;             const float res = (gc & 1) ? (o * cs[1] + v * cs[0]) : (v * cs[0] - o * cs[1]);
;             P[(size_t)gr * LDP + gc] = f2bf(res);
;           }
.LBB0_1360:
	v_lshrrev_b32_e32 v48, 1, v50
	v_and_b32_e32 v51, v48, v123
	v_sub_u32_e32 v52, v51, v122
	v_ashrrev_i32_e32 v61, 6, v118
	v_cmp_lt_u32_e32 vcc, v51, v122
	v_min_u32_e32 v60, v51, v52
	v_mov_b32_e32 v113, v129
	v_lshl_add_u64 v[48:49], s[22:23], 0, v[112:113]
	v_and_b32_e32 v56, 64, v214
	v_mov_b64_e32 v[52:53], s[28:29]
	v_xor_b32_e32 v58, 1, v214
	v_add_u32_e32 v59, 64, v56
	v_cmp_lt_i32_e64 s[10:11], v58, v59
	v_and_b32_e32 v62, 1, v50
	v_ashrrev_i32_e32 v51, 31, v50
	v_cndmask_b32_e64 v58, v214, v58, s[10:11]
	v_lshlrev_b32_e32 v63, 2, v58
	v_cmp_eq_u32_e64 s[10:11], 0, v62
	v_lshlrev_b64 v[50:51], 1, v[50:51]
	s_nop 1
	v_cndmask_b32_e32 v190, v117, v61, vcc
	v_lshl_add_u32 v190, v190, v120, v60
	v_ashrrev_i32_e32 v191, 31, v190
	v_lshl_add_u64 v[190:191], v[190:191], 3, v[48:49]
	global_load_dwordx2 v[190:191], v[190:191], off
	ds_bpermute_b32 v240, v63, v32
	v_cndmask_b32_e32 v192, v116, v61, vcc
	v_lshl_add_u32 v192, v192, v120, v60
	v_ashrrev_i32_e32 v193, 31, v192
	v_lshl_add_u64 v[192:193], v[192:193], 3, v[48:49]
	global_load_dwordx2 v[192:193], v[192:193], off
	ds_bpermute_b32 v241, v63, v33
	v_cndmask_b32_e32 v194, v115, v61, vcc
	v_lshl_add_u32 v194, v194, v120, v60
	v_ashrrev_i32_e32 v195, 31, v194
	v_lshl_add_u64 v[194:195], v[194:195], 3, v[48:49]
	global_load_dwordx2 v[194:195], v[194:195], off
	ds_bpermute_b32 v242, v63, v34
	v_cndmask_b32_e32 v196, v111, v61, vcc
	v_lshl_add_u32 v196, v196, v120, v60
	v_ashrrev_i32_e32 v197, 31, v196
	v_lshl_add_u64 v[196:197], v[196:197], 3, v[48:49]
	global_load_dwordx2 v[196:197], v[196:197], off
	ds_bpermute_b32 v243, v63, v35
	v_cndmask_b32_e32 v198, v103, v61, vcc
	v_lshl_add_u32 v198, v198, v120, v60
	v_ashrrev_i32_e32 v199, 31, v198
	v_lshl_add_u64 v[198:199], v[198:199], 3, v[48:49]
	global_load_dwordx2 v[198:199], v[198:199], off
	ds_bpermute_b32 v244, v63, v36
	v_cndmask_b32_e32 v200, v101, v61, vcc
	v_lshl_add_u32 v200, v200, v120, v60
	v_ashrrev_i32_e32 v201, 31, v200
	v_lshl_add_u64 v[200:201], v[200:201], 3, v[48:49]
	global_load_dwordx2 v[200:201], v[200:201], off
	ds_bpermute_b32 v245, v63, v37
	v_cndmask_b32_e32 v202, v99, v61, vcc
	v_lshl_add_u32 v202, v202, v120, v60
	v_ashrrev_i32_e32 v203, 31, v202
	v_lshl_add_u64 v[202:203], v[202:203], 3, v[48:49]
	global_load_dwordx2 v[202:203], v[202:203], off
	ds_bpermute_b32 v246, v63, v38
	v_cndmask_b32_e32 v204, v95, v61, vcc
	v_lshl_add_u32 v204, v204, v120, v60
	v_ashrrev_i32_e32 v205, 31, v204
	v_lshl_add_u64 v[204:205], v[204:205], 3, v[48:49]
	global_load_dwordx2 v[204:205], v[204:205], off
	ds_bpermute_b32 v247, v63, v39
	v_cndmask_b32_e32 v206, v87, v61, vcc
	v_lshl_add_u32 v206, v206, v120, v60
	v_ashrrev_i32_e32 v207, 31, v206
	v_lshl_add_u64 v[206:207], v[206:207], 3, v[48:49]
	global_load_dwordx2 v[206:207], v[206:207], off
	ds_bpermute_b32 v248, v63, v40
	v_cndmask_b32_e32 v208, v85, v61, vcc
	v_lshl_add_u32 v208, v208, v120, v60
	v_ashrrev_i32_e32 v209, 31, v208
	v_lshl_add_u64 v[208:209], v[208:209], 3, v[48:49]
	global_load_dwordx2 v[208:209], v[208:209], off
	ds_bpermute_b32 v249, v63, v41
	v_cndmask_b32_e32 v216, v83, v61, vcc
	v_lshl_add_u32 v216, v216, v120, v60
	v_ashrrev_i32_e32 v217, 31, v216
	v_lshl_add_u64 v[216:217], v[216:217], 3, v[48:49]
	global_load_dwordx2 v[216:217], v[216:217], off
	ds_bpermute_b32 v250, v63, v42
	v_cndmask_b32_e32 v218, v78, v61, vcc
	v_lshl_add_u32 v218, v218, v120, v60
	v_ashrrev_i32_e32 v219, 31, v218
	v_lshl_add_u64 v[218:219], v[218:219], 3, v[48:49]
	global_load_dwordx2 v[218:219], v[218:219], off
	ds_bpermute_b32 v251, v63, v43
	v_cndmask_b32_e32 v220, v76, v61, vcc
	v_lshl_add_u32 v220, v220, v120, v60
	v_ashrrev_i32_e32 v221, 31, v220
	v_lshl_add_u64 v[220:221], v[220:221], 3, v[48:49]
	global_load_dwordx2 v[220:221], v[220:221], off
	ds_bpermute_b32 v252, v63, v44
	v_cndmask_b32_e32 v222, v74, v61, vcc
	v_lshl_add_u32 v222, v222, v120, v60
	v_ashrrev_i32_e32 v223, 31, v222
	v_lshl_add_u64 v[222:223], v[222:223], 3, v[48:49]
	global_load_dwordx2 v[222:223], v[222:223], off
	ds_bpermute_b32 v253, v63, v45
	v_cndmask_b32_e32 v224, v72, v61, vcc
	v_lshl_add_u32 v224, v224, v120, v60
	v_ashrrev_i32_e32 v225, 31, v224
	v_lshl_add_u64 v[224:225], v[224:225], 3, v[48:49]
	global_load_dwordx2 v[224:225], v[224:225], off
	ds_bpermute_b32 v254, v63, v46
	v_cndmask_b32_e32 v226, v70, v61, vcc
	v_lshl_add_u32 v226, v226, v120, v60
	v_ashrrev_i32_e32 v227, 31, v226
	v_lshl_add_u64 v[226:227], v[226:227], 3, v[48:49]
	global_load_dwordx2 v[226:227], v[226:227], off
	ds_bpermute_b32 v255, v63, v47
	s_waitcnt lgkmcnt(0)
	s_waitcnt vmcnt(15)
	v_mul_f32_e32 v240, v191, v240
	v_cndmask_b32_e64 v240, v240, -v240, s[10:11]
	v_fmac_f32_e32 v240, v32, v190
	v_cvt_pk_bf16_f32 v240, v240, s0
	v_mad_i64_i32 v[190:191], s[14:15], v79, s95, v[52:53]
	v_lshl_add_u64 v[190:191], v[190:191], 0, v[50:51]
	global_store_short v[190:191], v240, off
	s_waitcnt vmcnt(15)
; DI u16 f2bf(float a) { return (u16)(pk2(a, 0.f) & 0xffffu); }
; template <int EPI>
; __device__ __forceinline__ void gemm_tile(const Params& p, int layer, const u16* __restrict__ A, const u16* __restrict__ Bt, int mt, int nt, char* lds) {
;     ...
;             const f32x2 cs = tab[pos * nf + f];
;             const float v = acc[i][j][e];
;             const float o = __shfl_xor(v, 1);
;             const float res = (gc & 1) ? (o * cs[1] + v * cs[0]) : (v * cs[0] - o * cs[1]);
;             P[(size_t)gr * LDP + gc] = f2bf(res);
;           }
	v_mul_f32_e32 v241, v193, v241
	v_cndmask_b32_e64 v241, v241, -v241, s[10:11]
	v_fmac_f32_e32 v241, v33, v192
	v_cvt_pk_bf16_f32 v241, v241, s0
	v_mad_i64_i32 v[192:193], s[14:15], v114, s95, v[52:53]
	v_lshl_add_u64 v[192:193], v[192:193], 0, v[50:51]
	global_store_short v[192:193], v241, off
	s_waitcnt vmcnt(15)
	v_mul_f32_e32 v242, v195, v242
	v_cndmask_b32_e64 v242, v242, -v242, s[10:11]
	v_fmac_f32_e32 v242, v34, v194
	v_cvt_pk_bf16_f32 v242, v242, s0
	v_mad_i64_i32 v[194:195], s[14:15], v110, s95, v[52:53]
	v_lshl_add_u64 v[194:195], v[194:195], 0, v[50:51]
	global_store_short v[194:195], v242, off
	s_waitcnt vmcnt(15)
	v_mul_f32_e32 v243, v197, v243
	v_cndmask_b32_e64 v243, v243, -v243, s[10:11]
	v_fmac_f32_e32 v243, v35, v196
	v_cvt_pk_bf16_f32 v243, v243, s0
	v_mad_i64_i32 v[196:197], s[14:15], v102, s95, v[52:53]
	v_lshl_add_u64 v[196:197], v[196:197], 0, v[50:51]
	global_store_short v[196:197], v243, off
	s_waitcnt vmcnt(15)
	v_mul_f32_e32 v244, v199, v244
	v_cndmask_b32_e64 v244, v244, -v244, s[10:11]
	v_fmac_f32_e32 v244, v36, v198
	v_cvt_pk_bf16_f32 v244, v244, s0
	v_mad_i64_i32 v[198:199], s[14:15], v100, s95, v[52:53]
	v_lshl_add_u64 v[198:199], v[198:199], 0, v[50:51]
	global_store_short v[198:199], v244, off
	s_waitcnt vmcnt(15)
	v_mul_f32_e32 v245, v201, v245
	v_cndmask_b32_e64 v245, v245, -v245, s[10:11]
	v_fmac_f32_e32 v245, v37, v200
	v_cvt_pk_bf16_f32 v245, v245, s0
	v_mad_i64_i32 v[200:201], s[14:15], v98, s95, v[52:53]
	v_lshl_add_u64 v[200:201], v[200:201], 0, v[50:51]
	global_store_short v[200:201], v245, off
	s_waitcnt vmcnt(15)
	v_mul_f32_e32 v246, v203, v246
	v_cndmask_b32_e64 v246, v246, -v246, s[10:11]
	v_fmac_f32_e32 v246, v38, v202
	v_cvt_pk_bf16_f32 v246, v246, s0
	v_mad_i64_i32 v[202:203], s[14:15], v94, s95, v[52:53]
	v_lshl_add_u64 v[202:203], v[202:203], 0, v[50:51]
	global_store_short v[202:203], v246, off
	s_waitcnt vmcnt(15)
	v_mul_f32_e32 v247, v205, v247
	v_cndmask_b32_e64 v247, v247, -v247, s[10:11]
	v_fmac_f32_e32 v247, v39, v204
	v_cvt_pk_bf16_f32 v247, v247, s0
	v_mad_i64_i32 v[204:205], s[14:15], v86, s95, v[52:53]
	v_lshl_add_u64 v[204:205], v[204:205], 0, v[50:51]
	global_store_short v[204:205], v247, off
	s_waitcnt vmcnt(15)
	v_mul_f32_e32 v248, v207, v248
	v_cndmask_b32_e64 v248, v248, -v248, s[10:11]
	v_fmac_f32_e32 v248, v40, v206
	v_cvt_pk_bf16_f32 v248, v248, s0
	v_mad_i64_i32 v[206:207], s[14:15], v84, s95, v[52:53]
	v_lshl_add_u64 v[206:207], v[206:207], 0, v[50:51]
	global_store_short v[206:207], v248, off
	s_waitcnt vmcnt(15)
	v_mul_f32_e32 v249, v209, v249
	v_cndmask_b32_e64 v249, v249, -v249, s[10:11]
	v_fmac_f32_e32 v249, v41, v208
	v_cvt_pk_bf16_f32 v249, v249, s0
	v_mad_i64_i32 v[208:209], s[14:15], v82, s95, v[52:53]
	v_lshl_add_u64 v[208:209], v[208:209], 0, v[50:51]
	global_store_short v[208:209], v249, off
	s_waitcnt vmcnt(15)
	v_mul_f32_e32 v250, v217, v250
	v_cndmask_b32_e64 v250, v250, -v250, s[10:11]
	v_fmac_f32_e32 v250, v42, v216
	v_cvt_pk_bf16_f32 v250, v250, s0
	v_mad_i64_i32 v[216:217], s[14:15], v77, s95, v[52:53]
	v_lshl_add_u64 v[216:217], v[216:217], 0, v[50:51]
	global_store_short v[216:217], v250, off
	s_waitcnt vmcnt(15)
	v_mul_f32_e32 v251, v219, v251
	v_cndmask_b32_e64 v251, v251, -v251, s[10:11]
	v_fmac_f32_e32 v251, v43, v218
	v_cvt_pk_bf16_f32 v251, v251, s0
	v_mad_i64_i32 v[218:219], s[14:15], v75, s95, v[52:53]
	v_lshl_add_u64 v[218:219], v[218:219], 0, v[50:51]
	global_store_short v[218:219], v251, off
	s_waitcnt vmcnt(15)
	v_mul_f32_e32 v252, v221, v252
	v_cndmask_b32_e64 v252, v252, -v252, s[10:11]
	v_fmac_f32_e32 v252, v44, v220
	v_cvt_pk_bf16_f32 v252, v252, s0
	v_mad_i64_i32 v[220:221], s[14:15], v73, s95, v[52:53]
	v_lshl_add_u64 v[220:221], v[220:221], 0, v[50:51]
	global_store_short v[220:221], v252, off
	s_waitcnt vmcnt(15)
	v_mul_f32_e32 v253, v223, v253
	v_cndmask_b32_e64 v253, v253, -v253, s[10:11]
	v_fmac_f32_e32 v253, v45, v222
	v_cvt_pk_bf16_f32 v253, v253, s0
	v_mad_i64_i32 v[222:223], s[14:15], v71, s95, v[52:53]
	v_lshl_add_u64 v[222:223], v[222:223], 0, v[50:51]
	global_store_short v[222:223], v253, off
	s_waitcnt vmcnt(15)
	v_mul_f32_e32 v254, v225, v254
	v_cndmask_b32_e64 v254, v254, -v254, s[10:11]
	v_fmac_f32_e32 v254, v46, v224
	v_cvt_pk_bf16_f32 v254, v254, s0
	v_mad_i64_i32 v[224:225], s[14:15], v69, s95, v[52:53]
	v_lshl_add_u64 v[224:225], v[224:225], 0, v[50:51]
	global_store_short v[224:225], v254, off
	s_waitcnt vmcnt(15)
	v_mul_f32_e32 v255, v227, v255
	v_cndmask_b32_e64 v255, v255, -v255, s[10:11]
	v_fmac_f32_e32 v255, v47, v226
	v_cvt_pk_bf16_f32 v255, v255, s0
	v_mad_i64_i32 v[226:227], s[14:15], v68, s95, v[52:53]
	v_lshl_add_u64 v[226:227], v[226:227], 0, v[50:51]
	global_store_short v[226:227], v255, off

; DI u16 f2bf(float a) { return (u16)(pk2(a, 0.f) & 0xffffu); }
; DI int crow(int i, int h) { return (i & 3) + 8 * (i >> 2) + 4 * h; }
; template <int EPI>
; __device__ __forceinline__ void gemm_tile(const Params& p, int layer, const u16* __restrict__ A, const u16* __restrict__ Bt, int mt, int nt, char* lds) {
;     ...
;         const bool ropeA = gcb < 1024, ropeB = (gcb >= 1536 && gcb < 2816);
;         const bool latent = m0 >= NCTX;
;         if (latent && (ropeA || ropeB)) {
;           int pair, nf; bool userow; const f32x2* tab;
;           if (ropeA) { pair = (gc & 63) >> 1; nf = 16; tab = (const f32x2*)(p.ws + OFF_TABA); }
;           else       { pair = (gc & 127) >> 1; nf = 32; tab = (const f32x2*)(p.ws + OFF_TABB); }
;           userow = pair < nf;
;           const int f = userow ? pair : pair - nf;
; #pragma unroll
;           for (int e = 0; e < 16; ++e) {
;             const int gr = grb + crow(e, h);
;             const int t = gr - NCTX;
;             const int pos = userow ? (t >> 6) : (t & 63);
;             const f32x2 cs = tab[pos * nf + f];
;             const float v = acc[i][j][e];
;             const float o = __shfl_xor(v, 1);
;             const float res = (gc & 1) ? (o * cs[1] + v * cs[0]) : (v * cs[0] - o * cs[1]);
;             P[(size_t)gr * LDP + gc] = f2bf(res);
;           }
.LBB0_1387:
	v_lshrrev_b32_e32 v32, 1, v34
	s_waitcnt lgkmcnt(0)
	v_and_b32_e32 v35, v32, v107
	v_sub_u32_e32 v36, v35, v106
	v_ashrrev_i32_e32 v45, 6, v118
	v_cmp_lt_u32_e32 vcc, v35, v106
	v_min_u32_e32 v44, v35, v36
	v_mov_b32_e32 v97, v129
	v_lshl_add_u64 v[32:33], s[22:23], 0, v[96:97]
	v_and_b32_e32 v40, 64, v214
	v_mov_b64_e32 v[36:37], s[28:29]
	v_xor_b32_e32 v42, 1, v214
	v_add_u32_e32 v43, 64, v40
	v_cmp_lt_i32_e64 s[0:1], v42, v43
	v_and_b32_e32 v46, 1, v34
	v_ashrrev_i32_e32 v35, 31, v34
	v_cndmask_b32_e64 v42, v214, v42, s[0:1]
	v_lshlrev_b32_e32 v47, 2, v42
	v_cmp_eq_u32_e64 s[0:1], 0, v46
	v_lshlrev_b64 v[34:35], 1, v[34:35]
	s_nop 1
	v_cndmask_b32_e32 v190, v117, v45, vcc
	v_lshl_add_u32 v190, v190, v105, v44
	v_ashrrev_i32_e32 v191, 31, v190
	v_lshl_add_u64 v[190:191], v[190:191], 3, v[32:33]
	global_load_dwordx2 v[190:191], v[190:191], off
	ds_bpermute_b32 v240, v47, v16
	v_cndmask_b32_e32 v192, v116, v45, vcc
	v_lshl_add_u32 v192, v192, v105, v44
	v_ashrrev_i32_e32 v193, 31, v192
	v_lshl_add_u64 v[192:193], v[192:193], 3, v[32:33]
	global_load_dwordx2 v[192:193], v[192:193], off
	ds_bpermute_b32 v241, v47, v17
	v_cndmask_b32_e32 v194, v115, v45, vcc
	v_lshl_add_u32 v194, v194, v105, v44
	v_ashrrev_i32_e32 v195, 31, v194
	v_lshl_add_u64 v[194:195], v[194:195], 3, v[32:33]
	global_load_dwordx2 v[194:195], v[194:195], off
	ds_bpermute_b32 v242, v47, v18
	v_cndmask_b32_e32 v196, v111, v45, vcc
	v_lshl_add_u32 v196, v196, v105, v44
	v_ashrrev_i32_e32 v197, 31, v196
	v_lshl_add_u64 v[196:197], v[196:197], 3, v[32:33]
	global_load_dwordx2 v[196:197], v[196:197], off
	ds_bpermute_b32 v243, v47, v19
	v_cndmask_b32_e32 v198, v103, v45, vcc
	v_lshl_add_u32 v198, v198, v105, v44
	v_ashrrev_i32_e32 v199, 31, v198
	v_lshl_add_u64 v[198:199], v[198:199], 3, v[32:33]
	global_load_dwordx2 v[198:199], v[198:199], off
	ds_bpermute_b32 v244, v47, v20
	v_cndmask_b32_e32 v200, v101, v45, vcc
	v_lshl_add_u32 v200, v200, v105, v44
	v_ashrrev_i32_e32 v201, 31, v200
	v_lshl_add_u64 v[200:201], v[200:201], 3, v[32:33]
	global_load_dwordx2 v[200:201], v[200:201], off
	ds_bpermute_b32 v245, v47, v21
	v_cndmask_b32_e32 v202, v99, v45, vcc
	v_lshl_add_u32 v202, v202, v105, v44
	v_ashrrev_i32_e32 v203, 31, v202
	v_lshl_add_u64 v[202:203], v[202:203], 3, v[32:33]
	global_load_dwordx2 v[202:203], v[202:203], off
	ds_bpermute_b32 v246, v47, v22
	v_cndmask_b32_e32 v204, v95, v45, vcc
	v_lshl_add_u32 v204, v204, v105, v44
	v_ashrrev_i32_e32 v205, 31, v204
	v_lshl_add_u64 v[204:205], v[204:205], 3, v[32:33]
	global_load_dwordx2 v[204:205], v[204:205], off
	ds_bpermute_b32 v247, v47, v23
	v_cndmask_b32_e32 v206, v87, v45, vcc
	v_lshl_add_u32 v206, v206, v105, v44
	v_ashrrev_i32_e32 v207, 31, v206
	v_lshl_add_u64 v[206:207], v[206:207], 3, v[32:33]
	global_load_dwordx2 v[206:207], v[206:207], off
	ds_bpermute_b32 v248, v47, v24
	v_cndmask_b32_e32 v208, v85, v45, vcc
	v_lshl_add_u32 v208, v208, v105, v44
	v_ashrrev_i32_e32 v209, 31, v208
	v_lshl_add_u64 v[208:209], v[208:209], 3, v[32:33]
	global_load_dwordx2 v[208:209], v[208:209], off
	ds_bpermute_b32 v249, v47, v25
	v_cndmask_b32_e32 v216, v83, v45, vcc
	v_lshl_add_u32 v216, v216, v105, v44
	v_ashrrev_i32_e32 v217, 31, v216
	v_lshl_add_u64 v[216:217], v[216:217], 3, v[32:33]
	global_load_dwordx2 v[216:217], v[216:217], off
	ds_bpermute_b32 v250, v47, v26
	v_cndmask_b32_e32 v218, v78, v45, vcc
	v_lshl_add_u32 v218, v218, v105, v44
	v_ashrrev_i32_e32 v219, 31, v218
	v_lshl_add_u64 v[218:219], v[218:219], 3, v[32:33]
	global_load_dwordx2 v[218:219], v[218:219], off
	ds_bpermute_b32 v251, v47, v27
	v_cndmask_b32_e32 v220, v76, v45, vcc
	v_lshl_add_u32 v220, v220, v105, v44
	v_ashrrev_i32_e32 v221, 31, v220
	v_lshl_add_u64 v[220:221], v[220:221], 3, v[32:33]
	global_load_dwordx2 v[220:221], v[220:221], off
	ds_bpermute_b32 v252, v47, v28
	v_cndmask_b32_e32 v222, v74, v45, vcc
	v_lshl_add_u32 v222, v222, v105, v44
	v_ashrrev_i32_e32 v223, 31, v222
	v_lshl_add_u64 v[222:223], v[222:223], 3, v[32:33]
	global_load_dwordx2 v[222:223], v[222:223], off
	ds_bpermute_b32 v253, v47, v29
	v_cndmask_b32_e32 v224, v72, v45, vcc
	v_lshl_add_u32 v224, v224, v105, v44
	v_ashrrev_i32_e32 v225, 31, v224
	v_lshl_add_u64 v[224:225], v[224:225], 3, v[32:33]
	global_load_dwordx2 v[224:225], v[224:225], off
	ds_bpermute_b32 v254, v47, v30
	v_cndmask_b32_e32 v226, v70, v45, vcc
	v_lshl_add_u32 v226, v226, v105, v44
	v_ashrrev_i32_e32 v227, 31, v226
	v_lshl_add_u64 v[226:227], v[226:227], 3, v[32:33]
	global_load_dwordx2 v[226:227], v[226:227], off
	ds_bpermute_b32 v255, v47, v31
	s_waitcnt lgkmcnt(0)
	s_waitcnt vmcnt(15)
	v_mul_f32_e32 v240, v191, v240
	v_cndmask_b32_e64 v240, v240, -v240, s[0:1]
	v_fmac_f32_e32 v240, v16, v190
	v_cvt_pk_bf16_f32 v240, v240, s0
	v_mad_i64_i32 v[190:191], s[8:9], v79, s95, v[36:37]
	v_lshl_add_u64 v[190:191], v[190:191], 0, v[34:35]
	global_store_short v[190:191], v240, off
	s_waitcnt vmcnt(15)
; DI u16 f2bf(float a) { return (u16)(pk2(a, 0.f) & 0xffffu); }
; template <int EPI>
; __device__ __forceinline__ void gemm_tile(const Params& p, int layer, const u16* __restrict__ A, const u16* __restrict__ Bt, int mt, int nt, char* lds) {
;     ...
;             const f32x2 cs = tab[pos * nf + f];
;             const float v = acc[i][j][e];
;             const float o = __shfl_xor(v, 1);
;             const float res = (gc & 1) ? (o * cs[1] + v * cs[0]) : (v * cs[0] - o * cs[1]);
;             P[(size_t)gr * LDP + gc] = f2bf(res);
;           }
	v_mul_f32_e32 v241, v193, v241
	v_cndmask_b32_e64 v241, v241, -v241, s[0:1]
	v_fmac_f32_e32 v241, v17, v192
	v_cvt_pk_bf16_f32 v241, v241, s0
	v_mad_i64_i32 v[192:193], s[8:9], v114, s95, v[36:37]
	v_lshl_add_u64 v[192:193], v[192:193], 0, v[34:35]
	global_store_short v[192:193], v241, off
	s_waitcnt vmcnt(15)
	v_mul_f32_e32 v242, v195, v242
	v_cndmask_b32_e64 v242, v242, -v242, s[0:1]
	v_fmac_f32_e32 v242, v18, v194
	v_cvt_pk_bf16_f32 v242, v242, s0
	v_mad_i64_i32 v[194:195], s[8:9], v110, s95, v[36:37]
	v_lshl_add_u64 v[194:195], v[194:195], 0, v[34:35]
	global_store_short v[194:195], v242, off
	s_waitcnt vmcnt(15)
	v_mul_f32_e32 v243, v197, v243
	v_cndmask_b32_e64 v243, v243, -v243, s[0:1]
	v_fmac_f32_e32 v243, v19, v196
	v_cvt_pk_bf16_f32 v243, v243, s0
	v_mad_i64_i32 v[196:197], s[8:9], v102, s95, v[36:37]
	v_lshl_add_u64 v[196:197], v[196:197], 0, v[34:35]
	global_store_short v[196:197], v243, off
	s_waitcnt vmcnt(15)
	v_mul_f32_e32 v244, v199, v244
	v_cndmask_b32_e64 v244, v244, -v244, s[0:1]
	v_fmac_f32_e32 v244, v20, v198
	v_cvt_pk_bf16_f32 v244, v244, s0
	v_mad_i64_i32 v[198:199], s[8:9], v100, s95, v[36:37]
	v_lshl_add_u64 v[198:199], v[198:199], 0, v[34:35]
	global_store_short v[198:199], v244, off
	s_waitcnt vmcnt(15)
	v_mul_f32_e32 v245, v201, v245
	v_cndmask_b32_e64 v245, v245, -v245, s[0:1]
	v_fmac_f32_e32 v245, v21, v200
	v_cvt_pk_bf16_f32 v245, v245, s0
	v_mad_i64_i32 v[200:201], s[8:9], v98, s95, v[36:37]
	v_lshl_add_u64 v[200:201], v[200:201], 0, v[34:35]
	global_store_short v[200:201], v245, off
	s_waitcnt vmcnt(15)
	v_mul_f32_e32 v246, v203, v246
	v_cndmask_b32_e64 v246, v246, -v246, s[0:1]
	v_fmac_f32_e32 v246, v22, v202
	v_cvt_pk_bf16_f32 v246, v246, s0
	v_mad_i64_i32 v[202:203], s[8:9], v94, s95, v[36:37]
	v_lshl_add_u64 v[202:203], v[202:203], 0, v[34:35]
	global_store_short v[202:203], v246, off
	s_waitcnt vmcnt(15)
	v_mul_f32_e32 v247, v205, v247
	v_cndmask_b32_e64 v247, v247, -v247, s[0:1]
	v_fmac_f32_e32 v247, v23, v204
	v_cvt_pk_bf16_f32 v247, v247, s0
	v_mad_i64_i32 v[204:205], s[8:9], v86, s95, v[36:37]
	v_lshl_add_u64 v[204:205], v[204:205], 0, v[34:35]
	global_store_short v[204:205], v247, off
	s_waitcnt vmcnt(15)
	v_mul_f32_e32 v248, v207, v248
	v_cndmask_b32_e64 v248, v248, -v248, s[0:1]
	v_fmac_f32_e32 v248, v24, v206
	v_cvt_pk_bf16_f32 v248, v248, s0
	v_mad_i64_i32 v[206:207], s[8:9], v84, s95, v[36:37]
	v_lshl_add_u64 v[206:207], v[206:207], 0, v[34:35]
	global_store_short v[206:207], v248, off
	s_waitcnt vmcnt(15)
	v_mul_f32_e32 v249, v209, v249
	v_cndmask_b32_e64 v249, v249, -v249, s[0:1]
	v_fmac_f32_e32 v249, v25, v208
	v_cvt_pk_bf16_f32 v249, v249, s0
	v_mad_i64_i32 v[208:209], s[8:9], v82, s95, v[36:37]
	v_lshl_add_u64 v[208:209], v[208:209], 0, v[34:35]
	global_store_short v[208:209], v249, off
	s_waitcnt vmcnt(15)
	v_mul_f32_e32 v250, v217, v250
	v_cndmask_b32_e64 v250, v250, -v250, s[0:1]
	v_fmac_f32_e32 v250, v26, v216
	v_cvt_pk_bf16_f32 v250, v250, s0
	v_mad_i64_i32 v[216:217], s[8:9], v77, s95, v[36:37]
	v_lshl_add_u64 v[216:217], v[216:217], 0, v[34:35]
	global_store_short v[216:217], v250, off
	s_waitcnt vmcnt(15)
	v_mul_f32_e32 v251, v219, v251
	v_cndmask_b32_e64 v251, v251, -v251, s[0:1]
	v_fmac_f32_e32 v251, v27, v218
	v_cvt_pk_bf16_f32 v251, v251, s0
	v_mad_i64_i32 v[218:219], s[8:9], v75, s95, v[36:37]
	v_lshl_add_u64 v[218:219], v[218:219], 0, v[34:35]
	global_store_short v[218:219], v251, off
	s_waitcnt vmcnt(15)
	v_mul_f32_e32 v252, v221, v252
	v_cndmask_b32_e64 v252, v252, -v252, s[0:1]
	v_fmac_f32_e32 v252, v28, v220
	v_cvt_pk_bf16_f32 v252, v252, s0
	v_mad_i64_i32 v[220:221], s[8:9], v73, s95, v[36:37]
	v_lshl_add_u64 v[220:221], v[220:221], 0, v[34:35]
	global_store_short v[220:221], v252, off
	s_waitcnt vmcnt(15)
	v_mul_f32_e32 v253, v223, v253
	v_cndmask_b32_e64 v253, v253, -v253, s[0:1]
	v_fmac_f32_e32 v253, v29, v222
	v_cvt_pk_bf16_f32 v253, v253, s0
	v_mad_i64_i32 v[222:223], s[8:9], v71, s95, v[36:37]
	v_lshl_add_u64 v[222:223], v[222:223], 0, v[34:35]
	global_store_short v[222:223], v253, off
	s_waitcnt vmcnt(15)
	v_mul_f32_e32 v254, v225, v254
	v_cndmask_b32_e64 v254, v254, -v254, s[0:1]
	v_fmac_f32_e32 v254, v30, v224
	v_cvt_pk_bf16_f32 v254, v254, s0
	v_mad_i64_i32 v[224:225], s[8:9], v69, s95, v[36:37]
	v_lshl_add_u64 v[224:225], v[224:225], 0, v[34:35]
	global_store_short v[224:225], v254, off
	s_waitcnt vmcnt(15)
	v_mul_f32_e32 v255, v227, v255
	v_cndmask_b32_e64 v255, v255, -v255, s[0:1]
	v_fmac_f32_e32 v255, v31, v226
	v_cvt_pk_bf16_f32 v255, v255, s0
	v_mad_i64_i32 v[226:227], s[8:9], v68, s95, v[36:37]
	v_lshl_add_u64 v[226:227], v[226:227], 0, v[34:35]
	global_store_short v[226:227], v255, off

; DI u16 f2bf(float a) { return (u16)(pk2(a, 0.f) & 0xffffu); }
; DI int crow(int i, int h) { return (i & 3) + 8 * (i >> 2) + 4 * h; }
; template <int EPI>
; __device__ __forceinline__ void gemm_tile(const Params& p, int layer, const u16* __restrict__ A, const u16* __restrict__ Bt, int mt, int nt, char* lds) {
;     ...
;         const bool ropeA = gcb < 1024, ropeB = (gcb >= 1536 && gcb < 2816);
;         const bool latent = m0 >= NCTX;
;         if (latent && (ropeA || ropeB)) {
;           int pair, nf; bool userow; const f32x2* tab;
;           if (ropeA) { pair = (gc & 63) >> 1; nf = 16; tab = (const f32x2*)(p.ws + OFF_TABA); }
;           else       { pair = (gc & 127) >> 1; nf = 32; tab = (const f32x2*)(p.ws + OFF_TABB); }
;           userow = pair < nf;
;           const int f = userow ? pair : pair - nf;
; #pragma unroll
;           for (int e = 0; e < 16; ++e) {
;             const int gr = grb + crow(e, h);
;             const int t = gr - NCTX;
;             const int pos = userow ? (t >> 6) : (t & 63);
;             const f32x2 cs = tab[pos * nf + f];
;             const float v = acc[i][j][e];
;             const float o = __shfl_xor(v, 1);
;             const float res = (gc & 1) ? (o * cs[1] + v * cs[0]) : (v * cs[0] - o * cs[1]);
;             P[(size_t)gr * LDP + gc] = f2bf(res);
;           }
.LBB0_1421:
	v_lshrrev_b32_e32 v16, 1, v18
	v_and_b32_e32 v19, v16, v91
	v_sub_u32_e32 v20, v19, v90
	v_ashrrev_i32_e32 v29, 6, v118
	v_cmp_lt_u32_e32 vcc, v19, v90
	v_min_u32_e32 v28, v19, v20
	v_mov_b32_e32 v81, v129
	v_lshl_add_u64 v[16:17], s[22:23], 0, v[80:81]
	v_and_b32_e32 v24, 64, v214
	v_mov_b64_e32 v[20:21], s[28:29]
	v_xor_b32_e32 v26, 1, v214
	v_add_u32_e32 v27, 64, v24
	v_cmp_lt_i32_e64 s[0:1], v26, v27
	v_and_b32_e32 v30, 1, v18
	v_ashrrev_i32_e32 v19, 31, v18
	v_cndmask_b32_e64 v26, v214, v26, s[0:1]
	v_lshlrev_b32_e32 v31, 2, v26
	v_cmp_eq_u32_e64 s[0:1], 0, v30
	v_lshlrev_b64 v[18:19], 1, v[18:19]
	s_nop 1
	v_cndmask_b32_e32 v190, v117, v29, vcc
	v_lshl_add_u32 v190, v190, v88, v28
	v_ashrrev_i32_e32 v191, 31, v190
	v_lshl_add_u64 v[190:191], v[190:191], 3, v[16:17]
	global_load_dwordx2 v[190:191], v[190:191], off
	ds_bpermute_b32 v240, v31, v0
	v_cndmask_b32_e32 v192, v116, v29, vcc
	v_lshl_add_u32 v192, v192, v88, v28
	v_ashrrev_i32_e32 v193, 31, v192
	v_lshl_add_u64 v[192:193], v[192:193], 3, v[16:17]
	global_load_dwordx2 v[192:193], v[192:193], off
	ds_bpermute_b32 v241, v31, v1
	v_cndmask_b32_e32 v194, v115, v29, vcc
	v_lshl_add_u32 v194, v194, v88, v28
	v_ashrrev_i32_e32 v195, 31, v194
	v_lshl_add_u64 v[194:195], v[194:195], 3, v[16:17]
	global_load_dwordx2 v[194:195], v[194:195], off
	ds_bpermute_b32 v242, v31, v2
	v_cndmask_b32_e32 v196, v111, v29, vcc
	v_lshl_add_u32 v196, v196, v88, v28
	v_ashrrev_i32_e32 v197, 31, v196
	v_lshl_add_u64 v[196:197], v[196:197], 3, v[16:17]
	global_load_dwordx2 v[196:197], v[196:197], off
	ds_bpermute_b32 v243, v31, v3
	v_cndmask_b32_e32 v198, v103, v29, vcc
	v_lshl_add_u32 v198, v198, v88, v28
	v_ashrrev_i32_e32 v199, 31, v198
	v_lshl_add_u64 v[198:199], v[198:199], 3, v[16:17]
	global_load_dwordx2 v[198:199], v[198:199], off
	ds_bpermute_b32 v244, v31, v4
	v_cndmask_b32_e32 v200, v101, v29, vcc
	v_lshl_add_u32 v200, v200, v88, v28
	v_ashrrev_i32_e32 v201, 31, v200
	v_lshl_add_u64 v[200:201], v[200:201], 3, v[16:17]
	global_load_dwordx2 v[200:201], v[200:201], off
	ds_bpermute_b32 v245, v31, v5
	v_cndmask_b32_e32 v202, v99, v29, vcc
	v_lshl_add_u32 v202, v202, v88, v28
	v_ashrrev_i32_e32 v203, 31, v202
	v_lshl_add_u64 v[202:203], v[202:203], 3, v[16:17]
	global_load_dwordx2 v[202:203], v[202:203], off
	ds_bpermute_b32 v246, v31, v6
	v_cndmask_b32_e32 v204, v95, v29, vcc
	v_lshl_add_u32 v204, v204, v88, v28
	v_ashrrev_i32_e32 v205, 31, v204
	v_lshl_add_u64 v[204:205], v[204:205], 3, v[16:17]
	global_load_dwordx2 v[204:205], v[204:205], off
	ds_bpermute_b32 v247, v31, v7
	v_cndmask_b32_e32 v206, v87, v29, vcc
	v_lshl_add_u32 v206, v206, v88, v28
	v_ashrrev_i32_e32 v207, 31, v206
	v_lshl_add_u64 v[206:207], v[206:207], 3, v[16:17]
	global_load_dwordx2 v[206:207], v[206:207], off
	ds_bpermute_b32 v248, v31, v8
	v_cndmask_b32_e32 v208, v85, v29, vcc
	v_lshl_add_u32 v208, v208, v88, v28
	v_ashrrev_i32_e32 v209, 31, v208
	v_lshl_add_u64 v[208:209], v[208:209], 3, v[16:17]
	global_load_dwordx2 v[208:209], v[208:209], off
	ds_bpermute_b32 v249, v31, v9
	v_cndmask_b32_e32 v216, v83, v29, vcc
	v_lshl_add_u32 v216, v216, v88, v28
	v_ashrrev_i32_e32 v217, 31, v216
	v_lshl_add_u64 v[216:217], v[216:217], 3, v[16:17]
	global_load_dwordx2 v[216:217], v[216:217], off
	ds_bpermute_b32 v250, v31, v10
	v_cndmask_b32_e32 v218, v78, v29, vcc
	v_lshl_add_u32 v218, v218, v88, v28
	v_ashrrev_i32_e32 v219, 31, v218
	v_lshl_add_u64 v[218:219], v[218:219], 3, v[16:17]
	global_load_dwordx2 v[218:219], v[218:219], off
	ds_bpermute_b32 v251, v31, v11
	v_cndmask_b32_e32 v220, v76, v29, vcc
	v_lshl_add_u32 v220, v220, v88, v28
	v_ashrrev_i32_e32 v221, 31, v220
	v_lshl_add_u64 v[220:221], v[220:221], 3, v[16:17]
	global_load_dwordx2 v[220:221], v[220:221], off
	ds_bpermute_b32 v252, v31, v12
	v_cndmask_b32_e32 v222, v74, v29, vcc
	v_lshl_add_u32 v222, v222, v88, v28
	v_ashrrev_i32_e32 v223, 31, v222
	v_lshl_add_u64 v[222:223], v[222:223], 3, v[16:17]
	global_load_dwordx2 v[222:223], v[222:223], off
	ds_bpermute_b32 v253, v31, v13
	v_cndmask_b32_e32 v224, v72, v29, vcc
	v_lshl_add_u32 v224, v224, v88, v28
	v_ashrrev_i32_e32 v225, 31, v224
	v_lshl_add_u64 v[224:225], v[224:225], 3, v[16:17]
	global_load_dwordx2 v[224:225], v[224:225], off
	ds_bpermute_b32 v254, v31, v14
	v_cndmask_b32_e32 v226, v70, v29, vcc
	v_lshl_add_u32 v226, v226, v88, v28
	v_ashrrev_i32_e32 v227, 31, v226
	v_lshl_add_u64 v[226:227], v[226:227], 3, v[16:17]
	global_load_dwordx2 v[226:227], v[226:227], off
	ds_bpermute_b32 v255, v31, v15
	s_waitcnt lgkmcnt(0)
	s_waitcnt vmcnt(15)
	v_mul_f32_e32 v240, v191, v240
	v_cndmask_b32_e64 v240, v240, -v240, s[0:1]
	v_fmac_f32_e32 v240, v0, v190
	v_cvt_pk_bf16_f32 v240, v240, s0
	v_mad_i64_i32 v[190:191], s[6:7], v79, s95, v[20:21]
	v_lshl_add_u64 v[190:191], v[190:191], 0, v[18:19]
	global_store_short v[190:191], v240, off
	s_waitcnt vmcnt(15)
; DI u16 f2bf(float a) { return (u16)(pk2(a, 0.f) & 0xffffu); }
; template <int EPI>
; __device__ __forceinline__ void gemm_tile(const Params& p, int layer, const u16* __restrict__ A, const u16* __restrict__ Bt, int mt, int nt, char* lds) {
;     ...
;             const f32x2 cs = tab[pos * nf + f];
;             const float v = acc[i][j][e];
;             const float o = __shfl_xor(v, 1);
;             const float res = (gc & 1) ? (o * cs[1] + v * cs[0]) : (v * cs[0] - o * cs[1]);
;             P[(size_t)gr * LDP + gc] = f2bf(res);
;           }
	v_mul_f32_e32 v241, v193, v241
	v_cndmask_b32_e64 v241, v241, -v241, s[0:1]
	v_fmac_f32_e32 v241, v1, v192
	v_cvt_pk_bf16_f32 v241, v241, s0
	v_mad_i64_i32 v[192:193], s[6:7], v114, s95, v[20:21]
	v_lshl_add_u64 v[192:193], v[192:193], 0, v[18:19]
	global_store_short v[192:193], v241, off
	s_waitcnt vmcnt(15)
	v_mul_f32_e32 v242, v195, v242
	v_cndmask_b32_e64 v242, v242, -v242, s[0:1]
	v_fmac_f32_e32 v242, v2, v194
	v_cvt_pk_bf16_f32 v242, v242, s0
	v_mad_i64_i32 v[194:195], s[6:7], v110, s95, v[20:21]
	v_lshl_add_u64 v[194:195], v[194:195], 0, v[18:19]
	global_store_short v[194:195], v242, off
	s_waitcnt vmcnt(15)
	v_mul_f32_e32 v243, v197, v243
	v_cndmask_b32_e64 v243, v243, -v243, s[0:1]
	v_fmac_f32_e32 v243, v3, v196
	v_cvt_pk_bf16_f32 v243, v243, s0
	v_mad_i64_i32 v[196:197], s[6:7], v102, s95, v[20:21]
	v_lshl_add_u64 v[196:197], v[196:197], 0, v[18:19]
	global_store_short v[196:197], v243, off
	s_waitcnt vmcnt(15)
	v_mul_f32_e32 v244, v199, v244
	v_cndmask_b32_e64 v244, v244, -v244, s[0:1]
	v_fmac_f32_e32 v244, v4, v198
	v_cvt_pk_bf16_f32 v244, v244, s0
	v_mad_i64_i32 v[198:199], s[6:7], v100, s95, v[20:21]
	v_lshl_add_u64 v[198:199], v[198:199], 0, v[18:19]
	global_store_short v[198:199], v244, off
	s_waitcnt vmcnt(15)
	v_mul_f32_e32 v245, v201, v245
	v_cndmask_b32_e64 v245, v245, -v245, s[0:1]
	v_fmac_f32_e32 v245, v5, v200
	v_cvt_pk_bf16_f32 v245, v245, s0
	v_mad_i64_i32 v[200:201], s[6:7], v98, s95, v[20:21]
	v_lshl_add_u64 v[200:201], v[200:201], 0, v[18:19]
	global_store_short v[200:201], v245, off
	s_waitcnt vmcnt(15)
	v_mul_f32_e32 v246, v203, v246
	v_cndmask_b32_e64 v246, v246, -v246, s[0:1]
	v_fmac_f32_e32 v246, v6, v202
	v_cvt_pk_bf16_f32 v246, v246, s0
	v_mad_i64_i32 v[202:203], s[6:7], v94, s95, v[20:21]
	v_lshl_add_u64 v[202:203], v[202:203], 0, v[18:19]
	global_store_short v[202:203], v246, off
	s_waitcnt vmcnt(15)
	v_mul_f32_e32 v247, v205, v247
	v_cndmask_b32_e64 v247, v247, -v247, s[0:1]
	v_fmac_f32_e32 v247, v7, v204
	v_cvt_pk_bf16_f32 v247, v247, s0
	v_mad_i64_i32 v[204:205], s[6:7], v86, s95, v[20:21]
	v_lshl_add_u64 v[204:205], v[204:205], 0, v[18:19]
	global_store_short v[204:205], v247, off
	s_waitcnt vmcnt(15)
	v_mul_f32_e32 v248, v207, v248
	v_cndmask_b32_e64 v248, v248, -v248, s[0:1]
	v_fmac_f32_e32 v248, v8, v206
	v_cvt_pk_bf16_f32 v248, v248, s0
	v_mad_i64_i32 v[206:207], s[6:7], v84, s95, v[20:21]
	v_lshl_add_u64 v[206:207], v[206:207], 0, v[18:19]
	global_store_short v[206:207], v248, off
	s_waitcnt vmcnt(15)
	v_mul_f32_e32 v249, v209, v249
	v_cndmask_b32_e64 v249, v249, -v249, s[0:1]
	v_fmac_f32_e32 v249, v9, v208
	v_cvt_pk_bf16_f32 v249, v249, s0
	v_mad_i64_i32 v[208:209], s[6:7], v82, s95, v[20:21]
	v_lshl_add_u64 v[208:209], v[208:209], 0, v[18:19]
	global_store_short v[208:209], v249, off
	s_waitcnt vmcnt(15)
	v_mul_f32_e32 v250, v217, v250
	v_cndmask_b32_e64 v250, v250, -v250, s[0:1]
	v_fmac_f32_e32 v250, v10, v216
	v_cvt_pk_bf16_f32 v250, v250, s0
	v_mad_i64_i32 v[216:217], s[6:7], v77, s95, v[20:21]
	v_lshl_add_u64 v[216:217], v[216:217], 0, v[18:19]
	global_store_short v[216:217], v250, off
	s_waitcnt vmcnt(15)
	v_mul_f32_e32 v251, v219, v251
	v_cndmask_b32_e64 v251, v251, -v251, s[0:1]
	v_fmac_f32_e32 v251, v11, v218
	v_cvt_pk_bf16_f32 v251, v251, s0
	v_mad_i64_i32 v[218:219], s[6:7], v75, s95, v[20:21]
	v_lshl_add_u64 v[218:219], v[218:219], 0, v[18:19]
	global_store_short v[218:219], v251, off
	s_waitcnt vmcnt(15)
	v_mul_f32_e32 v252, v221, v252
	v_cndmask_b32_e64 v252, v252, -v252, s[0:1]
	v_fmac_f32_e32 v252, v12, v220
	v_cvt_pk_bf16_f32 v252, v252, s0
	v_mad_i64_i32 v[220:221], s[6:7], v73, s95, v[20:21]
	v_lshl_add_u64 v[220:221], v[220:221], 0, v[18:19]
	global_store_short v[220:221], v252, off
	s_waitcnt vmcnt(15)
	v_mul_f32_e32 v253, v223, v253
	v_cndmask_b32_e64 v253, v253, -v253, s[0:1]
	v_fmac_f32_e32 v253, v13, v222
	v_cvt_pk_bf16_f32 v253, v253, s0
	v_mad_i64_i32 v[222:223], s[6:7], v71, s95, v[20:21]
	v_lshl_add_u64 v[222:223], v[222:223], 0, v[18:19]
	global_store_short v[222:223], v253, off
	s_waitcnt vmcnt(15)
	v_mul_f32_e32 v254, v225, v254
	v_cndmask_b32_e64 v254, v254, -v254, s[0:1]
	v_fmac_f32_e32 v254, v14, v224
	v_cvt_pk_bf16_f32 v254, v254, s0
	v_mad_i64_i32 v[224:225], s[6:7], v69, s95, v[20:21]
	v_lshl_add_u64 v[224:225], v[224:225], 0, v[18:19]
	global_store_short v[224:225], v254, off
	s_waitcnt vmcnt(15)
	v_mul_f32_e32 v255, v227, v255
	v_cndmask_b32_e64 v255, v255, -v255, s[0:1]
	v_fmac_f32_e32 v255, v15, v226
	v_cvt_pk_bf16_f32 v255, v255, s0
	v_mad_i64_i32 v[226:227], s[6:7], v68, s95, v[20:21]
	v_lshl_add_u64 v[226:227], v[226:227], 0, v[18:19]
	global_store_short v[226:227], v255, off
	s_branch .LBB0_1224

; #define MFMA32(a, b, c) __builtin_amdgcn_mfma_f32_32x32x16_bf16((a), (b), (c), 0, 0, 0)
; DI int crow(int i, int h) { return (i & 3) + 8 * (i >> 2) + 4 * h; }
; DI unsigned f2ord(float f) { unsigned u = __float_as_uint(f); return (u & 0x80000000u) ? ~u : (u | 0x80000000u); }
; #define INS32(T, X) { _Pragma("unroll") for (int jj = 0; jj < 16; ++jj) { unsigned t_ = max(T[jj], X); X = min(T[jj], X); T[jj] = t_; } }
; __device__ __forceinline__ void route_task(const Params& p, int layer, const u16* qg, int rb, int hd, int r, int h) {
;     ...
; #pragma unroll 1
;     for (int n = 0; n < 4; ++n) {
;       f32x16 acc;
; #pragma unroll
;       for (int e = 0; e < 16; ++e) acc[e] = 0.f;
; #pragma unroll
;       for (int s = 0; s < 8; ++s) {
;         bf16x8 kf = *(const bf16x8*)(kg + (size_t)n * 32 * 128 + 16 * s);
;         acc = MFMA32(kf, qf[s], acc);
;       }
; #pragma unroll
;       for (int e = 0; e < 16; ++e) {
;         unsigned key = (f2ord(acc[e]) & ~127u) | (unsigned)(127 - (n * 32 + crow(e, h)));
;         INS32(tp, key);
;       }
.LBB0_1873:
	global_load_dwordx4 v[190:193], v[50:51], off offset:-128
	global_load_dwordx4 v[194:197], v[50:51], off offset:-96
	global_load_dwordx4 v[198:201], v[50:51], off offset:-64
	global_load_dwordx4 v[202:205], v[50:51], off offset:-32
	global_load_dwordx4 v[206:209], v[50:51], off
	global_load_dwordx4 v[216:219], v[50:51], off offset:32
	global_load_dwordx4 v[220:223], v[50:51], off offset:64
	global_load_dwordx4 v[224:227], v[50:51], off offset:96
	v_lshl_add_u64 v[50:51], v[50:51], 0, s[16:17]
	s_waitcnt vmcnt(7) lgkmcnt(7)
	v_mfma_f32_32x32x16_bf16 v[0:15], v[190:193], v[16:19], 0
	s_waitcnt vmcnt(6) lgkmcnt(6)
	v_mfma_f32_32x32x16_bf16 v[0:15], v[194:197], v[20:23], v[0:15]
	s_waitcnt vmcnt(5) lgkmcnt(5)
	v_mfma_f32_32x32x16_bf16 v[0:15], v[198:201], v[24:27], v[0:15]
	s_waitcnt vmcnt(4) lgkmcnt(4)
	v_mfma_f32_32x32x16_bf16 v[0:15], v[202:205], v[28:31], v[0:15]
	s_waitcnt vmcnt(3) lgkmcnt(3)
	v_mfma_f32_32x32x16_bf16 v[0:15], v[206:209], v[32:35], v[0:15]
	s_waitcnt vmcnt(2) lgkmcnt(2)
	v_mfma_f32_32x32x16_bf16 v[0:15], v[216:219], v[36:39], v[0:15]
	s_waitcnt vmcnt(1) lgkmcnt(1)
	v_mfma_f32_32x32x16_bf16 v[0:15], v[220:223], v[40:43], v[0:15]
	s_waitcnt vmcnt(0) lgkmcnt(0)
	v_mfma_f32_32x32x16_bf16 v[0:15], v[224:227], v[44:47], v[0:15]
	s_nop 11
	v_not_b32_e32 v70, v0
	v_or_b32_e32 v71, 0x80000000, v0
	v_cmp_gt_i32_e32 vcc, 0, v0
	v_or_b32_e32 v72, 0x80000000, v1
	s_nop 0
	v_cndmask_b32_e32 v0, v71, v70, vcc
	v_and_b32_e32 v70, 0xffffff80, v0
	v_add_u32_e32 v0, s18, v53
	v_add3_u32 v70, v0, v70, s61
	v_max_u32_e32 v71, v69, v70
	v_min_u32_e32 v69, v69, v70
	v_max_u32_e32 v70, v68, v69
	v_min_u32_e32 v68, v68, v69
	v_max_u32_e32 v69, v67, v68
	v_min_u32_e32 v67, v67, v68
	v_max_u32_e32 v68, v66, v67
	v_min_u32_e32 v66, v66, v67
	v_max_u32_e32 v67, v65, v66
	v_min_u32_e32 v65, v65, v66
	v_max_u32_e32 v66, v64, v65
	v_min_u32_e32 v64, v64, v65
	v_max_u32_e32 v65, v63, v64
	v_min_u32_e32 v63, v63, v64
	v_max_u32_e32 v64, v62, v63
	v_min_u32_e32 v62, v62, v63
	v_max_u32_e32 v63, v61, v62
	v_min_u32_e32 v61, v61, v62
	v_max_u32_e32 v62, v60, v61
	v_min_u32_e32 v60, v60, v61
	v_max_u32_e32 v61, v59, v60
	v_min_u32_e32 v59, v59, v60
	v_max_u32_e32 v60, v58, v59
	v_min_u32_e32 v58, v58, v59
	v_max_u32_e32 v59, v57, v58
	v_min_u32_e32 v57, v57, v58
	v_max_u32_e32 v58, v56, v57
	v_min_u32_e32 v56, v56, v57
	v_max_u32_e32 v57, v55, v56
	v_min_u32_e32 v55, v55, v56
	v_not_b32_e32 v56, v1
	v_cmp_gt_i32_e32 vcc, 0, v1
	s_sub_i32 s18, s18, 32
	s_cmpk_lg_i32 s18, 0xff80
	v_cndmask_b32_e32 v1, v72, v56, vcc
	v_and_b32_e32 v1, 0xffffff80, v1
	v_add3_u32 v1, v0, v1, s62
	v_max_u32_e32 v56, v71, v1
	v_min_u32_e32 v1, v71, v1
	v_max_u32_e32 v71, v70, v1
	v_min_u32_e32 v1, v70, v1
	v_max_u32_e32 v70, v69, v1
	v_min_u32_e32 v1, v69, v1
	v_max_u32_e32 v69, v68, v1
	v_min_u32_e32 v1, v68, v1
	v_max_u32_e32 v68, v67, v1
	v_min_u32_e32 v1, v67, v1
	v_max_u32_e32 v67, v66, v1
	v_min_u32_e32 v1, v66, v1
	v_max_u32_e32 v66, v65, v1
	v_min_u32_e32 v1, v65, v1
	v_max_u32_e32 v65, v64, v1
	v_min_u32_e32 v1, v64, v1
	v_max_u32_e32 v64, v63, v1
	v_min_u32_e32 v1, v63, v1
	v_max_u32_e32 v63, v62, v1
	v_min_u32_e32 v1, v62, v1
	v_max_u32_e32 v62, v61, v1
	v_min_u32_e32 v1, v61, v1
	v_max_u32_e32 v61, v60, v1
	v_min_u32_e32 v1, v60, v1
	v_max_u32_e32 v60, v59, v1
	v_min_u32_e32 v1, v59, v1
	v_max_u32_e32 v59, v58, v1
	v_min_u32_e32 v1, v58, v1
	v_max_u32_e32 v58, v57, v1
	v_min_u32_e32 v1, v57, v1
	v_max3_u32 v1, v54, v55, v1
	v_not_b32_e32 v54, v2
	v_or_b32_e32 v55, 0x80000000, v2
	v_cmp_gt_i32_e32 vcc, 0, v2
	s_nop 1
	v_cndmask_b32_e32 v2, v55, v54, vcc
	v_and_b32_e32 v2, 0xffffff80, v2
	v_add3_u32 v2, v0, v2, s63
	v_max_u32_e32 v54, v56, v2
	v_min_u32_e32 v2, v56, v2
	v_max_u32_e32 v55, v71, v2
	v_min_u32_e32 v2, v71, v2
	v_max_u32_e32 v56, v70, v2
	v_min_u32_e32 v2, v70, v2
	v_max_u32_e32 v57, v69, v2
	v_min_u32_e32 v2, v69, v2
	v_max_u32_e32 v69, v68, v2
	v_min_u32_e32 v2, v68, v2
	v_max_u32_e32 v68, v67, v2
	v_min_u32_e32 v2, v67, v2
	v_max_u32_e32 v67, v66, v2
	v_min_u32_e32 v2, v66, v2
	v_max_u32_e32 v66, v65, v2
	v_min_u32_e32 v2, v65, v2
	v_max_u32_e32 v65, v64, v2
	v_min_u32_e32 v2, v64, v2
	v_max_u32_e32 v64, v63, v2
	v_min_u32_e32 v2, v63, v2
	v_max_u32_e32 v63, v62, v2
	v_min_u32_e32 v2, v62, v2
	v_max_u32_e32 v62, v61, v2
	v_min_u32_e32 v2, v61, v2
	v_max_u32_e32 v61, v60, v2
	v_min_u32_e32 v2, v60, v2
	v_max_u32_e32 v60, v59, v2
	v_min_u32_e32 v2, v59, v2
	v_max_u32_e32 v59, v58, v2
	v_min_u32_e32 v2, v58, v2
	v_not_b32_e32 v58, v3
	v_or_b32_e32 v70, 0x80000000, v3
	v_cmp_gt_i32_e32 vcc, 0, v3
	s_nop 1
	v_cndmask_b32_e32 v3, v70, v58, vcc
	v_and_b32_e32 v3, 0xffffff80, v3
	v_add3_u32 v3, v0, v3, s64
	v_max_u32_e32 v58, v54, v3
	v_min_u32_e32 v3, v54, v3
	v_max_u32_e32 v54, v55, v3
	v_min_u32_e32 v3, v55, v3
	v_max_u32_e32 v55, v56, v3
	v_min_u32_e32 v3, v56, v3
	v_max_u32_e32 v56, v57, v3
	v_min_u32_e32 v3, v57, v3
	v_max_u32_e32 v57, v69, v3
	v_min_u32_e32 v3, v69, v3
	v_max_u32_e32 v69, v68, v3
	v_min_u32_e32 v3, v68, v3
	v_max_u32_e32 v68, v67, v3
	v_min_u32_e32 v3, v67, v3
	v_max_u32_e32 v67, v66, v3
	v_min_u32_e32 v3, v66, v3
	v_max_u32_e32 v66, v65, v3
	v_min_u32_e32 v3, v65, v3
	v_max_u32_e32 v65, v64, v3
	v_min_u32_e32 v3, v64, v3
	v_max_u32_e32 v64, v63, v3
	v_min_u32_e32 v3, v63, v3
	v_max_u32_e32 v63, v62, v3
	v_min_u32_e32 v3, v62, v3
	v_max_u32_e32 v62, v61, v3
	v_min_u32_e32 v3, v61, v3
	v_max_u32_e32 v61, v60, v3
	v_min_u32_e32 v3, v60, v3
	v_max_u32_e32 v60, v59, v3
	v_min_u32_e32 v3, v59, v3
	v_max3_u32 v1, v1, v2, v3
	v_not_b32_e32 v2, v4
	v_or_b32_e32 v3, 0x80000000, v4
	v_cmp_gt_i32_e32 vcc, 0, v4
	s_nop 1
; DI int crow(int i, int h) { return (i & 3) + 8 * (i >> 2) + 4 * h; }
; DI unsigned f2ord(float f) { unsigned u = __float_as_uint(f); return (u & 0x80000000u) ? ~u : (u | 0x80000000u); }
; #define INS32(T, X) { _Pragma("unroll") for (int jj = 0; jj < 16; ++jj) { unsigned t_ = max(T[jj], X); X = min(T[jj], X); T[jj] = t_; } }
; __device__ __forceinline__ void route_task(const Params& p, int layer, const u16* qg, int rb, int hd, int r, int h) {
;     ...
; #pragma unroll
;       for (int e = 0; e < 16; ++e) {
;         unsigned key = (f2ord(acc[e]) & ~127u) | (unsigned)(127 - (n * 32 + crow(e, h)));
;         INS32(tp, key);
;       }
;     }
	v_cndmask_b32_e32 v2, v3, v2, vcc
	v_and_b32_e32 v2, 0xffffff80, v2
	v_add3_u32 v2, v0, v2, s65
	v_max_u32_e32 v3, v58, v2
	v_min_u32_e32 v2, v58, v2
	v_max_u32_e32 v4, v54, v2
	v_min_u32_e32 v2, v54, v2
	v_max_u32_e32 v54, v55, v2
	v_min_u32_e32 v2, v55, v2
	v_max_u32_e32 v55, v56, v2
	v_min_u32_e32 v2, v56, v2
	v_max_u32_e32 v56, v57, v2
	v_min_u32_e32 v2, v57, v2
	v_max_u32_e32 v57, v69, v2
	v_min_u32_e32 v2, v69, v2
	v_max_u32_e32 v58, v68, v2
	v_min_u32_e32 v2, v68, v2
	v_max_u32_e32 v59, v67, v2
	v_min_u32_e32 v2, v67, v2
	v_max_u32_e32 v67, v66, v2
	v_min_u32_e32 v2, v66, v2
	v_max_u32_e32 v66, v65, v2
	v_min_u32_e32 v2, v65, v2
	v_max_u32_e32 v65, v64, v2
	v_min_u32_e32 v2, v64, v2
	v_max_u32_e32 v64, v63, v2
	v_min_u32_e32 v2, v63, v2
	v_max_u32_e32 v63, v62, v2
	v_min_u32_e32 v2, v62, v2
	v_max_u32_e32 v62, v61, v2
	v_min_u32_e32 v2, v61, v2
	v_max_u32_e32 v61, v60, v2
	v_min_u32_e32 v2, v60, v2
	v_not_b32_e32 v60, v5
	v_or_b32_e32 v68, 0x80000000, v5
	v_cmp_gt_i32_e32 vcc, 0, v5
	s_nop 1
	v_cndmask_b32_e32 v5, v68, v60, vcc
	v_and_b32_e32 v5, 0xffffff80, v5
	v_add3_u32 v5, v0, v5, s66
	v_max_u32_e32 v60, v3, v5
	v_min_u32_e32 v3, v3, v5
	v_max_u32_e32 v5, v4, v3
	v_min_u32_e32 v3, v4, v3
	v_max_u32_e32 v4, v54, v3
	v_min_u32_e32 v3, v54, v3
	v_max_u32_e32 v54, v55, v3
	v_min_u32_e32 v3, v55, v3
	v_max_u32_e32 v55, v56, v3
	v_min_u32_e32 v3, v56, v3
	v_max_u32_e32 v56, v57, v3
	v_min_u32_e32 v3, v57, v3
	v_max_u32_e32 v57, v58, v3
	v_min_u32_e32 v3, v58, v3
	v_max_u32_e32 v58, v59, v3
	v_min_u32_e32 v3, v59, v3
	v_max_u32_e32 v59, v67, v3
	v_min_u32_e32 v3, v67, v3
	v_max_u32_e32 v67, v66, v3
	v_min_u32_e32 v3, v66, v3
	v_max_u32_e32 v66, v65, v3
	v_min_u32_e32 v3, v65, v3
	v_max_u32_e32 v65, v64, v3
	v_min_u32_e32 v3, v64, v3
	v_max_u32_e32 v64, v63, v3
	v_min_u32_e32 v3, v63, v3
	v_max_u32_e32 v63, v62, v3
	v_min_u32_e32 v3, v62, v3
	v_max_u32_e32 v62, v61, v3
	v_min_u32_e32 v3, v61, v3
	v_max3_u32 v1, v1, v2, v3
	v_not_b32_e32 v2, v6
	v_or_b32_e32 v3, 0x80000000, v6
	v_cmp_gt_i32_e32 vcc, 0, v6
	s_nop 1
	v_cndmask_b32_e32 v2, v3, v2, vcc
	v_and_b32_e32 v2, 0xffffff80, v2
	v_add3_u32 v2, v0, v2, s67
	v_max_u32_e32 v3, v60, v2
	v_min_u32_e32 v2, v60, v2
	v_max_u32_e32 v6, v5, v2
	v_min_u32_e32 v2, v5, v2
	v_max_u32_e32 v5, v4, v2
	v_min_u32_e32 v2, v4, v2
	v_max_u32_e32 v4, v54, v2
	v_min_u32_e32 v2, v54, v2
	v_max_u32_e32 v54, v55, v2
	v_min_u32_e32 v2, v55, v2
	v_max_u32_e32 v55, v56, v2
	v_min_u32_e32 v2, v56, v2
	v_max_u32_e32 v56, v57, v2
	v_min_u32_e32 v2, v57, v2
	v_max_u32_e32 v57, v58, v2
	v_min_u32_e32 v2, v58, v2
	v_max_u32_e32 v58, v59, v2
	v_min_u32_e32 v2, v59, v2
	v_max_u32_e32 v59, v67, v2
	v_min_u32_e32 v2, v67, v2
	v_max_u32_e32 v60, v66, v2
	v_min_u32_e32 v2, v66, v2
	v_max_u32_e32 v61, v65, v2
	v_min_u32_e32 v2, v65, v2
	v_max_u32_e32 v65, v64, v2
	v_min_u32_e32 v2, v64, v2
	v_max_u32_e32 v64, v63, v2
	v_min_u32_e32 v2, v63, v2
	v_max_u32_e32 v63, v62, v2
	v_min_u32_e32 v2, v62, v2
	v_not_b32_e32 v62, v7
	v_or_b32_e32 v66, 0x80000000, v7
	v_cmp_gt_i32_e32 vcc, 0, v7
	s_nop 1
	v_cndmask_b32_e32 v7, v66, v62, vcc
	v_and_b32_e32 v7, 0xffffff80, v7
	v_add3_u32 v7, v0, v7, s68
	v_max_u32_e32 v62, v3, v7
	v_min_u32_e32 v3, v3, v7
	v_max_u32_e32 v7, v6, v3
	v_min_u32_e32 v3, v6, v3
	v_max_u32_e32 v6, v5, v3
	v_min_u32_e32 v3, v5, v3
	v_max_u32_e32 v5, v4, v3
	v_min_u32_e32 v3, v4, v3
	v_max_u32_e32 v4, v54, v3
	v_min_u32_e32 v3, v54, v3
	v_max_u32_e32 v54, v55, v3
	v_min_u32_e32 v3, v55, v3
	v_max_u32_e32 v55, v56, v3
	v_min_u32_e32 v3, v56, v3
	v_max_u32_e32 v56, v57, v3
	v_min_u32_e32 v3, v57, v3
	v_max_u32_e32 v57, v58, v3
	v_min_u32_e32 v3, v58, v3
	v_max_u32_e32 v58, v59, v3
	v_min_u32_e32 v3, v59, v3
	v_max_u32_e32 v59, v60, v3
	v_min_u32_e32 v3, v60, v3
	v_max_u32_e32 v60, v61, v3
	v_min_u32_e32 v3, v61, v3
	v_max_u32_e32 v61, v65, v3
	v_min_u32_e32 v3, v65, v3
	v_max_u32_e32 v65, v64, v3
	v_min_u32_e32 v3, v64, v3
	v_max_u32_e32 v64, v63, v3
	v_min_u32_e32 v3, v63, v3
	v_max3_u32 v1, v1, v2, v3
	v_not_b32_e32 v2, v8
	v_or_b32_e32 v3, 0x80000000, v8
	v_cmp_gt_i32_e32 vcc, 0, v8
	v_not_b32_e32 v63, v9
	s_nop 0
	v_cndmask_b32_e32 v2, v3, v2, vcc
	v_and_b32_e32 v2, 0xffffff80, v2
	v_add3_u32 v2, v0, v2, s69
	v_max_u32_e32 v3, v62, v2
	v_min_u32_e32 v2, v62, v2
	v_max_u32_e32 v8, v7, v2
	v_min_u32_e32 v2, v7, v2
	v_max_u32_e32 v7, v6, v2
	v_min_u32_e32 v2, v6, v2
	v_max_u32_e32 v6, v5, v2
	v_min_u32_e32 v2, v5, v2
	v_max_u32_e32 v5, v4, v2
	v_min_u32_e32 v2, v4, v2
	v_max_u32_e32 v4, v54, v2
	v_min_u32_e32 v2, v54, v2
	v_max_u32_e32 v54, v55, v2
	v_min_u32_e32 v2, v55, v2
	v_max_u32_e32 v55, v56, v2
	v_min_u32_e32 v2, v56, v2
	v_max_u32_e32 v56, v57, v2
	v_min_u32_e32 v2, v57, v2
	v_max_u32_e32 v57, v58, v2
	v_min_u32_e32 v2, v58, v2
	v_max_u32_e32 v58, v59, v2
	v_min_u32_e32 v2, v59, v2
	v_max_u32_e32 v59, v60, v2
	v_min_u32_e32 v2, v60, v2
	v_max_u32_e32 v60, v61, v2
	v_min_u32_e32 v2, v61, v2
	v_max_u32_e32 v61, v65, v2
	v_min_u32_e32 v2, v65, v2
	v_max_u32_e32 v62, v64, v2
	v_min_u32_e32 v2, v64, v2
	v_or_b32_e32 v64, 0x80000000, v9
	v_cmp_gt_i32_e32 vcc, 0, v9
	s_nop 1
	v_cndmask_b32_e32 v9, v64, v63, vcc
	v_and_b32_e32 v9, 0xffffff80, v9
	v_add3_u32 v9, v0, v9, s70
	v_max_u32_e32 v63, v3, v9
	v_min_u32_e32 v3, v3, v9
	v_max_u32_e32 v9, v8, v3
	v_min_u32_e32 v3, v8, v3
	v_max_u32_e32 v8, v7, v3
	v_min_u32_e32 v3, v7, v3
	v_max_u32_e32 v7, v6, v3
	v_min_u32_e32 v3, v6, v3
	v_max_u32_e32 v6, v5, v3
	v_min_u32_e32 v3, v5, v3
	v_max_u32_e32 v5, v4, v3
	v_min_u32_e32 v3, v4, v3
	v_max_u32_e32 v4, v54, v3
	v_min_u32_e32 v3, v54, v3
	v_max_u32_e32 v54, v55, v3
	v_min_u32_e32 v3, v55, v3
	v_max_u32_e32 v55, v56, v3
; DI int crow(int i, int h) { return (i & 3) + 8 * (i >> 2) + 4 * h; }
; DI unsigned f2ord(float f) { unsigned u = __float_as_uint(f); return (u & 0x80000000u) ? ~u : (u | 0x80000000u); }
; #define INS32(T, X) { _Pragma("unroll") for (int jj = 0; jj < 16; ++jj) { unsigned t_ = max(T[jj], X); X = min(T[jj], X); T[jj] = t_; } }
; __device__ __forceinline__ void route_task(const Params& p, int layer, const u16* qg, int rb, int hd, int r, int h) {
;     ...
; #pragma unroll
;       for (int e = 0; e < 16; ++e) {
;         unsigned key = (f2ord(acc[e]) & ~127u) | (unsigned)(127 - (n * 32 + crow(e, h)));
;         INS32(tp, key);
;       }
;     }
	v_min_u32_e32 v3, v56, v3
	v_max_u32_e32 v56, v57, v3
	v_min_u32_e32 v3, v57, v3
	v_max_u32_e32 v57, v58, v3
	v_min_u32_e32 v3, v58, v3
	v_max_u32_e32 v58, v59, v3
	v_min_u32_e32 v3, v59, v3
	v_max_u32_e32 v59, v60, v3
	v_min_u32_e32 v3, v60, v3
	v_max_u32_e32 v60, v61, v3
	v_min_u32_e32 v3, v61, v3
	v_max_u32_e32 v61, v62, v3
	v_min_u32_e32 v3, v62, v3
	v_max3_u32 v1, v1, v2, v3
	v_not_b32_e32 v2, v10
	v_or_b32_e32 v3, 0x80000000, v10
	v_cmp_gt_i32_e32 vcc, 0, v10
	v_or_b32_e32 v62, 0x80000000, v11
	s_nop 0
	v_cndmask_b32_e32 v2, v3, v2, vcc
	v_and_b32_e32 v2, 0xffffff80, v2
	v_add3_u32 v2, v0, v2, s71
	v_max_u32_e32 v3, v63, v2
	v_min_u32_e32 v2, v63, v2
	v_max_u32_e32 v10, v9, v2
	v_min_u32_e32 v2, v9, v2
	v_max_u32_e32 v9, v8, v2
	v_min_u32_e32 v2, v8, v2
	v_max_u32_e32 v8, v7, v2
	v_min_u32_e32 v2, v7, v2
	v_max_u32_e32 v7, v6, v2
	v_min_u32_e32 v2, v6, v2
	v_max_u32_e32 v6, v5, v2
	v_min_u32_e32 v2, v5, v2
	v_max_u32_e32 v5, v4, v2
	v_min_u32_e32 v2, v4, v2
	v_max_u32_e32 v4, v54, v2
	v_min_u32_e32 v2, v54, v2
	v_max_u32_e32 v54, v55, v2
	v_min_u32_e32 v2, v55, v2
	v_max_u32_e32 v55, v56, v2
	v_min_u32_e32 v2, v56, v2
	v_max_u32_e32 v56, v57, v2
	v_min_u32_e32 v2, v57, v2
	v_max_u32_e32 v57, v58, v2
	v_min_u32_e32 v2, v58, v2
	v_max_u32_e32 v58, v59, v2
	v_min_u32_e32 v2, v59, v2
	v_max_u32_e32 v59, v60, v2
	v_min_u32_e32 v2, v60, v2
	v_max_u32_e32 v60, v61, v2
	v_min_u32_e32 v2, v61, v2
	v_not_b32_e32 v61, v11
	v_cmp_gt_i32_e32 vcc, 0, v11
	s_nop 1
	v_cndmask_b32_e32 v11, v62, v61, vcc
	v_and_b32_e32 v11, 0xffffff80, v11
	v_add3_u32 v11, v0, v11, s72
	v_max_u32_e32 v61, v3, v11
	v_min_u32_e32 v3, v3, v11
	v_max_u32_e32 v11, v10, v3
	v_min_u32_e32 v3, v10, v3
	v_max_u32_e32 v10, v9, v3
	v_min_u32_e32 v3, v9, v3
	v_max_u32_e32 v9, v8, v3
	v_min_u32_e32 v3, v8, v3
	v_max_u32_e32 v8, v7, v3
	v_min_u32_e32 v3, v7, v3
	v_max_u32_e32 v7, v6, v3
	v_min_u32_e32 v3, v6, v3
	v_max_u32_e32 v6, v5, v3
	v_min_u32_e32 v3, v5, v3
	v_max_u32_e32 v5, v4, v3
	v_min_u32_e32 v3, v4, v3
	v_max_u32_e32 v4, v54, v3
	v_min_u32_e32 v3, v54, v3
	v_max_u32_e32 v54, v55, v3
	v_min_u32_e32 v3, v55, v3
	v_max_u32_e32 v55, v56, v3
	v_min_u32_e32 v3, v56, v3
	v_max_u32_e32 v56, v57, v3
	v_min_u32_e32 v3, v57, v3
	v_max_u32_e32 v57, v58, v3
	v_min_u32_e32 v3, v58, v3
	v_max_u32_e32 v58, v59, v3
	v_min_u32_e32 v3, v59, v3
	v_max_u32_e32 v59, v60, v3
	v_min_u32_e32 v3, v60, v3
	v_max3_u32 v1, v1, v2, v3
	v_not_b32_e32 v2, v12
	v_or_b32_e32 v3, 0x80000000, v12
	v_cmp_gt_i32_e32 vcc, 0, v12
	v_or_b32_e32 v60, 0x80000000, v13
	s_nop 0
	v_cndmask_b32_e32 v2, v3, v2, vcc
	v_and_b32_e32 v2, 0xffffff80, v2
	v_add3_u32 v2, v0, v2, s73
	v_max_u32_e32 v3, v61, v2
	v_min_u32_e32 v2, v61, v2
	v_max_u32_e32 v12, v11, v2
	v_min_u32_e32 v2, v11, v2
	v_max_u32_e32 v11, v10, v2
	v_min_u32_e32 v2, v10, v2
	v_max_u32_e32 v10, v9, v2
	v_min_u32_e32 v2, v9, v2
	v_max_u32_e32 v9, v8, v2
	v_min_u32_e32 v2, v8, v2
	v_max_u32_e32 v8, v7, v2
	v_min_u32_e32 v2, v7, v2
	v_max_u32_e32 v7, v6, v2
	v_min_u32_e32 v2, v6, v2
	v_max_u32_e32 v6, v5, v2
	v_min_u32_e32 v2, v5, v2
	v_max_u32_e32 v5, v4, v2
	v_min_u32_e32 v2, v4, v2
	v_max_u32_e32 v4, v54, v2
	v_min_u32_e32 v2, v54, v2
	v_max_u32_e32 v54, v55, v2
	v_min_u32_e32 v2, v55, v2
	v_max_u32_e32 v55, v56, v2
	v_min_u32_e32 v2, v56, v2
	v_max_u32_e32 v56, v57, v2
	v_min_u32_e32 v2, v57, v2
	v_max_u32_e32 v57, v58, v2
	v_min_u32_e32 v2, v58, v2
	v_max_u32_e32 v58, v59, v2
	v_min_u32_e32 v2, v59, v2
	v_not_b32_e32 v59, v13
	v_cmp_gt_i32_e32 vcc, 0, v13
	s_nop 1
	v_cndmask_b32_e32 v13, v60, v59, vcc
	v_and_b32_e32 v13, 0xffffff80, v13
	v_add3_u32 v13, v0, v13, s77
	v_max_u32_e32 v59, v3, v13
	v_min_u32_e32 v3, v3, v13
	v_max_u32_e32 v13, v12, v3
	v_min_u32_e32 v3, v12, v3
	v_max_u32_e32 v12, v11, v3
	v_min_u32_e32 v3, v11, v3
	v_max_u32_e32 v11, v10, v3
	v_min_u32_e32 v3, v10, v3
	v_max_u32_e32 v10, v9, v3
	v_min_u32_e32 v3, v9, v3
	v_max_u32_e32 v9, v8, v3
	v_min_u32_e32 v3, v8, v3
	v_max_u32_e32 v8, v7, v3
	v_min_u32_e32 v3, v7, v3
	v_max_u32_e32 v7, v6, v3
	v_min_u32_e32 v3, v6, v3
	v_max_u32_e32 v6, v5, v3
	v_min_u32_e32 v3, v5, v3
	v_max_u32_e32 v5, v4, v3
	v_min_u32_e32 v3, v4, v3
	v_max_u32_e32 v4, v54, v3
	v_min_u32_e32 v3, v54, v3
	v_max_u32_e32 v54, v55, v3
	v_min_u32_e32 v3, v55, v3
	v_max_u32_e32 v55, v56, v3
	v_min_u32_e32 v3, v56, v3
	v_max_u32_e32 v56, v57, v3
	v_min_u32_e32 v3, v57, v3
	v_max_u32_e32 v57, v58, v3
	v_min_u32_e32 v3, v58, v3
	v_max3_u32 v1, v1, v2, v3
	v_not_b32_e32 v2, v14
	v_or_b32_e32 v3, 0x80000000, v14
	v_cmp_gt_i32_e32 vcc, 0, v14
	s_nop 1
	v_cndmask_b32_e32 v2, v3, v2, vcc
	v_and_b32_e32 v2, 0xffffff80, v2
	v_add3_u32 v2, v0, v2, s78
	v_max_u32_e32 v3, v59, v2
	v_min_u32_e32 v2, v59, v2
	v_max_u32_e32 v14, v13, v2
	v_min_u32_e32 v2, v13, v2
	v_max_u32_e32 v13, v12, v2
	v_min_u32_e32 v2, v12, v2
	v_max_u32_e32 v12, v11, v2
	v_min_u32_e32 v2, v11, v2
	v_max_u32_e32 v11, v10, v2
	v_min_u32_e32 v2, v10, v2
	v_max_u32_e32 v10, v9, v2
	v_min_u32_e32 v2, v9, v2
	v_max_u32_e32 v9, v8, v2
	v_min_u32_e32 v2, v8, v2
	v_max_u32_e32 v8, v7, v2
	v_min_u32_e32 v2, v7, v2
	v_max_u32_e32 v7, v6, v2
	v_min_u32_e32 v2, v6, v2
	v_max_u32_e32 v6, v5, v2
	v_min_u32_e32 v2, v5, v2
	v_max_u32_e32 v5, v4, v2
	v_min_u32_e32 v2, v4, v2
	v_max_u32_e32 v4, v54, v2
	v_min_u32_e32 v2, v54, v2
	v_max_u32_e32 v54, v55, v2
	v_min_u32_e32 v2, v55, v2
	v_max_u32_e32 v55, v56, v2
	v_min_u32_e32 v2, v56, v2
	v_max_u32_e32 v70, v57, v2
	v_min_u32_e32 v2, v57, v2
	v_not_b32_e32 v56, v15
	v_or_b32_e32 v57, 0x80000000, v15
	v_cmp_gt_i32_e32 vcc, 0, v15
	s_nop 1
	v_cndmask_b32_e32 v15, v57, v56, vcc
	v_and_b32_e32 v15, 0xffffff80, v15
	v_add3_u32 v0, v0, v15, s79
	v_max_u32_e32 v69, v3, v0
	v_min_u32_e32 v0, v3, v0
	v_max_u32_e32 v68, v14, v0
	v_min_u32_e32 v0, v14, v0
	v_max_u32_e32 v67, v13, v0
	v_min_u32_e32 v0, v13, v0
	v_max_u32_e32 v66, v12, v0
	v_min_u32_e32 v0, v12, v0
	v_max_u32_e32 v65, v11, v0
	v_min_u32_e32 v0, v11, v0
	v_max_u32_e32 v64, v10, v0
	v_min_u32_e32 v0, v10, v0
	v_max_u32_e32 v63, v9, v0
	v_min_u32_e32 v0, v9, v0
	v_max_u32_e32 v62, v8, v0
	v_min_u32_e32 v0, v8, v0
	v_max_u32_e32 v61, v7, v0
	v_min_u32_e32 v0, v7, v0
	v_max_u32_e32 v60, v6, v0
	v_min_u32_e32 v0, v6, v0
	v_max_u32_e32 v59, v5, v0
	v_min_u32_e32 v0, v5, v0
	v_max_u32_e32 v58, v4, v0
	v_min_u32_e32 v0, v4, v0
	v_max_u32_e32 v57, v54, v0
	v_min_u32_e32 v0, v54, v0
	v_max_u32_e32 v56, v55, v0
	v_min_u32_e32 v0, v55, v0
	v_max_u32_e32 v55, v70, v0
	v_min_u32_e32 v0, v70, v0
	v_max3_u32 v54, v1, v2, v0
	s_cbranch_scc1 .LBB0_1873
; #define MFMA32(a, b, c) __builtin_amdgcn_mfma_f32_32x32x16_bf16((a), (b), (c), 0, 0, 0)
; __device__ __forceinline__ void route_task(const Params& p, int layer, const u16* qg, int rb, int hd, int r, int h) {
;     ...
;   for (int ph = 0; ph < 2; ++ph) {
;     bf16x8 qf[8];
; #pragma unroll
;     for (int s = 0; s < 8; ++s) qf[s] = *(const bf16x8*)(qg + ph * 128 + 16 * s);
;     const u16* kg = KY + ((size_t)((layer * 8 + hd) * 2 + ph) * 128 + r) * 128 + 8 * h;
;     unsigned tp[16];
; #pragma unroll
;     for (int jj = 0; jj < 16; ++jj) tp[jj] = 0u;
; #pragma unroll 1
;     for (int n = 0; n < 4; ++n) {
;       f32x16 acc;
; #pragma unroll
;       for (int e = 0; e < 16; ++e) acc[e] = 0.f;
; #pragma unroll
;       for (int s = 0; s < 8; ++s) {
;         bf16x8 kf = *(const bf16x8*)(kg + (size_t)n * 32 * 128 + 16 * s);
;         acc = MFMA32(kf, qf[s], acc);
;     ...
;     for (int jj = 0; jj < 16; ++jj) ot[jj] = (unsigned)__shfl_xor((int)tp[jj], 32);
	ds_read_b128 v[16:19], v83 offset:256
	ds_read_b128 v[20:23], v83 offset:288
	ds_read_b128 v[24:27], v83 offset:320
	ds_read_b128 v[28:31], v83 offset:352
	ds_read_b128 v[32:35], v83 offset:384
	ds_read_b128 v[36:39], v83 offset:416
	ds_read_b128 v[40:43], v83 offset:448
	ds_read_b128 v[44:47], v83 offset:480
	v_and_b32_e32 v0, 64, v214
	v_add_u32_e32 v0, 64, v0
	v_xor_b32_e32 v1, 32, v214
	v_cmp_lt_i32_e32 vcc, v1, v0
	s_mov_b32 s18, 0
	v_lshl_add_u64 v[48:49], s[14:15], 0, v[48:49]
	v_cndmask_b32_e32 v0, v214, v1, vcc
	v_lshlrev_b32_e32 v85, 2, v0
	ds_bpermute_b32 v84, v85, v69
	ds_bpermute_b32 v82, v85, v68
	ds_bpermute_b32 v81, v85, v67
	ds_bpermute_b32 v80, v85, v66
	ds_bpermute_b32 v79, v85, v65
	ds_bpermute_b32 v78, v85, v64
	ds_bpermute_b32 v77, v85, v63
	ds_bpermute_b32 v76, v85, v62
	ds_bpermute_b32 v75, v85, v61
	ds_bpermute_b32 v74, v85, v60
	ds_bpermute_b32 v73, v85, v59
	ds_bpermute_b32 v72, v85, v58
	ds_bpermute_b32 v71, v85, v57
	ds_bpermute_b32 v70, v85, v56
	ds_bpermute_b32 v51, v85, v55
	ds_bpermute_b32 v50, v85, v54
	v_mov_b32_e32 v86, 0
	v_mov_b32_e32 v87, 0
	v_mov_b32_e32 v88, 0
	v_mov_b32_e32 v89, 0
	v_mov_b32_e32 v90, 0
	v_mov_b32_e32 v91, 0
	v_mov_b32_e32 v92, 0
	v_mov_b32_e32 v93, 0
	v_mov_b32_e32 v94, 0
	v_mov_b32_e32 v95, 0
	v_mov_b32_e32 v96, 0
	v_mov_b32_e32 v97, 0
	v_mov_b32_e32 v98, 0
	v_mov_b32_e32 v99, 0
	v_mov_b32_e32 v100, 0
	v_mov_b32_e32 v83, 0
.LBB0_1875:
	global_load_dwordx4 v[190:193], v[48:49], off offset:-128
	global_load_dwordx4 v[194:197], v[48:49], off offset:-96
	global_load_dwordx4 v[198:201], v[48:49], off offset:-64
	global_load_dwordx4 v[202:205], v[48:49], off offset:-32
	global_load_dwordx4 v[206:209], v[48:49], off
	global_load_dwordx4 v[216:219], v[48:49], off offset:32
	global_load_dwordx4 v[220:223], v[48:49], off offset:64
	global_load_dwordx4 v[224:227], v[48:49], off offset:96
	v_lshl_add_u64 v[48:49], v[48:49], 0, s[16:17]
	s_waitcnt vmcnt(7) lgkmcnt(14)
	v_mfma_f32_32x32x16_bf16 v[0:15], v[190:193], v[16:19], 0
	s_waitcnt vmcnt(6)
	v_mfma_f32_32x32x16_bf16 v[0:15], v[194:197], v[20:23], v[0:15]
	s_waitcnt vmcnt(5)
	v_mfma_f32_32x32x16_bf16 v[0:15], v[198:201], v[24:27], v[0:15]
	s_waitcnt vmcnt(4)
	v_mfma_f32_32x32x16_bf16 v[0:15], v[202:205], v[28:31], v[0:15]
	s_waitcnt vmcnt(3)
	v_mfma_f32_32x32x16_bf16 v[0:15], v[206:209], v[32:35], v[0:15]
	s_waitcnt vmcnt(2)
	v_mfma_f32_32x32x16_bf16 v[0:15], v[216:219], v[36:39], v[0:15]
	s_waitcnt vmcnt(1)
	v_mfma_f32_32x32x16_bf16 v[0:15], v[220:223], v[40:43], v[0:15]
	s_waitcnt vmcnt(0)
	v_mfma_f32_32x32x16_bf16 v[0:15], v[224:227], v[44:47], v[0:15]
	s_nop 11
	v_not_b32_e32 v101, v0
	v_or_b32_e32 v102, 0x80000000, v0
	v_cmp_gt_i32_e32 vcc, 0, v0
	v_or_b32_e32 v103, 0x80000000, v1
	s_nop 0
	v_cndmask_b32_e32 v0, v102, v101, vcc
	v_and_b32_e32 v101, 0xffffff80, v0
	v_add_u32_e32 v0, s18, v53
	v_add3_u32 v101, v0, v101, s61
	v_max_u32_e32 v102, v86, v101
	v_min_u32_e32 v86, v86, v101
	v_max_u32_e32 v101, v87, v86
	v_min_u32_e32 v86, v87, v86
	v_max_u32_e32 v87, v88, v86
	v_min_u32_e32 v86, v88, v86
	v_max_u32_e32 v88, v89, v86
	v_min_u32_e32 v86, v89, v86
	v_max_u32_e32 v89, v90, v86
	v_min_u32_e32 v86, v90, v86
	v_max_u32_e32 v90, v91, v86
	v_min_u32_e32 v86, v91, v86
	v_max_u32_e32 v91, v92, v86
	v_min_u32_e32 v86, v92, v86
	v_max_u32_e32 v92, v93, v86
	v_min_u32_e32 v86, v93, v86
	v_max_u32_e32 v93, v94, v86
	v_min_u32_e32 v86, v94, v86
	v_max_u32_e32 v94, v95, v86
	v_min_u32_e32 v86, v95, v86
	v_max_u32_e32 v95, v96, v86
	v_min_u32_e32 v86, v96, v86
	v_max_u32_e32 v96, v97, v86
	v_min_u32_e32 v86, v97, v86
	v_max_u32_e32 v97, v98, v86
	v_min_u32_e32 v86, v98, v86
	v_max_u32_e32 v98, v99, v86
	v_min_u32_e32 v86, v99, v86
	v_max_u32_e32 v99, v100, v86
	v_min_u32_e32 v86, v100, v86
	v_not_b32_e32 v100, v1
	v_cmp_gt_i32_e32 vcc, 0, v1
	s_sub_i32 s18, s18, 32
	s_cmpk_lg_i32 s18, 0xff80
	v_cndmask_b32_e32 v1, v103, v100, vcc
	v_and_b32_e32 v1, 0xffffff80, v1
	v_add3_u32 v1, v0, v1, s62
	v_max_u32_e32 v100, v102, v1
	v_min_u32_e32 v1, v102, v1
	v_max_u32_e32 v102, v101, v1
	v_min_u32_e32 v1, v101, v1
	v_max_u32_e32 v101, v87, v1
	v_min_u32_e32 v1, v87, v1
	v_max_u32_e32 v87, v88, v1
	v_min_u32_e32 v1, v88, v1
	v_max_u32_e32 v88, v89, v1
	v_min_u32_e32 v1, v89, v1
	v_max_u32_e32 v89, v90, v1
	v_min_u32_e32 v1, v90, v1
	v_max_u32_e32 v90, v91, v1
	v_min_u32_e32 v1, v91, v1
	v_max_u32_e32 v91, v92, v1
	v_min_u32_e32 v1, v92, v1
	v_max_u32_e32 v92, v93, v1
	v_min_u32_e32 v1, v93, v1
	v_max_u32_e32 v93, v94, v1
	v_min_u32_e32 v1, v94, v1
	v_max_u32_e32 v94, v95, v1
	v_min_u32_e32 v1, v95, v1
	v_max_u32_e32 v95, v96, v1
	v_min_u32_e32 v1, v96, v1
	v_max_u32_e32 v96, v97, v1
	v_min_u32_e32 v1, v97, v1
	v_max_u32_e32 v97, v98, v1
	v_min_u32_e32 v1, v98, v1
	v_max_u32_e32 v98, v99, v1
	v_min_u32_e32 v1, v99, v1
	v_max3_u32 v1, v83, v86, v1
	v_not_b32_e32 v83, v2
	v_or_b32_e32 v86, 0x80000000, v2
	v_cmp_gt_i32_e32 vcc, 0, v2
	s_nop 1
	v_cndmask_b32_e32 v2, v86, v83, vcc
	v_and_b32_e32 v2, 0xffffff80, v2
	v_add3_u32 v2, v0, v2, s63
	v_max_u32_e32 v83, v100, v2
	v_min_u32_e32 v2, v100, v2
	v_max_u32_e32 v86, v102, v2
	v_min_u32_e32 v2, v102, v2
	v_max_u32_e32 v99, v101, v2
	v_min_u32_e32 v2, v101, v2
	v_max_u32_e32 v100, v87, v2
	v_min_u32_e32 v2, v87, v2
	v_max_u32_e32 v87, v88, v2
	v_min_u32_e32 v2, v88, v2
	v_max_u32_e32 v88, v89, v2
	v_min_u32_e32 v2, v89, v2
	v_max_u32_e32 v89, v90, v2
	v_min_u32_e32 v2, v90, v2
	v_max_u32_e32 v90, v91, v2
	v_min_u32_e32 v2, v91, v2
	v_max_u32_e32 v91, v92, v2
	v_min_u32_e32 v2, v92, v2
	v_max_u32_e32 v92, v93, v2
	v_min_u32_e32 v2, v93, v2
	v_max_u32_e32 v93, v94, v2
	v_min_u32_e32 v2, v94, v2
; DI int crow(int i, int h) { return (i & 3) + 8 * (i >> 2) + 4 * h; }
; DI unsigned f2ord(float f) { unsigned u = __float_as_uint(f); return (u & 0x80000000u) ? ~u : (u | 0x80000000u); }
; #define INS32(T, X) { _Pragma("unroll") for (int jj = 0; jj < 16; ++jj) { unsigned t_ = max(T[jj], X); X = min(T[jj], X); T[jj] = t_; } }
; __device__ __forceinline__ void route_task(const Params& p, int layer, const u16* qg, int rb, int hd, int r, int h) {
;     ...
; #pragma unroll
;       for (int e = 0; e < 16; ++e) {
;         unsigned key = (f2ord(acc[e]) & ~127u) | (unsigned)(127 - (n * 32 + crow(e, h)));
;         INS32(tp, key);
;       }
;     }
	v_max_u32_e32 v94, v95, v2
	v_min_u32_e32 v2, v95, v2
	v_max_u32_e32 v95, v96, v2
	v_min_u32_e32 v2, v96, v2
	v_max_u32_e32 v96, v97, v2
	v_min_u32_e32 v2, v97, v2
	v_max_u32_e32 v97, v98, v2
	v_min_u32_e32 v2, v98, v2
	v_not_b32_e32 v98, v3
	v_or_b32_e32 v101, 0x80000000, v3
	v_cmp_gt_i32_e32 vcc, 0, v3
	s_nop 1
	v_cndmask_b32_e32 v3, v101, v98, vcc
	v_and_b32_e32 v3, 0xffffff80, v3
	v_add3_u32 v3, v0, v3, s64
	v_max_u32_e32 v98, v83, v3
	v_min_u32_e32 v3, v83, v3
	v_max_u32_e32 v83, v86, v3
	v_min_u32_e32 v3, v86, v3
	v_max_u32_e32 v86, v99, v3
	v_min_u32_e32 v3, v99, v3
	v_max_u32_e32 v99, v100, v3
	v_min_u32_e32 v3, v100, v3
	v_max_u32_e32 v100, v87, v3
	v_min_u32_e32 v3, v87, v3
	v_max_u32_e32 v87, v88, v3
	v_min_u32_e32 v3, v88, v3
	v_max_u32_e32 v88, v89, v3
	v_min_u32_e32 v3, v89, v3
	v_max_u32_e32 v89, v90, v3
	v_min_u32_e32 v3, v90, v3
	v_max_u32_e32 v90, v91, v3
	v_min_u32_e32 v3, v91, v3
	v_max_u32_e32 v91, v92, v3
	v_min_u32_e32 v3, v92, v3
	v_max_u32_e32 v92, v93, v3
	v_min_u32_e32 v3, v93, v3
	v_max_u32_e32 v93, v94, v3
	v_min_u32_e32 v3, v94, v3
	v_max_u32_e32 v94, v95, v3
	v_min_u32_e32 v3, v95, v3
	v_max_u32_e32 v95, v96, v3
	v_min_u32_e32 v3, v96, v3
	v_max_u32_e32 v96, v97, v3
	v_min_u32_e32 v3, v97, v3
	v_max3_u32 v1, v1, v2, v3
	v_not_b32_e32 v2, v4
	v_or_b32_e32 v3, 0x80000000, v4
	v_cmp_gt_i32_e32 vcc, 0, v4
	s_nop 1
	v_cndmask_b32_e32 v2, v3, v2, vcc
	v_and_b32_e32 v2, 0xffffff80, v2
	v_add3_u32 v2, v0, v2, s65
	v_max_u32_e32 v3, v98, v2
	v_min_u32_e32 v2, v98, v2
	v_max_u32_e32 v4, v83, v2
	v_min_u32_e32 v2, v83, v2
	v_max_u32_e32 v83, v86, v2
	v_min_u32_e32 v2, v86, v2
	v_max_u32_e32 v86, v99, v2
	v_min_u32_e32 v2, v99, v2
	v_max_u32_e32 v97, v100, v2
	v_min_u32_e32 v2, v100, v2
	v_max_u32_e32 v98, v87, v2
	v_min_u32_e32 v2, v87, v2
	v_max_u32_e32 v87, v88, v2
	v_min_u32_e32 v2, v88, v2
	v_max_u32_e32 v88, v89, v2
	v_min_u32_e32 v2, v89, v2
	v_max_u32_e32 v89, v90, v2
	v_min_u32_e32 v2, v90, v2
	v_max_u32_e32 v90, v91, v2
	v_min_u32_e32 v2, v91, v2
	v_max_u32_e32 v91, v92, v2
	v_min_u32_e32 v2, v92, v2
	v_max_u32_e32 v92, v93, v2
	v_min_u32_e32 v2, v93, v2
	v_max_u32_e32 v93, v94, v2
	v_min_u32_e32 v2, v94, v2
	v_max_u32_e32 v94, v95, v2
	v_min_u32_e32 v2, v95, v2
	v_max_u32_e32 v95, v96, v2
	v_min_u32_e32 v2, v96, v2
	v_not_b32_e32 v96, v5
	v_or_b32_e32 v99, 0x80000000, v5
	v_cmp_gt_i32_e32 vcc, 0, v5
	s_nop 1
	v_cndmask_b32_e32 v5, v99, v96, vcc
	v_and_b32_e32 v5, 0xffffff80, v5
	v_add3_u32 v5, v0, v5, s66
	v_max_u32_e32 v96, v3, v5
	v_min_u32_e32 v3, v3, v5
	v_max_u32_e32 v5, v4, v3
	v_min_u32_e32 v3, v4, v3
	v_max_u32_e32 v4, v83, v3
	v_min_u32_e32 v3, v83, v3
	v_max_u32_e32 v83, v86, v3
	v_min_u32_e32 v3, v86, v3
	v_max_u32_e32 v86, v97, v3
	v_min_u32_e32 v3, v97, v3
	v_max_u32_e32 v97, v98, v3
	v_min_u32_e32 v3, v98, v3
	v_max_u32_e32 v98, v87, v3
	v_min_u32_e32 v3, v87, v3
	v_max_u32_e32 v87, v88, v3
	v_min_u32_e32 v3, v88, v3
	v_max_u32_e32 v88, v89, v3
	v_min_u32_e32 v3, v89, v3
	v_max_u32_e32 v89, v90, v3
	v_min_u32_e32 v3, v90, v3
	v_max_u32_e32 v90, v91, v3
	v_min_u32_e32 v3, v91, v3
	v_max_u32_e32 v91, v92, v3
	v_min_u32_e32 v3, v92, v3
	v_max_u32_e32 v92, v93, v3
	v_min_u32_e32 v3, v93, v3
	v_max_u32_e32 v93, v94, v3
	v_min_u32_e32 v3, v94, v3
	v_max_u32_e32 v94, v95, v3
	v_min_u32_e32 v3, v95, v3
	v_max3_u32 v1, v1, v2, v3
	v_not_b32_e32 v2, v6
	v_or_b32_e32 v3, 0x80000000, v6
	v_cmp_gt_i32_e32 vcc, 0, v6
	s_nop 1
	v_cndmask_b32_e32 v2, v3, v2, vcc
	v_and_b32_e32 v2, 0xffffff80, v2
	v_add3_u32 v2, v0, v2, s67
	v_max_u32_e32 v3, v96, v2
	v_min_u32_e32 v2, v96, v2
	v_max_u32_e32 v6, v5, v2
	v_min_u32_e32 v2, v5, v2
	v_max_u32_e32 v5, v4, v2
	v_min_u32_e32 v2, v4, v2
	v_max_u32_e32 v4, v83, v2
	v_min_u32_e32 v2, v83, v2
	v_max_u32_e32 v83, v86, v2
	v_min_u32_e32 v2, v86, v2
	v_max_u32_e32 v86, v97, v2
	v_min_u32_e32 v2, v97, v2
	v_max_u32_e32 v95, v98, v2
	v_min_u32_e32 v2, v98, v2
	v_max_u32_e32 v96, v87, v2
	v_min_u32_e32 v2, v87, v2
	v_max_u32_e32 v87, v88, v2
	v_min_u32_e32 v2, v88, v2
	v_max_u32_e32 v88, v89, v2
	v_min_u32_e32 v2, v89, v2
	v_max_u32_e32 v89, v90, v2
	v_min_u32_e32 v2, v90, v2
	v_max_u32_e32 v90, v91, v2
	v_min_u32_e32 v2, v91, v2
	v_max_u32_e32 v91, v92, v2
	v_min_u32_e32 v2, v92, v2
	v_max_u32_e32 v92, v93, v2
	v_min_u32_e32 v2, v93, v2
	v_max_u32_e32 v93, v94, v2
	v_min_u32_e32 v2, v94, v2
	v_not_b32_e32 v94, v7
	v_or_b32_e32 v97, 0x80000000, v7
	v_cmp_gt_i32_e32 vcc, 0, v7
	s_nop 1
	v_cndmask_b32_e32 v7, v97, v94, vcc
	v_and_b32_e32 v7, 0xffffff80, v7
	v_add3_u32 v7, v0, v7, s68
	v_max_u32_e32 v94, v3, v7
	v_min_u32_e32 v3, v3, v7
	v_max_u32_e32 v7, v6, v3
	v_min_u32_e32 v3, v6, v3
	v_max_u32_e32 v6, v5, v3
	v_min_u32_e32 v3, v5, v3
	v_max_u32_e32 v5, v4, v3
	v_min_u32_e32 v3, v4, v3
	v_max_u32_e32 v4, v83, v3
	v_min_u32_e32 v3, v83, v3
	v_max_u32_e32 v83, v86, v3
	v_min_u32_e32 v3, v86, v3
	v_max_u32_e32 v86, v95, v3
	v_min_u32_e32 v3, v95, v3
	v_max_u32_e32 v95, v96, v3
	v_min_u32_e32 v3, v96, v3
	v_max_u32_e32 v96, v87, v3
	v_min_u32_e32 v3, v87, v3
	v_max_u32_e32 v87, v88, v3
	v_min_u32_e32 v3, v88, v3
	v_max_u32_e32 v88, v89, v3
	v_min_u32_e32 v3, v89, v3
	v_max_u32_e32 v89, v90, v3
	v_min_u32_e32 v3, v90, v3
	v_max_u32_e32 v90, v91, v3
	v_min_u32_e32 v3, v91, v3
	v_max_u32_e32 v91, v92, v3
	v_min_u32_e32 v3, v92, v3
	v_max_u32_e32 v92, v93, v3
	v_min_u32_e32 v3, v93, v3
	v_max3_u32 v1, v1, v2, v3
	v_not_b32_e32 v2, v8
	v_or_b32_e32 v3, 0x80000000, v8
	v_cmp_gt_i32_e32 vcc, 0, v8
	s_nop 1
	v_cndmask_b32_e32 v2, v3, v2, vcc
	v_and_b32_e32 v2, 0xffffff80, v2
	v_add3_u32 v2, v0, v2, s69
	v_max_u32_e32 v3, v94, v2
	v_min_u32_e32 v2, v94, v2
	v_max_u32_e32 v8, v7, v2
; DI int crow(int i, int h) { return (i & 3) + 8 * (i >> 2) + 4 * h; }
; DI unsigned f2ord(float f) { unsigned u = __float_as_uint(f); return (u & 0x80000000u) ? ~u : (u | 0x80000000u); }
; #define INS32(T, X) { _Pragma("unroll") for (int jj = 0; jj < 16; ++jj) { unsigned t_ = max(T[jj], X); X = min(T[jj], X); T[jj] = t_; } }
; __device__ __forceinline__ void route_task(const Params& p, int layer, const u16* qg, int rb, int hd, int r, int h) {
;     ...
; #pragma unroll
;       for (int e = 0; e < 16; ++e) {
;         unsigned key = (f2ord(acc[e]) & ~127u) | (unsigned)(127 - (n * 32 + crow(e, h)));
;         INS32(tp, key);
;       }
;     }
	v_min_u32_e32 v2, v7, v2
	v_max_u32_e32 v7, v6, v2
	v_min_u32_e32 v2, v6, v2
	v_max_u32_e32 v6, v5, v2
	v_min_u32_e32 v2, v5, v2
	v_max_u32_e32 v5, v4, v2
	v_min_u32_e32 v2, v4, v2
	v_max_u32_e32 v4, v83, v2
	v_min_u32_e32 v2, v83, v2
	v_max_u32_e32 v83, v86, v2
	v_min_u32_e32 v2, v86, v2
	v_max_u32_e32 v86, v95, v2
	v_min_u32_e32 v2, v95, v2
	v_max_u32_e32 v93, v96, v2
	v_min_u32_e32 v2, v96, v2
	v_max_u32_e32 v94, v87, v2
	v_min_u32_e32 v2, v87, v2
	v_max_u32_e32 v87, v88, v2
	v_min_u32_e32 v2, v88, v2
	v_max_u32_e32 v88, v89, v2
	v_min_u32_e32 v2, v89, v2
	v_max_u32_e32 v89, v90, v2
	v_min_u32_e32 v2, v90, v2
	v_max_u32_e32 v90, v91, v2
	v_min_u32_e32 v2, v91, v2
	v_max_u32_e32 v91, v92, v2
	v_min_u32_e32 v2, v92, v2
	v_not_b32_e32 v92, v9
	v_or_b32_e32 v95, 0x80000000, v9
	v_cmp_gt_i32_e32 vcc, 0, v9
	s_nop 1
	v_cndmask_b32_e32 v9, v95, v92, vcc
	v_and_b32_e32 v9, 0xffffff80, v9
	v_add3_u32 v9, v0, v9, s70
	v_max_u32_e32 v92, v3, v9
	v_min_u32_e32 v3, v3, v9
	v_max_u32_e32 v9, v8, v3
	v_min_u32_e32 v3, v8, v3
	v_max_u32_e32 v8, v7, v3
	v_min_u32_e32 v3, v7, v3
	v_max_u32_e32 v7, v6, v3
	v_min_u32_e32 v3, v6, v3
	v_max_u32_e32 v6, v5, v3
	v_min_u32_e32 v3, v5, v3
	v_max_u32_e32 v5, v4, v3
	v_min_u32_e32 v3, v4, v3
	v_max_u32_e32 v4, v83, v3
	v_min_u32_e32 v3, v83, v3
	v_max_u32_e32 v83, v86, v3
	v_min_u32_e32 v3, v86, v3
	v_max_u32_e32 v86, v93, v3
	v_min_u32_e32 v3, v93, v3
	v_max_u32_e32 v93, v94, v3
	v_min_u32_e32 v3, v94, v3
	v_max_u32_e32 v94, v87, v3
	v_min_u32_e32 v3, v87, v3
	v_max_u32_e32 v87, v88, v3
	v_min_u32_e32 v3, v88, v3
	v_max_u32_e32 v88, v89, v3
	v_min_u32_e32 v3, v89, v3
	v_max_u32_e32 v89, v90, v3
	v_min_u32_e32 v3, v90, v3
	v_max_u32_e32 v90, v91, v3
	v_min_u32_e32 v3, v91, v3
	v_max3_u32 v1, v1, v2, v3
	v_not_b32_e32 v2, v10
	v_or_b32_e32 v3, 0x80000000, v10
	v_cmp_gt_i32_e32 vcc, 0, v10
	s_nop 1
	v_cndmask_b32_e32 v2, v3, v2, vcc
	v_and_b32_e32 v2, 0xffffff80, v2
	v_add3_u32 v2, v0, v2, s71
	v_max_u32_e32 v3, v92, v2
	v_min_u32_e32 v2, v92, v2
	v_max_u32_e32 v10, v9, v2
	v_min_u32_e32 v2, v9, v2
	v_max_u32_e32 v9, v8, v2
	v_min_u32_e32 v2, v8, v2
	v_max_u32_e32 v8, v7, v2
	v_min_u32_e32 v2, v7, v2
	v_max_u32_e32 v7, v6, v2
	v_min_u32_e32 v2, v6, v2
	v_max_u32_e32 v6, v5, v2
	v_min_u32_e32 v2, v5, v2
	v_max_u32_e32 v5, v4, v2
	v_min_u32_e32 v2, v4, v2
	v_max_u32_e32 v4, v83, v2
	v_min_u32_e32 v2, v83, v2
	v_max_u32_e32 v83, v86, v2
	v_min_u32_e32 v2, v86, v2
	v_max_u32_e32 v86, v93, v2
	v_min_u32_e32 v2, v93, v2
	v_max_u32_e32 v91, v94, v2
	v_min_u32_e32 v2, v94, v2
	v_max_u32_e32 v92, v87, v2
	v_min_u32_e32 v2, v87, v2
	v_max_u32_e32 v87, v88, v2
	v_min_u32_e32 v2, v88, v2
	v_max_u32_e32 v88, v89, v2
	v_min_u32_e32 v2, v89, v2
	v_max_u32_e32 v89, v90, v2
	v_min_u32_e32 v2, v90, v2
	v_not_b32_e32 v90, v11
	v_or_b32_e32 v93, 0x80000000, v11
	v_cmp_gt_i32_e32 vcc, 0, v11
	s_nop 1
	v_cndmask_b32_e32 v11, v93, v90, vcc
	v_and_b32_e32 v11, 0xffffff80, v11
	v_add3_u32 v11, v0, v11, s72
	v_max_u32_e32 v90, v3, v11
	v_min_u32_e32 v3, v3, v11
	v_max_u32_e32 v11, v10, v3
	v_min_u32_e32 v3, v10, v3
	v_max_u32_e32 v10, v9, v3
	v_min_u32_e32 v3, v9, v3
	v_max_u32_e32 v9, v8, v3
	v_min_u32_e32 v3, v8, v3
	v_max_u32_e32 v8, v7, v3
	v_min_u32_e32 v3, v7, v3
	v_max_u32_e32 v7, v6, v3
	v_min_u32_e32 v3, v6, v3
	v_max_u32_e32 v6, v5, v3
	v_min_u32_e32 v3, v5, v3
	v_max_u32_e32 v5, v4, v3
	v_min_u32_e32 v3, v4, v3
	v_max_u32_e32 v4, v83, v3
	v_min_u32_e32 v3, v83, v3
	v_max_u32_e32 v83, v86, v3
	v_min_u32_e32 v3, v86, v3
	v_max_u32_e32 v86, v91, v3
	v_min_u32_e32 v3, v91, v3
	v_max_u32_e32 v91, v92, v3
	v_min_u32_e32 v3, v92, v3
	v_max_u32_e32 v92, v87, v3
	v_min_u32_e32 v3, v87, v3
	v_max_u32_e32 v87, v88, v3
	v_min_u32_e32 v3, v88, v3
	v_max_u32_e32 v88, v89, v3
	v_min_u32_e32 v3, v89, v3
	v_max3_u32 v1, v1, v2, v3
	v_not_b32_e32 v2, v12
	v_or_b32_e32 v3, 0x80000000, v12
	v_cmp_gt_i32_e32 vcc, 0, v12
	s_nop 1
	v_cndmask_b32_e32 v2, v3, v2, vcc
	v_and_b32_e32 v2, 0xffffff80, v2
	v_add3_u32 v2, v0, v2, s73
	v_max_u32_e32 v3, v90, v2
	v_min_u32_e32 v2, v90, v2
	v_max_u32_e32 v12, v11, v2
	v_min_u32_e32 v2, v11, v2
	v_max_u32_e32 v11, v10, v2
	v_min_u32_e32 v2, v10, v2
	v_max_u32_e32 v10, v9, v2
	v_min_u32_e32 v2, v9, v2
	v_max_u32_e32 v9, v8, v2
	v_min_u32_e32 v2, v8, v2
	v_max_u32_e32 v8, v7, v2
	v_min_u32_e32 v2, v7, v2
	v_max_u32_e32 v7, v6, v2
	v_min_u32_e32 v2, v6, v2
	v_max_u32_e32 v6, v5, v2
	v_min_u32_e32 v2, v5, v2
	v_max_u32_e32 v5, v4, v2
	v_min_u32_e32 v2, v4, v2
	v_max_u32_e32 v4, v83, v2
	v_min_u32_e32 v2, v83, v2
	v_max_u32_e32 v83, v86, v2
	v_min_u32_e32 v2, v86, v2
	v_max_u32_e32 v86, v91, v2
	v_min_u32_e32 v2, v91, v2
	v_max_u32_e32 v89, v92, v2
	v_min_u32_e32 v2, v92, v2
	v_max_u32_e32 v90, v87, v2
	v_min_u32_e32 v2, v87, v2
	v_max_u32_e32 v87, v88, v2
	v_min_u32_e32 v2, v88, v2
	v_not_b32_e32 v88, v13
	v_or_b32_e32 v91, 0x80000000, v13
	v_cmp_gt_i32_e32 vcc, 0, v13
	s_nop 1
	v_cndmask_b32_e32 v13, v91, v88, vcc
	v_and_b32_e32 v13, 0xffffff80, v13
	v_add3_u32 v13, v0, v13, s77
	v_max_u32_e32 v88, v3, v13
	v_min_u32_e32 v3, v3, v13
	v_max_u32_e32 v13, v12, v3
	v_min_u32_e32 v3, v12, v3
	v_max_u32_e32 v12, v11, v3
	v_min_u32_e32 v3, v11, v3
	v_max_u32_e32 v11, v10, v3
	v_min_u32_e32 v3, v10, v3
	v_max_u32_e32 v10, v9, v3
	v_min_u32_e32 v3, v9, v3
	v_max_u32_e32 v9, v8, v3
	v_min_u32_e32 v3, v8, v3
	v_max_u32_e32 v8, v7, v3
	v_min_u32_e32 v3, v7, v3
	v_max_u32_e32 v7, v6, v3
	v_min_u32_e32 v3, v6, v3
	v_max_u32_e32 v6, v5, v3
	v_min_u32_e32 v3, v5, v3
	v_max_u32_e32 v5, v4, v3
	v_min_u32_e32 v3, v4, v3
	v_max_u32_e32 v4, v83, v3
	v_min_u32_e32 v3, v83, v3
	v_max_u32_e32 v83, v86, v3
	v_min_u32_e32 v3, v86, v3
; DI int crow(int i, int h) { return (i & 3) + 8 * (i >> 2) + 4 * h; }
; DI unsigned f2ord(float f) { unsigned u = __float_as_uint(f); return (u & 0x80000000u) ? ~u : (u | 0x80000000u); }
; #define INS32(T, X) { _Pragma("unroll") for (int jj = 0; jj < 16; ++jj) { unsigned t_ = max(T[jj], X); X = min(T[jj], X); T[jj] = t_; } }
; __device__ __forceinline__ void route_task(const Params& p, int layer, const u16* qg, int rb, int hd, int r, int h) {
;     ...
; #pragma unroll
;       for (int e = 0; e < 16; ++e) {
;         unsigned key = (f2ord(acc[e]) & ~127u) | (unsigned)(127 - (n * 32 + crow(e, h)));
;         INS32(tp, key);
;       }
;     }
;     unsigned ot[16];
; #pragma unroll
;     for (int jj = 0; jj < 16; ++jj) ot[jj] = (unsigned)__shfl_xor((int)tp[jj], 32);
; #pragma unroll
;     for (int jj = 0; jj < 16; ++jj) { unsigned key = ot[jj]; INS32(tp, key); }
; #pragma unroll
;     for (int jj = 0; jj < 16; ++jj) top[ph][jj] = tp[jj];
;   }
;   if (h == 0) {
	v_max_u32_e32 v86, v89, v3
	v_min_u32_e32 v3, v89, v3
	v_max_u32_e32 v89, v90, v3
	v_min_u32_e32 v3, v90, v3
	v_max_u32_e32 v90, v87, v3
	v_min_u32_e32 v3, v87, v3
	v_max3_u32 v1, v1, v2, v3
	v_not_b32_e32 v2, v14
	v_or_b32_e32 v3, 0x80000000, v14
	v_cmp_gt_i32_e32 vcc, 0, v14
	v_or_b32_e32 v87, 0x80000000, v15
	s_nop 0
	v_cndmask_b32_e32 v2, v3, v2, vcc
	v_and_b32_e32 v2, 0xffffff80, v2
	v_add3_u32 v2, v0, v2, s78
	v_max_u32_e32 v3, v88, v2
	v_min_u32_e32 v2, v88, v2
	v_max_u32_e32 v14, v13, v2
	v_min_u32_e32 v2, v13, v2
	v_max_u32_e32 v13, v12, v2
	v_min_u32_e32 v2, v12, v2
	v_max_u32_e32 v12, v11, v2
	v_min_u32_e32 v2, v11, v2
	v_max_u32_e32 v11, v10, v2
	v_min_u32_e32 v2, v10, v2
	v_max_u32_e32 v10, v9, v2
	v_min_u32_e32 v2, v9, v2
	v_max_u32_e32 v9, v8, v2
	v_min_u32_e32 v2, v8, v2
	v_max_u32_e32 v8, v7, v2
	v_min_u32_e32 v2, v7, v2
	v_max_u32_e32 v7, v6, v2
	v_min_u32_e32 v2, v6, v2
	v_max_u32_e32 v6, v5, v2
	v_min_u32_e32 v2, v5, v2
	v_max_u32_e32 v5, v4, v2
	v_min_u32_e32 v2, v4, v2
	v_max_u32_e32 v4, v83, v2
	v_min_u32_e32 v2, v83, v2
	v_max_u32_e32 v83, v86, v2
	v_min_u32_e32 v2, v86, v2
	v_not_b32_e32 v86, v15
	v_cmp_gt_i32_e32 vcc, 0, v15
	v_max_u32_e32 v100, v89, v2
	v_min_u32_e32 v2, v89, v2
	v_cndmask_b32_e32 v15, v87, v86, vcc
	v_and_b32_e32 v15, 0xffffff80, v15
	v_add3_u32 v0, v0, v15, s79
	v_max_u32_e32 v86, v3, v0
	v_min_u32_e32 v0, v3, v0
	v_max_u32_e32 v87, v14, v0
	v_min_u32_e32 v0, v14, v0
	v_max_u32_e32 v88, v13, v0
	v_min_u32_e32 v0, v13, v0
	v_max_u32_e32 v89, v12, v0
	v_min_u32_e32 v0, v12, v0
	v_max_u32_e32 v101, v90, v2
	v_min_u32_e32 v2, v90, v2
	v_max_u32_e32 v90, v11, v0
	v_min_u32_e32 v0, v11, v0
	v_max_u32_e32 v91, v10, v0
	v_min_u32_e32 v0, v10, v0
	v_max_u32_e32 v92, v9, v0
	v_min_u32_e32 v0, v9, v0
	v_max_u32_e32 v93, v8, v0
	v_min_u32_e32 v0, v8, v0
	v_max_u32_e32 v94, v7, v0
	v_min_u32_e32 v0, v7, v0
	v_max_u32_e32 v95, v6, v0
	v_min_u32_e32 v0, v6, v0
	v_max_u32_e32 v96, v5, v0
	v_min_u32_e32 v0, v5, v0
	v_max_u32_e32 v97, v4, v0
	v_min_u32_e32 v0, v4, v0
	v_max_u32_e32 v98, v83, v0
	v_min_u32_e32 v0, v83, v0
	v_max_u32_e32 v99, v100, v0
	v_min_u32_e32 v0, v100, v0
	v_max_u32_e32 v100, v101, v0
	v_min_u32_e32 v0, v101, v0
	v_max3_u32 v83, v1, v2, v0
	s_cbranch_scc1 .LBB0_1875
	ds_bpermute_b32 v17, v85, v86
	ds_bpermute_b32 v16, v85, v87
	ds_bpermute_b32 v13, v85, v88
	ds_bpermute_b32 v12, v85, v89
	ds_bpermute_b32 v11, v85, v90
	ds_bpermute_b32 v10, v85, v91
	ds_bpermute_b32 v9, v85, v92
	ds_bpermute_b32 v8, v85, v93
	ds_bpermute_b32 v7, v85, v94
	ds_bpermute_b32 v6, v85, v95
	ds_bpermute_b32 v5, v85, v96
	ds_bpermute_b32 v4, v85, v97
	ds_bpermute_b32 v3, v85, v98
	ds_bpermute_b32 v2, v85, v99
	ds_bpermute_b32 v1, v85, v100
	ds_bpermute_b32 v0, v85, v83
	v_cmp_eq_u32_e32 vcc, 0, v139
	s_and_saveexec_b64 s[18:19], vcc
	s_cbranch_execz .LBB0_1867
	v_max_u32_e32 v14, v69, v84
	v_min_u32_e32 v15, v69, v84
	v_max_u32_e32 v18, v68, v15
	v_min_u32_e32 v15, v68, v15
	v_max_u32_e32 v31, v14, v82
	v_min_u32_e32 v14, v14, v82
	v_max_u32_e32 v19, v67, v15
	v_min_u32_e32 v15, v67, v15
	v_max_u32_e32 v32, v18, v14
	v_min_u32_e32 v14, v18, v14
	v_max_u32_e32 v20, v66, v15
	v_min_u32_e32 v15, v66, v15
	v_max_u32_e32 v18, v19, v14
	v_min_u32_e32 v14, v19, v14
	v_max_u32_e32 v21, v65, v15
	v_min_u32_e32 v15, v65, v15
	v_max_u32_e32 v19, v20, v14
	v_min_u32_e32 v14, v20, v14
	v_max_u32_e32 v22, v64, v15
	v_min_u32_e32 v15, v64, v15
	v_max_u32_e32 v20, v21, v14
	v_min_u32_e32 v14, v21, v14
	v_max_u32_e32 v23, v63, v15
	v_min_u32_e32 v15, v63, v15
	v_max_u32_e32 v21, v22, v14
	v_min_u32_e32 v14, v22, v14
	v_max_u32_e32 v24, v62, v15
	v_min_u32_e32 v15, v62, v15
	v_max_u32_e32 v22, v23, v14
	v_min_u32_e32 v14, v23, v14
	v_max_u32_e32 v25, v61, v15
	v_min_u32_e32 v15, v61, v15
	v_max_u32_e32 v23, v24, v14
	v_min_u32_e32 v14, v24, v14
	v_max_u32_e32 v26, v60, v15
	v_min_u32_e32 v15, v60, v15
	v_max_u32_e32 v24, v25, v14
	v_min_u32_e32 v14, v25, v14
	v_max_u32_e32 v27, v59, v15
	v_min_u32_e32 v15, v59, v15
	v_max_u32_e32 v25, v26, v14
	v_min_u32_e32 v14, v26, v14
	v_max_u32_e32 v28, v58, v15
	v_min_u32_e32 v15, v58, v15
	v_max_u32_e32 v26, v27, v14
	v_min_u32_e32 v14, v27, v14
	v_max_u32_e32 v29, v57, v15
	v_min_u32_e32 v15, v57, v15
	v_max_u32_e32 v27, v28, v14
	v_min_u32_e32 v14, v28, v14
	v_max_u32_e32 v30, v56, v15
	v_max_u32_e32 v28, v29, v14
	v_min_u32_e32 v14, v29, v14
	v_max_u32_e32 v29, v30, v14
	v_min_u32_e32 v30, v30, v14
	s_waitcnt lgkmcnt(14)
; #define INS32(T, X) { _Pragma("unroll") for (int jj = 0; jj < 16; ++jj) { unsigned t_ = max(T[jj], X); X = min(T[jj], X); T[jj] = t_; } }
; __device__ __forceinline__ void route_task(const Params& p, int layer, const u16* qg, int rb, int hd, int r, int h) {
;     ...
;     for (int jj = 0; jj < 16; ++jj) { unsigned key = ot[jj]; INS32(tp, key); }
	v_max_u32_e32 v14, v31, v81
	v_min_u32_e32 v31, v31, v81
	v_max_u32_e32 v33, v32, v31
	v_min_u32_e32 v31, v32, v31
	v_max_u32_e32 v32, v18, v31
	v_min_u32_e32 v18, v18, v31
	v_max_u32_e32 v31, v19, v18
	v_min_u32_e32 v18, v19, v18
	v_max_u32_e32 v19, v20, v18
	v_min_u32_e32 v18, v20, v18
	v_max_u32_e32 v20, v21, v18
	v_min_u32_e32 v18, v21, v18
	v_max_u32_e32 v21, v22, v18
	v_min_u32_e32 v18, v22, v18
	v_max_u32_e32 v22, v23, v18
	v_min_u32_e32 v18, v23, v18
	v_max_u32_e32 v23, v24, v18
	v_min_u32_e32 v18, v24, v18
	v_max_u32_e32 v24, v25, v18
	v_min_u32_e32 v18, v25, v18
	v_max_u32_e32 v25, v26, v18
	v_min_u32_e32 v18, v26, v18
	v_max_u32_e32 v26, v27, v18
	v_min_u32_e32 v18, v27, v18
	v_max_u32_e32 v27, v28, v18
	v_min_u32_e32 v18, v28, v18
	v_max_u32_e32 v28, v29, v18
	v_min_u32_e32 v18, v29, v18
	v_max_u32_e32 v29, v14, v80
	v_min_u32_e32 v14, v14, v80
	v_max_u32_e32 v34, v33, v14
	v_min_u32_e32 v14, v33, v14
	v_max_u32_e32 v33, v32, v14
	v_min_u32_e32 v14, v32, v14
	v_max_u32_e32 v32, v31, v14
	v_min_u32_e32 v14, v31, v14
	v_max_u32_e32 v31, v19, v14
	v_min_u32_e32 v14, v19, v14
	v_max_u32_e32 v19, v20, v14
	v_min_u32_e32 v14, v20, v14
	v_max_u32_e32 v20, v21, v14
	v_min_u32_e32 v14, v21, v14
	v_max_u32_e32 v21, v22, v14
	v_min_u32_e32 v14, v22, v14
	v_max_u32_e32 v22, v23, v14
	v_min_u32_e32 v14, v23, v14
	v_max_u32_e32 v23, v24, v14
	v_min_u32_e32 v14, v24, v14
	v_max_u32_e32 v24, v25, v14
	v_min_u32_e32 v14, v25, v14
	v_max_u32_e32 v25, v26, v14
	v_min_u32_e32 v14, v26, v14
	v_max_u32_e32 v26, v27, v14
	v_min_u32_e32 v14, v27, v14
	v_max_u32_e32 v27, v28, v14
	v_min_u32_e32 v28, v28, v14
	v_max_u32_e32 v14, v29, v79
	v_min_u32_e32 v29, v29, v79
	v_max_u32_e32 v35, v34, v29
	v_min_u32_e32 v29, v34, v29
	v_max_u32_e32 v34, v33, v29
	v_min_u32_e32 v29, v33, v29
	v_max_u32_e32 v33, v32, v29
	v_min_u32_e32 v29, v32, v29
	v_max_u32_e32 v32, v31, v29
	v_min_u32_e32 v29, v31, v29
	v_max_u32_e32 v31, v19, v29
	v_min_u32_e32 v19, v19, v29
	v_max_u32_e32 v29, v20, v19
	v_min_u32_e32 v19, v20, v19
	v_max_u32_e32 v20, v21, v19
	v_min_u32_e32 v19, v21, v19
	v_max_u32_e32 v21, v22, v19
	v_min_u32_e32 v19, v22, v19
	v_max_u32_e32 v22, v23, v19
	v_min_u32_e32 v19, v23, v19
	v_max_u32_e32 v23, v24, v19
	v_min_u32_e32 v19, v24, v19
	v_max_u32_e32 v24, v25, v19
	v_min_u32_e32 v19, v25, v19
	v_max_u32_e32 v25, v26, v19
	v_min_u32_e32 v19, v26, v19
	v_max_u32_e32 v26, v27, v19
	v_min_u32_e32 v19, v27, v19
	v_max_u32_e32 v27, v14, v78
	v_min_u32_e32 v14, v14, v78
	v_max_u32_e32 v36, v35, v14
	v_min_u32_e32 v14, v35, v14
	v_max_u32_e32 v35, v34, v14
	v_min_u32_e32 v14, v34, v14
	v_max_u32_e32 v34, v33, v14
	v_min_u32_e32 v14, v33, v14
	v_max_u32_e32 v33, v32, v14
	v_min_u32_e32 v14, v32, v14
	v_max_u32_e32 v32, v31, v14
	v_min_u32_e32 v14, v31, v14
	v_max_u32_e32 v31, v29, v14
	v_min_u32_e32 v14, v29, v14
	v_max_u32_e32 v29, v20, v14
	v_min_u32_e32 v14, v20, v14
	v_max_u32_e32 v20, v21, v14
	v_min_u32_e32 v14, v21, v14
	v_max_u32_e32 v21, v22, v14
	v_min_u32_e32 v14, v22, v14
	v_max_u32_e32 v22, v23, v14
	v_min_u32_e32 v14, v23, v14
	v_max_u32_e32 v23, v24, v14
	v_min_u32_e32 v14, v24, v14
	v_max_u32_e32 v24, v25, v14
	v_min_u32_e32 v14, v25, v14
	v_max_u32_e32 v25, v26, v14
	v_min_u32_e32 v26, v26, v14
	v_max_u32_e32 v14, v27, v77
	v_min_u32_e32 v27, v27, v77
	v_max_u32_e32 v37, v36, v27
	v_min_u32_e32 v27, v36, v27
	v_max_u32_e32 v36, v35, v27
	v_min_u32_e32 v27, v35, v27
	v_max_u32_e32 v35, v34, v27
	v_min_u32_e32 v27, v34, v27
	v_max_u32_e32 v34, v33, v27
	v_min_u32_e32 v27, v33, v27
	v_max_u32_e32 v33, v32, v27
	v_min_u32_e32 v27, v32, v27
	v_max_u32_e32 v32, v31, v27
	v_min_u32_e32 v27, v31, v27
	v_max_u32_e32 v31, v29, v27
	v_min_u32_e32 v27, v29, v27
	v_max_u32_e32 v29, v20, v27
	v_min_u32_e32 v20, v20, v27
	v_max_u32_e32 v27, v21, v20
	v_min_u32_e32 v20, v21, v20
	v_max_u32_e32 v21, v22, v20
	v_min_u32_e32 v20, v22, v20
	v_max_u32_e32 v22, v23, v20
	v_min_u32_e32 v20, v23, v20
	v_max_u32_e32 v23, v24, v20
	v_min_u32_e32 v20, v24, v20
	v_max_u32_e32 v24, v25, v20
	v_min_u32_e32 v20, v25, v20
	v_max_u32_e32 v25, v14, v76
	v_min_u32_e32 v14, v14, v76
	v_max_u32_e32 v38, v37, v14
	v_min_u32_e32 v14, v37, v14
	v_max_u32_e32 v37, v36, v14
	v_min_u32_e32 v14, v36, v14
	v_max_u32_e32 v36, v35, v14
	v_min_u32_e32 v14, v35, v14
	v_max_u32_e32 v35, v34, v14
	v_min_u32_e32 v14, v34, v14
	v_max_u32_e32 v34, v33, v14
	v_min_u32_e32 v14, v33, v14
	v_max_u32_e32 v33, v32, v14
	v_min_u32_e32 v14, v32, v14
	v_max_u32_e32 v32, v31, v14
	v_min_u32_e32 v14, v31, v14
	v_max_u32_e32 v31, v29, v14
	v_min_u32_e32 v14, v29, v14
	v_max_u32_e32 v29, v27, v14
	v_min_u32_e32 v14, v27, v14
	v_max_u32_e32 v27, v21, v14
	v_min_u32_e32 v14, v21, v14
	v_max_u32_e32 v21, v22, v14
	v_min_u32_e32 v14, v22, v14
	v_max_u32_e32 v22, v23, v14
	v_min_u32_e32 v14, v23, v14
	v_max_u32_e32 v23, v24, v14
	v_min_u32_e32 v24, v24, v14
	v_max_u32_e32 v14, v25, v75
	v_min_u32_e32 v25, v25, v75
	v_max_u32_e32 v39, v38, v25
	v_min_u32_e32 v25, v38, v25
	v_max_u32_e32 v38, v37, v25
	v_min_u32_e32 v25, v37, v25
	v_max_u32_e32 v37, v36, v25
	v_min_u32_e32 v25, v36, v25
	v_max_u32_e32 v36, v35, v25
	v_min_u32_e32 v25, v35, v25
	v_max_u32_e32 v35, v34, v25
	v_min_u32_e32 v25, v34, v25
	v_max_u32_e32 v34, v33, v25
	v_min_u32_e32 v25, v33, v25
	v_max_u32_e32 v33, v32, v25
	v_min_u32_e32 v25, v32, v25
	v_max_u32_e32 v32, v31, v25
	v_min_u32_e32 v25, v31, v25
	v_max_u32_e32 v31, v29, v25
	v_min_u32_e32 v25, v29, v25
	v_max_u32_e32 v29, v27, v25
	v_min_u32_e32 v25, v27, v25
	v_max_u32_e32 v27, v21, v25
	v_min_u32_e32 v21, v21, v25
	v_max_u32_e32 v25, v22, v21
	v_min_u32_e32 v21, v22, v21
; #define INS32(T, X) { _Pragma("unroll") for (int jj = 0; jj < 16; ++jj) { unsigned t_ = max(T[jj], X); X = min(T[jj], X); T[jj] = t_; } }
; __device__ __forceinline__ void route_task(const Params& p, int layer, const u16* qg, int rb, int hd, int r, int h) {
;     ...
;     for (int jj = 0; jj < 16; ++jj) { unsigned key = ot[jj]; INS32(tp, key); }
	v_max_u32_e32 v22, v23, v21
	v_min_u32_e32 v21, v23, v21
	v_max_u32_e32 v23, v14, v74
	v_min_u32_e32 v14, v14, v74
	v_max_u32_e32 v40, v39, v14
	v_min_u32_e32 v14, v39, v14
	v_max_u32_e32 v39, v38, v14
	v_min_u32_e32 v14, v38, v14
	v_max_u32_e32 v38, v37, v14
	v_min_u32_e32 v14, v37, v14
	v_max_u32_e32 v37, v36, v14
	v_min_u32_e32 v14, v36, v14
	v_max_u32_e32 v36, v35, v14
	v_min_u32_e32 v14, v35, v14
	v_max_u32_e32 v35, v34, v14
	v_min_u32_e32 v14, v34, v14
	v_max_u32_e32 v34, v33, v14
	v_min_u32_e32 v14, v33, v14
	v_max_u32_e32 v33, v32, v14
	v_min_u32_e32 v14, v32, v14
	v_max_u32_e32 v32, v31, v14
	v_min_u32_e32 v14, v31, v14
	v_max_u32_e32 v31, v29, v14
	v_min_u32_e32 v14, v29, v14
	v_max_u32_e32 v29, v27, v14
	v_min_u32_e32 v14, v27, v14
	v_max_u32_e32 v27, v25, v14
	v_min_u32_e32 v14, v25, v14
	v_max_u32_e32 v25, v22, v14
	v_min_u32_e32 v22, v22, v14
	v_max_u32_e32 v14, v23, v73
	v_min_u32_e32 v23, v23, v73
	v_max_u32_e32 v41, v40, v23
	v_min_u32_e32 v23, v40, v23
	v_max_u32_e32 v40, v39, v23
	v_min_u32_e32 v23, v39, v23
	v_max_u32_e32 v39, v38, v23
	v_min_u32_e32 v23, v38, v23
	v_max_u32_e32 v38, v37, v23
	v_min_u32_e32 v23, v37, v23
	v_max_u32_e32 v37, v36, v23
	v_min_u32_e32 v23, v36, v23
	v_max_u32_e32 v36, v35, v23
	v_min_u32_e32 v23, v35, v23
	v_max_u32_e32 v35, v34, v23
	v_min_u32_e32 v23, v34, v23
	v_max_u32_e32 v34, v33, v23
	v_min_u32_e32 v23, v33, v23
	v_max_u32_e32 v33, v32, v23
	v_min_u32_e32 v23, v32, v23
	v_max_u32_e32 v32, v31, v23
	v_min_u32_e32 v23, v31, v23
	v_max_u32_e32 v31, v29, v23
	v_min_u32_e32 v23, v29, v23
	v_max_u32_e32 v29, v27, v23
	v_min_u32_e32 v23, v27, v23
	v_max_u32_e32 v27, v25, v23
	v_min_u32_e32 v23, v25, v23
	v_max_u32_e32 v25, v14, v72
	v_min_u32_e32 v14, v14, v72
	v_max_u32_e32 v42, v41, v14
	v_min_u32_e32 v14, v41, v14
	v_max_u32_e32 v41, v40, v14
	v_min_u32_e32 v14, v40, v14
	v_max_u32_e32 v40, v39, v14
	v_min_u32_e32 v14, v39, v14
	v_max_u32_e32 v39, v38, v14
	v_min_u32_e32 v14, v38, v14
	v_max_u32_e32 v38, v37, v14
	v_min_u32_e32 v14, v37, v14
	v_max_u32_e32 v37, v36, v14
	v_min_u32_e32 v14, v36, v14
	v_max_u32_e32 v36, v35, v14
	v_min_u32_e32 v14, v35, v14
	v_max_u32_e32 v35, v34, v14
	v_min_u32_e32 v14, v34, v14
	v_max_u32_e32 v34, v33, v14
	v_min_u32_e32 v14, v33, v14
	v_max_u32_e32 v33, v32, v14
	v_min_u32_e32 v14, v32, v14
	v_max_u32_e32 v32, v31, v14
	v_min_u32_e32 v14, v31, v14
	v_max_u32_e32 v31, v29, v14
	v_min_u32_e32 v14, v29, v14
	v_max_u32_e32 v29, v27, v14
	v_min_u32_e32 v27, v27, v14
	v_max_u32_e32 v14, v25, v71
	v_min_u32_e32 v25, v25, v71
	v_max_u32_e32 v43, v42, v25
	v_min_u32_e32 v25, v42, v25
	v_max_u32_e32 v42, v41, v25
	v_min_u32_e32 v25, v41, v25
	v_max_u32_e32 v41, v40, v25
	v_min_u32_e32 v25, v40, v25
	v_max_u32_e32 v40, v39, v25
	v_min_u32_e32 v25, v39, v25
	v_max_u32_e32 v39, v38, v25
	v_min_u32_e32 v25, v38, v25
	v_max_u32_e32 v38, v37, v25
	v_min_u32_e32 v25, v37, v25
	v_max_u32_e32 v37, v36, v25
	v_min_u32_e32 v25, v36, v25
	v_max_u32_e32 v36, v35, v25
	v_min_u32_e32 v25, v35, v25
	v_max_u32_e32 v35, v34, v25
	v_min_u32_e32 v25, v34, v25
	v_max_u32_e32 v34, v33, v25
	v_min_u32_e32 v25, v33, v25
	v_max_u32_e32 v33, v32, v25
	v_min_u32_e32 v25, v32, v25
	v_max_u32_e32 v32, v31, v25
	v_min_u32_e32 v25, v31, v25
	v_max_u32_e32 v31, v29, v25
	v_min_u32_e32 v25, v29, v25
	v_max_u32_e32 v29, v14, v70
	v_min_u32_e32 v14, v14, v70
	v_max_u32_e32 v44, v43, v14
	v_min_u32_e32 v14, v43, v14
	v_max_u32_e32 v43, v42, v14
	v_min_u32_e32 v14, v42, v14
	v_max_u32_e32 v42, v41, v14
	v_min_u32_e32 v14, v41, v14
	v_max_u32_e32 v41, v40, v14
	v_min_u32_e32 v14, v40, v14
	v_max_u32_e32 v40, v39, v14
	v_min_u32_e32 v14, v39, v14
	v_max_u32_e32 v39, v38, v14
	v_min_u32_e32 v14, v38, v14
	v_max_u32_e32 v38, v37, v14
	v_min_u32_e32 v14, v37, v14
	v_max_u32_e32 v37, v36, v14
	v_min_u32_e32 v14, v36, v14
	v_max_u32_e32 v36, v35, v14
	v_min_u32_e32 v14, v35, v14
	v_max_u32_e32 v35, v34, v14
	v_min_u32_e32 v14, v34, v14
	v_max_u32_e32 v34, v33, v14
	v_min_u32_e32 v14, v33, v14
	v_min_u32_e32 v15, v56, v15
	v_max_u32_e32 v33, v32, v14
	v_min_u32_e32 v14, v32, v14
	v_max_u32_e32 v32, v31, v14
	v_min_u32_e32 v31, v31, v14
	v_max_u32_e32 v14, v29, v51
	v_min_u32_e32 v29, v29, v51
	v_max_u32_e32 v63, v55, v15
	v_max_u32_e32 v46, v44, v29
	v_min_u32_e32 v29, v44, v29
	v_min_u32_e32 v47, v14, v50
	v_max_u32_e32 v64, v63, v30
	v_max_u32_e32 v45, v43, v29
	v_min_u32_e32 v29, v43, v29
	v_min_u32_e32 v48, v46, v47
	v_max_u32_e32 v65, v64, v18
	v_max_u32_e32 v44, v42, v29
	v_min_u32_e32 v29, v42, v29
	v_min_u32_e32 v49, v45, v48
	v_max_u32_e32 v66, v65, v28
	v_max_u32_e32 v43, v41, v29
	v_min_u32_e32 v29, v41, v29
	v_min_u32_e32 v51, v44, v49
	v_max_u32_e32 v67, v66, v19
	v_max_u32_e32 v42, v40, v29
	v_min_u32_e32 v29, v40, v29
	v_min_u32_e32 v53, v43, v51
	v_max_u32_e32 v68, v67, v26
	v_max_u32_e32 v41, v39, v29
	v_min_u32_e32 v29, v39, v29
	v_min_u32_e32 v56, v42, v53
	v_max_u32_e32 v69, v68, v20
	v_max_u32_e32 v40, v38, v29
	v_min_u32_e32 v29, v38, v29
	v_min_u32_e32 v57, v41, v56
	v_max_u32_e32 v70, v69, v24
	v_max_u32_e32 v39, v37, v29
	v_min_u32_e32 v29, v37, v29
	v_min_u32_e32 v58, v40, v57
	v_max_u32_e32 v71, v70, v21
	v_min_u32_e32 v30, v63, v30
	v_min_u32_e32 v15, v55, v15
	v_max_u32_e32 v38, v36, v29
	v_min_u32_e32 v29, v36, v29
	v_min_u32_e32 v59, v39, v58
	v_max_u32_e32 v72, v71, v22
	v_min_u32_e32 v28, v65, v28
	v_min_u32_e32 v18, v64, v18
	v_max3_u32 v15, v54, v15, v30
	v_max_u32_e32 v37, v35, v29
	v_min_u32_e32 v29, v35, v29
	v_min_u32_e32 v60, v38, v59
	v_max_u32_e32 v73, v72, v23
	v_min_u32_e32 v26, v67, v26
	v_min_u32_e32 v19, v66, v19
	v_max3_u32 v15, v15, v18, v28
	v_max_u32_e32 v36, v34, v29
	v_min_u32_e32 v29, v34, v29
	v_min_u32_e32 v61, v37, v60
	v_max_u32_e32 v74, v73, v27
	v_min_u32_e32 v24, v69, v24
	v_min_u32_e32 v20, v68, v20
	v_max3_u32 v15, v15, v19, v26
	v_max_u32_e32 v35, v33, v29
	v_min_u32_e32 v29, v33, v29
	v_min_u32_e32 v62, v36, v61
	v_max_u32_e32 v75, v74, v25
	v_min_u32_e32 v22, v71, v22
	v_min_u32_e32 v21, v70, v21
	v_max3_u32 v15, v15, v20, v24
	v_min_u32_e32 v18, v86, v17
	v_max_u32_e32 v17, v86, v17
	v_min_u32_e32 v33, v32, v29
	v_min_u32_e32 v34, v35, v62
	v_max_u32_e32 v29, v32, v29
	v_max_u32_e32 v76, v75, v31
	v_min_u32_e32 v27, v73, v27
	v_min_u32_e32 v23, v72, v23
	v_max3_u32 v15, v15, v21, v22
	v_max_u32_e32 v45, v45, v48
	v_min_u32_e32 v19, v87, v18
	v_max_u32_e32 v18, v87, v18
	v_min_u32_e32 v48, v17, v16
	v_max_u32_e32 v16, v17, v16
	v_min_u32_e32 v32, v29, v34
	v_max_u32_e32 v77, v76, v33
	v_min_u32_e32 v31, v75, v31
	v_min_u32_e32 v25, v74, v25
	v_max3_u32 v15, v15, v23, v27
	v_max_u32_e32 v44, v44, v49
	v_min_u32_e32 v20, v88, v19
	v_max_u32_e32 v19, v88, v19
	v_min_u32_e32 v49, v18, v48
	v_max_u32_e32 v18, v18, v48
	s_waitcnt lgkmcnt(13)
; #define INS32(T, X) { _Pragma("unroll") for (int jj = 0; jj < 16; ++jj) { unsigned t_ = max(T[jj], X); X = min(T[jj], X); T[jj] = t_; } }
; __device__ __forceinline__ void route_task(const Params& p, int layer, const u16* qg, int rb, int hd, int r, int h) {
;     ...
;     for (int jj = 0; jj < 16; ++jj) { unsigned key = ot[jj]; INS32(tp, key); }
	v_min_u32_e32 v17, v16, v13
	v_max_u32_e32 v13, v16, v13
	v_min_u32_e32 v78, v77, v32
	v_min_u32_e32 v33, v76, v33
	v_max3_u32 v15, v15, v25, v31
	v_max_u32_e32 v43, v43, v51
	v_min_u32_e32 v21, v89, v20
	v_max_u32_e32 v20, v89, v20
	v_min_u32_e32 v51, v19, v49
	v_max_u32_e32 v19, v19, v49
	v_min_u32_e32 v48, v18, v17
	v_max_u32_e32 v17, v18, v17
	s_waitcnt lgkmcnt(12)
	v_min_u32_e32 v16, v13, v12
	v_max3_u32 v15, v15, v33, v78
	v_max_u32_e32 v33, v77, v32
	v_add_u32_e32 v32, s34, v52
	v_min_u32_e32 v22, v90, v21
	v_max_u32_e32 v21, v90, v21
	v_min_u32_e32 v52, v20, v51
	v_max_u32_e32 v20, v20, v51
	v_min_u32_e32 v49, v19, v48
	v_max_u32_e32 v19, v19, v48
	v_min_u32_e32 v18, v17, v16
	v_max_u32_e32 v42, v42, v53
	v_min_u32_e32 v23, v91, v22
	v_max_u32_e32 v22, v91, v22
	v_min_u32_e32 v53, v21, v52
	v_max_u32_e32 v21, v21, v52
	v_min_u32_e32 v51, v20, v49
	v_max_u32_e32 v20, v20, v49
	v_min_u32_e32 v48, v19, v18
	v_max_u32_e32 v12, v13, v12
	v_min_u32_e32 v24, v92, v23
	v_max_u32_e32 v23, v92, v23
	v_min_u32_e32 v54, v22, v53
	v_max_u32_e32 v22, v22, v53
	v_min_u32_e32 v52, v21, v51
	v_max_u32_e32 v21, v21, v51
	v_min_u32_e32 v49, v20, v48
	v_max_u32_e32 v16, v17, v16
	s_waitcnt lgkmcnt(11)
	v_min_u32_e32 v13, v12, v11
	v_max_u32_e32 v11, v12, v11
	v_min_u32_e32 v25, v93, v24
	v_max_u32_e32 v24, v93, v24
	v_min_u32_e32 v55, v23, v54
	v_max_u32_e32 v23, v23, v54
	v_min_u32_e32 v53, v22, v52
	v_max_u32_e32 v22, v22, v52
	v_min_u32_e32 v51, v21, v49
	v_min_u32_e32 v17, v16, v13
	v_max_u32_e32 v13, v16, v13
	s_waitcnt lgkmcnt(10)
	v_min_u32_e32 v12, v11, v10
	v_max_u32_e32 v10, v11, v10
	v_max_u32_e32 v41, v41, v56
	v_min_u32_e32 v26, v94, v25
	v_max_u32_e32 v25, v94, v25
	v_min_u32_e32 v56, v24, v55
	v_max_u32_e32 v24, v24, v55
	v_min_u32_e32 v54, v23, v53
	v_max_u32_e32 v23, v23, v53
	v_min_u32_e32 v52, v22, v51
	v_max_u32_e32 v18, v19, v18
	v_min_u32_e32 v16, v13, v12
	v_max_u32_e32 v12, v13, v12
	s_waitcnt lgkmcnt(9)
	v_min_u32_e32 v11, v10, v9
	v_max_u32_e32 v9, v10, v9
	v_max_u32_e32 v40, v40, v57
	v_min_u32_e32 v27, v95, v26
	v_max_u32_e32 v26, v95, v26
	v_min_u32_e32 v57, v25, v56
	v_max_u32_e32 v25, v25, v56
	v_min_u32_e32 v55, v24, v54
	v_max_u32_e32 v24, v24, v54
	v_min_u32_e32 v53, v23, v52
	v_max_u32_e32 v20, v20, v48
	v_min_u32_e32 v19, v18, v17
	v_max_u32_e32 v17, v18, v17
	v_min_u32_e32 v13, v12, v11
	v_max_u32_e32 v11, v12, v11
	s_waitcnt lgkmcnt(8)
	v_min_u32_e32 v10, v9, v8
	v_max_u32_e32 v8, v9, v8
	v_max_u32_e32 v39, v39, v58
	v_min_u32_e32 v28, v96, v27
	v_max_u32_e32 v27, v96, v27
	v_min_u32_e32 v58, v26, v57
	v_max_u32_e32 v26, v26, v57
	v_min_u32_e32 v56, v25, v55
	v_max_u32_e32 v25, v25, v55
	v_min_u32_e32 v54, v24, v53
	v_max_u32_e32 v21, v21, v49
	v_min_u32_e32 v48, v20, v19
	v_max_u32_e32 v19, v20, v19
	v_min_u32_e32 v18, v17, v16
	v_min_u32_e32 v12, v11, v10
	v_max_u32_e32 v10, v11, v10
	s_waitcnt lgkmcnt(7)
	v_min_u32_e32 v9, v8, v7
	v_max_u32_e32 v7, v8, v7
	v_max_u32_e32 v34, v29, v34
	v_max_u32_e32 v38, v38, v59
	v_min_u32_e32 v29, v97, v28
	v_max_u32_e32 v28, v97, v28
	v_min_u32_e32 v59, v27, v58
	v_max_u32_e32 v27, v27, v58
	v_min_u32_e32 v57, v26, v56
	v_max_u32_e32 v26, v26, v56
	v_min_u32_e32 v55, v25, v54
	v_max_u32_e32 v22, v22, v51
	v_min_u32_e32 v49, v21, v48
	v_max_u32_e32 v21, v21, v48
	v_min_u32_e32 v20, v19, v18
	v_min_u32_e32 v11, v10, v9
	v_max_u32_e32 v9, v10, v9
	s_waitcnt lgkmcnt(6)
	v_min_u32_e32 v8, v7, v6
	v_max_u32_e32 v6, v7, v6
	v_max_u32_e32 v37, v37, v60
	v_min_u32_e32 v30, v98, v29
	v_max_u32_e32 v29, v98, v29
	v_min_u32_e32 v60, v28, v59
	v_max_u32_e32 v28, v28, v59
	v_min_u32_e32 v58, v27, v57
	v_max_u32_e32 v27, v27, v57
	v_min_u32_e32 v56, v26, v55
	v_max_u32_e32 v23, v23, v52
	v_min_u32_e32 v51, v22, v49
	v_max_u32_e32 v22, v22, v49
	v_min_u32_e32 v48, v21, v20
	v_max_u32_e32 v16, v17, v16
	v_min_u32_e32 v10, v9, v8
	v_max_u32_e32 v8, v9, v8
	s_waitcnt lgkmcnt(5)
	v_min_u32_e32 v7, v6, v5
	v_max_u32_e32 v5, v6, v5
	v_max_u32_e32 v36, v36, v61
	v_min_u32_e32 v31, v99, v30
	v_max_u32_e32 v30, v99, v30
	v_min_u32_e32 v61, v29, v60
	v_max_u32_e32 v29, v29, v60
	v_min_u32_e32 v59, v28, v58
	v_max_u32_e32 v28, v28, v58
	v_min_u32_e32 v57, v27, v56
	v_max_u32_e32 v24, v24, v53
	v_min_u32_e32 v52, v23, v51
	v_max_u32_e32 v23, v23, v51
	v_min_u32_e32 v49, v22, v48
	v_max_u32_e32 v18, v19, v18
	v_min_u32_e32 v17, v16, v13
	v_max_u32_e32 v13, v16, v13
	v_min_u32_e32 v9, v8, v7
	v_max_u32_e32 v7, v8, v7
	s_waitcnt lgkmcnt(4)
	v_min_u32_e32 v6, v5, v4
	v_max_u32_e32 v4, v5, v4
	v_max_u32_e32 v35, v35, v62
	v_max_u32_e32 v46, v46, v47
	v_min_u32_e32 v47, v100, v31
	v_max_u32_e32 v31, v100, v31
	v_min_u32_e32 v62, v30, v61
	v_max_u32_e32 v30, v30, v61
	v_min_u32_e32 v60, v29, v59
	v_max_u32_e32 v29, v29, v59
	v_min_u32_e32 v58, v28, v57
	v_max_u32_e32 v25, v25, v54
	v_min_u32_e32 v53, v24, v52
	v_max_u32_e32 v24, v24, v52
	v_min_u32_e32 v51, v23, v49
	v_min_u32_e32 v19, v18, v17
	v_max_u32_e32 v17, v18, v17
	v_min_u32_e32 v16, v13, v12
	v_max_u32_e32 v12, v13, v12
	v_min_u32_e32 v8, v7, v6
	v_max_u32_e32 v6, v7, v6
	s_waitcnt lgkmcnt(3)
	v_min_u32_e32 v5, v4, v3
	v_max_u32_e32 v3, v4, v3
	v_min_u32_e32 v63, v31, v62
	v_max_u32_e32 v31, v31, v62
	v_min_u32_e32 v61, v30, v60
	v_max_u32_e32 v30, v30, v60
	v_min_u32_e32 v59, v29, v58
	v_max_u32_e32 v26, v26, v55
	v_min_u32_e32 v54, v25, v53
	v_max_u32_e32 v25, v25, v53
	v_min_u32_e32 v52, v24, v51
	v_min_u32_e32 v18, v17, v16
	v_max_u32_e32 v16, v17, v16
	v_min_u32_e32 v13, v12, v11
	v_max_u32_e32 v11, v12, v11
	v_min_u32_e32 v7, v6, v5
	v_max_u32_e32 v5, v6, v5
	s_waitcnt lgkmcnt(2)
; DI unsigned f2ord(float f) { unsigned u = __float_as_uint(f); return (u & 0x80000000u) ? ~u : (u | 0x80000000u); }
; DI float ord2f(unsigned u) { return __uint_as_float((u & 0x80000000u) ? (u & 0x7fffffffu) : ~u); }
; #define INS32(T, X) { _Pragma("unroll") for (int jj = 0; jj < 16; ++jj) { unsigned t_ = max(T[jj], X); X = min(T[jj], X); T[jj] = t_; } }
; __device__ __forceinline__ void route_task(const Params& p, int layer, const u16* qg, int rb, int hd, int r, int h) {
;     ...
;     for (int jj = 0; jj < 16; ++jj) { unsigned key = ot[jj]; INS32(tp, key); }
;     ...
; #pragma unroll
;     for (int a = 0; a < 16; ++a) {
;       const float va = ord2f(top[0][a] & ~127u);
; #pragma unroll
;       for (int b = 0; b < 16; ++b) {
;         if ((a + 1) * (b + 1) <= 16) {
;           const float vb = ord2f(top[1][b] & ~127u);
;           unsigned key = (f2ord(va + vb) & ~255u) | (unsigned)(255 - (a * 16 + b));
;           INS32(ct, key);
;         }
;       }
;     }
	v_min_u32_e32 v4, v3, v2
	v_max_u32_e32 v2, v3, v2
	v_min_u32_e32 v62, v31, v61
	v_max_u32_e32 v31, v31, v61
	v_min_u32_e32 v60, v30, v59
	v_max_u32_e32 v27, v27, v56
	v_min_u32_e32 v55, v26, v54
	v_max_u32_e32 v26, v26, v54
	v_min_u32_e32 v53, v25, v52
	v_min_u32_e32 v17, v16, v13
	v_max_u32_e32 v13, v16, v13
	v_min_u32_e32 v12, v11, v10
	v_max_u32_e32 v10, v11, v10
	v_min_u32_e32 v6, v5, v4
	v_max_u32_e32 v4, v5, v4
	s_waitcnt lgkmcnt(1)
	v_min_u32_e32 v3, v2, v1
	v_max_u32_e32 v1, v2, v1
	v_max3_u32 v47, v83, v47, v63
	v_min_u32_e32 v61, v31, v60
	v_max_u32_e32 v28, v28, v57
	v_min_u32_e32 v56, v27, v55
	v_max_u32_e32 v27, v27, v55
	v_min_u32_e32 v54, v26, v53
	v_min_u32_e32 v16, v13, v12
	v_max_u32_e32 v12, v13, v12
	v_min_u32_e32 v11, v10, v9
	v_max_u32_e32 v9, v10, v9
	v_min_u32_e32 v5, v4, v3
	v_max_u32_e32 v3, v4, v3
	s_waitcnt lgkmcnt(0)
	v_min_u32_e32 v2, v1, v0
	v_max_u32_e32 v63, v1, v0
	v_max3_u32 v47, v47, v62, v61
	v_max_u32_e32 v29, v29, v58
	v_min_u32_e32 v57, v28, v56
	v_max_u32_e32 v28, v28, v56
	v_min_u32_e32 v55, v27, v54
	v_max_u32_e32 v20, v21, v20
	v_min_u32_e32 v13, v12, v11
	v_max_u32_e32 v11, v12, v11
	v_min_u32_e32 v10, v9, v8
	v_max_u32_e32 v8, v9, v8
	v_max_u32_e32 v62, v3, v2
	v_and_b32_e32 v0, 0x7fffff80, v63
	v_bitop3_b32 v1, v63, s61, v63 bitop3:0xcf
	v_cmp_gt_i32_e32 vcc, 0, v63
	v_max_u32_e32 v30, v30, v59
	v_min_u32_e32 v58, v29, v57
	v_max_u32_e32 v29, v29, v57
	v_min_u32_e32 v56, v28, v55
	v_max_u32_e32 v22, v22, v48
	v_min_u32_e32 v21, v20, v19
	v_max_u32_e32 v19, v20, v19
	v_min_u32_e32 v12, v11, v10
	v_max_u32_e32 v10, v11, v10
	v_min_u32_e32 v9, v8, v7
	v_max_u32_e32 v7, v8, v7
	v_min_u32_e32 v4, v3, v2
	v_max_u32_e32 v50, v14, v50
	v_cndmask_b32_e32 v1, v1, v0, vcc
	v_and_b32_e32 v0, 0x7fffff80, v62
	v_bitop3_b32 v2, v62, s61, v62 bitop3:0xcf
	v_cmp_gt_i32_e32 vcc, 0, v62
	v_max_u32_e32 v31, v31, v60
	v_min_u32_e32 v59, v30, v58
	v_max_u32_e32 v30, v30, v58
	v_min_u32_e32 v57, v29, v56
	v_max_u32_e32 v23, v23, v49
	v_min_u32_e32 v48, v22, v21
	v_max_u32_e32 v21, v22, v21
	v_min_u32_e32 v20, v19, v18
	v_max_u32_e32 v18, v19, v18
	v_min_u32_e32 v11, v10, v9
	v_max_u32_e32 v9, v10, v9
	v_min_u32_e32 v8, v7, v6
	v_max_u32_e32 v6, v7, v6
	v_cndmask_b32_e32 v0, v2, v0, vcc
	v_and_b32_e32 v2, 0x7fffff80, v50
	v_bitop3_b32 v3, v50, s61, v50 bitop3:0xcf
	v_cmp_gt_i32_e32 vcc, 0, v50
	v_min_u32_e32 v60, v31, v59
	v_max_u32_e32 v31, v31, v59
	v_min_u32_e32 v58, v30, v57
	v_max_u32_e32 v24, v24, v51
	v_min_u32_e32 v49, v23, v48
	v_max_u32_e32 v23, v23, v48
	v_min_u32_e32 v22, v21, v20
	v_min_u32_e32 v19, v18, v17
	v_max_u32_e32 v17, v18, v17
	v_min_u32_e32 v10, v9, v8
	v_max_u32_e32 v8, v9, v8
	v_min_u32_e32 v7, v6, v5
	v_max_u32_e32 v5, v6, v5
	v_cndmask_b32_e32 v2, v3, v2, vcc
	v_min_u32_e32 v59, v31, v58
	v_max_u32_e32 v25, v25, v52
	v_min_u32_e32 v51, v24, v49
	v_max_u32_e32 v24, v24, v49
	v_min_u32_e32 v48, v23, v22
	v_min_u32_e32 v18, v17, v16
	v_max_u32_e32 v16, v17, v16
	v_min_u32_e32 v9, v8, v7
	v_max_u32_e32 v7, v8, v7
	v_min_u32_e32 v6, v5, v4
	v_max_u32_e32 v61, v5, v4
	v_pk_add_f32 v[4:5], v[2:3], v[0:1] op_sel_hi:[0,1]
	v_max3_u32 v47, v47, v60, v59
	v_max_u32_e32 v26, v26, v53
	v_min_u32_e32 v52, v25, v51
	v_max_u32_e32 v25, v25, v51
	v_min_u32_e32 v49, v24, v48
	v_max_u32_e32 v20, v21, v20
	v_min_u32_e32 v17, v16, v13
	v_max_u32_e32 v13, v16, v13
	v_min_u32_e32 v8, v7, v6
	v_max_u32_e32 v60, v7, v6
	v_not_b32_e32 v3, v5
	v_or_b32_e32 v6, 0x80000000, v5
	v_cmp_gt_i32_e32 vcc, 0, v5
	v_max_u32_e32 v27, v27, v54
	v_min_u32_e32 v53, v26, v52
	v_max_u32_e32 v26, v26, v52
	v_min_u32_e32 v51, v25, v49
	v_min_u32_e32 v21, v20, v19
	v_max_u32_e32 v19, v20, v19
	v_min_u32_e32 v16, v13, v12
	v_max_u32_e32 v12, v13, v12
	v_cndmask_b32_e32 v3, v6, v3, vcc
	v_max_u32_e32 v28, v28, v55
	v_min_u32_e32 v54, v27, v53
	v_max_u32_e32 v27, v27, v53
	v_min_u32_e32 v52, v26, v51
	v_min_u32_e32 v20, v19, v18
	v_max_u32_e32 v18, v19, v18
	v_min_u32_e32 v13, v12, v11
	v_max_u32_e32 v11, v12, v11
	v_or_b32_e32 v5, 0xff, v3
	v_not_b32_e32 v3, v4
	v_or_b32_e32 v6, 0x80000000, v4
	v_cmp_gt_i32_e32 vcc, 0, v4
	v_max_u32_e32 v29, v29, v56
	v_min_u32_e32 v55, v28, v54
	v_max_u32_e32 v28, v28, v54
	v_min_u32_e32 v53, v27, v52
	v_min_u32_e32 v19, v18, v17
	v_max_u32_e32 v17, v18, v17
	v_min_u32_e32 v12, v11, v10
	v_max_u32_e32 v10, v11, v10
	v_cndmask_b32_e32 v3, v6, v3, vcc
	v_max_u32_e32 v30, v30, v57
	v_min_u32_e32 v56, v29, v55
	v_max_u32_e32 v29, v29, v55
	v_min_u32_e32 v54, v28, v53
	v_min_u32_e32 v18, v17, v16
	v_max_u32_e32 v16, v17, v16
	v_min_u32_e32 v11, v10, v9
	v_max_u32_e32 v9, v10, v9
	v_and_b32_e32 v3, 0xffffff00, v3
	v_max_u32_e32 v31, v31, v58
	v_min_u32_e32 v57, v30, v56
	v_max_u32_e32 v30, v30, v56
	v_min_u32_e32 v55, v29, v54
	v_min_u32_e32 v17, v16, v13
	v_max_u32_e32 v13, v16, v13
	v_min_u32_e32 v10, v9, v8
	v_max_u32_e32 v59, v9, v8
	v_or_b32_e32 v4, 0xfe, v3
	v_and_b32_e32 v3, 0x7fffff80, v61
	v_bitop3_b32 v8, v61, s61, v61 bitop3:0xcf
	v_cmp_gt_i32_e32 vcc, 0, v61
	v_min_u32_e32 v58, v31, v57
	v_max_u32_e32 v31, v31, v57
	v_min_u32_e32 v56, v30, v55
	v_min_u32_e32 v16, v13, v12
	v_max_u32_e32 v12, v13, v12
	v_cndmask_b32_e32 v3, v8, v3, vcc
	v_min_u32_e32 v57, v31, v56
	v_max_u32_e32 v22, v23, v22
	v_min_u32_e32 v13, v12, v11
	v_max_u32_e32 v11, v12, v11
	v_add_f32_e32 v8, v2, v3
	v_max3_u32 v47, v47, v58, v57
	v_min_u32_e32 v23, v22, v21
	v_max_u32_e32 v21, v22, v21
	v_min_u32_e32 v12, v11, v10
	v_max_u32_e32 v58, v11, v10
	v_not_b32_e32 v9, v8
	v_or_b32_e32 v10, 0x80000000, v8
	v_cmp_gt_i32_e32 vcc, 0, v8
	v_min_u32_e32 v22, v21, v20
	v_max_u32_e32 v20, v21, v20
	v_cndmask_b32_e32 v8, v10, v9, vcc
; DI unsigned f2ord(float f) { unsigned u = __float_as_uint(f); return (u & 0x80000000u) ? ~u : (u | 0x80000000u); }
; DI float ord2f(unsigned u) { return __uint_as_float((u & 0x80000000u) ? (u & 0x7fffffffu) : ~u); }
; #define INS32(T, X) { _Pragma("unroll") for (int jj = 0; jj < 16; ++jj) { unsigned t_ = max(T[jj], X); X = min(T[jj], X); T[jj] = t_; } }
; __device__ __forceinline__ void route_task(const Params& p, int layer, const u16* qg, int rb, int hd, int r, int h) {
;     ...
; #pragma unroll
;     for (int a = 0; a < 16; ++a) {
;       const float va = ord2f(top[0][a] & ~127u);
; #pragma unroll
;       for (int b = 0; b < 16; ++b) {
;         if ((a + 1) * (b + 1) <= 16) {
;           const float vb = ord2f(top[1][b] & ~127u);
;           unsigned key = (f2ord(va + vb) & ~255u) | (unsigned)(255 - (a * 16 + b));
;           INS32(ct, key);
;         }
;       }
;     }
	v_min_u32_e32 v21, v20, v19
	v_max_u32_e32 v19, v20, v19
	v_and_b32_e32 v8, 0xffffff00, v8
	v_min_u32_e32 v20, v19, v18
	v_max_u32_e32 v18, v19, v18
	v_max_u32_e32 v7, v5, v4
	v_or_b32_e32 v8, 0xfd, v8
	v_min_u32_e32 v19, v18, v17
	v_max_u32_e32 v17, v18, v17
	v_min_u32_e32 v6, v5, v4
	v_min_u32_e32 v9, v7, v8
	v_med3_u32 v5, v5, v4, v8
	v_max_u32_e32 v7, v7, v8
	v_and_b32_e32 v4, 0x7fffff80, v60
	v_bitop3_b32 v8, v60, s61, v60 bitop3:0xcf
	v_cmp_gt_i32_e32 vcc, 0, v60
	v_min_u32_e32 v18, v17, v16
	v_max_u32_e32 v16, v17, v16
	v_cndmask_b32_e32 v4, v8, v4, vcc
	v_min_u32_e32 v17, v16, v13
	v_max_u32_e32 v13, v16, v13
	v_add_f32_e32 v8, v2, v4
	v_min_u32_e32 v16, v13, v12
	v_max_u32_e32 v57, v13, v12
	v_not_b32_e32 v11, v8
	v_or_b32_e32 v12, 0x80000000, v8
	v_cmp_gt_i32_e32 vcc, 0, v8
	v_min_u32_e32 v10, v6, v9
	v_max_u32_e32 v24, v24, v48
	v_cndmask_b32_e32 v8, v12, v11, vcc
	v_and_b32_e32 v8, 0xffffff00, v8
	v_or_b32_e32 v8, 0xfc, v8
	v_min_u32_e32 v11, v7, v8
	v_min_u32_e32 v12, v5, v11
	v_med3_u32 v6, v6, v9, v11
	v_max_u32_e32 v9, v5, v11
	v_max_u32_e32 v7, v7, v8
	v_and_b32_e32 v5, 0x7fffff80, v59
	v_bitop3_b32 v8, v59, s61, v59 bitop3:0xcf
	v_cmp_gt_i32_e32 vcc, 0, v59
	v_max_u32_e32 v25, v25, v49
	v_min_u32_e32 v48, v24, v23
	v_cndmask_b32_e32 v5, v8, v5, vcc
	v_max_u32_e32 v23, v24, v23
	v_add_f32_e32 v8, v2, v5
	v_max_u32_e32 v26, v26, v51
	v_min_u32_e32 v49, v25, v48
	v_max_u32_e32 v25, v25, v48
	v_min_u32_e32 v24, v23, v22
	v_not_b32_e32 v11, v8
	v_or_b32_e32 v14, 0x80000000, v8
	v_cmp_gt_i32_e32 vcc, 0, v8
	v_max_u32_e32 v27, v27, v52
	v_min_u32_e32 v51, v26, v49
	v_max_u32_e32 v26, v26, v49
	v_min_u32_e32 v48, v25, v24
	v_cndmask_b32_e32 v8, v14, v11, vcc
	v_max_u32_e32 v28, v28, v53
	v_min_u32_e32 v52, v27, v51
	v_max_u32_e32 v27, v27, v51
	v_min_u32_e32 v49, v26, v48
	v_max_u32_e32 v22, v23, v22
	v_and_b32_e32 v8, 0xffffff00, v8
	v_max_u32_e32 v29, v29, v54
	v_min_u32_e32 v53, v28, v52
	v_max_u32_e32 v28, v28, v52
	v_min_u32_e32 v51, v27, v49
	v_min_u32_e32 v23, v22, v21
	v_max_u32_e32 v21, v22, v21
	v_or_b32_e32 v8, 0xfb, v8
	v_max_u32_e32 v30, v30, v55
	v_min_u32_e32 v54, v29, v53
	v_max_u32_e32 v29, v29, v53
	v_min_u32_e32 v52, v28, v51
	v_min_u32_e32 v22, v21, v20
	v_max_u32_e32 v20, v21, v20
	v_min_u32_e32 v11, v7, v8
	v_max_u32_e32 v31, v31, v56
	v_min_u32_e32 v55, v30, v54
	v_max_u32_e32 v30, v30, v54
	v_min_u32_e32 v53, v29, v52
	v_min_u32_e32 v21, v20, v19
	v_max_u32_e32 v19, v20, v19
	v_min_u32_e32 v14, v9, v11
	v_max_u32_e32 v9, v9, v11
	v_max_u32_e32 v7, v7, v8
	v_and_b32_e32 v8, 0x7fffff80, v58
	v_bitop3_b32 v11, v58, s61, v58 bitop3:0xcf
	v_cmp_gt_i32_e32 vcc, 0, v58
	v_min_u32_e32 v56, v31, v55
	v_max_u32_e32 v31, v31, v55
	v_min_u32_e32 v54, v30, v53
	v_min_u32_e32 v20, v19, v18
	v_max_u32_e32 v18, v19, v18
	v_cndmask_b32_e32 v8, v11, v8, vcc
	v_min_u32_e32 v55, v31, v54
	v_min_u32_e32 v19, v18, v17
	v_max_u32_e32 v17, v18, v17
	v_add_f32_e32 v11, v2, v8
	v_max3_u32 v47, v47, v56, v55
	v_min_u32_e32 v18, v17, v16
	v_max_u32_e32 v56, v17, v16
	v_min_u32_e32 v13, v10, v12
	v_min_u32_e32 v16, v6, v14
	v_med3_u32 v10, v10, v12, v14
	v_max_u32_e32 v6, v6, v14
	v_not_b32_e32 v12, v11
	v_or_b32_e32 v14, 0x80000000, v11
	v_cmp_gt_i32_e32 vcc, 0, v11
	v_max_u32_e32 v24, v25, v24
	v_min_u32_e32 v25, v24, v23
	v_cndmask_b32_e32 v11, v14, v12, vcc
	v_max_u32_e32 v23, v24, v23
	v_and_b32_e32 v11, 0xffffff00, v11
	v_min_u32_e32 v24, v23, v22
	v_max_u32_e32 v22, v23, v22
	v_or_b32_e32 v11, 0xfa, v11
	v_min_u32_e32 v23, v22, v21
	v_max_u32_e32 v21, v22, v21
	v_min_u32_e32 v12, v7, v11
	v_min_u32_e32 v22, v21, v20
	v_max_u32_e32 v20, v21, v20
	v_min_u32_e32 v14, v9, v12
	v_max_u32_e32 v9, v9, v12
	v_max_u32_e32 v11, v7, v11
	v_and_b32_e32 v7, 0x7fffff80, v57
	v_bitop3_b32 v12, v57, s61, v57 bitop3:0xcf
	v_cmp_gt_i32_e32 vcc, 0, v57
	v_min_u32_e32 v21, v20, v19
	v_max_u32_e32 v19, v20, v19
	v_cndmask_b32_e32 v7, v12, v7, vcc
	v_min_u32_e32 v20, v19, v18
	v_max_u32_e32 v55, v19, v18
	v_min_u32_e32 v18, v6, v14
	v_add_f32_e32 v12, v2, v7
	v_min_u32_e32 v17, v13, v16
	v_med3_u32 v13, v13, v16, v18
	v_max_u32_e32 v6, v6, v14
	v_not_b32_e32 v14, v12
	v_or_b32_e32 v16, 0x80000000, v12
	v_cmp_gt_i32_e32 vcc, 0, v12
	v_max_u32_e32 v26, v26, v48
	v_max_u32_e32 v27, v27, v49
	v_cndmask_b32_e32 v12, v16, v14, vcc
	v_min_u32_e32 v48, v26, v25
	v_max_u32_e32 v25, v26, v25
	v_and_b32_e32 v12, 0xffffff00, v12
	v_max_u32_e32 v28, v28, v51
	v_min_u32_e32 v49, v27, v48
	v_max_u32_e32 v27, v27, v48
	v_min_u32_e32 v26, v25, v24
	v_or_b32_e32 v12, 0xf9, v12
	v_max_u32_e32 v29, v29, v52
	v_min_u32_e32 v51, v28, v49
	v_max_u32_e32 v28, v28, v49
	v_min_u32_e32 v48, v27, v26
	v_min_u32_e32 v14, v11, v12
	v_max_u32_e32 v30, v30, v53
	v_min_u32_e32 v52, v29, v51
	v_max_u32_e32 v29, v29, v51
	v_min_u32_e32 v49, v28, v48
	v_max_u32_e32 v24, v25, v24
	v_min_u32_e32 v16, v9, v14
	v_max_u32_e32 v31, v31, v54
	v_min_u32_e32 v53, v30, v52
	v_max_u32_e32 v30, v30, v52
	v_min_u32_e32 v51, v29, v49
	v_min_u32_e32 v25, v24, v23
	v_max_u32_e32 v23, v24, v23
	v_min_u32_e32 v19, v10, v18
	v_max_u32_e32 v10, v10, v18
	v_min_u32_e32 v18, v6, v16
	v_max_u32_e32 v16, v6, v16
	v_max_u32_e32 v11, v11, v12
	v_and_b32_e32 v6, 0x7fffff80, v56
	v_bitop3_b32 v12, v56, s61, v56 bitop3:0xcf
	v_cmp_gt_i32_e32 vcc, 0, v56
	v_min_u32_e32 v54, v31, v53
	v_max_u32_e32 v31, v31, v53
	v_min_u32_e32 v52, v30, v51
	v_min_u32_e32 v24, v23, v22
	v_max_u32_e32 v22, v23, v22
	v_cndmask_b32_e32 v6, v12, v6, vcc
	v_min_u32_e32 v53, v31, v52
	v_min_u32_e32 v23, v22, v21
	v_max_u32_e32 v21, v22, v21
	v_add_f32_e32 v12, v2, v6
	v_max3_u32 v47, v47, v54, v53
	v_min_u32_e32 v22, v21, v20
; DI unsigned f2ord(float f) { unsigned u = __float_as_uint(f); return (u & 0x80000000u) ? ~u : (u | 0x80000000u); }
; DI float ord2f(unsigned u) { return __uint_as_float((u & 0x80000000u) ? (u & 0x7fffffffu) : ~u); }
; #define INS32(T, X) { _Pragma("unroll") for (int jj = 0; jj < 16; ++jj) { unsigned t_ = max(T[jj], X); X = min(T[jj], X); T[jj] = t_; } }
; __device__ __forceinline__ void route_task(const Params& p, int layer, const u16* qg, int rb, int hd, int r, int h) {
;     ...
; #pragma unroll
;     for (int a = 0; a < 16; ++a) {
;       const float va = ord2f(top[0][a] & ~127u);
; #pragma unroll
;       for (int b = 0; b < 16; ++b) {
;         if ((a + 1) * (b + 1) <= 16) {
;           const float vb = ord2f(top[1][b] & ~127u);
;           unsigned key = (f2ord(va + vb) & ~255u) | (unsigned)(255 - (a * 16 + b));
;           INS32(ct, key);
;         }
;       }
;     }
	v_max_u32_e32 v54, v21, v20
	v_min_u32_e32 v21, v10, v18
	v_max_u32_e32 v10, v10, v18
	v_max_u32_e32 v9, v9, v14
	v_not_b32_e32 v14, v12
	v_or_b32_e32 v18, 0x80000000, v12
	v_cmp_gt_i32_e32 vcc, 0, v12
	v_min_u32_e32 v20, v17, v19
	v_med3_u32 v17, v17, v19, v21
	v_cndmask_b32_e32 v12, v18, v14, vcc
	v_and_b32_e32 v12, 0xffffff00, v12
	v_or_b32_e32 v12, 0xf8, v12
	v_min_u32_e32 v14, v11, v12
	v_min_u32_e32 v18, v9, v14
	v_max_u32_e32 v9, v9, v14
	v_max_u32_e32 v11, v11, v12
	v_and_b32_e32 v12, 0x7fffff80, v55
	v_bitop3_b32 v14, v55, s61, v55 bitop3:0xcf
	v_cmp_gt_i32_e32 vcc, 0, v55
	v_min_u32_e32 v19, v16, v18
	v_max_u32_e32 v16, v16, v18
	v_cndmask_b32_e32 v12, v14, v12, vcc
	v_add_f32_e32 v12, v2, v12
	v_not_b32_e32 v14, v12
	v_or_b32_e32 v18, 0x80000000, v12
	v_cmp_gt_i32_e32 vcc, 0, v12
	v_max_u32_e32 v26, v27, v26
	v_min_u32_e32 v27, v26, v25
	v_cndmask_b32_e32 v12, v18, v14, vcc
	v_and_b32_e32 v12, 0xffffff00, v12
	v_or_b32_e32 v12, 0xf7, v12
	v_min_u32_e32 v14, v11, v12
	v_max_u32_e32 v25, v26, v25
	v_min_u32_e32 v18, v9, v14
	v_max_u32_e32 v9, v9, v14
	v_max_u32_e32 v11, v11, v12
	v_and_b32_e32 v12, 0x7fffff80, v54
	v_bitop3_b32 v14, v54, s61, v54 bitop3:0xcf
	v_cmp_gt_i32_e32 vcc, 0, v54
	v_min_u32_e32 v26, v25, v24
	v_max_u32_e32 v24, v25, v24
	v_cndmask_b32_e32 v12, v14, v12, vcc
	v_min_u32_e32 v25, v24, v23
	v_max_u32_e32 v23, v24, v23
	v_add_f32_e32 v12, v2, v12
	v_min_u32_e32 v24, v23, v22
	v_max_u32_e32 v53, v23, v22
	v_min_u32_e32 v22, v13, v21
	v_max_u32_e32 v13, v13, v21
	v_min_u32_e32 v21, v10, v19
	v_max_u32_e32 v10, v10, v19
	v_min_u32_e32 v19, v16, v18
	v_max_u32_e32 v16, v16, v18
	v_not_b32_e32 v14, v12
	v_or_b32_e32 v18, 0x80000000, v12
	v_cmp_gt_i32_e32 vcc, 0, v12
	v_max_u32_e32 v28, v28, v48
	v_max_u32_e32 v29, v29, v49
	v_cndmask_b32_e32 v12, v18, v14, vcc
	v_and_b32_e32 v12, 0xffffff00, v12
	v_min_u32_e32 v48, v28, v27
	v_max_u32_e32 v27, v28, v27
	v_or_b32_e32 v12, 0xf6, v12
	v_max_u32_e32 v30, v30, v51
	v_min_u32_e32 v49, v29, v48
	v_max_u32_e32 v29, v29, v48
	v_min_u32_e32 v28, v27, v26
	v_min_u32_e32 v14, v11, v12
	v_max_u32_e32 v31, v31, v52
	v_min_u32_e32 v51, v30, v49
	v_max_u32_e32 v30, v30, v49
	v_min_u32_e32 v48, v29, v28
	v_min_u32_e32 v18, v9, v14
	v_max_u32_e32 v9, v9, v14
	v_max_u32_e32 v11, v11, v12
	v_and_b32_e32 v12, 0x7fffff80, v53
	v_bitop3_b32 v14, v53, s61, v53 bitop3:0xcf
	v_cmp_gt_i32_e32 vcc, 0, v53
	v_min_u32_e32 v52, v31, v51
	v_max_u32_e32 v31, v31, v51
	v_min_u32_e32 v49, v30, v48
	v_max_u32_e32 v26, v27, v26
	v_cndmask_b32_e32 v12, v14, v12, vcc
	v_min_u32_e32 v51, v31, v49
	v_min_u32_e32 v27, v26, v25
	v_max_u32_e32 v25, v26, v25
	v_add_f32_e32 v12, v2, v12
	v_max3_u32 v47, v47, v52, v51
	v_min_u32_e32 v26, v25, v24
	v_max_u32_e32 v52, v25, v24
	v_min_u32_e32 v24, v13, v21
	v_max_u32_e32 v13, v13, v21
	v_min_u32_e32 v21, v10, v19
	v_max_u32_e32 v10, v10, v19
	v_min_u32_e32 v19, v16, v18
	v_max_u32_e32 v16, v16, v18
	v_not_b32_e32 v14, v12
	v_or_b32_e32 v18, 0x80000000, v12
	v_cmp_gt_i32_e32 vcc, 0, v12
	v_min_u32_e32 v23, v20, v22
	v_med3_u32 v20, v20, v22, v24
	v_cndmask_b32_e32 v12, v18, v14, vcc
	v_and_b32_e32 v12, 0xffffff00, v12
	v_or_b32_e32 v12, 0xf5, v12
	v_min_u32_e32 v14, v11, v12
	v_min_u32_e32 v18, v9, v14
	v_max_u32_e32 v9, v9, v14
	v_max_u32_e32 v11, v11, v12
	v_and_b32_e32 v12, 0x7fffff80, v52
	v_bitop3_b32 v14, v52, s61, v52 bitop3:0xcf
	v_cmp_gt_i32_e32 vcc, 0, v52
	v_min_u32_e32 v22, v13, v21
	v_max_u32_e32 v13, v13, v21
	v_cndmask_b32_e32 v12, v14, v12, vcc
	v_add_f32_e32 v12, v2, v12
	v_min_u32_e32 v21, v10, v19
	v_max_u32_e32 v10, v10, v19
	v_min_u32_e32 v19, v16, v18
	v_max_u32_e32 v16, v16, v18
	v_not_b32_e32 v14, v12
	v_or_b32_e32 v18, 0x80000000, v12
	v_cmp_gt_i32_e32 vcc, 0, v12
	v_max_u32_e32 v28, v29, v28
	v_min_u32_e32 v29, v28, v27
	v_cndmask_b32_e32 v12, v18, v14, vcc
	v_and_b32_e32 v12, 0xffffff00, v12
	v_max_u32_e32 v27, v28, v27
	v_or_b32_e32 v12, 0xf4, v12
	v_max_u32_e32 v51, v27, v26
	v_min_u32_e32 v14, v11, v12
	v_min_u32_e32 v18, v9, v14
	v_max_u32_e32 v9, v9, v14
	v_max_u32_e32 v11, v11, v12
	v_and_b32_e32 v12, 0x7fffff80, v51
	v_bitop3_b32 v14, v51, s61, v51 bitop3:0xcf
	v_cmp_gt_i32_e32 vcc, 0, v51
	v_min_u32_e32 v25, v17, v24
	v_max_u32_e32 v17, v17, v24
	v_cndmask_b32_e32 v12, v14, v12, vcc
	v_add_f32_e32 v12, v2, v12
	v_max_u32_e32 v30, v30, v48
	v_min_u32_e32 v24, v17, v22
	v_max_u32_e32 v17, v17, v22
	v_min_u32_e32 v22, v13, v21
	v_max_u32_e32 v13, v13, v21
	v_min_u32_e32 v21, v10, v19
	v_max_u32_e32 v10, v10, v19
	v_min_u32_e32 v19, v16, v18
	v_max_u32_e32 v16, v16, v18
	v_not_b32_e32 v14, v12
	v_or_b32_e32 v18, 0x80000000, v12
	v_cmp_gt_i32_e32 vcc, 0, v12
	v_max_u32_e32 v31, v31, v49
	v_min_u32_e32 v48, v30, v29
	v_max_u32_e32 v29, v30, v29
	v_min_u32_e32 v28, v27, v26
	v_cndmask_b32_e32 v12, v18, v14, vcc
	v_min_u32_e32 v49, v31, v48
	v_max_u32_e32 v31, v31, v48
	v_min_u32_e32 v30, v29, v28
	v_and_b32_e32 v12, 0xffffff00, v12
	v_min_u32_e32 v48, v31, v30
	v_or_b32_e32 v12, 0xf3, v12
	v_max3_u32 v47, v47, v49, v48
	v_max_u32_e32 v49, v29, v28
	v_min_u32_e32 v14, v11, v12
	v_min_u32_e32 v18, v9, v14
	v_max_u32_e32 v9, v9, v14
	v_max_u32_e32 v11, v11, v12
	v_and_b32_e32 v12, 0x7fffff80, v49
	v_bitop3_b32 v14, v49, s61, v49 bitop3:0xcf
	v_cmp_gt_i32_e32 vcc, 0, v49
	v_min_u32_e32 v26, v23, v25
	v_min_u32_e32 v27, v20, v24
	v_cndmask_b32_e32 v12, v14, v12, vcc
	v_add_f32_e32 v12, v2, v12
	v_med3_u32 v23, v23, v25, v24
	v_max_u32_e32 v20, v20, v24
	v_min_u32_e32 v24, v17, v22
	v_max_u32_e32 v17, v17, v22
	v_min_u32_e32 v22, v13, v21
	v_max_u32_e32 v13, v13, v21
	v_min_u32_e32 v21, v10, v19
	v_max_u32_e32 v10, v10, v19
; DI unsigned f2ord(float f) { unsigned u = __float_as_uint(f); return (u & 0x80000000u) ? ~u : (u | 0x80000000u); }
; DI float ord2f(unsigned u) { return __uint_as_float((u & 0x80000000u) ? (u & 0x7fffffffu) : ~u); }
; #define INS32(T, X) { _Pragma("unroll") for (int jj = 0; jj < 16; ++jj) { unsigned t_ = max(T[jj], X); X = min(T[jj], X); T[jj] = t_; } }
; __device__ __forceinline__ void route_task(const Params& p, int layer, const u16* qg, int rb, int hd, int r, int h) {
;     ...
; #pragma unroll
;     for (int a = 0; a < 16; ++a) {
;       const float va = ord2f(top[0][a] & ~127u);
; #pragma unroll
;       for (int b = 0; b < 16; ++b) {
;         if ((a + 1) * (b + 1) <= 16) {
;           const float vb = ord2f(top[1][b] & ~127u);
;           unsigned key = (f2ord(va + vb) & ~255u) | (unsigned)(255 - (a * 16 + b));
;           INS32(ct, key);
;         }
;       }
;     }
	v_min_u32_e32 v19, v16, v18
	v_max_u32_e32 v16, v16, v18
	v_not_b32_e32 v14, v12
	v_or_b32_e32 v18, 0x80000000, v12
	v_cmp_gt_i32_e32 vcc, 0, v12
	v_max_u32_e32 v48, v31, v30
	v_min_u32_e32 v25, v20, v24
	v_cndmask_b32_e32 v12, v18, v14, vcc
	v_and_b32_e32 v12, 0xffffff00, v12
	v_or_b32_e32 v12, 0xf2, v12
	v_min_u32_e32 v14, v11, v12
	v_min_u32_e32 v18, v9, v14
	v_max_u32_e32 v9, v9, v14
	v_max_u32_e32 v11, v11, v12
	v_and_b32_e32 v12, 0x7fffff80, v48
	v_bitop3_b32 v14, v48, s61, v48 bitop3:0xcf
	v_cmp_gt_i32_e32 vcc, 0, v48
	v_max_u32_e32 v20, v20, v24
	v_min_u32_e32 v24, v17, v22
	v_cndmask_b32_e32 v12, v14, v12, vcc
	v_add_f32_e32 v12, v2, v12
	v_max_u32_e32 v17, v17, v22
	v_min_u32_e32 v22, v13, v21
	v_max_u32_e32 v13, v13, v21
	v_min_u32_e32 v21, v10, v19
	v_max_u32_e32 v10, v10, v19
	v_min_u32_e32 v19, v16, v18
	v_max_u32_e32 v16, v16, v18
	v_not_b32_e32 v14, v12
	v_or_b32_e32 v18, 0x80000000, v12
	v_cmp_gt_i32_e32 vcc, 0, v12
	v_min_u32_e32 v28, v26, v27
	v_min_u32_e32 v29, v23, v25
	v_cndmask_b32_e32 v12, v18, v14, vcc
	v_and_b32_e32 v12, 0xffffff00, v12
	v_or_b32_e32 v12, 0xf1, v12
	v_min_u32_e32 v14, v11, v12
	v_min_u32_e32 v18, v9, v14
	v_max_u32_e32 v9, v9, v14
	v_max_u32_e32 v11, v11, v12
	v_and_b32_e32 v12, 0x7fffff80, v47
	v_bitop3_b32 v14, v47, s61, v47 bitop3:0xcf
	v_cmp_gt_i32_e32 vcc, 0, v47
	v_med3_u32 v26, v26, v27, v25
	v_max_u32_e32 v23, v23, v25
	v_cndmask_b32_e32 v12, v14, v12, vcc
	v_add_f32_e32 v2, v2, v12
	v_not_b32_e32 v12, v2
	v_or_b32_e32 v14, 0x80000000, v2
	v_cmp_gt_i32_e32 vcc, 0, v2
	v_min_u32_e32 v25, v20, v24
	v_max_u32_e32 v20, v20, v24
	v_cndmask_b32_e32 v2, v14, v12, vcc
	v_and_b32_e32 v2, 0xffffff00, v2
	v_or_b32_e32 v2, 0xf0, v2
	v_min_u32_e32 v12, v11, v2
	v_min_u32_e32 v14, v9, v12
	v_max_u32_e32 v9, v9, v12
	v_max_u32_e32 v2, v11, v2
	v_and_b32_e32 v11, 0x7fffff80, v46
	v_bitop3_b32 v12, v46, s61, v46 bitop3:0xcf
	v_cmp_gt_i32_e32 vcc, 0, v46
	v_min_u32_e32 v24, v17, v22
	v_max_u32_e32 v17, v17, v22
	v_min_u32_e32 v22, v13, v21
	v_max_u32_e32 v13, v13, v21
	v_min_u32_e32 v21, v10, v19
	v_max_u32_e32 v10, v10, v19
	v_min_u32_e32 v19, v16, v18
	v_max_u32_e32 v16, v16, v18
	v_cndmask_b32_e32 v11, v12, v11, vcc
	v_min_u32_e32 v27, v23, v25
	v_max_u32_e32 v23, v23, v25
	v_min_u32_e32 v25, v20, v24
	v_max_u32_e32 v20, v20, v24
	v_min_u32_e32 v24, v17, v22
	v_max_u32_e32 v17, v17, v22
	v_min_u32_e32 v22, v13, v21
	v_max_u32_e32 v13, v13, v21
	v_min_u32_e32 v21, v10, v19
	v_max_u32_e32 v10, v10, v19
	v_min_u32_e32 v18, v16, v14
	v_add_f32_e32 v12, v11, v1
	v_min_u32_e32 v19, v10, v18
	v_max_u32_e32 v10, v10, v18
	v_max_u32_e32 v14, v16, v14
	v_not_b32_e32 v16, v12
	v_or_b32_e32 v18, 0x80000000, v12
	v_cmp_gt_i32_e32 vcc, 0, v12
	v_min_u32_e32 v30, v28, v29
	v_min_u32_e32 v31, v26, v27
	v_cndmask_b32_e32 v12, v18, v16, vcc
	v_and_b32_e32 v12, 0xffffff00, v12
	v_or_b32_e32 v12, 0xef, v12
	v_min_u32_e32 v16, v2, v12
	v_med3_u32 v28, v28, v29, v27
	v_max_u32_e32 v26, v26, v27
	v_min_u32_e32 v27, v23, v25
	v_max_u32_e32 v23, v23, v25
	v_min_u32_e32 v25, v20, v24
	v_max_u32_e32 v20, v20, v24
	v_min_u32_e32 v24, v17, v22
	v_max_u32_e32 v17, v17, v22
	v_min_u32_e32 v22, v13, v21
	v_max_u32_e32 v13, v13, v21
	v_min_u32_e32 v18, v9, v16
	v_max_u32_e32 v2, v2, v12
	v_add_f32_e32 v12, v11, v0
	v_min_u32_e32 v21, v13, v19
	v_max_u32_e32 v13, v13, v19
	v_min_u32_e32 v19, v14, v18
	v_max_u32_e32 v14, v14, v18
	v_max_u32_e32 v9, v9, v16
	v_not_b32_e32 v16, v12
	v_or_b32_e32 v18, 0x80000000, v12
	v_cmp_gt_i32_e32 vcc, 0, v12
	v_min_u32_e32 v29, v26, v27
	v_max_u32_e32 v26, v26, v27
	v_cndmask_b32_e32 v12, v18, v16, vcc
	v_and_b32_e32 v12, 0xffffff00, v12
	v_or_b32_e32 v12, 0xee, v12
	v_min_u32_e32 v16, v2, v12
	v_min_u32_e32 v27, v23, v25
	v_max_u32_e32 v23, v23, v25
	v_min_u32_e32 v25, v20, v24
	v_max_u32_e32 v20, v20, v24
	v_min_u32_e32 v24, v17, v22
	v_max_u32_e32 v17, v17, v22
	v_min_u32_e32 v18, v9, v16
	v_max_u32_e32 v2, v2, v12
	v_add_f32_e32 v12, v11, v3
	v_min_u32_e32 v22, v17, v21
	v_max_u32_e32 v17, v17, v21
	v_min_u32_e32 v21, v10, v19
	v_max_u32_e32 v10, v10, v19
	v_min_u32_e32 v19, v14, v18
	v_max_u32_e32 v14, v14, v18
	v_max_u32_e32 v9, v9, v16
	v_not_b32_e32 v16, v12
	v_or_b32_e32 v18, 0x80000000, v12
	v_cmp_gt_i32_e32 vcc, 0, v12
	v_min_u32_e32 v64, v30, v31
	v_min_u32_e32 v65, v28, v29
	v_cndmask_b32_e32 v12, v18, v16, vcc
	v_and_b32_e32 v12, 0xffffff00, v12
	v_or_b32_e32 v12, 0xed, v12
	v_min_u32_e32 v16, v2, v12
	v_med3_u32 v30, v30, v31, v29
	v_max_u32_e32 v28, v28, v29
	v_min_u32_e32 v29, v26, v27
	v_max_u32_e32 v26, v26, v27
	v_min_u32_e32 v27, v23, v25
	v_max_u32_e32 v23, v23, v25
	v_min_u32_e32 v25, v20, v24
	v_max_u32_e32 v20, v20, v24
	v_min_u32_e32 v18, v9, v16
	v_max_u32_e32 v2, v2, v12
	v_add_f32_e32 v12, v11, v4
	v_min_u32_e32 v24, v20, v22
	v_max_u32_e32 v20, v20, v22
	v_min_u32_e32 v22, v13, v21
	v_max_u32_e32 v13, v13, v21
	v_min_u32_e32 v21, v10, v19
	v_max_u32_e32 v10, v10, v19
	v_min_u32_e32 v19, v14, v18
	v_max_u32_e32 v14, v14, v18
	v_max_u32_e32 v9, v9, v16
	v_not_b32_e32 v16, v12
	v_or_b32_e32 v18, 0x80000000, v12
	v_cmp_gt_i32_e32 vcc, 0, v12
	v_min_u32_e32 v31, v28, v29
	v_max_u32_e32 v28, v28, v29
	v_cndmask_b32_e32 v12, v18, v16, vcc
	v_and_b32_e32 v12, 0xffffff00, v12
	v_or_b32_e32 v12, 0xec, v12
	v_min_u32_e32 v16, v2, v12
	v_min_u32_e32 v29, v26, v27
	v_max_u32_e32 v26, v26, v27
	v_min_u32_e32 v27, v23, v25
	v_max_u32_e32 v23, v23, v25
	v_min_u32_e32 v18, v9, v16
	v_max_u32_e32 v2, v2, v12
	v_add_f32_e32 v12, v11, v5
	v_min_u32_e32 v25, v23, v24
	v_max_u32_e32 v23, v23, v24
	v_min_u32_e32 v24, v17, v22
	v_max_u32_e32 v17, v17, v22
	v_min_u32_e32 v22, v13, v21
; DI unsigned f2ord(float f) { unsigned u = __float_as_uint(f); return (u & 0x80000000u) ? ~u : (u | 0x80000000u); }
; DI float ord2f(unsigned u) { return __uint_as_float((u & 0x80000000u) ? (u & 0x7fffffffu) : ~u); }
; #define INS32(T, X) { _Pragma("unroll") for (int jj = 0; jj < 16; ++jj) { unsigned t_ = max(T[jj], X); X = min(T[jj], X); T[jj] = t_; } }
; __device__ __forceinline__ void route_task(const Params& p, int layer, const u16* qg, int rb, int hd, int r, int h) {
;     ...
; #pragma unroll
;     for (int a = 0; a < 16; ++a) {
;       const float va = ord2f(top[0][a] & ~127u);
; #pragma unroll
;       for (int b = 0; b < 16; ++b) {
;         if ((a + 1) * (b + 1) <= 16) {
;           const float vb = ord2f(top[1][b] & ~127u);
;           unsigned key = (f2ord(va + vb) & ~255u) | (unsigned)(255 - (a * 16 + b));
;           INS32(ct, key);
;         }
;       }
;     }
	v_max_u32_e32 v13, v13, v21
	v_min_u32_e32 v21, v10, v19
	v_max_u32_e32 v10, v10, v19
	v_min_u32_e32 v19, v14, v18
	v_max_u32_e32 v14, v14, v18
	v_max_u32_e32 v9, v9, v16
	v_not_b32_e32 v16, v12
	v_or_b32_e32 v18, 0x80000000, v12
	v_cmp_gt_i32_e32 vcc, 0, v12
	v_add_f32_e32 v8, v11, v8
	v_add_f32_e32 v7, v11, v7
	v_cndmask_b32_e32 v12, v18, v16, vcc
	v_and_b32_e32 v12, 0xffffff00, v12
	v_or_b32_e32 v12, 0xeb, v12
	v_min_u32_e32 v16, v2, v12
	v_min_u32_e32 v18, v9, v16
	v_max_u32_e32 v9, v9, v16
	v_max_u32_e32 v2, v2, v12
	v_not_b32_e32 v12, v8
	v_or_b32_e32 v16, 0x80000000, v8
	v_cmp_gt_i32_e32 vcc, 0, v8
	v_add_f32_e32 v6, v11, v6
	v_min_u32_e32 v66, v64, v65
	v_cndmask_b32_e32 v8, v16, v12, vcc
	v_and_b32_e32 v8, 0xffffff00, v8
	v_or_b32_e32 v8, 0xea, v8
	v_min_u32_e32 v12, v2, v8
	v_min_u32_e32 v16, v9, v12
	v_max_u32_e32 v9, v9, v12
	v_max_u32_e32 v2, v2, v8
	v_not_b32_e32 v8, v7
	v_or_b32_e32 v12, 0x80000000, v7
	v_cmp_gt_i32_e32 vcc, 0, v7
	v_min_u32_e32 v67, v30, v31
	v_med3_u32 v64, v64, v65, v31
	v_cndmask_b32_e32 v7, v12, v8, vcc
	v_and_b32_e32 v7, 0xffffff00, v7
	v_or_b32_e32 v7, 0xe9, v7
	v_min_u32_e32 v8, v2, v7
	v_min_u32_e32 v12, v9, v8
	v_max_u32_e32 v8, v9, v8
	v_max_u32_e32 v2, v2, v7
	v_not_b32_e32 v7, v6
	v_or_b32_e32 v9, 0x80000000, v6
	v_cmp_gt_i32_e32 vcc, 0, v6
	v_max_u32_e32 v30, v30, v31
	v_min_u32_e32 v31, v28, v29
	v_cndmask_b32_e32 v6, v9, v7, vcc
	v_and_b32_e32 v6, 0xffffff00, v6
	v_max_u32_e32 v28, v28, v29
	v_min_u32_e32 v29, v26, v27
	v_max_u32_e32 v26, v26, v27
	v_or_b32_e32 v6, 0xe8, v6
	v_min_u32_e32 v65, v30, v31
	v_max_u32_e32 v30, v30, v31
	v_min_u32_e32 v31, v28, v29
	v_max_u32_e32 v28, v28, v29
	v_min_u32_e32 v27, v26, v25
	v_max_u32_e32 v25, v26, v25
	v_min_u32_e32 v26, v20, v24
	v_max_u32_e32 v20, v20, v24
	v_min_u32_e32 v24, v17, v22
	v_max_u32_e32 v17, v17, v22
	v_min_u32_e32 v22, v13, v21
	v_max_u32_e32 v13, v13, v21
	v_min_u32_e32 v21, v10, v19
	v_max_u32_e32 v10, v10, v19
	v_min_u32_e32 v19, v14, v18
	v_max_u32_e32 v14, v14, v18
	v_min_u32_e32 v7, v2, v6
	v_min_u32_e32 v29, v28, v27
	v_max_u32_e32 v27, v28, v27
	v_min_u32_e32 v28, v23, v26
	v_max_u32_e32 v23, v23, v26
	v_min_u32_e32 v26, v20, v24
	v_max_u32_e32 v20, v20, v24
	v_min_u32_e32 v24, v17, v22
	v_max_u32_e32 v17, v17, v22
	v_min_u32_e32 v22, v13, v21
	v_max_u32_e32 v13, v13, v21
	v_min_u32_e32 v21, v10, v19
	v_max_u32_e32 v10, v10, v19
	v_min_u32_e32 v18, v14, v16
	v_max_u32_e32 v14, v14, v16
	v_min_u32_e32 v9, v8, v7
	v_max_u32_e32 v7, v8, v7
	v_max_u32_e32 v2, v2, v6
	v_and_b32_e32 v6, 0x7fffff80, v45
	v_bitop3_b32 v8, v45, s61, v45 bitop3:0xcf
	v_cmp_gt_i32_e32 vcc, 0, v45
	v_min_u32_e32 v19, v10, v18
	v_max_u32_e32 v10, v10, v18
	v_min_u32_e32 v16, v14, v12
	v_max_u32_e32 v12, v14, v12
	v_cndmask_b32_e32 v6, v8, v6, vcc
	v_min_u32_e32 v18, v10, v16
	v_max_u32_e32 v10, v10, v16
	v_min_u32_e32 v11, v12, v9
	v_add_f32_e32 v8, v6, v1
	v_min_u32_e32 v14, v10, v11
	v_max_u32_e32 v10, v10, v11
	v_max_u32_e32 v9, v12, v9
	v_not_b32_e32 v11, v8
	v_or_b32_e32 v12, 0x80000000, v8
	v_cmp_gt_i32_e32 vcc, 0, v8
	v_min_u32_e32 v68, v66, v67
	v_min_u32_e32 v69, v64, v65
	v_cndmask_b32_e32 v8, v12, v11, vcc
	v_med3_u32 v66, v66, v67, v65
	v_max_u32_e32 v64, v64, v65
	v_min_u32_e32 v65, v30, v31
	v_max_u32_e32 v30, v30, v31
	v_and_b32_e32 v8, 0xffffff00, v8
	v_min_u32_e32 v31, v30, v29
	v_max_u32_e32 v29, v30, v29
	v_min_u32_e32 v30, v25, v28
	v_max_u32_e32 v25, v25, v28
	v_min_u32_e32 v28, v23, v26
	v_max_u32_e32 v23, v23, v26
	v_min_u32_e32 v26, v20, v24
	v_max_u32_e32 v20, v20, v24
	v_min_u32_e32 v24, v17, v22
	v_max_u32_e32 v17, v17, v22
	v_min_u32_e32 v22, v13, v21
	v_max_u32_e32 v13, v13, v21
	v_or_b32_e32 v8, 0xdf, v8
	v_min_u32_e32 v21, v13, v19
	v_max_u32_e32 v13, v13, v19
	v_min_u32_e32 v11, v2, v8
	v_min_u32_e32 v19, v13, v18
	v_max_u32_e32 v13, v13, v18
	v_min_u32_e32 v12, v7, v11
	v_max_u32_e32 v2, v2, v8
	v_add_f32_e32 v8, v6, v0
	v_min_u32_e32 v16, v13, v14
	v_max_u32_e32 v13, v13, v14
	v_min_u32_e32 v14, v9, v12
	v_max_u32_e32 v9, v9, v12
	v_max_u32_e32 v7, v7, v11
	v_not_b32_e32 v11, v8
	v_or_b32_e32 v12, 0x80000000, v8
	v_cmp_gt_i32_e32 vcc, 0, v8
	v_min_u32_e32 v67, v64, v65
	v_max_u32_e32 v64, v64, v65
	v_cndmask_b32_e32 v8, v12, v11, vcc
	v_and_b32_e32 v8, 0xffffff00, v8
	v_min_u32_e32 v65, v64, v31
	v_max_u32_e32 v31, v64, v31
	v_min_u32_e32 v64, v27, v30
	v_max_u32_e32 v27, v27, v30
	v_min_u32_e32 v30, v25, v28
	v_max_u32_e32 v25, v25, v28
	v_min_u32_e32 v28, v23, v26
	v_max_u32_e32 v23, v23, v26
	v_min_u32_e32 v26, v20, v24
	v_max_u32_e32 v20, v20, v24
	v_min_u32_e32 v24, v17, v22
	v_max_u32_e32 v17, v17, v22
	v_or_b32_e32 v8, 0xde, v8
	v_min_u32_e32 v22, v17, v21
	v_max_u32_e32 v17, v17, v21
	v_min_u32_e32 v11, v2, v8
	v_min_u32_e32 v21, v17, v19
	v_max_u32_e32 v17, v17, v19
	v_min_u32_e32 v12, v7, v11
	v_max_u32_e32 v2, v2, v8
	v_add_f32_e32 v8, v6, v3
	v_min_u32_e32 v18, v17, v16
	v_max_u32_e32 v16, v17, v16
	v_min_u32_e32 v17, v10, v14
	v_max_u32_e32 v10, v10, v14
	v_min_u32_e32 v14, v9, v12
	v_max_u32_e32 v9, v9, v12
	v_max_u32_e32 v7, v7, v11
	v_not_b32_e32 v11, v8
	v_or_b32_e32 v12, 0x80000000, v8
	v_cmp_gt_i32_e32 vcc, 0, v8
	v_min_u32_e32 v71, v66, v67
	v_max_u32_e32 v66, v66, v67
	v_cndmask_b32_e32 v8, v12, v11, vcc
	v_and_b32_e32 v8, 0xffffff00, v8
	v_min_u32_e32 v70, v68, v69
	v_med3_u32 v68, v68, v69, v67
	v_min_u32_e32 v67, v66, v65
	v_max_u32_e32 v65, v66, v65
	v_min_u32_e32 v66, v29, v64
	v_max_u32_e32 v29, v29, v64
	v_min_u32_e32 v64, v27, v30
	v_max_u32_e32 v27, v27, v30
	v_min_u32_e32 v30, v25, v28
	v_max_u32_e32 v25, v25, v28
	v_min_u32_e32 v28, v23, v26
	v_max_u32_e32 v23, v23, v26
; DI unsigned f2ord(float f) { unsigned u = __float_as_uint(f); return (u & 0x80000000u) ? ~u : (u | 0x80000000u); }
; DI float ord2f(unsigned u) { return __uint_as_float((u & 0x80000000u) ? (u & 0x7fffffffu) : ~u); }
; #define INS32(T, X) { _Pragma("unroll") for (int jj = 0; jj < 16; ++jj) { unsigned t_ = max(T[jj], X); X = min(T[jj], X); T[jj] = t_; } }
; __device__ __forceinline__ void route_task(const Params& p, int layer, const u16* qg, int rb, int hd, int r, int h) {
;     ...
; #pragma unroll
;     for (int a = 0; a < 16; ++a) {
;       const float va = ord2f(top[0][a] & ~127u);
; #pragma unroll
;       for (int b = 0; b < 16; ++b) {
;         if ((a + 1) * (b + 1) <= 16) {
;           const float vb = ord2f(top[1][b] & ~127u);
;           unsigned key = (f2ord(va + vb) & ~255u) | (unsigned)(255 - (a * 16 + b));
;           INS32(ct, key);
;         }
;       }
;     }
	v_min_u32_e32 v26, v20, v24
	v_max_u32_e32 v20, v20, v24
	v_or_b32_e32 v8, 0xdd, v8
	v_min_u32_e32 v24, v20, v22
	v_max_u32_e32 v20, v20, v22
	v_min_u32_e32 v11, v2, v8
	v_min_u32_e32 v22, v20, v21
	v_max_u32_e32 v20, v20, v21
	v_min_u32_e32 v12, v7, v11
	v_max_u32_e32 v2, v2, v8
	v_add_f32_e32 v8, v6, v4
	v_min_u32_e32 v19, v20, v18
	v_max_u32_e32 v18, v20, v18
	v_min_u32_e32 v20, v13, v17
	v_max_u32_e32 v13, v13, v17
	v_min_u32_e32 v17, v10, v14
	v_max_u32_e32 v10, v10, v14
	v_min_u32_e32 v14, v9, v12
	v_max_u32_e32 v9, v9, v12
	v_max_u32_e32 v7, v7, v11
	v_not_b32_e32 v11, v8
	v_or_b32_e32 v12, 0x80000000, v8
	v_cmp_gt_i32_e32 vcc, 0, v8
	v_add_f32_e32 v5, v6, v5
	v_not_b32_e32 v6, v5
	v_cndmask_b32_e32 v8, v12, v11, vcc
	v_and_b32_e32 v8, 0xffffff00, v8
	v_or_b32_e32 v8, 0xdc, v8
	v_min_u32_e32 v11, v2, v8
	v_max_u32_e32 v2, v2, v8
	v_or_b32_e32 v8, 0x80000000, v5
	v_cmp_gt_i32_e32 vcc, 0, v5
	v_min_u32_e32 v72, v70, v71
	v_min_u32_e32 v69, v68, v67
	v_cndmask_b32_e32 v5, v8, v6, vcc
	v_and_b32_e32 v5, 0xffffff00, v5
	v_med3_u32 v70, v70, v71, v67
	v_max_u32_e32 v67, v68, v67
	v_min_u32_e32 v68, v31, v66
	v_max_u32_e32 v31, v31, v66
	v_min_u32_e32 v66, v29, v64
	v_max_u32_e32 v29, v29, v64
	v_min_u32_e32 v64, v27, v30
	v_max_u32_e32 v27, v27, v30
	v_min_u32_e32 v30, v25, v28
	v_max_u32_e32 v25, v25, v28
	v_min_u32_e32 v28, v23, v26
	v_max_u32_e32 v23, v23, v26
	v_or_b32_e32 v5, 0xdb, v5
	v_min_u32_e32 v71, v65, v68
	v_max_u32_e32 v65, v65, v68
	v_min_u32_e32 v68, v31, v66
	v_max_u32_e32 v31, v31, v66
	v_min_u32_e32 v66, v29, v64
	v_max_u32_e32 v29, v29, v64
	v_min_u32_e32 v64, v27, v30
	v_max_u32_e32 v27, v27, v30
	v_min_u32_e32 v30, v25, v28
	v_max_u32_e32 v25, v25, v28
	v_min_u32_e32 v26, v23, v24
	v_max_u32_e32 v23, v23, v24
	v_min_u32_e32 v12, v7, v11
	v_max_u32_e32 v7, v7, v11
	v_min_u32_e32 v6, v2, v5
	v_min_u32_e32 v28, v25, v26
	v_max_u32_e32 v25, v25, v26
	v_min_u32_e32 v24, v23, v22
	v_max_u32_e32 v22, v23, v22
	v_min_u32_e32 v8, v7, v6
	v_max_u32_e32 v6, v7, v6
	v_max_u32_e32 v2, v2, v5
	v_and_b32_e32 v5, 0x7fffff80, v44
	v_bitop3_b32 v7, v44, s61, v44 bitop3:0xcf
	v_cmp_gt_i32_e32 vcc, 0, v44
	v_min_u32_e32 v26, v25, v24
	v_max_u32_e32 v24, v25, v24
	v_min_u32_e32 v21, v22, v19
	v_max_u32_e32 v19, v22, v19
	v_min_u32_e32 v22, v16, v20
	v_max_u32_e32 v16, v16, v20
	v_min_u32_e32 v20, v13, v17
	v_max_u32_e32 v13, v13, v17
	v_min_u32_e32 v17, v10, v14
	v_max_u32_e32 v10, v10, v14
	v_min_u32_e32 v14, v9, v12
	v_max_u32_e32 v9, v9, v12
	v_cndmask_b32_e32 v5, v7, v5, vcc
	v_min_u32_e32 v23, v24, v21
	v_max_u32_e32 v21, v24, v21
	v_min_u32_e32 v24, v18, v22
	v_max_u32_e32 v18, v18, v22
	v_min_u32_e32 v22, v16, v20
	v_max_u32_e32 v16, v16, v20
	v_min_u32_e32 v20, v13, v17
	v_max_u32_e32 v13, v13, v17
	v_min_u32_e32 v17, v10, v14
	v_max_u32_e32 v10, v10, v14
	v_min_u32_e32 v11, v9, v8
	v_add_f32_e32 v7, v5, v1
	v_min_u32_e32 v12, v10, v11
	v_max_u32_e32 v10, v10, v11
	v_max_u32_e32 v8, v9, v8
	v_not_b32_e32 v9, v7
	v_or_b32_e32 v11, 0x80000000, v7
	v_cmp_gt_i32_e32 vcc, 0, v7
	v_min_u32_e32 v69, v72, v69
	v_min_u32_e32 v72, v67, v71
	v_cndmask_b32_e32 v7, v11, v9, vcc
	v_max_u32_e32 v67, v67, v71
	v_min_u32_e32 v71, v65, v68
	v_max_u32_e32 v65, v65, v68
	v_min_u32_e32 v68, v31, v66
	v_max_u32_e32 v31, v31, v66
	v_min_u32_e32 v66, v29, v64
	v_max_u32_e32 v29, v29, v64
	v_min_u32_e32 v64, v27, v30
	v_max_u32_e32 v27, v27, v30
	v_and_b32_e32 v7, 0xffffff00, v7
	v_min_u32_e32 v30, v27, v28
	v_max_u32_e32 v27, v27, v28
	v_or_b32_e32 v7, 0xcf, v7
	v_min_u32_e32 v28, v27, v26
	v_max_u32_e32 v26, v27, v26
	v_min_u32_e32 v9, v2, v7
	v_min_u32_e32 v25, v26, v23
	v_max_u32_e32 v23, v26, v23
	v_min_u32_e32 v26, v19, v24
	v_max_u32_e32 v19, v19, v24
	v_min_u32_e32 v24, v18, v22
	v_max_u32_e32 v18, v18, v22
	v_min_u32_e32 v22, v16, v20
	v_max_u32_e32 v16, v16, v20
	v_min_u32_e32 v20, v13, v17
	v_max_u32_e32 v13, v13, v17
	v_min_u32_e32 v11, v6, v9
	v_max_u32_e32 v2, v2, v7
	v_add_f32_e32 v7, v5, v0
	v_min_u32_e32 v14, v13, v12
	v_max_u32_e32 v12, v13, v12
	v_min_u32_e32 v13, v8, v11
	v_max_u32_e32 v8, v8, v11
	v_max_u32_e32 v6, v6, v9
	v_not_b32_e32 v9, v7
	v_or_b32_e32 v11, 0x80000000, v7
	v_cmp_gt_i32_e32 vcc, 0, v7
	v_min_u32_e32 v73, v70, v72
	v_max_u32_e32 v70, v70, v72
	v_cndmask_b32_e32 v7, v11, v9, vcc
	v_min_u32_e32 v72, v67, v71
	v_max_u32_e32 v67, v67, v71
	v_min_u32_e32 v71, v65, v68
	v_max_u32_e32 v65, v65, v68
	v_min_u32_e32 v68, v31, v66
	v_max_u32_e32 v31, v31, v66
	v_min_u32_e32 v66, v29, v64
	v_max_u32_e32 v29, v29, v64
	v_and_b32_e32 v7, 0xffffff00, v7
	v_min_u32_e32 v64, v29, v30
	v_max_u32_e32 v29, v29, v30
	v_or_b32_e32 v7, 0xce, v7
	v_min_u32_e32 v30, v29, v28
	v_max_u32_e32 v28, v29, v28
	v_min_u32_e32 v9, v2, v7
	v_min_u32_e32 v27, v28, v25
	v_max_u32_e32 v25, v28, v25
	v_min_u32_e32 v28, v21, v26
	v_max_u32_e32 v21, v21, v26
	v_min_u32_e32 v26, v19, v24
	v_max_u32_e32 v19, v19, v24
	v_min_u32_e32 v24, v18, v22
	v_max_u32_e32 v18, v18, v22
	v_min_u32_e32 v22, v16, v20
	v_max_u32_e32 v16, v16, v20
	v_min_u32_e32 v11, v6, v9
	v_max_u32_e32 v2, v2, v7
	v_add_f32_e32 v7, v5, v3
	v_min_u32_e32 v17, v16, v14
	v_max_u32_e32 v14, v16, v14
	v_min_u32_e32 v16, v10, v13
	v_max_u32_e32 v10, v10, v13
	v_min_u32_e32 v13, v8, v11
	v_max_u32_e32 v8, v8, v11
	v_max_u32_e32 v6, v6, v9
	v_not_b32_e32 v9, v7
	v_or_b32_e32 v11, 0x80000000, v7
	v_cmp_gt_i32_e32 vcc, 0, v7
	v_add_f32_e32 v4, v5, v4
	v_not_b32_e32 v5, v4
	v_cndmask_b32_e32 v7, v11, v9, vcc
	v_and_b32_e32 v7, 0xffffff00, v7
	v_or_b32_e32 v7, 0xcd, v7
	v_min_u32_e32 v9, v2, v7
	v_max_u32_e32 v2, v2, v7
	v_or_b32_e32 v7, 0x80000000, v4
	v_cmp_gt_i32_e32 vcc, 0, v4
; DI unsigned f2ord(float f) { unsigned u = __float_as_uint(f); return (u & 0x80000000u) ? ~u : (u | 0x80000000u); }
; DI float ord2f(unsigned u) { return __uint_as_float((u & 0x80000000u) ? (u & 0x7fffffffu) : ~u); }
; #define INS32(T, X) { _Pragma("unroll") for (int jj = 0; jj < 16; ++jj) { unsigned t_ = max(T[jj], X); X = min(T[jj], X); T[jj] = t_; } }
; __device__ __forceinline__ void route_task(const Params& p, int layer, const u16* qg, int rb, int hd, int r, int h) {
;     ...
; #pragma unroll
;     for (int a = 0; a < 16; ++a) {
;       const float va = ord2f(top[0][a] & ~127u);
; #pragma unroll
;       for (int b = 0; b < 16; ++b) {
;         if ((a + 1) * (b + 1) <= 16) {
;           const float vb = ord2f(top[1][b] & ~127u);
;           unsigned key = (f2ord(va + vb) & ~255u) | (unsigned)(255 - (a * 16 + b));
;           INS32(ct, key);
;         }
;       }
;     }
	v_min_u32_e32 v74, v70, v72
	v_max_u32_e32 v70, v70, v72
	v_cndmask_b32_e32 v4, v7, v5, vcc
	v_min_u32_e32 v72, v67, v71
	v_max_u32_e32 v67, v67, v71
	v_min_u32_e32 v71, v65, v68
	v_max_u32_e32 v65, v65, v68
	v_min_u32_e32 v68, v31, v66
	v_max_u32_e32 v31, v31, v66
	v_and_b32_e32 v4, 0xffffff00, v4
	v_max3_u32 v69, v69, v73, v74
	v_min_u32_e32 v73, v70, v72
	v_max_u32_e32 v70, v70, v72
	v_min_u32_e32 v72, v67, v71
	v_max_u32_e32 v67, v67, v71
	v_min_u32_e32 v71, v65, v68
	v_max_u32_e32 v65, v65, v68
	v_min_u32_e32 v66, v31, v64
	v_max_u32_e32 v31, v31, v64
	v_or_b32_e32 v4, 0xcc, v4
	v_min_u32_e32 v68, v65, v66
	v_max_u32_e32 v65, v65, v66
	v_min_u32_e32 v64, v31, v30
	v_max_u32_e32 v30, v31, v30
	v_min_u32_e32 v11, v6, v9
	v_max_u32_e32 v6, v6, v9
	v_min_u32_e32 v5, v2, v4
	v_min_u32_e32 v66, v65, v64
	v_max_u32_e32 v64, v65, v64
	v_min_u32_e32 v29, v30, v27
	v_max_u32_e32 v27, v30, v27
	v_min_u32_e32 v30, v23, v28
	v_max_u32_e32 v23, v23, v28
	v_min_u32_e32 v28, v21, v26
	v_max_u32_e32 v21, v21, v26
	v_min_u32_e32 v26, v19, v24
	v_max_u32_e32 v19, v19, v24
	v_min_u32_e32 v24, v18, v22
	v_max_u32_e32 v18, v18, v22
	v_min_u32_e32 v7, v6, v5
	v_max_u32_e32 v5, v6, v5
	v_max_u32_e32 v2, v2, v4
	v_and_b32_e32 v4, 0x7fffff80, v43
	v_bitop3_b32 v6, v43, s61, v43 bitop3:0xcf
	v_cmp_gt_i32_e32 vcc, 0, v43
	v_min_u32_e32 v31, v64, v29
	v_max_u32_e32 v29, v64, v29
	v_min_u32_e32 v64, v25, v30
	v_max_u32_e32 v25, v25, v30
	v_min_u32_e32 v30, v23, v28
	v_max_u32_e32 v23, v23, v28
	v_min_u32_e32 v28, v21, v26
	v_max_u32_e32 v21, v21, v26
	v_min_u32_e32 v26, v19, v24
	v_max_u32_e32 v19, v19, v24
	v_min_u32_e32 v20, v18, v17
	v_max_u32_e32 v17, v18, v17
	v_min_u32_e32 v18, v12, v16
	v_max_u32_e32 v12, v12, v16
	v_min_u32_e32 v16, v10, v13
	v_max_u32_e32 v10, v10, v13
	v_min_u32_e32 v13, v8, v11
	v_max_u32_e32 v8, v8, v11
	v_cndmask_b32_e32 v4, v6, v4, vcc
	v_min_u32_e32 v22, v19, v20
	v_max_u32_e32 v19, v19, v20
	v_min_u32_e32 v20, v14, v18
	v_max_u32_e32 v14, v14, v18
	v_min_u32_e32 v18, v12, v16
	v_max_u32_e32 v12, v12, v16
	v_min_u32_e32 v16, v10, v13
	v_max_u32_e32 v10, v10, v13
	v_min_u32_e32 v9, v8, v7
	v_add_f32_e32 v6, v4, v1
	v_min_u32_e32 v11, v10, v9
	v_max_u32_e32 v9, v10, v9
	v_max_u32_e32 v7, v8, v7
	v_not_b32_e32 v8, v6
	v_or_b32_e32 v10, 0x80000000, v6
	v_cmp_gt_i32_e32 vcc, 0, v6
	v_min_u32_e32 v74, v70, v72
	v_max_u32_e32 v70, v70, v72
	v_min_u32_e32 v72, v67, v71
	v_max_u32_e32 v67, v67, v71
	v_cndmask_b32_e32 v6, v10, v8, vcc
	v_min_u32_e32 v71, v67, v68
	v_max_u32_e32 v67, v67, v68
	v_and_b32_e32 v6, 0xffffff00, v6
	v_min_u32_e32 v68, v67, v66
	v_max_u32_e32 v66, v67, v66
	v_or_b32_e32 v6, 0xbf, v6
	v_min_u32_e32 v65, v66, v31
	v_max_u32_e32 v31, v66, v31
	v_min_u32_e32 v66, v27, v64
	v_max_u32_e32 v27, v27, v64
	v_min_u32_e32 v64, v25, v30
	v_max_u32_e32 v25, v25, v30
	v_min_u32_e32 v30, v23, v28
	v_max_u32_e32 v23, v23, v28
	v_min_u32_e32 v28, v21, v26
	v_max_u32_e32 v21, v21, v26
	v_min_u32_e32 v8, v2, v6
	v_min_u32_e32 v24, v21, v22
	v_max_u32_e32 v21, v21, v22
	v_min_u32_e32 v22, v17, v20
	v_max_u32_e32 v17, v17, v20
	v_min_u32_e32 v20, v14, v18
	v_max_u32_e32 v14, v14, v18
	v_min_u32_e32 v18, v12, v16
	v_max_u32_e32 v12, v12, v16
	v_min_u32_e32 v10, v5, v8
	v_max_u32_e32 v2, v2, v6
	v_add_f32_e32 v6, v4, v0
	v_min_u32_e32 v13, v12, v11
	v_max_u32_e32 v11, v12, v11
	v_min_u32_e32 v12, v7, v10
	v_max_u32_e32 v7, v7, v10
	v_max_u32_e32 v5, v5, v8
	v_not_b32_e32 v8, v6
	v_or_b32_e32 v10, 0x80000000, v6
	v_cmp_gt_i32_e32 vcc, 0, v6
	v_add_f32_e32 v3, v4, v3
	v_not_b32_e32 v4, v3
	v_cndmask_b32_e32 v6, v10, v8, vcc
	v_and_b32_e32 v6, 0xffffff00, v6
	v_or_b32_e32 v6, 0xbe, v6
	v_min_u32_e32 v8, v2, v6
	v_max_u32_e32 v2, v2, v6
	v_or_b32_e32 v6, 0x80000000, v3
	v_cmp_gt_i32_e32 vcc, 0, v3
	v_max3_u32 v69, v69, v73, v74
	v_min_u32_e32 v73, v70, v72
	v_max_u32_e32 v70, v70, v72
	v_cndmask_b32_e32 v3, v6, v4, vcc
	v_min_u32_e32 v72, v70, v71
	v_max_u32_e32 v70, v70, v71
	v_and_b32_e32 v3, 0xffffff00, v3
	v_min_u32_e32 v71, v70, v68
	v_max_u32_e32 v68, v70, v68
	v_or_b32_e32 v3, 0xbd, v3
	v_max3_u32 v69, v69, v73, v72
	v_min_u32_e32 v67, v68, v65
	v_max_u32_e32 v65, v68, v65
	v_min_u32_e32 v68, v29, v66
	v_max_u32_e32 v29, v29, v66
	v_min_u32_e32 v66, v27, v64
	v_max_u32_e32 v27, v27, v64
	v_min_u32_e32 v64, v25, v30
	v_max_u32_e32 v25, v25, v30
	v_min_u32_e32 v30, v23, v28
	v_max_u32_e32 v23, v23, v28
	v_min_u32_e32 v10, v5, v8
	v_max_u32_e32 v5, v5, v8
	v_min_u32_e32 v4, v2, v3
	v_max3_u32 v67, v69, v71, v67
	v_min_u32_e32 v69, v31, v68
	v_max_u32_e32 v31, v31, v68
	v_min_u32_e32 v68, v29, v66
	v_max_u32_e32 v29, v29, v66
	v_min_u32_e32 v66, v27, v64
	v_max_u32_e32 v27, v27, v64
	v_min_u32_e32 v64, v25, v30
	v_max_u32_e32 v25, v25, v30
	v_min_u32_e32 v26, v23, v24
	v_max_u32_e32 v23, v23, v24
	v_min_u32_e32 v24, v19, v22
	v_max_u32_e32 v19, v19, v22
	v_min_u32_e32 v22, v17, v20
	v_max_u32_e32 v17, v17, v20
	v_min_u32_e32 v20, v14, v18
	v_max_u32_e32 v14, v14, v18
	v_min_u32_e32 v6, v5, v4
	v_max_u32_e32 v4, v5, v4
	v_max_u32_e32 v2, v2, v3
	v_and_b32_e32 v3, 0x7fffff80, v42
	v_bitop3_b32 v5, v42, s61, v42 bitop3:0xcf
	v_cmp_gt_i32_e32 vcc, 0, v42
	v_min_u32_e32 v28, v25, v26
	v_max_u32_e32 v25, v25, v26
	v_min_u32_e32 v26, v21, v24
	v_max_u32_e32 v21, v21, v24
	v_min_u32_e32 v24, v19, v22
	v_max_u32_e32 v19, v19, v22
	v_min_u32_e32 v22, v17, v20
	v_max_u32_e32 v17, v17, v20
	v_min_u32_e32 v16, v14, v13
	v_max_u32_e32 v13, v14, v13
	v_min_u32_e32 v14, v9, v12
	v_max_u32_e32 v9, v9, v12
	v_min_u32_e32 v12, v7, v10
	v_max_u32_e32 v7, v7, v10
	v_cndmask_b32_e32 v3, v5, v3, vcc
	v_min_u32_e32 v18, v17, v16
	v_max_u32_e32 v16, v17, v16
; DI unsigned f2ord(float f) { unsigned u = __float_as_uint(f); return (u & 0x80000000u) ? ~u : (u | 0x80000000u); }
; DI float ord2f(unsigned u) { return __uint_as_float((u & 0x80000000u) ? (u & 0x7fffffffu) : ~u); }
; #define INS32(T, X) { _Pragma("unroll") for (int jj = 0; jj < 16; ++jj) { unsigned t_ = max(T[jj], X); X = min(T[jj], X); T[jj] = t_; } }
; __device__ __forceinline__ void route_task(const Params& p, int layer, const u16* qg, int rb, int hd, int r, int h) {
;     ...
; #pragma unroll
;     for (int a = 0; a < 16; ++a) {
;       const float va = ord2f(top[0][a] & ~127u);
; #pragma unroll
;       for (int b = 0; b < 16; ++b) {
;         if ((a + 1) * (b + 1) <= 16) {
;           const float vb = ord2f(top[1][b] & ~127u);
;           unsigned key = (f2ord(va + vb) & ~255u) | (unsigned)(255 - (a * 16 + b));
;           INS32(ct, key);
;         }
;       }
;     }
	v_min_u32_e32 v17, v11, v14
	v_max_u32_e32 v11, v11, v14
	v_min_u32_e32 v14, v9, v12
	v_max_u32_e32 v9, v9, v12
	v_min_u32_e32 v8, v7, v6
	v_add_f32_e32 v5, v3, v1
	v_min_u32_e32 v10, v9, v8
	v_max_u32_e32 v8, v9, v8
	v_max_u32_e32 v6, v7, v6
	v_not_b32_e32 v7, v5
	v_or_b32_e32 v9, 0x80000000, v5
	v_cmp_gt_i32_e32 vcc, 0, v5
	v_add_f32_e32 v3, v3, v0
	v_min_u32_e32 v70, v65, v69
	v_cndmask_b32_e32 v5, v9, v7, vcc
	v_and_b32_e32 v5, 0xffffff00, v5
	v_or_b32_e32 v5, 0xaf, v5
	v_min_u32_e32 v7, v2, v5
	v_min_u32_e32 v9, v4, v7
	v_max_u32_e32 v4, v4, v7
	v_max_u32_e32 v2, v2, v5
	v_not_b32_e32 v5, v3
	v_or_b32_e32 v7, 0x80000000, v3
	v_cmp_gt_i32_e32 vcc, 0, v3
	v_max_u32_e32 v65, v65, v69
	v_min_u32_e32 v69, v31, v68
	v_cndmask_b32_e32 v3, v7, v5, vcc
	v_and_b32_e32 v3, 0xffffff00, v3
	v_max_u32_e32 v31, v31, v68
	v_min_u32_e32 v68, v29, v66
	v_max_u32_e32 v29, v29, v66
	v_min_u32_e32 v66, v27, v64
	v_max_u32_e32 v27, v27, v64
	v_or_b32_e32 v3, 0xae, v3
	v_min_u32_e32 v71, v65, v69
	v_max_u32_e32 v65, v65, v69
	v_min_u32_e32 v69, v31, v68
	v_max_u32_e32 v31, v31, v68
	v_min_u32_e32 v68, v29, v66
	v_max_u32_e32 v29, v29, v66
	v_min_u32_e32 v30, v27, v28
	v_max_u32_e32 v27, v27, v28
	v_min_u32_e32 v28, v23, v26
	v_max_u32_e32 v23, v23, v26
	v_min_u32_e32 v26, v21, v24
	v_max_u32_e32 v21, v21, v24
	v_min_u32_e32 v24, v19, v22
	v_max_u32_e32 v19, v19, v22
	v_min_u32_e32 v5, v2, v3
	v_min_u32_e32 v64, v29, v30
	v_max_u32_e32 v29, v29, v30
	v_min_u32_e32 v30, v25, v28
	v_max_u32_e32 v25, v25, v28
	v_min_u32_e32 v28, v23, v26
	v_max_u32_e32 v23, v23, v26
	v_min_u32_e32 v26, v21, v24
	v_max_u32_e32 v21, v21, v24
	v_min_u32_e32 v20, v19, v18
	v_max_u32_e32 v18, v19, v18
	v_min_u32_e32 v19, v13, v17
	v_max_u32_e32 v13, v13, v17
	v_min_u32_e32 v17, v11, v14
	v_max_u32_e32 v11, v11, v14
	v_min_u32_e32 v7, v4, v5
	v_max_u32_e32 v4, v4, v5
	v_max_u32_e32 v2, v2, v3
	v_and_b32_e32 v3, 0x7fffff80, v41
	v_bitop3_b32 v5, v41, s61, v41 bitop3:0xcf
	v_cmp_gt_i32_e32 vcc, 0, v41
	v_min_u32_e32 v22, v21, v20
	v_max_u32_e32 v20, v21, v20
	v_min_u32_e32 v21, v16, v19
	v_max_u32_e32 v16, v16, v19
	v_min_u32_e32 v19, v13, v17
	v_max_u32_e32 v13, v13, v17
	v_min_u32_e32 v12, v11, v10
	v_max_u32_e32 v10, v11, v10
	v_min_u32_e32 v11, v6, v9
	v_max_u32_e32 v6, v6, v9
	v_cndmask_b32_e32 v3, v5, v3, vcc
	v_min_u32_e32 v14, v13, v12
	v_max_u32_e32 v12, v13, v12
	v_min_u32_e32 v13, v8, v11
	v_max_u32_e32 v8, v8, v11
	v_min_u32_e32 v9, v6, v7
	v_add_f32_e32 v5, v3, v1
	v_min_u32_e32 v11, v8, v9
	v_max_u32_e32 v8, v8, v9
	v_max_u32_e32 v6, v6, v7
	v_not_b32_e32 v7, v5
	v_or_b32_e32 v9, 0x80000000, v5
	v_cmp_gt_i32_e32 vcc, 0, v5
	v_add_f32_e32 v3, v3, v0
	v_max3_u32 v67, v67, v70, v71
	v_cndmask_b32_e32 v5, v9, v7, vcc
	v_and_b32_e32 v5, 0xffffff00, v5
	v_or_b32_e32 v5, 0x9f, v5
	v_min_u32_e32 v7, v2, v5
	v_min_u32_e32 v9, v4, v7
	v_max_u32_e32 v4, v4, v7
	v_max_u32_e32 v2, v2, v5
	v_not_b32_e32 v5, v3
	v_or_b32_e32 v7, 0x80000000, v3
	v_cmp_gt_i32_e32 vcc, 0, v3
	v_min_u32_e32 v70, v65, v69
	v_max_u32_e32 v65, v65, v69
	v_cndmask_b32_e32 v3, v7, v5, vcc
	v_min_u32_e32 v69, v31, v68
	v_max_u32_e32 v31, v31, v68
	v_and_b32_e32 v3, 0xffffff00, v3
	v_min_u32_e32 v71, v65, v69
	v_max_u32_e32 v65, v65, v69
	v_min_u32_e32 v66, v31, v64
	v_max_u32_e32 v31, v31, v64
	v_min_u32_e32 v64, v27, v30
	v_max_u32_e32 v27, v27, v30
	v_min_u32_e32 v30, v25, v28
	v_max_u32_e32 v25, v25, v28
	v_min_u32_e32 v28, v23, v26
	v_max_u32_e32 v23, v23, v26
	v_or_b32_e32 v3, 0x9e, v3
	v_min_u32_e32 v68, v65, v66
	v_max_u32_e32 v65, v65, v66
	v_min_u32_e32 v66, v29, v64
	v_max_u32_e32 v29, v29, v64
	v_min_u32_e32 v64, v27, v30
	v_max_u32_e32 v27, v27, v30
	v_min_u32_e32 v30, v25, v28
	v_max_u32_e32 v25, v25, v28
	v_min_u32_e32 v24, v23, v22
	v_max_u32_e32 v22, v23, v22
	v_min_u32_e32 v23, v18, v21
	v_max_u32_e32 v18, v18, v21
	v_min_u32_e32 v21, v16, v19
	v_max_u32_e32 v16, v16, v19
	v_min_u32_e32 v5, v2, v3
	v_min_u32_e32 v26, v25, v24
	v_max_u32_e32 v24, v25, v24
	v_min_u32_e32 v25, v20, v23
	v_max_u32_e32 v20, v20, v23
	v_min_u32_e32 v23, v18, v21
	v_max_u32_e32 v18, v18, v21
	v_min_u32_e32 v17, v16, v14
	v_max_u32_e32 v14, v16, v14
	v_min_u32_e32 v16, v10, v13
	v_max_u32_e32 v10, v10, v13
	v_min_u32_e32 v7, v4, v5
	v_max_u32_e32 v4, v4, v5
	v_max_u32_e32 v2, v2, v3
	v_and_b32_e32 v3, 0x7fffff80, v40
	v_bitop3_b32 v5, v40, s61, v40 bitop3:0xcf
	v_cmp_gt_i32_e32 vcc, 0, v40
	v_min_u32_e32 v19, v18, v17
	v_max_u32_e32 v17, v18, v17
	v_min_u32_e32 v18, v12, v16
	v_max_u32_e32 v12, v12, v16
	v_min_u32_e32 v13, v10, v11
	v_max_u32_e32 v10, v10, v11
	v_min_u32_e32 v11, v6, v9
	v_max_u32_e32 v6, v6, v9
	v_cndmask_b32_e32 v3, v5, v3, vcc
	v_min_u32_e32 v16, v12, v13
	v_max_u32_e32 v12, v12, v13
	v_min_u32_e32 v13, v8, v11
	v_max_u32_e32 v8, v8, v11
	v_min_u32_e32 v9, v6, v7
	v_add_f32_e32 v5, v3, v1
	v_min_u32_e32 v11, v8, v9
	v_max_u32_e32 v8, v8, v9
	v_max_u32_e32 v6, v6, v7
	v_not_b32_e32 v7, v5
	v_or_b32_e32 v9, 0x80000000, v5
	v_cmp_gt_i32_e32 vcc, 0, v5
	v_add_f32_e32 v0, v3, v0
	v_not_b32_e32 v3, v0
	v_cndmask_b32_e32 v5, v9, v7, vcc
	v_and_b32_e32 v5, 0xffffff00, v5
	v_or_b32_e32 v5, 0x8f, v5
	v_min_u32_e32 v7, v2, v5
	v_max_u32_e32 v2, v2, v5
	v_or_b32_e32 v5, 0x80000000, v0
	v_cmp_gt_i32_e32 vcc, 0, v0
	v_min_u32_e32 v69, v31, v66
	v_max_u32_e32 v31, v31, v66
	v_cndmask_b32_e32 v0, v5, v3, vcc
	v_and_b32_e32 v0, 0xffffff00, v0
	v_min_u32_e32 v66, v29, v64
	v_max_u32_e32 v29, v29, v64
	v_min_u32_e32 v64, v27, v30
	v_max_u32_e32 v27, v27, v30
	v_or_b32_e32 v0, 0x8e, v0
	v_min_u32_e32 v28, v27, v26
	v_max_u32_e32 v26, v27, v26
	v_min_u32_e32 v27, v22, v25
	v_max_u32_e32 v22, v22, v25
	v_min_u32_e32 v25, v20, v23
; DI unsigned f2ord(float f) { unsigned u = __float_as_uint(f); return (u & 0x80000000u) ? ~u : (u | 0x80000000u); }
; DI float ord2f(unsigned u) { return __uint_as_float((u & 0x80000000u) ? (u & 0x7fffffffu) : ~u); }
; #define INS32(T, X) { _Pragma("unroll") for (int jj = 0; jj < 16; ++jj) { unsigned t_ = max(T[jj], X); X = min(T[jj], X); T[jj] = t_; } }
; __device__ __forceinline__ void route_task(const Params& p, int layer, const u16* qg, int rb, int hd, int r, int h) {
;     ...
; #pragma unroll
;     for (int a = 0; a < 16; ++a) {
;       const float va = ord2f(top[0][a] & ~127u);
; #pragma unroll
;       for (int b = 0; b < 16; ++b) {
;         if ((a + 1) * (b + 1) <= 16) {
;           const float vb = ord2f(top[1][b] & ~127u);
;           unsigned key = (f2ord(va + vb) & ~255u) | (unsigned)(255 - (a * 16 + b));
;           INS32(ct, key);
;         }
;       }
;     }
	v_max_u32_e32 v20, v20, v23
	v_min_u32_e32 v9, v4, v7
	v_max_u32_e32 v4, v4, v7
	v_min_u32_e32 v3, v2, v0
	v_min_u32_e32 v21, v20, v19
	v_max_u32_e32 v19, v20, v19
	v_min_u32_e32 v20, v14, v18
	v_max_u32_e32 v14, v14, v18
	v_min_u32_e32 v5, v4, v3
	v_max_u32_e32 v3, v4, v3
	v_max_u32_e32 v0, v2, v0
	v_and_b32_e32 v2, 0x7fffff80, v39
	v_bitop3_b32 v4, v39, s61, v39 bitop3:0xcf
	v_cmp_gt_i32_e32 vcc, 0, v39
	v_min_u32_e32 v18, v14, v16
	v_max_u32_e32 v14, v14, v16
	v_min_u32_e32 v16, v10, v13
	v_max_u32_e32 v10, v10, v13
	v_cndmask_b32_e32 v2, v4, v2, vcc
	v_min_u32_e32 v13, v10, v11
	v_max_u32_e32 v10, v10, v11
	v_min_u32_e32 v11, v6, v9
	v_max_u32_e32 v6, v6, v9
	v_add_f32_e32 v2, v2, v1
	v_min_u32_e32 v7, v6, v5
	v_max_u32_e32 v5, v6, v5
	v_not_b32_e32 v4, v2
	v_or_b32_e32 v6, 0x80000000, v2
	v_cmp_gt_i32_e32 vcc, 0, v2
	v_max3_u32 v67, v67, v70, v71
	v_min_u32_e32 v70, v65, v69
	v_cndmask_b32_e32 v2, v6, v4, vcc
	v_and_b32_e32 v2, 0xffffff00, v2
	v_max3_u32 v67, v67, v68, v70
	v_min_u32_e32 v68, v31, v66
	v_max_u32_e32 v31, v31, v66
	v_min_u32_e32 v66, v29, v64
	v_max_u32_e32 v29, v29, v64
	v_or_b32_e32 v2, 0x7f, v2
	v_min_u32_e32 v30, v29, v28
	v_max_u32_e32 v28, v29, v28
	v_min_u32_e32 v29, v24, v27
	v_max_u32_e32 v24, v24, v27
	v_min_u32_e32 v27, v22, v25
	v_max_u32_e32 v22, v22, v25
	v_min_u32_e32 v4, v0, v2
	v_min_u32_e32 v23, v22, v21
	v_max_u32_e32 v21, v22, v21
	v_min_u32_e32 v22, v17, v20
	v_max_u32_e32 v17, v17, v20
	v_min_u32_e32 v6, v3, v4
	v_max_u32_e32 v3, v3, v4
	v_max_u32_e32 v0, v0, v2
	v_and_b32_e32 v2, 0x7fffff80, v38
	v_bitop3_b32 v4, v38, s61, v38 bitop3:0xcf
	v_cmp_gt_i32_e32 vcc, 0, v38
	v_min_u32_e32 v20, v17, v18
	v_max_u32_e32 v17, v17, v18
	v_min_u32_e32 v18, v12, v16
	v_max_u32_e32 v12, v12, v16
	v_cndmask_b32_e32 v2, v4, v2, vcc
	v_min_u32_e32 v16, v12, v13
	v_max_u32_e32 v12, v12, v13
	v_min_u32_e32 v13, v8, v11
	v_max_u32_e32 v8, v8, v11
	v_add_f32_e32 v2, v2, v1
	v_min_u32_e32 v9, v8, v7
	v_max_u32_e32 v7, v8, v7
	v_min_u32_e32 v8, v5, v6
	v_max_u32_e32 v5, v5, v6
	v_not_b32_e32 v4, v2
	v_or_b32_e32 v6, 0x80000000, v2
	v_cmp_gt_i32_e32 vcc, 0, v2
	v_max_u32_e32 v65, v65, v69
	v_min_u32_e32 v69, v65, v68
	v_cndmask_b32_e32 v2, v6, v4, vcc
	v_and_b32_e32 v2, 0xffffff00, v2
	v_max_u32_e32 v65, v65, v68
	v_min_u32_e32 v68, v31, v66
	v_max_u32_e32 v31, v31, v66
	v_or_b32_e32 v2, 0x6f, v2
	v_min_u32_e32 v64, v31, v30
	v_max_u32_e32 v30, v31, v30
	v_min_u32_e32 v31, v26, v29
	v_max_u32_e32 v26, v26, v29
	v_min_u32_e32 v29, v24, v27
	v_max_u32_e32 v24, v24, v27
	v_min_u32_e32 v4, v0, v2
	v_min_u32_e32 v25, v24, v23
	v_max_u32_e32 v23, v24, v23
	v_min_u32_e32 v24, v19, v22
	v_max_u32_e32 v19, v19, v22
	v_min_u32_e32 v6, v3, v4
	v_max_u32_e32 v3, v3, v4
	v_max_u32_e32 v0, v0, v2
	v_and_b32_e32 v2, 0x7fffff80, v37
	v_bitop3_b32 v4, v37, s61, v37 bitop3:0xcf
	v_cmp_gt_i32_e32 vcc, 0, v37
	v_min_u32_e32 v22, v19, v20
	v_max_u32_e32 v19, v19, v20
	v_min_u32_e32 v20, v14, v18
	v_max_u32_e32 v14, v14, v18
	v_cndmask_b32_e32 v2, v4, v2, vcc
	v_min_u32_e32 v18, v14, v16
	v_max_u32_e32 v14, v14, v16
	v_min_u32_e32 v16, v10, v13
	v_max_u32_e32 v10, v10, v13
	v_add_f32_e32 v2, v2, v1
	v_min_u32_e32 v11, v10, v9
	v_max_u32_e32 v9, v10, v9
	v_min_u32_e32 v10, v7, v8
	v_max_u32_e32 v7, v7, v8
	v_min_u32_e32 v8, v5, v6
	v_max_u32_e32 v5, v5, v6
	v_not_b32_e32 v4, v2
	v_or_b32_e32 v6, 0x80000000, v2
	v_cmp_gt_i32_e32 vcc, 0, v2
	v_min_u32_e32 v70, v65, v68
	v_max_u32_e32 v65, v65, v68
	v_cndmask_b32_e32 v2, v6, v4, vcc
	v_and_b32_e32 v2, 0xffffff00, v2
	v_or_b32_e32 v2, 0x5f, v2
	v_min_u32_e32 v66, v65, v64
	v_max_u32_e32 v64, v65, v64
	v_min_u32_e32 v65, v28, v31
	v_max_u32_e32 v28, v28, v31
	v_min_u32_e32 v31, v26, v29
	v_max_u32_e32 v26, v26, v29
	v_min_u32_e32 v4, v0, v2
	v_min_u32_e32 v27, v26, v25
	v_max_u32_e32 v25, v26, v25
	v_min_u32_e32 v26, v21, v24
	v_max_u32_e32 v21, v21, v24
	v_min_u32_e32 v6, v3, v4
	v_max_u32_e32 v3, v3, v4
	v_max_u32_e32 v0, v0, v2
	v_and_b32_e32 v2, 0x7fffff80, v36
	v_bitop3_b32 v4, v36, s61, v36 bitop3:0xcf
	v_cmp_gt_i32_e32 vcc, 0, v36
	v_min_u32_e32 v24, v21, v22
	v_max_u32_e32 v21, v21, v22
	v_min_u32_e32 v22, v17, v20
	v_max_u32_e32 v17, v17, v20
	v_cndmask_b32_e32 v2, v4, v2, vcc
	v_min_u32_e32 v20, v17, v18
	v_max_u32_e32 v17, v17, v18
	v_min_u32_e32 v18, v12, v16
	v_max_u32_e32 v12, v12, v16
	v_add_f32_e32 v2, v2, v1
	v_min_u32_e32 v13, v12, v11
	v_max_u32_e32 v11, v12, v11
	v_min_u32_e32 v12, v9, v10
	v_max_u32_e32 v9, v9, v10
	v_min_u32_e32 v10, v7, v8
	v_max_u32_e32 v7, v7, v8
	v_min_u32_e32 v8, v5, v6
	v_max_u32_e32 v5, v5, v6
	v_not_b32_e32 v4, v2
	v_or_b32_e32 v6, 0x80000000, v2
	v_cmp_gt_i32_e32 vcc, 0, v2
	v_min_u32_e32 v68, v30, v65
	v_max_u32_e32 v30, v30, v65
	v_cndmask_b32_e32 v2, v6, v4, vcc
	v_and_b32_e32 v2, 0xffffff00, v2
	v_or_b32_e32 v2, 0x4f, v2
	v_min_u32_e32 v65, v28, v31
	v_max_u32_e32 v28, v28, v31
	v_min_u32_e32 v4, v0, v2
	v_min_u32_e32 v29, v28, v27
	v_max_u32_e32 v27, v28, v27
	v_min_u32_e32 v28, v23, v26
	v_max_u32_e32 v23, v23, v26
	v_min_u32_e32 v6, v3, v4
	v_max_u32_e32 v3, v3, v4
	v_max_u32_e32 v0, v0, v2
	v_and_b32_e32 v2, 0x7fffff80, v35
	v_bitop3_b32 v4, v35, s61, v35 bitop3:0xcf
	v_cmp_gt_i32_e32 vcc, 0, v35
	v_min_u32_e32 v26, v23, v24
	v_max_u32_e32 v23, v23, v24
	v_min_u32_e32 v24, v19, v22
	v_max_u32_e32 v19, v19, v22
	v_cndmask_b32_e32 v2, v4, v2, vcc
	v_min_u32_e32 v22, v19, v20
	v_max_u32_e32 v19, v19, v20
	v_min_u32_e32 v20, v14, v18
	v_max_u32_e32 v14, v14, v18
	v_add_f32_e32 v2, v2, v1
	v_min_u32_e32 v16, v14, v13
	v_max_u32_e32 v13, v14, v13
	v_min_u32_e32 v14, v11, v12
	v_max_u32_e32 v11, v11, v12
	v_min_u32_e32 v12, v9, v10
; DI unsigned f2ord(float f) { unsigned u = __float_as_uint(f); return (u & 0x80000000u) ? ~u : (u | 0x80000000u); }
; DI float ord2f(unsigned u) { return __uint_as_float((u & 0x80000000u) ? (u & 0x7fffffffu) : ~u); }
; #define INS32(T, X) { _Pragma("unroll") for (int jj = 0; jj < 16; ++jj) { unsigned t_ = max(T[jj], X); X = min(T[jj], X); T[jj] = t_; } }
; __device__ __forceinline__ void route_task(const Params& p, int layer, const u16* qg, int rb, int hd, int r, int h) {
;     ...
; #pragma unroll
;     for (int a = 0; a < 16; ++a) {
;       const float va = ord2f(top[0][a] & ~127u);
; #pragma unroll
;       for (int b = 0; b < 16; ++b) {
;         if ((a + 1) * (b + 1) <= 16) {
;           const float vb = ord2f(top[1][b] & ~127u);
;           unsigned key = (f2ord(va + vb) & ~255u) | (unsigned)(255 - (a * 16 + b));
;           INS32(ct, key);
;         }
;       }
;     }
	v_max_u32_e32 v9, v9, v10
	v_min_u32_e32 v10, v7, v8
	v_max_u32_e32 v7, v7, v8
	v_min_u32_e32 v8, v5, v6
	v_max_u32_e32 v5, v5, v6
	v_not_b32_e32 v4, v2
	v_or_b32_e32 v6, 0x80000000, v2
	v_cmp_gt_i32_e32 vcc, 0, v2
	v_max3_u32 v67, v67, v69, v70
	v_min_u32_e32 v69, v64, v68
	v_cndmask_b32_e32 v2, v6, v4, vcc
	v_and_or_b32 v2, v2, s81, 63
	v_max3_u32 v66, v67, v66, v69
	v_min_u32_e32 v67, v30, v65
	v_max_u32_e32 v30, v30, v65
	v_min_u32_e32 v4, v0, v2
	v_min_u32_e32 v31, v30, v29
	v_max_u32_e32 v29, v30, v29
	v_min_u32_e32 v30, v25, v28
	v_max_u32_e32 v25, v25, v28
	v_min_u32_e32 v6, v3, v4
	v_max_u32_e32 v3, v3, v4
	v_max_u32_e32 v0, v0, v2
	v_and_b32_e32 v2, 0x7fffff80, v34
	v_bitop3_b32 v4, v34, s61, v34 bitop3:0xcf
	v_cmp_gt_i32_e32 vcc, 0, v34
	v_min_u32_e32 v28, v25, v26
	v_max_u32_e32 v25, v25, v26
	v_min_u32_e32 v26, v21, v24
	v_max_u32_e32 v21, v21, v24
	v_cndmask_b32_e32 v2, v4, v2, vcc
	v_min_u32_e32 v24, v21, v22
	v_max_u32_e32 v21, v21, v22
	v_min_u32_e32 v22, v17, v20
	v_max_u32_e32 v17, v17, v20
	v_add_f32_e32 v2, v2, v1
	v_min_u32_e32 v18, v17, v16
	v_max_u32_e32 v16, v17, v16
	v_min_u32_e32 v17, v13, v14
	v_max_u32_e32 v13, v13, v14
	v_min_u32_e32 v14, v11, v12
	v_max_u32_e32 v11, v11, v12
	v_min_u32_e32 v12, v9, v10
	v_max_u32_e32 v9, v9, v10
	v_min_u32_e32 v10, v7, v8
	v_max_u32_e32 v7, v7, v8
	v_min_u32_e32 v8, v5, v6
	v_max_u32_e32 v5, v5, v6
	v_not_b32_e32 v4, v2
	v_or_b32_e32 v6, 0x80000000, v2
	v_cmp_gt_i32_e32 vcc, 0, v2
	v_max_u32_e32 v64, v64, v68
	v_min_u32_e32 v68, v64, v67
	v_cndmask_b32_e32 v2, v6, v4, vcc
	v_and_or_b32 v2, v2, s81, 47
	v_max_u32_e32 v64, v64, v67
	v_min_u32_e32 v4, v0, v2
	v_min_u32_e32 v65, v64, v31
	v_max_u32_e32 v31, v64, v31
	v_min_u32_e32 v64, v27, v30
	v_max_u32_e32 v27, v27, v30
	v_min_u32_e32 v6, v3, v4
	v_max_u32_e32 v3, v3, v4
	v_max_u32_e32 v0, v0, v2
	v_and_b32_e32 v2, 0x7fffff80, v33
	v_bitop3_b32 v4, v33, s61, v33 bitop3:0xcf
	v_cmp_gt_i32_e32 vcc, 0, v33
	v_min_u32_e32 v30, v27, v28
	v_max_u32_e32 v27, v27, v28
	v_min_u32_e32 v28, v23, v26
	v_max_u32_e32 v23, v23, v26
	v_cndmask_b32_e32 v2, v4, v2, vcc
	v_min_u32_e32 v26, v23, v24
	v_max_u32_e32 v23, v23, v24
	v_min_u32_e32 v24, v19, v22
	v_max_u32_e32 v19, v19, v22
	v_add_f32_e32 v2, v2, v1
	v_min_u32_e32 v20, v19, v18
	v_max_u32_e32 v18, v19, v18
	v_min_u32_e32 v19, v16, v17
	v_max_u32_e32 v16, v16, v17
	v_min_u32_e32 v17, v13, v14
	v_max_u32_e32 v13, v13, v14
	v_min_u32_e32 v14, v11, v12
	v_max_u32_e32 v11, v11, v12
	v_min_u32_e32 v12, v9, v10
	v_max_u32_e32 v9, v9, v10
	v_min_u32_e32 v10, v7, v8
	v_max_u32_e32 v7, v7, v8
	v_min_u32_e32 v8, v5, v6
	v_max_u32_e32 v5, v5, v6
	v_not_b32_e32 v4, v2
	v_or_b32_e32 v6, 0x80000000, v2
	v_cmp_gt_i32_e32 vcc, 0, v2
	v_max3_u32 v65, v66, v68, v65
	v_min_u32_e32 v66, v29, v64
	v_cndmask_b32_e32 v2, v6, v4, vcc
	v_max_u32_e32 v29, v29, v64
	v_and_or_b32 v2, v2, s81, 31
	v_min_u32_e32 v67, v31, v66
	v_max_u32_e32 v31, v31, v66
	v_min_u32_e32 v64, v29, v30
	v_max_u32_e32 v29, v29, v30
	v_min_u32_e32 v30, v25, v28
	v_max_u32_e32 v25, v25, v28
	v_min_u32_e32 v4, v0, v2
	v_min_u32_e32 v66, v31, v64
	v_max_u32_e32 v31, v31, v64
	v_min_u32_e32 v64, v27, v30
	v_max_u32_e32 v27, v27, v30
	v_min_u32_e32 v28, v25, v26
	v_max_u32_e32 v25, v25, v26
	v_min_u32_e32 v26, v21, v24
	v_max_u32_e32 v21, v21, v24
	v_min_u32_e32 v6, v3, v4
	v_max3_u32 v65, v65, v67, v66
	v_min_u32_e32 v66, v29, v64
	v_max_u32_e32 v29, v29, v64
	v_min_u32_e32 v30, v27, v28
	v_max_u32_e32 v27, v27, v28
	v_min_u32_e32 v28, v23, v26
	v_max_u32_e32 v23, v23, v26
	v_min_u32_e32 v22, v21, v20
	v_max_u32_e32 v20, v21, v20
	v_min_u32_e32 v21, v18, v19
	v_max_u32_e32 v18, v18, v19
	v_min_u32_e32 v19, v16, v17
	v_max_u32_e32 v16, v16, v17
	v_min_u32_e32 v17, v13, v14
	v_max_u32_e32 v13, v13, v14
	v_min_u32_e32 v14, v11, v12
	v_max_u32_e32 v11, v11, v12
	v_min_u32_e32 v12, v9, v10
	v_max_u32_e32 v9, v9, v10
	v_min_u32_e32 v10, v7, v8
	v_max_u32_e32 v7, v7, v8
	v_min_u32_e32 v8, v5, v6
	v_min_u32_e32 v67, v31, v66
	v_max_u32_e32 v31, v31, v66
	v_min_u32_e32 v64, v29, v30
	v_max_u32_e32 v29, v29, v30
	v_min_u32_e32 v30, v25, v28
	v_max_u32_e32 v25, v25, v28
	v_min_u32_e32 v24, v23, v22
	v_max_u32_e32 v22, v23, v22
	v_min_u32_e32 v23, v20, v21
	v_max_u32_e32 v20, v20, v21
	v_min_u32_e32 v21, v18, v19
	v_max_u32_e32 v18, v18, v19
	v_min_u32_e32 v19, v16, v17
	v_max_u32_e32 v16, v16, v17
	v_min_u32_e32 v17, v13, v14
	v_max_u32_e32 v13, v13, v14
	v_min_u32_e32 v14, v11, v12
	v_max_u32_e32 v11, v11, v12
	v_min_u32_e32 v12, v9, v10
	v_max_u32_e32 v9, v9, v10
	v_min_u32_e32 v10, v7, v8
	v_max_u32_e32 v3, v3, v4
	v_max_u32_e32 v0, v0, v2
	v_and_b32_e32 v2, 0x7fffff80, v15
	v_bitop3_b32 v4, v15, s61, v15 bitop3:0xcf
	v_cmp_gt_i32_e32 vcc, 0, v15
	v_min_u32_e32 v66, v31, v64
	v_max_u32_e32 v31, v31, v64
	v_min_u32_e32 v64, v27, v30
	v_max_u32_e32 v27, v27, v30
	v_min_u32_e32 v26, v25, v24
	v_max_u32_e32 v24, v25, v24
	v_min_u32_e32 v25, v22, v23
	v_max_u32_e32 v22, v22, v23
	v_min_u32_e32 v23, v20, v21
	v_max_u32_e32 v20, v20, v21
	v_min_u32_e32 v21, v18, v19
	v_max_u32_e32 v18, v18, v19
	v_min_u32_e32 v19, v16, v17
	v_max_u32_e32 v16, v16, v17
	v_min_u32_e32 v17, v13, v14
	v_max_u32_e32 v13, v13, v14
	v_min_u32_e32 v14, v11, v12
	v_max_u32_e32 v11, v11, v12
	v_min_u32_e32 v12, v9, v10
	v_cndmask_b32_e32 v2, v4, v2, vcc
	v_max3_u32 v65, v65, v67, v66
	v_min_u32_e32 v66, v29, v64
	v_max_u32_e32 v29, v29, v64
	v_min_u32_e32 v28, v27, v26
	v_max_u32_e32 v26, v27, v26
	v_min_u32_e32 v27, v24, v25
	v_max_u32_e32 v24, v24, v25
	v_min_u32_e32 v25, v22, v23
	v_max_u32_e32 v22, v22, v23
	v_min_u32_e32 v23, v20, v21
	v_max_u32_e32 v20, v20, v21
; DI unsigned f2ord(float f) { unsigned u = __float_as_uint(f); return (u & 0x80000000u) ? ~u : (u | 0x80000000u); }
; DI float ord2f(unsigned u) { return __uint_as_float((u & 0x80000000u) ? (u & 0x7fffffffu) : ~u); }
; #define INS32(T, X) { _Pragma("unroll") for (int jj = 0; jj < 16; ++jj) { unsigned t_ = max(T[jj], X); X = min(T[jj], X); T[jj] = t_; } }
; __device__ __forceinline__ void route_task(const Params& p, int layer, const u16* qg, int rb, int hd, int r, int h) {
;     ...
; #pragma unroll
;       for (int b = 0; b < 16; ++b) {
;         if ((a + 1) * (b + 1) <= 16) {
;           const float vb = ord2f(top[1][b] & ~127u);
;           unsigned key = (f2ord(va + vb) & ~255u) | (unsigned)(255 - (a * 16 + b));
;           INS32(ct, key);
;         }
;       }
;     }
;     const float v0 = ord2f(ct[0] & ~255u);
;     float vs[16];
;     float den = 0.f;
; #pragma unroll
;     for (int jj = 0; jj < 16; ++jj) { vs[jj] = __expf(ord2f(ct[jj] & ~255u) - v0); den += vs[jj]; }
	v_min_u32_e32 v21, v18, v19
	v_max_u32_e32 v18, v18, v19
	v_min_u32_e32 v19, v16, v17
	v_max_u32_e32 v16, v16, v17
	v_min_u32_e32 v17, v13, v14
	v_max_u32_e32 v13, v13, v14
	v_min_u32_e32 v14, v11, v12
	v_add_f32_e32 v1, v2, v1
	v_min_u32_e32 v67, v31, v66
	v_max_u32_e32 v31, v31, v66
	v_min_u32_e32 v30, v29, v28
	v_max_u32_e32 v28, v29, v28
	v_min_u32_e32 v29, v26, v27
	v_max_u32_e32 v26, v26, v27
	v_min_u32_e32 v27, v24, v25
	v_max_u32_e32 v24, v24, v25
	v_min_u32_e32 v25, v22, v23
	v_max_u32_e32 v22, v22, v23
	v_min_u32_e32 v23, v20, v21
	v_max_u32_e32 v20, v20, v21
	v_min_u32_e32 v21, v18, v19
	v_max_u32_e32 v18, v18, v19
	v_min_u32_e32 v19, v16, v17
	v_max_u32_e32 v16, v16, v17
	v_min_u32_e32 v17, v13, v14
	v_not_b32_e32 v2, v1
	v_or_b32_e32 v4, 0x80000000, v1
	v_cmp_gt_i32_e32 vcc, 0, v1
	v_min_u32_e32 v64, v31, v30
	v_max_u32_e32 v30, v31, v30
	v_min_u32_e32 v31, v28, v29
	v_max_u32_e32 v28, v28, v29
	v_min_u32_e32 v29, v26, v27
	v_max_u32_e32 v26, v26, v27
	v_min_u32_e32 v27, v24, v25
	v_max_u32_e32 v24, v24, v25
	v_min_u32_e32 v25, v22, v23
	v_max_u32_e32 v22, v22, v23
	v_min_u32_e32 v23, v20, v21
	v_max_u32_e32 v20, v20, v21
	v_min_u32_e32 v21, v18, v19
	v_max_u32_e32 v18, v18, v19
	v_min_u32_e32 v19, v16, v17
	v_cndmask_b32_e32 v1, v4, v2, vcc
	v_max3_u32 v64, v65, v67, v64
	v_min_u32_e32 v65, v30, v31
	v_max_u32_e32 v30, v30, v31
	v_min_u32_e32 v31, v28, v29
	v_max_u32_e32 v28, v28, v29
	v_min_u32_e32 v29, v26, v27
	v_max_u32_e32 v26, v26, v27
	v_min_u32_e32 v27, v24, v25
	v_max_u32_e32 v24, v24, v25
	v_min_u32_e32 v25, v22, v23
	v_max_u32_e32 v22, v22, v23
	v_min_u32_e32 v23, v20, v21
	v_max_u32_e32 v20, v20, v21
	v_min_u32_e32 v21, v18, v19
	v_and_or_b32 v1, v1, s81, 15
	v_min_u32_e32 v66, v30, v31
	v_max_u32_e32 v30, v30, v31
	v_min_u32_e32 v31, v28, v29
	v_max_u32_e32 v28, v28, v29
	v_min_u32_e32 v29, v26, v27
	v_max_u32_e32 v26, v26, v27
	v_min_u32_e32 v27, v24, v25
	v_max_u32_e32 v24, v24, v25
	v_min_u32_e32 v25, v22, v23
	v_max_u32_e32 v22, v22, v23
	v_min_u32_e32 v23, v20, v21
	v_min_u32_e32 v2, v0, v1
	v_max3_u32 v64, v64, v65, v66
	v_min_u32_e32 v65, v30, v31
	v_max_u32_e32 v30, v30, v31
	v_min_u32_e32 v31, v28, v29
	v_max_u32_e32 v28, v28, v29
	v_min_u32_e32 v29, v26, v27
	v_max_u32_e32 v26, v26, v27
	v_min_u32_e32 v27, v24, v25
	v_max_u32_e32 v24, v24, v25
	v_min_u32_e32 v25, v22, v23
	v_max_u32_e32 v5, v5, v6
	v_min_u32_e32 v4, v3, v2
	v_min_u32_e32 v66, v30, v31
	v_max_u32_e32 v30, v30, v31
	v_min_u32_e32 v31, v28, v29
	v_max_u32_e32 v28, v28, v29
	v_min_u32_e32 v29, v26, v27
	v_max_u32_e32 v26, v26, v27
	v_min_u32_e32 v27, v24, v25
	v_max_u32_e32 v24, v24, v25
	v_max_u32_e32 v22, v22, v23
	v_max_u32_e32 v23, v7, v8
	v_min_u32_e32 v25, v5, v4
	v_max3_u32 v64, v64, v65, v66
	v_min_u32_e32 v65, v30, v31
	v_max_u32_e32 v30, v30, v31
	v_min_u32_e32 v31, v28, v29
	v_max_u32_e32 v28, v28, v29
	v_min_u32_e32 v29, v26, v27
	v_max_u32_e32 v26, v26, v27
	v_max_u32_e32 v20, v20, v21
	v_max_u32_e32 v21, v9, v10
	v_min_u32_e32 v27, v23, v25
	v_min_u32_e32 v66, v30, v31
	v_max_u32_e32 v30, v30, v31
	v_min_u32_e32 v31, v28, v29
	v_max_u32_e32 v28, v28, v29
	v_max_u32_e32 v18, v18, v19
	v_max_u32_e32 v19, v11, v12
	v_min_u32_e32 v29, v21, v27
	v_max_u32_e32 v16, v16, v17
	v_max_u32_e32 v17, v13, v14
	v_min_u32_e32 v6, v19, v29
	v_min_u32_e32 v7, v17, v6
	v_min_u32_e32 v8, v16, v7
	v_min_u32_e32 v9, v18, v8
	v_min_u32_e32 v10, v20, v9
	v_min_u32_e32 v11, v22, v10
	v_min_u32_e32 v12, v24, v11
	v_min_u32_e32 v13, v26, v12
	v_max3_u32 v64, v64, v65, v66
	v_min_u32_e32 v65, v30, v31
	v_max_u32_e32 v30, v30, v31
	v_min_u32_e32 v14, v28, v13
	v_max_u32_e32 v0, v0, v1
	v_min_u32_e32 v31, v30, v14
	v_max_u32_e32 v7, v16, v7
	v_max_u32_e32 v6, v17, v6
	v_max_u32_e32 v2, v3, v2
	v_and_b32_e32 v16, 0x7fffff00, v0
	v_bitop3_b32 v17, v0, s80, v0 bitop3:0xcf
	v_cmp_gt_i32_e32 vcc, 0, v0
	v_max3_u32 v64, v64, v65, v31
	v_max_u32_e32 v8, v18, v8
	v_max_u32_e32 v4, v5, v4
	v_cndmask_b32_e32 v31, v17, v16, vcc
	v_and_b32_e32 v17, 0x7fffff00, v2
	v_bitop3_b32 v18, v2, s80, v2 bitop3:0xcf
	v_cmp_gt_i32_e32 vcc, 0, v2
	v_max_u32_e32 v76, v19, v29
	v_max_u32_e32 v80, v23, v25
	v_sub_f32_e32 v16, v31, v31
	v_cndmask_b32_e32 v17, v18, v17, vcc
	v_and_b32_e32 v18, 0x7fffff00, v4
	v_bitop3_b32 v19, v4, s80, v4 bitop3:0xcf
	v_cmp_gt_i32_e32 vcc, 0, v4
	v_max_u32_e32 v9, v20, v9
	v_mul_f32_e32 v16, 0x3fb8aa3b, v16
	v_sub_f32_e32 v17, v17, v31
	v_cndmask_b32_e32 v18, v19, v18, vcc
	v_and_b32_e32 v19, 0x7fffff00, v80
	v_bitop3_b32 v20, v80, s80, v80 bitop3:0xcf
	v_cmp_gt_i32_e32 vcc, 0, v80
	v_exp_f32_e32 v16, v16
	v_mul_f32_e32 v17, 0x3fb8aa3b, v17
	v_sub_f32_e32 v18, v18, v31
	v_cndmask_b32_e32 v19, v20, v19, vcc
	v_exp_f32_e32 v17, v17
	v_mul_f32_e32 v18, 0x3fb8aa3b, v18
	v_sub_f32_e32 v19, v19, v31
	v_exp_f32_e32 v18, v18
	v_mul_f32_e32 v19, 0x3fb8aa3b, v19
	v_exp_f32_e32 v19, v19
	v_add_f32_e32 v20, 0, v16
	v_add_f32_e32 v20, v17, v20
	v_max_u32_e32 v78, v21, v27
	v_add_f32_e32 v20, v18, v20
	v_max_u32_e32 v11, v24, v11
	v_add_f32_e32 v24, v19, v20
	v_and_b32_e32 v20, 0x7fffff00, v78
	v_bitop3_b32 v21, v78, s80, v78 bitop3:0xcf
	v_cmp_gt_i32_e32 vcc, 0, v78
	v_max_u32_e32 v10, v22, v10
	v_bitop3_b32 v22, v76, s80, v76 bitop3:0xcf
	v_cndmask_b32_e32 v20, v21, v20, vcc
	v_and_b32_e32 v21, 0x7fffff00, v76
	v_cmp_gt_i32_e32 vcc, 0, v76
	v_sub_f32_e32 v20, v20, v31
	v_bitop3_b32 v23, v6, s80, v6 bitop3:0xcf
	v_cndmask_b32_e32 v21, v22, v21, vcc
	v_and_b32_e32 v22, 0x7fffff00, v6
	v_cmp_gt_i32_e32 vcc, 0, v6
	v_mul_f32_e32 v20, 0x3fb8aa3b, v20
	v_sub_f32_e32 v21, v21, v31
	v_cndmask_b32_e32 v22, v23, v22, vcc
	v_and_b32_e32 v23, 0x7fffff00, v7
; DI float ord2f(unsigned u) { return __uint_as_float((u & 0x80000000u) ? (u & 0x7fffffffu) : ~u); }
; __device__ __forceinline__ void route_task(const Params& p, int layer, const u16* qg, int rb, int hd, int r, int h) {
;     ...
;     for (int jj = 0; jj < 16; ++jj) { vs[jj] = __expf(ord2f(ct[jj] & ~255u) - v0); den += vs[jj]; }
;     const float inv = 1.f / den;
;     unsigned eo[16];
; #pragma unroll
;     for (int jj = 0; jj < 16; ++jj) {
;       const unsigned flat = 255u - (ct[jj] & 255u);
;       const unsigned a = flat >> 4, b = flat & 15u;
;       unsigned ka = top[0][0], kb = top[1][0];
; #pragma unroll
;       for (int k = 1; k < 16; ++k) { ka = (a == (unsigned)k) ? top[0][k] : ka; kb = (b == (unsigned)k) ? top[1][k] : kb; }
;       eo[jj] = (127u - (ka & 127u)) * 128u + (127u - (kb & 127u));
	v_bitop3_b32 v25, v7, s80, v7 bitop3:0xcf
	v_cmp_gt_i32_e32 vcc, 0, v7
	v_exp_f32_e32 v20, v20
	v_mul_f32_e32 v21, 0x3fb8aa3b, v21
	v_sub_f32_e32 v22, v22, v31
	v_cndmask_b32_e32 v23, v25, v23, vcc
	v_exp_f32_e32 v21, v21
	v_mul_f32_e32 v22, 0x3fb8aa3b, v22
	v_sub_f32_e32 v23, v23, v31
	v_exp_f32_e32 v22, v22
	v_mul_f32_e32 v23, 0x3fb8aa3b, v23
	v_exp_f32_e32 v23, v23
	v_add_f32_e32 v24, v20, v24
	v_add_f32_e32 v24, v21, v24
	v_add_f32_e32 v24, v22, v24
	v_max_u32_e32 v13, v28, v13
	v_add_f32_e32 v28, v23, v24
	v_and_b32_e32 v24, 0x7fffff00, v8
	v_bitop3_b32 v25, v8, s80, v8 bitop3:0xcf
	v_cmp_gt_i32_e32 vcc, 0, v8
	v_max_u32_e32 v12, v26, v12
	v_bitop3_b32 v26, v9, s80, v9 bitop3:0xcf
	v_cndmask_b32_e32 v24, v25, v24, vcc
	v_and_b32_e32 v25, 0x7fffff00, v9
	v_cmp_gt_i32_e32 vcc, 0, v9
	v_sub_f32_e32 v24, v24, v31
	v_bitop3_b32 v27, v10, s80, v10 bitop3:0xcf
	v_cndmask_b32_e32 v25, v26, v25, vcc
	v_and_b32_e32 v26, 0x7fffff00, v10
	v_cmp_gt_i32_e32 vcc, 0, v10
	v_mul_f32_e32 v24, 0x3fb8aa3b, v24
	v_sub_f32_e32 v25, v25, v31
	v_cndmask_b32_e32 v26, v27, v26, vcc
	v_and_b32_e32 v27, 0x7fffff00, v11
	v_bitop3_b32 v29, v11, s80, v11 bitop3:0xcf
	v_cmp_gt_i32_e32 vcc, 0, v11
	v_exp_f32_e32 v24, v24
	v_mul_f32_e32 v25, 0x3fb8aa3b, v25
	v_sub_f32_e32 v26, v26, v31
	v_cndmask_b32_e32 v27, v29, v27, vcc
	v_exp_f32_e32 v25, v25
	v_mul_f32_e32 v26, 0x3fb8aa3b, v26
	v_sub_f32_e32 v27, v27, v31
	v_exp_f32_e32 v26, v26
	v_mul_f32_e32 v27, 0x3fb8aa3b, v27
	v_exp_f32_e32 v27, v27
	v_add_f32_e32 v28, v24, v28
	v_add_f32_e32 v28, v25, v28
	v_add_f32_e32 v28, v26, v28
	v_add_f32_e32 v67, v27, v28
	v_and_b32_e32 v28, 0x7fffff00, v12
	v_bitop3_b32 v29, v12, s80, v12 bitop3:0xcf
	v_cmp_gt_i32_e32 vcc, 0, v12
	v_max_u32_e32 v14, v30, v14
	v_bitop3_b32 v30, v13, s80, v13 bitop3:0xcf
	v_cndmask_b32_e32 v28, v29, v28, vcc
	v_and_b32_e32 v29, 0x7fffff00, v13
	v_cmp_gt_i32_e32 vcc, 0, v13
	v_not_b32_e32 v1, v0
	v_bitop3_b32 v82, v14, s80, v14 bitop3:0xcf
	v_cndmask_b32_e32 v29, v30, v29, vcc
	v_and_b32_e32 v30, 0x7fffff00, v14
	v_cmp_gt_i32_e32 vcc, 0, v14
	v_bitop3_b32 v83, v64, s80, v64 bitop3:0xcf
	v_bfe_u32 v1, v1, 4, 4
	v_cndmask_b32_e32 v30, v82, v30, vcc
	v_and_b32_e32 v82, 0x7fffff00, v64
	v_cmp_gt_i32_e32 vcc, 0, v64
	v_bitop3_b32 v0, v0, 15, v0 bitop3:0xc
	v_sub_f32_e32 v28, v28, v31
	v_cndmask_b32_e32 v82, v83, v82, vcc
	v_cmp_eq_u32_e32 vcc, 1, v1
	v_sub_f32_e32 v29, v29, v31
	v_sub_f32_e32 v30, v30, v31
	v_sub_f32_e32 v31, v82, v31
	v_cndmask_b32_e32 v82, v50, v46, vcc
	v_cmp_eq_u32_e32 vcc, 1, v0
	v_not_b32_e32 v3, v2
	v_bitop3_b32 v2, v2, 15, v2 bitop3:0xc
	v_cndmask_b32_e32 v83, v63, v62, vcc
	v_cmp_eq_u32_e32 vcc, 2, v1
	v_not_b32_e32 v5, v4
	v_not_b32_e32 v81, v80
	v_cndmask_b32_e32 v82, v82, v45, vcc
	v_cmp_eq_u32_e32 vcc, 2, v0
	v_not_b32_e32 v79, v78
	v_not_b32_e32 v77, v76
	v_cndmask_b32_e32 v83, v83, v61, vcc
	v_cmp_eq_u32_e32 vcc, 3, v1
	v_bitop3_b32 v76, v76, 15, v76 bitop3:0xc
	v_not_b32_e32 v75, v6
	v_cndmask_b32_e32 v82, v82, v44, vcc
	v_cmp_eq_u32_e32 vcc, 3, v0
	v_bfe_u32 v75, v75, 4, 4
	v_bitop3_b32 v6, v6, 15, v6 bitop3:0xc
	v_cndmask_b32_e32 v83, v83, v60, vcc
	v_cmp_eq_u32_e32 vcc, 4, v1
	v_not_b32_e32 v74, v7
	v_bfe_u32 v74, v74, 4, 4
	v_cndmask_b32_e32 v82, v82, v43, vcc
	v_cmp_eq_u32_e32 vcc, 4, v0
	v_bitop3_b32 v7, v7, 15, v7 bitop3:0xc
	v_not_b32_e32 v73, v8
	v_cndmask_b32_e32 v83, v83, v59, vcc
	v_cmp_eq_u32_e32 vcc, 5, v1
	v_bfe_u32 v73, v73, 4, 4
	v_bitop3_b32 v8, v8, 15, v8 bitop3:0xc
	v_cndmask_b32_e32 v82, v82, v42, vcc
	v_cmp_eq_u32_e32 vcc, 5, v0
	v_not_b32_e32 v72, v9
	v_bfe_u32 v72, v72, 4, 4
	v_cndmask_b32_e32 v83, v83, v58, vcc
	v_cmp_eq_u32_e32 vcc, 6, v1
	v_bitop3_b32 v9, v9, 15, v9 bitop3:0xc
	v_not_b32_e32 v71, v10
	v_cndmask_b32_e32 v82, v82, v41, vcc
	v_cmp_eq_u32_e32 vcc, 6, v0
	v_bfe_u32 v71, v71, 4, 4
	v_bitop3_b32 v10, v10, 15, v10 bitop3:0xc
	v_cndmask_b32_e32 v83, v83, v57, vcc
	v_cmp_eq_u32_e32 vcc, 7, v1
	v_not_b32_e32 v70, v11
	v_bfe_u32 v70, v70, 4, 4
	v_cndmask_b32_e32 v82, v82, v40, vcc
	v_cmp_eq_u32_e32 vcc, 7, v0
	v_bitop3_b32 v11, v11, 15, v11 bitop3:0xc
	v_not_b32_e32 v69, v12
	v_cndmask_b32_e32 v83, v83, v56, vcc
	v_cmp_eq_u32_e32 vcc, 8, v1
	v_bfe_u32 v69, v69, 4, 4
	v_bitop3_b32 v12, v12, 15, v12 bitop3:0xc
	v_cndmask_b32_e32 v82, v82, v39, vcc
	v_cmp_eq_u32_e32 vcc, 8, v0
	v_not_b32_e32 v68, v13
	v_bfe_u32 v68, v68, 4, 4
	v_cndmask_b32_e32 v83, v83, v55, vcc
	v_cmp_eq_u32_e32 vcc, 9, v1
	v_bitop3_b32 v13, v13, 15, v13 bitop3:0xc
	v_not_b32_e32 v66, v14
	v_cndmask_b32_e32 v82, v82, v38, vcc
	v_cmp_eq_u32_e32 vcc, 9, v0
	v_bfe_u32 v66, v66, 4, 4
	v_bitop3_b32 v14, v14, 15, v14 bitop3:0xc
	v_cndmask_b32_e32 v83, v83, v54, vcc
	v_cmp_eq_u32_e32 vcc, 10, v1
	v_not_b32_e32 v65, v64
	v_bfe_u32 v65, v65, 4, 4
	v_cndmask_b32_e32 v82, v82, v37, vcc
	v_cmp_eq_u32_e32 vcc, 10, v0
	v_bitop3_b32 v64, v64, 15, v64 bitop3:0xc
	v_mul_f32_e32 v28, 0x3fb8aa3b, v28
	v_cndmask_b32_e32 v83, v83, v53, vcc
	v_cmp_eq_u32_e32 vcc, 11, v1
	v_exp_f32_e32 v28, v28
	v_mul_f32_e32 v29, 0x3fb8aa3b, v29
	v_cndmask_b32_e32 v82, v82, v36, vcc
	v_cmp_eq_u32_e32 vcc, 11, v0
	v_exp_f32_e32 v29, v29
	v_mul_f32_e32 v30, 0x3fb8aa3b, v30
	v_cndmask_b32_e32 v83, v83, v52, vcc
	v_cmp_eq_u32_e32 vcc, 12, v1
	v_exp_f32_e32 v30, v30
	v_mul_f32_e32 v31, 0x3fb8aa3b, v31
	v_cndmask_b32_e32 v82, v82, v35, vcc
	v_cmp_eq_u32_e32 vcc, 12, v0
	v_exp_f32_e32 v31, v31
	v_add_f32_e32 v67, v28, v67
	v_cndmask_b32_e32 v83, v83, v51, vcc
	v_cmp_eq_u32_e32 vcc, 13, v1
	v_add_f32_e32 v67, v29, v67
	v_add_f32_e32 v67, v30, v67
	v_cndmask_b32_e32 v82, v82, v34, vcc
	v_cmp_eq_u32_e32 vcc, 13, v0
	v_add_f32_e32 v67, v31, v67
	v_or_b32_e32 v32, v32, v138
; __device__ __forceinline__ void route_task(const Params& p, int layer, const u16* qg, int rb, int hd, int r, int h) {
;     ...
;     for (int jj = 0; jj < 16; ++jj) {
;       const unsigned flat = 255u - (ct[jj] & 255u);
;       const unsigned a = flat >> 4, b = flat & 15u;
;       unsigned ka = top[0][0], kb = top[1][0];
; #pragma unroll
;       for (int k = 1; k < 16; ++k) { ka = (a == (unsigned)k) ? top[0][k] : ka; kb = (b == (unsigned)k) ? top[1][k] : kb; }
;       eo[jj] = (127u - (ka & 127u)) * 128u + (127u - (kb & 127u));
;     }
	v_cndmask_b32_e32 v83, v83, v49, vcc
	v_cmp_eq_u32_e32 vcc, 14, v1
	s_nop 1
	v_cndmask_b32_e32 v82, v82, v33, vcc
	v_cmp_eq_u32_e32 vcc, 14, v0
	s_nop 1
	v_cndmask_b32_e32 v83, v83, v48, vcc
	v_cmp_eq_u32_e32 vcc, 15, v1
	s_nop 1
	v_cndmask_b32_e32 v1, v82, v15, vcc
	v_cmp_eq_u32_e32 vcc, 15, v0
	v_lshlrev_b32_e32 v1, 7, v1
	v_and_b32_e32 v1, 0x3f80, v1
	v_cndmask_b32_e32 v0, v83, v47, vcc
	v_and_b32_e32 v0, 0x7f, v0
	v_bitop3_b32 v0, v1, s82, v0 bitop3:0x36
	v_bfe_u32 v1, v3, 4, 4
	v_cmp_eq_u32_e32 vcc, 1, v1
	s_nop 1
	v_cndmask_b32_e32 v3, v50, v46, vcc
	v_cmp_eq_u32_e32 vcc, 1, v2
	s_nop 1
	v_cndmask_b32_e32 v82, v63, v62, vcc
	v_cmp_eq_u32_e32 vcc, 2, v1
	s_nop 1
	v_cndmask_b32_e32 v3, v3, v45, vcc
	v_cmp_eq_u32_e32 vcc, 2, v2
	s_nop 1
	v_cndmask_b32_e32 v82, v82, v61, vcc
	v_cmp_eq_u32_e32 vcc, 3, v1
	s_nop 1
	v_cndmask_b32_e32 v3, v3, v44, vcc
	v_cmp_eq_u32_e32 vcc, 3, v2
	s_nop 1
	v_cndmask_b32_e32 v82, v82, v60, vcc
	v_cmp_eq_u32_e32 vcc, 4, v1
	s_nop 1
	v_cndmask_b32_e32 v3, v3, v43, vcc
	v_cmp_eq_u32_e32 vcc, 4, v2
	s_nop 1
	v_cndmask_b32_e32 v82, v82, v59, vcc
	v_cmp_eq_u32_e32 vcc, 5, v1
	s_nop 1
	v_cndmask_b32_e32 v3, v3, v42, vcc
	v_cmp_eq_u32_e32 vcc, 5, v2
	s_nop 1
	v_cndmask_b32_e32 v82, v82, v58, vcc
	v_cmp_eq_u32_e32 vcc, 6, v1
	s_nop 1
	v_cndmask_b32_e32 v3, v3, v41, vcc
	v_cmp_eq_u32_e32 vcc, 6, v2
	s_nop 1
	v_cndmask_b32_e32 v82, v82, v57, vcc
	v_cmp_eq_u32_e32 vcc, 7, v1
	s_nop 1
	v_cndmask_b32_e32 v3, v3, v40, vcc
	v_cmp_eq_u32_e32 vcc, 7, v2
	s_nop 1
	v_cndmask_b32_e32 v82, v82, v56, vcc
	v_cmp_eq_u32_e32 vcc, 8, v1
	s_nop 1
	v_cndmask_b32_e32 v3, v3, v39, vcc
	v_cmp_eq_u32_e32 vcc, 8, v2
	s_nop 1
	v_cndmask_b32_e32 v82, v82, v55, vcc
	v_cmp_eq_u32_e32 vcc, 9, v1
	s_nop 1
	v_cndmask_b32_e32 v3, v3, v38, vcc
	v_cmp_eq_u32_e32 vcc, 9, v2
	s_nop 1
	v_cndmask_b32_e32 v82, v82, v54, vcc
	v_cmp_eq_u32_e32 vcc, 10, v1
	s_nop 1
	v_cndmask_b32_e32 v3, v3, v37, vcc
	v_cmp_eq_u32_e32 vcc, 10, v2
	s_nop 1
	v_cndmask_b32_e32 v82, v82, v53, vcc
	v_cmp_eq_u32_e32 vcc, 11, v1
	s_nop 1
	v_cndmask_b32_e32 v3, v3, v36, vcc
	v_cmp_eq_u32_e32 vcc, 11, v2
	s_nop 1
	v_cndmask_b32_e32 v82, v82, v52, vcc
	v_cmp_eq_u32_e32 vcc, 12, v1
	s_nop 1
	v_cndmask_b32_e32 v3, v3, v35, vcc
	v_cmp_eq_u32_e32 vcc, 12, v2
	s_nop 1
	v_cndmask_b32_e32 v82, v82, v51, vcc
	v_cmp_eq_u32_e32 vcc, 13, v1
	s_nop 1
	v_cndmask_b32_e32 v3, v3, v34, vcc
	v_cmp_eq_u32_e32 vcc, 13, v2
	s_nop 1
	v_cndmask_b32_e32 v82, v82, v49, vcc
	v_cmp_eq_u32_e32 vcc, 14, v1
	s_nop 1
	v_cndmask_b32_e32 v3, v3, v33, vcc
	v_cmp_eq_u32_e32 vcc, 14, v2
	s_nop 1
	v_cndmask_b32_e32 v82, v82, v48, vcc
	v_cmp_eq_u32_e32 vcc, 15, v1
	s_nop 1
	v_cndmask_b32_e32 v1, v3, v15, vcc
	v_cmp_eq_u32_e32 vcc, 15, v2
	v_lshlrev_b32_e32 v1, 7, v1
	v_and_b32_e32 v1, 0x3f80, v1
	v_cndmask_b32_e32 v2, v82, v47, vcc
	v_and_b32_e32 v2, 0x7f, v2
	v_bitop3_b32 v1, v1, s82, v2 bitop3:0x36
	v_bfe_u32 v2, v5, 4, 4
	v_bitop3_b32 v3, v4, 15, v4 bitop3:0xc
	v_cmp_eq_u32_e32 vcc, 1, v2
	s_nop 1
	v_cndmask_b32_e32 v4, v50, v46, vcc
	v_cmp_eq_u32_e32 vcc, 1, v3
	s_nop 1
	v_cndmask_b32_e32 v5, v63, v62, vcc
	v_cmp_eq_u32_e32 vcc, 2, v2
	s_nop 1
	v_cndmask_b32_e32 v4, v4, v45, vcc
	v_cmp_eq_u32_e32 vcc, 2, v3
	s_nop 1
	v_cndmask_b32_e32 v5, v5, v61, vcc
	v_cmp_eq_u32_e32 vcc, 3, v2
	s_nop 1
	v_cndmask_b32_e32 v4, v4, v44, vcc
	v_cmp_eq_u32_e32 vcc, 3, v3
	s_nop 1
	v_cndmask_b32_e32 v5, v5, v60, vcc
	v_cmp_eq_u32_e32 vcc, 4, v2
	s_nop 1
	v_cndmask_b32_e32 v4, v4, v43, vcc
	v_cmp_eq_u32_e32 vcc, 4, v3
	s_nop 1
	v_cndmask_b32_e32 v5, v5, v59, vcc
	v_cmp_eq_u32_e32 vcc, 5, v2
	s_nop 1
	v_cndmask_b32_e32 v4, v4, v42, vcc
	v_cmp_eq_u32_e32 vcc, 5, v3
	s_nop 1
	v_cndmask_b32_e32 v5, v5, v58, vcc
	v_cmp_eq_u32_e32 vcc, 6, v2
	s_nop 1
	v_cndmask_b32_e32 v4, v4, v41, vcc
	v_cmp_eq_u32_e32 vcc, 6, v3
	s_nop 1
	v_cndmask_b32_e32 v5, v5, v57, vcc
	v_cmp_eq_u32_e32 vcc, 7, v2
	s_nop 1
	v_cndmask_b32_e32 v4, v4, v40, vcc
	v_cmp_eq_u32_e32 vcc, 7, v3
	s_nop 1
	v_cndmask_b32_e32 v5, v5, v56, vcc
	v_cmp_eq_u32_e32 vcc, 8, v2
	s_nop 1
	v_cndmask_b32_e32 v4, v4, v39, vcc
	v_cmp_eq_u32_e32 vcc, 8, v3
	s_nop 1
	v_cndmask_b32_e32 v5, v5, v55, vcc
	v_cmp_eq_u32_e32 vcc, 9, v2
	s_nop 1
	v_cndmask_b32_e32 v4, v4, v38, vcc
	v_cmp_eq_u32_e32 vcc, 9, v3
	s_nop 1
	v_cndmask_b32_e32 v5, v5, v54, vcc
	v_cmp_eq_u32_e32 vcc, 10, v2
	s_nop 1
	v_cndmask_b32_e32 v4, v4, v37, vcc
	v_cmp_eq_u32_e32 vcc, 10, v3
	s_nop 1
	v_cndmask_b32_e32 v5, v5, v53, vcc
	v_cmp_eq_u32_e32 vcc, 11, v2
	s_nop 1
	v_cndmask_b32_e32 v4, v4, v36, vcc
	v_cmp_eq_u32_e32 vcc, 11, v3
	s_nop 1
	v_cndmask_b32_e32 v5, v5, v52, vcc
	v_cmp_eq_u32_e32 vcc, 12, v2
	s_nop 1
	v_cndmask_b32_e32 v4, v4, v35, vcc
	v_cmp_eq_u32_e32 vcc, 12, v3
	s_nop 1
	v_cndmask_b32_e32 v5, v5, v51, vcc
	v_cmp_eq_u32_e32 vcc, 13, v2
	s_nop 1
	v_cndmask_b32_e32 v4, v4, v34, vcc
	v_cmp_eq_u32_e32 vcc, 13, v3
	s_nop 1
	v_cndmask_b32_e32 v5, v5, v49, vcc
	v_cmp_eq_u32_e32 vcc, 14, v2
	s_nop 1
	v_cndmask_b32_e32 v4, v4, v33, vcc
	v_cmp_eq_u32_e32 vcc, 14, v3
	s_nop 1
	v_cndmask_b32_e32 v5, v5, v48, vcc
	v_cmp_eq_u32_e32 vcc, 15, v2
	s_nop 1
	v_cndmask_b32_e32 v2, v4, v15, vcc
	v_cmp_eq_u32_e32 vcc, 15, v3
	v_lshlrev_b32_e32 v2, 7, v2
	v_and_b32_e32 v2, 0x3f80, v2
	v_cndmask_b32_e32 v3, v5, v47, vcc
	v_and_b32_e32 v3, 0x7f, v3
	v_bitop3_b32 v2, v2, s82, v3 bitop3:0x36
	v_bfe_u32 v3, v81, 4, 4
	v_bitop3_b32 v4, v80, 15, v80 bitop3:0xc
	v_cmp_eq_u32_e32 vcc, 1, v3
	s_nop 1
	v_cndmask_b32_e32 v5, v50, v46, vcc
	v_cmp_eq_u32_e32 vcc, 1, v4
	s_nop 1
	v_cndmask_b32_e32 v80, v63, v62, vcc
	v_cmp_eq_u32_e32 vcc, 2, v3
	s_nop 1
	v_cndmask_b32_e32 v5, v5, v45, vcc
	v_cmp_eq_u32_e32 vcc, 2, v4
	s_nop 1
	v_cndmask_b32_e32 v80, v80, v61, vcc
; __device__ __forceinline__ void route_task(const Params& p, int layer, const u16* qg, int rb, int hd, int r, int h) {
;     ...
;     for (int jj = 0; jj < 16; ++jj) {
;       const unsigned flat = 255u - (ct[jj] & 255u);
;       const unsigned a = flat >> 4, b = flat & 15u;
;       unsigned ka = top[0][0], kb = top[1][0];
; #pragma unroll
;       for (int k = 1; k < 16; ++k) { ka = (a == (unsigned)k) ? top[0][k] : ka; kb = (b == (unsigned)k) ? top[1][k] : kb; }
;       eo[jj] = (127u - (ka & 127u)) * 128u + (127u - (kb & 127u));
;     }
	v_cmp_eq_u32_e32 vcc, 3, v3
	s_nop 1
	v_cndmask_b32_e32 v5, v5, v44, vcc
	v_cmp_eq_u32_e32 vcc, 3, v4
	s_nop 1
	v_cndmask_b32_e32 v80, v80, v60, vcc
	v_cmp_eq_u32_e32 vcc, 4, v3
	s_nop 1
	v_cndmask_b32_e32 v5, v5, v43, vcc
	v_cmp_eq_u32_e32 vcc, 4, v4
	s_nop 1
	v_cndmask_b32_e32 v80, v80, v59, vcc
	v_cmp_eq_u32_e32 vcc, 5, v3
	s_nop 1
	v_cndmask_b32_e32 v5, v5, v42, vcc
	v_cmp_eq_u32_e32 vcc, 5, v4
	s_nop 1
	v_cndmask_b32_e32 v80, v80, v58, vcc
	v_cmp_eq_u32_e32 vcc, 6, v3
	s_nop 1
	v_cndmask_b32_e32 v5, v5, v41, vcc
	v_cmp_eq_u32_e32 vcc, 6, v4
	s_nop 1
	v_cndmask_b32_e32 v80, v80, v57, vcc
	v_cmp_eq_u32_e32 vcc, 7, v3
	s_nop 1
	v_cndmask_b32_e32 v5, v5, v40, vcc
	v_cmp_eq_u32_e32 vcc, 7, v4
	s_nop 1
	v_cndmask_b32_e32 v80, v80, v56, vcc
	v_cmp_eq_u32_e32 vcc, 8, v3
	s_nop 1
	v_cndmask_b32_e32 v5, v5, v39, vcc
	v_cmp_eq_u32_e32 vcc, 8, v4
	s_nop 1
	v_cndmask_b32_e32 v80, v80, v55, vcc
	v_cmp_eq_u32_e32 vcc, 9, v3
	s_nop 1
	v_cndmask_b32_e32 v5, v5, v38, vcc
	v_cmp_eq_u32_e32 vcc, 9, v4
	s_nop 1
	v_cndmask_b32_e32 v80, v80, v54, vcc
	v_cmp_eq_u32_e32 vcc, 10, v3
	s_nop 1
	v_cndmask_b32_e32 v5, v5, v37, vcc
	v_cmp_eq_u32_e32 vcc, 10, v4
	s_nop 1
	v_cndmask_b32_e32 v80, v80, v53, vcc
	v_cmp_eq_u32_e32 vcc, 11, v3
	s_nop 1
	v_cndmask_b32_e32 v5, v5, v36, vcc
	v_cmp_eq_u32_e32 vcc, 11, v4
	s_nop 1
	v_cndmask_b32_e32 v80, v80, v52, vcc
	v_cmp_eq_u32_e32 vcc, 12, v3
	s_nop 1
	v_cndmask_b32_e32 v5, v5, v35, vcc
	v_cmp_eq_u32_e32 vcc, 12, v4
	s_nop 1
	v_cndmask_b32_e32 v80, v80, v51, vcc
	v_cmp_eq_u32_e32 vcc, 13, v3
	s_nop 1
	v_cndmask_b32_e32 v5, v5, v34, vcc
	v_cmp_eq_u32_e32 vcc, 13, v4
	s_nop 1
	v_cndmask_b32_e32 v80, v80, v49, vcc
	v_cmp_eq_u32_e32 vcc, 14, v3
	s_nop 1
	v_cndmask_b32_e32 v5, v5, v33, vcc
	v_cmp_eq_u32_e32 vcc, 14, v4
	s_nop 1
	v_cndmask_b32_e32 v80, v80, v48, vcc
	v_cmp_eq_u32_e32 vcc, 15, v3
	s_nop 1
	v_cndmask_b32_e32 v3, v5, v15, vcc
	v_cmp_eq_u32_e32 vcc, 15, v4
	v_lshlrev_b32_e32 v3, 7, v3
	v_and_b32_e32 v3, 0x3f80, v3
	v_cndmask_b32_e32 v4, v80, v47, vcc
	v_and_b32_e32 v4, 0x7f, v4
	v_bitop3_b32 v3, v3, s82, v4 bitop3:0x36
	v_bfe_u32 v4, v79, 4, 4
	v_bitop3_b32 v5, v78, 15, v78 bitop3:0xc
	v_cmp_eq_u32_e32 vcc, 1, v4
	s_nop 1
	v_cndmask_b32_e32 v78, v50, v46, vcc
	v_cmp_eq_u32_e32 vcc, 1, v5
	s_nop 1
	v_cndmask_b32_e32 v79, v63, v62, vcc
	v_cmp_eq_u32_e32 vcc, 2, v4
	s_nop 1
	v_cndmask_b32_e32 v78, v78, v45, vcc
	v_cmp_eq_u32_e32 vcc, 2, v5
	s_nop 1
	v_cndmask_b32_e32 v79, v79, v61, vcc
	v_cmp_eq_u32_e32 vcc, 3, v4
	s_nop 1
	v_cndmask_b32_e32 v78, v78, v44, vcc
	v_cmp_eq_u32_e32 vcc, 3, v5
	s_nop 1
	v_cndmask_b32_e32 v79, v79, v60, vcc
	v_cmp_eq_u32_e32 vcc, 4, v4
	s_nop 1
	v_cndmask_b32_e32 v78, v78, v43, vcc
	v_cmp_eq_u32_e32 vcc, 4, v5
	s_nop 1
	v_cndmask_b32_e32 v79, v79, v59, vcc
	v_cmp_eq_u32_e32 vcc, 5, v4
	s_nop 1
	v_cndmask_b32_e32 v78, v78, v42, vcc
	v_cmp_eq_u32_e32 vcc, 5, v5
	s_nop 1
	v_cndmask_b32_e32 v79, v79, v58, vcc
	v_cmp_eq_u32_e32 vcc, 6, v4
	s_nop 1
	v_cndmask_b32_e32 v78, v78, v41, vcc
	v_cmp_eq_u32_e32 vcc, 6, v5
	s_nop 1
	v_cndmask_b32_e32 v79, v79, v57, vcc
	v_cmp_eq_u32_e32 vcc, 7, v4
	s_nop 1
	v_cndmask_b32_e32 v78, v78, v40, vcc
	v_cmp_eq_u32_e32 vcc, 7, v5
	s_nop 1
	v_cndmask_b32_e32 v79, v79, v56, vcc
	v_cmp_eq_u32_e32 vcc, 8, v4
	s_nop 1
	v_cndmask_b32_e32 v78, v78, v39, vcc
	v_cmp_eq_u32_e32 vcc, 8, v5
	s_nop 1
	v_cndmask_b32_e32 v79, v79, v55, vcc
	v_cmp_eq_u32_e32 vcc, 9, v4
	s_nop 1
	v_cndmask_b32_e32 v78, v78, v38, vcc
	v_cmp_eq_u32_e32 vcc, 9, v5
	s_nop 1
	v_cndmask_b32_e32 v79, v79, v54, vcc
	v_cmp_eq_u32_e32 vcc, 10, v4
	s_nop 1
	v_cndmask_b32_e32 v78, v78, v37, vcc
	v_cmp_eq_u32_e32 vcc, 10, v5
	s_nop 1
	v_cndmask_b32_e32 v79, v79, v53, vcc
	v_cmp_eq_u32_e32 vcc, 11, v4
	s_nop 1
	v_cndmask_b32_e32 v78, v78, v36, vcc
	v_cmp_eq_u32_e32 vcc, 11, v5
	s_nop 1
	v_cndmask_b32_e32 v79, v79, v52, vcc
	v_cmp_eq_u32_e32 vcc, 12, v4
	s_nop 1
	v_cndmask_b32_e32 v78, v78, v35, vcc
	v_cmp_eq_u32_e32 vcc, 12, v5
	s_nop 1
	v_cndmask_b32_e32 v79, v79, v51, vcc
	v_cmp_eq_u32_e32 vcc, 13, v4
	s_nop 1
	v_cndmask_b32_e32 v78, v78, v34, vcc
	v_cmp_eq_u32_e32 vcc, 13, v5
	s_nop 1
	v_cndmask_b32_e32 v79, v79, v49, vcc
	v_cmp_eq_u32_e32 vcc, 14, v4
	s_nop 1
	v_cndmask_b32_e32 v78, v78, v33, vcc
	v_cmp_eq_u32_e32 vcc, 14, v5
	s_nop 1
	v_cndmask_b32_e32 v79, v79, v48, vcc
	v_cmp_eq_u32_e32 vcc, 15, v4
	s_nop 1
	v_cndmask_b32_e32 v4, v78, v15, vcc
	v_cmp_eq_u32_e32 vcc, 15, v5
	v_lshlrev_b32_e32 v4, 7, v4
	v_and_b32_e32 v4, 0x3f80, v4
	v_cndmask_b32_e32 v5, v79, v47, vcc
	v_and_b32_e32 v5, 0x7f, v5
	v_bitop3_b32 v4, v4, s82, v5 bitop3:0x36
	v_bfe_u32 v5, v77, 4, 4
	v_cmp_eq_u32_e32 vcc, 1, v5
	s_nop 1
	v_cndmask_b32_e32 v77, v50, v46, vcc
	v_cmp_eq_u32_e32 vcc, 1, v76
	s_nop 1
	v_cndmask_b32_e32 v78, v63, v62, vcc
	v_cmp_eq_u32_e32 vcc, 2, v5
	s_nop 1
	v_cndmask_b32_e32 v77, v77, v45, vcc
	v_cmp_eq_u32_e32 vcc, 2, v76
	s_nop 1
	v_cndmask_b32_e32 v78, v78, v61, vcc
	v_cmp_eq_u32_e32 vcc, 3, v5
	s_nop 1
	v_cndmask_b32_e32 v77, v77, v44, vcc
	v_cmp_eq_u32_e32 vcc, 3, v76
	s_nop 1
	v_cndmask_b32_e32 v78, v78, v60, vcc
	v_cmp_eq_u32_e32 vcc, 4, v5
	s_nop 1
	v_cndmask_b32_e32 v77, v77, v43, vcc
	v_cmp_eq_u32_e32 vcc, 4, v76
	s_nop 1
	v_cndmask_b32_e32 v78, v78, v59, vcc
	v_cmp_eq_u32_e32 vcc, 5, v5
	s_nop 1
	v_cndmask_b32_e32 v77, v77, v42, vcc
	v_cmp_eq_u32_e32 vcc, 5, v76
	s_nop 1
	v_cndmask_b32_e32 v78, v78, v58, vcc
	v_cmp_eq_u32_e32 vcc, 6, v5
	s_nop 1
	v_cndmask_b32_e32 v77, v77, v41, vcc
	v_cmp_eq_u32_e32 vcc, 6, v76
	s_nop 1
	v_cndmask_b32_e32 v78, v78, v57, vcc
	v_cmp_eq_u32_e32 vcc, 7, v5
	s_nop 1
	v_cndmask_b32_e32 v77, v77, v40, vcc
	v_cmp_eq_u32_e32 vcc, 7, v76
	s_nop 1
	v_cndmask_b32_e32 v78, v78, v56, vcc
; __device__ __forceinline__ void route_task(const Params& p, int layer, const u16* qg, int rb, int hd, int r, int h) {
;     ...
;     for (int jj = 0; jj < 16; ++jj) {
;       const unsigned flat = 255u - (ct[jj] & 255u);
;       const unsigned a = flat >> 4, b = flat & 15u;
;       unsigned ka = top[0][0], kb = top[1][0];
; #pragma unroll
;       for (int k = 1; k < 16; ++k) { ka = (a == (unsigned)k) ? top[0][k] : ka; kb = (b == (unsigned)k) ? top[1][k] : kb; }
;       eo[jj] = (127u - (ka & 127u)) * 128u + (127u - (kb & 127u));
;     }
	v_cmp_eq_u32_e32 vcc, 8, v5
	s_nop 1
	v_cndmask_b32_e32 v77, v77, v39, vcc
	v_cmp_eq_u32_e32 vcc, 8, v76
	s_nop 1
	v_cndmask_b32_e32 v78, v78, v55, vcc
	v_cmp_eq_u32_e32 vcc, 9, v5
	s_nop 1
	v_cndmask_b32_e32 v77, v77, v38, vcc
	v_cmp_eq_u32_e32 vcc, 9, v76
	s_nop 1
	v_cndmask_b32_e32 v78, v78, v54, vcc
	v_cmp_eq_u32_e32 vcc, 10, v5
	s_nop 1
	v_cndmask_b32_e32 v77, v77, v37, vcc
	v_cmp_eq_u32_e32 vcc, 10, v76
	s_nop 1
	v_cndmask_b32_e32 v78, v78, v53, vcc
	v_cmp_eq_u32_e32 vcc, 11, v5
	s_nop 1
	v_cndmask_b32_e32 v77, v77, v36, vcc
	v_cmp_eq_u32_e32 vcc, 11, v76
	s_nop 1
	v_cndmask_b32_e32 v78, v78, v52, vcc
	v_cmp_eq_u32_e32 vcc, 12, v5
	s_nop 1
	v_cndmask_b32_e32 v77, v77, v35, vcc
	v_cmp_eq_u32_e32 vcc, 12, v76
	s_nop 1
	v_cndmask_b32_e32 v78, v78, v51, vcc
	v_cmp_eq_u32_e32 vcc, 13, v5
	s_nop 1
	v_cndmask_b32_e32 v77, v77, v34, vcc
	v_cmp_eq_u32_e32 vcc, 13, v76
	s_nop 1
	v_cndmask_b32_e32 v78, v78, v49, vcc
	v_cmp_eq_u32_e32 vcc, 14, v5
	s_nop 1
	v_cndmask_b32_e32 v77, v77, v33, vcc
	v_cmp_eq_u32_e32 vcc, 14, v76
	s_nop 1
	v_cndmask_b32_e32 v78, v78, v48, vcc
	v_cmp_eq_u32_e32 vcc, 15, v5
	s_nop 1
	v_cndmask_b32_e32 v5, v77, v15, vcc
	v_cmp_eq_u32_e32 vcc, 15, v76
	v_lshlrev_b32_e32 v5, 7, v5
	v_and_b32_e32 v5, 0x3f80, v5
	v_cndmask_b32_e32 v76, v78, v47, vcc
	v_and_b32_e32 v76, 0x7f, v76
	v_cmp_eq_u32_e32 vcc, 1, v75
	v_bitop3_b32 v5, v5, s82, v76 bitop3:0x36
	s_nop 0
	v_cndmask_b32_e32 v76, v50, v46, vcc
	v_cmp_eq_u32_e32 vcc, 1, v6
	s_nop 1
	v_cndmask_b32_e32 v77, v63, v62, vcc
	v_cmp_eq_u32_e32 vcc, 2, v75
	s_nop 1
	v_cndmask_b32_e32 v76, v76, v45, vcc
	v_cmp_eq_u32_e32 vcc, 2, v6
	s_nop 1
	v_cndmask_b32_e32 v77, v77, v61, vcc
	v_cmp_eq_u32_e32 vcc, 3, v75
	s_nop 1
	v_cndmask_b32_e32 v76, v76, v44, vcc
	v_cmp_eq_u32_e32 vcc, 3, v6
	s_nop 1
	v_cndmask_b32_e32 v77, v77, v60, vcc
	v_cmp_eq_u32_e32 vcc, 4, v75
	s_nop 1
	v_cndmask_b32_e32 v76, v76, v43, vcc
	v_cmp_eq_u32_e32 vcc, 4, v6
	s_nop 1
	v_cndmask_b32_e32 v77, v77, v59, vcc
	v_cmp_eq_u32_e32 vcc, 5, v75
	s_nop 1
	v_cndmask_b32_e32 v76, v76, v42, vcc
	v_cmp_eq_u32_e32 vcc, 5, v6
	s_nop 1
	v_cndmask_b32_e32 v77, v77, v58, vcc
	v_cmp_eq_u32_e32 vcc, 6, v75
	s_nop 1
	v_cndmask_b32_e32 v76, v76, v41, vcc
	v_cmp_eq_u32_e32 vcc, 6, v6
	s_nop 1
	v_cndmask_b32_e32 v77, v77, v57, vcc
	v_cmp_eq_u32_e32 vcc, 7, v75
	s_nop 1
	v_cndmask_b32_e32 v76, v76, v40, vcc
	v_cmp_eq_u32_e32 vcc, 7, v6
	s_nop 1
	v_cndmask_b32_e32 v77, v77, v56, vcc
	v_cmp_eq_u32_e32 vcc, 8, v75
	s_nop 1
	v_cndmask_b32_e32 v76, v76, v39, vcc
	v_cmp_eq_u32_e32 vcc, 8, v6
	s_nop 1
	v_cndmask_b32_e32 v77, v77, v55, vcc
	v_cmp_eq_u32_e32 vcc, 9, v75
	s_nop 1
	v_cndmask_b32_e32 v76, v76, v38, vcc
	v_cmp_eq_u32_e32 vcc, 9, v6
	s_nop 1
	v_cndmask_b32_e32 v77, v77, v54, vcc
	v_cmp_eq_u32_e32 vcc, 10, v75
	s_nop 1
	v_cndmask_b32_e32 v76, v76, v37, vcc
	v_cmp_eq_u32_e32 vcc, 10, v6
	s_nop 1
	v_cndmask_b32_e32 v77, v77, v53, vcc
	v_cmp_eq_u32_e32 vcc, 11, v75
	s_nop 1
	v_cndmask_b32_e32 v76, v76, v36, vcc
	v_cmp_eq_u32_e32 vcc, 11, v6
	s_nop 1
	v_cndmask_b32_e32 v77, v77, v52, vcc
	v_cmp_eq_u32_e32 vcc, 12, v75
	s_nop 1
	v_cndmask_b32_e32 v76, v76, v35, vcc
	v_cmp_eq_u32_e32 vcc, 12, v6
	s_nop 1
	v_cndmask_b32_e32 v77, v77, v51, vcc
	v_cmp_eq_u32_e32 vcc, 13, v75
	s_nop 1
	v_cndmask_b32_e32 v76, v76, v34, vcc
	v_cmp_eq_u32_e32 vcc, 13, v6
	s_nop 1
	v_cndmask_b32_e32 v77, v77, v49, vcc
	v_cmp_eq_u32_e32 vcc, 14, v75
	s_nop 1
	v_cndmask_b32_e32 v76, v76, v33, vcc
	v_cmp_eq_u32_e32 vcc, 14, v6
	s_nop 1
	v_cndmask_b32_e32 v77, v77, v48, vcc
	v_cmp_eq_u32_e32 vcc, 15, v75
	s_nop 1
	v_cndmask_b32_e32 v75, v76, v15, vcc
	v_cmp_eq_u32_e32 vcc, 15, v6
	v_lshlrev_b32_e32 v75, 7, v75
	v_and_b32_e32 v75, 0x3f80, v75
	v_cndmask_b32_e32 v6, v77, v47, vcc
	v_and_b32_e32 v6, 0x7f, v6
	v_cmp_eq_u32_e32 vcc, 1, v74
	v_bitop3_b32 v6, v75, s82, v6 bitop3:0x36
	s_nop 0
	v_cndmask_b32_e32 v75, v50, v46, vcc
	v_cmp_eq_u32_e32 vcc, 1, v7
	s_nop 1
	v_cndmask_b32_e32 v76, v63, v62, vcc
	v_cmp_eq_u32_e32 vcc, 2, v74
	s_nop 1
	v_cndmask_b32_e32 v75, v75, v45, vcc
	v_cmp_eq_u32_e32 vcc, 2, v7
	s_nop 1
	v_cndmask_b32_e32 v76, v76, v61, vcc
	v_cmp_eq_u32_e32 vcc, 3, v74
	s_nop 1
	v_cndmask_b32_e32 v75, v75, v44, vcc
	v_cmp_eq_u32_e32 vcc, 3, v7
	s_nop 1
	v_cndmask_b32_e32 v76, v76, v60, vcc
	v_cmp_eq_u32_e32 vcc, 4, v74
	s_nop 1
	v_cndmask_b32_e32 v75, v75, v43, vcc
	v_cmp_eq_u32_e32 vcc, 4, v7
	s_nop 1
	v_cndmask_b32_e32 v76, v76, v59, vcc
	v_cmp_eq_u32_e32 vcc, 5, v74
	s_nop 1
	v_cndmask_b32_e32 v75, v75, v42, vcc
	v_cmp_eq_u32_e32 vcc, 5, v7
	s_nop 1
	v_cndmask_b32_e32 v76, v76, v58, vcc
	v_cmp_eq_u32_e32 vcc, 6, v74
	s_nop 1
	v_cndmask_b32_e32 v75, v75, v41, vcc
	v_cmp_eq_u32_e32 vcc, 6, v7
	s_nop 1
	v_cndmask_b32_e32 v76, v76, v57, vcc
	v_cmp_eq_u32_e32 vcc, 7, v74
	s_nop 1
	v_cndmask_b32_e32 v75, v75, v40, vcc
	v_cmp_eq_u32_e32 vcc, 7, v7
	s_nop 1
	v_cndmask_b32_e32 v76, v76, v56, vcc
	v_cmp_eq_u32_e32 vcc, 8, v74
	s_nop 1
	v_cndmask_b32_e32 v75, v75, v39, vcc
	v_cmp_eq_u32_e32 vcc, 8, v7
	s_nop 1
	v_cndmask_b32_e32 v76, v76, v55, vcc
	v_cmp_eq_u32_e32 vcc, 9, v74
	s_nop 1
	v_cndmask_b32_e32 v75, v75, v38, vcc
	v_cmp_eq_u32_e32 vcc, 9, v7
	s_nop 1
	v_cndmask_b32_e32 v76, v76, v54, vcc
	v_cmp_eq_u32_e32 vcc, 10, v74
	s_nop 1
	v_cndmask_b32_e32 v75, v75, v37, vcc
	v_cmp_eq_u32_e32 vcc, 10, v7
	s_nop 1
	v_cndmask_b32_e32 v76, v76, v53, vcc
	v_cmp_eq_u32_e32 vcc, 11, v74
	s_nop 1
	v_cndmask_b32_e32 v75, v75, v36, vcc
	v_cmp_eq_u32_e32 vcc, 11, v7
	s_nop 1
	v_cndmask_b32_e32 v76, v76, v52, vcc
	v_cmp_eq_u32_e32 vcc, 12, v74
	s_nop 1
	v_cndmask_b32_e32 v75, v75, v35, vcc
	v_cmp_eq_u32_e32 vcc, 12, v7
	s_nop 1
	v_cndmask_b32_e32 v76, v76, v51, vcc
; __device__ __forceinline__ void route_task(const Params& p, int layer, const u16* qg, int rb, int hd, int r, int h) {
;     ...
;     for (int jj = 0; jj < 16; ++jj) {
;       const unsigned flat = 255u - (ct[jj] & 255u);
;       const unsigned a = flat >> 4, b = flat & 15u;
;       unsigned ka = top[0][0], kb = top[1][0];
; #pragma unroll
;       for (int k = 1; k < 16; ++k) { ka = (a == (unsigned)k) ? top[0][k] : ka; kb = (b == (unsigned)k) ? top[1][k] : kb; }
;       eo[jj] = (127u - (ka & 127u)) * 128u + (127u - (kb & 127u));
;     }
	v_cmp_eq_u32_e32 vcc, 13, v74
	s_nop 1
	v_cndmask_b32_e32 v75, v75, v34, vcc
	v_cmp_eq_u32_e32 vcc, 13, v7
	s_nop 1
	v_cndmask_b32_e32 v76, v76, v49, vcc
	v_cmp_eq_u32_e32 vcc, 14, v74
	s_nop 1
	v_cndmask_b32_e32 v75, v75, v33, vcc
	v_cmp_eq_u32_e32 vcc, 14, v7
	s_nop 1
	v_cndmask_b32_e32 v76, v76, v48, vcc
	v_cmp_eq_u32_e32 vcc, 15, v74
	s_nop 1
	v_cndmask_b32_e32 v74, v75, v15, vcc
	v_cmp_eq_u32_e32 vcc, 15, v7
	v_lshlrev_b32_e32 v74, 7, v74
	v_and_b32_e32 v74, 0x3f80, v74
	v_cndmask_b32_e32 v7, v76, v47, vcc
	v_and_b32_e32 v7, 0x7f, v7
	v_cmp_eq_u32_e32 vcc, 1, v73
	v_bitop3_b32 v7, v74, s82, v7 bitop3:0x36
	s_nop 0
	v_cndmask_b32_e32 v74, v50, v46, vcc
	v_cmp_eq_u32_e32 vcc, 1, v8
	s_nop 1
	v_cndmask_b32_e32 v75, v63, v62, vcc
	v_cmp_eq_u32_e32 vcc, 2, v73
	s_nop 1
	v_cndmask_b32_e32 v74, v74, v45, vcc
	v_cmp_eq_u32_e32 vcc, 2, v8
	s_nop 1
	v_cndmask_b32_e32 v75, v75, v61, vcc
	v_cmp_eq_u32_e32 vcc, 3, v73
	s_nop 1
	v_cndmask_b32_e32 v74, v74, v44, vcc
	v_cmp_eq_u32_e32 vcc, 3, v8
	s_nop 1
	v_cndmask_b32_e32 v75, v75, v60, vcc
	v_cmp_eq_u32_e32 vcc, 4, v73
	s_nop 1
	v_cndmask_b32_e32 v74, v74, v43, vcc
	v_cmp_eq_u32_e32 vcc, 4, v8
	s_nop 1
	v_cndmask_b32_e32 v75, v75, v59, vcc
	v_cmp_eq_u32_e32 vcc, 5, v73
	s_nop 1
	v_cndmask_b32_e32 v74, v74, v42, vcc
	v_cmp_eq_u32_e32 vcc, 5, v8
	s_nop 1
	v_cndmask_b32_e32 v75, v75, v58, vcc
	v_cmp_eq_u32_e32 vcc, 6, v73
	s_nop 1
	v_cndmask_b32_e32 v74, v74, v41, vcc
	v_cmp_eq_u32_e32 vcc, 6, v8
	s_nop 1
	v_cndmask_b32_e32 v75, v75, v57, vcc
	v_cmp_eq_u32_e32 vcc, 7, v73
	s_nop 1
	v_cndmask_b32_e32 v74, v74, v40, vcc
	v_cmp_eq_u32_e32 vcc, 7, v8
	s_nop 1
	v_cndmask_b32_e32 v75, v75, v56, vcc
	v_cmp_eq_u32_e32 vcc, 8, v73
	s_nop 1
	v_cndmask_b32_e32 v74, v74, v39, vcc
	v_cmp_eq_u32_e32 vcc, 8, v8
	s_nop 1
	v_cndmask_b32_e32 v75, v75, v55, vcc
	v_cmp_eq_u32_e32 vcc, 9, v73
	s_nop 1
	v_cndmask_b32_e32 v74, v74, v38, vcc
	v_cmp_eq_u32_e32 vcc, 9, v8
	s_nop 1
	v_cndmask_b32_e32 v75, v75, v54, vcc
	v_cmp_eq_u32_e32 vcc, 10, v73
	s_nop 1
	v_cndmask_b32_e32 v74, v74, v37, vcc
	v_cmp_eq_u32_e32 vcc, 10, v8
	s_nop 1
	v_cndmask_b32_e32 v75, v75, v53, vcc
	v_cmp_eq_u32_e32 vcc, 11, v73
	s_nop 1
	v_cndmask_b32_e32 v74, v74, v36, vcc
	v_cmp_eq_u32_e32 vcc, 11, v8
	s_nop 1
	v_cndmask_b32_e32 v75, v75, v52, vcc
	v_cmp_eq_u32_e32 vcc, 12, v73
	s_nop 1
	v_cndmask_b32_e32 v74, v74, v35, vcc
	v_cmp_eq_u32_e32 vcc, 12, v8
	s_nop 1
	v_cndmask_b32_e32 v75, v75, v51, vcc
	v_cmp_eq_u32_e32 vcc, 13, v73
	s_nop 1
	v_cndmask_b32_e32 v74, v74, v34, vcc
	v_cmp_eq_u32_e32 vcc, 13, v8
	s_nop 1
	v_cndmask_b32_e32 v75, v75, v49, vcc
	v_cmp_eq_u32_e32 vcc, 14, v73
	s_nop 1
	v_cndmask_b32_e32 v74, v74, v33, vcc
	v_cmp_eq_u32_e32 vcc, 14, v8
	s_nop 1
	v_cndmask_b32_e32 v75, v75, v48, vcc
	v_cmp_eq_u32_e32 vcc, 15, v73
	s_nop 1
	v_cndmask_b32_e32 v73, v74, v15, vcc
	v_cmp_eq_u32_e32 vcc, 15, v8
	v_lshlrev_b32_e32 v73, 7, v73
	v_and_b32_e32 v73, 0x3f80, v73
	v_cndmask_b32_e32 v8, v75, v47, vcc
	v_and_b32_e32 v8, 0x7f, v8
	v_cmp_eq_u32_e32 vcc, 1, v72
	v_bitop3_b32 v8, v73, s82, v8 bitop3:0x36
	s_nop 0
	v_cndmask_b32_e32 v73, v50, v46, vcc
	v_cmp_eq_u32_e32 vcc, 1, v9
	s_nop 1
	v_cndmask_b32_e32 v74, v63, v62, vcc
	v_cmp_eq_u32_e32 vcc, 2, v72
	s_nop 1
	v_cndmask_b32_e32 v73, v73, v45, vcc
	v_cmp_eq_u32_e32 vcc, 2, v9
	s_nop 1
	v_cndmask_b32_e32 v74, v74, v61, vcc
	v_cmp_eq_u32_e32 vcc, 3, v72
	s_nop 1
	v_cndmask_b32_e32 v73, v73, v44, vcc
	v_cmp_eq_u32_e32 vcc, 3, v9
	s_nop 1
	v_cndmask_b32_e32 v74, v74, v60, vcc
	v_cmp_eq_u32_e32 vcc, 4, v72
	s_nop 1
	v_cndmask_b32_e32 v73, v73, v43, vcc
	v_cmp_eq_u32_e32 vcc, 4, v9
	s_nop 1
	v_cndmask_b32_e32 v74, v74, v59, vcc
	v_cmp_eq_u32_e32 vcc, 5, v72
	s_nop 1
	v_cndmask_b32_e32 v73, v73, v42, vcc
	v_cmp_eq_u32_e32 vcc, 5, v9
	s_nop 1
	v_cndmask_b32_e32 v74, v74, v58, vcc
	v_cmp_eq_u32_e32 vcc, 6, v72
	s_nop 1
	v_cndmask_b32_e32 v73, v73, v41, vcc
	v_cmp_eq_u32_e32 vcc, 6, v9
	s_nop 1
	v_cndmask_b32_e32 v74, v74, v57, vcc
	v_cmp_eq_u32_e32 vcc, 7, v72
	s_nop 1
	v_cndmask_b32_e32 v73, v73, v40, vcc
	v_cmp_eq_u32_e32 vcc, 7, v9
	s_nop 1
	v_cndmask_b32_e32 v74, v74, v56, vcc
	v_cmp_eq_u32_e32 vcc, 8, v72
	s_nop 1
	v_cndmask_b32_e32 v73, v73, v39, vcc
	v_cmp_eq_u32_e32 vcc, 8, v9
	s_nop 1
	v_cndmask_b32_e32 v74, v74, v55, vcc
	v_cmp_eq_u32_e32 vcc, 9, v72
	s_nop 1
	v_cndmask_b32_e32 v73, v73, v38, vcc
	v_cmp_eq_u32_e32 vcc, 9, v9
	s_nop 1
	v_cndmask_b32_e32 v74, v74, v54, vcc
	v_cmp_eq_u32_e32 vcc, 10, v72
	s_nop 1
	v_cndmask_b32_e32 v73, v73, v37, vcc
	v_cmp_eq_u32_e32 vcc, 10, v9
	s_nop 1
	v_cndmask_b32_e32 v74, v74, v53, vcc
	v_cmp_eq_u32_e32 vcc, 11, v72
	s_nop 1
	v_cndmask_b32_e32 v73, v73, v36, vcc
	v_cmp_eq_u32_e32 vcc, 11, v9
	s_nop 1
	v_cndmask_b32_e32 v74, v74, v52, vcc
	v_cmp_eq_u32_e32 vcc, 12, v72
	s_nop 1
	v_cndmask_b32_e32 v73, v73, v35, vcc
	v_cmp_eq_u32_e32 vcc, 12, v9
	s_nop 1
	v_cndmask_b32_e32 v74, v74, v51, vcc
	v_cmp_eq_u32_e32 vcc, 13, v72
	s_nop 1
	v_cndmask_b32_e32 v73, v73, v34, vcc
	v_cmp_eq_u32_e32 vcc, 13, v9
	s_nop 1
	v_cndmask_b32_e32 v74, v74, v49, vcc
	v_cmp_eq_u32_e32 vcc, 14, v72
	s_nop 1
	v_cndmask_b32_e32 v73, v73, v33, vcc
	v_cmp_eq_u32_e32 vcc, 14, v9
	s_nop 1
	v_cndmask_b32_e32 v74, v74, v48, vcc
	v_cmp_eq_u32_e32 vcc, 15, v72
	s_nop 1
	v_cndmask_b32_e32 v72, v73, v15, vcc
	v_cmp_eq_u32_e32 vcc, 15, v9
	v_lshlrev_b32_e32 v72, 7, v72
	v_and_b32_e32 v72, 0x3f80, v72
	v_cndmask_b32_e32 v9, v74, v47, vcc
	v_and_b32_e32 v9, 0x7f, v9
	v_cmp_eq_u32_e32 vcc, 1, v71
	v_bitop3_b32 v9, v72, s82, v9 bitop3:0x36
	s_nop 0
	v_cndmask_b32_e32 v72, v50, v46, vcc
	v_cmp_eq_u32_e32 vcc, 1, v10
	s_nop 1
	v_cndmask_b32_e32 v73, v63, v62, vcc
	v_cmp_eq_u32_e32 vcc, 2, v71
	s_nop 1
; __device__ __forceinline__ void route_task(const Params& p, int layer, const u16* qg, int rb, int hd, int r, int h) {
;     ...
;     for (int jj = 0; jj < 16; ++jj) {
;       const unsigned flat = 255u - (ct[jj] & 255u);
;       const unsigned a = flat >> 4, b = flat & 15u;
;       unsigned ka = top[0][0], kb = top[1][0];
; #pragma unroll
;       for (int k = 1; k < 16; ++k) { ka = (a == (unsigned)k) ? top[0][k] : ka; kb = (b == (unsigned)k) ? top[1][k] : kb; }
;       eo[jj] = (127u - (ka & 127u)) * 128u + (127u - (kb & 127u));
;     }
	v_cndmask_b32_e32 v72, v72, v45, vcc
	v_cmp_eq_u32_e32 vcc, 2, v10
	s_nop 1
	v_cndmask_b32_e32 v73, v73, v61, vcc
	v_cmp_eq_u32_e32 vcc, 3, v71
	s_nop 1
	v_cndmask_b32_e32 v72, v72, v44, vcc
	v_cmp_eq_u32_e32 vcc, 3, v10
	s_nop 1
	v_cndmask_b32_e32 v73, v73, v60, vcc
	v_cmp_eq_u32_e32 vcc, 4, v71
	s_nop 1
	v_cndmask_b32_e32 v72, v72, v43, vcc
	v_cmp_eq_u32_e32 vcc, 4, v10
	s_nop 1
	v_cndmask_b32_e32 v73, v73, v59, vcc
	v_cmp_eq_u32_e32 vcc, 5, v71
	s_nop 1
	v_cndmask_b32_e32 v72, v72, v42, vcc
	v_cmp_eq_u32_e32 vcc, 5, v10
	s_nop 1
	v_cndmask_b32_e32 v73, v73, v58, vcc
	v_cmp_eq_u32_e32 vcc, 6, v71
	s_nop 1
	v_cndmask_b32_e32 v72, v72, v41, vcc
	v_cmp_eq_u32_e32 vcc, 6, v10
	s_nop 1
	v_cndmask_b32_e32 v73, v73, v57, vcc
	v_cmp_eq_u32_e32 vcc, 7, v71
	s_nop 1
	v_cndmask_b32_e32 v72, v72, v40, vcc
	v_cmp_eq_u32_e32 vcc, 7, v10
	s_nop 1
	v_cndmask_b32_e32 v73, v73, v56, vcc
	v_cmp_eq_u32_e32 vcc, 8, v71
	s_nop 1
	v_cndmask_b32_e32 v72, v72, v39, vcc
	v_cmp_eq_u32_e32 vcc, 8, v10
	s_nop 1
	v_cndmask_b32_e32 v73, v73, v55, vcc
	v_cmp_eq_u32_e32 vcc, 9, v71
	s_nop 1
	v_cndmask_b32_e32 v72, v72, v38, vcc
	v_cmp_eq_u32_e32 vcc, 9, v10
	s_nop 1
	v_cndmask_b32_e32 v73, v73, v54, vcc
	v_cmp_eq_u32_e32 vcc, 10, v71
	s_nop 1
	v_cndmask_b32_e32 v72, v72, v37, vcc
	v_cmp_eq_u32_e32 vcc, 10, v10
	s_nop 1
	v_cndmask_b32_e32 v73, v73, v53, vcc
	v_cmp_eq_u32_e32 vcc, 11, v71
	s_nop 1
	v_cndmask_b32_e32 v72, v72, v36, vcc
	v_cmp_eq_u32_e32 vcc, 11, v10
	s_nop 1
	v_cndmask_b32_e32 v73, v73, v52, vcc
	v_cmp_eq_u32_e32 vcc, 12, v71
	s_nop 1
	v_cndmask_b32_e32 v72, v72, v35, vcc
	v_cmp_eq_u32_e32 vcc, 12, v10
	s_nop 1
	v_cndmask_b32_e32 v73, v73, v51, vcc
	v_cmp_eq_u32_e32 vcc, 13, v71
	s_nop 1
	v_cndmask_b32_e32 v72, v72, v34, vcc
	v_cmp_eq_u32_e32 vcc, 13, v10
	s_nop 1
	v_cndmask_b32_e32 v73, v73, v49, vcc
	v_cmp_eq_u32_e32 vcc, 14, v71
	s_nop 1
	v_cndmask_b32_e32 v72, v72, v33, vcc
	v_cmp_eq_u32_e32 vcc, 14, v10
	s_nop 1
	v_cndmask_b32_e32 v73, v73, v48, vcc
	v_cmp_eq_u32_e32 vcc, 15, v71
	s_nop 1
	v_cndmask_b32_e32 v71, v72, v15, vcc
	v_cmp_eq_u32_e32 vcc, 15, v10
	v_lshlrev_b32_e32 v71, 7, v71
	v_and_b32_e32 v71, 0x3f80, v71
	v_cndmask_b32_e32 v10, v73, v47, vcc
	v_and_b32_e32 v10, 0x7f, v10
	v_cmp_eq_u32_e32 vcc, 1, v70
	v_bitop3_b32 v10, v71, s82, v10 bitop3:0x36
	s_nop 0
	v_cndmask_b32_e32 v71, v50, v46, vcc
	v_cmp_eq_u32_e32 vcc, 1, v11
	s_nop 1
	v_cndmask_b32_e32 v72, v63, v62, vcc
	v_cmp_eq_u32_e32 vcc, 2, v70
	s_nop 1
	v_cndmask_b32_e32 v71, v71, v45, vcc
	v_cmp_eq_u32_e32 vcc, 2, v11
	s_nop 1
	v_cndmask_b32_e32 v72, v72, v61, vcc
	v_cmp_eq_u32_e32 vcc, 3, v70
	s_nop 1
	v_cndmask_b32_e32 v71, v71, v44, vcc
	v_cmp_eq_u32_e32 vcc, 3, v11
	s_nop 1
	v_cndmask_b32_e32 v72, v72, v60, vcc
	v_cmp_eq_u32_e32 vcc, 4, v70
	s_nop 1
	v_cndmask_b32_e32 v71, v71, v43, vcc
	v_cmp_eq_u32_e32 vcc, 4, v11
	s_nop 1
	v_cndmask_b32_e32 v72, v72, v59, vcc
	v_cmp_eq_u32_e32 vcc, 5, v70
	s_nop 1
	v_cndmask_b32_e32 v71, v71, v42, vcc
	v_cmp_eq_u32_e32 vcc, 5, v11
	s_nop 1
	v_cndmask_b32_e32 v72, v72, v58, vcc
	v_cmp_eq_u32_e32 vcc, 6, v70
	s_nop 1
	v_cndmask_b32_e32 v71, v71, v41, vcc
	v_cmp_eq_u32_e32 vcc, 6, v11
	s_nop 1
	v_cndmask_b32_e32 v72, v72, v57, vcc
	v_cmp_eq_u32_e32 vcc, 7, v70
	s_nop 1
	v_cndmask_b32_e32 v71, v71, v40, vcc
	v_cmp_eq_u32_e32 vcc, 7, v11
	s_nop 1
	v_cndmask_b32_e32 v72, v72, v56, vcc
	v_cmp_eq_u32_e32 vcc, 8, v70
	s_nop 1
	v_cndmask_b32_e32 v71, v71, v39, vcc
	v_cmp_eq_u32_e32 vcc, 8, v11
	s_nop 1
	v_cndmask_b32_e32 v72, v72, v55, vcc
	v_cmp_eq_u32_e32 vcc, 9, v70
	s_nop 1
	v_cndmask_b32_e32 v71, v71, v38, vcc
	v_cmp_eq_u32_e32 vcc, 9, v11
	s_nop 1
	v_cndmask_b32_e32 v72, v72, v54, vcc
	v_cmp_eq_u32_e32 vcc, 10, v70
	s_nop 1
	v_cndmask_b32_e32 v71, v71, v37, vcc
	v_cmp_eq_u32_e32 vcc, 10, v11
	s_nop 1
	v_cndmask_b32_e32 v72, v72, v53, vcc
	v_cmp_eq_u32_e32 vcc, 11, v70
	s_nop 1
	v_cndmask_b32_e32 v71, v71, v36, vcc
	v_cmp_eq_u32_e32 vcc, 11, v11
	s_nop 1
	v_cndmask_b32_e32 v72, v72, v52, vcc
	v_cmp_eq_u32_e32 vcc, 12, v70
	s_nop 1
	v_cndmask_b32_e32 v71, v71, v35, vcc
	v_cmp_eq_u32_e32 vcc, 12, v11
	s_nop 1
	v_cndmask_b32_e32 v72, v72, v51, vcc
	v_cmp_eq_u32_e32 vcc, 13, v70
	s_nop 1
	v_cndmask_b32_e32 v71, v71, v34, vcc
	v_cmp_eq_u32_e32 vcc, 13, v11
	s_nop 1
	v_cndmask_b32_e32 v72, v72, v49, vcc
	v_cmp_eq_u32_e32 vcc, 14, v70
	s_nop 1
	v_cndmask_b32_e32 v71, v71, v33, vcc
	v_cmp_eq_u32_e32 vcc, 14, v11
	s_nop 1
	v_cndmask_b32_e32 v72, v72, v48, vcc
	v_cmp_eq_u32_e32 vcc, 15, v70
	s_nop 1
	v_cndmask_b32_e32 v70, v71, v15, vcc
	v_cmp_eq_u32_e32 vcc, 15, v11
	v_lshlrev_b32_e32 v70, 7, v70
	v_and_b32_e32 v70, 0x3f80, v70
	v_cndmask_b32_e32 v11, v72, v47, vcc
	v_and_b32_e32 v11, 0x7f, v11
	v_cmp_eq_u32_e32 vcc, 1, v69
	v_bitop3_b32 v11, v70, s82, v11 bitop3:0x36
	s_nop 0
	v_cndmask_b32_e32 v70, v50, v46, vcc
	v_cmp_eq_u32_e32 vcc, 1, v12
	s_nop 1
	v_cndmask_b32_e32 v71, v63, v62, vcc
	v_cmp_eq_u32_e32 vcc, 2, v69
	s_nop 1
	v_cndmask_b32_e32 v70, v70, v45, vcc
	v_cmp_eq_u32_e32 vcc, 2, v12
	s_nop 1
	v_cndmask_b32_e32 v71, v71, v61, vcc
	v_cmp_eq_u32_e32 vcc, 3, v69
	s_nop 1
	v_cndmask_b32_e32 v70, v70, v44, vcc
	v_cmp_eq_u32_e32 vcc, 3, v12
	s_nop 1
	v_cndmask_b32_e32 v71, v71, v60, vcc
	v_cmp_eq_u32_e32 vcc, 4, v69
	s_nop 1
	v_cndmask_b32_e32 v70, v70, v43, vcc
	v_cmp_eq_u32_e32 vcc, 4, v12
	s_nop 1
	v_cndmask_b32_e32 v71, v71, v59, vcc
	v_cmp_eq_u32_e32 vcc, 5, v69
	s_nop 1
	v_cndmask_b32_e32 v70, v70, v42, vcc
	v_cmp_eq_u32_e32 vcc, 5, v12
	s_nop 1
	v_cndmask_b32_e32 v71, v71, v58, vcc
	v_cmp_eq_u32_e32 vcc, 6, v69
	s_nop 1
	v_cndmask_b32_e32 v70, v70, v41, vcc
	v_cmp_eq_u32_e32 vcc, 6, v12
	s_nop 1
	v_cndmask_b32_e32 v71, v71, v57, vcc
; __device__ __forceinline__ void route_task(const Params& p, int layer, const u16* qg, int rb, int hd, int r, int h) {
;     ...
;     for (int jj = 0; jj < 16; ++jj) {
;       const unsigned flat = 255u - (ct[jj] & 255u);
;       const unsigned a = flat >> 4, b = flat & 15u;
;       unsigned ka = top[0][0], kb = top[1][0];
; #pragma unroll
;       for (int k = 1; k < 16; ++k) { ka = (a == (unsigned)k) ? top[0][k] : ka; kb = (b == (unsigned)k) ? top[1][k] : kb; }
;       eo[jj] = (127u - (ka & 127u)) * 128u + (127u - (kb & 127u));
;     }
	v_cmp_eq_u32_e32 vcc, 7, v69
	s_nop 1
	v_cndmask_b32_e32 v70, v70, v40, vcc
	v_cmp_eq_u32_e32 vcc, 7, v12
	s_nop 1
	v_cndmask_b32_e32 v71, v71, v56, vcc
	v_cmp_eq_u32_e32 vcc, 8, v69
	s_nop 1
	v_cndmask_b32_e32 v70, v70, v39, vcc
	v_cmp_eq_u32_e32 vcc, 8, v12
	s_nop 1
	v_cndmask_b32_e32 v71, v71, v55, vcc
	v_cmp_eq_u32_e32 vcc, 9, v69
	s_nop 1
	v_cndmask_b32_e32 v70, v70, v38, vcc
	v_cmp_eq_u32_e32 vcc, 9, v12
	s_nop 1
	v_cndmask_b32_e32 v71, v71, v54, vcc
	v_cmp_eq_u32_e32 vcc, 10, v69
	s_nop 1
	v_cndmask_b32_e32 v70, v70, v37, vcc
	v_cmp_eq_u32_e32 vcc, 10, v12
	s_nop 1
	v_cndmask_b32_e32 v71, v71, v53, vcc
	v_cmp_eq_u32_e32 vcc, 11, v69
	s_nop 1
	v_cndmask_b32_e32 v70, v70, v36, vcc
	v_cmp_eq_u32_e32 vcc, 11, v12
	s_nop 1
	v_cndmask_b32_e32 v71, v71, v52, vcc
	v_cmp_eq_u32_e32 vcc, 12, v69
	s_nop 1
	v_cndmask_b32_e32 v70, v70, v35, vcc
	v_cmp_eq_u32_e32 vcc, 12, v12
	s_nop 1
	v_cndmask_b32_e32 v71, v71, v51, vcc
	v_cmp_eq_u32_e32 vcc, 13, v69
	s_nop 1
	v_cndmask_b32_e32 v70, v70, v34, vcc
	v_cmp_eq_u32_e32 vcc, 13, v12
	s_nop 1
	v_cndmask_b32_e32 v71, v71, v49, vcc
	v_cmp_eq_u32_e32 vcc, 14, v69
	s_nop 1
	v_cndmask_b32_e32 v70, v70, v33, vcc
	v_cmp_eq_u32_e32 vcc, 14, v12
	s_nop 1
	v_cndmask_b32_e32 v71, v71, v48, vcc
	v_cmp_eq_u32_e32 vcc, 15, v69
	s_nop 1
	v_cndmask_b32_e32 v69, v70, v15, vcc
	v_cmp_eq_u32_e32 vcc, 15, v12
	v_lshlrev_b32_e32 v69, 7, v69
	v_and_b32_e32 v69, 0x3f80, v69
	v_cndmask_b32_e32 v12, v71, v47, vcc
	v_and_b32_e32 v12, 0x7f, v12
	v_cmp_eq_u32_e32 vcc, 1, v68
	v_bitop3_b32 v12, v69, s82, v12 bitop3:0x36
	s_nop 0
	v_cndmask_b32_e32 v69, v50, v46, vcc
	v_cmp_eq_u32_e32 vcc, 1, v13
	s_nop 1
	v_cndmask_b32_e32 v70, v63, v62, vcc
	v_cmp_eq_u32_e32 vcc, 2, v68
	s_nop 1
	v_cndmask_b32_e32 v69, v69, v45, vcc
	v_cmp_eq_u32_e32 vcc, 2, v13
	s_nop 1
	v_cndmask_b32_e32 v70, v70, v61, vcc
	v_cmp_eq_u32_e32 vcc, 3, v68
	s_nop 1
	v_cndmask_b32_e32 v69, v69, v44, vcc
	v_cmp_eq_u32_e32 vcc, 3, v13
	s_nop 1
	v_cndmask_b32_e32 v70, v70, v60, vcc
	v_cmp_eq_u32_e32 vcc, 4, v68
	s_nop 1
	v_cndmask_b32_e32 v69, v69, v43, vcc
	v_cmp_eq_u32_e32 vcc, 4, v13
	s_nop 1
	v_cndmask_b32_e32 v70, v70, v59, vcc
	v_cmp_eq_u32_e32 vcc, 5, v68
	s_nop 1
	v_cndmask_b32_e32 v69, v69, v42, vcc
	v_cmp_eq_u32_e32 vcc, 5, v13
	s_nop 1
	v_cndmask_b32_e32 v70, v70, v58, vcc
	v_cmp_eq_u32_e32 vcc, 6, v68
	s_nop 1
	v_cndmask_b32_e32 v69, v69, v41, vcc
	v_cmp_eq_u32_e32 vcc, 6, v13
	s_nop 1
	v_cndmask_b32_e32 v70, v70, v57, vcc
	v_cmp_eq_u32_e32 vcc, 7, v68
	s_nop 1
	v_cndmask_b32_e32 v69, v69, v40, vcc
	v_cmp_eq_u32_e32 vcc, 7, v13
	s_nop 1
	v_cndmask_b32_e32 v70, v70, v56, vcc
	v_cmp_eq_u32_e32 vcc, 8, v68
	s_nop 1
	v_cndmask_b32_e32 v69, v69, v39, vcc
	v_cmp_eq_u32_e32 vcc, 8, v13
	s_nop 1
	v_cndmask_b32_e32 v70, v70, v55, vcc
	v_cmp_eq_u32_e32 vcc, 9, v68
	s_nop 1
	v_cndmask_b32_e32 v69, v69, v38, vcc
	v_cmp_eq_u32_e32 vcc, 9, v13
	s_nop 1
	v_cndmask_b32_e32 v70, v70, v54, vcc
	v_cmp_eq_u32_e32 vcc, 10, v68
	s_nop 1
	v_cndmask_b32_e32 v69, v69, v37, vcc
	v_cmp_eq_u32_e32 vcc, 10, v13
	s_nop 1
	v_cndmask_b32_e32 v70, v70, v53, vcc
	v_cmp_eq_u32_e32 vcc, 11, v68
	s_nop 1
	v_cndmask_b32_e32 v69, v69, v36, vcc
	v_cmp_eq_u32_e32 vcc, 11, v13
	s_nop 1
	v_cndmask_b32_e32 v70, v70, v52, vcc
	v_cmp_eq_u32_e32 vcc, 12, v68
	s_nop 1
	v_cndmask_b32_e32 v69, v69, v35, vcc
	v_cmp_eq_u32_e32 vcc, 12, v13
	s_nop 1
	v_cndmask_b32_e32 v70, v70, v51, vcc
	v_cmp_eq_u32_e32 vcc, 13, v68
	s_nop 1
	v_cndmask_b32_e32 v69, v69, v34, vcc
	v_cmp_eq_u32_e32 vcc, 13, v13
	s_nop 1
	v_cndmask_b32_e32 v70, v70, v49, vcc
	v_cmp_eq_u32_e32 vcc, 14, v68
	s_nop 1
	v_cndmask_b32_e32 v69, v69, v33, vcc
	v_cmp_eq_u32_e32 vcc, 14, v13
	s_nop 1
	v_cndmask_b32_e32 v70, v70, v48, vcc
	v_cmp_eq_u32_e32 vcc, 15, v68
	s_nop 1
	v_cndmask_b32_e32 v68, v69, v15, vcc
	v_cmp_eq_u32_e32 vcc, 15, v13
	v_lshlrev_b32_e32 v68, 7, v68
	v_and_b32_e32 v68, 0x3f80, v68
	v_cndmask_b32_e32 v13, v70, v47, vcc
	v_and_b32_e32 v13, 0x7f, v13
	v_cmp_eq_u32_e32 vcc, 1, v66
	v_bitop3_b32 v13, v68, s82, v13 bitop3:0x36
	s_nop 0
	v_cndmask_b32_e32 v68, v50, v46, vcc
	v_cmp_eq_u32_e32 vcc, 1, v14
	s_nop 1
	v_cndmask_b32_e32 v69, v63, v62, vcc
	v_cmp_eq_u32_e32 vcc, 2, v66
	s_nop 1
	v_cndmask_b32_e32 v68, v68, v45, vcc
	v_cmp_eq_u32_e32 vcc, 2, v14
	s_nop 1
	v_cndmask_b32_e32 v69, v69, v61, vcc
	v_cmp_eq_u32_e32 vcc, 3, v66
	s_nop 1
	v_cndmask_b32_e32 v68, v68, v44, vcc
	v_cmp_eq_u32_e32 vcc, 3, v14
	s_nop 1
	v_cndmask_b32_e32 v69, v69, v60, vcc
	v_cmp_eq_u32_e32 vcc, 4, v66
	s_nop 1
	v_cndmask_b32_e32 v68, v68, v43, vcc
	v_cmp_eq_u32_e32 vcc, 4, v14
	s_nop 1
	v_cndmask_b32_e32 v69, v69, v59, vcc
	v_cmp_eq_u32_e32 vcc, 5, v66
	s_nop 1
	v_cndmask_b32_e32 v68, v68, v42, vcc
	v_cmp_eq_u32_e32 vcc, 5, v14
	s_nop 1
	v_cndmask_b32_e32 v69, v69, v58, vcc
	v_cmp_eq_u32_e32 vcc, 6, v66
	s_nop 1
	v_cndmask_b32_e32 v68, v68, v41, vcc
	v_cmp_eq_u32_e32 vcc, 6, v14
	s_nop 1
	v_cndmask_b32_e32 v69, v69, v57, vcc
	v_cmp_eq_u32_e32 vcc, 7, v66
	s_nop 1
	v_cndmask_b32_e32 v68, v68, v40, vcc
	v_cmp_eq_u32_e32 vcc, 7, v14
	s_nop 1
	v_cndmask_b32_e32 v69, v69, v56, vcc
	v_cmp_eq_u32_e32 vcc, 8, v66
	s_nop 1
	v_cndmask_b32_e32 v68, v68, v39, vcc
	v_cmp_eq_u32_e32 vcc, 8, v14
	s_nop 1
	v_cndmask_b32_e32 v69, v69, v55, vcc
	v_cmp_eq_u32_e32 vcc, 9, v66
; __device__ __forceinline__ void route_task(const Params& p, int layer, const u16* qg, int rb, int hd, int r, int h) {
;     ...
;     const float inv = 1.f / den;
;     unsigned eo[16];
; #pragma unroll
;     for (int jj = 0; jj < 16; ++jj) {
;       const unsigned flat = 255u - (ct[jj] & 255u);
;       const unsigned a = flat >> 4, b = flat & 15u;
;       unsigned ka = top[0][0], kb = top[1][0];
; #pragma unroll
;       for (int k = 1; k < 16; ++k) { ka = (a == (unsigned)k) ? top[0][k] : ka; kb = (b == (unsigned)k) ? top[1][k] : kb; }
;       eo[jj] = (127u - (ka & 127u)) * 128u + (127u - (kb & 127u));
;     }
;     const size_t ob = (size_t)(rb + r) * 128 + hd * 16;
; #pragma unroll
;     for (int g4 = 0; g4 < 4; ++g4) {
;       *(u32x4*)(EX + ob + g4 * 4) = u32x4{eo[g4 * 4], eo[g4 * 4 + 1], eo[g4 * 4 + 2], eo[g4 * 4 + 3]};
;       *(f32x4*)(GT + ob + g4 * 4) = f32x4{vs[g4 * 4] * inv, vs[g4 * 4 + 1] * inv, vs[g4 * 4 + 2] * inv, vs[g4 * 4 + 3] * inv};
;     }
	s_nop 1
	v_cndmask_b32_e32 v68, v68, v38, vcc
	v_cmp_eq_u32_e32 vcc, 9, v14
	s_nop 1
	v_cndmask_b32_e32 v69, v69, v54, vcc
	v_cmp_eq_u32_e32 vcc, 10, v66
	s_nop 1
	v_cndmask_b32_e32 v68, v68, v37, vcc
	v_cmp_eq_u32_e32 vcc, 10, v14
	s_nop 1
	v_cndmask_b32_e32 v69, v69, v53, vcc
	v_cmp_eq_u32_e32 vcc, 11, v66
	s_nop 1
	v_cndmask_b32_e32 v68, v68, v36, vcc
	v_cmp_eq_u32_e32 vcc, 11, v14
	s_nop 1
	v_cndmask_b32_e32 v69, v69, v52, vcc
	v_cmp_eq_u32_e32 vcc, 12, v66
	s_nop 1
	v_cndmask_b32_e32 v68, v68, v35, vcc
	v_cmp_eq_u32_e32 vcc, 12, v14
	s_nop 1
	v_cndmask_b32_e32 v69, v69, v51, vcc
	v_cmp_eq_u32_e32 vcc, 13, v66
	s_nop 1
	v_cndmask_b32_e32 v68, v68, v34, vcc
	v_cmp_eq_u32_e32 vcc, 13, v14
	s_nop 1
	v_cndmask_b32_e32 v69, v69, v49, vcc
	v_cmp_eq_u32_e32 vcc, 14, v66
	s_nop 1
	v_cndmask_b32_e32 v68, v68, v33, vcc
	v_cmp_eq_u32_e32 vcc, 14, v14
	s_nop 1
	v_cndmask_b32_e32 v69, v69, v48, vcc
	v_cmp_eq_u32_e32 vcc, 15, v66
	s_nop 1
	v_cndmask_b32_e32 v66, v68, v15, vcc
	v_cmp_eq_u32_e32 vcc, 15, v14
	v_lshlrev_b32_e32 v66, 7, v66
	v_and_b32_e32 v66, 0x3f80, v66
	v_cndmask_b32_e32 v14, v69, v47, vcc
	v_cmp_eq_u32_e32 vcc, 1, v65
	v_and_b32_e32 v14, 0x7f, v14
	v_bitop3_b32 v14, v66, s82, v14 bitop3:0x36
	v_cndmask_b32_e32 v46, v50, v46, vcc
	v_cmp_eq_u32_e32 vcc, 1, v64
	s_nop 1
	v_cndmask_b32_e32 v50, v63, v62, vcc
	v_cmp_eq_u32_e32 vcc, 2, v65
	s_nop 1
	v_cndmask_b32_e32 v45, v46, v45, vcc
	v_cmp_eq_u32_e32 vcc, 2, v64
	s_nop 1
	v_cndmask_b32_e32 v46, v50, v61, vcc
	v_cmp_eq_u32_e32 vcc, 3, v65
	s_nop 1
	v_cndmask_b32_e32 v44, v45, v44, vcc
	v_cmp_eq_u32_e32 vcc, 3, v64
	s_nop 1
	v_cndmask_b32_e32 v45, v46, v60, vcc
	v_cmp_eq_u32_e32 vcc, 4, v65
	s_nop 1
	v_cndmask_b32_e32 v43, v44, v43, vcc
	v_cmp_eq_u32_e32 vcc, 4, v64
	s_nop 1
	v_cndmask_b32_e32 v44, v45, v59, vcc
	v_cmp_eq_u32_e32 vcc, 5, v65
	s_nop 1
	v_cndmask_b32_e32 v42, v43, v42, vcc
	v_cmp_eq_u32_e32 vcc, 5, v64
	s_nop 1
	v_cndmask_b32_e32 v43, v44, v58, vcc
	v_cmp_eq_u32_e32 vcc, 6, v65
	s_nop 1
	v_cndmask_b32_e32 v41, v42, v41, vcc
	v_cmp_eq_u32_e32 vcc, 6, v64
	s_nop 1
	v_cndmask_b32_e32 v42, v43, v57, vcc
	v_cmp_eq_u32_e32 vcc, 7, v65
	s_nop 1
	v_cndmask_b32_e32 v40, v41, v40, vcc
	v_cmp_eq_u32_e32 vcc, 7, v64
	s_nop 1
	v_cndmask_b32_e32 v41, v42, v56, vcc
	v_cmp_eq_u32_e32 vcc, 8, v65
	s_nop 1
	v_cndmask_b32_e32 v39, v40, v39, vcc
	v_cmp_eq_u32_e32 vcc, 8, v64
	s_nop 1
	v_cndmask_b32_e32 v40, v41, v55, vcc
	v_cmp_eq_u32_e32 vcc, 9, v65
	s_nop 1
	v_cndmask_b32_e32 v38, v39, v38, vcc
	v_cmp_eq_u32_e32 vcc, 9, v64
	s_nop 1
	v_cndmask_b32_e32 v39, v40, v54, vcc
	v_cmp_eq_u32_e32 vcc, 10, v65
	s_nop 1
	v_cndmask_b32_e32 v37, v38, v37, vcc
	v_cmp_eq_u32_e32 vcc, 10, v64
	s_nop 1
	v_cndmask_b32_e32 v38, v39, v53, vcc
	v_cmp_eq_u32_e32 vcc, 11, v65
	s_nop 1
	v_cndmask_b32_e32 v36, v37, v36, vcc
	v_cmp_eq_u32_e32 vcc, 11, v64
	s_nop 1
	v_cndmask_b32_e32 v37, v38, v52, vcc
	v_cmp_eq_u32_e32 vcc, 12, v65
	s_nop 1
	v_cndmask_b32_e32 v35, v36, v35, vcc
	v_cmp_eq_u32_e32 vcc, 12, v64
	s_nop 1
	v_cndmask_b32_e32 v36, v37, v51, vcc
	v_cmp_eq_u32_e32 vcc, 13, v65
	s_nop 1
	v_cndmask_b32_e32 v34, v35, v34, vcc
	v_cmp_eq_u32_e32 vcc, 13, v64
	s_nop 1
	v_cndmask_b32_e32 v35, v36, v49, vcc
	v_cmp_eq_u32_e32 vcc, 14, v65
	s_nop 1
	v_cndmask_b32_e32 v33, v34, v33, vcc
	v_cmp_eq_u32_e32 vcc, 14, v64
	s_nop 1
	v_cndmask_b32_e32 v34, v35, v48, vcc
	v_cmp_eq_u32_e32 vcc, 15, v65
	s_nop 1
	v_cndmask_b32_e32 v15, v33, v15, vcc
	v_cmp_eq_u32_e32 vcc, 15, v64
	v_lshlrev_b32_e32 v15, 7, v15
	v_and_b32_e32 v15, 0x3f80, v15
	v_cndmask_b32_e32 v33, v34, v47, vcc
	v_div_scale_f32 v34, s[34:35], v67, v67, 1.0
	v_rcp_f32_e32 v35, v34
	v_and_b32_e32 v33, 0x7f, v33
	v_bitop3_b32 v15, v15, s82, v33 bitop3:0x36
	s_lshl_b32 s34, s83, 4
	v_fma_f32 v33, -v34, v35, 1.0
	v_fmac_f32_e32 v35, v33, v35
	v_div_scale_f32 v33, vcc, 1.0, v67, 1.0
	v_mul_f32_e32 v36, v33, v35
	v_fma_f32 v37, -v34, v36, v33
	v_fmac_f32_e32 v36, v37, v35
	v_fma_f32 v33, -v34, v36, v33
	v_div_fmas_f32 v33, v33, v35, v36
	v_div_fixup_f32 v34, v33, v67, 1.0
	v_ashrrev_i32_e32 v33, 31, v32
	v_lshlrev_b64 v[32:33], 7, v[32:33]
	s_ashr_i32 s35, s34, 31
	v_lshl_add_u64 v[32:33], v[32:33], 0, s[34:35]
	v_lshlrev_b64 v[32:33], 2, v[32:33]
	v_lshl_add_u64 v[36:37], s[10:11], 0, v[32:33]
	v_lshl_add_u64 v[32:33], s[8:9], 0, v[32:33]
	global_store_dwordx4 v[36:37], v[0:3], off
	s_nop 1
	v_pk_mul_f32 v[2:3], v[18:19], v[34:35] op_sel_hi:[1,0]
	v_pk_mul_f32 v[0:1], v[16:17], v[34:35] op_sel_hi:[1,0]
	global_store_dwordx4 v[32:33], v[0:3], off
	global_store_dwordx4 v[36:37], v[4:7], off offset:16
	s_nop 0
	v_pk_mul_f32 v[2:3], v[22:23], v[34:35] op_sel_hi:[1,0]
	v_pk_mul_f32 v[0:1], v[20:21], v[34:35] op_sel_hi:[1,0]
	global_store_dwordx4 v[32:33], v[0:3], off offset:16
	global_store_dwordx4 v[36:37], v[8:11], off offset:32
	s_nop 0
	v_pk_mul_f32 v[2:3], v[26:27], v[34:35] op_sel_hi:[1,0]
	v_pk_mul_f32 v[0:1], v[24:25], v[34:35] op_sel_hi:[1,0]
	global_store_dwordx4 v[32:33], v[0:3], off offset:32
	global_store_dwordx4 v[36:37], v[12:15], off offset:48
	s_nop 0
	v_pk_mul_f32 v[2:3], v[30:31], v[34:35] op_sel_hi:[1,0]
	v_pk_mul_f32 v[0:1], v[28:29], v[34:35] op_sel_hi:[1,0]
	global_store_dwordx4 v[32:33], v[0:3], off offset:48
	s_branch .LBB0_1867

; DI u16 f2bf(float a) { return (u16)(pk2(a, 0.f) & 0xffffu); }
; DI int crow(int i, int h) { return (i & 3) + 8 * (i >> 2) + 4 * h; }
; template <int EPI>
; __device__ __forceinline__ void gemm_tile(const Params& p, int layer, const u16* __restrict__ A, const u16* __restrict__ Bt, int mt, int nt, char* lds) {
;     ...
;         if (latent && (ropeA || ropeB)) {
;           int pair, nf; bool userow; const f32x2* tab;
;           if (ropeA) { pair = (gc & 63) >> 1; nf = 16; tab = (const f32x2*)(p.ws + OFF_TABA); }
;           else       { pair = (gc & 127) >> 1; nf = 32; tab = (const f32x2*)(p.ws + OFF_TABB); }
;           userow = pair < nf;
;           const int f = userow ? pair : pair - nf;
; #pragma unroll
;           for (int e = 0; e < 16; ++e) {
;             const int gr = grb + crow(e, h);
;             const int t = gr - NCTX;
;             const int pos = userow ? (t >> 6) : (t & 63);
;             const f32x2 cs = tab[pos * nf + f];
;             const float v = acc[i][j][e];
;             const float o = __shfl_xor(v, 1);
;             const float res = (gc & 1) ? (o * cs[1] + v * cs[0]) : (v * cs[0] - o * cs[1]);
;             P[(size_t)gr * LDP + gc] = f2bf(res);
.LBB0_2023:
	s_or_b64 exec, exec, s[12:13]
	v_or_b32_e32 v175, 1, v170
	v_or_b32_e32 v173, 2, v170
	v_or_b32_e32 v171, 3, v170
	v_or_b32_e32 v168, 8, v170
	v_or_b32_e32 v166, 9, v170
	v_or_b32_e32 v164, 10, v170
	v_or_b32_e32 v162, 11, v170
	v_or_b32_e32 v160, 16, v170
	v_or_b32_e32 v158, 17, v170
	v_or_b32_e32 v156, 18, v170
	v_or_b32_e32 v154, 19, v170
	v_or_b32_e32 v152, 24, v170
	v_or_b32_e32 v150, 25, v170
	v_or_b32_e32 v148, 26, v170
	v_or_b32_e32 v147, 27, v170
	v_cndmask_b32_e64 v144, 63, 31, s[6:7]
	v_cndmask_b32_e64 v128, v140, v141, s[6:7]
	v_cndmask_b32_e64 v143, 32, 16, s[6:7]
	v_add_u32_e32 v178, 0xffffff00, v130
	v_cndmask_b32_e64 v142, 5, 4, s[6:7]
	v_bitop3_b32 v177, v170, 5, 1 bitop3:0xc8
	v_bitop3_b32 v176, v170, 6, 2 bitop3:0xc8
	v_bitop3_b32 v174, v170, 7, 3 bitop3:0xc8
	v_bitop3_b32 v172, v170, 12, 8 bitop3:0xc8
	v_bitop3_b32 v169, v170, 13, 9 bitop3:0xc8
	v_bitop3_b32 v167, v170, 14, 10 bitop3:0xc8
	v_bitop3_b32 v165, v170, 15, 11 bitop3:0xc8
	v_bitop3_b32 v163, v170, 20, 16 bitop3:0xc8
	v_bitop3_b32 v161, v170, 21, 17 bitop3:0xc8
	v_bitop3_b32 v159, v170, 22, 18 bitop3:0xc8
	v_bitop3_b32 v157, v170, 23, 19 bitop3:0xc8
	v_bitop3_b32 v155, v170, 28, 24 bitop3:0xc8
	v_bitop3_b32 v153, v170, 29, 25 bitop3:0xc8
	v_bitop3_b32 v151, v170, 30, 26 bitop3:0xc8
	v_bitop3_b32 v149, v170, 31, 27 bitop3:0xc8
	s_and_saveexec_b64 s[12:13], s[4:5]
	s_cbranch_execz .LBB0_2025
	s_waitcnt lgkmcnt(0)
	v_lshrrev_b32_e32 v132, 1, v134
	v_and_b32_e32 v135, v132, v144
	v_sub_u32_e32 v179, v135, v143
	v_ashrrev_i32_e32 v186, 6, v178
	v_cmp_lt_u32_e32 vcc, v135, v143
	v_min_u32_e32 v179, v135, v179
	v_lshl_add_u64 v[132:133], s[22:23], 0, v[128:129]
	v_and_b32_e32 v183, 64, v214
	v_xor_b32_e32 v182, 1, v214
	v_add_u32_e32 v183, 64, v183
	v_cmp_lt_i32_e64 s[4:5], v182, v183
	v_ashrrev_i32_e32 v135, 31, v134
	v_and_b32_e32 v187, 1, v134
	v_cndmask_b32_e64 v184, v214, v182, s[4:5]
	v_lshlrev_b32_e32 v188, 2, v184
	v_lshl_add_u64 v[134:135], v[134:135], 1, s[28:29]
	v_cmp_eq_u32_e64 s[4:5], 0, v187
	s_nop 1
	v_cndmask_b32_e32 v190, v136, v186, vcc
	v_lshl_add_u32 v190, v190, v142, v179
	v_ashrrev_i32_e32 v191, 31, v190
	v_lshl_add_u64 v[190:191], v[190:191], 3, v[132:133]
	global_load_dwordx2 v[190:191], v[190:191], off
	ds_bpermute_b32 v240, v188, v112
	v_cndmask_b32_e32 v192, v177, v186, vcc
	v_lshl_add_u32 v192, v192, v142, v179
	v_ashrrev_i32_e32 v193, 31, v192
	v_lshl_add_u64 v[192:193], v[192:193], 3, v[132:133]
	global_load_dwordx2 v[192:193], v[192:193], off
	ds_bpermute_b32 v241, v188, v113
	v_cndmask_b32_e32 v194, v176, v186, vcc
	v_lshl_add_u32 v194, v194, v142, v179
	v_ashrrev_i32_e32 v195, 31, v194
	v_lshl_add_u64 v[194:195], v[194:195], 3, v[132:133]
	global_load_dwordx2 v[194:195], v[194:195], off
	ds_bpermute_b32 v242, v188, v114
	v_cndmask_b32_e32 v196, v174, v186, vcc
	v_lshl_add_u32 v196, v196, v142, v179
	v_ashrrev_i32_e32 v197, 31, v196
	v_lshl_add_u64 v[196:197], v[196:197], 3, v[132:133]
	global_load_dwordx2 v[196:197], v[196:197], off
	ds_bpermute_b32 v243, v188, v115
	v_cndmask_b32_e32 v198, v172, v186, vcc
	v_lshl_add_u32 v198, v198, v142, v179
	v_ashrrev_i32_e32 v199, 31, v198
	v_lshl_add_u64 v[198:199], v[198:199], 3, v[132:133]
	global_load_dwordx2 v[198:199], v[198:199], off
	ds_bpermute_b32 v244, v188, v116
	v_cndmask_b32_e32 v200, v169, v186, vcc
	v_lshl_add_u32 v200, v200, v142, v179
	v_ashrrev_i32_e32 v201, 31, v200
	v_lshl_add_u64 v[200:201], v[200:201], 3, v[132:133]
	global_load_dwordx2 v[200:201], v[200:201], off
	ds_bpermute_b32 v245, v188, v117
	v_cndmask_b32_e32 v202, v167, v186, vcc
	v_lshl_add_u32 v202, v202, v142, v179
	v_ashrrev_i32_e32 v203, 31, v202
	v_lshl_add_u64 v[202:203], v[202:203], 3, v[132:133]
	global_load_dwordx2 v[202:203], v[202:203], off
	ds_bpermute_b32 v246, v188, v118
	v_cndmask_b32_e32 v204, v165, v186, vcc
	v_lshl_add_u32 v204, v204, v142, v179
	v_ashrrev_i32_e32 v205, 31, v204
	v_lshl_add_u64 v[204:205], v[204:205], 3, v[132:133]
	global_load_dwordx2 v[204:205], v[204:205], off
	ds_bpermute_b32 v247, v188, v119
	v_cndmask_b32_e32 v206, v163, v186, vcc
	v_lshl_add_u32 v206, v206, v142, v179
	v_ashrrev_i32_e32 v207, 31, v206
	v_lshl_add_u64 v[206:207], v[206:207], 3, v[132:133]
	global_load_dwordx2 v[206:207], v[206:207], off
	ds_bpermute_b32 v248, v188, v120
	v_cndmask_b32_e32 v208, v161, v186, vcc
	v_lshl_add_u32 v208, v208, v142, v179
	v_ashrrev_i32_e32 v209, 31, v208
	v_lshl_add_u64 v[208:209], v[208:209], 3, v[132:133]
	global_load_dwordx2 v[208:209], v[208:209], off
	ds_bpermute_b32 v249, v188, v121
	v_cndmask_b32_e32 v216, v159, v186, vcc
	v_lshl_add_u32 v216, v216, v142, v179
	v_ashrrev_i32_e32 v217, 31, v216
	v_lshl_add_u64 v[216:217], v[216:217], 3, v[132:133]
	global_load_dwordx2 v[216:217], v[216:217], off
	ds_bpermute_b32 v250, v188, v122
	v_cndmask_b32_e32 v218, v157, v186, vcc
	v_lshl_add_u32 v218, v218, v142, v179
	v_ashrrev_i32_e32 v219, 31, v218
	v_lshl_add_u64 v[218:219], v[218:219], 3, v[132:133]
	global_load_dwordx2 v[218:219], v[218:219], off
	ds_bpermute_b32 v251, v188, v123
	v_cndmask_b32_e32 v220, v155, v186, vcc
	v_lshl_add_u32 v220, v220, v142, v179
	v_ashrrev_i32_e32 v221, 31, v220
	v_lshl_add_u64 v[220:221], v[220:221], 3, v[132:133]
	global_load_dwordx2 v[220:221], v[220:221], off
	ds_bpermute_b32 v252, v188, v124
	v_cndmask_b32_e32 v222, v153, v186, vcc
	v_lshl_add_u32 v222, v222, v142, v179
	v_ashrrev_i32_e32 v223, 31, v222
	v_lshl_add_u64 v[222:223], v[222:223], 3, v[132:133]
	global_load_dwordx2 v[222:223], v[222:223], off
	ds_bpermute_b32 v253, v188, v125
	v_cndmask_b32_e32 v224, v151, v186, vcc
	v_lshl_add_u32 v224, v224, v142, v179
	v_ashrrev_i32_e32 v225, 31, v224
	v_lshl_add_u64 v[224:225], v[224:225], 3, v[132:133]
	global_load_dwordx2 v[224:225], v[224:225], off
	ds_bpermute_b32 v254, v188, v126
	v_cndmask_b32_e32 v226, v149, v186, vcc
	v_lshl_add_u32 v226, v226, v142, v179
	v_ashrrev_i32_e32 v227, 31, v226
	v_lshl_add_u64 v[226:227], v[226:227], 3, v[132:133]
	global_load_dwordx2 v[226:227], v[226:227], off
	ds_bpermute_b32 v255, v188, v127
	s_waitcnt lgkmcnt(0)
; DI u16 f2bf(float a) { return (u16)(pk2(a, 0.f) & 0xffffu); }
; DI int crow(int i, int h) { return (i & 3) + 8 * (i >> 2) + 4 * h; }
; template <int EPI>
; __device__ __forceinline__ void gemm_tile(const Params& p, int layer, const u16* __restrict__ A, const u16* __restrict__ Bt, int mt, int nt, char* lds) {
;     ...
;           for (int e = 0; e < 16; ++e) {
;             const int gr = grb + crow(e, h);
;             const int t = gr - NCTX;
;             const int pos = userow ? (t >> 6) : (t & 63);
;             const f32x2 cs = tab[pos * nf + f];
;             const float v = acc[i][j][e];
;             const float o = __shfl_xor(v, 1);
;             const float res = (gc & 1) ? (o * cs[1] + v * cs[0]) : (v * cs[0] - o * cs[1]);
;             P[(size_t)gr * LDP + gc] = f2bf(res);
;           }
	s_waitcnt vmcnt(15)
	v_mul_f32_e32 v240, v191, v240
	v_cndmask_b32_e64 v240, v240, -v240, s[4:5]
	v_fmac_f32_e32 v240, v112, v190
	v_cvt_pk_bf16_f32 v240, v240, s0
	v_mad_i64_i32 v[190:191], s[14:15], v170, s90, v[134:135]
	global_store_short v[190:191], v240, off
	s_waitcnt vmcnt(15)
	v_mul_f32_e32 v241, v193, v241
	v_cndmask_b32_e64 v241, v241, -v241, s[4:5]
	v_fmac_f32_e32 v241, v113, v192
	v_cvt_pk_bf16_f32 v241, v241, s0
	v_mad_i64_i32 v[192:193], s[14:15], v175, s90, v[134:135]
	global_store_short v[192:193], v241, off
	s_waitcnt vmcnt(15)
	v_mul_f32_e32 v242, v195, v242
	v_cndmask_b32_e64 v242, v242, -v242, s[4:5]
	v_fmac_f32_e32 v242, v114, v194
	v_cvt_pk_bf16_f32 v242, v242, s0
	v_mad_i64_i32 v[194:195], s[14:15], v173, s90, v[134:135]
	global_store_short v[194:195], v242, off
	s_waitcnt vmcnt(15)
	v_mul_f32_e32 v243, v197, v243
	v_cndmask_b32_e64 v243, v243, -v243, s[4:5]
	v_fmac_f32_e32 v243, v115, v196
	v_cvt_pk_bf16_f32 v243, v243, s0
	v_mad_i64_i32 v[196:197], s[14:15], v171, s90, v[134:135]
	global_store_short v[196:197], v243, off
	s_waitcnt vmcnt(15)
	v_mul_f32_e32 v244, v199, v244
	v_cndmask_b32_e64 v244, v244, -v244, s[4:5]
	v_fmac_f32_e32 v244, v116, v198
	v_cvt_pk_bf16_f32 v244, v244, s0
	v_mad_i64_i32 v[198:199], s[14:15], v168, s90, v[134:135]
	global_store_short v[198:199], v244, off
	s_waitcnt vmcnt(15)
	v_mul_f32_e32 v245, v201, v245
	v_cndmask_b32_e64 v245, v245, -v245, s[4:5]
	v_fmac_f32_e32 v245, v117, v200
	v_cvt_pk_bf16_f32 v245, v245, s0
	v_mad_i64_i32 v[200:201], s[14:15], v166, s90, v[134:135]
	global_store_short v[200:201], v245, off
	s_waitcnt vmcnt(15)
	v_mul_f32_e32 v246, v203, v246
	v_cndmask_b32_e64 v246, v246, -v246, s[4:5]
	v_fmac_f32_e32 v246, v118, v202
	v_cvt_pk_bf16_f32 v246, v246, s0
	v_mad_i64_i32 v[202:203], s[14:15], v164, s90, v[134:135]
	global_store_short v[202:203], v246, off
	s_waitcnt vmcnt(15)
	v_mul_f32_e32 v247, v205, v247
	v_cndmask_b32_e64 v247, v247, -v247, s[4:5]
	v_fmac_f32_e32 v247, v119, v204
	v_cvt_pk_bf16_f32 v247, v247, s0
	v_mad_i64_i32 v[204:205], s[14:15], v162, s90, v[134:135]
	global_store_short v[204:205], v247, off
	s_waitcnt vmcnt(15)
	v_mul_f32_e32 v248, v207, v248
	v_cndmask_b32_e64 v248, v248, -v248, s[4:5]
	v_fmac_f32_e32 v248, v120, v206
	v_cvt_pk_bf16_f32 v248, v248, s0
	v_mad_i64_i32 v[206:207], s[14:15], v160, s90, v[134:135]
	global_store_short v[206:207], v248, off
	s_waitcnt vmcnt(15)
	v_mul_f32_e32 v249, v209, v249
	v_cndmask_b32_e64 v249, v249, -v249, s[4:5]
	v_fmac_f32_e32 v249, v121, v208
	v_cvt_pk_bf16_f32 v249, v249, s0
	v_mad_i64_i32 v[208:209], s[14:15], v158, s90, v[134:135]
	global_store_short v[208:209], v249, off
	s_waitcnt vmcnt(15)
	v_mul_f32_e32 v250, v217, v250
	v_cndmask_b32_e64 v250, v250, -v250, s[4:5]
	v_fmac_f32_e32 v250, v122, v216
	v_cvt_pk_bf16_f32 v250, v250, s0
	v_mad_i64_i32 v[216:217], s[14:15], v156, s90, v[134:135]
	global_store_short v[216:217], v250, off
	s_waitcnt vmcnt(15)
	v_mul_f32_e32 v251, v219, v251
	v_cndmask_b32_e64 v251, v251, -v251, s[4:5]
	v_fmac_f32_e32 v251, v123, v218
	v_cvt_pk_bf16_f32 v251, v251, s0
	v_mad_i64_i32 v[218:219], s[14:15], v154, s90, v[134:135]
	global_store_short v[218:219], v251, off
	s_waitcnt vmcnt(15)
	v_mul_f32_e32 v252, v221, v252
	v_cndmask_b32_e64 v252, v252, -v252, s[4:5]
	v_fmac_f32_e32 v252, v124, v220
	v_cvt_pk_bf16_f32 v252, v252, s0
	v_mad_i64_i32 v[220:221], s[14:15], v152, s90, v[134:135]
	global_store_short v[220:221], v252, off
	s_waitcnt vmcnt(15)
	v_mul_f32_e32 v253, v223, v253
	v_cndmask_b32_e64 v253, v253, -v253, s[4:5]
	v_fmac_f32_e32 v253, v125, v222
	v_cvt_pk_bf16_f32 v253, v253, s0
	v_mad_i64_i32 v[222:223], s[14:15], v150, s90, v[134:135]
	global_store_short v[222:223], v253, off
	s_waitcnt vmcnt(15)
	v_mul_f32_e32 v254, v225, v254
	v_cndmask_b32_e64 v254, v254, -v254, s[4:5]
	v_fmac_f32_e32 v254, v126, v224
	v_cvt_pk_bf16_f32 v254, v254, s0
	v_mad_i64_i32 v[224:225], s[14:15], v148, s90, v[134:135]
	global_store_short v[224:225], v254, off
	s_waitcnt vmcnt(15)
	v_mul_f32_e32 v255, v227, v255
	v_cndmask_b32_e64 v255, v255, -v255, s[4:5]
	v_fmac_f32_e32 v255, v127, v226
	v_cvt_pk_bf16_f32 v255, v255, s0
	v_mad_i64_i32 v[226:227], s[14:15], v147, s90, v[134:135]
	global_store_short v[226:227], v255, off

; DI u16 f2bf(float a) { return (u16)(pk2(a, 0.f) & 0xffffu); }
; DI int crow(int i, int h) { return (i & 3) + 8 * (i >> 2) + 4 * h; }
; template <int EPI>
; __device__ __forceinline__ void gemm_tile(const Params& p, int layer, const u16* __restrict__ A, const u16* __restrict__ Bt, int mt, int nt, char* lds) {
;     ...
;         if (latent && (ropeA || ropeB)) {
;           int pair, nf; bool userow; const f32x2* tab;
;           if (ropeA) { pair = (gc & 63) >> 1; nf = 16; tab = (const f32x2*)(p.ws + OFF_TABA); }
;           else       { pair = (gc & 127) >> 1; nf = 32; tab = (const f32x2*)(p.ws + OFF_TABB); }
;           userow = pair < nf;
;           const int f = userow ? pair : pair - nf;
; #pragma unroll
;           for (int e = 0; e < 16; ++e) {
;             const int gr = grb + crow(e, h);
;             const int t = gr - NCTX;
;             const int pos = userow ? (t >> 6) : (t & 63);
;             const f32x2 cs = tab[pos * nf + f];
;             const float v = acc[i][j][e];
;             const float o = __shfl_xor(v, 1);
;             const float res = (gc & 1) ? (o * cs[1] + v * cs[0]) : (v * cs[0] - o * cs[1]);
;             P[(size_t)gr * LDP + gc] = f2bf(res);
.LBB0_2039:
	s_or_b64 exec, exec, s[8:9]
	v_cndmask_b32_e64 v123, 63, 31, s[14:15]
	v_cndmask_b32_e64 v112, v140, v141, s[14:15]
	v_cndmask_b32_e64 v122, 32, 16, s[14:15]
	v_cndmask_b32_e64 v120, 5, 4, s[14:15]
	s_and_saveexec_b64 s[12:13], s[18:19]
	s_cbranch_execz .LBB0_2041
	v_lshrrev_b32_e32 v114, 1, v116
	v_mov_b32_e32 v113, v129
	v_and_b32_e32 v117, v114, v123
	v_lshl_add_u64 v[114:115], s[22:23], 0, v[112:113]
	v_sub_u32_e32 v113, v117, v122
	v_ashrrev_i32_e32 v179, 6, v178
	v_cmp_lt_u32_e32 vcc, v117, v122
	v_min_u32_e32 v113, v117, v113
	s_waitcnt lgkmcnt(0)
	v_and_b32_e32 v132, 64, v214
	v_mov_b64_e32 v[118:119], s[28:29]
	v_xor_b32_e32 v134, 1, v214
	v_add_u32_e32 v135, 64, v132
	v_cmp_lt_i32_e64 s[8:9], v134, v135
	v_and_b32_e32 v180, 1, v116
	v_ashrrev_i32_e32 v117, 31, v116
	v_cndmask_b32_e64 v134, v214, v134, s[8:9]
	v_lshlrev_b32_e32 v181, 2, v134
	v_cmp_eq_u32_e64 s[8:9], 0, v180
	v_lshlrev_b64 v[116:117], 1, v[116:117]
	s_nop 1
	v_cndmask_b32_e32 v190, v136, v179, vcc
	v_lshl_add_u32 v190, v190, v120, v113
	v_ashrrev_i32_e32 v191, 31, v190
	v_lshl_add_u64 v[190:191], v[190:191], 3, v[114:115]
	global_load_dwordx2 v[190:191], v[190:191], off
	ds_bpermute_b32 v240, v181, v96
	v_cndmask_b32_e32 v192, v177, v179, vcc
	v_lshl_add_u32 v192, v192, v120, v113
	v_ashrrev_i32_e32 v193, 31, v192
	v_lshl_add_u64 v[192:193], v[192:193], 3, v[114:115]
	global_load_dwordx2 v[192:193], v[192:193], off
	ds_bpermute_b32 v241, v181, v97
	v_cndmask_b32_e32 v194, v176, v179, vcc
	v_lshl_add_u32 v194, v194, v120, v113
	v_ashrrev_i32_e32 v195, 31, v194
	v_lshl_add_u64 v[194:195], v[194:195], 3, v[114:115]
	global_load_dwordx2 v[194:195], v[194:195], off
	ds_bpermute_b32 v242, v181, v98
	v_cndmask_b32_e32 v196, v174, v179, vcc
	v_lshl_add_u32 v196, v196, v120, v113
	v_ashrrev_i32_e32 v197, 31, v196
	v_lshl_add_u64 v[196:197], v[196:197], 3, v[114:115]
	global_load_dwordx2 v[196:197], v[196:197], off
	ds_bpermute_b32 v243, v181, v99
	v_cndmask_b32_e32 v198, v172, v179, vcc
	v_lshl_add_u32 v198, v198, v120, v113
	v_ashrrev_i32_e32 v199, 31, v198
	v_lshl_add_u64 v[198:199], v[198:199], 3, v[114:115]
	global_load_dwordx2 v[198:199], v[198:199], off
	ds_bpermute_b32 v244, v181, v100
	v_cndmask_b32_e32 v200, v169, v179, vcc
	v_lshl_add_u32 v200, v200, v120, v113
	v_ashrrev_i32_e32 v201, 31, v200
	v_lshl_add_u64 v[200:201], v[200:201], 3, v[114:115]
	global_load_dwordx2 v[200:201], v[200:201], off
	ds_bpermute_b32 v245, v181, v101
	v_cndmask_b32_e32 v202, v167, v179, vcc
	v_lshl_add_u32 v202, v202, v120, v113
	v_ashrrev_i32_e32 v203, 31, v202
	v_lshl_add_u64 v[202:203], v[202:203], 3, v[114:115]
	global_load_dwordx2 v[202:203], v[202:203], off
	ds_bpermute_b32 v246, v181, v102
	v_cndmask_b32_e32 v204, v165, v179, vcc
	v_lshl_add_u32 v204, v204, v120, v113
	v_ashrrev_i32_e32 v205, 31, v204
	v_lshl_add_u64 v[204:205], v[204:205], 3, v[114:115]
	global_load_dwordx2 v[204:205], v[204:205], off
	ds_bpermute_b32 v247, v181, v103
	v_cndmask_b32_e32 v206, v163, v179, vcc
	v_lshl_add_u32 v206, v206, v120, v113
	v_ashrrev_i32_e32 v207, 31, v206
	v_lshl_add_u64 v[206:207], v[206:207], 3, v[114:115]
	global_load_dwordx2 v[206:207], v[206:207], off
	ds_bpermute_b32 v248, v181, v104
	v_cndmask_b32_e32 v208, v161, v179, vcc
	v_lshl_add_u32 v208, v208, v120, v113
	v_ashrrev_i32_e32 v209, 31, v208
	v_lshl_add_u64 v[208:209], v[208:209], 3, v[114:115]
	global_load_dwordx2 v[208:209], v[208:209], off
	ds_bpermute_b32 v249, v181, v105
	v_cndmask_b32_e32 v216, v159, v179, vcc
	v_lshl_add_u32 v216, v216, v120, v113
	v_ashrrev_i32_e32 v217, 31, v216
	v_lshl_add_u64 v[216:217], v[216:217], 3, v[114:115]
	global_load_dwordx2 v[216:217], v[216:217], off
	ds_bpermute_b32 v250, v181, v106
	v_cndmask_b32_e32 v218, v157, v179, vcc
	v_lshl_add_u32 v218, v218, v120, v113
	v_ashrrev_i32_e32 v219, 31, v218
	v_lshl_add_u64 v[218:219], v[218:219], 3, v[114:115]
	global_load_dwordx2 v[218:219], v[218:219], off
	ds_bpermute_b32 v251, v181, v107
	v_cndmask_b32_e32 v220, v155, v179, vcc
	v_lshl_add_u32 v220, v220, v120, v113
	v_ashrrev_i32_e32 v221, 31, v220
	v_lshl_add_u64 v[220:221], v[220:221], 3, v[114:115]
	global_load_dwordx2 v[220:221], v[220:221], off
	ds_bpermute_b32 v252, v181, v108
	v_cndmask_b32_e32 v222, v153, v179, vcc
	v_lshl_add_u32 v222, v222, v120, v113
	v_ashrrev_i32_e32 v223, 31, v222
	v_lshl_add_u64 v[222:223], v[222:223], 3, v[114:115]
	global_load_dwordx2 v[222:223], v[222:223], off
	ds_bpermute_b32 v253, v181, v109
	v_cndmask_b32_e32 v224, v151, v179, vcc
	v_lshl_add_u32 v224, v224, v120, v113
	v_ashrrev_i32_e32 v225, 31, v224
	v_lshl_add_u64 v[224:225], v[224:225], 3, v[114:115]
	global_load_dwordx2 v[224:225], v[224:225], off
	ds_bpermute_b32 v254, v181, v110
	v_cndmask_b32_e32 v226, v149, v179, vcc
	v_lshl_add_u32 v226, v226, v120, v113
	v_ashrrev_i32_e32 v227, 31, v226
	v_lshl_add_u64 v[226:227], v[226:227], 3, v[114:115]
	global_load_dwordx2 v[226:227], v[226:227], off
	ds_bpermute_b32 v255, v181, v111
	s_waitcnt lgkmcnt(0)
	s_waitcnt vmcnt(15)
; DI u16 f2bf(float a) { return (u16)(pk2(a, 0.f) & 0xffffu); }
; DI int crow(int i, int h) { return (i & 3) + 8 * (i >> 2) + 4 * h; }
; template <int EPI>
; __device__ __forceinline__ void gemm_tile(const Params& p, int layer, const u16* __restrict__ A, const u16* __restrict__ Bt, int mt, int nt, char* lds) {
;     ...
;           for (int e = 0; e < 16; ++e) {
;             const int gr = grb + crow(e, h);
;             const int t = gr - NCTX;
;             const int pos = userow ? (t >> 6) : (t & 63);
;             const f32x2 cs = tab[pos * nf + f];
;             const float v = acc[i][j][e];
;             const float o = __shfl_xor(v, 1);
;             const float res = (gc & 1) ? (o * cs[1] + v * cs[0]) : (v * cs[0] - o * cs[1]);
;             P[(size_t)gr * LDP + gc] = f2bf(res);
;           }
	v_mul_f32_e32 v240, v191, v240
	v_cndmask_b32_e64 v240, v240, -v240, s[8:9]
	v_fmac_f32_e32 v240, v96, v190
	v_cvt_pk_bf16_f32 v240, v240, s0
	v_mad_i64_i32 v[190:191], s[18:19], v170, s90, v[118:119]
	v_lshl_add_u64 v[190:191], v[190:191], 0, v[116:117]
	global_store_short v[190:191], v240, off
	s_waitcnt vmcnt(15)
	v_mul_f32_e32 v241, v193, v241
	v_cndmask_b32_e64 v241, v241, -v241, s[8:9]
	v_fmac_f32_e32 v241, v97, v192
	v_cvt_pk_bf16_f32 v241, v241, s0
	v_mad_i64_i32 v[192:193], s[18:19], v175, s90, v[118:119]
	v_lshl_add_u64 v[192:193], v[192:193], 0, v[116:117]
	global_store_short v[192:193], v241, off
	s_waitcnt vmcnt(15)
	v_mul_f32_e32 v242, v195, v242
	v_cndmask_b32_e64 v242, v242, -v242, s[8:9]
	v_fmac_f32_e32 v242, v98, v194
	v_cvt_pk_bf16_f32 v242, v242, s0
	v_mad_i64_i32 v[194:195], s[18:19], v173, s90, v[118:119]
	v_lshl_add_u64 v[194:195], v[194:195], 0, v[116:117]
	global_store_short v[194:195], v242, off
	s_waitcnt vmcnt(15)
	v_mul_f32_e32 v243, v197, v243
	v_cndmask_b32_e64 v243, v243, -v243, s[8:9]
	v_fmac_f32_e32 v243, v99, v196
	v_cvt_pk_bf16_f32 v243, v243, s0
	v_mad_i64_i32 v[196:197], s[18:19], v171, s90, v[118:119]
	v_lshl_add_u64 v[196:197], v[196:197], 0, v[116:117]
	global_store_short v[196:197], v243, off
	s_waitcnt vmcnt(15)
	v_mul_f32_e32 v244, v199, v244
	v_cndmask_b32_e64 v244, v244, -v244, s[8:9]
	v_fmac_f32_e32 v244, v100, v198
	v_cvt_pk_bf16_f32 v244, v244, s0
	v_mad_i64_i32 v[198:199], s[18:19], v168, s90, v[118:119]
	v_lshl_add_u64 v[198:199], v[198:199], 0, v[116:117]
	global_store_short v[198:199], v244, off
	s_waitcnt vmcnt(15)
	v_mul_f32_e32 v245, v201, v245
	v_cndmask_b32_e64 v245, v245, -v245, s[8:9]
	v_fmac_f32_e32 v245, v101, v200
	v_cvt_pk_bf16_f32 v245, v245, s0
	v_mad_i64_i32 v[200:201], s[18:19], v166, s90, v[118:119]
	v_lshl_add_u64 v[200:201], v[200:201], 0, v[116:117]
	global_store_short v[200:201], v245, off
	s_waitcnt vmcnt(15)
	v_mul_f32_e32 v246, v203, v246
	v_cndmask_b32_e64 v246, v246, -v246, s[8:9]
	v_fmac_f32_e32 v246, v102, v202
	v_cvt_pk_bf16_f32 v246, v246, s0
	v_mad_i64_i32 v[202:203], s[18:19], v164, s90, v[118:119]
	v_lshl_add_u64 v[202:203], v[202:203], 0, v[116:117]
	global_store_short v[202:203], v246, off
	s_waitcnt vmcnt(15)
	v_mul_f32_e32 v247, v205, v247
	v_cndmask_b32_e64 v247, v247, -v247, s[8:9]
	v_fmac_f32_e32 v247, v103, v204
	v_cvt_pk_bf16_f32 v247, v247, s0
	v_mad_i64_i32 v[204:205], s[18:19], v162, s90, v[118:119]
	v_lshl_add_u64 v[204:205], v[204:205], 0, v[116:117]
	global_store_short v[204:205], v247, off
	s_waitcnt vmcnt(15)
	v_mul_f32_e32 v248, v207, v248
	v_cndmask_b32_e64 v248, v248, -v248, s[8:9]
	v_fmac_f32_e32 v248, v104, v206
	v_cvt_pk_bf16_f32 v248, v248, s0
	v_mad_i64_i32 v[206:207], s[18:19], v160, s90, v[118:119]
	v_lshl_add_u64 v[206:207], v[206:207], 0, v[116:117]
	global_store_short v[206:207], v248, off
	s_waitcnt vmcnt(15)
	v_mul_f32_e32 v249, v209, v249
	v_cndmask_b32_e64 v249, v249, -v249, s[8:9]
	v_fmac_f32_e32 v249, v105, v208
	v_cvt_pk_bf16_f32 v249, v249, s0
	v_mad_i64_i32 v[208:209], s[18:19], v158, s90, v[118:119]
	v_lshl_add_u64 v[208:209], v[208:209], 0, v[116:117]
	global_store_short v[208:209], v249, off
	s_waitcnt vmcnt(15)
	v_mul_f32_e32 v250, v217, v250
	v_cndmask_b32_e64 v250, v250, -v250, s[8:9]
	v_fmac_f32_e32 v250, v106, v216
	v_cvt_pk_bf16_f32 v250, v250, s0
	v_mad_i64_i32 v[216:217], s[18:19], v156, s90, v[118:119]
	v_lshl_add_u64 v[216:217], v[216:217], 0, v[116:117]
	global_store_short v[216:217], v250, off
	s_waitcnt vmcnt(15)
	v_mul_f32_e32 v251, v219, v251
	v_cndmask_b32_e64 v251, v251, -v251, s[8:9]
	v_fmac_f32_e32 v251, v107, v218
	v_cvt_pk_bf16_f32 v251, v251, s0
	v_mad_i64_i32 v[218:219], s[18:19], v154, s90, v[118:119]
	v_lshl_add_u64 v[218:219], v[218:219], 0, v[116:117]
	global_store_short v[218:219], v251, off
	s_waitcnt vmcnt(15)
	v_mul_f32_e32 v252, v221, v252
	v_cndmask_b32_e64 v252, v252, -v252, s[8:9]
	v_fmac_f32_e32 v252, v108, v220
	v_cvt_pk_bf16_f32 v252, v252, s0
	v_mad_i64_i32 v[220:221], s[18:19], v152, s90, v[118:119]
	v_lshl_add_u64 v[220:221], v[220:221], 0, v[116:117]
	global_store_short v[220:221], v252, off
	s_waitcnt vmcnt(15)
	v_mul_f32_e32 v253, v223, v253
	v_cndmask_b32_e64 v253, v253, -v253, s[8:9]
	v_fmac_f32_e32 v253, v109, v222
	v_cvt_pk_bf16_f32 v253, v253, s0
	v_mad_i64_i32 v[222:223], s[18:19], v150, s90, v[118:119]
	v_lshl_add_u64 v[222:223], v[222:223], 0, v[116:117]
	global_store_short v[222:223], v253, off
	s_waitcnt vmcnt(15)
	v_mul_f32_e32 v254, v225, v254
	v_cndmask_b32_e64 v254, v254, -v254, s[8:9]
	v_fmac_f32_e32 v254, v110, v224
	v_cvt_pk_bf16_f32 v254, v254, s0
	v_mad_i64_i32 v[224:225], s[18:19], v148, s90, v[118:119]
	v_lshl_add_u64 v[224:225], v[224:225], 0, v[116:117]
	global_store_short v[224:225], v254, off
	s_waitcnt vmcnt(15)
	v_mul_f32_e32 v255, v227, v255
	v_cndmask_b32_e64 v255, v255, -v255, s[8:9]
	v_fmac_f32_e32 v255, v111, v226
	v_cvt_pk_bf16_f32 v255, v255, s0
	v_mad_i64_i32 v[226:227], s[18:19], v147, s90, v[118:119]
	v_lshl_add_u64 v[226:227], v[226:227], 0, v[116:117]
	global_store_short v[226:227], v255, off

; DI u16 f2bf(float a) { return (u16)(pk2(a, 0.f) & 0xffffu); }
; DI int crow(int i, int h) { return (i & 3) + 8 * (i >> 2) + 4 * h; }
; template <int EPI>
; __device__ __forceinline__ void gemm_tile(const Params& p, int layer, const u16* __restrict__ A, const u16* __restrict__ Bt, int mt, int nt, char* lds) {
;     ...
;         if (latent && (ropeA || ropeB)) {
;           int pair, nf; bool userow; const f32x2* tab;
;           if (ropeA) { pair = (gc & 63) >> 1; nf = 16; tab = (const f32x2*)(p.ws + OFF_TABA); }
;           else       { pair = (gc & 127) >> 1; nf = 32; tab = (const f32x2*)(p.ws + OFF_TABB); }
;           userow = pair < nf;
;           const int f = userow ? pair : pair - nf;
; #pragma unroll
;           for (int e = 0; e < 16; ++e) {
;             const int gr = grb + crow(e, h);
;             const int t = gr - NCTX;
;             const int pos = userow ? (t >> 6) : (t & 63);
;             const f32x2 cs = tab[pos * nf + f];
;             const float v = acc[i][j][e];
;             const float o = __shfl_xor(v, 1);
;             const float res = (gc & 1) ? (o * cs[1] + v * cs[0]) : (v * cs[0] - o * cs[1]);
;             P[(size_t)gr * LDP + gc] = f2bf(res);
.LBB0_2071:
	s_or_b64 exec, exec, s[16:17]
	v_cndmask_b32_e64 v107, 63, 31, s[8:9]
	v_cndmask_b32_e64 v96, v140, v141, s[8:9]
	v_cndmask_b32_e64 v106, 32, 16, s[8:9]
	v_cndmask_b32_e64 v105, 5, 4, s[8:9]
	s_and_saveexec_b64 s[20:21], s[50:51]
	s_cbranch_execz .LBB0_2073
	v_lshrrev_b32_e32 v98, 1, v100
	v_mov_b32_e32 v97, v129
	v_and_b32_e32 v101, v98, v107
	s_waitcnt lgkmcnt(0)
	v_lshl_add_u64 v[98:99], s[22:23], 0, v[96:97]
	v_sub_u32_e32 v97, v101, v106
	v_ashrrev_i32_e32 v113, 6, v178
	v_cmp_lt_u32_e32 vcc, v101, v106
	v_min_u32_e32 v97, v101, v97
	v_and_b32_e32 v114, 64, v214
	v_mov_b64_e32 v[102:103], s[28:29]
	v_xor_b32_e32 v116, 1, v214
	v_add_u32_e32 v117, 64, v114
	v_cmp_lt_i32_e64 s[16:17], v116, v117
	v_and_b32_e32 v118, 1, v100
	v_ashrrev_i32_e32 v101, 31, v100
	v_cndmask_b32_e64 v116, v214, v116, s[16:17]
	v_lshlrev_b32_e32 v119, 2, v116
	v_cmp_eq_u32_e64 s[16:17], 0, v118
	v_lshlrev_b64 v[100:101], 1, v[100:101]
	s_nop 1
	v_cndmask_b32_e32 v190, v136, v113, vcc
	v_lshl_add_u32 v190, v190, v105, v97
	v_ashrrev_i32_e32 v191, 31, v190
	v_lshl_add_u64 v[190:191], v[190:191], 3, v[98:99]
	global_load_dwordx2 v[190:191], v[190:191], off
	ds_bpermute_b32 v240, v119, v80
	v_cndmask_b32_e32 v192, v177, v113, vcc
	v_lshl_add_u32 v192, v192, v105, v97
	v_ashrrev_i32_e32 v193, 31, v192
	v_lshl_add_u64 v[192:193], v[192:193], 3, v[98:99]
	global_load_dwordx2 v[192:193], v[192:193], off
	ds_bpermute_b32 v241, v119, v81
	v_cndmask_b32_e32 v194, v176, v113, vcc
	v_lshl_add_u32 v194, v194, v105, v97
	v_ashrrev_i32_e32 v195, 31, v194
	v_lshl_add_u64 v[194:195], v[194:195], 3, v[98:99]
	global_load_dwordx2 v[194:195], v[194:195], off
	ds_bpermute_b32 v242, v119, v82
	v_cndmask_b32_e32 v196, v174, v113, vcc
	v_lshl_add_u32 v196, v196, v105, v97
	v_ashrrev_i32_e32 v197, 31, v196
	v_lshl_add_u64 v[196:197], v[196:197], 3, v[98:99]
	global_load_dwordx2 v[196:197], v[196:197], off
	ds_bpermute_b32 v243, v119, v83
	v_cndmask_b32_e32 v198, v172, v113, vcc
	v_lshl_add_u32 v198, v198, v105, v97
	v_ashrrev_i32_e32 v199, 31, v198
	v_lshl_add_u64 v[198:199], v[198:199], 3, v[98:99]
	global_load_dwordx2 v[198:199], v[198:199], off
	ds_bpermute_b32 v244, v119, v84
	v_cndmask_b32_e32 v200, v169, v113, vcc
	v_lshl_add_u32 v200, v200, v105, v97
	v_ashrrev_i32_e32 v201, 31, v200
	v_lshl_add_u64 v[200:201], v[200:201], 3, v[98:99]
	global_load_dwordx2 v[200:201], v[200:201], off
	ds_bpermute_b32 v245, v119, v85
	v_cndmask_b32_e32 v202, v167, v113, vcc
	v_lshl_add_u32 v202, v202, v105, v97
	v_ashrrev_i32_e32 v203, 31, v202
	v_lshl_add_u64 v[202:203], v[202:203], 3, v[98:99]
	global_load_dwordx2 v[202:203], v[202:203], off
	ds_bpermute_b32 v246, v119, v86
	v_cndmask_b32_e32 v204, v165, v113, vcc
	v_lshl_add_u32 v204, v204, v105, v97
	v_ashrrev_i32_e32 v205, 31, v204
	v_lshl_add_u64 v[204:205], v[204:205], 3, v[98:99]
	global_load_dwordx2 v[204:205], v[204:205], off
	ds_bpermute_b32 v247, v119, v87
	v_cndmask_b32_e32 v206, v163, v113, vcc
	v_lshl_add_u32 v206, v206, v105, v97
	v_ashrrev_i32_e32 v207, 31, v206
	v_lshl_add_u64 v[206:207], v[206:207], 3, v[98:99]
	global_load_dwordx2 v[206:207], v[206:207], off
	ds_bpermute_b32 v248, v119, v88
	v_cndmask_b32_e32 v208, v161, v113, vcc
	v_lshl_add_u32 v208, v208, v105, v97
	v_ashrrev_i32_e32 v209, 31, v208
	v_lshl_add_u64 v[208:209], v[208:209], 3, v[98:99]
	global_load_dwordx2 v[208:209], v[208:209], off
	ds_bpermute_b32 v249, v119, v89
	v_cndmask_b32_e32 v216, v159, v113, vcc
	v_lshl_add_u32 v216, v216, v105, v97
	v_ashrrev_i32_e32 v217, 31, v216
	v_lshl_add_u64 v[216:217], v[216:217], 3, v[98:99]
	global_load_dwordx2 v[216:217], v[216:217], off
	ds_bpermute_b32 v250, v119, v90
	v_cndmask_b32_e32 v218, v157, v113, vcc
	v_lshl_add_u32 v218, v218, v105, v97
	v_ashrrev_i32_e32 v219, 31, v218
	v_lshl_add_u64 v[218:219], v[218:219], 3, v[98:99]
	global_load_dwordx2 v[218:219], v[218:219], off
	ds_bpermute_b32 v251, v119, v91
	v_cndmask_b32_e32 v220, v155, v113, vcc
	v_lshl_add_u32 v220, v220, v105, v97
	v_ashrrev_i32_e32 v221, 31, v220
	v_lshl_add_u64 v[220:221], v[220:221], 3, v[98:99]
	global_load_dwordx2 v[220:221], v[220:221], off
	ds_bpermute_b32 v252, v119, v92
	v_cndmask_b32_e32 v222, v153, v113, vcc
	v_lshl_add_u32 v222, v222, v105, v97
	v_ashrrev_i32_e32 v223, 31, v222
	v_lshl_add_u64 v[222:223], v[222:223], 3, v[98:99]
	global_load_dwordx2 v[222:223], v[222:223], off
	ds_bpermute_b32 v253, v119, v93
	v_cndmask_b32_e32 v224, v151, v113, vcc
	v_lshl_add_u32 v224, v224, v105, v97
	v_ashrrev_i32_e32 v225, 31, v224
	v_lshl_add_u64 v[224:225], v[224:225], 3, v[98:99]
	global_load_dwordx2 v[224:225], v[224:225], off
	ds_bpermute_b32 v254, v119, v94
	v_cndmask_b32_e32 v226, v149, v113, vcc
	v_lshl_add_u32 v226, v226, v105, v97
	v_ashrrev_i32_e32 v227, 31, v226
	v_lshl_add_u64 v[226:227], v[226:227], 3, v[98:99]
	global_load_dwordx2 v[226:227], v[226:227], off
	ds_bpermute_b32 v255, v119, v95
	s_waitcnt lgkmcnt(0)
	s_waitcnt vmcnt(15)
; DI u16 f2bf(float a) { return (u16)(pk2(a, 0.f) & 0xffffu); }
; DI int crow(int i, int h) { return (i & 3) + 8 * (i >> 2) + 4 * h; }
; template <int EPI>
; __device__ __forceinline__ void gemm_tile(const Params& p, int layer, const u16* __restrict__ A, const u16* __restrict__ Bt, int mt, int nt, char* lds) {
;     ...
;           for (int e = 0; e < 16; ++e) {
;             const int gr = grb + crow(e, h);
;             const int t = gr - NCTX;
;             const int pos = userow ? (t >> 6) : (t & 63);
;             const f32x2 cs = tab[pos * nf + f];
;             const float v = acc[i][j][e];
;             const float o = __shfl_xor(v, 1);
;             const float res = (gc & 1) ? (o * cs[1] + v * cs[0]) : (v * cs[0] - o * cs[1]);
;             P[(size_t)gr * LDP + gc] = f2bf(res);
;           }
	v_mul_f32_e32 v240, v191, v240
	v_cndmask_b32_e64 v240, v240, -v240, s[16:17]
	v_fmac_f32_e32 v240, v80, v190
	v_cvt_pk_bf16_f32 v240, v240, s0
	v_mad_i64_i32 v[190:191], s[50:51], v170, s90, v[102:103]
	v_lshl_add_u64 v[190:191], v[190:191], 0, v[100:101]
	global_store_short v[190:191], v240, off
	s_waitcnt vmcnt(15)
	v_mul_f32_e32 v241, v193, v241
	v_cndmask_b32_e64 v241, v241, -v241, s[16:17]
	v_fmac_f32_e32 v241, v81, v192
	v_cvt_pk_bf16_f32 v241, v241, s0
	v_mad_i64_i32 v[192:193], s[50:51], v175, s90, v[102:103]
	v_lshl_add_u64 v[192:193], v[192:193], 0, v[100:101]
	global_store_short v[192:193], v241, off
	s_waitcnt vmcnt(15)
	v_mul_f32_e32 v242, v195, v242
	v_cndmask_b32_e64 v242, v242, -v242, s[16:17]
	v_fmac_f32_e32 v242, v82, v194
	v_cvt_pk_bf16_f32 v242, v242, s0
	v_mad_i64_i32 v[194:195], s[50:51], v173, s90, v[102:103]
	v_lshl_add_u64 v[194:195], v[194:195], 0, v[100:101]
	global_store_short v[194:195], v242, off
	s_waitcnt vmcnt(15)
	v_mul_f32_e32 v243, v197, v243
	v_cndmask_b32_e64 v243, v243, -v243, s[16:17]
	v_fmac_f32_e32 v243, v83, v196
	v_cvt_pk_bf16_f32 v243, v243, s0
	v_mad_i64_i32 v[196:197], s[50:51], v171, s90, v[102:103]
	v_lshl_add_u64 v[196:197], v[196:197], 0, v[100:101]
	global_store_short v[196:197], v243, off
	s_waitcnt vmcnt(15)
	v_mul_f32_e32 v244, v199, v244
	v_cndmask_b32_e64 v244, v244, -v244, s[16:17]
	v_fmac_f32_e32 v244, v84, v198
	v_cvt_pk_bf16_f32 v244, v244, s0
	v_mad_i64_i32 v[198:199], s[50:51], v168, s90, v[102:103]
	v_lshl_add_u64 v[198:199], v[198:199], 0, v[100:101]
	global_store_short v[198:199], v244, off
	s_waitcnt vmcnt(15)
	v_mul_f32_e32 v245, v201, v245
	v_cndmask_b32_e64 v245, v245, -v245, s[16:17]
	v_fmac_f32_e32 v245, v85, v200
	v_cvt_pk_bf16_f32 v245, v245, s0
	v_mad_i64_i32 v[200:201], s[50:51], v166, s90, v[102:103]
	v_lshl_add_u64 v[200:201], v[200:201], 0, v[100:101]
	global_store_short v[200:201], v245, off
	s_waitcnt vmcnt(15)
	v_mul_f32_e32 v246, v203, v246
	v_cndmask_b32_e64 v246, v246, -v246, s[16:17]
	v_fmac_f32_e32 v246, v86, v202
	v_cvt_pk_bf16_f32 v246, v246, s0
	v_mad_i64_i32 v[202:203], s[50:51], v164, s90, v[102:103]
	v_lshl_add_u64 v[202:203], v[202:203], 0, v[100:101]
	global_store_short v[202:203], v246, off
	s_waitcnt vmcnt(15)
	v_mul_f32_e32 v247, v205, v247
	v_cndmask_b32_e64 v247, v247, -v247, s[16:17]
	v_fmac_f32_e32 v247, v87, v204
	v_cvt_pk_bf16_f32 v247, v247, s0
	v_mad_i64_i32 v[204:205], s[50:51], v162, s90, v[102:103]
	v_lshl_add_u64 v[204:205], v[204:205], 0, v[100:101]
	global_store_short v[204:205], v247, off
	s_waitcnt vmcnt(15)
	v_mul_f32_e32 v248, v207, v248
	v_cndmask_b32_e64 v248, v248, -v248, s[16:17]
	v_fmac_f32_e32 v248, v88, v206
	v_cvt_pk_bf16_f32 v248, v248, s0
	v_mad_i64_i32 v[206:207], s[50:51], v160, s90, v[102:103]
	v_lshl_add_u64 v[206:207], v[206:207], 0, v[100:101]
	global_store_short v[206:207], v248, off
	s_waitcnt vmcnt(15)
	v_mul_f32_e32 v249, v209, v249
	v_cndmask_b32_e64 v249, v249, -v249, s[16:17]
	v_fmac_f32_e32 v249, v89, v208
	v_cvt_pk_bf16_f32 v249, v249, s0
	v_mad_i64_i32 v[208:209], s[50:51], v158, s90, v[102:103]
	v_lshl_add_u64 v[208:209], v[208:209], 0, v[100:101]
	global_store_short v[208:209], v249, off
	s_waitcnt vmcnt(15)
	v_mul_f32_e32 v250, v217, v250
	v_cndmask_b32_e64 v250, v250, -v250, s[16:17]
	v_fmac_f32_e32 v250, v90, v216
	v_cvt_pk_bf16_f32 v250, v250, s0
	v_mad_i64_i32 v[216:217], s[50:51], v156, s90, v[102:103]
	v_lshl_add_u64 v[216:217], v[216:217], 0, v[100:101]
	global_store_short v[216:217], v250, off
	s_waitcnt vmcnt(15)
	v_mul_f32_e32 v251, v219, v251
	v_cndmask_b32_e64 v251, v251, -v251, s[16:17]
	v_fmac_f32_e32 v251, v91, v218
	v_cvt_pk_bf16_f32 v251, v251, s0
	v_mad_i64_i32 v[218:219], s[50:51], v154, s90, v[102:103]
	v_lshl_add_u64 v[218:219], v[218:219], 0, v[100:101]
	global_store_short v[218:219], v251, off
	s_waitcnt vmcnt(15)
	v_mul_f32_e32 v252, v221, v252
	v_cndmask_b32_e64 v252, v252, -v252, s[16:17]
	v_fmac_f32_e32 v252, v92, v220
	v_cvt_pk_bf16_f32 v252, v252, s0
	v_mad_i64_i32 v[220:221], s[50:51], v152, s90, v[102:103]
	v_lshl_add_u64 v[220:221], v[220:221], 0, v[100:101]
	global_store_short v[220:221], v252, off
	s_waitcnt vmcnt(15)
	v_mul_f32_e32 v253, v223, v253
	v_cndmask_b32_e64 v253, v253, -v253, s[16:17]
	v_fmac_f32_e32 v253, v93, v222
	v_cvt_pk_bf16_f32 v253, v253, s0
	v_mad_i64_i32 v[222:223], s[50:51], v150, s90, v[102:103]
	v_lshl_add_u64 v[222:223], v[222:223], 0, v[100:101]
	global_store_short v[222:223], v253, off
	s_waitcnt vmcnt(15)
	v_mul_f32_e32 v254, v225, v254
	v_cndmask_b32_e64 v254, v254, -v254, s[16:17]
	v_fmac_f32_e32 v254, v94, v224
	v_cvt_pk_bf16_f32 v254, v254, s0
	v_mad_i64_i32 v[224:225], s[50:51], v148, s90, v[102:103]
	v_lshl_add_u64 v[224:225], v[224:225], 0, v[100:101]
	global_store_short v[224:225], v254, off
	s_waitcnt vmcnt(15)
	v_mul_f32_e32 v255, v227, v255
	v_cndmask_b32_e64 v255, v255, -v255, s[16:17]
	v_fmac_f32_e32 v255, v95, v226
	v_cvt_pk_bf16_f32 v255, v255, s0
	v_mad_i64_i32 v[226:227], s[50:51], v147, s90, v[102:103]
	v_lshl_add_u64 v[226:227], v[226:227], 0, v[100:101]
	global_store_short v[226:227], v255, off

; DI u16 f2bf(float a) { return (u16)(pk2(a, 0.f) & 0xffffu); }
; DI int crow(int i, int h) { return (i & 3) + 8 * (i >> 2) + 4 * h; }
; template <int EPI>
; __device__ __forceinline__ void gemm_tile(const Params& p, int layer, const u16* __restrict__ A, const u16* __restrict__ Bt, int mt, int nt, char* lds) {
;     ...
;         if (latent && (ropeA || ropeB)) {
;           int pair, nf; bool userow; const f32x2* tab;
;           if (ropeA) { pair = (gc & 63) >> 1; nf = 16; tab = (const f32x2*)(p.ws + OFF_TABA); }
;           else       { pair = (gc & 127) >> 1; nf = 32; tab = (const f32x2*)(p.ws + OFF_TABB); }
;           userow = pair < nf;
;           const int f = userow ? pair : pair - nf;
; #pragma unroll
;           for (int e = 0; e < 16; ++e) {
;             const int gr = grb + crow(e, h);
;             const int t = gr - NCTX;
;             const int pos = userow ? (t >> 6) : (t & 63);
;             const f32x2 cs = tab[pos * nf + f];
;             const float v = acc[i][j][e];
;             const float o = __shfl_xor(v, 1);
;             const float res = (gc & 1) ? (o * cs[1] + v * cs[0]) : (v * cs[0] - o * cs[1]);
;             P[(size_t)gr * LDP + gc] = f2bf(res);
;           }
.LBB0_2124:
	v_lshrrev_b32_e32 v48, 1, v50
	v_and_b32_e32 v51, v48, v123
	v_sub_u32_e32 v52, v51, v122
	v_ashrrev_i32_e32 v61, 6, v118
	v_cmp_lt_u32_e32 vcc, v51, v122
	v_min_u32_e32 v60, v51, v52
	v_mov_b32_e32 v113, v129
	v_lshl_add_u64 v[48:49], s[22:23], 0, v[112:113]
	v_and_b32_e32 v56, 64, v214
	v_mov_b64_e32 v[52:53], s[28:29]
	v_xor_b32_e32 v58, 1, v214
	v_add_u32_e32 v59, 64, v56
	v_cmp_lt_i32_e64 s[6:7], v58, v59
	v_and_b32_e32 v62, 1, v50
	v_ashrrev_i32_e32 v51, 31, v50
	v_cndmask_b32_e64 v58, v214, v58, s[6:7]
	v_lshlrev_b32_e32 v63, 2, v58
	v_cmp_eq_u32_e64 s[6:7], 0, v62
	v_lshlrev_b64 v[50:51], 1, v[50:51]
	s_nop 1
	v_cndmask_b32_e32 v190, v117, v61, vcc
	v_lshl_add_u32 v190, v190, v120, v60
	v_ashrrev_i32_e32 v191, 31, v190
	v_lshl_add_u64 v[190:191], v[190:191], 3, v[48:49]
	global_load_dwordx2 v[190:191], v[190:191], off
	ds_bpermute_b32 v240, v63, v32
	v_cndmask_b32_e32 v192, v116, v61, vcc
	v_lshl_add_u32 v192, v192, v120, v60
	v_ashrrev_i32_e32 v193, 31, v192
	v_lshl_add_u64 v[192:193], v[192:193], 3, v[48:49]
	global_load_dwordx2 v[192:193], v[192:193], off
	ds_bpermute_b32 v241, v63, v33
	v_cndmask_b32_e32 v194, v115, v61, vcc
	v_lshl_add_u32 v194, v194, v120, v60
	v_ashrrev_i32_e32 v195, 31, v194
	v_lshl_add_u64 v[194:195], v[194:195], 3, v[48:49]
	global_load_dwordx2 v[194:195], v[194:195], off
	ds_bpermute_b32 v242, v63, v34
	v_cndmask_b32_e32 v196, v111, v61, vcc
	v_lshl_add_u32 v196, v196, v120, v60
	v_ashrrev_i32_e32 v197, 31, v196
	v_lshl_add_u64 v[196:197], v[196:197], 3, v[48:49]
	global_load_dwordx2 v[196:197], v[196:197], off
	ds_bpermute_b32 v243, v63, v35
	v_cndmask_b32_e32 v198, v103, v61, vcc
	v_lshl_add_u32 v198, v198, v120, v60
	v_ashrrev_i32_e32 v199, 31, v198
	v_lshl_add_u64 v[198:199], v[198:199], 3, v[48:49]
	global_load_dwordx2 v[198:199], v[198:199], off
	ds_bpermute_b32 v244, v63, v36
	v_cndmask_b32_e32 v200, v101, v61, vcc
	v_lshl_add_u32 v200, v200, v120, v60
	v_ashrrev_i32_e32 v201, 31, v200
	v_lshl_add_u64 v[200:201], v[200:201], 3, v[48:49]
	global_load_dwordx2 v[200:201], v[200:201], off
	ds_bpermute_b32 v245, v63, v37
	v_cndmask_b32_e32 v202, v99, v61, vcc
	v_lshl_add_u32 v202, v202, v120, v60
	v_ashrrev_i32_e32 v203, 31, v202
	v_lshl_add_u64 v[202:203], v[202:203], 3, v[48:49]
	global_load_dwordx2 v[202:203], v[202:203], off
	ds_bpermute_b32 v246, v63, v38
	v_cndmask_b32_e32 v204, v95, v61, vcc
	v_lshl_add_u32 v204, v204, v120, v60
	v_ashrrev_i32_e32 v205, 31, v204
	v_lshl_add_u64 v[204:205], v[204:205], 3, v[48:49]
	global_load_dwordx2 v[204:205], v[204:205], off
	ds_bpermute_b32 v247, v63, v39
	v_cndmask_b32_e32 v206, v87, v61, vcc
	v_lshl_add_u32 v206, v206, v120, v60
	v_ashrrev_i32_e32 v207, 31, v206
	v_lshl_add_u64 v[206:207], v[206:207], 3, v[48:49]
	global_load_dwordx2 v[206:207], v[206:207], off
	ds_bpermute_b32 v248, v63, v40
	v_cndmask_b32_e32 v208, v85, v61, vcc
	v_lshl_add_u32 v208, v208, v120, v60
	v_ashrrev_i32_e32 v209, 31, v208
	v_lshl_add_u64 v[208:209], v[208:209], 3, v[48:49]
	global_load_dwordx2 v[208:209], v[208:209], off
	ds_bpermute_b32 v249, v63, v41
	v_cndmask_b32_e32 v216, v83, v61, vcc
	v_lshl_add_u32 v216, v216, v120, v60
	v_ashrrev_i32_e32 v217, 31, v216
	v_lshl_add_u64 v[216:217], v[216:217], 3, v[48:49]
	global_load_dwordx2 v[216:217], v[216:217], off
	ds_bpermute_b32 v250, v63, v42
	v_cndmask_b32_e32 v218, v78, v61, vcc
	v_lshl_add_u32 v218, v218, v120, v60
	v_ashrrev_i32_e32 v219, 31, v218
	v_lshl_add_u64 v[218:219], v[218:219], 3, v[48:49]
	global_load_dwordx2 v[218:219], v[218:219], off
	ds_bpermute_b32 v251, v63, v43
	v_cndmask_b32_e32 v220, v76, v61, vcc
	v_lshl_add_u32 v220, v220, v120, v60
	v_ashrrev_i32_e32 v221, 31, v220
	v_lshl_add_u64 v[220:221], v[220:221], 3, v[48:49]
	global_load_dwordx2 v[220:221], v[220:221], off
	ds_bpermute_b32 v252, v63, v44
	v_cndmask_b32_e32 v222, v74, v61, vcc
	v_lshl_add_u32 v222, v222, v120, v60
	v_ashrrev_i32_e32 v223, 31, v222
	v_lshl_add_u64 v[222:223], v[222:223], 3, v[48:49]
	global_load_dwordx2 v[222:223], v[222:223], off
	ds_bpermute_b32 v253, v63, v45
	v_cndmask_b32_e32 v224, v72, v61, vcc
	v_lshl_add_u32 v224, v224, v120, v60
	v_ashrrev_i32_e32 v225, 31, v224
	v_lshl_add_u64 v[224:225], v[224:225], 3, v[48:49]
	global_load_dwordx2 v[224:225], v[224:225], off
	ds_bpermute_b32 v254, v63, v46
	v_cndmask_b32_e32 v226, v70, v61, vcc
	v_lshl_add_u32 v226, v226, v120, v60
	v_ashrrev_i32_e32 v227, 31, v226
	v_lshl_add_u64 v[226:227], v[226:227], 3, v[48:49]
	global_load_dwordx2 v[226:227], v[226:227], off
	ds_bpermute_b32 v255, v63, v47
	s_waitcnt lgkmcnt(0)
	s_waitcnt vmcnt(15)
	v_mul_f32_e32 v240, v191, v240
	v_cndmask_b32_e64 v240, v240, -v240, s[6:7]
	v_fmac_f32_e32 v240, v32, v190
	v_cvt_pk_bf16_f32 v240, v240, s0
	v_mad_i64_i32 v[190:191], s[14:15], v79, s90, v[52:53]
	v_lshl_add_u64 v[190:191], v[190:191], 0, v[50:51]
	global_store_short v[190:191], v240, off
	s_waitcnt vmcnt(15)
; DI u16 f2bf(float a) { return (u16)(pk2(a, 0.f) & 0xffffu); }
; DI int crow(int i, int h) { return (i & 3) + 8 * (i >> 2) + 4 * h; }
; template <int EPI>
; __device__ __forceinline__ void gemm_tile(const Params& p, int layer, const u16* __restrict__ A, const u16* __restrict__ Bt, int mt, int nt, char* lds) {
;     ...
;           for (int e = 0; e < 16; ++e) {
;             const int gr = grb + crow(e, h);
;             const int t = gr - NCTX;
;             const int pos = userow ? (t >> 6) : (t & 63);
;             const f32x2 cs = tab[pos * nf + f];
;             const float v = acc[i][j][e];
;             const float o = __shfl_xor(v, 1);
;             const float res = (gc & 1) ? (o * cs[1] + v * cs[0]) : (v * cs[0] - o * cs[1]);
;             P[(size_t)gr * LDP + gc] = f2bf(res);
;           }
	v_mul_f32_e32 v241, v193, v241
	v_cndmask_b32_e64 v241, v241, -v241, s[6:7]
	v_fmac_f32_e32 v241, v33, v192
	v_cvt_pk_bf16_f32 v241, v241, s0
	v_mad_i64_i32 v[192:193], s[14:15], v114, s90, v[52:53]
	v_lshl_add_u64 v[192:193], v[192:193], 0, v[50:51]
	global_store_short v[192:193], v241, off
	s_waitcnt vmcnt(15)
	v_mul_f32_e32 v242, v195, v242
	v_cndmask_b32_e64 v242, v242, -v242, s[6:7]
	v_fmac_f32_e32 v242, v34, v194
	v_cvt_pk_bf16_f32 v242, v242, s0
	v_mad_i64_i32 v[194:195], s[14:15], v110, s90, v[52:53]
	v_lshl_add_u64 v[194:195], v[194:195], 0, v[50:51]
	global_store_short v[194:195], v242, off
	s_waitcnt vmcnt(15)
	v_mul_f32_e32 v243, v197, v243
	v_cndmask_b32_e64 v243, v243, -v243, s[6:7]
	v_fmac_f32_e32 v243, v35, v196
	v_cvt_pk_bf16_f32 v243, v243, s0
	v_mad_i64_i32 v[196:197], s[14:15], v102, s90, v[52:53]
	v_lshl_add_u64 v[196:197], v[196:197], 0, v[50:51]
	global_store_short v[196:197], v243, off
	s_waitcnt vmcnt(15)
	v_mul_f32_e32 v244, v199, v244
	v_cndmask_b32_e64 v244, v244, -v244, s[6:7]
	v_fmac_f32_e32 v244, v36, v198
	v_cvt_pk_bf16_f32 v244, v244, s0
	v_mad_i64_i32 v[198:199], s[14:15], v100, s90, v[52:53]
	v_lshl_add_u64 v[198:199], v[198:199], 0, v[50:51]
	global_store_short v[198:199], v244, off
	s_waitcnt vmcnt(15)
	v_mul_f32_e32 v245, v201, v245
	v_cndmask_b32_e64 v245, v245, -v245, s[6:7]
	v_fmac_f32_e32 v245, v37, v200
	v_cvt_pk_bf16_f32 v245, v245, s0
	v_mad_i64_i32 v[200:201], s[14:15], v98, s90, v[52:53]
	v_lshl_add_u64 v[200:201], v[200:201], 0, v[50:51]
	global_store_short v[200:201], v245, off
	s_waitcnt vmcnt(15)
	v_mul_f32_e32 v246, v203, v246
	v_cndmask_b32_e64 v246, v246, -v246, s[6:7]
	v_fmac_f32_e32 v246, v38, v202
	v_cvt_pk_bf16_f32 v246, v246, s0
	v_mad_i64_i32 v[202:203], s[14:15], v94, s90, v[52:53]
	v_lshl_add_u64 v[202:203], v[202:203], 0, v[50:51]
	global_store_short v[202:203], v246, off
	s_waitcnt vmcnt(15)
	v_mul_f32_e32 v247, v205, v247
	v_cndmask_b32_e64 v247, v247, -v247, s[6:7]
	v_fmac_f32_e32 v247, v39, v204
	v_cvt_pk_bf16_f32 v247, v247, s0
	v_mad_i64_i32 v[204:205], s[14:15], v86, s90, v[52:53]
	v_lshl_add_u64 v[204:205], v[204:205], 0, v[50:51]
	global_store_short v[204:205], v247, off
	s_waitcnt vmcnt(15)
	v_mul_f32_e32 v248, v207, v248
	v_cndmask_b32_e64 v248, v248, -v248, s[6:7]
	v_fmac_f32_e32 v248, v40, v206
	v_cvt_pk_bf16_f32 v248, v248, s0
	v_mad_i64_i32 v[206:207], s[14:15], v84, s90, v[52:53]
	v_lshl_add_u64 v[206:207], v[206:207], 0, v[50:51]
	global_store_short v[206:207], v248, off
	s_waitcnt vmcnt(15)
	v_mul_f32_e32 v249, v209, v249
	v_cndmask_b32_e64 v249, v249, -v249, s[6:7]
	v_fmac_f32_e32 v249, v41, v208
	v_cvt_pk_bf16_f32 v249, v249, s0
	v_mad_i64_i32 v[208:209], s[14:15], v82, s90, v[52:53]
	v_lshl_add_u64 v[208:209], v[208:209], 0, v[50:51]
	global_store_short v[208:209], v249, off
	s_waitcnt vmcnt(15)
	v_mul_f32_e32 v250, v217, v250
	v_cndmask_b32_e64 v250, v250, -v250, s[6:7]
	v_fmac_f32_e32 v250, v42, v216
	v_cvt_pk_bf16_f32 v250, v250, s0
	v_mad_i64_i32 v[216:217], s[14:15], v77, s90, v[52:53]
	v_lshl_add_u64 v[216:217], v[216:217], 0, v[50:51]
	global_store_short v[216:217], v250, off
	s_waitcnt vmcnt(15)
	v_mul_f32_e32 v251, v219, v251
	v_cndmask_b32_e64 v251, v251, -v251, s[6:7]
	v_fmac_f32_e32 v251, v43, v218
	v_cvt_pk_bf16_f32 v251, v251, s0
	v_mad_i64_i32 v[218:219], s[14:15], v75, s90, v[52:53]
	v_lshl_add_u64 v[218:219], v[218:219], 0, v[50:51]
	global_store_short v[218:219], v251, off
	s_waitcnt vmcnt(15)
	v_mul_f32_e32 v252, v221, v252
	v_cndmask_b32_e64 v252, v252, -v252, s[6:7]
	v_fmac_f32_e32 v252, v44, v220
	v_cvt_pk_bf16_f32 v252, v252, s0
	v_mad_i64_i32 v[220:221], s[14:15], v73, s90, v[52:53]
	v_lshl_add_u64 v[220:221], v[220:221], 0, v[50:51]
	global_store_short v[220:221], v252, off
	s_waitcnt vmcnt(15)
	v_mul_f32_e32 v253, v223, v253
	v_cndmask_b32_e64 v253, v253, -v253, s[6:7]
	v_fmac_f32_e32 v253, v45, v222
	v_cvt_pk_bf16_f32 v253, v253, s0
	v_mad_i64_i32 v[222:223], s[14:15], v71, s90, v[52:53]
	v_lshl_add_u64 v[222:223], v[222:223], 0, v[50:51]
	global_store_short v[222:223], v253, off
	s_waitcnt vmcnt(15)
	v_mul_f32_e32 v254, v225, v254
	v_cndmask_b32_e64 v254, v254, -v254, s[6:7]
	v_fmac_f32_e32 v254, v46, v224
	v_cvt_pk_bf16_f32 v254, v254, s0
	v_mad_i64_i32 v[224:225], s[14:15], v69, s90, v[52:53]
	v_lshl_add_u64 v[224:225], v[224:225], 0, v[50:51]
	global_store_short v[224:225], v254, off
	s_waitcnt vmcnt(15)
	v_mul_f32_e32 v255, v227, v255
	v_cndmask_b32_e64 v255, v255, -v255, s[6:7]
	v_fmac_f32_e32 v255, v47, v226
	v_cvt_pk_bf16_f32 v255, v255, s0
	v_mad_i64_i32 v[226:227], s[14:15], v68, s90, v[52:53]
	v_lshl_add_u64 v[226:227], v[226:227], 0, v[50:51]
	global_store_short v[226:227], v255, off

; DI u16 f2bf(float a) { return (u16)(pk2(a, 0.f) & 0xffffu); }
; DI int crow(int i, int h) { return (i & 3) + 8 * (i >> 2) + 4 * h; }
; template <int EPI>
; __device__ __forceinline__ void gemm_tile(const Params& p, int layer, const u16* __restrict__ A, const u16* __restrict__ Bt, int mt, int nt, char* lds) {
;     ...
;         if (latent && (ropeA || ropeB)) {
;           int pair, nf; bool userow; const f32x2* tab;
;           if (ropeA) { pair = (gc & 63) >> 1; nf = 16; tab = (const f32x2*)(p.ws + OFF_TABA); }
;           else       { pair = (gc & 127) >> 1; nf = 32; tab = (const f32x2*)(p.ws + OFF_TABB); }
;           userow = pair < nf;
;           const int f = userow ? pair : pair - nf;
; #pragma unroll
;           for (int e = 0; e < 16; ++e) {
;             const int gr = grb + crow(e, h);
;             const int t = gr - NCTX;
;             const int pos = userow ? (t >> 6) : (t & 63);
;             const f32x2 cs = tab[pos * nf + f];
;             const float v = acc[i][j][e];
;             const float o = __shfl_xor(v, 1);
;             const float res = (gc & 1) ? (o * cs[1] + v * cs[0]) : (v * cs[0] - o * cs[1]);
;             P[(size_t)gr * LDP + gc] = f2bf(res);
;           }
.LBB0_2151:
	v_lshrrev_b32_e32 v32, 1, v34
	s_waitcnt lgkmcnt(0)
	v_and_b32_e32 v35, v32, v107
	v_sub_u32_e32 v36, v35, v106
	v_ashrrev_i32_e32 v45, 6, v118
	v_cmp_lt_u32_e32 vcc, v35, v106
	v_min_u32_e32 v44, v35, v36
	v_mov_b32_e32 v97, v129
	v_lshl_add_u64 v[32:33], s[22:23], 0, v[96:97]
	v_and_b32_e32 v40, 64, v214
	v_mov_b64_e32 v[36:37], s[28:29]
	v_xor_b32_e32 v42, 1, v214
	v_add_u32_e32 v43, 64, v40
	v_cmp_lt_i32_e64 s[0:1], v42, v43
	v_and_b32_e32 v46, 1, v34
	v_ashrrev_i32_e32 v35, 31, v34
	v_cndmask_b32_e64 v42, v214, v42, s[0:1]
	v_lshlrev_b32_e32 v47, 2, v42
	v_cmp_eq_u32_e64 s[0:1], 0, v46
	v_lshlrev_b64 v[34:35], 1, v[34:35]
	s_nop 1
	v_cndmask_b32_e32 v190, v117, v45, vcc
	v_lshl_add_u32 v190, v190, v105, v44
	v_ashrrev_i32_e32 v191, 31, v190
	v_lshl_add_u64 v[190:191], v[190:191], 3, v[32:33]
	global_load_dwordx2 v[190:191], v[190:191], off
	ds_bpermute_b32 v240, v47, v16
	v_cndmask_b32_e32 v192, v116, v45, vcc
	v_lshl_add_u32 v192, v192, v105, v44
	v_ashrrev_i32_e32 v193, 31, v192
	v_lshl_add_u64 v[192:193], v[192:193], 3, v[32:33]
	global_load_dwordx2 v[192:193], v[192:193], off
	ds_bpermute_b32 v241, v47, v17
	v_cndmask_b32_e32 v194, v115, v45, vcc
	v_lshl_add_u32 v194, v194, v105, v44
	v_ashrrev_i32_e32 v195, 31, v194
	v_lshl_add_u64 v[194:195], v[194:195], 3, v[32:33]
	global_load_dwordx2 v[194:195], v[194:195], off
	ds_bpermute_b32 v242, v47, v18
	v_cndmask_b32_e32 v196, v111, v45, vcc
	v_lshl_add_u32 v196, v196, v105, v44
	v_ashrrev_i32_e32 v197, 31, v196
	v_lshl_add_u64 v[196:197], v[196:197], 3, v[32:33]
	global_load_dwordx2 v[196:197], v[196:197], off
	ds_bpermute_b32 v243, v47, v19
	v_cndmask_b32_e32 v198, v103, v45, vcc
	v_lshl_add_u32 v198, v198, v105, v44
	v_ashrrev_i32_e32 v199, 31, v198
	v_lshl_add_u64 v[198:199], v[198:199], 3, v[32:33]
	global_load_dwordx2 v[198:199], v[198:199], off
	ds_bpermute_b32 v244, v47, v20
	v_cndmask_b32_e32 v200, v101, v45, vcc
	v_lshl_add_u32 v200, v200, v105, v44
	v_ashrrev_i32_e32 v201, 31, v200
	v_lshl_add_u64 v[200:201], v[200:201], 3, v[32:33]
	global_load_dwordx2 v[200:201], v[200:201], off
	ds_bpermute_b32 v245, v47, v21
	v_cndmask_b32_e32 v202, v99, v45, vcc
	v_lshl_add_u32 v202, v202, v105, v44
	v_ashrrev_i32_e32 v203, 31, v202
	v_lshl_add_u64 v[202:203], v[202:203], 3, v[32:33]
	global_load_dwordx2 v[202:203], v[202:203], off
	ds_bpermute_b32 v246, v47, v22
	v_cndmask_b32_e32 v204, v95, v45, vcc
	v_lshl_add_u32 v204, v204, v105, v44
	v_ashrrev_i32_e32 v205, 31, v204
	v_lshl_add_u64 v[204:205], v[204:205], 3, v[32:33]
	global_load_dwordx2 v[204:205], v[204:205], off
	ds_bpermute_b32 v247, v47, v23
	v_cndmask_b32_e32 v206, v87, v45, vcc
	v_lshl_add_u32 v206, v206, v105, v44
	v_ashrrev_i32_e32 v207, 31, v206
	v_lshl_add_u64 v[206:207], v[206:207], 3, v[32:33]
	global_load_dwordx2 v[206:207], v[206:207], off
	ds_bpermute_b32 v248, v47, v24
	v_cndmask_b32_e32 v208, v85, v45, vcc
	v_lshl_add_u32 v208, v208, v105, v44
	v_ashrrev_i32_e32 v209, 31, v208
	v_lshl_add_u64 v[208:209], v[208:209], 3, v[32:33]
	global_load_dwordx2 v[208:209], v[208:209], off
	ds_bpermute_b32 v249, v47, v25
	v_cndmask_b32_e32 v216, v83, v45, vcc
	v_lshl_add_u32 v216, v216, v105, v44
	v_ashrrev_i32_e32 v217, 31, v216
	v_lshl_add_u64 v[216:217], v[216:217], 3, v[32:33]
	global_load_dwordx2 v[216:217], v[216:217], off
	ds_bpermute_b32 v250, v47, v26
	v_cndmask_b32_e32 v218, v78, v45, vcc
	v_lshl_add_u32 v218, v218, v105, v44
	v_ashrrev_i32_e32 v219, 31, v218
	v_lshl_add_u64 v[218:219], v[218:219], 3, v[32:33]
	global_load_dwordx2 v[218:219], v[218:219], off
	ds_bpermute_b32 v251, v47, v27
	v_cndmask_b32_e32 v220, v76, v45, vcc
	v_lshl_add_u32 v220, v220, v105, v44
	v_ashrrev_i32_e32 v221, 31, v220
	v_lshl_add_u64 v[220:221], v[220:221], 3, v[32:33]
	global_load_dwordx2 v[220:221], v[220:221], off
	ds_bpermute_b32 v252, v47, v28
	v_cndmask_b32_e32 v222, v74, v45, vcc
	v_lshl_add_u32 v222, v222, v105, v44
	v_ashrrev_i32_e32 v223, 31, v222
	v_lshl_add_u64 v[222:223], v[222:223], 3, v[32:33]
	global_load_dwordx2 v[222:223], v[222:223], off
	ds_bpermute_b32 v253, v47, v29
	v_cndmask_b32_e32 v224, v72, v45, vcc
	v_lshl_add_u32 v224, v224, v105, v44
	v_ashrrev_i32_e32 v225, 31, v224
	v_lshl_add_u64 v[224:225], v[224:225], 3, v[32:33]
	global_load_dwordx2 v[224:225], v[224:225], off
	ds_bpermute_b32 v254, v47, v30
	v_cndmask_b32_e32 v226, v70, v45, vcc
	v_lshl_add_u32 v226, v226, v105, v44
	v_ashrrev_i32_e32 v227, 31, v226
	v_lshl_add_u64 v[226:227], v[226:227], 3, v[32:33]
	global_load_dwordx2 v[226:227], v[226:227], off
	ds_bpermute_b32 v255, v47, v31
	s_waitcnt lgkmcnt(0)
	s_waitcnt vmcnt(15)
	v_mul_f32_e32 v240, v191, v240
	v_cndmask_b32_e64 v240, v240, -v240, s[0:1]
	v_fmac_f32_e32 v240, v16, v190
	v_cvt_pk_bf16_f32 v240, v240, s0
	v_mad_i64_i32 v[190:191], s[8:9], v79, s90, v[36:37]
	v_lshl_add_u64 v[190:191], v[190:191], 0, v[34:35]
	global_store_short v[190:191], v240, off
	s_waitcnt vmcnt(15)
; DI u16 f2bf(float a) { return (u16)(pk2(a, 0.f) & 0xffffu); }
; DI int crow(int i, int h) { return (i & 3) + 8 * (i >> 2) + 4 * h; }
; template <int EPI>
; __device__ __forceinline__ void gemm_tile(const Params& p, int layer, const u16* __restrict__ A, const u16* __restrict__ Bt, int mt, int nt, char* lds) {
;     ...
;           for (int e = 0; e < 16; ++e) {
;             const int gr = grb + crow(e, h);
;             const int t = gr - NCTX;
;             const int pos = userow ? (t >> 6) : (t & 63);
;             const f32x2 cs = tab[pos * nf + f];
;             const float v = acc[i][j][e];
;             const float o = __shfl_xor(v, 1);
;             const float res = (gc & 1) ? (o * cs[1] + v * cs[0]) : (v * cs[0] - o * cs[1]);
;             P[(size_t)gr * LDP + gc] = f2bf(res);
;           }
	v_mul_f32_e32 v241, v193, v241
	v_cndmask_b32_e64 v241, v241, -v241, s[0:1]
	v_fmac_f32_e32 v241, v17, v192
	v_cvt_pk_bf16_f32 v241, v241, s0
	v_mad_i64_i32 v[192:193], s[8:9], v114, s90, v[36:37]
	v_lshl_add_u64 v[192:193], v[192:193], 0, v[34:35]
	global_store_short v[192:193], v241, off
	s_waitcnt vmcnt(15)
	v_mul_f32_e32 v242, v195, v242
	v_cndmask_b32_e64 v242, v242, -v242, s[0:1]
	v_fmac_f32_e32 v242, v18, v194
	v_cvt_pk_bf16_f32 v242, v242, s0
	v_mad_i64_i32 v[194:195], s[8:9], v110, s90, v[36:37]
	v_lshl_add_u64 v[194:195], v[194:195], 0, v[34:35]
	global_store_short v[194:195], v242, off
	s_waitcnt vmcnt(15)
	v_mul_f32_e32 v243, v197, v243
	v_cndmask_b32_e64 v243, v243, -v243, s[0:1]
	v_fmac_f32_e32 v243, v19, v196
	v_cvt_pk_bf16_f32 v243, v243, s0
	v_mad_i64_i32 v[196:197], s[8:9], v102, s90, v[36:37]
	v_lshl_add_u64 v[196:197], v[196:197], 0, v[34:35]
	global_store_short v[196:197], v243, off
	s_waitcnt vmcnt(15)
	v_mul_f32_e32 v244, v199, v244
	v_cndmask_b32_e64 v244, v244, -v244, s[0:1]
	v_fmac_f32_e32 v244, v20, v198
	v_cvt_pk_bf16_f32 v244, v244, s0
	v_mad_i64_i32 v[198:199], s[8:9], v100, s90, v[36:37]
	v_lshl_add_u64 v[198:199], v[198:199], 0, v[34:35]
	global_store_short v[198:199], v244, off
	s_waitcnt vmcnt(15)
	v_mul_f32_e32 v245, v201, v245
	v_cndmask_b32_e64 v245, v245, -v245, s[0:1]
	v_fmac_f32_e32 v245, v21, v200
	v_cvt_pk_bf16_f32 v245, v245, s0
	v_mad_i64_i32 v[200:201], s[8:9], v98, s90, v[36:37]
	v_lshl_add_u64 v[200:201], v[200:201], 0, v[34:35]
	global_store_short v[200:201], v245, off
	s_waitcnt vmcnt(15)
	v_mul_f32_e32 v246, v203, v246
	v_cndmask_b32_e64 v246, v246, -v246, s[0:1]
	v_fmac_f32_e32 v246, v22, v202
	v_cvt_pk_bf16_f32 v246, v246, s0
	v_mad_i64_i32 v[202:203], s[8:9], v94, s90, v[36:37]
	v_lshl_add_u64 v[202:203], v[202:203], 0, v[34:35]
	global_store_short v[202:203], v246, off
	s_waitcnt vmcnt(15)
	v_mul_f32_e32 v247, v205, v247
	v_cndmask_b32_e64 v247, v247, -v247, s[0:1]
	v_fmac_f32_e32 v247, v23, v204
	v_cvt_pk_bf16_f32 v247, v247, s0
	v_mad_i64_i32 v[204:205], s[8:9], v86, s90, v[36:37]
	v_lshl_add_u64 v[204:205], v[204:205], 0, v[34:35]
	global_store_short v[204:205], v247, off
	s_waitcnt vmcnt(15)
	v_mul_f32_e32 v248, v207, v248
	v_cndmask_b32_e64 v248, v248, -v248, s[0:1]
	v_fmac_f32_e32 v248, v24, v206
	v_cvt_pk_bf16_f32 v248, v248, s0
	v_mad_i64_i32 v[206:207], s[8:9], v84, s90, v[36:37]
	v_lshl_add_u64 v[206:207], v[206:207], 0, v[34:35]
	global_store_short v[206:207], v248, off
	s_waitcnt vmcnt(15)
	v_mul_f32_e32 v249, v209, v249
	v_cndmask_b32_e64 v249, v249, -v249, s[0:1]
	v_fmac_f32_e32 v249, v25, v208
	v_cvt_pk_bf16_f32 v249, v249, s0
	v_mad_i64_i32 v[208:209], s[8:9], v82, s90, v[36:37]
	v_lshl_add_u64 v[208:209], v[208:209], 0, v[34:35]
	global_store_short v[208:209], v249, off
	s_waitcnt vmcnt(15)
	v_mul_f32_e32 v250, v217, v250
	v_cndmask_b32_e64 v250, v250, -v250, s[0:1]
	v_fmac_f32_e32 v250, v26, v216
	v_cvt_pk_bf16_f32 v250, v250, s0
	v_mad_i64_i32 v[216:217], s[8:9], v77, s90, v[36:37]
	v_lshl_add_u64 v[216:217], v[216:217], 0, v[34:35]
	global_store_short v[216:217], v250, off
	s_waitcnt vmcnt(15)
	v_mul_f32_e32 v251, v219, v251
	v_cndmask_b32_e64 v251, v251, -v251, s[0:1]
	v_fmac_f32_e32 v251, v27, v218
	v_cvt_pk_bf16_f32 v251, v251, s0
	v_mad_i64_i32 v[218:219], s[8:9], v75, s90, v[36:37]
	v_lshl_add_u64 v[218:219], v[218:219], 0, v[34:35]
	global_store_short v[218:219], v251, off
	s_waitcnt vmcnt(15)
	v_mul_f32_e32 v252, v221, v252
	v_cndmask_b32_e64 v252, v252, -v252, s[0:1]
	v_fmac_f32_e32 v252, v28, v220
	v_cvt_pk_bf16_f32 v252, v252, s0
	v_mad_i64_i32 v[220:221], s[8:9], v73, s90, v[36:37]
	v_lshl_add_u64 v[220:221], v[220:221], 0, v[34:35]
	global_store_short v[220:221], v252, off
	s_waitcnt vmcnt(15)
	v_mul_f32_e32 v253, v223, v253
	v_cndmask_b32_e64 v253, v253, -v253, s[0:1]
	v_fmac_f32_e32 v253, v29, v222
	v_cvt_pk_bf16_f32 v253, v253, s0
	v_mad_i64_i32 v[222:223], s[8:9], v71, s90, v[36:37]
	v_lshl_add_u64 v[222:223], v[222:223], 0, v[34:35]
	global_store_short v[222:223], v253, off
	s_waitcnt vmcnt(15)
	v_mul_f32_e32 v254, v225, v254
	v_cndmask_b32_e64 v254, v254, -v254, s[0:1]
	v_fmac_f32_e32 v254, v30, v224
	v_cvt_pk_bf16_f32 v254, v254, s0
	v_mad_i64_i32 v[224:225], s[8:9], v69, s90, v[36:37]
	v_lshl_add_u64 v[224:225], v[224:225], 0, v[34:35]
	global_store_short v[224:225], v254, off
	s_waitcnt vmcnt(15)
	v_mul_f32_e32 v255, v227, v255
	v_cndmask_b32_e64 v255, v255, -v255, s[0:1]
	v_fmac_f32_e32 v255, v31, v226
	v_cvt_pk_bf16_f32 v255, v255, s0
	v_mad_i64_i32 v[226:227], s[8:9], v68, s90, v[36:37]
	v_lshl_add_u64 v[226:227], v[226:227], 0, v[34:35]
	global_store_short v[226:227], v255, off

; DI u16 f2bf(float a) { return (u16)(pk2(a, 0.f) & 0xffffu); }
; DI int crow(int i, int h) { return (i & 3) + 8 * (i >> 2) + 4 * h; }
; template <int EPI>
; __device__ __forceinline__ void gemm_tile(const Params& p, int layer, const u16* __restrict__ A, const u16* __restrict__ Bt, int mt, int nt, char* lds) {
;     ...
;         if (latent && (ropeA || ropeB)) {
;           int pair, nf; bool userow; const f32x2* tab;
;           if (ropeA) { pair = (gc & 63) >> 1; nf = 16; tab = (const f32x2*)(p.ws + OFF_TABA); }
;           else       { pair = (gc & 127) >> 1; nf = 32; tab = (const f32x2*)(p.ws + OFF_TABB); }
;           userow = pair < nf;
;           const int f = userow ? pair : pair - nf;
; #pragma unroll
;           for (int e = 0; e < 16; ++e) {
;             const int gr = grb + crow(e, h);
;             const int t = gr - NCTX;
;             const int pos = userow ? (t >> 6) : (t & 63);
;             const f32x2 cs = tab[pos * nf + f];
;             const float v = acc[i][j][e];
;             const float o = __shfl_xor(v, 1);
;             const float res = (gc & 1) ? (o * cs[1] + v * cs[0]) : (v * cs[0] - o * cs[1]);
;             P[(size_t)gr * LDP + gc] = f2bf(res);
;           }
.LBB0_2185:
	v_lshrrev_b32_e32 v16, 1, v18
	v_and_b32_e32 v19, v16, v91
	v_sub_u32_e32 v20, v19, v90
	v_ashrrev_i32_e32 v29, 6, v118
	v_cmp_lt_u32_e32 vcc, v19, v90
	v_min_u32_e32 v28, v19, v20
	v_mov_b32_e32 v81, v129
	v_lshl_add_u64 v[16:17], s[22:23], 0, v[80:81]
	v_and_b32_e32 v24, 64, v214
	v_mov_b64_e32 v[20:21], s[28:29]
	v_xor_b32_e32 v26, 1, v214
	v_add_u32_e32 v27, 64, v24
	v_cmp_lt_i32_e64 s[0:1], v26, v27
	v_and_b32_e32 v30, 1, v18
	v_ashrrev_i32_e32 v19, 31, v18
	v_cndmask_b32_e64 v26, v214, v26, s[0:1]
	v_lshlrev_b32_e32 v31, 2, v26
	v_cmp_eq_u32_e64 s[0:1], 0, v30
	v_lshlrev_b64 v[18:19], 1, v[18:19]
	s_nop 1
	v_cndmask_b32_e32 v190, v117, v29, vcc
	v_lshl_add_u32 v190, v190, v88, v28
	v_ashrrev_i32_e32 v191, 31, v190
	v_lshl_add_u64 v[190:191], v[190:191], 3, v[16:17]
	global_load_dwordx2 v[190:191], v[190:191], off
	ds_bpermute_b32 v240, v31, v0
	v_cndmask_b32_e32 v192, v116, v29, vcc
	v_lshl_add_u32 v192, v192, v88, v28
	v_ashrrev_i32_e32 v193, 31, v192
	v_lshl_add_u64 v[192:193], v[192:193], 3, v[16:17]
	global_load_dwordx2 v[192:193], v[192:193], off
	ds_bpermute_b32 v241, v31, v1
	v_cndmask_b32_e32 v194, v115, v29, vcc
	v_lshl_add_u32 v194, v194, v88, v28
	v_ashrrev_i32_e32 v195, 31, v194
	v_lshl_add_u64 v[194:195], v[194:195], 3, v[16:17]
	global_load_dwordx2 v[194:195], v[194:195], off
	ds_bpermute_b32 v242, v31, v2
	v_cndmask_b32_e32 v196, v111, v29, vcc
	v_lshl_add_u32 v196, v196, v88, v28
	v_ashrrev_i32_e32 v197, 31, v196
	v_lshl_add_u64 v[196:197], v[196:197], 3, v[16:17]
	global_load_dwordx2 v[196:197], v[196:197], off
	ds_bpermute_b32 v243, v31, v3
	v_cndmask_b32_e32 v198, v103, v29, vcc
	v_lshl_add_u32 v198, v198, v88, v28
	v_ashrrev_i32_e32 v199, 31, v198
	v_lshl_add_u64 v[198:199], v[198:199], 3, v[16:17]
	global_load_dwordx2 v[198:199], v[198:199], off
	ds_bpermute_b32 v244, v31, v4
	v_cndmask_b32_e32 v200, v101, v29, vcc
	v_lshl_add_u32 v200, v200, v88, v28
	v_ashrrev_i32_e32 v201, 31, v200
	v_lshl_add_u64 v[200:201], v[200:201], 3, v[16:17]
	global_load_dwordx2 v[200:201], v[200:201], off
	ds_bpermute_b32 v245, v31, v5
	v_cndmask_b32_e32 v202, v99, v29, vcc
	v_lshl_add_u32 v202, v202, v88, v28
	v_ashrrev_i32_e32 v203, 31, v202
	v_lshl_add_u64 v[202:203], v[202:203], 3, v[16:17]
	global_load_dwordx2 v[202:203], v[202:203], off
	ds_bpermute_b32 v246, v31, v6
	v_cndmask_b32_e32 v204, v95, v29, vcc
	v_lshl_add_u32 v204, v204, v88, v28
	v_ashrrev_i32_e32 v205, 31, v204
	v_lshl_add_u64 v[204:205], v[204:205], 3, v[16:17]
	global_load_dwordx2 v[204:205], v[204:205], off
	ds_bpermute_b32 v247, v31, v7
	v_cndmask_b32_e32 v206, v87, v29, vcc
	v_lshl_add_u32 v206, v206, v88, v28
	v_ashrrev_i32_e32 v207, 31, v206
	v_lshl_add_u64 v[206:207], v[206:207], 3, v[16:17]
	global_load_dwordx2 v[206:207], v[206:207], off
	ds_bpermute_b32 v248, v31, v8
	v_cndmask_b32_e32 v208, v85, v29, vcc
	v_lshl_add_u32 v208, v208, v88, v28
	v_ashrrev_i32_e32 v209, 31, v208
	v_lshl_add_u64 v[208:209], v[208:209], 3, v[16:17]
	global_load_dwordx2 v[208:209], v[208:209], off
	ds_bpermute_b32 v249, v31, v9
	v_cndmask_b32_e32 v216, v83, v29, vcc
	v_lshl_add_u32 v216, v216, v88, v28
	v_ashrrev_i32_e32 v217, 31, v216
	v_lshl_add_u64 v[216:217], v[216:217], 3, v[16:17]
	global_load_dwordx2 v[216:217], v[216:217], off
	ds_bpermute_b32 v250, v31, v10
	v_cndmask_b32_e32 v218, v78, v29, vcc
	v_lshl_add_u32 v218, v218, v88, v28
	v_ashrrev_i32_e32 v219, 31, v218
	v_lshl_add_u64 v[218:219], v[218:219], 3, v[16:17]
	global_load_dwordx2 v[218:219], v[218:219], off
	ds_bpermute_b32 v251, v31, v11
	v_cndmask_b32_e32 v220, v76, v29, vcc
	v_lshl_add_u32 v220, v220, v88, v28
	v_ashrrev_i32_e32 v221, 31, v220
	v_lshl_add_u64 v[220:221], v[220:221], 3, v[16:17]
	global_load_dwordx2 v[220:221], v[220:221], off
	ds_bpermute_b32 v252, v31, v12
	v_cndmask_b32_e32 v222, v74, v29, vcc
	v_lshl_add_u32 v222, v222, v88, v28
	v_ashrrev_i32_e32 v223, 31, v222
	v_lshl_add_u64 v[222:223], v[222:223], 3, v[16:17]
	global_load_dwordx2 v[222:223], v[222:223], off
	ds_bpermute_b32 v253, v31, v13
	v_cndmask_b32_e32 v224, v72, v29, vcc
	v_lshl_add_u32 v224, v224, v88, v28
	v_ashrrev_i32_e32 v225, 31, v224
	v_lshl_add_u64 v[224:225], v[224:225], 3, v[16:17]
	global_load_dwordx2 v[224:225], v[224:225], off
	ds_bpermute_b32 v254, v31, v14
	v_cndmask_b32_e32 v226, v70, v29, vcc
	v_lshl_add_u32 v226, v226, v88, v28
	v_ashrrev_i32_e32 v227, 31, v226
	v_lshl_add_u64 v[226:227], v[226:227], 3, v[16:17]
	global_load_dwordx2 v[226:227], v[226:227], off
	ds_bpermute_b32 v255, v31, v15
	s_waitcnt lgkmcnt(0)
	s_waitcnt vmcnt(15)
	v_mul_f32_e32 v240, v191, v240
	v_cndmask_b32_e64 v240, v240, -v240, s[0:1]
	v_fmac_f32_e32 v240, v0, v190
	v_cvt_pk_bf16_f32 v240, v240, s0
	v_mad_i64_i32 v[190:191], s[6:7], v79, s90, v[20:21]
	v_lshl_add_u64 v[190:191], v[190:191], 0, v[18:19]
	global_store_short v[190:191], v240, off
	s_waitcnt vmcnt(15)
; DI u16 f2bf(float a) { return (u16)(pk2(a, 0.f) & 0xffffu); }
; DI int crow(int i, int h) { return (i & 3) + 8 * (i >> 2) + 4 * h; }
; template <int EPI>
; __device__ __forceinline__ void gemm_tile(const Params& p, int layer, const u16* __restrict__ A, const u16* __restrict__ Bt, int mt, int nt, char* lds) {
;     ...
;           for (int e = 0; e < 16; ++e) {
;             const int gr = grb + crow(e, h);
;             const int t = gr - NCTX;
;             const int pos = userow ? (t >> 6) : (t & 63);
;             const f32x2 cs = tab[pos * nf + f];
;             const float v = acc[i][j][e];
;             const float o = __shfl_xor(v, 1);
;             const float res = (gc & 1) ? (o * cs[1] + v * cs[0]) : (v * cs[0] - o * cs[1]);
;             P[(size_t)gr * LDP + gc] = f2bf(res);
;           }
	v_mul_f32_e32 v241, v193, v241
	v_cndmask_b32_e64 v241, v241, -v241, s[0:1]
	v_fmac_f32_e32 v241, v1, v192
	v_cvt_pk_bf16_f32 v241, v241, s0
	v_mad_i64_i32 v[192:193], s[6:7], v114, s90, v[20:21]
	v_lshl_add_u64 v[192:193], v[192:193], 0, v[18:19]
	global_store_short v[192:193], v241, off
	s_waitcnt vmcnt(15)
	v_mul_f32_e32 v242, v195, v242
	v_cndmask_b32_e64 v242, v242, -v242, s[0:1]
	v_fmac_f32_e32 v242, v2, v194
	v_cvt_pk_bf16_f32 v242, v242, s0
	v_mad_i64_i32 v[194:195], s[6:7], v110, s90, v[20:21]
	v_lshl_add_u64 v[194:195], v[194:195], 0, v[18:19]
	global_store_short v[194:195], v242, off
	s_waitcnt vmcnt(15)
	v_mul_f32_e32 v243, v197, v243
	v_cndmask_b32_e64 v243, v243, -v243, s[0:1]
	v_fmac_f32_e32 v243, v3, v196
	v_cvt_pk_bf16_f32 v243, v243, s0
	v_mad_i64_i32 v[196:197], s[6:7], v102, s90, v[20:21]
	v_lshl_add_u64 v[196:197], v[196:197], 0, v[18:19]
	global_store_short v[196:197], v243, off
	s_waitcnt vmcnt(15)
	v_mul_f32_e32 v244, v199, v244
	v_cndmask_b32_e64 v244, v244, -v244, s[0:1]
	v_fmac_f32_e32 v244, v4, v198
	v_cvt_pk_bf16_f32 v244, v244, s0
	v_mad_i64_i32 v[198:199], s[6:7], v100, s90, v[20:21]
	v_lshl_add_u64 v[198:199], v[198:199], 0, v[18:19]
	global_store_short v[198:199], v244, off
	s_waitcnt vmcnt(15)
	v_mul_f32_e32 v245, v201, v245
	v_cndmask_b32_e64 v245, v245, -v245, s[0:1]
	v_fmac_f32_e32 v245, v5, v200
	v_cvt_pk_bf16_f32 v245, v245, s0
	v_mad_i64_i32 v[200:201], s[6:7], v98, s90, v[20:21]
	v_lshl_add_u64 v[200:201], v[200:201], 0, v[18:19]
	global_store_short v[200:201], v245, off
	s_waitcnt vmcnt(15)
	v_mul_f32_e32 v246, v203, v246
	v_cndmask_b32_e64 v246, v246, -v246, s[0:1]
	v_fmac_f32_e32 v246, v6, v202
	v_cvt_pk_bf16_f32 v246, v246, s0
	v_mad_i64_i32 v[202:203], s[6:7], v94, s90, v[20:21]
	v_lshl_add_u64 v[202:203], v[202:203], 0, v[18:19]
	global_store_short v[202:203], v246, off
	s_waitcnt vmcnt(15)
	v_mul_f32_e32 v247, v205, v247
	v_cndmask_b32_e64 v247, v247, -v247, s[0:1]
	v_fmac_f32_e32 v247, v7, v204
	v_cvt_pk_bf16_f32 v247, v247, s0
	v_mad_i64_i32 v[204:205], s[6:7], v86, s90, v[20:21]
	v_lshl_add_u64 v[204:205], v[204:205], 0, v[18:19]
	global_store_short v[204:205], v247, off
	s_waitcnt vmcnt(15)
	v_mul_f32_e32 v248, v207, v248
	v_cndmask_b32_e64 v248, v248, -v248, s[0:1]
	v_fmac_f32_e32 v248, v8, v206
	v_cvt_pk_bf16_f32 v248, v248, s0
	v_mad_i64_i32 v[206:207], s[6:7], v84, s90, v[20:21]
	v_lshl_add_u64 v[206:207], v[206:207], 0, v[18:19]
	global_store_short v[206:207], v248, off
	s_waitcnt vmcnt(15)
	v_mul_f32_e32 v249, v209, v249
	v_cndmask_b32_e64 v249, v249, -v249, s[0:1]
	v_fmac_f32_e32 v249, v9, v208
	v_cvt_pk_bf16_f32 v249, v249, s0
	v_mad_i64_i32 v[208:209], s[6:7], v82, s90, v[20:21]
	v_lshl_add_u64 v[208:209], v[208:209], 0, v[18:19]
	global_store_short v[208:209], v249, off
	s_waitcnt vmcnt(15)
	v_mul_f32_e32 v250, v217, v250
	v_cndmask_b32_e64 v250, v250, -v250, s[0:1]
	v_fmac_f32_e32 v250, v10, v216
	v_cvt_pk_bf16_f32 v250, v250, s0
	v_mad_i64_i32 v[216:217], s[6:7], v77, s90, v[20:21]
	v_lshl_add_u64 v[216:217], v[216:217], 0, v[18:19]
	global_store_short v[216:217], v250, off
	s_waitcnt vmcnt(15)
	v_mul_f32_e32 v251, v219, v251
	v_cndmask_b32_e64 v251, v251, -v251, s[0:1]
	v_fmac_f32_e32 v251, v11, v218
	v_cvt_pk_bf16_f32 v251, v251, s0
	v_mad_i64_i32 v[218:219], s[6:7], v75, s90, v[20:21]
	v_lshl_add_u64 v[218:219], v[218:219], 0, v[18:19]
	global_store_short v[218:219], v251, off
	s_waitcnt vmcnt(15)
	v_mul_f32_e32 v252, v221, v252
	v_cndmask_b32_e64 v252, v252, -v252, s[0:1]
	v_fmac_f32_e32 v252, v12, v220
	v_cvt_pk_bf16_f32 v252, v252, s0
	v_mad_i64_i32 v[220:221], s[6:7], v73, s90, v[20:21]
	v_lshl_add_u64 v[220:221], v[220:221], 0, v[18:19]
	global_store_short v[220:221], v252, off
	s_waitcnt vmcnt(15)
	v_mul_f32_e32 v253, v223, v253
	v_cndmask_b32_e64 v253, v253, -v253, s[0:1]
	v_fmac_f32_e32 v253, v13, v222
	v_cvt_pk_bf16_f32 v253, v253, s0
	v_mad_i64_i32 v[222:223], s[6:7], v71, s90, v[20:21]
	v_lshl_add_u64 v[222:223], v[222:223], 0, v[18:19]
	global_store_short v[222:223], v253, off
	s_waitcnt vmcnt(15)
	v_mul_f32_e32 v254, v225, v254
	v_cndmask_b32_e64 v254, v254, -v254, s[0:1]
	v_fmac_f32_e32 v254, v14, v224
	v_cvt_pk_bf16_f32 v254, v254, s0
	v_mad_i64_i32 v[224:225], s[6:7], v69, s90, v[20:21]
	v_lshl_add_u64 v[224:225], v[224:225], 0, v[18:19]
	global_store_short v[224:225], v254, off
	s_waitcnt vmcnt(15)
	v_mul_f32_e32 v255, v227, v255
	v_cndmask_b32_e64 v255, v255, -v255, s[0:1]
	v_fmac_f32_e32 v255, v15, v226
	v_cvt_pk_bf16_f32 v255, v255, s0
	v_mad_i64_i32 v[226:227], s[6:7], v68, s90, v[20:21]
	v_lshl_add_u64 v[226:227], v[226:227], 0, v[18:19]
	global_store_short v[226:227], v255, off
	s_branch .LBB0_1988

; #define MFMA32(a, b, c) __builtin_amdgcn_mfma_f32_32x32x16_bf16((a), (b), (c), 0, 0, 0)
; DI int crow(int i, int h) { return (i & 3) + 8 * (i >> 2) + 4 * h; }
; DI unsigned f2ord(float f) { unsigned u = __float_as_uint(f); return (u & 0x80000000u) ? ~u : (u | 0x80000000u); }
; #define INS32(T, X) { _Pragma("unroll") for (int jj = 0; jj < 16; ++jj) { unsigned t_ = max(T[jj], X); X = min(T[jj], X); T[jj] = t_; } }
; __device__ __forceinline__ void route_task(const Params& p, int layer, const u16* qg, int rb, int hd, int r, int h) {
;     ...
;     for (int n = 0; n < 4; ++n) {
;       f32x16 acc;
; #pragma unroll
;       for (int e = 0; e < 16; ++e) acc[e] = 0.f;
; #pragma unroll
;       for (int s = 0; s < 8; ++s) {
;         bf16x8 kf = *(const bf16x8*)(kg + (size_t)n * 32 * 128 + 16 * s);
;         acc = MFMA32(kf, qf[s], acc);
;       }
; #pragma unroll
;       for (int e = 0; e < 16; ++e) {
;         unsigned key = (f2ord(acc[e]) & ~127u) | (unsigned)(127 - (n * 32 + crow(e, h)));
;         INS32(tp, key);
;       }
.LBB0_2501:
	global_load_dwordx4 v[190:193], v[50:51], off offset:-128
	global_load_dwordx4 v[194:197], v[50:51], off offset:-96
	global_load_dwordx4 v[198:201], v[50:51], off offset:-64
	global_load_dwordx4 v[202:205], v[50:51], off offset:-32
	global_load_dwordx4 v[206:209], v[50:51], off
	global_load_dwordx4 v[216:219], v[50:51], off offset:32
	global_load_dwordx4 v[220:223], v[50:51], off offset:64
	global_load_dwordx4 v[224:227], v[50:51], off offset:96
	v_lshl_add_u64 v[50:51], v[50:51], 0, s[16:17]
	s_waitcnt vmcnt(7) lgkmcnt(7)
	v_mfma_f32_32x32x16_bf16 v[0:15], v[190:193], v[16:19], 0
	s_waitcnt vmcnt(6) lgkmcnt(6)
	v_mfma_f32_32x32x16_bf16 v[0:15], v[194:197], v[20:23], v[0:15]
	s_waitcnt vmcnt(5) lgkmcnt(5)
	v_mfma_f32_32x32x16_bf16 v[0:15], v[198:201], v[24:27], v[0:15]
	s_waitcnt vmcnt(4) lgkmcnt(4)
	v_mfma_f32_32x32x16_bf16 v[0:15], v[202:205], v[28:31], v[0:15]
	s_waitcnt vmcnt(3) lgkmcnt(3)
	v_mfma_f32_32x32x16_bf16 v[0:15], v[206:209], v[32:35], v[0:15]
	s_waitcnt vmcnt(2) lgkmcnt(2)
	v_mfma_f32_32x32x16_bf16 v[0:15], v[216:219], v[36:39], v[0:15]
	s_waitcnt vmcnt(1) lgkmcnt(1)
	v_mfma_f32_32x32x16_bf16 v[0:15], v[220:223], v[40:43], v[0:15]
	s_waitcnt vmcnt(0) lgkmcnt(0)
	v_mfma_f32_32x32x16_bf16 v[0:15], v[224:227], v[44:47], v[0:15]
	s_nop 11
	v_not_b32_e32 v70, v0
	v_or_b32_e32 v71, 0x80000000, v0
	v_cmp_gt_i32_e32 vcc, 0, v0
	v_or_b32_e32 v72, 0x80000000, v1
	s_nop 0
	v_cndmask_b32_e32 v0, v71, v70, vcc
	v_and_b32_e32 v70, 0xffffff80, v0
	v_add_u32_e32 v0, s18, v53
	v_add3_u32 v70, v0, v70, s52
	v_max_u32_e32 v71, v69, v70
	v_min_u32_e32 v69, v69, v70
	v_max_u32_e32 v70, v68, v69
	v_min_u32_e32 v68, v68, v69
	v_max_u32_e32 v69, v67, v68
	v_min_u32_e32 v67, v67, v68
	v_max_u32_e32 v68, v66, v67
	v_min_u32_e32 v66, v66, v67
	v_max_u32_e32 v67, v65, v66
	v_min_u32_e32 v65, v65, v66
	v_max_u32_e32 v66, v64, v65
	v_min_u32_e32 v64, v64, v65
	v_max_u32_e32 v65, v63, v64
	v_min_u32_e32 v63, v63, v64
	v_max_u32_e32 v64, v62, v63
	v_min_u32_e32 v62, v62, v63
	v_max_u32_e32 v63, v61, v62
	v_min_u32_e32 v61, v61, v62
	v_max_u32_e32 v62, v60, v61
	v_min_u32_e32 v60, v60, v61
	v_max_u32_e32 v61, v59, v60
	v_min_u32_e32 v59, v59, v60
	v_max_u32_e32 v60, v58, v59
	v_min_u32_e32 v58, v58, v59
	v_max_u32_e32 v59, v57, v58
	v_min_u32_e32 v57, v57, v58
	v_max_u32_e32 v58, v56, v57
	v_min_u32_e32 v56, v56, v57
	v_max_u32_e32 v57, v55, v56
	v_min_u32_e32 v55, v55, v56
	v_not_b32_e32 v56, v1
	v_cmp_gt_i32_e32 vcc, 0, v1
	s_sub_i32 s18, s18, 32
	s_cmpk_lg_i32 s18, 0xff80
	v_cndmask_b32_e32 v1, v72, v56, vcc
	v_and_b32_e32 v1, 0xffffff80, v1
	v_add3_u32 v1, v0, v1, s53
	v_max_u32_e32 v56, v71, v1
	v_min_u32_e32 v1, v71, v1
	v_max_u32_e32 v71, v70, v1
	v_min_u32_e32 v1, v70, v1
	v_max_u32_e32 v70, v69, v1
	v_min_u32_e32 v1, v69, v1
	v_max_u32_e32 v69, v68, v1
	v_min_u32_e32 v1, v68, v1
	v_max_u32_e32 v68, v67, v1
	v_min_u32_e32 v1, v67, v1
	v_max_u32_e32 v67, v66, v1
	v_min_u32_e32 v1, v66, v1
	v_max_u32_e32 v66, v65, v1
	v_min_u32_e32 v1, v65, v1
	v_max_u32_e32 v65, v64, v1
	v_min_u32_e32 v1, v64, v1
	v_max_u32_e32 v64, v63, v1
	v_min_u32_e32 v1, v63, v1
	v_max_u32_e32 v63, v62, v1
	v_min_u32_e32 v1, v62, v1
	v_max_u32_e32 v62, v61, v1
	v_min_u32_e32 v1, v61, v1
	v_max_u32_e32 v61, v60, v1
	v_min_u32_e32 v1, v60, v1
	v_max_u32_e32 v60, v59, v1
	v_min_u32_e32 v1, v59, v1
	v_max_u32_e32 v59, v58, v1
	v_min_u32_e32 v1, v58, v1
	v_max_u32_e32 v58, v57, v1
	v_min_u32_e32 v1, v57, v1
	v_max3_u32 v1, v54, v55, v1
	v_not_b32_e32 v54, v2
	v_or_b32_e32 v55, 0x80000000, v2
	v_cmp_gt_i32_e32 vcc, 0, v2
	s_nop 1
	v_cndmask_b32_e32 v2, v55, v54, vcc
	v_and_b32_e32 v2, 0xffffff80, v2
	v_add3_u32 v2, v0, v2, s54
	v_max_u32_e32 v54, v56, v2
	v_min_u32_e32 v2, v56, v2
	v_max_u32_e32 v55, v71, v2
	v_min_u32_e32 v2, v71, v2
	v_max_u32_e32 v56, v70, v2
	v_min_u32_e32 v2, v70, v2
	v_max_u32_e32 v57, v69, v2
	v_min_u32_e32 v2, v69, v2
	v_max_u32_e32 v69, v68, v2
	v_min_u32_e32 v2, v68, v2
	v_max_u32_e32 v68, v67, v2
	v_min_u32_e32 v2, v67, v2
	v_max_u32_e32 v67, v66, v2
	v_min_u32_e32 v2, v66, v2
	v_max_u32_e32 v66, v65, v2
	v_min_u32_e32 v2, v65, v2
	v_max_u32_e32 v65, v64, v2
	v_min_u32_e32 v2, v64, v2
	v_max_u32_e32 v64, v63, v2
	v_min_u32_e32 v2, v63, v2
	v_max_u32_e32 v63, v62, v2
	v_min_u32_e32 v2, v62, v2
	v_max_u32_e32 v62, v61, v2
	v_min_u32_e32 v2, v61, v2
	v_max_u32_e32 v61, v60, v2
	v_min_u32_e32 v2, v60, v2
	v_max_u32_e32 v60, v59, v2
	v_min_u32_e32 v2, v59, v2
	v_max_u32_e32 v59, v58, v2
	v_min_u32_e32 v2, v58, v2
	v_not_b32_e32 v58, v3
	v_or_b32_e32 v70, 0x80000000, v3
	v_cmp_gt_i32_e32 vcc, 0, v3
	s_nop 1
	v_cndmask_b32_e32 v3, v70, v58, vcc
	v_and_b32_e32 v3, 0xffffff80, v3
	v_add3_u32 v3, v0, v3, s55
	v_max_u32_e32 v58, v54, v3
	v_min_u32_e32 v3, v54, v3
	v_max_u32_e32 v54, v55, v3
	v_min_u32_e32 v3, v55, v3
	v_max_u32_e32 v55, v56, v3
	v_min_u32_e32 v3, v56, v3
	v_max_u32_e32 v56, v57, v3
	v_min_u32_e32 v3, v57, v3
	v_max_u32_e32 v57, v69, v3
	v_min_u32_e32 v3, v69, v3
	v_max_u32_e32 v69, v68, v3
	v_min_u32_e32 v3, v68, v3
	v_max_u32_e32 v68, v67, v3
	v_min_u32_e32 v3, v67, v3
	v_max_u32_e32 v67, v66, v3
	v_min_u32_e32 v3, v66, v3
	v_max_u32_e32 v66, v65, v3
	v_min_u32_e32 v3, v65, v3
	v_max_u32_e32 v65, v64, v3
	v_min_u32_e32 v3, v64, v3
	v_max_u32_e32 v64, v63, v3
	v_min_u32_e32 v3, v63, v3
	v_max_u32_e32 v63, v62, v3
	v_min_u32_e32 v3, v62, v3
	v_max_u32_e32 v62, v61, v3
	v_min_u32_e32 v3, v61, v3
	v_max_u32_e32 v61, v60, v3
	v_min_u32_e32 v3, v60, v3
	v_max_u32_e32 v60, v59, v3
	v_min_u32_e32 v3, v59, v3
	v_max3_u32 v1, v1, v2, v3
	v_not_b32_e32 v2, v4
	v_or_b32_e32 v3, 0x80000000, v4
	v_cmp_gt_i32_e32 vcc, 0, v4
	s_nop 1
; DI int crow(int i, int h) { return (i & 3) + 8 * (i >> 2) + 4 * h; }
; DI unsigned f2ord(float f) { unsigned u = __float_as_uint(f); return (u & 0x80000000u) ? ~u : (u | 0x80000000u); }
; #define INS32(T, X) { _Pragma("unroll") for (int jj = 0; jj < 16; ++jj) { unsigned t_ = max(T[jj], X); X = min(T[jj], X); T[jj] = t_; } }
; __device__ __forceinline__ void route_task(const Params& p, int layer, const u16* qg, int rb, int hd, int r, int h) {
;     ...
;       for (int e = 0; e < 16; ++e) {
;         unsigned key = (f2ord(acc[e]) & ~127u) | (unsigned)(127 - (n * 32 + crow(e, h)));
;         INS32(tp, key);
;       }
	v_cndmask_b32_e32 v2, v3, v2, vcc
	v_and_b32_e32 v2, 0xffffff80, v2
	v_add3_u32 v2, v0, v2, s56
	v_max_u32_e32 v3, v58, v2
	v_min_u32_e32 v2, v58, v2
	v_max_u32_e32 v4, v54, v2
	v_min_u32_e32 v2, v54, v2
	v_max_u32_e32 v54, v55, v2
	v_min_u32_e32 v2, v55, v2
	v_max_u32_e32 v55, v56, v2
	v_min_u32_e32 v2, v56, v2
	v_max_u32_e32 v56, v57, v2
	v_min_u32_e32 v2, v57, v2
	v_max_u32_e32 v57, v69, v2
	v_min_u32_e32 v2, v69, v2
	v_max_u32_e32 v58, v68, v2
	v_min_u32_e32 v2, v68, v2
	v_max_u32_e32 v59, v67, v2
	v_min_u32_e32 v2, v67, v2
	v_max_u32_e32 v67, v66, v2
	v_min_u32_e32 v2, v66, v2
	v_max_u32_e32 v66, v65, v2
	v_min_u32_e32 v2, v65, v2
	v_max_u32_e32 v65, v64, v2
	v_min_u32_e32 v2, v64, v2
	v_max_u32_e32 v64, v63, v2
	v_min_u32_e32 v2, v63, v2
	v_max_u32_e32 v63, v62, v2
	v_min_u32_e32 v2, v62, v2
	v_max_u32_e32 v62, v61, v2
	v_min_u32_e32 v2, v61, v2
	v_max_u32_e32 v61, v60, v2
	v_min_u32_e32 v2, v60, v2
	v_not_b32_e32 v60, v5
	v_or_b32_e32 v68, 0x80000000, v5
	v_cmp_gt_i32_e32 vcc, 0, v5
	s_nop 1
	v_cndmask_b32_e32 v5, v68, v60, vcc
	v_and_b32_e32 v5, 0xffffff80, v5
	v_add3_u32 v5, v0, v5, s57
	v_max_u32_e32 v60, v3, v5
	v_min_u32_e32 v3, v3, v5
	v_max_u32_e32 v5, v4, v3
	v_min_u32_e32 v3, v4, v3
	v_max_u32_e32 v4, v54, v3
	v_min_u32_e32 v3, v54, v3
	v_max_u32_e32 v54, v55, v3
	v_min_u32_e32 v3, v55, v3
	v_max_u32_e32 v55, v56, v3
	v_min_u32_e32 v3, v56, v3
	v_max_u32_e32 v56, v57, v3
	v_min_u32_e32 v3, v57, v3
	v_max_u32_e32 v57, v58, v3
	v_min_u32_e32 v3, v58, v3
	v_max_u32_e32 v58, v59, v3
	v_min_u32_e32 v3, v59, v3
	v_max_u32_e32 v59, v67, v3
	v_min_u32_e32 v3, v67, v3
	v_max_u32_e32 v67, v66, v3
	v_min_u32_e32 v3, v66, v3
	v_max_u32_e32 v66, v65, v3
	v_min_u32_e32 v3, v65, v3
	v_max_u32_e32 v65, v64, v3
	v_min_u32_e32 v3, v64, v3
	v_max_u32_e32 v64, v63, v3
	v_min_u32_e32 v3, v63, v3
	v_max_u32_e32 v63, v62, v3
	v_min_u32_e32 v3, v62, v3
	v_max_u32_e32 v62, v61, v3
	v_min_u32_e32 v3, v61, v3
	v_max3_u32 v1, v1, v2, v3
	v_not_b32_e32 v2, v6
	v_or_b32_e32 v3, 0x80000000, v6
	v_cmp_gt_i32_e32 vcc, 0, v6
	s_nop 1
	v_cndmask_b32_e32 v2, v3, v2, vcc
	v_and_b32_e32 v2, 0xffffff80, v2
	v_add3_u32 v2, v0, v2, s58
	v_max_u32_e32 v3, v60, v2
	v_min_u32_e32 v2, v60, v2
	v_max_u32_e32 v6, v5, v2
	v_min_u32_e32 v2, v5, v2
	v_max_u32_e32 v5, v4, v2
	v_min_u32_e32 v2, v4, v2
	v_max_u32_e32 v4, v54, v2
	v_min_u32_e32 v2, v54, v2
	v_max_u32_e32 v54, v55, v2
	v_min_u32_e32 v2, v55, v2
	v_max_u32_e32 v55, v56, v2
	v_min_u32_e32 v2, v56, v2
	v_max_u32_e32 v56, v57, v2
	v_min_u32_e32 v2, v57, v2
	v_max_u32_e32 v57, v58, v2
	v_min_u32_e32 v2, v58, v2
	v_max_u32_e32 v58, v59, v2
	v_min_u32_e32 v2, v59, v2
	v_max_u32_e32 v59, v67, v2
	v_min_u32_e32 v2, v67, v2
	v_max_u32_e32 v60, v66, v2
	v_min_u32_e32 v2, v66, v2
	v_max_u32_e32 v61, v65, v2
	v_min_u32_e32 v2, v65, v2
	v_max_u32_e32 v65, v64, v2
	v_min_u32_e32 v2, v64, v2
	v_max_u32_e32 v64, v63, v2
	v_min_u32_e32 v2, v63, v2
	v_max_u32_e32 v63, v62, v2
	v_min_u32_e32 v2, v62, v2
	v_not_b32_e32 v62, v7
	v_or_b32_e32 v66, 0x80000000, v7
	v_cmp_gt_i32_e32 vcc, 0, v7
	s_nop 1
	v_cndmask_b32_e32 v7, v66, v62, vcc
	v_and_b32_e32 v7, 0xffffff80, v7
	v_add3_u32 v7, v0, v7, s59
	v_max_u32_e32 v62, v3, v7
	v_min_u32_e32 v3, v3, v7
	v_max_u32_e32 v7, v6, v3
	v_min_u32_e32 v3, v6, v3
	v_max_u32_e32 v6, v5, v3
	v_min_u32_e32 v3, v5, v3
	v_max_u32_e32 v5, v4, v3
	v_min_u32_e32 v3, v4, v3
	v_max_u32_e32 v4, v54, v3
	v_min_u32_e32 v3, v54, v3
	v_max_u32_e32 v54, v55, v3
	v_min_u32_e32 v3, v55, v3
	v_max_u32_e32 v55, v56, v3
	v_min_u32_e32 v3, v56, v3
	v_max_u32_e32 v56, v57, v3
	v_min_u32_e32 v3, v57, v3
	v_max_u32_e32 v57, v58, v3
	v_min_u32_e32 v3, v58, v3
	v_max_u32_e32 v58, v59, v3
	v_min_u32_e32 v3, v59, v3
	v_max_u32_e32 v59, v60, v3
	v_min_u32_e32 v3, v60, v3
	v_max_u32_e32 v60, v61, v3
	v_min_u32_e32 v3, v61, v3
	v_max_u32_e32 v61, v65, v3
	v_min_u32_e32 v3, v65, v3
	v_max_u32_e32 v65, v64, v3
	v_min_u32_e32 v3, v64, v3
	v_max_u32_e32 v64, v63, v3
	v_min_u32_e32 v3, v63, v3
	v_max3_u32 v1, v1, v2, v3
	v_not_b32_e32 v2, v8
	v_or_b32_e32 v3, 0x80000000, v8
	v_cmp_gt_i32_e32 vcc, 0, v8
	v_not_b32_e32 v63, v9
	s_nop 0
	v_cndmask_b32_e32 v2, v3, v2, vcc
	v_and_b32_e32 v2, 0xffffff80, v2
	v_add3_u32 v2, v0, v2, s60
	v_max_u32_e32 v3, v62, v2
	v_min_u32_e32 v2, v62, v2
	v_max_u32_e32 v8, v7, v2
	v_min_u32_e32 v2, v7, v2
	v_max_u32_e32 v7, v6, v2
	v_min_u32_e32 v2, v6, v2
	v_max_u32_e32 v6, v5, v2
	v_min_u32_e32 v2, v5, v2
	v_max_u32_e32 v5, v4, v2
	v_min_u32_e32 v2, v4, v2
	v_max_u32_e32 v4, v54, v2
	v_min_u32_e32 v2, v54, v2
	v_max_u32_e32 v54, v55, v2
	v_min_u32_e32 v2, v55, v2
	v_max_u32_e32 v55, v56, v2
	v_min_u32_e32 v2, v56, v2
	v_max_u32_e32 v56, v57, v2
	v_min_u32_e32 v2, v57, v2
	v_max_u32_e32 v57, v58, v2
	v_min_u32_e32 v2, v58, v2
	v_max_u32_e32 v58, v59, v2
	v_min_u32_e32 v2, v59, v2
	v_max_u32_e32 v59, v60, v2
	v_min_u32_e32 v2, v60, v2
	v_max_u32_e32 v60, v61, v2
	v_min_u32_e32 v2, v61, v2
	v_max_u32_e32 v61, v65, v2
	v_min_u32_e32 v2, v65, v2
	v_max_u32_e32 v62, v64, v2
	v_min_u32_e32 v2, v64, v2
	v_or_b32_e32 v64, 0x80000000, v9
	v_cmp_gt_i32_e32 vcc, 0, v9
	s_nop 1
	v_cndmask_b32_e32 v9, v64, v63, vcc
	v_and_b32_e32 v9, 0xffffff80, v9
	v_add3_u32 v9, v0, v9, s61
	v_max_u32_e32 v63, v3, v9
	v_min_u32_e32 v3, v3, v9
	v_max_u32_e32 v9, v8, v3
	v_min_u32_e32 v3, v8, v3
	v_max_u32_e32 v8, v7, v3
	v_min_u32_e32 v3, v7, v3
	v_max_u32_e32 v7, v6, v3
	v_min_u32_e32 v3, v6, v3
	v_max_u32_e32 v6, v5, v3
	v_min_u32_e32 v3, v5, v3
	v_max_u32_e32 v5, v4, v3
	v_min_u32_e32 v3, v4, v3
	v_max_u32_e32 v4, v54, v3
	v_min_u32_e32 v3, v54, v3
	v_max_u32_e32 v54, v55, v3
	v_min_u32_e32 v3, v55, v3
	v_max_u32_e32 v55, v56, v3
; DI int crow(int i, int h) { return (i & 3) + 8 * (i >> 2) + 4 * h; }
; DI unsigned f2ord(float f) { unsigned u = __float_as_uint(f); return (u & 0x80000000u) ? ~u : (u | 0x80000000u); }
; #define INS32(T, X) { _Pragma("unroll") for (int jj = 0; jj < 16; ++jj) { unsigned t_ = max(T[jj], X); X = min(T[jj], X); T[jj] = t_; } }
; __device__ __forceinline__ void route_task(const Params& p, int layer, const u16* qg, int rb, int hd, int r, int h) {
;     ...
; #pragma unroll
;       for (int e = 0; e < 16; ++e) {
;         unsigned key = (f2ord(acc[e]) & ~127u) | (unsigned)(127 - (n * 32 + crow(e, h)));
;         INS32(tp, key);
;       }
	v_min_u32_e32 v3, v56, v3
	v_max_u32_e32 v56, v57, v3
	v_min_u32_e32 v3, v57, v3
	v_max_u32_e32 v57, v58, v3
	v_min_u32_e32 v3, v58, v3
	v_max_u32_e32 v58, v59, v3
	v_min_u32_e32 v3, v59, v3
	v_max_u32_e32 v59, v60, v3
	v_min_u32_e32 v3, v60, v3
	v_max_u32_e32 v60, v61, v3
	v_min_u32_e32 v3, v61, v3
	v_max_u32_e32 v61, v62, v3
	v_min_u32_e32 v3, v62, v3
	v_max3_u32 v1, v1, v2, v3
	v_not_b32_e32 v2, v10
	v_or_b32_e32 v3, 0x80000000, v10
	v_cmp_gt_i32_e32 vcc, 0, v10
	v_or_b32_e32 v62, 0x80000000, v11
	s_nop 0
	v_cndmask_b32_e32 v2, v3, v2, vcc
	v_and_b32_e32 v2, 0xffffff80, v2
	v_add3_u32 v2, v0, v2, s62
	v_max_u32_e32 v3, v63, v2
	v_min_u32_e32 v2, v63, v2
	v_max_u32_e32 v10, v9, v2
	v_min_u32_e32 v2, v9, v2
	v_max_u32_e32 v9, v8, v2
	v_min_u32_e32 v2, v8, v2
	v_max_u32_e32 v8, v7, v2
	v_min_u32_e32 v2, v7, v2
	v_max_u32_e32 v7, v6, v2
	v_min_u32_e32 v2, v6, v2
	v_max_u32_e32 v6, v5, v2
	v_min_u32_e32 v2, v5, v2
	v_max_u32_e32 v5, v4, v2
	v_min_u32_e32 v2, v4, v2
	v_max_u32_e32 v4, v54, v2
	v_min_u32_e32 v2, v54, v2
	v_max_u32_e32 v54, v55, v2
	v_min_u32_e32 v2, v55, v2
	v_max_u32_e32 v55, v56, v2
	v_min_u32_e32 v2, v56, v2
	v_max_u32_e32 v56, v57, v2
	v_min_u32_e32 v2, v57, v2
	v_max_u32_e32 v57, v58, v2
	v_min_u32_e32 v2, v58, v2
	v_max_u32_e32 v58, v59, v2
	v_min_u32_e32 v2, v59, v2
	v_max_u32_e32 v59, v60, v2
	v_min_u32_e32 v2, v60, v2
	v_max_u32_e32 v60, v61, v2
	v_min_u32_e32 v2, v61, v2
	v_not_b32_e32 v61, v11
	v_cmp_gt_i32_e32 vcc, 0, v11
	s_nop 1
	v_cndmask_b32_e32 v11, v62, v61, vcc
	v_and_b32_e32 v11, 0xffffff80, v11
	v_add3_u32 v11, v0, v11, s63
	v_max_u32_e32 v61, v3, v11
	v_min_u32_e32 v3, v3, v11
	v_max_u32_e32 v11, v10, v3
	v_min_u32_e32 v3, v10, v3
	v_max_u32_e32 v10, v9, v3
	v_min_u32_e32 v3, v9, v3
	v_max_u32_e32 v9, v8, v3
	v_min_u32_e32 v3, v8, v3
	v_max_u32_e32 v8, v7, v3
	v_min_u32_e32 v3, v7, v3
	v_max_u32_e32 v7, v6, v3
	v_min_u32_e32 v3, v6, v3
	v_max_u32_e32 v6, v5, v3
	v_min_u32_e32 v3, v5, v3
	v_max_u32_e32 v5, v4, v3
	v_min_u32_e32 v3, v4, v3
	v_max_u32_e32 v4, v54, v3
	v_min_u32_e32 v3, v54, v3
	v_max_u32_e32 v54, v55, v3
	v_min_u32_e32 v3, v55, v3
	v_max_u32_e32 v55, v56, v3
	v_min_u32_e32 v3, v56, v3
	v_max_u32_e32 v56, v57, v3
	v_min_u32_e32 v3, v57, v3
	v_max_u32_e32 v57, v58, v3
	v_min_u32_e32 v3, v58, v3
	v_max_u32_e32 v58, v59, v3
	v_min_u32_e32 v3, v59, v3
	v_max_u32_e32 v59, v60, v3
	v_min_u32_e32 v3, v60, v3
	v_max3_u32 v1, v1, v2, v3
	v_not_b32_e32 v2, v12
	v_or_b32_e32 v3, 0x80000000, v12
	v_cmp_gt_i32_e32 vcc, 0, v12
	v_or_b32_e32 v60, 0x80000000, v13
	s_nop 0
	v_cndmask_b32_e32 v2, v3, v2, vcc
	v_and_b32_e32 v2, 0xffffff80, v2
	v_add3_u32 v2, v0, v2, s64
	v_max_u32_e32 v3, v61, v2
	v_min_u32_e32 v2, v61, v2
	v_max_u32_e32 v12, v11, v2
	v_min_u32_e32 v2, v11, v2
	v_max_u32_e32 v11, v10, v2
	v_min_u32_e32 v2, v10, v2
	v_max_u32_e32 v10, v9, v2
	v_min_u32_e32 v2, v9, v2
	v_max_u32_e32 v9, v8, v2
	v_min_u32_e32 v2, v8, v2
	v_max_u32_e32 v8, v7, v2
	v_min_u32_e32 v2, v7, v2
	v_max_u32_e32 v7, v6, v2
	v_min_u32_e32 v2, v6, v2
	v_max_u32_e32 v6, v5, v2
	v_min_u32_e32 v2, v5, v2
	v_max_u32_e32 v5, v4, v2
	v_min_u32_e32 v2, v4, v2
	v_max_u32_e32 v4, v54, v2
	v_min_u32_e32 v2, v54, v2
	v_max_u32_e32 v54, v55, v2
	v_min_u32_e32 v2, v55, v2
	v_max_u32_e32 v55, v56, v2
	v_min_u32_e32 v2, v56, v2
	v_max_u32_e32 v56, v57, v2
	v_min_u32_e32 v2, v57, v2
	v_max_u32_e32 v57, v58, v2
	v_min_u32_e32 v2, v58, v2
	v_max_u32_e32 v58, v59, v2
	v_min_u32_e32 v2, v59, v2
	v_not_b32_e32 v59, v13
	v_cmp_gt_i32_e32 vcc, 0, v13
	s_nop 1
	v_cndmask_b32_e32 v13, v60, v59, vcc
	v_and_b32_e32 v13, 0xffffff80, v13
	v_add3_u32 v13, v0, v13, s65
	v_max_u32_e32 v59, v3, v13
	v_min_u32_e32 v3, v3, v13
	v_max_u32_e32 v13, v12, v3
	v_min_u32_e32 v3, v12, v3
	v_max_u32_e32 v12, v11, v3
	v_min_u32_e32 v3, v11, v3
	v_max_u32_e32 v11, v10, v3
	v_min_u32_e32 v3, v10, v3
	v_max_u32_e32 v10, v9, v3
	v_min_u32_e32 v3, v9, v3
	v_max_u32_e32 v9, v8, v3
	v_min_u32_e32 v3, v8, v3
	v_max_u32_e32 v8, v7, v3
	v_min_u32_e32 v3, v7, v3
	v_max_u32_e32 v7, v6, v3
	v_min_u32_e32 v3, v6, v3
	v_max_u32_e32 v6, v5, v3
	v_min_u32_e32 v3, v5, v3
	v_max_u32_e32 v5, v4, v3
	v_min_u32_e32 v3, v4, v3
	v_max_u32_e32 v4, v54, v3
	v_min_u32_e32 v3, v54, v3
	v_max_u32_e32 v54, v55, v3
	v_min_u32_e32 v3, v55, v3
	v_max_u32_e32 v55, v56, v3
	v_min_u32_e32 v3, v56, v3
	v_max_u32_e32 v56, v57, v3
	v_min_u32_e32 v3, v57, v3
	v_max_u32_e32 v57, v58, v3
	v_min_u32_e32 v3, v58, v3
	v_max3_u32 v1, v1, v2, v3
	v_not_b32_e32 v2, v14
	v_or_b32_e32 v3, 0x80000000, v14
	v_cmp_gt_i32_e32 vcc, 0, v14
	s_nop 1
	v_cndmask_b32_e32 v2, v3, v2, vcc
	v_and_b32_e32 v2, 0xffffff80, v2
	v_add3_u32 v2, v0, v2, s66
	v_max_u32_e32 v3, v59, v2
	v_min_u32_e32 v2, v59, v2
	v_max_u32_e32 v14, v13, v2
	v_min_u32_e32 v2, v13, v2
	v_max_u32_e32 v13, v12, v2
	v_min_u32_e32 v2, v12, v2
	v_max_u32_e32 v12, v11, v2
	v_min_u32_e32 v2, v11, v2
	v_max_u32_e32 v11, v10, v2
	v_min_u32_e32 v2, v10, v2
	v_max_u32_e32 v10, v9, v2
	v_min_u32_e32 v2, v9, v2
	v_max_u32_e32 v9, v8, v2
	v_min_u32_e32 v2, v8, v2
	v_max_u32_e32 v8, v7, v2
	v_min_u32_e32 v2, v7, v2
	v_max_u32_e32 v7, v6, v2
	v_min_u32_e32 v2, v6, v2
	v_max_u32_e32 v6, v5, v2
	v_min_u32_e32 v2, v5, v2
	v_max_u32_e32 v5, v4, v2
	v_min_u32_e32 v2, v4, v2
	v_max_u32_e32 v4, v54, v2
	v_min_u32_e32 v2, v54, v2
	v_max_u32_e32 v54, v55, v2
	v_min_u32_e32 v2, v55, v2
	v_max_u32_e32 v55, v56, v2
	v_min_u32_e32 v2, v56, v2
	v_max_u32_e32 v70, v57, v2
	v_min_u32_e32 v2, v57, v2
	v_not_b32_e32 v56, v15
	v_or_b32_e32 v57, 0x80000000, v15
	v_cmp_gt_i32_e32 vcc, 0, v15
	s_nop 1
	v_cndmask_b32_e32 v15, v57, v56, vcc
	v_and_b32_e32 v15, 0xffffff80, v15
	v_add3_u32 v0, v0, v15, s67
	v_max_u32_e32 v69, v3, v0
	v_min_u32_e32 v0, v3, v0
	v_max_u32_e32 v68, v14, v0
	v_min_u32_e32 v0, v14, v0
	v_max_u32_e32 v67, v13, v0
	v_min_u32_e32 v0, v13, v0
	v_max_u32_e32 v66, v12, v0
	v_min_u32_e32 v0, v12, v0
	v_max_u32_e32 v65, v11, v0
	v_min_u32_e32 v0, v11, v0
	v_max_u32_e32 v64, v10, v0
	v_min_u32_e32 v0, v10, v0
	v_max_u32_e32 v63, v9, v0
	v_min_u32_e32 v0, v9, v0
	v_max_u32_e32 v62, v8, v0
	v_min_u32_e32 v0, v8, v0
	v_max_u32_e32 v61, v7, v0
	v_min_u32_e32 v0, v7, v0
	v_max_u32_e32 v60, v6, v0
	v_min_u32_e32 v0, v6, v0
	v_max_u32_e32 v59, v5, v0
	v_min_u32_e32 v0, v5, v0
	v_max_u32_e32 v58, v4, v0
	v_min_u32_e32 v0, v4, v0
	v_max_u32_e32 v57, v54, v0
	v_min_u32_e32 v0, v54, v0
	v_max_u32_e32 v56, v55, v0
	v_min_u32_e32 v0, v55, v0
	v_max_u32_e32 v55, v70, v0
	v_min_u32_e32 v0, v70, v0
	v_max3_u32 v54, v1, v2, v0
	s_cbranch_scc1 .LBB0_2501
; #define MFMA32(a, b, c) __builtin_amdgcn_mfma_f32_32x32x16_bf16((a), (b), (c), 0, 0, 0)
; __device__ __forceinline__ void route_task(const Params& p, int layer, const u16* qg, int rb, int hd, int r, int h) {
;     ...
;   for (int ph = 0; ph < 2; ++ph) {
;     bf16x8 qf[8];
; #pragma unroll
;     for (int s = 0; s < 8; ++s) qf[s] = *(const bf16x8*)(qg + ph * 128 + 16 * s);
;     const u16* kg = KY + ((size_t)((layer * 8 + hd) * 2 + ph) * 128 + r) * 128 + 8 * h;
;     unsigned tp[16];
; #pragma unroll
;     for (int jj = 0; jj < 16; ++jj) tp[jj] = 0u;
; #pragma unroll 1
;     for (int n = 0; n < 4; ++n) {
;       f32x16 acc;
; #pragma unroll
;       for (int e = 0; e < 16; ++e) acc[e] = 0.f;
; #pragma unroll
;       for (int s = 0; s < 8; ++s) {
;         bf16x8 kf = *(const bf16x8*)(kg + (size_t)n * 32 * 128 + 16 * s);
;         acc = MFMA32(kf, qf[s], acc);
;     ...
;     for (int jj = 0; jj < 16; ++jj) ot[jj] = (unsigned)__shfl_xor((int)tp[jj], 32);
	ds_read_b128 v[16:19], v83 offset:256
	ds_read_b128 v[20:23], v83 offset:288
	ds_read_b128 v[24:27], v83 offset:320
	ds_read_b128 v[28:31], v83 offset:352
	ds_read_b128 v[32:35], v83 offset:384
	ds_read_b128 v[36:39], v83 offset:416
	ds_read_b128 v[40:43], v83 offset:448
	ds_read_b128 v[44:47], v83 offset:480
	v_and_b32_e32 v0, 64, v214
	v_add_u32_e32 v0, 64, v0
	v_xor_b32_e32 v1, 32, v214
	v_cmp_lt_i32_e32 vcc, v1, v0
	s_mov_b32 s14, 0
	v_lshl_add_u64 v[48:49], s[12:13], 0, v[48:49]
	v_cndmask_b32_e32 v0, v214, v1, vcc
	v_lshlrev_b32_e32 v85, 2, v0
	ds_bpermute_b32 v84, v85, v69
	ds_bpermute_b32 v82, v85, v68
	ds_bpermute_b32 v81, v85, v67
	ds_bpermute_b32 v80, v85, v66
	ds_bpermute_b32 v79, v85, v65
	ds_bpermute_b32 v78, v85, v64
	ds_bpermute_b32 v77, v85, v63
	ds_bpermute_b32 v76, v85, v62
	ds_bpermute_b32 v75, v85, v61
	ds_bpermute_b32 v74, v85, v60
	ds_bpermute_b32 v73, v85, v59
	ds_bpermute_b32 v72, v85, v58
	ds_bpermute_b32 v71, v85, v57
	ds_bpermute_b32 v70, v85, v56
	ds_bpermute_b32 v51, v85, v55
	ds_bpermute_b32 v50, v85, v54
	v_mov_b32_e32 v86, 0
	v_mov_b32_e32 v87, 0
	v_mov_b32_e32 v88, 0
	v_mov_b32_e32 v89, 0
	v_mov_b32_e32 v90, 0
	v_mov_b32_e32 v91, 0
	v_mov_b32_e32 v92, 0
	v_mov_b32_e32 v93, 0
	v_mov_b32_e32 v94, 0
	v_mov_b32_e32 v95, 0
	v_mov_b32_e32 v96, 0
	v_mov_b32_e32 v97, 0
	v_mov_b32_e32 v98, 0
	v_mov_b32_e32 v99, 0
	v_mov_b32_e32 v100, 0
	v_mov_b32_e32 v83, 0
.LBB0_2503:
	global_load_dwordx4 v[190:193], v[48:49], off offset:-128
	global_load_dwordx4 v[194:197], v[48:49], off offset:-96
	global_load_dwordx4 v[198:201], v[48:49], off offset:-64
	global_load_dwordx4 v[202:205], v[48:49], off offset:-32
	global_load_dwordx4 v[206:209], v[48:49], off
	global_load_dwordx4 v[216:219], v[48:49], off offset:32
	global_load_dwordx4 v[220:223], v[48:49], off offset:64
	global_load_dwordx4 v[224:227], v[48:49], off offset:96
	v_lshl_add_u64 v[48:49], v[48:49], 0, s[16:17]
	s_waitcnt vmcnt(7) lgkmcnt(14)
	v_mfma_f32_32x32x16_bf16 v[0:15], v[190:193], v[16:19], 0
	s_waitcnt vmcnt(6)
	v_mfma_f32_32x32x16_bf16 v[0:15], v[194:197], v[20:23], v[0:15]
	s_waitcnt vmcnt(5)
	v_mfma_f32_32x32x16_bf16 v[0:15], v[198:201], v[24:27], v[0:15]
	s_waitcnt vmcnt(4)
	v_mfma_f32_32x32x16_bf16 v[0:15], v[202:205], v[28:31], v[0:15]
	s_waitcnt vmcnt(3)
	v_mfma_f32_32x32x16_bf16 v[0:15], v[206:209], v[32:35], v[0:15]
	s_waitcnt vmcnt(2)
	v_mfma_f32_32x32x16_bf16 v[0:15], v[216:219], v[36:39], v[0:15]
	s_waitcnt vmcnt(1)
	v_mfma_f32_32x32x16_bf16 v[0:15], v[220:223], v[40:43], v[0:15]
	s_waitcnt vmcnt(0)
	v_mfma_f32_32x32x16_bf16 v[0:15], v[224:227], v[44:47], v[0:15]
	s_nop 11
	v_not_b32_e32 v101, v0
	v_or_b32_e32 v102, 0x80000000, v0
	v_cmp_gt_i32_e32 vcc, 0, v0
	v_or_b32_e32 v103, 0x80000000, v1
	s_nop 0
	v_cndmask_b32_e32 v0, v102, v101, vcc
	v_and_b32_e32 v101, 0xffffff80, v0
	v_add_u32_e32 v0, s14, v53
	v_add3_u32 v101, v0, v101, s52
	v_max_u32_e32 v102, v86, v101
	v_min_u32_e32 v86, v86, v101
	v_max_u32_e32 v101, v87, v86
	v_min_u32_e32 v86, v87, v86
	v_max_u32_e32 v87, v88, v86
	v_min_u32_e32 v86, v88, v86
	v_max_u32_e32 v88, v89, v86
	v_min_u32_e32 v86, v89, v86
	v_max_u32_e32 v89, v90, v86
	v_min_u32_e32 v86, v90, v86
	v_max_u32_e32 v90, v91, v86
	v_min_u32_e32 v86, v91, v86
	v_max_u32_e32 v91, v92, v86
	v_min_u32_e32 v86, v92, v86
	v_max_u32_e32 v92, v93, v86
	v_min_u32_e32 v86, v93, v86
	v_max_u32_e32 v93, v94, v86
	v_min_u32_e32 v86, v94, v86
	v_max_u32_e32 v94, v95, v86
	v_min_u32_e32 v86, v95, v86
	v_max_u32_e32 v95, v96, v86
	v_min_u32_e32 v86, v96, v86
	v_max_u32_e32 v96, v97, v86
	v_min_u32_e32 v86, v97, v86
	v_max_u32_e32 v97, v98, v86
	v_min_u32_e32 v86, v98, v86
	v_max_u32_e32 v98, v99, v86
	v_min_u32_e32 v86, v99, v86
	v_max_u32_e32 v99, v100, v86
	v_min_u32_e32 v86, v100, v86
	v_not_b32_e32 v100, v1
	v_cmp_gt_i32_e32 vcc, 0, v1
	s_sub_i32 s14, s14, 32
	s_cmpk_lg_i32 s14, 0xff80
	v_cndmask_b32_e32 v1, v103, v100, vcc
	v_and_b32_e32 v1, 0xffffff80, v1
	v_add3_u32 v1, v0, v1, s53
	v_max_u32_e32 v100, v102, v1
	v_min_u32_e32 v1, v102, v1
	v_max_u32_e32 v102, v101, v1
	v_min_u32_e32 v1, v101, v1
	v_max_u32_e32 v101, v87, v1
	v_min_u32_e32 v1, v87, v1
	v_max_u32_e32 v87, v88, v1
	v_min_u32_e32 v1, v88, v1
	v_max_u32_e32 v88, v89, v1
	v_min_u32_e32 v1, v89, v1
	v_max_u32_e32 v89, v90, v1
	v_min_u32_e32 v1, v90, v1
	v_max_u32_e32 v90, v91, v1
	v_min_u32_e32 v1, v91, v1
	v_max_u32_e32 v91, v92, v1
	v_min_u32_e32 v1, v92, v1
	v_max_u32_e32 v92, v93, v1
	v_min_u32_e32 v1, v93, v1
	v_max_u32_e32 v93, v94, v1
	v_min_u32_e32 v1, v94, v1
	v_max_u32_e32 v94, v95, v1
	v_min_u32_e32 v1, v95, v1
	v_max_u32_e32 v95, v96, v1
	v_min_u32_e32 v1, v96, v1
	v_max_u32_e32 v96, v97, v1
	v_min_u32_e32 v1, v97, v1
	v_max_u32_e32 v97, v98, v1
	v_min_u32_e32 v1, v98, v1
	v_max_u32_e32 v98, v99, v1
	v_min_u32_e32 v1, v99, v1
	v_max3_u32 v1, v83, v86, v1
	v_not_b32_e32 v83, v2
	v_or_b32_e32 v86, 0x80000000, v2
	v_cmp_gt_i32_e32 vcc, 0, v2
	s_nop 1
	v_cndmask_b32_e32 v2, v86, v83, vcc
	v_and_b32_e32 v2, 0xffffff80, v2
	v_add3_u32 v2, v0, v2, s54
	v_max_u32_e32 v83, v100, v2
	v_min_u32_e32 v2, v100, v2
	v_max_u32_e32 v86, v102, v2
	v_min_u32_e32 v2, v102, v2
	v_max_u32_e32 v99, v101, v2
	v_min_u32_e32 v2, v101, v2
	v_max_u32_e32 v100, v87, v2
	v_min_u32_e32 v2, v87, v2
	v_max_u32_e32 v87, v88, v2
	v_min_u32_e32 v2, v88, v2
	v_max_u32_e32 v88, v89, v2
	v_min_u32_e32 v2, v89, v2
	v_max_u32_e32 v89, v90, v2
	v_min_u32_e32 v2, v90, v2
	v_max_u32_e32 v90, v91, v2
	v_min_u32_e32 v2, v91, v2
	v_max_u32_e32 v91, v92, v2
	v_min_u32_e32 v2, v92, v2
	v_max_u32_e32 v92, v93, v2
	v_min_u32_e32 v2, v93, v2
	v_max_u32_e32 v93, v94, v2
	v_min_u32_e32 v2, v94, v2
; DI int crow(int i, int h) { return (i & 3) + 8 * (i >> 2) + 4 * h; }
; DI unsigned f2ord(float f) { unsigned u = __float_as_uint(f); return (u & 0x80000000u) ? ~u : (u | 0x80000000u); }
; #define INS32(T, X) { _Pragma("unroll") for (int jj = 0; jj < 16; ++jj) { unsigned t_ = max(T[jj], X); X = min(T[jj], X); T[jj] = t_; } }
; __device__ __forceinline__ void route_task(const Params& p, int layer, const u16* qg, int rb, int hd, int r, int h) {
;     ...
; #pragma unroll
;       for (int e = 0; e < 16; ++e) {
;         unsigned key = (f2ord(acc[e]) & ~127u) | (unsigned)(127 - (n * 32 + crow(e, h)));
;         INS32(tp, key);
;       }
	v_max_u32_e32 v94, v95, v2
	v_min_u32_e32 v2, v95, v2
	v_max_u32_e32 v95, v96, v2
	v_min_u32_e32 v2, v96, v2
	v_max_u32_e32 v96, v97, v2
	v_min_u32_e32 v2, v97, v2
	v_max_u32_e32 v97, v98, v2
	v_min_u32_e32 v2, v98, v2
	v_not_b32_e32 v98, v3
	v_or_b32_e32 v101, 0x80000000, v3
	v_cmp_gt_i32_e32 vcc, 0, v3
	s_nop 1
	v_cndmask_b32_e32 v3, v101, v98, vcc
	v_and_b32_e32 v3, 0xffffff80, v3
	v_add3_u32 v3, v0, v3, s55
	v_max_u32_e32 v98, v83, v3
	v_min_u32_e32 v3, v83, v3
	v_max_u32_e32 v83, v86, v3
	v_min_u32_e32 v3, v86, v3
	v_max_u32_e32 v86, v99, v3
	v_min_u32_e32 v3, v99, v3
	v_max_u32_e32 v99, v100, v3
	v_min_u32_e32 v3, v100, v3
	v_max_u32_e32 v100, v87, v3
	v_min_u32_e32 v3, v87, v3
	v_max_u32_e32 v87, v88, v3
	v_min_u32_e32 v3, v88, v3
	v_max_u32_e32 v88, v89, v3
	v_min_u32_e32 v3, v89, v3
	v_max_u32_e32 v89, v90, v3
	v_min_u32_e32 v3, v90, v3
	v_max_u32_e32 v90, v91, v3
	v_min_u32_e32 v3, v91, v3
	v_max_u32_e32 v91, v92, v3
	v_min_u32_e32 v3, v92, v3
	v_max_u32_e32 v92, v93, v3
	v_min_u32_e32 v3, v93, v3
	v_max_u32_e32 v93, v94, v3
	v_min_u32_e32 v3, v94, v3
	v_max_u32_e32 v94, v95, v3
	v_min_u32_e32 v3, v95, v3
	v_max_u32_e32 v95, v96, v3
	v_min_u32_e32 v3, v96, v3
	v_max_u32_e32 v96, v97, v3
	v_min_u32_e32 v3, v97, v3
	v_max3_u32 v1, v1, v2, v3
	v_not_b32_e32 v2, v4
	v_or_b32_e32 v3, 0x80000000, v4
	v_cmp_gt_i32_e32 vcc, 0, v4
	s_nop 1
	v_cndmask_b32_e32 v2, v3, v2, vcc
	v_and_b32_e32 v2, 0xffffff80, v2
	v_add3_u32 v2, v0, v2, s56
	v_max_u32_e32 v3, v98, v2
	v_min_u32_e32 v2, v98, v2
	v_max_u32_e32 v4, v83, v2
	v_min_u32_e32 v2, v83, v2
	v_max_u32_e32 v83, v86, v2
	v_min_u32_e32 v2, v86, v2
	v_max_u32_e32 v86, v99, v2
	v_min_u32_e32 v2, v99, v2
	v_max_u32_e32 v97, v100, v2
	v_min_u32_e32 v2, v100, v2
	v_max_u32_e32 v98, v87, v2
	v_min_u32_e32 v2, v87, v2
	v_max_u32_e32 v87, v88, v2
	v_min_u32_e32 v2, v88, v2
	v_max_u32_e32 v88, v89, v2
	v_min_u32_e32 v2, v89, v2
	v_max_u32_e32 v89, v90, v2
	v_min_u32_e32 v2, v90, v2
	v_max_u32_e32 v90, v91, v2
	v_min_u32_e32 v2, v91, v2
	v_max_u32_e32 v91, v92, v2
	v_min_u32_e32 v2, v92, v2
	v_max_u32_e32 v92, v93, v2
	v_min_u32_e32 v2, v93, v2
	v_max_u32_e32 v93, v94, v2
	v_min_u32_e32 v2, v94, v2
	v_max_u32_e32 v94, v95, v2
	v_min_u32_e32 v2, v95, v2
	v_max_u32_e32 v95, v96, v2
	v_min_u32_e32 v2, v96, v2
	v_not_b32_e32 v96, v5
	v_or_b32_e32 v99, 0x80000000, v5
	v_cmp_gt_i32_e32 vcc, 0, v5
	s_nop 1
	v_cndmask_b32_e32 v5, v99, v96, vcc
	v_and_b32_e32 v5, 0xffffff80, v5
	v_add3_u32 v5, v0, v5, s57
	v_max_u32_e32 v96, v3, v5
	v_min_u32_e32 v3, v3, v5
	v_max_u32_e32 v5, v4, v3
	v_min_u32_e32 v3, v4, v3
	v_max_u32_e32 v4, v83, v3
	v_min_u32_e32 v3, v83, v3
	v_max_u32_e32 v83, v86, v3
	v_min_u32_e32 v3, v86, v3
	v_max_u32_e32 v86, v97, v3
	v_min_u32_e32 v3, v97, v3
	v_max_u32_e32 v97, v98, v3
	v_min_u32_e32 v3, v98, v3
	v_max_u32_e32 v98, v87, v3
	v_min_u32_e32 v3, v87, v3
	v_max_u32_e32 v87, v88, v3
	v_min_u32_e32 v3, v88, v3
	v_max_u32_e32 v88, v89, v3
	v_min_u32_e32 v3, v89, v3
	v_max_u32_e32 v89, v90, v3
	v_min_u32_e32 v3, v90, v3
	v_max_u32_e32 v90, v91, v3
	v_min_u32_e32 v3, v91, v3
	v_max_u32_e32 v91, v92, v3
	v_min_u32_e32 v3, v92, v3
	v_max_u32_e32 v92, v93, v3
	v_min_u32_e32 v3, v93, v3
	v_max_u32_e32 v93, v94, v3
	v_min_u32_e32 v3, v94, v3
	v_max_u32_e32 v94, v95, v3
	v_min_u32_e32 v3, v95, v3
	v_max3_u32 v1, v1, v2, v3
	v_not_b32_e32 v2, v6
	v_or_b32_e32 v3, 0x80000000, v6
	v_cmp_gt_i32_e32 vcc, 0, v6
	s_nop 1
	v_cndmask_b32_e32 v2, v3, v2, vcc
	v_and_b32_e32 v2, 0xffffff80, v2
	v_add3_u32 v2, v0, v2, s58
	v_max_u32_e32 v3, v96, v2
	v_min_u32_e32 v2, v96, v2
	v_max_u32_e32 v6, v5, v2
	v_min_u32_e32 v2, v5, v2
	v_max_u32_e32 v5, v4, v2
	v_min_u32_e32 v2, v4, v2
	v_max_u32_e32 v4, v83, v2
	v_min_u32_e32 v2, v83, v2
	v_max_u32_e32 v83, v86, v2
	v_min_u32_e32 v2, v86, v2
	v_max_u32_e32 v86, v97, v2
	v_min_u32_e32 v2, v97, v2
	v_max_u32_e32 v95, v98, v2
	v_min_u32_e32 v2, v98, v2
	v_max_u32_e32 v96, v87, v2
	v_min_u32_e32 v2, v87, v2
	v_max_u32_e32 v87, v88, v2
	v_min_u32_e32 v2, v88, v2
	v_max_u32_e32 v88, v89, v2
	v_min_u32_e32 v2, v89, v2
	v_max_u32_e32 v89, v90, v2
	v_min_u32_e32 v2, v90, v2
	v_max_u32_e32 v90, v91, v2
	v_min_u32_e32 v2, v91, v2
	v_max_u32_e32 v91, v92, v2
	v_min_u32_e32 v2, v92, v2
	v_max_u32_e32 v92, v93, v2
	v_min_u32_e32 v2, v93, v2
	v_max_u32_e32 v93, v94, v2
	v_min_u32_e32 v2, v94, v2
	v_not_b32_e32 v94, v7
	v_or_b32_e32 v97, 0x80000000, v7
	v_cmp_gt_i32_e32 vcc, 0, v7
	s_nop 1
	v_cndmask_b32_e32 v7, v97, v94, vcc
	v_and_b32_e32 v7, 0xffffff80, v7
	v_add3_u32 v7, v0, v7, s59
	v_max_u32_e32 v94, v3, v7
	v_min_u32_e32 v3, v3, v7
	v_max_u32_e32 v7, v6, v3
	v_min_u32_e32 v3, v6, v3
	v_max_u32_e32 v6, v5, v3
	v_min_u32_e32 v3, v5, v3
	v_max_u32_e32 v5, v4, v3
	v_min_u32_e32 v3, v4, v3
	v_max_u32_e32 v4, v83, v3
	v_min_u32_e32 v3, v83, v3
	v_max_u32_e32 v83, v86, v3
	v_min_u32_e32 v3, v86, v3
	v_max_u32_e32 v86, v95, v3
	v_min_u32_e32 v3, v95, v3
	v_max_u32_e32 v95, v96, v3
	v_min_u32_e32 v3, v96, v3
	v_max_u32_e32 v96, v87, v3
	v_min_u32_e32 v3, v87, v3
	v_max_u32_e32 v87, v88, v3
	v_min_u32_e32 v3, v88, v3
	v_max_u32_e32 v88, v89, v3
	v_min_u32_e32 v3, v89, v3
	v_max_u32_e32 v89, v90, v3
	v_min_u32_e32 v3, v90, v3
	v_max_u32_e32 v90, v91, v3
	v_min_u32_e32 v3, v91, v3
	v_max_u32_e32 v91, v92, v3
	v_min_u32_e32 v3, v92, v3
	v_max_u32_e32 v92, v93, v3
	v_min_u32_e32 v3, v93, v3
	v_max3_u32 v1, v1, v2, v3
	v_not_b32_e32 v2, v8
	v_or_b32_e32 v3, 0x80000000, v8
	v_cmp_gt_i32_e32 vcc, 0, v8
	s_nop 1
	v_cndmask_b32_e32 v2, v3, v2, vcc
	v_and_b32_e32 v2, 0xffffff80, v2
	v_add3_u32 v2, v0, v2, s60
	v_max_u32_e32 v3, v94, v2
	v_min_u32_e32 v2, v94, v2
	v_max_u32_e32 v8, v7, v2
; DI int crow(int i, int h) { return (i & 3) + 8 * (i >> 2) + 4 * h; }
; DI unsigned f2ord(float f) { unsigned u = __float_as_uint(f); return (u & 0x80000000u) ? ~u : (u | 0x80000000u); }
; #define INS32(T, X) { _Pragma("unroll") for (int jj = 0; jj < 16; ++jj) { unsigned t_ = max(T[jj], X); X = min(T[jj], X); T[jj] = t_; } }
; __device__ __forceinline__ void route_task(const Params& p, int layer, const u16* qg, int rb, int hd, int r, int h) {
;     ...
; #pragma unroll
;       for (int e = 0; e < 16; ++e) {
;         unsigned key = (f2ord(acc[e]) & ~127u) | (unsigned)(127 - (n * 32 + crow(e, h)));
;         INS32(tp, key);
;       }
	v_min_u32_e32 v2, v7, v2
	v_max_u32_e32 v7, v6, v2
	v_min_u32_e32 v2, v6, v2
	v_max_u32_e32 v6, v5, v2
	v_min_u32_e32 v2, v5, v2
	v_max_u32_e32 v5, v4, v2
	v_min_u32_e32 v2, v4, v2
	v_max_u32_e32 v4, v83, v2
	v_min_u32_e32 v2, v83, v2
	v_max_u32_e32 v83, v86, v2
	v_min_u32_e32 v2, v86, v2
	v_max_u32_e32 v86, v95, v2
	v_min_u32_e32 v2, v95, v2
	v_max_u32_e32 v93, v96, v2
	v_min_u32_e32 v2, v96, v2
	v_max_u32_e32 v94, v87, v2
	v_min_u32_e32 v2, v87, v2
	v_max_u32_e32 v87, v88, v2
	v_min_u32_e32 v2, v88, v2
	v_max_u32_e32 v88, v89, v2
	v_min_u32_e32 v2, v89, v2
	v_max_u32_e32 v89, v90, v2
	v_min_u32_e32 v2, v90, v2
	v_max_u32_e32 v90, v91, v2
	v_min_u32_e32 v2, v91, v2
	v_max_u32_e32 v91, v92, v2
	v_min_u32_e32 v2, v92, v2
	v_not_b32_e32 v92, v9
	v_or_b32_e32 v95, 0x80000000, v9
	v_cmp_gt_i32_e32 vcc, 0, v9
	s_nop 1
	v_cndmask_b32_e32 v9, v95, v92, vcc
	v_and_b32_e32 v9, 0xffffff80, v9
	v_add3_u32 v9, v0, v9, s61
	v_max_u32_e32 v92, v3, v9
	v_min_u32_e32 v3, v3, v9
	v_max_u32_e32 v9, v8, v3
	v_min_u32_e32 v3, v8, v3
	v_max_u32_e32 v8, v7, v3
	v_min_u32_e32 v3, v7, v3
	v_max_u32_e32 v7, v6, v3
	v_min_u32_e32 v3, v6, v3
	v_max_u32_e32 v6, v5, v3
	v_min_u32_e32 v3, v5, v3
	v_max_u32_e32 v5, v4, v3
	v_min_u32_e32 v3, v4, v3
	v_max_u32_e32 v4, v83, v3
	v_min_u32_e32 v3, v83, v3
	v_max_u32_e32 v83, v86, v3
	v_min_u32_e32 v3, v86, v3
	v_max_u32_e32 v86, v93, v3
	v_min_u32_e32 v3, v93, v3
	v_max_u32_e32 v93, v94, v3
	v_min_u32_e32 v3, v94, v3
	v_max_u32_e32 v94, v87, v3
	v_min_u32_e32 v3, v87, v3
	v_max_u32_e32 v87, v88, v3
	v_min_u32_e32 v3, v88, v3
	v_max_u32_e32 v88, v89, v3
	v_min_u32_e32 v3, v89, v3
	v_max_u32_e32 v89, v90, v3
	v_min_u32_e32 v3, v90, v3
	v_max_u32_e32 v90, v91, v3
	v_min_u32_e32 v3, v91, v3
	v_max3_u32 v1, v1, v2, v3
	v_not_b32_e32 v2, v10
	v_or_b32_e32 v3, 0x80000000, v10
	v_cmp_gt_i32_e32 vcc, 0, v10
	s_nop 1
	v_cndmask_b32_e32 v2, v3, v2, vcc
	v_and_b32_e32 v2, 0xffffff80, v2
	v_add3_u32 v2, v0, v2, s62
	v_max_u32_e32 v3, v92, v2
	v_min_u32_e32 v2, v92, v2
	v_max_u32_e32 v10, v9, v2
	v_min_u32_e32 v2, v9, v2
	v_max_u32_e32 v9, v8, v2
	v_min_u32_e32 v2, v8, v2
	v_max_u32_e32 v8, v7, v2
	v_min_u32_e32 v2, v7, v2
	v_max_u32_e32 v7, v6, v2
	v_min_u32_e32 v2, v6, v2
	v_max_u32_e32 v6, v5, v2
	v_min_u32_e32 v2, v5, v2
	v_max_u32_e32 v5, v4, v2
	v_min_u32_e32 v2, v4, v2
	v_max_u32_e32 v4, v83, v2
	v_min_u32_e32 v2, v83, v2
	v_max_u32_e32 v83, v86, v2
	v_min_u32_e32 v2, v86, v2
	v_max_u32_e32 v86, v93, v2
	v_min_u32_e32 v2, v93, v2
	v_max_u32_e32 v91, v94, v2
	v_min_u32_e32 v2, v94, v2
	v_max_u32_e32 v92, v87, v2
	v_min_u32_e32 v2, v87, v2
	v_max_u32_e32 v87, v88, v2
	v_min_u32_e32 v2, v88, v2
	v_max_u32_e32 v88, v89, v2
	v_min_u32_e32 v2, v89, v2
	v_max_u32_e32 v89, v90, v2
	v_min_u32_e32 v2, v90, v2
	v_not_b32_e32 v90, v11
	v_or_b32_e32 v93, 0x80000000, v11
	v_cmp_gt_i32_e32 vcc, 0, v11
	s_nop 1
	v_cndmask_b32_e32 v11, v93, v90, vcc
	v_and_b32_e32 v11, 0xffffff80, v11
	v_add3_u32 v11, v0, v11, s63
	v_max_u32_e32 v90, v3, v11
	v_min_u32_e32 v3, v3, v11
	v_max_u32_e32 v11, v10, v3
	v_min_u32_e32 v3, v10, v3
	v_max_u32_e32 v10, v9, v3
	v_min_u32_e32 v3, v9, v3
	v_max_u32_e32 v9, v8, v3
	v_min_u32_e32 v3, v8, v3
	v_max_u32_e32 v8, v7, v3
	v_min_u32_e32 v3, v7, v3
	v_max_u32_e32 v7, v6, v3
	v_min_u32_e32 v3, v6, v3
	v_max_u32_e32 v6, v5, v3
	v_min_u32_e32 v3, v5, v3
	v_max_u32_e32 v5, v4, v3
	v_min_u32_e32 v3, v4, v3
	v_max_u32_e32 v4, v83, v3
	v_min_u32_e32 v3, v83, v3
	v_max_u32_e32 v83, v86, v3
	v_min_u32_e32 v3, v86, v3
	v_max_u32_e32 v86, v91, v3
	v_min_u32_e32 v3, v91, v3
	v_max_u32_e32 v91, v92, v3
	v_min_u32_e32 v3, v92, v3
	v_max_u32_e32 v92, v87, v3
	v_min_u32_e32 v3, v87, v3
	v_max_u32_e32 v87, v88, v3
	v_min_u32_e32 v3, v88, v3
	v_max_u32_e32 v88, v89, v3
	v_min_u32_e32 v3, v89, v3
	v_max3_u32 v1, v1, v2, v3
	v_not_b32_e32 v2, v12
	v_or_b32_e32 v3, 0x80000000, v12
	v_cmp_gt_i32_e32 vcc, 0, v12
	s_nop 1
	v_cndmask_b32_e32 v2, v3, v2, vcc
	v_and_b32_e32 v2, 0xffffff80, v2
	v_add3_u32 v2, v0, v2, s64
	v_max_u32_e32 v3, v90, v2
	v_min_u32_e32 v2, v90, v2
	v_max_u32_e32 v12, v11, v2
	v_min_u32_e32 v2, v11, v2
	v_max_u32_e32 v11, v10, v2
	v_min_u32_e32 v2, v10, v2
	v_max_u32_e32 v10, v9, v2
	v_min_u32_e32 v2, v9, v2
	v_max_u32_e32 v9, v8, v2
	v_min_u32_e32 v2, v8, v2
	v_max_u32_e32 v8, v7, v2
	v_min_u32_e32 v2, v7, v2
	v_max_u32_e32 v7, v6, v2
	v_min_u32_e32 v2, v6, v2
	v_max_u32_e32 v6, v5, v2
	v_min_u32_e32 v2, v5, v2
	v_max_u32_e32 v5, v4, v2
	v_min_u32_e32 v2, v4, v2
	v_max_u32_e32 v4, v83, v2
	v_min_u32_e32 v2, v83, v2
	v_max_u32_e32 v83, v86, v2
	v_min_u32_e32 v2, v86, v2
	v_max_u32_e32 v86, v91, v2
	v_min_u32_e32 v2, v91, v2
	v_max_u32_e32 v89, v92, v2
	v_min_u32_e32 v2, v92, v2
	v_max_u32_e32 v90, v87, v2
	v_min_u32_e32 v2, v87, v2
	v_max_u32_e32 v87, v88, v2
	v_min_u32_e32 v2, v88, v2
	v_not_b32_e32 v88, v13
	v_or_b32_e32 v91, 0x80000000, v13
	v_cmp_gt_i32_e32 vcc, 0, v13
	s_nop 1
	v_cndmask_b32_e32 v13, v91, v88, vcc
	v_and_b32_e32 v13, 0xffffff80, v13
	v_add3_u32 v13, v0, v13, s65
	v_max_u32_e32 v88, v3, v13
	v_min_u32_e32 v3, v3, v13
	v_max_u32_e32 v13, v12, v3
	v_min_u32_e32 v3, v12, v3
	v_max_u32_e32 v12, v11, v3
	v_min_u32_e32 v3, v11, v3
	v_max_u32_e32 v11, v10, v3
	v_min_u32_e32 v3, v10, v3
	v_max_u32_e32 v10, v9, v3
	v_min_u32_e32 v3, v9, v3
	v_max_u32_e32 v9, v8, v3
	v_min_u32_e32 v3, v8, v3
	v_max_u32_e32 v8, v7, v3
	v_min_u32_e32 v3, v7, v3
	v_max_u32_e32 v7, v6, v3
	v_min_u32_e32 v3, v6, v3
	v_max_u32_e32 v6, v5, v3
	v_min_u32_e32 v3, v5, v3
	v_max_u32_e32 v5, v4, v3
	v_min_u32_e32 v3, v4, v3
	v_max_u32_e32 v4, v83, v3
	v_min_u32_e32 v3, v83, v3
	v_max_u32_e32 v83, v86, v3
	v_min_u32_e32 v3, v86, v3
; DI int crow(int i, int h) { return (i & 3) + 8 * (i >> 2) + 4 * h; }
; DI unsigned f2ord(float f) { unsigned u = __float_as_uint(f); return (u & 0x80000000u) ? ~u : (u | 0x80000000u); }
; #define INS32(T, X) { _Pragma("unroll") for (int jj = 0; jj < 16; ++jj) { unsigned t_ = max(T[jj], X); X = min(T[jj], X); T[jj] = t_; } }
; __device__ __forceinline__ void route_task(const Params& p, int layer, const u16* qg, int rb, int hd, int r, int h) {
;     ...
; #pragma unroll
;       for (int e = 0; e < 16; ++e) {
;         unsigned key = (f2ord(acc[e]) & ~127u) | (unsigned)(127 - (n * 32 + crow(e, h)));
;         INS32(tp, key);
;       }
;     }
;     unsigned ot[16];
; #pragma unroll
;     for (int jj = 0; jj < 16; ++jj) ot[jj] = (unsigned)__shfl_xor((int)tp[jj], 32);
; #pragma unroll
;     for (int jj = 0; jj < 16; ++jj) { unsigned key = ot[jj]; INS32(tp, key); }
	v_max_u32_e32 v86, v89, v3
	v_min_u32_e32 v3, v89, v3
	v_max_u32_e32 v89, v90, v3
	v_min_u32_e32 v3, v90, v3
	v_max_u32_e32 v90, v87, v3
	v_min_u32_e32 v3, v87, v3
	v_max3_u32 v1, v1, v2, v3
	v_not_b32_e32 v2, v14
	v_or_b32_e32 v3, 0x80000000, v14
	v_cmp_gt_i32_e32 vcc, 0, v14
	v_or_b32_e32 v87, 0x80000000, v15
	s_nop 0
	v_cndmask_b32_e32 v2, v3, v2, vcc
	v_and_b32_e32 v2, 0xffffff80, v2
	v_add3_u32 v2, v0, v2, s66
	v_max_u32_e32 v3, v88, v2
	v_min_u32_e32 v2, v88, v2
	v_max_u32_e32 v14, v13, v2
	v_min_u32_e32 v2, v13, v2
	v_max_u32_e32 v13, v12, v2
	v_min_u32_e32 v2, v12, v2
	v_max_u32_e32 v12, v11, v2
	v_min_u32_e32 v2, v11, v2
	v_max_u32_e32 v11, v10, v2
	v_min_u32_e32 v2, v10, v2
	v_max_u32_e32 v10, v9, v2
	v_min_u32_e32 v2, v9, v2
	v_max_u32_e32 v9, v8, v2
	v_min_u32_e32 v2, v8, v2
	v_max_u32_e32 v8, v7, v2
	v_min_u32_e32 v2, v7, v2
	v_max_u32_e32 v7, v6, v2
	v_min_u32_e32 v2, v6, v2
	v_max_u32_e32 v6, v5, v2
	v_min_u32_e32 v2, v5, v2
	v_max_u32_e32 v5, v4, v2
	v_min_u32_e32 v2, v4, v2
	v_max_u32_e32 v4, v83, v2
	v_min_u32_e32 v2, v83, v2
	v_max_u32_e32 v83, v86, v2
	v_min_u32_e32 v2, v86, v2
	v_not_b32_e32 v86, v15
	v_cmp_gt_i32_e32 vcc, 0, v15
	v_max_u32_e32 v100, v89, v2
	v_min_u32_e32 v2, v89, v2
	v_cndmask_b32_e32 v15, v87, v86, vcc
	v_and_b32_e32 v15, 0xffffff80, v15
	v_add3_u32 v0, v0, v15, s67
	v_max_u32_e32 v86, v3, v0
	v_min_u32_e32 v0, v3, v0
	v_max_u32_e32 v87, v14, v0
	v_min_u32_e32 v0, v14, v0
	v_max_u32_e32 v88, v13, v0
	v_min_u32_e32 v0, v13, v0
	v_max_u32_e32 v89, v12, v0
	v_min_u32_e32 v0, v12, v0
	v_max_u32_e32 v101, v90, v2
	v_min_u32_e32 v2, v90, v2
	v_max_u32_e32 v90, v11, v0
	v_min_u32_e32 v0, v11, v0
	v_max_u32_e32 v91, v10, v0
	v_min_u32_e32 v0, v10, v0
	v_max_u32_e32 v92, v9, v0
	v_min_u32_e32 v0, v9, v0
	v_max_u32_e32 v93, v8, v0
	v_min_u32_e32 v0, v8, v0
	v_max_u32_e32 v94, v7, v0
	v_min_u32_e32 v0, v7, v0
	v_max_u32_e32 v95, v6, v0
	v_min_u32_e32 v0, v6, v0
	v_max_u32_e32 v96, v5, v0
	v_min_u32_e32 v0, v5, v0
	v_max_u32_e32 v97, v4, v0
	v_min_u32_e32 v0, v4, v0
	v_max_u32_e32 v98, v83, v0
	v_min_u32_e32 v0, v83, v0
	v_max_u32_e32 v99, v100, v0
	v_min_u32_e32 v0, v100, v0
	v_max_u32_e32 v100, v101, v0
	v_min_u32_e32 v0, v101, v0
	v_max3_u32 v83, v1, v2, v0
	s_cbranch_scc1 .LBB0_2503
	ds_bpermute_b32 v17, v85, v86
	ds_bpermute_b32 v16, v85, v87
	ds_bpermute_b32 v13, v85, v88
	ds_bpermute_b32 v12, v85, v89
	ds_bpermute_b32 v11, v85, v90
	ds_bpermute_b32 v10, v85, v91
	ds_bpermute_b32 v9, v85, v92
	ds_bpermute_b32 v8, v85, v93
	ds_bpermute_b32 v7, v85, v94
	ds_bpermute_b32 v6, v85, v95
	ds_bpermute_b32 v5, v85, v96
	ds_bpermute_b32 v4, v85, v97
	ds_bpermute_b32 v3, v85, v98
	ds_bpermute_b32 v2, v85, v99
	ds_bpermute_b32 v1, v85, v100
	ds_bpermute_b32 v0, v85, v83
	v_cmp_eq_u32_e32 vcc, 0, v139
	s_and_saveexec_b64 s[18:19], vcc
	s_cbranch_execz .LBB0_2495
	v_max_u32_e32 v14, v69, v84
	v_min_u32_e32 v15, v69, v84
	v_max_u32_e32 v18, v68, v15
	v_min_u32_e32 v15, v68, v15
	v_max_u32_e32 v31, v14, v82
	v_min_u32_e32 v14, v14, v82
	v_max_u32_e32 v19, v67, v15
	v_min_u32_e32 v15, v67, v15
	v_max_u32_e32 v32, v18, v14
	v_min_u32_e32 v14, v18, v14
	v_max_u32_e32 v20, v66, v15
	v_min_u32_e32 v15, v66, v15
	v_max_u32_e32 v18, v19, v14
	v_min_u32_e32 v14, v19, v14
	v_max_u32_e32 v21, v65, v15
	v_min_u32_e32 v15, v65, v15
	v_max_u32_e32 v19, v20, v14
	v_min_u32_e32 v14, v20, v14
	v_max_u32_e32 v22, v64, v15
	v_min_u32_e32 v15, v64, v15
	v_max_u32_e32 v20, v21, v14
	v_min_u32_e32 v14, v21, v14
	v_max_u32_e32 v23, v63, v15
	v_min_u32_e32 v15, v63, v15
	v_max_u32_e32 v21, v22, v14
	v_min_u32_e32 v14, v22, v14
	v_max_u32_e32 v24, v62, v15
	v_min_u32_e32 v15, v62, v15
	v_max_u32_e32 v22, v23, v14
	v_min_u32_e32 v14, v23, v14
	v_max_u32_e32 v25, v61, v15
	v_min_u32_e32 v15, v61, v15
	v_max_u32_e32 v23, v24, v14
	v_min_u32_e32 v14, v24, v14
	v_max_u32_e32 v26, v60, v15
	v_min_u32_e32 v15, v60, v15
	v_max_u32_e32 v24, v25, v14
	v_min_u32_e32 v14, v25, v14
	v_max_u32_e32 v27, v59, v15
	v_min_u32_e32 v15, v59, v15
	v_max_u32_e32 v25, v26, v14
	v_min_u32_e32 v14, v26, v14
	v_max_u32_e32 v28, v58, v15
	v_min_u32_e32 v15, v58, v15
	v_max_u32_e32 v26, v27, v14
	v_min_u32_e32 v14, v27, v14
	v_max_u32_e32 v29, v57, v15
	v_min_u32_e32 v15, v57, v15
	v_max_u32_e32 v27, v28, v14
	v_min_u32_e32 v14, v28, v14
	v_max_u32_e32 v30, v56, v15
	v_max_u32_e32 v28, v29, v14
	v_min_u32_e32 v14, v29, v14
	v_max_u32_e32 v29, v30, v14
	v_min_u32_e32 v30, v30, v14
	s_waitcnt lgkmcnt(14)
; #define INS32(T, X) { _Pragma("unroll") for (int jj = 0; jj < 16; ++jj) { unsigned t_ = max(T[jj], X); X = min(T[jj], X); T[jj] = t_; } }
; __device__ __forceinline__ void route_task(const Params& p, int layer, const u16* qg, int rb, int hd, int r, int h) {
;     ...
;     for (int jj = 0; jj < 16; ++jj) ot[jj] = (unsigned)__shfl_xor((int)tp[jj], 32);
; #pragma unroll
;     for (int jj = 0; jj < 16; ++jj) { unsigned key = ot[jj]; INS32(tp, key); }
	v_max_u32_e32 v14, v31, v81
	v_min_u32_e32 v31, v31, v81
	v_max_u32_e32 v33, v32, v31
	v_min_u32_e32 v31, v32, v31
	v_max_u32_e32 v32, v18, v31
	v_min_u32_e32 v18, v18, v31
	v_max_u32_e32 v31, v19, v18
	v_min_u32_e32 v18, v19, v18
	v_max_u32_e32 v19, v20, v18
	v_min_u32_e32 v18, v20, v18
	v_max_u32_e32 v20, v21, v18
	v_min_u32_e32 v18, v21, v18
	v_max_u32_e32 v21, v22, v18
	v_min_u32_e32 v18, v22, v18
	v_max_u32_e32 v22, v23, v18
	v_min_u32_e32 v18, v23, v18
	v_max_u32_e32 v23, v24, v18
	v_min_u32_e32 v18, v24, v18
	v_max_u32_e32 v24, v25, v18
	v_min_u32_e32 v18, v25, v18
	v_max_u32_e32 v25, v26, v18
	v_min_u32_e32 v18, v26, v18
	v_max_u32_e32 v26, v27, v18
	v_min_u32_e32 v18, v27, v18
	v_max_u32_e32 v27, v28, v18
	v_min_u32_e32 v18, v28, v18
	v_max_u32_e32 v28, v29, v18
	v_min_u32_e32 v18, v29, v18
	v_max_u32_e32 v29, v14, v80
	v_min_u32_e32 v14, v14, v80
	v_max_u32_e32 v34, v33, v14
	v_min_u32_e32 v14, v33, v14
	v_max_u32_e32 v33, v32, v14
	v_min_u32_e32 v14, v32, v14
	v_max_u32_e32 v32, v31, v14
	v_min_u32_e32 v14, v31, v14
	v_max_u32_e32 v31, v19, v14
	v_min_u32_e32 v14, v19, v14
	v_max_u32_e32 v19, v20, v14
	v_min_u32_e32 v14, v20, v14
	v_max_u32_e32 v20, v21, v14
	v_min_u32_e32 v14, v21, v14
	v_max_u32_e32 v21, v22, v14
	v_min_u32_e32 v14, v22, v14
	v_max_u32_e32 v22, v23, v14
	v_min_u32_e32 v14, v23, v14
	v_max_u32_e32 v23, v24, v14
	v_min_u32_e32 v14, v24, v14
	v_max_u32_e32 v24, v25, v14
	v_min_u32_e32 v14, v25, v14
	v_max_u32_e32 v25, v26, v14
	v_min_u32_e32 v14, v26, v14
	v_max_u32_e32 v26, v27, v14
	v_min_u32_e32 v14, v27, v14
	v_max_u32_e32 v27, v28, v14
	v_min_u32_e32 v28, v28, v14
	v_max_u32_e32 v14, v29, v79
	v_min_u32_e32 v29, v29, v79
	v_max_u32_e32 v35, v34, v29
	v_min_u32_e32 v29, v34, v29
	v_max_u32_e32 v34, v33, v29
	v_min_u32_e32 v29, v33, v29
	v_max_u32_e32 v33, v32, v29
	v_min_u32_e32 v29, v32, v29
	v_max_u32_e32 v32, v31, v29
	v_min_u32_e32 v29, v31, v29
	v_max_u32_e32 v31, v19, v29
	v_min_u32_e32 v19, v19, v29
	v_max_u32_e32 v29, v20, v19
	v_min_u32_e32 v19, v20, v19
	v_max_u32_e32 v20, v21, v19
	v_min_u32_e32 v19, v21, v19
	v_max_u32_e32 v21, v22, v19
	v_min_u32_e32 v19, v22, v19
	v_max_u32_e32 v22, v23, v19
	v_min_u32_e32 v19, v23, v19
	v_max_u32_e32 v23, v24, v19
	v_min_u32_e32 v19, v24, v19
	v_max_u32_e32 v24, v25, v19
	v_min_u32_e32 v19, v25, v19
	v_max_u32_e32 v25, v26, v19
	v_min_u32_e32 v19, v26, v19
	v_max_u32_e32 v26, v27, v19
	v_min_u32_e32 v19, v27, v19
	v_max_u32_e32 v27, v14, v78
	v_min_u32_e32 v14, v14, v78
	v_max_u32_e32 v36, v35, v14
	v_min_u32_e32 v14, v35, v14
	v_max_u32_e32 v35, v34, v14
	v_min_u32_e32 v14, v34, v14
	v_max_u32_e32 v34, v33, v14
	v_min_u32_e32 v14, v33, v14
	v_max_u32_e32 v33, v32, v14
	v_min_u32_e32 v14, v32, v14
	v_max_u32_e32 v32, v31, v14
	v_min_u32_e32 v14, v31, v14
	v_max_u32_e32 v31, v29, v14
	v_min_u32_e32 v14, v29, v14
	v_max_u32_e32 v29, v20, v14
	v_min_u32_e32 v14, v20, v14
	v_max_u32_e32 v20, v21, v14
	v_min_u32_e32 v14, v21, v14
	v_max_u32_e32 v21, v22, v14
	v_min_u32_e32 v14, v22, v14
	v_max_u32_e32 v22, v23, v14
	v_min_u32_e32 v14, v23, v14
	v_max_u32_e32 v23, v24, v14
	v_min_u32_e32 v14, v24, v14
	v_max_u32_e32 v24, v25, v14
	v_min_u32_e32 v14, v25, v14
	v_max_u32_e32 v25, v26, v14
	v_min_u32_e32 v26, v26, v14
	v_max_u32_e32 v14, v27, v77
	v_min_u32_e32 v27, v27, v77
	v_max_u32_e32 v37, v36, v27
	v_min_u32_e32 v27, v36, v27
	v_max_u32_e32 v36, v35, v27
	v_min_u32_e32 v27, v35, v27
	v_max_u32_e32 v35, v34, v27
	v_min_u32_e32 v27, v34, v27
	v_max_u32_e32 v34, v33, v27
	v_min_u32_e32 v27, v33, v27
	v_max_u32_e32 v33, v32, v27
	v_min_u32_e32 v27, v32, v27
	v_max_u32_e32 v32, v31, v27
	v_min_u32_e32 v27, v31, v27
	v_max_u32_e32 v31, v29, v27
	v_min_u32_e32 v27, v29, v27
	v_max_u32_e32 v29, v20, v27
	v_min_u32_e32 v20, v20, v27
	v_max_u32_e32 v27, v21, v20
	v_min_u32_e32 v20, v21, v20
	v_max_u32_e32 v21, v22, v20
	v_min_u32_e32 v20, v22, v20
	v_max_u32_e32 v22, v23, v20
	v_min_u32_e32 v20, v23, v20
	v_max_u32_e32 v23, v24, v20
	v_min_u32_e32 v20, v24, v20
	v_max_u32_e32 v24, v25, v20
	v_min_u32_e32 v20, v25, v20
	v_max_u32_e32 v25, v14, v76
	v_min_u32_e32 v14, v14, v76
	v_max_u32_e32 v38, v37, v14
	v_min_u32_e32 v14, v37, v14
	v_max_u32_e32 v37, v36, v14
	v_min_u32_e32 v14, v36, v14
	v_max_u32_e32 v36, v35, v14
	v_min_u32_e32 v14, v35, v14
	v_max_u32_e32 v35, v34, v14
	v_min_u32_e32 v14, v34, v14
	v_max_u32_e32 v34, v33, v14
	v_min_u32_e32 v14, v33, v14
	v_max_u32_e32 v33, v32, v14
	v_min_u32_e32 v14, v32, v14
	v_max_u32_e32 v32, v31, v14
	v_min_u32_e32 v14, v31, v14
	v_max_u32_e32 v31, v29, v14
	v_min_u32_e32 v14, v29, v14
	v_max_u32_e32 v29, v27, v14
	v_min_u32_e32 v14, v27, v14
	v_max_u32_e32 v27, v21, v14
	v_min_u32_e32 v14, v21, v14
	v_max_u32_e32 v21, v22, v14
	v_min_u32_e32 v14, v22, v14
	v_max_u32_e32 v22, v23, v14
	v_min_u32_e32 v14, v23, v14
	v_max_u32_e32 v23, v24, v14
	v_min_u32_e32 v24, v24, v14
	v_max_u32_e32 v14, v25, v75
	v_min_u32_e32 v25, v25, v75
	v_max_u32_e32 v39, v38, v25
	v_min_u32_e32 v25, v38, v25
	v_max_u32_e32 v38, v37, v25
	v_min_u32_e32 v25, v37, v25
	v_max_u32_e32 v37, v36, v25
	v_min_u32_e32 v25, v36, v25
	v_max_u32_e32 v36, v35, v25
	v_min_u32_e32 v25, v35, v25
	v_max_u32_e32 v35, v34, v25
	v_min_u32_e32 v25, v34, v25
	v_max_u32_e32 v34, v33, v25
	v_min_u32_e32 v25, v33, v25
	v_max_u32_e32 v33, v32, v25
	v_min_u32_e32 v25, v32, v25
	v_max_u32_e32 v32, v31, v25
	v_min_u32_e32 v25, v31, v25
	v_max_u32_e32 v31, v29, v25
	v_min_u32_e32 v25, v29, v25
	v_max_u32_e32 v29, v27, v25
	v_min_u32_e32 v25, v27, v25
	v_max_u32_e32 v27, v21, v25
	v_min_u32_e32 v21, v21, v25
	v_max_u32_e32 v25, v22, v21
	v_min_u32_e32 v21, v22, v21
; #define INS32(T, X) { _Pragma("unroll") for (int jj = 0; jj < 16; ++jj) { unsigned t_ = max(T[jj], X); X = min(T[jj], X); T[jj] = t_; } }
; __device__ __forceinline__ void route_task(const Params& p, int layer, const u16* qg, int rb, int hd, int r, int h) {
;     ...
;     for (int jj = 0; jj < 16; ++jj) ot[jj] = (unsigned)__shfl_xor((int)tp[jj], 32);
; #pragma unroll
;     for (int jj = 0; jj < 16; ++jj) { unsigned key = ot[jj]; INS32(tp, key); }
	v_max_u32_e32 v22, v23, v21
	v_min_u32_e32 v21, v23, v21
	v_max_u32_e32 v23, v14, v74
	v_min_u32_e32 v14, v14, v74
	v_max_u32_e32 v40, v39, v14
	v_min_u32_e32 v14, v39, v14
	v_max_u32_e32 v39, v38, v14
	v_min_u32_e32 v14, v38, v14
	v_max_u32_e32 v38, v37, v14
	v_min_u32_e32 v14, v37, v14
	v_max_u32_e32 v37, v36, v14
	v_min_u32_e32 v14, v36, v14
	v_max_u32_e32 v36, v35, v14
	v_min_u32_e32 v14, v35, v14
	v_max_u32_e32 v35, v34, v14
	v_min_u32_e32 v14, v34, v14
	v_max_u32_e32 v34, v33, v14
	v_min_u32_e32 v14, v33, v14
	v_max_u32_e32 v33, v32, v14
	v_min_u32_e32 v14, v32, v14
	v_max_u32_e32 v32, v31, v14
	v_min_u32_e32 v14, v31, v14
	v_max_u32_e32 v31, v29, v14
	v_min_u32_e32 v14, v29, v14
	v_max_u32_e32 v29, v27, v14
	v_min_u32_e32 v14, v27, v14
	v_max_u32_e32 v27, v25, v14
	v_min_u32_e32 v14, v25, v14
	v_max_u32_e32 v25, v22, v14
	v_min_u32_e32 v22, v22, v14
	v_max_u32_e32 v14, v23, v73
	v_min_u32_e32 v23, v23, v73
	v_max_u32_e32 v41, v40, v23
	v_min_u32_e32 v23, v40, v23
	v_max_u32_e32 v40, v39, v23
	v_min_u32_e32 v23, v39, v23
	v_max_u32_e32 v39, v38, v23
	v_min_u32_e32 v23, v38, v23
	v_max_u32_e32 v38, v37, v23
	v_min_u32_e32 v23, v37, v23
	v_max_u32_e32 v37, v36, v23
	v_min_u32_e32 v23, v36, v23
	v_max_u32_e32 v36, v35, v23
	v_min_u32_e32 v23, v35, v23
	v_max_u32_e32 v35, v34, v23
	v_min_u32_e32 v23, v34, v23
	v_max_u32_e32 v34, v33, v23
	v_min_u32_e32 v23, v33, v23
	v_max_u32_e32 v33, v32, v23
	v_min_u32_e32 v23, v32, v23
	v_max_u32_e32 v32, v31, v23
	v_min_u32_e32 v23, v31, v23
	v_max_u32_e32 v31, v29, v23
	v_min_u32_e32 v23, v29, v23
	v_max_u32_e32 v29, v27, v23
	v_min_u32_e32 v23, v27, v23
	v_max_u32_e32 v27, v25, v23
	v_min_u32_e32 v23, v25, v23
	v_max_u32_e32 v25, v14, v72
	v_min_u32_e32 v14, v14, v72
	v_max_u32_e32 v42, v41, v14
	v_min_u32_e32 v14, v41, v14
	v_max_u32_e32 v41, v40, v14
	v_min_u32_e32 v14, v40, v14
	v_max_u32_e32 v40, v39, v14
	v_min_u32_e32 v14, v39, v14
	v_max_u32_e32 v39, v38, v14
	v_min_u32_e32 v14, v38, v14
	v_max_u32_e32 v38, v37, v14
	v_min_u32_e32 v14, v37, v14
	v_max_u32_e32 v37, v36, v14
	v_min_u32_e32 v14, v36, v14
	v_max_u32_e32 v36, v35, v14
	v_min_u32_e32 v14, v35, v14
	v_max_u32_e32 v35, v34, v14
	v_min_u32_e32 v14, v34, v14
	v_max_u32_e32 v34, v33, v14
	v_min_u32_e32 v14, v33, v14
	v_max_u32_e32 v33, v32, v14
	v_min_u32_e32 v14, v32, v14
	v_max_u32_e32 v32, v31, v14
	v_min_u32_e32 v14, v31, v14
	v_max_u32_e32 v31, v29, v14
	v_min_u32_e32 v14, v29, v14
	v_max_u32_e32 v29, v27, v14
	v_min_u32_e32 v27, v27, v14
	v_max_u32_e32 v14, v25, v71
	v_min_u32_e32 v25, v25, v71
	v_max_u32_e32 v43, v42, v25
	v_min_u32_e32 v25, v42, v25
	v_max_u32_e32 v42, v41, v25
	v_min_u32_e32 v25, v41, v25
	v_max_u32_e32 v41, v40, v25
	v_min_u32_e32 v25, v40, v25
	v_max_u32_e32 v40, v39, v25
	v_min_u32_e32 v25, v39, v25
	v_max_u32_e32 v39, v38, v25
	v_min_u32_e32 v25, v38, v25
	v_max_u32_e32 v38, v37, v25
	v_min_u32_e32 v25, v37, v25
	v_max_u32_e32 v37, v36, v25
	v_min_u32_e32 v25, v36, v25
	v_max_u32_e32 v36, v35, v25
	v_min_u32_e32 v25, v35, v25
	v_max_u32_e32 v35, v34, v25
	v_min_u32_e32 v25, v34, v25
	v_max_u32_e32 v34, v33, v25
	v_min_u32_e32 v25, v33, v25
	v_max_u32_e32 v33, v32, v25
	v_min_u32_e32 v25, v32, v25
	v_max_u32_e32 v32, v31, v25
	v_min_u32_e32 v25, v31, v25
	v_max_u32_e32 v31, v29, v25
	v_min_u32_e32 v25, v29, v25
	v_max_u32_e32 v29, v14, v70
	v_min_u32_e32 v14, v14, v70
	v_max_u32_e32 v44, v43, v14
	v_min_u32_e32 v14, v43, v14
	v_max_u32_e32 v43, v42, v14
	v_min_u32_e32 v14, v42, v14
	v_max_u32_e32 v42, v41, v14
	v_min_u32_e32 v14, v41, v14
	v_max_u32_e32 v41, v40, v14
	v_min_u32_e32 v14, v40, v14
	v_max_u32_e32 v40, v39, v14
	v_min_u32_e32 v14, v39, v14
	v_max_u32_e32 v39, v38, v14
	v_min_u32_e32 v14, v38, v14
	v_max_u32_e32 v38, v37, v14
	v_min_u32_e32 v14, v37, v14
	v_max_u32_e32 v37, v36, v14
	v_min_u32_e32 v14, v36, v14
	v_max_u32_e32 v36, v35, v14
	v_min_u32_e32 v14, v35, v14
	v_max_u32_e32 v35, v34, v14
	v_min_u32_e32 v14, v34, v14
	v_max_u32_e32 v34, v33, v14
	v_min_u32_e32 v14, v33, v14
	v_min_u32_e32 v15, v56, v15
	v_max_u32_e32 v33, v32, v14
	v_min_u32_e32 v14, v32, v14
	v_max_u32_e32 v32, v31, v14
	v_min_u32_e32 v31, v31, v14
	v_max_u32_e32 v14, v29, v51
	v_min_u32_e32 v29, v29, v51
	v_max_u32_e32 v63, v55, v15
	v_max_u32_e32 v46, v44, v29
	v_min_u32_e32 v29, v44, v29
	v_min_u32_e32 v47, v14, v50
	v_max_u32_e32 v64, v63, v30
	v_max_u32_e32 v45, v43, v29
	v_min_u32_e32 v29, v43, v29
	v_min_u32_e32 v48, v46, v47
	v_max_u32_e32 v65, v64, v18
	v_max_u32_e32 v44, v42, v29
	v_min_u32_e32 v29, v42, v29
	v_min_u32_e32 v49, v45, v48
	v_max_u32_e32 v66, v65, v28
	v_max_u32_e32 v43, v41, v29
	v_min_u32_e32 v29, v41, v29
	v_min_u32_e32 v51, v44, v49
	v_max_u32_e32 v67, v66, v19
	v_max_u32_e32 v42, v40, v29
	v_min_u32_e32 v29, v40, v29
	v_min_u32_e32 v53, v43, v51
	v_max_u32_e32 v68, v67, v26
	v_max_u32_e32 v41, v39, v29
	v_min_u32_e32 v29, v39, v29
	v_min_u32_e32 v56, v42, v53
	v_max_u32_e32 v69, v68, v20
	v_max_u32_e32 v40, v38, v29
	v_min_u32_e32 v29, v38, v29
	v_min_u32_e32 v57, v41, v56
	v_max_u32_e32 v70, v69, v24
	v_max_u32_e32 v39, v37, v29
	v_min_u32_e32 v29, v37, v29
	v_min_u32_e32 v58, v40, v57
	v_max_u32_e32 v71, v70, v21
	v_min_u32_e32 v30, v63, v30
	v_min_u32_e32 v15, v55, v15
	v_max_u32_e32 v38, v36, v29
	v_min_u32_e32 v29, v36, v29
	v_min_u32_e32 v59, v39, v58
	v_max_u32_e32 v72, v71, v22
	v_min_u32_e32 v28, v65, v28
	v_min_u32_e32 v18, v64, v18
	v_max3_u32 v15, v54, v15, v30
	v_max_u32_e32 v37, v35, v29
	v_min_u32_e32 v29, v35, v29
	v_min_u32_e32 v60, v38, v59
	v_max_u32_e32 v73, v72, v23
	v_min_u32_e32 v26, v67, v26
	v_min_u32_e32 v19, v66, v19
	v_max3_u32 v15, v15, v18, v28
	v_max_u32_e32 v36, v34, v29
	v_min_u32_e32 v29, v34, v29
	v_min_u32_e32 v61, v37, v60
	v_max_u32_e32 v74, v73, v27
	v_min_u32_e32 v24, v69, v24
	v_min_u32_e32 v20, v68, v20
	v_max3_u32 v15, v15, v19, v26
	v_max_u32_e32 v35, v33, v29
	v_min_u32_e32 v29, v33, v29
	v_min_u32_e32 v62, v36, v61
	v_max_u32_e32 v75, v74, v25
	v_min_u32_e32 v22, v71, v22
	v_min_u32_e32 v21, v70, v21
	v_max3_u32 v15, v15, v20, v24
	v_min_u32_e32 v18, v86, v17
	v_max_u32_e32 v17, v86, v17
	v_min_u32_e32 v33, v32, v29
	v_min_u32_e32 v34, v35, v62
	v_max_u32_e32 v29, v32, v29
	v_max_u32_e32 v76, v75, v31
	v_min_u32_e32 v27, v73, v27
	v_min_u32_e32 v23, v72, v23
	v_max3_u32 v15, v15, v21, v22
	v_max_u32_e32 v45, v45, v48
	v_min_u32_e32 v19, v87, v18
	v_max_u32_e32 v18, v87, v18
	v_min_u32_e32 v48, v17, v16
	v_max_u32_e32 v16, v17, v16
	v_min_u32_e32 v32, v29, v34
	v_max_u32_e32 v77, v76, v33
	v_min_u32_e32 v31, v75, v31
	v_min_u32_e32 v25, v74, v25
	v_max3_u32 v15, v15, v23, v27
	v_max_u32_e32 v44, v44, v49
	v_min_u32_e32 v20, v88, v19
	v_max_u32_e32 v19, v88, v19
	v_min_u32_e32 v49, v18, v48
	v_max_u32_e32 v18, v18, v48
	s_waitcnt lgkmcnt(13)
; #define INS32(T, X) { _Pragma("unroll") for (int jj = 0; jj < 16; ++jj) { unsigned t_ = max(T[jj], X); X = min(T[jj], X); T[jj] = t_; } }
; __device__ __forceinline__ void route_task(const Params& p, int layer, const u16* qg, int rb, int hd, int r, int h) {
;     ...
;     for (int jj = 0; jj < 16; ++jj) ot[jj] = (unsigned)__shfl_xor((int)tp[jj], 32);
; #pragma unroll
;     for (int jj = 0; jj < 16; ++jj) { unsigned key = ot[jj]; INS32(tp, key); }
	v_min_u32_e32 v17, v16, v13
	v_max_u32_e32 v13, v16, v13
	v_min_u32_e32 v78, v77, v32
	v_min_u32_e32 v33, v76, v33
	v_max3_u32 v15, v15, v25, v31
	v_max_u32_e32 v43, v43, v51
	v_min_u32_e32 v21, v89, v20
	v_max_u32_e32 v20, v89, v20
	v_min_u32_e32 v51, v19, v49
	v_max_u32_e32 v19, v19, v49
	v_min_u32_e32 v48, v18, v17
	v_max_u32_e32 v17, v18, v17
	s_waitcnt lgkmcnt(12)
	v_min_u32_e32 v16, v13, v12
	v_max3_u32 v15, v15, v33, v78
	v_max_u32_e32 v33, v77, v32
	v_add_u32_e32 v32, s34, v52
	v_min_u32_e32 v22, v90, v21
	v_max_u32_e32 v21, v90, v21
	v_min_u32_e32 v52, v20, v51
	v_max_u32_e32 v20, v20, v51
	v_min_u32_e32 v49, v19, v48
	v_max_u32_e32 v19, v19, v48
	v_min_u32_e32 v18, v17, v16
	v_max_u32_e32 v42, v42, v53
	v_min_u32_e32 v23, v91, v22
	v_max_u32_e32 v22, v91, v22
	v_min_u32_e32 v53, v21, v52
	v_max_u32_e32 v21, v21, v52
	v_min_u32_e32 v51, v20, v49
	v_max_u32_e32 v20, v20, v49
	v_min_u32_e32 v48, v19, v18
	v_max_u32_e32 v12, v13, v12
	v_min_u32_e32 v24, v92, v23
	v_max_u32_e32 v23, v92, v23
	v_min_u32_e32 v54, v22, v53
	v_max_u32_e32 v22, v22, v53
	v_min_u32_e32 v52, v21, v51
	v_max_u32_e32 v21, v21, v51
	v_min_u32_e32 v49, v20, v48
	v_max_u32_e32 v16, v17, v16
	s_waitcnt lgkmcnt(11)
	v_min_u32_e32 v13, v12, v11
	v_max_u32_e32 v11, v12, v11
	v_min_u32_e32 v25, v93, v24
	v_max_u32_e32 v24, v93, v24
	v_min_u32_e32 v55, v23, v54
	v_max_u32_e32 v23, v23, v54
	v_min_u32_e32 v53, v22, v52
	v_max_u32_e32 v22, v22, v52
	v_min_u32_e32 v51, v21, v49
	v_min_u32_e32 v17, v16, v13
	v_max_u32_e32 v13, v16, v13
	s_waitcnt lgkmcnt(10)
	v_min_u32_e32 v12, v11, v10
	v_max_u32_e32 v10, v11, v10
	v_max_u32_e32 v41, v41, v56
	v_min_u32_e32 v26, v94, v25
	v_max_u32_e32 v25, v94, v25
	v_min_u32_e32 v56, v24, v55
	v_max_u32_e32 v24, v24, v55
	v_min_u32_e32 v54, v23, v53
	v_max_u32_e32 v23, v23, v53
	v_min_u32_e32 v52, v22, v51
	v_max_u32_e32 v18, v19, v18
	v_min_u32_e32 v16, v13, v12
	v_max_u32_e32 v12, v13, v12
	s_waitcnt lgkmcnt(9)
	v_min_u32_e32 v11, v10, v9
	v_max_u32_e32 v9, v10, v9
	v_max_u32_e32 v40, v40, v57
	v_min_u32_e32 v27, v95, v26
	v_max_u32_e32 v26, v95, v26
	v_min_u32_e32 v57, v25, v56
	v_max_u32_e32 v25, v25, v56
	v_min_u32_e32 v55, v24, v54
	v_max_u32_e32 v24, v24, v54
	v_min_u32_e32 v53, v23, v52
	v_max_u32_e32 v20, v20, v48
	v_min_u32_e32 v19, v18, v17
	v_max_u32_e32 v17, v18, v17
	v_min_u32_e32 v13, v12, v11
	v_max_u32_e32 v11, v12, v11
	s_waitcnt lgkmcnt(8)
	v_min_u32_e32 v10, v9, v8
	v_max_u32_e32 v8, v9, v8
	v_max_u32_e32 v39, v39, v58
	v_min_u32_e32 v28, v96, v27
	v_max_u32_e32 v27, v96, v27
	v_min_u32_e32 v58, v26, v57
	v_max_u32_e32 v26, v26, v57
	v_min_u32_e32 v56, v25, v55
	v_max_u32_e32 v25, v25, v55
	v_min_u32_e32 v54, v24, v53
	v_max_u32_e32 v21, v21, v49
	v_min_u32_e32 v48, v20, v19
	v_max_u32_e32 v19, v20, v19
	v_min_u32_e32 v18, v17, v16
	v_min_u32_e32 v12, v11, v10
	v_max_u32_e32 v10, v11, v10
	s_waitcnt lgkmcnt(7)
	v_min_u32_e32 v9, v8, v7
	v_max_u32_e32 v7, v8, v7
	v_max_u32_e32 v34, v29, v34
	v_max_u32_e32 v38, v38, v59
	v_min_u32_e32 v29, v97, v28
	v_max_u32_e32 v28, v97, v28
	v_min_u32_e32 v59, v27, v58
	v_max_u32_e32 v27, v27, v58
	v_min_u32_e32 v57, v26, v56
	v_max_u32_e32 v26, v26, v56
	v_min_u32_e32 v55, v25, v54
	v_max_u32_e32 v22, v22, v51
	v_min_u32_e32 v49, v21, v48
	v_max_u32_e32 v21, v21, v48
	v_min_u32_e32 v20, v19, v18
	v_min_u32_e32 v11, v10, v9
	v_max_u32_e32 v9, v10, v9
	s_waitcnt lgkmcnt(6)
	v_min_u32_e32 v8, v7, v6
	v_max_u32_e32 v6, v7, v6
	v_max_u32_e32 v37, v37, v60
	v_min_u32_e32 v30, v98, v29
	v_max_u32_e32 v29, v98, v29
	v_min_u32_e32 v60, v28, v59
	v_max_u32_e32 v28, v28, v59
	v_min_u32_e32 v58, v27, v57
	v_max_u32_e32 v27, v27, v57
	v_min_u32_e32 v56, v26, v55
	v_max_u32_e32 v23, v23, v52
	v_min_u32_e32 v51, v22, v49
	v_max_u32_e32 v22, v22, v49
	v_min_u32_e32 v48, v21, v20
	v_max_u32_e32 v16, v17, v16
	v_min_u32_e32 v10, v9, v8
	v_max_u32_e32 v8, v9, v8
	s_waitcnt lgkmcnt(5)
	v_min_u32_e32 v7, v6, v5
	v_max_u32_e32 v5, v6, v5
	v_max_u32_e32 v36, v36, v61
	v_min_u32_e32 v31, v99, v30
	v_max_u32_e32 v30, v99, v30
	v_min_u32_e32 v61, v29, v60
	v_max_u32_e32 v29, v29, v60
	v_min_u32_e32 v59, v28, v58
	v_max_u32_e32 v28, v28, v58
	v_min_u32_e32 v57, v27, v56
	v_max_u32_e32 v24, v24, v53
	v_min_u32_e32 v52, v23, v51
	v_max_u32_e32 v23, v23, v51
	v_min_u32_e32 v49, v22, v48
	v_max_u32_e32 v18, v19, v18
	v_min_u32_e32 v17, v16, v13
	v_max_u32_e32 v13, v16, v13
	v_min_u32_e32 v9, v8, v7
	v_max_u32_e32 v7, v8, v7
	s_waitcnt lgkmcnt(4)
	v_min_u32_e32 v6, v5, v4
	v_max_u32_e32 v4, v5, v4
	v_max_u32_e32 v35, v35, v62
	v_max_u32_e32 v46, v46, v47
	v_min_u32_e32 v47, v100, v31
	v_max_u32_e32 v31, v100, v31
	v_min_u32_e32 v62, v30, v61
	v_max_u32_e32 v30, v30, v61
	v_min_u32_e32 v60, v29, v59
	v_max_u32_e32 v29, v29, v59
	v_min_u32_e32 v58, v28, v57
	v_max_u32_e32 v25, v25, v54
	v_min_u32_e32 v53, v24, v52
	v_max_u32_e32 v24, v24, v52
	v_min_u32_e32 v51, v23, v49
	v_min_u32_e32 v19, v18, v17
	v_max_u32_e32 v17, v18, v17
	v_min_u32_e32 v16, v13, v12
	v_max_u32_e32 v12, v13, v12
	v_min_u32_e32 v8, v7, v6
	v_max_u32_e32 v6, v7, v6
	s_waitcnt lgkmcnt(3)
	v_min_u32_e32 v5, v4, v3
	v_max_u32_e32 v3, v4, v3
	v_min_u32_e32 v63, v31, v62
	v_max_u32_e32 v31, v31, v62
	v_min_u32_e32 v61, v30, v60
	v_max_u32_e32 v30, v30, v60
	v_min_u32_e32 v59, v29, v58
	v_max_u32_e32 v26, v26, v55
	v_min_u32_e32 v54, v25, v53
	v_max_u32_e32 v25, v25, v53
	v_min_u32_e32 v52, v24, v51
	v_min_u32_e32 v18, v17, v16
	v_max_u32_e32 v16, v17, v16
	v_min_u32_e32 v13, v12, v11
	v_max_u32_e32 v11, v12, v11
	v_min_u32_e32 v7, v6, v5
	v_max_u32_e32 v5, v6, v5
	s_waitcnt lgkmcnt(2)
; DI unsigned f2ord(float f) { unsigned u = __float_as_uint(f); return (u & 0x80000000u) ? ~u : (u | 0x80000000u); }
; DI float ord2f(unsigned u) { return __uint_as_float((u & 0x80000000u) ? (u & 0x7fffffffu) : ~u); }
; #define INS32(T, X) { _Pragma("unroll") for (int jj = 0; jj < 16; ++jj) { unsigned t_ = max(T[jj], X); X = min(T[jj], X); T[jj] = t_; } }
; __device__ __forceinline__ void route_task(const Params& p, int layer, const u16* qg, int rb, int hd, int r, int h) {
;     ...
;     for (int jj = 0; jj < 16; ++jj) { unsigned key = ot[jj]; INS32(tp, key); }
; #pragma unroll
;     for (int jj = 0; jj < 16; ++jj) top[ph][jj] = tp[jj];
;   }
;   if (h == 0) {
;     unsigned ct[16];
; #pragma unroll
;     for (int jj = 0; jj < 16; ++jj) ct[jj] = 0u;
; #pragma unroll
;     for (int a = 0; a < 16; ++a) {
;       const float va = ord2f(top[0][a] & ~127u);
; #pragma unroll
;       for (int b = 0; b < 16; ++b) {
;         if ((a + 1) * (b + 1) <= 16) {
;           const float vb = ord2f(top[1][b] & ~127u);
;           unsigned key = (f2ord(va + vb) & ~255u) | (unsigned)(255 - (a * 16 + b));
;           INS32(ct, key);
	v_min_u32_e32 v4, v3, v2
	v_max_u32_e32 v2, v3, v2
	v_min_u32_e32 v62, v31, v61
	v_max_u32_e32 v31, v31, v61
	v_min_u32_e32 v60, v30, v59
	v_max_u32_e32 v27, v27, v56
	v_min_u32_e32 v55, v26, v54
	v_max_u32_e32 v26, v26, v54
	v_min_u32_e32 v53, v25, v52
	v_min_u32_e32 v17, v16, v13
	v_max_u32_e32 v13, v16, v13
	v_min_u32_e32 v12, v11, v10
	v_max_u32_e32 v10, v11, v10
	v_min_u32_e32 v6, v5, v4
	v_max_u32_e32 v4, v5, v4
	s_waitcnt lgkmcnt(1)
	v_min_u32_e32 v3, v2, v1
	v_max_u32_e32 v1, v2, v1
	v_max3_u32 v47, v83, v47, v63
	v_min_u32_e32 v61, v31, v60
	v_max_u32_e32 v28, v28, v57
	v_min_u32_e32 v56, v27, v55
	v_max_u32_e32 v27, v27, v55
	v_min_u32_e32 v54, v26, v53
	v_min_u32_e32 v16, v13, v12
	v_max_u32_e32 v12, v13, v12
	v_min_u32_e32 v11, v10, v9
	v_max_u32_e32 v9, v10, v9
	v_min_u32_e32 v5, v4, v3
	v_max_u32_e32 v3, v4, v3
	s_waitcnt lgkmcnt(0)
	v_min_u32_e32 v2, v1, v0
	v_max_u32_e32 v63, v1, v0
	v_max3_u32 v47, v47, v62, v61
	v_max_u32_e32 v29, v29, v58
	v_min_u32_e32 v57, v28, v56
	v_max_u32_e32 v28, v28, v56
	v_min_u32_e32 v55, v27, v54
	v_max_u32_e32 v20, v21, v20
	v_min_u32_e32 v13, v12, v11
	v_max_u32_e32 v11, v12, v11
	v_min_u32_e32 v10, v9, v8
	v_max_u32_e32 v8, v9, v8
	v_max_u32_e32 v62, v3, v2
	v_and_b32_e32 v0, 0x7fffff80, v63
	v_bitop3_b32 v1, v63, s52, v63 bitop3:0xcf
	v_cmp_gt_i32_e32 vcc, 0, v63
	v_max_u32_e32 v30, v30, v59
	v_min_u32_e32 v58, v29, v57
	v_max_u32_e32 v29, v29, v57
	v_min_u32_e32 v56, v28, v55
	v_max_u32_e32 v22, v22, v48
	v_min_u32_e32 v21, v20, v19
	v_max_u32_e32 v19, v20, v19
	v_min_u32_e32 v12, v11, v10
	v_max_u32_e32 v10, v11, v10
	v_min_u32_e32 v9, v8, v7
	v_max_u32_e32 v7, v8, v7
	v_min_u32_e32 v4, v3, v2
	v_max_u32_e32 v50, v14, v50
	v_cndmask_b32_e32 v1, v1, v0, vcc
	v_and_b32_e32 v0, 0x7fffff80, v62
	v_bitop3_b32 v2, v62, s52, v62 bitop3:0xcf
	v_cmp_gt_i32_e32 vcc, 0, v62
	v_max_u32_e32 v31, v31, v60
	v_min_u32_e32 v59, v30, v58
	v_max_u32_e32 v30, v30, v58
	v_min_u32_e32 v57, v29, v56
	v_max_u32_e32 v23, v23, v49
	v_min_u32_e32 v48, v22, v21
	v_max_u32_e32 v21, v22, v21
	v_min_u32_e32 v20, v19, v18
	v_max_u32_e32 v18, v19, v18
	v_min_u32_e32 v11, v10, v9
	v_max_u32_e32 v9, v10, v9
	v_min_u32_e32 v8, v7, v6
	v_max_u32_e32 v6, v7, v6
	v_cndmask_b32_e32 v0, v2, v0, vcc
	v_and_b32_e32 v2, 0x7fffff80, v50
	v_bitop3_b32 v3, v50, s52, v50 bitop3:0xcf
	v_cmp_gt_i32_e32 vcc, 0, v50
	v_min_u32_e32 v60, v31, v59
	v_max_u32_e32 v31, v31, v59
	v_min_u32_e32 v58, v30, v57
	v_max_u32_e32 v24, v24, v51
	v_min_u32_e32 v49, v23, v48
	v_max_u32_e32 v23, v23, v48
	v_min_u32_e32 v22, v21, v20
	v_min_u32_e32 v19, v18, v17
	v_max_u32_e32 v17, v18, v17
	v_min_u32_e32 v10, v9, v8
	v_max_u32_e32 v8, v9, v8
	v_min_u32_e32 v7, v6, v5
	v_max_u32_e32 v5, v6, v5
	v_cndmask_b32_e32 v2, v3, v2, vcc
	v_min_u32_e32 v59, v31, v58
	v_max_u32_e32 v25, v25, v52
	v_min_u32_e32 v51, v24, v49
	v_max_u32_e32 v24, v24, v49
	v_min_u32_e32 v48, v23, v22
	v_min_u32_e32 v18, v17, v16
	v_max_u32_e32 v16, v17, v16
	v_min_u32_e32 v9, v8, v7
	v_max_u32_e32 v7, v8, v7
	v_min_u32_e32 v6, v5, v4
	v_max_u32_e32 v61, v5, v4
	v_pk_add_f32 v[4:5], v[2:3], v[0:1] op_sel_hi:[0,1]
	v_max3_u32 v47, v47, v60, v59
	v_max_u32_e32 v26, v26, v53
	v_min_u32_e32 v52, v25, v51
	v_max_u32_e32 v25, v25, v51
	v_min_u32_e32 v49, v24, v48
	v_max_u32_e32 v20, v21, v20
	v_min_u32_e32 v17, v16, v13
	v_max_u32_e32 v13, v16, v13
	v_min_u32_e32 v8, v7, v6
	v_max_u32_e32 v60, v7, v6
	v_not_b32_e32 v3, v5
	v_or_b32_e32 v6, 0x80000000, v5
	v_cmp_gt_i32_e32 vcc, 0, v5
	v_max_u32_e32 v27, v27, v54
	v_min_u32_e32 v53, v26, v52
	v_max_u32_e32 v26, v26, v52
	v_min_u32_e32 v51, v25, v49
	v_min_u32_e32 v21, v20, v19
	v_max_u32_e32 v19, v20, v19
	v_min_u32_e32 v16, v13, v12
	v_max_u32_e32 v12, v13, v12
	v_cndmask_b32_e32 v3, v6, v3, vcc
	v_max_u32_e32 v28, v28, v55
	v_min_u32_e32 v54, v27, v53
	v_max_u32_e32 v27, v27, v53
	v_min_u32_e32 v52, v26, v51
	v_min_u32_e32 v20, v19, v18
	v_max_u32_e32 v18, v19, v18
	v_min_u32_e32 v13, v12, v11
	v_max_u32_e32 v11, v12, v11
	v_or_b32_e32 v5, 0xff, v3
	v_not_b32_e32 v3, v4
	v_or_b32_e32 v6, 0x80000000, v4
	v_cmp_gt_i32_e32 vcc, 0, v4
	v_max_u32_e32 v29, v29, v56
	v_min_u32_e32 v55, v28, v54
	v_max_u32_e32 v28, v28, v54
	v_min_u32_e32 v53, v27, v52
	v_min_u32_e32 v19, v18, v17
	v_max_u32_e32 v17, v18, v17
	v_min_u32_e32 v12, v11, v10
	v_max_u32_e32 v10, v11, v10
	v_cndmask_b32_e32 v3, v6, v3, vcc
	v_max_u32_e32 v30, v30, v57
	v_min_u32_e32 v56, v29, v55
	v_max_u32_e32 v29, v29, v55
	v_min_u32_e32 v54, v28, v53
	v_min_u32_e32 v18, v17, v16
	v_max_u32_e32 v16, v17, v16
	v_min_u32_e32 v11, v10, v9
	v_max_u32_e32 v9, v10, v9
	v_and_b32_e32 v3, 0xffffff00, v3
	v_max_u32_e32 v31, v31, v58
	v_min_u32_e32 v57, v30, v56
	v_max_u32_e32 v30, v30, v56
	v_min_u32_e32 v55, v29, v54
	v_min_u32_e32 v17, v16, v13
	v_max_u32_e32 v13, v16, v13
	v_min_u32_e32 v10, v9, v8
	v_max_u32_e32 v59, v9, v8
	v_or_b32_e32 v4, 0xfe, v3
	v_and_b32_e32 v3, 0x7fffff80, v61
	v_bitop3_b32 v8, v61, s52, v61 bitop3:0xcf
	v_cmp_gt_i32_e32 vcc, 0, v61
	v_min_u32_e32 v58, v31, v57
	v_max_u32_e32 v31, v31, v57
	v_min_u32_e32 v56, v30, v55
	v_min_u32_e32 v16, v13, v12
	v_max_u32_e32 v12, v13, v12
	v_cndmask_b32_e32 v3, v8, v3, vcc
	v_min_u32_e32 v57, v31, v56
	v_max_u32_e32 v22, v23, v22
	v_min_u32_e32 v13, v12, v11
	v_max_u32_e32 v11, v12, v11
	v_add_f32_e32 v8, v2, v3
	v_max3_u32 v47, v47, v58, v57
	v_min_u32_e32 v23, v22, v21
	v_max_u32_e32 v21, v22, v21
	v_min_u32_e32 v12, v11, v10
	v_max_u32_e32 v58, v11, v10
	v_not_b32_e32 v9, v8
	v_or_b32_e32 v10, 0x80000000, v8
	v_cmp_gt_i32_e32 vcc, 0, v8
	v_min_u32_e32 v22, v21, v20
	v_max_u32_e32 v20, v21, v20
	v_cndmask_b32_e32 v8, v10, v9, vcc
; DI unsigned f2ord(float f) { unsigned u = __float_as_uint(f); return (u & 0x80000000u) ? ~u : (u | 0x80000000u); }
; DI float ord2f(unsigned u) { return __uint_as_float((u & 0x80000000u) ? (u & 0x7fffffffu) : ~u); }
; #define INS32(T, X) { _Pragma("unroll") for (int jj = 0; jj < 16; ++jj) { unsigned t_ = max(T[jj], X); X = min(T[jj], X); T[jj] = t_; } }
; __device__ __forceinline__ void route_task(const Params& p, int layer, const u16* qg, int rb, int hd, int r, int h) {
;     ...
;     for (int a = 0; a < 16; ++a) {
;       const float va = ord2f(top[0][a] & ~127u);
; #pragma unroll
;       for (int b = 0; b < 16; ++b) {
;         if ((a + 1) * (b + 1) <= 16) {
;           const float vb = ord2f(top[1][b] & ~127u);
;           unsigned key = (f2ord(va + vb) & ~255u) | (unsigned)(255 - (a * 16 + b));
;           INS32(ct, key);
;         }
;       }
;     }
	v_min_u32_e32 v21, v20, v19
	v_max_u32_e32 v19, v20, v19
	v_and_b32_e32 v8, 0xffffff00, v8
	v_min_u32_e32 v20, v19, v18
	v_max_u32_e32 v18, v19, v18
	v_max_u32_e32 v7, v5, v4
	v_or_b32_e32 v8, 0xfd, v8
	v_min_u32_e32 v19, v18, v17
	v_max_u32_e32 v17, v18, v17
	v_min_u32_e32 v6, v5, v4
	v_min_u32_e32 v9, v7, v8
	v_med3_u32 v5, v5, v4, v8
	v_max_u32_e32 v7, v7, v8
	v_and_b32_e32 v4, 0x7fffff80, v60
	v_bitop3_b32 v8, v60, s52, v60 bitop3:0xcf
	v_cmp_gt_i32_e32 vcc, 0, v60
	v_min_u32_e32 v18, v17, v16
	v_max_u32_e32 v16, v17, v16
	v_cndmask_b32_e32 v4, v8, v4, vcc
	v_min_u32_e32 v17, v16, v13
	v_max_u32_e32 v13, v16, v13
	v_add_f32_e32 v8, v2, v4
	v_min_u32_e32 v16, v13, v12
	v_max_u32_e32 v57, v13, v12
	v_not_b32_e32 v11, v8
	v_or_b32_e32 v12, 0x80000000, v8
	v_cmp_gt_i32_e32 vcc, 0, v8
	v_min_u32_e32 v10, v6, v9
	v_max_u32_e32 v24, v24, v48
	v_cndmask_b32_e32 v8, v12, v11, vcc
	v_and_b32_e32 v8, 0xffffff00, v8
	v_or_b32_e32 v8, 0xfc, v8
	v_min_u32_e32 v11, v7, v8
	v_min_u32_e32 v12, v5, v11
	v_med3_u32 v6, v6, v9, v11
	v_max_u32_e32 v9, v5, v11
	v_max_u32_e32 v7, v7, v8
	v_and_b32_e32 v5, 0x7fffff80, v59
	v_bitop3_b32 v8, v59, s52, v59 bitop3:0xcf
	v_cmp_gt_i32_e32 vcc, 0, v59
	v_max_u32_e32 v25, v25, v49
	v_min_u32_e32 v48, v24, v23
	v_cndmask_b32_e32 v5, v8, v5, vcc
	v_max_u32_e32 v23, v24, v23
	v_add_f32_e32 v8, v2, v5
	v_max_u32_e32 v26, v26, v51
	v_min_u32_e32 v49, v25, v48
	v_max_u32_e32 v25, v25, v48
	v_min_u32_e32 v24, v23, v22
	v_not_b32_e32 v11, v8
	v_or_b32_e32 v14, 0x80000000, v8
	v_cmp_gt_i32_e32 vcc, 0, v8
	v_max_u32_e32 v27, v27, v52
	v_min_u32_e32 v51, v26, v49
	v_max_u32_e32 v26, v26, v49
	v_min_u32_e32 v48, v25, v24
	v_cndmask_b32_e32 v8, v14, v11, vcc
	v_max_u32_e32 v28, v28, v53
	v_min_u32_e32 v52, v27, v51
	v_max_u32_e32 v27, v27, v51
	v_min_u32_e32 v49, v26, v48
	v_max_u32_e32 v22, v23, v22
	v_and_b32_e32 v8, 0xffffff00, v8
	v_max_u32_e32 v29, v29, v54
	v_min_u32_e32 v53, v28, v52
	v_max_u32_e32 v28, v28, v52
	v_min_u32_e32 v51, v27, v49
	v_min_u32_e32 v23, v22, v21
	v_max_u32_e32 v21, v22, v21
	v_or_b32_e32 v8, 0xfb, v8
	v_max_u32_e32 v30, v30, v55
	v_min_u32_e32 v54, v29, v53
	v_max_u32_e32 v29, v29, v53
	v_min_u32_e32 v52, v28, v51
	v_min_u32_e32 v22, v21, v20
	v_max_u32_e32 v20, v21, v20
	v_min_u32_e32 v11, v7, v8
	v_max_u32_e32 v31, v31, v56
	v_min_u32_e32 v55, v30, v54
	v_max_u32_e32 v30, v30, v54
	v_min_u32_e32 v53, v29, v52
	v_min_u32_e32 v21, v20, v19
	v_max_u32_e32 v19, v20, v19
	v_min_u32_e32 v14, v9, v11
	v_max_u32_e32 v9, v9, v11
	v_max_u32_e32 v7, v7, v8
	v_and_b32_e32 v8, 0x7fffff80, v58
	v_bitop3_b32 v11, v58, s52, v58 bitop3:0xcf
	v_cmp_gt_i32_e32 vcc, 0, v58
	v_min_u32_e32 v56, v31, v55
	v_max_u32_e32 v31, v31, v55
	v_min_u32_e32 v54, v30, v53
	v_min_u32_e32 v20, v19, v18
	v_max_u32_e32 v18, v19, v18
	v_cndmask_b32_e32 v8, v11, v8, vcc
	v_min_u32_e32 v55, v31, v54
	v_min_u32_e32 v19, v18, v17
	v_max_u32_e32 v17, v18, v17
	v_add_f32_e32 v11, v2, v8
	v_max3_u32 v47, v47, v56, v55
	v_min_u32_e32 v18, v17, v16
	v_max_u32_e32 v56, v17, v16
	v_min_u32_e32 v13, v10, v12
	v_min_u32_e32 v16, v6, v14
	v_med3_u32 v10, v10, v12, v14
	v_max_u32_e32 v6, v6, v14
	v_not_b32_e32 v12, v11
	v_or_b32_e32 v14, 0x80000000, v11
	v_cmp_gt_i32_e32 vcc, 0, v11
	v_max_u32_e32 v24, v25, v24
	v_min_u32_e32 v25, v24, v23
	v_cndmask_b32_e32 v11, v14, v12, vcc
	v_max_u32_e32 v23, v24, v23
	v_and_b32_e32 v11, 0xffffff00, v11
	v_min_u32_e32 v24, v23, v22
	v_max_u32_e32 v22, v23, v22
	v_or_b32_e32 v11, 0xfa, v11
	v_min_u32_e32 v23, v22, v21
	v_max_u32_e32 v21, v22, v21
	v_min_u32_e32 v12, v7, v11
	v_min_u32_e32 v22, v21, v20
	v_max_u32_e32 v20, v21, v20
	v_min_u32_e32 v14, v9, v12
	v_max_u32_e32 v9, v9, v12
	v_max_u32_e32 v11, v7, v11
	v_and_b32_e32 v7, 0x7fffff80, v57
	v_bitop3_b32 v12, v57, s52, v57 bitop3:0xcf
	v_cmp_gt_i32_e32 vcc, 0, v57
	v_min_u32_e32 v21, v20, v19
	v_max_u32_e32 v19, v20, v19
	v_cndmask_b32_e32 v7, v12, v7, vcc
	v_min_u32_e32 v20, v19, v18
	v_max_u32_e32 v55, v19, v18
	v_min_u32_e32 v18, v6, v14
	v_add_f32_e32 v12, v2, v7
	v_min_u32_e32 v17, v13, v16
	v_med3_u32 v13, v13, v16, v18
	v_max_u32_e32 v6, v6, v14
	v_not_b32_e32 v14, v12
	v_or_b32_e32 v16, 0x80000000, v12
	v_cmp_gt_i32_e32 vcc, 0, v12
	v_max_u32_e32 v26, v26, v48
	v_max_u32_e32 v27, v27, v49
	v_cndmask_b32_e32 v12, v16, v14, vcc
	v_min_u32_e32 v48, v26, v25
	v_max_u32_e32 v25, v26, v25
	v_and_b32_e32 v12, 0xffffff00, v12
	v_max_u32_e32 v28, v28, v51
	v_min_u32_e32 v49, v27, v48
	v_max_u32_e32 v27, v27, v48
	v_min_u32_e32 v26, v25, v24
	v_or_b32_e32 v12, 0xf9, v12
	v_max_u32_e32 v29, v29, v52
	v_min_u32_e32 v51, v28, v49
	v_max_u32_e32 v28, v28, v49
	v_min_u32_e32 v48, v27, v26
	v_min_u32_e32 v14, v11, v12
	v_max_u32_e32 v30, v30, v53
	v_min_u32_e32 v52, v29, v51
	v_max_u32_e32 v29, v29, v51
	v_min_u32_e32 v49, v28, v48
	v_max_u32_e32 v24, v25, v24
	v_min_u32_e32 v16, v9, v14
	v_max_u32_e32 v31, v31, v54
	v_min_u32_e32 v53, v30, v52
	v_max_u32_e32 v30, v30, v52
	v_min_u32_e32 v51, v29, v49
	v_min_u32_e32 v25, v24, v23
	v_max_u32_e32 v23, v24, v23
	v_min_u32_e32 v19, v10, v18
	v_max_u32_e32 v10, v10, v18
	v_min_u32_e32 v18, v6, v16
	v_max_u32_e32 v16, v6, v16
	v_max_u32_e32 v11, v11, v12
	v_and_b32_e32 v6, 0x7fffff80, v56
	v_bitop3_b32 v12, v56, s52, v56 bitop3:0xcf
	v_cmp_gt_i32_e32 vcc, 0, v56
	v_min_u32_e32 v54, v31, v53
	v_max_u32_e32 v31, v31, v53
	v_min_u32_e32 v52, v30, v51
	v_min_u32_e32 v24, v23, v22
	v_max_u32_e32 v22, v23, v22
	v_cndmask_b32_e32 v6, v12, v6, vcc
	v_min_u32_e32 v53, v31, v52
	v_min_u32_e32 v23, v22, v21
	v_max_u32_e32 v21, v22, v21
	v_add_f32_e32 v12, v2, v6
	v_max3_u32 v47, v47, v54, v53
	v_min_u32_e32 v22, v21, v20
; DI unsigned f2ord(float f) { unsigned u = __float_as_uint(f); return (u & 0x80000000u) ? ~u : (u | 0x80000000u); }
; DI float ord2f(unsigned u) { return __uint_as_float((u & 0x80000000u) ? (u & 0x7fffffffu) : ~u); }
; #define INS32(T, X) { _Pragma("unroll") for (int jj = 0; jj < 16; ++jj) { unsigned t_ = max(T[jj], X); X = min(T[jj], X); T[jj] = t_; } }
; __device__ __forceinline__ void route_task(const Params& p, int layer, const u16* qg, int rb, int hd, int r, int h) {
;     ...
;     for (int a = 0; a < 16; ++a) {
;       const float va = ord2f(top[0][a] & ~127u);
; #pragma unroll
;       for (int b = 0; b < 16; ++b) {
;         if ((a + 1) * (b + 1) <= 16) {
;           const float vb = ord2f(top[1][b] & ~127u);
;           unsigned key = (f2ord(va + vb) & ~255u) | (unsigned)(255 - (a * 16 + b));
;           INS32(ct, key);
;         }
;       }
;     }
	v_max_u32_e32 v54, v21, v20
	v_min_u32_e32 v21, v10, v18
	v_max_u32_e32 v10, v10, v18
	v_max_u32_e32 v9, v9, v14
	v_not_b32_e32 v14, v12
	v_or_b32_e32 v18, 0x80000000, v12
	v_cmp_gt_i32_e32 vcc, 0, v12
	v_min_u32_e32 v20, v17, v19
	v_med3_u32 v17, v17, v19, v21
	v_cndmask_b32_e32 v12, v18, v14, vcc
	v_and_b32_e32 v12, 0xffffff00, v12
	v_or_b32_e32 v12, 0xf8, v12
	v_min_u32_e32 v14, v11, v12
	v_min_u32_e32 v18, v9, v14
	v_max_u32_e32 v9, v9, v14
	v_max_u32_e32 v11, v11, v12
	v_and_b32_e32 v12, 0x7fffff80, v55
	v_bitop3_b32 v14, v55, s52, v55 bitop3:0xcf
	v_cmp_gt_i32_e32 vcc, 0, v55
	v_min_u32_e32 v19, v16, v18
	v_max_u32_e32 v16, v16, v18
	v_cndmask_b32_e32 v12, v14, v12, vcc
	v_add_f32_e32 v12, v2, v12
	v_not_b32_e32 v14, v12
	v_or_b32_e32 v18, 0x80000000, v12
	v_cmp_gt_i32_e32 vcc, 0, v12
	v_max_u32_e32 v26, v27, v26
	v_min_u32_e32 v27, v26, v25
	v_cndmask_b32_e32 v12, v18, v14, vcc
	v_and_b32_e32 v12, 0xffffff00, v12
	v_or_b32_e32 v12, 0xf7, v12
	v_min_u32_e32 v14, v11, v12
	v_max_u32_e32 v25, v26, v25
	v_min_u32_e32 v18, v9, v14
	v_max_u32_e32 v9, v9, v14
	v_max_u32_e32 v11, v11, v12
	v_and_b32_e32 v12, 0x7fffff80, v54
	v_bitop3_b32 v14, v54, s52, v54 bitop3:0xcf
	v_cmp_gt_i32_e32 vcc, 0, v54
	v_min_u32_e32 v26, v25, v24
	v_max_u32_e32 v24, v25, v24
	v_cndmask_b32_e32 v12, v14, v12, vcc
	v_min_u32_e32 v25, v24, v23
	v_max_u32_e32 v23, v24, v23
	v_add_f32_e32 v12, v2, v12
	v_min_u32_e32 v24, v23, v22
	v_max_u32_e32 v53, v23, v22
	v_min_u32_e32 v22, v13, v21
	v_max_u32_e32 v13, v13, v21
	v_min_u32_e32 v21, v10, v19
	v_max_u32_e32 v10, v10, v19
	v_min_u32_e32 v19, v16, v18
	v_max_u32_e32 v16, v16, v18
	v_not_b32_e32 v14, v12
	v_or_b32_e32 v18, 0x80000000, v12
	v_cmp_gt_i32_e32 vcc, 0, v12
	v_max_u32_e32 v28, v28, v48
	v_max_u32_e32 v29, v29, v49
	v_cndmask_b32_e32 v12, v18, v14, vcc
	v_and_b32_e32 v12, 0xffffff00, v12
	v_min_u32_e32 v48, v28, v27
	v_max_u32_e32 v27, v28, v27
	v_or_b32_e32 v12, 0xf6, v12
	v_max_u32_e32 v30, v30, v51
	v_min_u32_e32 v49, v29, v48
	v_max_u32_e32 v29, v29, v48
	v_min_u32_e32 v28, v27, v26
	v_min_u32_e32 v14, v11, v12
	v_max_u32_e32 v31, v31, v52
	v_min_u32_e32 v51, v30, v49
	v_max_u32_e32 v30, v30, v49
	v_min_u32_e32 v48, v29, v28
	v_min_u32_e32 v18, v9, v14
	v_max_u32_e32 v9, v9, v14
	v_max_u32_e32 v11, v11, v12
	v_and_b32_e32 v12, 0x7fffff80, v53
	v_bitop3_b32 v14, v53, s52, v53 bitop3:0xcf
	v_cmp_gt_i32_e32 vcc, 0, v53
	v_min_u32_e32 v52, v31, v51
	v_max_u32_e32 v31, v31, v51
	v_min_u32_e32 v49, v30, v48
	v_max_u32_e32 v26, v27, v26
	v_cndmask_b32_e32 v12, v14, v12, vcc
	v_min_u32_e32 v51, v31, v49
	v_min_u32_e32 v27, v26, v25
	v_max_u32_e32 v25, v26, v25
	v_add_f32_e32 v12, v2, v12
	v_max3_u32 v47, v47, v52, v51
	v_min_u32_e32 v26, v25, v24
	v_max_u32_e32 v52, v25, v24
	v_min_u32_e32 v24, v13, v21
	v_max_u32_e32 v13, v13, v21
	v_min_u32_e32 v21, v10, v19
	v_max_u32_e32 v10, v10, v19
	v_min_u32_e32 v19, v16, v18
	v_max_u32_e32 v16, v16, v18
	v_not_b32_e32 v14, v12
	v_or_b32_e32 v18, 0x80000000, v12
	v_cmp_gt_i32_e32 vcc, 0, v12
	v_min_u32_e32 v23, v20, v22
	v_med3_u32 v20, v20, v22, v24
	v_cndmask_b32_e32 v12, v18, v14, vcc
	v_and_b32_e32 v12, 0xffffff00, v12
	v_or_b32_e32 v12, 0xf5, v12
	v_min_u32_e32 v14, v11, v12
	v_min_u32_e32 v18, v9, v14
	v_max_u32_e32 v9, v9, v14
	v_max_u32_e32 v11, v11, v12
	v_and_b32_e32 v12, 0x7fffff80, v52
	v_bitop3_b32 v14, v52, s52, v52 bitop3:0xcf
	v_cmp_gt_i32_e32 vcc, 0, v52
	v_min_u32_e32 v22, v13, v21
	v_max_u32_e32 v13, v13, v21
	v_cndmask_b32_e32 v12, v14, v12, vcc
	v_add_f32_e32 v12, v2, v12
	v_min_u32_e32 v21, v10, v19
	v_max_u32_e32 v10, v10, v19
	v_min_u32_e32 v19, v16, v18
	v_max_u32_e32 v16, v16, v18
	v_not_b32_e32 v14, v12
	v_or_b32_e32 v18, 0x80000000, v12
	v_cmp_gt_i32_e32 vcc, 0, v12
	v_max_u32_e32 v28, v29, v28
	v_min_u32_e32 v29, v28, v27
	v_cndmask_b32_e32 v12, v18, v14, vcc
	v_and_b32_e32 v12, 0xffffff00, v12
	v_max_u32_e32 v27, v28, v27
	v_or_b32_e32 v12, 0xf4, v12
	v_max_u32_e32 v51, v27, v26
	v_min_u32_e32 v14, v11, v12
	v_min_u32_e32 v18, v9, v14
	v_max_u32_e32 v9, v9, v14
	v_max_u32_e32 v11, v11, v12
	v_and_b32_e32 v12, 0x7fffff80, v51
	v_bitop3_b32 v14, v51, s52, v51 bitop3:0xcf
	v_cmp_gt_i32_e32 vcc, 0, v51
	v_min_u32_e32 v25, v17, v24
	v_max_u32_e32 v17, v17, v24
	v_cndmask_b32_e32 v12, v14, v12, vcc
	v_add_f32_e32 v12, v2, v12
	v_max_u32_e32 v30, v30, v48
	v_min_u32_e32 v24, v17, v22
	v_max_u32_e32 v17, v17, v22
	v_min_u32_e32 v22, v13, v21
	v_max_u32_e32 v13, v13, v21
	v_min_u32_e32 v21, v10, v19
	v_max_u32_e32 v10, v10, v19
	v_min_u32_e32 v19, v16, v18
	v_max_u32_e32 v16, v16, v18
	v_not_b32_e32 v14, v12
	v_or_b32_e32 v18, 0x80000000, v12
	v_cmp_gt_i32_e32 vcc, 0, v12
	v_max_u32_e32 v31, v31, v49
	v_min_u32_e32 v48, v30, v29
	v_max_u32_e32 v29, v30, v29
	v_min_u32_e32 v28, v27, v26
	v_cndmask_b32_e32 v12, v18, v14, vcc
	v_min_u32_e32 v49, v31, v48
	v_max_u32_e32 v31, v31, v48
	v_min_u32_e32 v30, v29, v28
	v_and_b32_e32 v12, 0xffffff00, v12
	v_min_u32_e32 v48, v31, v30
	v_or_b32_e32 v12, 0xf3, v12
	v_max3_u32 v47, v47, v49, v48
	v_max_u32_e32 v49, v29, v28
	v_min_u32_e32 v14, v11, v12
	v_min_u32_e32 v18, v9, v14
	v_max_u32_e32 v9, v9, v14
	v_max_u32_e32 v11, v11, v12
	v_and_b32_e32 v12, 0x7fffff80, v49
	v_bitop3_b32 v14, v49, s52, v49 bitop3:0xcf
	v_cmp_gt_i32_e32 vcc, 0, v49
	v_min_u32_e32 v26, v23, v25
	v_min_u32_e32 v27, v20, v24
	v_cndmask_b32_e32 v12, v14, v12, vcc
	v_add_f32_e32 v12, v2, v12
	v_med3_u32 v23, v23, v25, v24
	v_max_u32_e32 v20, v20, v24
	v_min_u32_e32 v24, v17, v22
	v_max_u32_e32 v17, v17, v22
	v_min_u32_e32 v22, v13, v21
	v_max_u32_e32 v13, v13, v21
	v_min_u32_e32 v21, v10, v19
	v_max_u32_e32 v10, v10, v19
; DI unsigned f2ord(float f) { unsigned u = __float_as_uint(f); return (u & 0x80000000u) ? ~u : (u | 0x80000000u); }
; DI float ord2f(unsigned u) { return __uint_as_float((u & 0x80000000u) ? (u & 0x7fffffffu) : ~u); }
; #define INS32(T, X) { _Pragma("unroll") for (int jj = 0; jj < 16; ++jj) { unsigned t_ = max(T[jj], X); X = min(T[jj], X); T[jj] = t_; } }
; __device__ __forceinline__ void route_task(const Params& p, int layer, const u16* qg, int rb, int hd, int r, int h) {
;     ...
;     for (int a = 0; a < 16; ++a) {
;       const float va = ord2f(top[0][a] & ~127u);
; #pragma unroll
;       for (int b = 0; b < 16; ++b) {
;         if ((a + 1) * (b + 1) <= 16) {
;           const float vb = ord2f(top[1][b] & ~127u);
;           unsigned key = (f2ord(va + vb) & ~255u) | (unsigned)(255 - (a * 16 + b));
;           INS32(ct, key);
;         }
;       }
;     }
	v_min_u32_e32 v19, v16, v18
	v_max_u32_e32 v16, v16, v18
	v_not_b32_e32 v14, v12
	v_or_b32_e32 v18, 0x80000000, v12
	v_cmp_gt_i32_e32 vcc, 0, v12
	v_max_u32_e32 v48, v31, v30
	v_min_u32_e32 v25, v20, v24
	v_cndmask_b32_e32 v12, v18, v14, vcc
	v_and_b32_e32 v12, 0xffffff00, v12
	v_or_b32_e32 v12, 0xf2, v12
	v_min_u32_e32 v14, v11, v12
	v_min_u32_e32 v18, v9, v14
	v_max_u32_e32 v9, v9, v14
	v_max_u32_e32 v11, v11, v12
	v_and_b32_e32 v12, 0x7fffff80, v48
	v_bitop3_b32 v14, v48, s52, v48 bitop3:0xcf
	v_cmp_gt_i32_e32 vcc, 0, v48
	v_max_u32_e32 v20, v20, v24
	v_min_u32_e32 v24, v17, v22
	v_cndmask_b32_e32 v12, v14, v12, vcc
	v_add_f32_e32 v12, v2, v12
	v_max_u32_e32 v17, v17, v22
	v_min_u32_e32 v22, v13, v21
	v_max_u32_e32 v13, v13, v21
	v_min_u32_e32 v21, v10, v19
	v_max_u32_e32 v10, v10, v19
	v_min_u32_e32 v19, v16, v18
	v_max_u32_e32 v16, v16, v18
	v_not_b32_e32 v14, v12
	v_or_b32_e32 v18, 0x80000000, v12
	v_cmp_gt_i32_e32 vcc, 0, v12
	v_min_u32_e32 v28, v26, v27
	v_min_u32_e32 v29, v23, v25
	v_cndmask_b32_e32 v12, v18, v14, vcc
	v_and_b32_e32 v12, 0xffffff00, v12
	v_or_b32_e32 v12, 0xf1, v12
	v_min_u32_e32 v14, v11, v12
	v_min_u32_e32 v18, v9, v14
	v_max_u32_e32 v9, v9, v14
	v_max_u32_e32 v11, v11, v12
	v_and_b32_e32 v12, 0x7fffff80, v47
	v_bitop3_b32 v14, v47, s52, v47 bitop3:0xcf
	v_cmp_gt_i32_e32 vcc, 0, v47
	v_med3_u32 v26, v26, v27, v25
	v_max_u32_e32 v23, v23, v25
	v_cndmask_b32_e32 v12, v14, v12, vcc
	v_add_f32_e32 v2, v2, v12
	v_not_b32_e32 v12, v2
	v_or_b32_e32 v14, 0x80000000, v2
	v_cmp_gt_i32_e32 vcc, 0, v2
	v_min_u32_e32 v25, v20, v24
	v_max_u32_e32 v20, v20, v24
	v_cndmask_b32_e32 v2, v14, v12, vcc
	v_and_b32_e32 v2, 0xffffff00, v2
	v_or_b32_e32 v2, 0xf0, v2
	v_min_u32_e32 v12, v11, v2
	v_min_u32_e32 v14, v9, v12
	v_max_u32_e32 v9, v9, v12
	v_max_u32_e32 v2, v11, v2
	v_and_b32_e32 v11, 0x7fffff80, v46
	v_bitop3_b32 v12, v46, s52, v46 bitop3:0xcf
	v_cmp_gt_i32_e32 vcc, 0, v46
	v_min_u32_e32 v24, v17, v22
	v_max_u32_e32 v17, v17, v22
	v_min_u32_e32 v22, v13, v21
	v_max_u32_e32 v13, v13, v21
	v_min_u32_e32 v21, v10, v19
	v_max_u32_e32 v10, v10, v19
	v_min_u32_e32 v19, v16, v18
	v_max_u32_e32 v16, v16, v18
	v_cndmask_b32_e32 v11, v12, v11, vcc
	v_min_u32_e32 v27, v23, v25
	v_max_u32_e32 v23, v23, v25
	v_min_u32_e32 v25, v20, v24
	v_max_u32_e32 v20, v20, v24
	v_min_u32_e32 v24, v17, v22
	v_max_u32_e32 v17, v17, v22
	v_min_u32_e32 v22, v13, v21
	v_max_u32_e32 v13, v13, v21
	v_min_u32_e32 v21, v10, v19
	v_max_u32_e32 v10, v10, v19
	v_min_u32_e32 v18, v16, v14
	v_add_f32_e32 v12, v11, v1
	v_min_u32_e32 v19, v10, v18
	v_max_u32_e32 v10, v10, v18
	v_max_u32_e32 v14, v16, v14
	v_not_b32_e32 v16, v12
	v_or_b32_e32 v18, 0x80000000, v12
	v_cmp_gt_i32_e32 vcc, 0, v12
	v_min_u32_e32 v30, v28, v29
	v_min_u32_e32 v31, v26, v27
	v_cndmask_b32_e32 v12, v18, v16, vcc
	v_and_b32_e32 v12, 0xffffff00, v12
	v_or_b32_e32 v12, 0xef, v12
	v_min_u32_e32 v16, v2, v12
	v_med3_u32 v28, v28, v29, v27
	v_max_u32_e32 v26, v26, v27
	v_min_u32_e32 v27, v23, v25
	v_max_u32_e32 v23, v23, v25
	v_min_u32_e32 v25, v20, v24
	v_max_u32_e32 v20, v20, v24
	v_min_u32_e32 v24, v17, v22
	v_max_u32_e32 v17, v17, v22
	v_min_u32_e32 v22, v13, v21
	v_max_u32_e32 v13, v13, v21
	v_min_u32_e32 v18, v9, v16
	v_max_u32_e32 v2, v2, v12
	v_add_f32_e32 v12, v11, v0
	v_min_u32_e32 v21, v13, v19
	v_max_u32_e32 v13, v13, v19
	v_min_u32_e32 v19, v14, v18
	v_max_u32_e32 v14, v14, v18
	v_max_u32_e32 v9, v9, v16
	v_not_b32_e32 v16, v12
	v_or_b32_e32 v18, 0x80000000, v12
	v_cmp_gt_i32_e32 vcc, 0, v12
	v_min_u32_e32 v29, v26, v27
	v_max_u32_e32 v26, v26, v27
	v_cndmask_b32_e32 v12, v18, v16, vcc
	v_and_b32_e32 v12, 0xffffff00, v12
	v_or_b32_e32 v12, 0xee, v12
	v_min_u32_e32 v16, v2, v12
	v_min_u32_e32 v27, v23, v25
	v_max_u32_e32 v23, v23, v25
	v_min_u32_e32 v25, v20, v24
	v_max_u32_e32 v20, v20, v24
	v_min_u32_e32 v24, v17, v22
	v_max_u32_e32 v17, v17, v22
	v_min_u32_e32 v18, v9, v16
	v_max_u32_e32 v2, v2, v12
	v_add_f32_e32 v12, v11, v3
	v_min_u32_e32 v22, v17, v21
	v_max_u32_e32 v17, v17, v21
	v_min_u32_e32 v21, v10, v19
	v_max_u32_e32 v10, v10, v19
	v_min_u32_e32 v19, v14, v18
	v_max_u32_e32 v14, v14, v18
	v_max_u32_e32 v9, v9, v16
	v_not_b32_e32 v16, v12
	v_or_b32_e32 v18, 0x80000000, v12
	v_cmp_gt_i32_e32 vcc, 0, v12
	v_min_u32_e32 v64, v30, v31
	v_min_u32_e32 v65, v28, v29
	v_cndmask_b32_e32 v12, v18, v16, vcc
	v_and_b32_e32 v12, 0xffffff00, v12
	v_or_b32_e32 v12, 0xed, v12
	v_min_u32_e32 v16, v2, v12
	v_med3_u32 v30, v30, v31, v29
	v_max_u32_e32 v28, v28, v29
	v_min_u32_e32 v29, v26, v27
	v_max_u32_e32 v26, v26, v27
	v_min_u32_e32 v27, v23, v25
	v_max_u32_e32 v23, v23, v25
	v_min_u32_e32 v25, v20, v24
	v_max_u32_e32 v20, v20, v24
	v_min_u32_e32 v18, v9, v16
	v_max_u32_e32 v2, v2, v12
	v_add_f32_e32 v12, v11, v4
	v_min_u32_e32 v24, v20, v22
	v_max_u32_e32 v20, v20, v22
	v_min_u32_e32 v22, v13, v21
	v_max_u32_e32 v13, v13, v21
	v_min_u32_e32 v21, v10, v19
	v_max_u32_e32 v10, v10, v19
	v_min_u32_e32 v19, v14, v18
	v_max_u32_e32 v14, v14, v18
	v_max_u32_e32 v9, v9, v16
	v_not_b32_e32 v16, v12
	v_or_b32_e32 v18, 0x80000000, v12
	v_cmp_gt_i32_e32 vcc, 0, v12
	v_min_u32_e32 v31, v28, v29
	v_max_u32_e32 v28, v28, v29
	v_cndmask_b32_e32 v12, v18, v16, vcc
	v_and_b32_e32 v12, 0xffffff00, v12
	v_or_b32_e32 v12, 0xec, v12
	v_min_u32_e32 v16, v2, v12
	v_min_u32_e32 v29, v26, v27
	v_max_u32_e32 v26, v26, v27
	v_min_u32_e32 v27, v23, v25
	v_max_u32_e32 v23, v23, v25
	v_min_u32_e32 v18, v9, v16
	v_max_u32_e32 v2, v2, v12
	v_add_f32_e32 v12, v11, v5
	v_min_u32_e32 v25, v23, v24
	v_max_u32_e32 v23, v23, v24
	v_min_u32_e32 v24, v17, v22
	v_max_u32_e32 v17, v17, v22
	v_min_u32_e32 v22, v13, v21
; DI unsigned f2ord(float f) { unsigned u = __float_as_uint(f); return (u & 0x80000000u) ? ~u : (u | 0x80000000u); }
; DI float ord2f(unsigned u) { return __uint_as_float((u & 0x80000000u) ? (u & 0x7fffffffu) : ~u); }
; #define INS32(T, X) { _Pragma("unroll") for (int jj = 0; jj < 16; ++jj) { unsigned t_ = max(T[jj], X); X = min(T[jj], X); T[jj] = t_; } }
; __device__ __forceinline__ void route_task(const Params& p, int layer, const u16* qg, int rb, int hd, int r, int h) {
;     ...
;     for (int a = 0; a < 16; ++a) {
;       const float va = ord2f(top[0][a] & ~127u);
; #pragma unroll
;       for (int b = 0; b < 16; ++b) {
;         if ((a + 1) * (b + 1) <= 16) {
;           const float vb = ord2f(top[1][b] & ~127u);
;           unsigned key = (f2ord(va + vb) & ~255u) | (unsigned)(255 - (a * 16 + b));
;           INS32(ct, key);
;         }
;       }
;     }
	v_max_u32_e32 v13, v13, v21
	v_min_u32_e32 v21, v10, v19
	v_max_u32_e32 v10, v10, v19
	v_min_u32_e32 v19, v14, v18
	v_max_u32_e32 v14, v14, v18
	v_max_u32_e32 v9, v9, v16
	v_not_b32_e32 v16, v12
	v_or_b32_e32 v18, 0x80000000, v12
	v_cmp_gt_i32_e32 vcc, 0, v12
	v_add_f32_e32 v8, v11, v8
	v_add_f32_e32 v7, v11, v7
	v_cndmask_b32_e32 v12, v18, v16, vcc
	v_and_b32_e32 v12, 0xffffff00, v12
	v_or_b32_e32 v12, 0xeb, v12
	v_min_u32_e32 v16, v2, v12
	v_min_u32_e32 v18, v9, v16
	v_max_u32_e32 v9, v9, v16
	v_max_u32_e32 v2, v2, v12
	v_not_b32_e32 v12, v8
	v_or_b32_e32 v16, 0x80000000, v8
	v_cmp_gt_i32_e32 vcc, 0, v8
	v_add_f32_e32 v6, v11, v6
	v_min_u32_e32 v66, v64, v65
	v_cndmask_b32_e32 v8, v16, v12, vcc
	v_and_b32_e32 v8, 0xffffff00, v8
	v_or_b32_e32 v8, 0xea, v8
	v_min_u32_e32 v12, v2, v8
	v_min_u32_e32 v16, v9, v12
	v_max_u32_e32 v9, v9, v12
	v_max_u32_e32 v2, v2, v8
	v_not_b32_e32 v8, v7
	v_or_b32_e32 v12, 0x80000000, v7
	v_cmp_gt_i32_e32 vcc, 0, v7
	v_min_u32_e32 v67, v30, v31
	v_med3_u32 v64, v64, v65, v31
	v_cndmask_b32_e32 v7, v12, v8, vcc
	v_and_b32_e32 v7, 0xffffff00, v7
	v_or_b32_e32 v7, 0xe9, v7
	v_min_u32_e32 v8, v2, v7
	v_min_u32_e32 v12, v9, v8
	v_max_u32_e32 v8, v9, v8
	v_max_u32_e32 v2, v2, v7
	v_not_b32_e32 v7, v6
	v_or_b32_e32 v9, 0x80000000, v6
	v_cmp_gt_i32_e32 vcc, 0, v6
	v_max_u32_e32 v30, v30, v31
	v_min_u32_e32 v31, v28, v29
	v_cndmask_b32_e32 v6, v9, v7, vcc
	v_and_b32_e32 v6, 0xffffff00, v6
	v_max_u32_e32 v28, v28, v29
	v_min_u32_e32 v29, v26, v27
	v_max_u32_e32 v26, v26, v27
	v_or_b32_e32 v6, 0xe8, v6
	v_min_u32_e32 v65, v30, v31
	v_max_u32_e32 v30, v30, v31
	v_min_u32_e32 v31, v28, v29
	v_max_u32_e32 v28, v28, v29
	v_min_u32_e32 v27, v26, v25
	v_max_u32_e32 v25, v26, v25
	v_min_u32_e32 v26, v20, v24
	v_max_u32_e32 v20, v20, v24
	v_min_u32_e32 v24, v17, v22
	v_max_u32_e32 v17, v17, v22
	v_min_u32_e32 v22, v13, v21
	v_max_u32_e32 v13, v13, v21
	v_min_u32_e32 v21, v10, v19
	v_max_u32_e32 v10, v10, v19
	v_min_u32_e32 v19, v14, v18
	v_max_u32_e32 v14, v14, v18
	v_min_u32_e32 v7, v2, v6
	v_min_u32_e32 v29, v28, v27
	v_max_u32_e32 v27, v28, v27
	v_min_u32_e32 v28, v23, v26
	v_max_u32_e32 v23, v23, v26
	v_min_u32_e32 v26, v20, v24
	v_max_u32_e32 v20, v20, v24
	v_min_u32_e32 v24, v17, v22
	v_max_u32_e32 v17, v17, v22
	v_min_u32_e32 v22, v13, v21
	v_max_u32_e32 v13, v13, v21
	v_min_u32_e32 v21, v10, v19
	v_max_u32_e32 v10, v10, v19
	v_min_u32_e32 v18, v14, v16
	v_max_u32_e32 v14, v14, v16
	v_min_u32_e32 v9, v8, v7
	v_max_u32_e32 v7, v8, v7
	v_max_u32_e32 v2, v2, v6
	v_and_b32_e32 v6, 0x7fffff80, v45
	v_bitop3_b32 v8, v45, s52, v45 bitop3:0xcf
	v_cmp_gt_i32_e32 vcc, 0, v45
	v_min_u32_e32 v19, v10, v18
	v_max_u32_e32 v10, v10, v18
	v_min_u32_e32 v16, v14, v12
	v_max_u32_e32 v12, v14, v12
	v_cndmask_b32_e32 v6, v8, v6, vcc
	v_min_u32_e32 v18, v10, v16
	v_max_u32_e32 v10, v10, v16
	v_min_u32_e32 v11, v12, v9
	v_add_f32_e32 v8, v6, v1
	v_min_u32_e32 v14, v10, v11
	v_max_u32_e32 v10, v10, v11
	v_max_u32_e32 v9, v12, v9
	v_not_b32_e32 v11, v8
	v_or_b32_e32 v12, 0x80000000, v8
	v_cmp_gt_i32_e32 vcc, 0, v8
	v_min_u32_e32 v68, v66, v67
	v_min_u32_e32 v69, v64, v65
	v_cndmask_b32_e32 v8, v12, v11, vcc
	v_med3_u32 v66, v66, v67, v65
	v_max_u32_e32 v64, v64, v65
	v_min_u32_e32 v65, v30, v31
	v_max_u32_e32 v30, v30, v31
	v_and_b32_e32 v8, 0xffffff00, v8
	v_min_u32_e32 v31, v30, v29
	v_max_u32_e32 v29, v30, v29
	v_min_u32_e32 v30, v25, v28
	v_max_u32_e32 v25, v25, v28
	v_min_u32_e32 v28, v23, v26
	v_max_u32_e32 v23, v23, v26
	v_min_u32_e32 v26, v20, v24
	v_max_u32_e32 v20, v20, v24
	v_min_u32_e32 v24, v17, v22
	v_max_u32_e32 v17, v17, v22
	v_min_u32_e32 v22, v13, v21
	v_max_u32_e32 v13, v13, v21
	v_or_b32_e32 v8, 0xdf, v8
	v_min_u32_e32 v21, v13, v19
	v_max_u32_e32 v13, v13, v19
	v_min_u32_e32 v11, v2, v8
	v_min_u32_e32 v19, v13, v18
	v_max_u32_e32 v13, v13, v18
	v_min_u32_e32 v12, v7, v11
	v_max_u32_e32 v2, v2, v8
	v_add_f32_e32 v8, v6, v0
	v_min_u32_e32 v16, v13, v14
	v_max_u32_e32 v13, v13, v14
	v_min_u32_e32 v14, v9, v12
	v_max_u32_e32 v9, v9, v12
	v_max_u32_e32 v7, v7, v11
	v_not_b32_e32 v11, v8
	v_or_b32_e32 v12, 0x80000000, v8
	v_cmp_gt_i32_e32 vcc, 0, v8
	v_min_u32_e32 v67, v64, v65
	v_max_u32_e32 v64, v64, v65
	v_cndmask_b32_e32 v8, v12, v11, vcc
	v_and_b32_e32 v8, 0xffffff00, v8
	v_min_u32_e32 v65, v64, v31
	v_max_u32_e32 v31, v64, v31
	v_min_u32_e32 v64, v27, v30
	v_max_u32_e32 v27, v27, v30
	v_min_u32_e32 v30, v25, v28
	v_max_u32_e32 v25, v25, v28
	v_min_u32_e32 v28, v23, v26
	v_max_u32_e32 v23, v23, v26
	v_min_u32_e32 v26, v20, v24
	v_max_u32_e32 v20, v20, v24
	v_min_u32_e32 v24, v17, v22
	v_max_u32_e32 v17, v17, v22
	v_or_b32_e32 v8, 0xde, v8
	v_min_u32_e32 v22, v17, v21
	v_max_u32_e32 v17, v17, v21
	v_min_u32_e32 v11, v2, v8
	v_min_u32_e32 v21, v17, v19
	v_max_u32_e32 v17, v17, v19
	v_min_u32_e32 v12, v7, v11
	v_max_u32_e32 v2, v2, v8
	v_add_f32_e32 v8, v6, v3
	v_min_u32_e32 v18, v17, v16
	v_max_u32_e32 v16, v17, v16
	v_min_u32_e32 v17, v10, v14
	v_max_u32_e32 v10, v10, v14
	v_min_u32_e32 v14, v9, v12
	v_max_u32_e32 v9, v9, v12
	v_max_u32_e32 v7, v7, v11
	v_not_b32_e32 v11, v8
	v_or_b32_e32 v12, 0x80000000, v8
	v_cmp_gt_i32_e32 vcc, 0, v8
	v_min_u32_e32 v71, v66, v67
	v_max_u32_e32 v66, v66, v67
	v_cndmask_b32_e32 v8, v12, v11, vcc
	v_and_b32_e32 v8, 0xffffff00, v8
	v_min_u32_e32 v70, v68, v69
	v_med3_u32 v68, v68, v69, v67
	v_min_u32_e32 v67, v66, v65
	v_max_u32_e32 v65, v66, v65
	v_min_u32_e32 v66, v29, v64
	v_max_u32_e32 v29, v29, v64
	v_min_u32_e32 v64, v27, v30
	v_max_u32_e32 v27, v27, v30
	v_min_u32_e32 v30, v25, v28
	v_max_u32_e32 v25, v25, v28
	v_min_u32_e32 v28, v23, v26
	v_max_u32_e32 v23, v23, v26
; DI unsigned f2ord(float f) { unsigned u = __float_as_uint(f); return (u & 0x80000000u) ? ~u : (u | 0x80000000u); }
; DI float ord2f(unsigned u) { return __uint_as_float((u & 0x80000000u) ? (u & 0x7fffffffu) : ~u); }
; #define INS32(T, X) { _Pragma("unroll") for (int jj = 0; jj < 16; ++jj) { unsigned t_ = max(T[jj], X); X = min(T[jj], X); T[jj] = t_; } }
; __device__ __forceinline__ void route_task(const Params& p, int layer, const u16* qg, int rb, int hd, int r, int h) {
;     ...
;     for (int a = 0; a < 16; ++a) {
;       const float va = ord2f(top[0][a] & ~127u);
; #pragma unroll
;       for (int b = 0; b < 16; ++b) {
;         if ((a + 1) * (b + 1) <= 16) {
;           const float vb = ord2f(top[1][b] & ~127u);
;           unsigned key = (f2ord(va + vb) & ~255u) | (unsigned)(255 - (a * 16 + b));
;           INS32(ct, key);
;         }
;       }
;     }
	v_min_u32_e32 v26, v20, v24
	v_max_u32_e32 v20, v20, v24
	v_or_b32_e32 v8, 0xdd, v8
	v_min_u32_e32 v24, v20, v22
	v_max_u32_e32 v20, v20, v22
	v_min_u32_e32 v11, v2, v8
	v_min_u32_e32 v22, v20, v21
	v_max_u32_e32 v20, v20, v21
	v_min_u32_e32 v12, v7, v11
	v_max_u32_e32 v2, v2, v8
	v_add_f32_e32 v8, v6, v4
	v_min_u32_e32 v19, v20, v18
	v_max_u32_e32 v18, v20, v18
	v_min_u32_e32 v20, v13, v17
	v_max_u32_e32 v13, v13, v17
	v_min_u32_e32 v17, v10, v14
	v_max_u32_e32 v10, v10, v14
	v_min_u32_e32 v14, v9, v12
	v_max_u32_e32 v9, v9, v12
	v_max_u32_e32 v7, v7, v11
	v_not_b32_e32 v11, v8
	v_or_b32_e32 v12, 0x80000000, v8
	v_cmp_gt_i32_e32 vcc, 0, v8
	v_add_f32_e32 v5, v6, v5
	v_not_b32_e32 v6, v5
	v_cndmask_b32_e32 v8, v12, v11, vcc
	v_and_b32_e32 v8, 0xffffff00, v8
	v_or_b32_e32 v8, 0xdc, v8
	v_min_u32_e32 v11, v2, v8
	v_max_u32_e32 v2, v2, v8
	v_or_b32_e32 v8, 0x80000000, v5
	v_cmp_gt_i32_e32 vcc, 0, v5
	v_min_u32_e32 v72, v70, v71
	v_min_u32_e32 v69, v68, v67
	v_cndmask_b32_e32 v5, v8, v6, vcc
	v_and_b32_e32 v5, 0xffffff00, v5
	v_med3_u32 v70, v70, v71, v67
	v_max_u32_e32 v67, v68, v67
	v_min_u32_e32 v68, v31, v66
	v_max_u32_e32 v31, v31, v66
	v_min_u32_e32 v66, v29, v64
	v_max_u32_e32 v29, v29, v64
	v_min_u32_e32 v64, v27, v30
	v_max_u32_e32 v27, v27, v30
	v_min_u32_e32 v30, v25, v28
	v_max_u32_e32 v25, v25, v28
	v_min_u32_e32 v28, v23, v26
	v_max_u32_e32 v23, v23, v26
	v_or_b32_e32 v5, 0xdb, v5
	v_min_u32_e32 v71, v65, v68
	v_max_u32_e32 v65, v65, v68
	v_min_u32_e32 v68, v31, v66
	v_max_u32_e32 v31, v31, v66
	v_min_u32_e32 v66, v29, v64
	v_max_u32_e32 v29, v29, v64
	v_min_u32_e32 v64, v27, v30
	v_max_u32_e32 v27, v27, v30
	v_min_u32_e32 v30, v25, v28
	v_max_u32_e32 v25, v25, v28
	v_min_u32_e32 v26, v23, v24
	v_max_u32_e32 v23, v23, v24
	v_min_u32_e32 v12, v7, v11
	v_max_u32_e32 v7, v7, v11
	v_min_u32_e32 v6, v2, v5
	v_min_u32_e32 v28, v25, v26
	v_max_u32_e32 v25, v25, v26
	v_min_u32_e32 v24, v23, v22
	v_max_u32_e32 v22, v23, v22
	v_min_u32_e32 v8, v7, v6
	v_max_u32_e32 v6, v7, v6
	v_max_u32_e32 v2, v2, v5
	v_and_b32_e32 v5, 0x7fffff80, v44
	v_bitop3_b32 v7, v44, s52, v44 bitop3:0xcf
	v_cmp_gt_i32_e32 vcc, 0, v44
	v_min_u32_e32 v26, v25, v24
	v_max_u32_e32 v24, v25, v24
	v_min_u32_e32 v21, v22, v19
	v_max_u32_e32 v19, v22, v19
	v_min_u32_e32 v22, v16, v20
	v_max_u32_e32 v16, v16, v20
	v_min_u32_e32 v20, v13, v17
	v_max_u32_e32 v13, v13, v17
	v_min_u32_e32 v17, v10, v14
	v_max_u32_e32 v10, v10, v14
	v_min_u32_e32 v14, v9, v12
	v_max_u32_e32 v9, v9, v12
	v_cndmask_b32_e32 v5, v7, v5, vcc
	v_min_u32_e32 v23, v24, v21
	v_max_u32_e32 v21, v24, v21
	v_min_u32_e32 v24, v18, v22
	v_max_u32_e32 v18, v18, v22
	v_min_u32_e32 v22, v16, v20
	v_max_u32_e32 v16, v16, v20
	v_min_u32_e32 v20, v13, v17
	v_max_u32_e32 v13, v13, v17
	v_min_u32_e32 v17, v10, v14
	v_max_u32_e32 v10, v10, v14
	v_min_u32_e32 v11, v9, v8
	v_add_f32_e32 v7, v5, v1
	v_min_u32_e32 v12, v10, v11
	v_max_u32_e32 v10, v10, v11
	v_max_u32_e32 v8, v9, v8
	v_not_b32_e32 v9, v7
	v_or_b32_e32 v11, 0x80000000, v7
	v_cmp_gt_i32_e32 vcc, 0, v7
	v_min_u32_e32 v69, v72, v69
	v_min_u32_e32 v72, v67, v71
	v_cndmask_b32_e32 v7, v11, v9, vcc
	v_max_u32_e32 v67, v67, v71
	v_min_u32_e32 v71, v65, v68
	v_max_u32_e32 v65, v65, v68
	v_min_u32_e32 v68, v31, v66
	v_max_u32_e32 v31, v31, v66
	v_min_u32_e32 v66, v29, v64
	v_max_u32_e32 v29, v29, v64
	v_min_u32_e32 v64, v27, v30
	v_max_u32_e32 v27, v27, v30
	v_and_b32_e32 v7, 0xffffff00, v7
	v_min_u32_e32 v30, v27, v28
	v_max_u32_e32 v27, v27, v28
	v_or_b32_e32 v7, 0xcf, v7
	v_min_u32_e32 v28, v27, v26
	v_max_u32_e32 v26, v27, v26
	v_min_u32_e32 v9, v2, v7
	v_min_u32_e32 v25, v26, v23
	v_max_u32_e32 v23, v26, v23
	v_min_u32_e32 v26, v19, v24
	v_max_u32_e32 v19, v19, v24
	v_min_u32_e32 v24, v18, v22
	v_max_u32_e32 v18, v18, v22
	v_min_u32_e32 v22, v16, v20
	v_max_u32_e32 v16, v16, v20
	v_min_u32_e32 v20, v13, v17
	v_max_u32_e32 v13, v13, v17
	v_min_u32_e32 v11, v6, v9
	v_max_u32_e32 v2, v2, v7
	v_add_f32_e32 v7, v5, v0
	v_min_u32_e32 v14, v13, v12
	v_max_u32_e32 v12, v13, v12
	v_min_u32_e32 v13, v8, v11
	v_max_u32_e32 v8, v8, v11
	v_max_u32_e32 v6, v6, v9
	v_not_b32_e32 v9, v7
	v_or_b32_e32 v11, 0x80000000, v7
	v_cmp_gt_i32_e32 vcc, 0, v7
	v_min_u32_e32 v73, v70, v72
	v_max_u32_e32 v70, v70, v72
	v_cndmask_b32_e32 v7, v11, v9, vcc
	v_min_u32_e32 v72, v67, v71
	v_max_u32_e32 v67, v67, v71
	v_min_u32_e32 v71, v65, v68
	v_max_u32_e32 v65, v65, v68
	v_min_u32_e32 v68, v31, v66
	v_max_u32_e32 v31, v31, v66
	v_min_u32_e32 v66, v29, v64
	v_max_u32_e32 v29, v29, v64
	v_and_b32_e32 v7, 0xffffff00, v7
	v_min_u32_e32 v64, v29, v30
	v_max_u32_e32 v29, v29, v30
	v_or_b32_e32 v7, 0xce, v7
	v_min_u32_e32 v30, v29, v28
	v_max_u32_e32 v28, v29, v28
	v_min_u32_e32 v9, v2, v7
	v_min_u32_e32 v27, v28, v25
	v_max_u32_e32 v25, v28, v25
	v_min_u32_e32 v28, v21, v26
	v_max_u32_e32 v21, v21, v26
	v_min_u32_e32 v26, v19, v24
	v_max_u32_e32 v19, v19, v24
	v_min_u32_e32 v24, v18, v22
	v_max_u32_e32 v18, v18, v22
	v_min_u32_e32 v22, v16, v20
	v_max_u32_e32 v16, v16, v20
	v_min_u32_e32 v11, v6, v9
	v_max_u32_e32 v2, v2, v7
	v_add_f32_e32 v7, v5, v3
	v_min_u32_e32 v17, v16, v14
	v_max_u32_e32 v14, v16, v14
	v_min_u32_e32 v16, v10, v13
	v_max_u32_e32 v10, v10, v13
	v_min_u32_e32 v13, v8, v11
	v_max_u32_e32 v8, v8, v11
	v_max_u32_e32 v6, v6, v9
	v_not_b32_e32 v9, v7
	v_or_b32_e32 v11, 0x80000000, v7
	v_cmp_gt_i32_e32 vcc, 0, v7
	v_add_f32_e32 v4, v5, v4
	v_not_b32_e32 v5, v4
	v_cndmask_b32_e32 v7, v11, v9, vcc
	v_and_b32_e32 v7, 0xffffff00, v7
	v_or_b32_e32 v7, 0xcd, v7
	v_min_u32_e32 v9, v2, v7
	v_max_u32_e32 v2, v2, v7
	v_or_b32_e32 v7, 0x80000000, v4
	v_cmp_gt_i32_e32 vcc, 0, v4
; DI unsigned f2ord(float f) { unsigned u = __float_as_uint(f); return (u & 0x80000000u) ? ~u : (u | 0x80000000u); }
; DI float ord2f(unsigned u) { return __uint_as_float((u & 0x80000000u) ? (u & 0x7fffffffu) : ~u); }
; #define INS32(T, X) { _Pragma("unroll") for (int jj = 0; jj < 16; ++jj) { unsigned t_ = max(T[jj], X); X = min(T[jj], X); T[jj] = t_; } }
; __device__ __forceinline__ void route_task(const Params& p, int layer, const u16* qg, int rb, int hd, int r, int h) {
;     ...
;     for (int a = 0; a < 16; ++a) {
;       const float va = ord2f(top[0][a] & ~127u);
; #pragma unroll
;       for (int b = 0; b < 16; ++b) {
;         if ((a + 1) * (b + 1) <= 16) {
;           const float vb = ord2f(top[1][b] & ~127u);
;           unsigned key = (f2ord(va + vb) & ~255u) | (unsigned)(255 - (a * 16 + b));
;           INS32(ct, key);
;         }
;       }
;     }
	v_min_u32_e32 v74, v70, v72
	v_max_u32_e32 v70, v70, v72
	v_cndmask_b32_e32 v4, v7, v5, vcc
	v_min_u32_e32 v72, v67, v71
	v_max_u32_e32 v67, v67, v71
	v_min_u32_e32 v71, v65, v68
	v_max_u32_e32 v65, v65, v68
	v_min_u32_e32 v68, v31, v66
	v_max_u32_e32 v31, v31, v66
	v_and_b32_e32 v4, 0xffffff00, v4
	v_max3_u32 v69, v69, v73, v74
	v_min_u32_e32 v73, v70, v72
	v_max_u32_e32 v70, v70, v72
	v_min_u32_e32 v72, v67, v71
	v_max_u32_e32 v67, v67, v71
	v_min_u32_e32 v71, v65, v68
	v_max_u32_e32 v65, v65, v68
	v_min_u32_e32 v66, v31, v64
	v_max_u32_e32 v31, v31, v64
	v_or_b32_e32 v4, 0xcc, v4
	v_min_u32_e32 v68, v65, v66
	v_max_u32_e32 v65, v65, v66
	v_min_u32_e32 v64, v31, v30
	v_max_u32_e32 v30, v31, v30
	v_min_u32_e32 v11, v6, v9
	v_max_u32_e32 v6, v6, v9
	v_min_u32_e32 v5, v2, v4
	v_min_u32_e32 v66, v65, v64
	v_max_u32_e32 v64, v65, v64
	v_min_u32_e32 v29, v30, v27
	v_max_u32_e32 v27, v30, v27
	v_min_u32_e32 v30, v23, v28
	v_max_u32_e32 v23, v23, v28
	v_min_u32_e32 v28, v21, v26
	v_max_u32_e32 v21, v21, v26
	v_min_u32_e32 v26, v19, v24
	v_max_u32_e32 v19, v19, v24
	v_min_u32_e32 v24, v18, v22
	v_max_u32_e32 v18, v18, v22
	v_min_u32_e32 v7, v6, v5
	v_max_u32_e32 v5, v6, v5
	v_max_u32_e32 v2, v2, v4
	v_and_b32_e32 v4, 0x7fffff80, v43
	v_bitop3_b32 v6, v43, s52, v43 bitop3:0xcf
	v_cmp_gt_i32_e32 vcc, 0, v43
	v_min_u32_e32 v31, v64, v29
	v_max_u32_e32 v29, v64, v29
	v_min_u32_e32 v64, v25, v30
	v_max_u32_e32 v25, v25, v30
	v_min_u32_e32 v30, v23, v28
	v_max_u32_e32 v23, v23, v28
	v_min_u32_e32 v28, v21, v26
	v_max_u32_e32 v21, v21, v26
	v_min_u32_e32 v26, v19, v24
	v_max_u32_e32 v19, v19, v24
	v_min_u32_e32 v20, v18, v17
	v_max_u32_e32 v17, v18, v17
	v_min_u32_e32 v18, v12, v16
	v_max_u32_e32 v12, v12, v16
	v_min_u32_e32 v16, v10, v13
	v_max_u32_e32 v10, v10, v13
	v_min_u32_e32 v13, v8, v11
	v_max_u32_e32 v8, v8, v11
	v_cndmask_b32_e32 v4, v6, v4, vcc
	v_min_u32_e32 v22, v19, v20
	v_max_u32_e32 v19, v19, v20
	v_min_u32_e32 v20, v14, v18
	v_max_u32_e32 v14, v14, v18
	v_min_u32_e32 v18, v12, v16
	v_max_u32_e32 v12, v12, v16
	v_min_u32_e32 v16, v10, v13
	v_max_u32_e32 v10, v10, v13
	v_min_u32_e32 v9, v8, v7
	v_add_f32_e32 v6, v4, v1
	v_min_u32_e32 v11, v10, v9
	v_max_u32_e32 v9, v10, v9
	v_max_u32_e32 v7, v8, v7
	v_not_b32_e32 v8, v6
	v_or_b32_e32 v10, 0x80000000, v6
	v_cmp_gt_i32_e32 vcc, 0, v6
	v_min_u32_e32 v74, v70, v72
	v_max_u32_e32 v70, v70, v72
	v_min_u32_e32 v72, v67, v71
	v_max_u32_e32 v67, v67, v71
	v_cndmask_b32_e32 v6, v10, v8, vcc
	v_min_u32_e32 v71, v67, v68
	v_max_u32_e32 v67, v67, v68
	v_and_b32_e32 v6, 0xffffff00, v6
	v_min_u32_e32 v68, v67, v66
	v_max_u32_e32 v66, v67, v66
	v_or_b32_e32 v6, 0xbf, v6
	v_min_u32_e32 v65, v66, v31
	v_max_u32_e32 v31, v66, v31
	v_min_u32_e32 v66, v27, v64
	v_max_u32_e32 v27, v27, v64
	v_min_u32_e32 v64, v25, v30
	v_max_u32_e32 v25, v25, v30
	v_min_u32_e32 v30, v23, v28
	v_max_u32_e32 v23, v23, v28
	v_min_u32_e32 v28, v21, v26
	v_max_u32_e32 v21, v21, v26
	v_min_u32_e32 v8, v2, v6
	v_min_u32_e32 v24, v21, v22
	v_max_u32_e32 v21, v21, v22
	v_min_u32_e32 v22, v17, v20
	v_max_u32_e32 v17, v17, v20
	v_min_u32_e32 v20, v14, v18
	v_max_u32_e32 v14, v14, v18
	v_min_u32_e32 v18, v12, v16
	v_max_u32_e32 v12, v12, v16
	v_min_u32_e32 v10, v5, v8
	v_max_u32_e32 v2, v2, v6
	v_add_f32_e32 v6, v4, v0
	v_min_u32_e32 v13, v12, v11
	v_max_u32_e32 v11, v12, v11
	v_min_u32_e32 v12, v7, v10
	v_max_u32_e32 v7, v7, v10
	v_max_u32_e32 v5, v5, v8
	v_not_b32_e32 v8, v6
	v_or_b32_e32 v10, 0x80000000, v6
	v_cmp_gt_i32_e32 vcc, 0, v6
	v_add_f32_e32 v3, v4, v3
	v_not_b32_e32 v4, v3
	v_cndmask_b32_e32 v6, v10, v8, vcc
	v_and_b32_e32 v6, 0xffffff00, v6
	v_or_b32_e32 v6, 0xbe, v6
	v_min_u32_e32 v8, v2, v6
	v_max_u32_e32 v2, v2, v6
	v_or_b32_e32 v6, 0x80000000, v3
	v_cmp_gt_i32_e32 vcc, 0, v3
	v_max3_u32 v69, v69, v73, v74
	v_min_u32_e32 v73, v70, v72
	v_max_u32_e32 v70, v70, v72
	v_cndmask_b32_e32 v3, v6, v4, vcc
	v_min_u32_e32 v72, v70, v71
	v_max_u32_e32 v70, v70, v71
	v_and_b32_e32 v3, 0xffffff00, v3
	v_min_u32_e32 v71, v70, v68
	v_max_u32_e32 v68, v70, v68
	v_or_b32_e32 v3, 0xbd, v3
	v_max3_u32 v69, v69, v73, v72
	v_min_u32_e32 v67, v68, v65
	v_max_u32_e32 v65, v68, v65
	v_min_u32_e32 v68, v29, v66
	v_max_u32_e32 v29, v29, v66
	v_min_u32_e32 v66, v27, v64
	v_max_u32_e32 v27, v27, v64
	v_min_u32_e32 v64, v25, v30
	v_max_u32_e32 v25, v25, v30
	v_min_u32_e32 v30, v23, v28
	v_max_u32_e32 v23, v23, v28
	v_min_u32_e32 v10, v5, v8
	v_max_u32_e32 v5, v5, v8
	v_min_u32_e32 v4, v2, v3
	v_max3_u32 v67, v69, v71, v67
	v_min_u32_e32 v69, v31, v68
	v_max_u32_e32 v31, v31, v68
	v_min_u32_e32 v68, v29, v66
	v_max_u32_e32 v29, v29, v66
	v_min_u32_e32 v66, v27, v64
	v_max_u32_e32 v27, v27, v64
	v_min_u32_e32 v64, v25, v30
	v_max_u32_e32 v25, v25, v30
	v_min_u32_e32 v26, v23, v24
	v_max_u32_e32 v23, v23, v24
	v_min_u32_e32 v24, v19, v22
	v_max_u32_e32 v19, v19, v22
	v_min_u32_e32 v22, v17, v20
	v_max_u32_e32 v17, v17, v20
	v_min_u32_e32 v20, v14, v18
	v_max_u32_e32 v14, v14, v18
	v_min_u32_e32 v6, v5, v4
	v_max_u32_e32 v4, v5, v4
	v_max_u32_e32 v2, v2, v3
	v_and_b32_e32 v3, 0x7fffff80, v42
	v_bitop3_b32 v5, v42, s52, v42 bitop3:0xcf
	v_cmp_gt_i32_e32 vcc, 0, v42
	v_min_u32_e32 v28, v25, v26
	v_max_u32_e32 v25, v25, v26
	v_min_u32_e32 v26, v21, v24
	v_max_u32_e32 v21, v21, v24
	v_min_u32_e32 v24, v19, v22
	v_max_u32_e32 v19, v19, v22
	v_min_u32_e32 v22, v17, v20
	v_max_u32_e32 v17, v17, v20
	v_min_u32_e32 v16, v14, v13
	v_max_u32_e32 v13, v14, v13
	v_min_u32_e32 v14, v9, v12
	v_max_u32_e32 v9, v9, v12
	v_min_u32_e32 v12, v7, v10
	v_max_u32_e32 v7, v7, v10
	v_cndmask_b32_e32 v3, v5, v3, vcc
	v_min_u32_e32 v18, v17, v16
	v_max_u32_e32 v16, v17, v16
; DI unsigned f2ord(float f) { unsigned u = __float_as_uint(f); return (u & 0x80000000u) ? ~u : (u | 0x80000000u); }
; DI float ord2f(unsigned u) { return __uint_as_float((u & 0x80000000u) ? (u & 0x7fffffffu) : ~u); }
; #define INS32(T, X) { _Pragma("unroll") for (int jj = 0; jj < 16; ++jj) { unsigned t_ = max(T[jj], X); X = min(T[jj], X); T[jj] = t_; } }
; __device__ __forceinline__ void route_task(const Params& p, int layer, const u16* qg, int rb, int hd, int r, int h) {
;     ...
;     for (int a = 0; a < 16; ++a) {
;       const float va = ord2f(top[0][a] & ~127u);
; #pragma unroll
;       for (int b = 0; b < 16; ++b) {
;         if ((a + 1) * (b + 1) <= 16) {
;           const float vb = ord2f(top[1][b] & ~127u);
;           unsigned key = (f2ord(va + vb) & ~255u) | (unsigned)(255 - (a * 16 + b));
;           INS32(ct, key);
;         }
;       }
;     }
	v_min_u32_e32 v17, v11, v14
	v_max_u32_e32 v11, v11, v14
	v_min_u32_e32 v14, v9, v12
	v_max_u32_e32 v9, v9, v12
	v_min_u32_e32 v8, v7, v6
	v_add_f32_e32 v5, v3, v1
	v_min_u32_e32 v10, v9, v8
	v_max_u32_e32 v8, v9, v8
	v_max_u32_e32 v6, v7, v6
	v_not_b32_e32 v7, v5
	v_or_b32_e32 v9, 0x80000000, v5
	v_cmp_gt_i32_e32 vcc, 0, v5
	v_add_f32_e32 v3, v3, v0
	v_min_u32_e32 v70, v65, v69
	v_cndmask_b32_e32 v5, v9, v7, vcc
	v_and_b32_e32 v5, 0xffffff00, v5
	v_or_b32_e32 v5, 0xaf, v5
	v_min_u32_e32 v7, v2, v5
	v_min_u32_e32 v9, v4, v7
	v_max_u32_e32 v4, v4, v7
	v_max_u32_e32 v2, v2, v5
	v_not_b32_e32 v5, v3
	v_or_b32_e32 v7, 0x80000000, v3
	v_cmp_gt_i32_e32 vcc, 0, v3
	v_max_u32_e32 v65, v65, v69
	v_min_u32_e32 v69, v31, v68
	v_cndmask_b32_e32 v3, v7, v5, vcc
	v_and_b32_e32 v3, 0xffffff00, v3
	v_max_u32_e32 v31, v31, v68
	v_min_u32_e32 v68, v29, v66
	v_max_u32_e32 v29, v29, v66
	v_min_u32_e32 v66, v27, v64
	v_max_u32_e32 v27, v27, v64
	v_or_b32_e32 v3, 0xae, v3
	v_min_u32_e32 v71, v65, v69
	v_max_u32_e32 v65, v65, v69
	v_min_u32_e32 v69, v31, v68
	v_max_u32_e32 v31, v31, v68
	v_min_u32_e32 v68, v29, v66
	v_max_u32_e32 v29, v29, v66
	v_min_u32_e32 v30, v27, v28
	v_max_u32_e32 v27, v27, v28
	v_min_u32_e32 v28, v23, v26
	v_max_u32_e32 v23, v23, v26
	v_min_u32_e32 v26, v21, v24
	v_max_u32_e32 v21, v21, v24
	v_min_u32_e32 v24, v19, v22
	v_max_u32_e32 v19, v19, v22
	v_min_u32_e32 v5, v2, v3
	v_min_u32_e32 v64, v29, v30
	v_max_u32_e32 v29, v29, v30
	v_min_u32_e32 v30, v25, v28
	v_max_u32_e32 v25, v25, v28
	v_min_u32_e32 v28, v23, v26
	v_max_u32_e32 v23, v23, v26
	v_min_u32_e32 v26, v21, v24
	v_max_u32_e32 v21, v21, v24
	v_min_u32_e32 v20, v19, v18
	v_max_u32_e32 v18, v19, v18
	v_min_u32_e32 v19, v13, v17
	v_max_u32_e32 v13, v13, v17
	v_min_u32_e32 v17, v11, v14
	v_max_u32_e32 v11, v11, v14
	v_min_u32_e32 v7, v4, v5
	v_max_u32_e32 v4, v4, v5
	v_max_u32_e32 v2, v2, v3
	v_and_b32_e32 v3, 0x7fffff80, v41
	v_bitop3_b32 v5, v41, s52, v41 bitop3:0xcf
	v_cmp_gt_i32_e32 vcc, 0, v41
	v_min_u32_e32 v22, v21, v20
	v_max_u32_e32 v20, v21, v20
	v_min_u32_e32 v21, v16, v19
	v_max_u32_e32 v16, v16, v19
	v_min_u32_e32 v19, v13, v17
	v_max_u32_e32 v13, v13, v17
	v_min_u32_e32 v12, v11, v10
	v_max_u32_e32 v10, v11, v10
	v_min_u32_e32 v11, v6, v9
	v_max_u32_e32 v6, v6, v9
	v_cndmask_b32_e32 v3, v5, v3, vcc
	v_min_u32_e32 v14, v13, v12
	v_max_u32_e32 v12, v13, v12
	v_min_u32_e32 v13, v8, v11
	v_max_u32_e32 v8, v8, v11
	v_min_u32_e32 v9, v6, v7
	v_add_f32_e32 v5, v3, v1
	v_min_u32_e32 v11, v8, v9
	v_max_u32_e32 v8, v8, v9
	v_max_u32_e32 v6, v6, v7
	v_not_b32_e32 v7, v5
	v_or_b32_e32 v9, 0x80000000, v5
	v_cmp_gt_i32_e32 vcc, 0, v5
	v_add_f32_e32 v3, v3, v0
	v_max3_u32 v67, v67, v70, v71
	v_cndmask_b32_e32 v5, v9, v7, vcc
	v_and_b32_e32 v5, 0xffffff00, v5
	v_or_b32_e32 v5, 0x9f, v5
	v_min_u32_e32 v7, v2, v5
	v_min_u32_e32 v9, v4, v7
	v_max_u32_e32 v4, v4, v7
	v_max_u32_e32 v2, v2, v5
	v_not_b32_e32 v5, v3
	v_or_b32_e32 v7, 0x80000000, v3
	v_cmp_gt_i32_e32 vcc, 0, v3
	v_min_u32_e32 v70, v65, v69
	v_max_u32_e32 v65, v65, v69
	v_cndmask_b32_e32 v3, v7, v5, vcc
	v_min_u32_e32 v69, v31, v68
	v_max_u32_e32 v31, v31, v68
	v_and_b32_e32 v3, 0xffffff00, v3
	v_min_u32_e32 v71, v65, v69
	v_max_u32_e32 v65, v65, v69
	v_min_u32_e32 v66, v31, v64
	v_max_u32_e32 v31, v31, v64
	v_min_u32_e32 v64, v27, v30
	v_max_u32_e32 v27, v27, v30
	v_min_u32_e32 v30, v25, v28
	v_max_u32_e32 v25, v25, v28
	v_min_u32_e32 v28, v23, v26
	v_max_u32_e32 v23, v23, v26
	v_or_b32_e32 v3, 0x9e, v3
	v_min_u32_e32 v68, v65, v66
	v_max_u32_e32 v65, v65, v66
	v_min_u32_e32 v66, v29, v64
	v_max_u32_e32 v29, v29, v64
	v_min_u32_e32 v64, v27, v30
	v_max_u32_e32 v27, v27, v30
	v_min_u32_e32 v30, v25, v28
	v_max_u32_e32 v25, v25, v28
	v_min_u32_e32 v24, v23, v22
	v_max_u32_e32 v22, v23, v22
	v_min_u32_e32 v23, v18, v21
	v_max_u32_e32 v18, v18, v21
	v_min_u32_e32 v21, v16, v19
	v_max_u32_e32 v16, v16, v19
	v_min_u32_e32 v5, v2, v3
	v_min_u32_e32 v26, v25, v24
	v_max_u32_e32 v24, v25, v24
	v_min_u32_e32 v25, v20, v23
	v_max_u32_e32 v20, v20, v23
	v_min_u32_e32 v23, v18, v21
	v_max_u32_e32 v18, v18, v21
	v_min_u32_e32 v17, v16, v14
	v_max_u32_e32 v14, v16, v14
	v_min_u32_e32 v16, v10, v13
	v_max_u32_e32 v10, v10, v13
	v_min_u32_e32 v7, v4, v5
	v_max_u32_e32 v4, v4, v5
	v_max_u32_e32 v2, v2, v3
	v_and_b32_e32 v3, 0x7fffff80, v40
	v_bitop3_b32 v5, v40, s52, v40 bitop3:0xcf
	v_cmp_gt_i32_e32 vcc, 0, v40
	v_min_u32_e32 v19, v18, v17
	v_max_u32_e32 v17, v18, v17
	v_min_u32_e32 v18, v12, v16
	v_max_u32_e32 v12, v12, v16
	v_min_u32_e32 v13, v10, v11
	v_max_u32_e32 v10, v10, v11
	v_min_u32_e32 v11, v6, v9
	v_max_u32_e32 v6, v6, v9
	v_cndmask_b32_e32 v3, v5, v3, vcc
	v_min_u32_e32 v16, v12, v13
	v_max_u32_e32 v12, v12, v13
	v_min_u32_e32 v13, v8, v11
	v_max_u32_e32 v8, v8, v11
	v_min_u32_e32 v9, v6, v7
	v_add_f32_e32 v5, v3, v1
	v_min_u32_e32 v11, v8, v9
	v_max_u32_e32 v8, v8, v9
	v_max_u32_e32 v6, v6, v7
	v_not_b32_e32 v7, v5
	v_or_b32_e32 v9, 0x80000000, v5
	v_cmp_gt_i32_e32 vcc, 0, v5
	v_add_f32_e32 v0, v3, v0
	v_not_b32_e32 v3, v0
	v_cndmask_b32_e32 v5, v9, v7, vcc
	v_and_b32_e32 v5, 0xffffff00, v5
	v_or_b32_e32 v5, 0x8f, v5
	v_min_u32_e32 v7, v2, v5
	v_max_u32_e32 v2, v2, v5
	v_or_b32_e32 v5, 0x80000000, v0
	v_cmp_gt_i32_e32 vcc, 0, v0
	v_min_u32_e32 v69, v31, v66
	v_max_u32_e32 v31, v31, v66
	v_cndmask_b32_e32 v0, v5, v3, vcc
	v_and_b32_e32 v0, 0xffffff00, v0
	v_min_u32_e32 v66, v29, v64
	v_max_u32_e32 v29, v29, v64
	v_min_u32_e32 v64, v27, v30
	v_max_u32_e32 v27, v27, v30
	v_or_b32_e32 v0, 0x8e, v0
	v_min_u32_e32 v28, v27, v26
	v_max_u32_e32 v26, v27, v26
	v_min_u32_e32 v27, v22, v25
	v_max_u32_e32 v22, v22, v25
	v_min_u32_e32 v25, v20, v23
; DI unsigned f2ord(float f) { unsigned u = __float_as_uint(f); return (u & 0x80000000u) ? ~u : (u | 0x80000000u); }
; DI float ord2f(unsigned u) { return __uint_as_float((u & 0x80000000u) ? (u & 0x7fffffffu) : ~u); }
; #define INS32(T, X) { _Pragma("unroll") for (int jj = 0; jj < 16; ++jj) { unsigned t_ = max(T[jj], X); X = min(T[jj], X); T[jj] = t_; } }
; __device__ __forceinline__ void route_task(const Params& p, int layer, const u16* qg, int rb, int hd, int r, int h) {
;     ...
;     for (int a = 0; a < 16; ++a) {
;       const float va = ord2f(top[0][a] & ~127u);
; #pragma unroll
;       for (int b = 0; b < 16; ++b) {
;         if ((a + 1) * (b + 1) <= 16) {
;           const float vb = ord2f(top[1][b] & ~127u);
;           unsigned key = (f2ord(va + vb) & ~255u) | (unsigned)(255 - (a * 16 + b));
;           INS32(ct, key);
;         }
;       }
;     }
	v_max_u32_e32 v20, v20, v23
	v_min_u32_e32 v9, v4, v7
	v_max_u32_e32 v4, v4, v7
	v_min_u32_e32 v3, v2, v0
	v_min_u32_e32 v21, v20, v19
	v_max_u32_e32 v19, v20, v19
	v_min_u32_e32 v20, v14, v18
	v_max_u32_e32 v14, v14, v18
	v_min_u32_e32 v5, v4, v3
	v_max_u32_e32 v3, v4, v3
	v_max_u32_e32 v0, v2, v0
	v_and_b32_e32 v2, 0x7fffff80, v39
	v_bitop3_b32 v4, v39, s52, v39 bitop3:0xcf
	v_cmp_gt_i32_e32 vcc, 0, v39
	v_min_u32_e32 v18, v14, v16
	v_max_u32_e32 v14, v14, v16
	v_min_u32_e32 v16, v10, v13
	v_max_u32_e32 v10, v10, v13
	v_cndmask_b32_e32 v2, v4, v2, vcc
	v_min_u32_e32 v13, v10, v11
	v_max_u32_e32 v10, v10, v11
	v_min_u32_e32 v11, v6, v9
	v_max_u32_e32 v6, v6, v9
	v_add_f32_e32 v2, v2, v1
	v_min_u32_e32 v7, v6, v5
	v_max_u32_e32 v5, v6, v5
	v_not_b32_e32 v4, v2
	v_or_b32_e32 v6, 0x80000000, v2
	v_cmp_gt_i32_e32 vcc, 0, v2
	v_max3_u32 v67, v67, v70, v71
	v_min_u32_e32 v70, v65, v69
	v_cndmask_b32_e32 v2, v6, v4, vcc
	v_and_b32_e32 v2, 0xffffff00, v2
	v_max3_u32 v67, v67, v68, v70
	v_min_u32_e32 v68, v31, v66
	v_max_u32_e32 v31, v31, v66
	v_min_u32_e32 v66, v29, v64
	v_max_u32_e32 v29, v29, v64
	v_or_b32_e32 v2, 0x7f, v2
	v_min_u32_e32 v30, v29, v28
	v_max_u32_e32 v28, v29, v28
	v_min_u32_e32 v29, v24, v27
	v_max_u32_e32 v24, v24, v27
	v_min_u32_e32 v27, v22, v25
	v_max_u32_e32 v22, v22, v25
	v_min_u32_e32 v4, v0, v2
	v_min_u32_e32 v23, v22, v21
	v_max_u32_e32 v21, v22, v21
	v_min_u32_e32 v22, v17, v20
	v_max_u32_e32 v17, v17, v20
	v_min_u32_e32 v6, v3, v4
	v_max_u32_e32 v3, v3, v4
	v_max_u32_e32 v0, v0, v2
	v_and_b32_e32 v2, 0x7fffff80, v38
	v_bitop3_b32 v4, v38, s52, v38 bitop3:0xcf
	v_cmp_gt_i32_e32 vcc, 0, v38
	v_min_u32_e32 v20, v17, v18
	v_max_u32_e32 v17, v17, v18
	v_min_u32_e32 v18, v12, v16
	v_max_u32_e32 v12, v12, v16
	v_cndmask_b32_e32 v2, v4, v2, vcc
	v_min_u32_e32 v16, v12, v13
	v_max_u32_e32 v12, v12, v13
	v_min_u32_e32 v13, v8, v11
	v_max_u32_e32 v8, v8, v11
	v_add_f32_e32 v2, v2, v1
	v_min_u32_e32 v9, v8, v7
	v_max_u32_e32 v7, v8, v7
	v_min_u32_e32 v8, v5, v6
	v_max_u32_e32 v5, v5, v6
	v_not_b32_e32 v4, v2
	v_or_b32_e32 v6, 0x80000000, v2
	v_cmp_gt_i32_e32 vcc, 0, v2
	v_max_u32_e32 v65, v65, v69
	v_min_u32_e32 v69, v65, v68
	v_cndmask_b32_e32 v2, v6, v4, vcc
	v_and_b32_e32 v2, 0xffffff00, v2
	v_max_u32_e32 v65, v65, v68
	v_min_u32_e32 v68, v31, v66
	v_max_u32_e32 v31, v31, v66
	v_or_b32_e32 v2, 0x6f, v2
	v_min_u32_e32 v64, v31, v30
	v_max_u32_e32 v30, v31, v30
	v_min_u32_e32 v31, v26, v29
	v_max_u32_e32 v26, v26, v29
	v_min_u32_e32 v29, v24, v27
	v_max_u32_e32 v24, v24, v27
	v_min_u32_e32 v4, v0, v2
	v_min_u32_e32 v25, v24, v23
	v_max_u32_e32 v23, v24, v23
	v_min_u32_e32 v24, v19, v22
	v_max_u32_e32 v19, v19, v22
	v_min_u32_e32 v6, v3, v4
	v_max_u32_e32 v3, v3, v4
	v_max_u32_e32 v0, v0, v2
	v_and_b32_e32 v2, 0x7fffff80, v37
	v_bitop3_b32 v4, v37, s52, v37 bitop3:0xcf
	v_cmp_gt_i32_e32 vcc, 0, v37
	v_min_u32_e32 v22, v19, v20
	v_max_u32_e32 v19, v19, v20
	v_min_u32_e32 v20, v14, v18
	v_max_u32_e32 v14, v14, v18
	v_cndmask_b32_e32 v2, v4, v2, vcc
	v_min_u32_e32 v18, v14, v16
	v_max_u32_e32 v14, v14, v16
	v_min_u32_e32 v16, v10, v13
	v_max_u32_e32 v10, v10, v13
	v_add_f32_e32 v2, v2, v1
	v_min_u32_e32 v11, v10, v9
	v_max_u32_e32 v9, v10, v9
	v_min_u32_e32 v10, v7, v8
	v_max_u32_e32 v7, v7, v8
	v_min_u32_e32 v8, v5, v6
	v_max_u32_e32 v5, v5, v6
	v_not_b32_e32 v4, v2
	v_or_b32_e32 v6, 0x80000000, v2
	v_cmp_gt_i32_e32 vcc, 0, v2
	v_min_u32_e32 v70, v65, v68
	v_max_u32_e32 v65, v65, v68
	v_cndmask_b32_e32 v2, v6, v4, vcc
	v_and_b32_e32 v2, 0xffffff00, v2
	v_or_b32_e32 v2, 0x5f, v2
	v_min_u32_e32 v66, v65, v64
	v_max_u32_e32 v64, v65, v64
	v_min_u32_e32 v65, v28, v31
	v_max_u32_e32 v28, v28, v31
	v_min_u32_e32 v31, v26, v29
	v_max_u32_e32 v26, v26, v29
	v_min_u32_e32 v4, v0, v2
	v_min_u32_e32 v27, v26, v25
	v_max_u32_e32 v25, v26, v25
	v_min_u32_e32 v26, v21, v24
	v_max_u32_e32 v21, v21, v24
	v_min_u32_e32 v6, v3, v4
	v_max_u32_e32 v3, v3, v4
	v_max_u32_e32 v0, v0, v2
	v_and_b32_e32 v2, 0x7fffff80, v36
	v_bitop3_b32 v4, v36, s52, v36 bitop3:0xcf
	v_cmp_gt_i32_e32 vcc, 0, v36
	v_min_u32_e32 v24, v21, v22
	v_max_u32_e32 v21, v21, v22
	v_min_u32_e32 v22, v17, v20
	v_max_u32_e32 v17, v17, v20
	v_cndmask_b32_e32 v2, v4, v2, vcc
	v_min_u32_e32 v20, v17, v18
	v_max_u32_e32 v17, v17, v18
	v_min_u32_e32 v18, v12, v16
	v_max_u32_e32 v12, v12, v16
	v_add_f32_e32 v2, v2, v1
	v_min_u32_e32 v13, v12, v11
	v_max_u32_e32 v11, v12, v11
	v_min_u32_e32 v12, v9, v10
	v_max_u32_e32 v9, v9, v10
	v_min_u32_e32 v10, v7, v8
	v_max_u32_e32 v7, v7, v8
	v_min_u32_e32 v8, v5, v6
	v_max_u32_e32 v5, v5, v6
	v_not_b32_e32 v4, v2
	v_or_b32_e32 v6, 0x80000000, v2
	v_cmp_gt_i32_e32 vcc, 0, v2
	v_min_u32_e32 v68, v30, v65
	v_max_u32_e32 v30, v30, v65
	v_cndmask_b32_e32 v2, v6, v4, vcc
	v_and_b32_e32 v2, 0xffffff00, v2
	v_or_b32_e32 v2, 0x4f, v2
	v_min_u32_e32 v65, v28, v31
	v_max_u32_e32 v28, v28, v31
	v_min_u32_e32 v4, v0, v2
	v_min_u32_e32 v29, v28, v27
	v_max_u32_e32 v27, v28, v27
	v_min_u32_e32 v28, v23, v26
	v_max_u32_e32 v23, v23, v26
	v_min_u32_e32 v6, v3, v4
	v_max_u32_e32 v3, v3, v4
	v_max_u32_e32 v0, v0, v2
	v_and_b32_e32 v2, 0x7fffff80, v35
	v_bitop3_b32 v4, v35, s52, v35 bitop3:0xcf
	v_cmp_gt_i32_e32 vcc, 0, v35
	v_min_u32_e32 v26, v23, v24
	v_max_u32_e32 v23, v23, v24
	v_min_u32_e32 v24, v19, v22
	v_max_u32_e32 v19, v19, v22
	v_cndmask_b32_e32 v2, v4, v2, vcc
	v_min_u32_e32 v22, v19, v20
	v_max_u32_e32 v19, v19, v20
	v_min_u32_e32 v20, v14, v18
	v_max_u32_e32 v14, v14, v18
	v_add_f32_e32 v2, v2, v1
	v_min_u32_e32 v16, v14, v13
	v_max_u32_e32 v13, v14, v13
	v_min_u32_e32 v14, v11, v12
	v_max_u32_e32 v11, v11, v12
	v_min_u32_e32 v12, v9, v10
; DI unsigned f2ord(float f) { unsigned u = __float_as_uint(f); return (u & 0x80000000u) ? ~u : (u | 0x80000000u); }
; DI float ord2f(unsigned u) { return __uint_as_float((u & 0x80000000u) ? (u & 0x7fffffffu) : ~u); }
; #define INS32(T, X) { _Pragma("unroll") for (int jj = 0; jj < 16; ++jj) { unsigned t_ = max(T[jj], X); X = min(T[jj], X); T[jj] = t_; } }
; __device__ __forceinline__ void route_task(const Params& p, int layer, const u16* qg, int rb, int hd, int r, int h) {
;     ...
;     for (int a = 0; a < 16; ++a) {
;       const float va = ord2f(top[0][a] & ~127u);
; #pragma unroll
;       for (int b = 0; b < 16; ++b) {
;         if ((a + 1) * (b + 1) <= 16) {
;           const float vb = ord2f(top[1][b] & ~127u);
;           unsigned key = (f2ord(va + vb) & ~255u) | (unsigned)(255 - (a * 16 + b));
;           INS32(ct, key);
;         }
;       }
;     }
	v_max_u32_e32 v9, v9, v10
	v_min_u32_e32 v10, v7, v8
	v_max_u32_e32 v7, v7, v8
	v_min_u32_e32 v8, v5, v6
	v_max_u32_e32 v5, v5, v6
	v_not_b32_e32 v4, v2
	v_or_b32_e32 v6, 0x80000000, v2
	v_cmp_gt_i32_e32 vcc, 0, v2
	v_max3_u32 v67, v67, v69, v70
	v_min_u32_e32 v69, v64, v68
	v_cndmask_b32_e32 v2, v6, v4, vcc
	v_and_or_b32 v2, v2, s69, 63
	v_max3_u32 v66, v67, v66, v69
	v_min_u32_e32 v67, v30, v65
	v_max_u32_e32 v30, v30, v65
	v_min_u32_e32 v4, v0, v2
	v_min_u32_e32 v31, v30, v29
	v_max_u32_e32 v29, v30, v29
	v_min_u32_e32 v30, v25, v28
	v_max_u32_e32 v25, v25, v28
	v_min_u32_e32 v6, v3, v4
	v_max_u32_e32 v3, v3, v4
	v_max_u32_e32 v0, v0, v2
	v_and_b32_e32 v2, 0x7fffff80, v34
	v_bitop3_b32 v4, v34, s52, v34 bitop3:0xcf
	v_cmp_gt_i32_e32 vcc, 0, v34
	v_min_u32_e32 v28, v25, v26
	v_max_u32_e32 v25, v25, v26
	v_min_u32_e32 v26, v21, v24
	v_max_u32_e32 v21, v21, v24
	v_cndmask_b32_e32 v2, v4, v2, vcc
	v_min_u32_e32 v24, v21, v22
	v_max_u32_e32 v21, v21, v22
	v_min_u32_e32 v22, v17, v20
	v_max_u32_e32 v17, v17, v20
	v_add_f32_e32 v2, v2, v1
	v_min_u32_e32 v18, v17, v16
	v_max_u32_e32 v16, v17, v16
	v_min_u32_e32 v17, v13, v14
	v_max_u32_e32 v13, v13, v14
	v_min_u32_e32 v14, v11, v12
	v_max_u32_e32 v11, v11, v12
	v_min_u32_e32 v12, v9, v10
	v_max_u32_e32 v9, v9, v10
	v_min_u32_e32 v10, v7, v8
	v_max_u32_e32 v7, v7, v8
	v_min_u32_e32 v8, v5, v6
	v_max_u32_e32 v5, v5, v6
	v_not_b32_e32 v4, v2
	v_or_b32_e32 v6, 0x80000000, v2
	v_cmp_gt_i32_e32 vcc, 0, v2
	v_max_u32_e32 v64, v64, v68
	v_min_u32_e32 v68, v64, v67
	v_cndmask_b32_e32 v2, v6, v4, vcc
	v_and_or_b32 v2, v2, s69, 47
	v_max_u32_e32 v64, v64, v67
	v_min_u32_e32 v4, v0, v2
	v_min_u32_e32 v65, v64, v31
	v_max_u32_e32 v31, v64, v31
	v_min_u32_e32 v64, v27, v30
	v_max_u32_e32 v27, v27, v30
	v_min_u32_e32 v6, v3, v4
	v_max_u32_e32 v3, v3, v4
	v_max_u32_e32 v0, v0, v2
	v_and_b32_e32 v2, 0x7fffff80, v33
	v_bitop3_b32 v4, v33, s52, v33 bitop3:0xcf
	v_cmp_gt_i32_e32 vcc, 0, v33
	v_min_u32_e32 v30, v27, v28
	v_max_u32_e32 v27, v27, v28
	v_min_u32_e32 v28, v23, v26
	v_max_u32_e32 v23, v23, v26
	v_cndmask_b32_e32 v2, v4, v2, vcc
	v_min_u32_e32 v26, v23, v24
	v_max_u32_e32 v23, v23, v24
	v_min_u32_e32 v24, v19, v22
	v_max_u32_e32 v19, v19, v22
	v_add_f32_e32 v2, v2, v1
	v_min_u32_e32 v20, v19, v18
	v_max_u32_e32 v18, v19, v18
	v_min_u32_e32 v19, v16, v17
	v_max_u32_e32 v16, v16, v17
	v_min_u32_e32 v17, v13, v14
	v_max_u32_e32 v13, v13, v14
	v_min_u32_e32 v14, v11, v12
	v_max_u32_e32 v11, v11, v12
	v_min_u32_e32 v12, v9, v10
	v_max_u32_e32 v9, v9, v10
	v_min_u32_e32 v10, v7, v8
	v_max_u32_e32 v7, v7, v8
	v_min_u32_e32 v8, v5, v6
	v_max_u32_e32 v5, v5, v6
	v_not_b32_e32 v4, v2
	v_or_b32_e32 v6, 0x80000000, v2
	v_cmp_gt_i32_e32 vcc, 0, v2
	v_max3_u32 v65, v66, v68, v65
	v_min_u32_e32 v66, v29, v64
	v_cndmask_b32_e32 v2, v6, v4, vcc
	v_max_u32_e32 v29, v29, v64
	v_and_or_b32 v2, v2, s69, 31
	v_min_u32_e32 v67, v31, v66
	v_max_u32_e32 v31, v31, v66
	v_min_u32_e32 v64, v29, v30
	v_max_u32_e32 v29, v29, v30
	v_min_u32_e32 v30, v25, v28
	v_max_u32_e32 v25, v25, v28
	v_min_u32_e32 v4, v0, v2
	v_min_u32_e32 v66, v31, v64
	v_max_u32_e32 v31, v31, v64
	v_min_u32_e32 v64, v27, v30
	v_max_u32_e32 v27, v27, v30
	v_min_u32_e32 v28, v25, v26
	v_max_u32_e32 v25, v25, v26
	v_min_u32_e32 v26, v21, v24
	v_max_u32_e32 v21, v21, v24
	v_min_u32_e32 v6, v3, v4
	v_max3_u32 v65, v65, v67, v66
	v_min_u32_e32 v66, v29, v64
	v_max_u32_e32 v29, v29, v64
	v_min_u32_e32 v30, v27, v28
	v_max_u32_e32 v27, v27, v28
	v_min_u32_e32 v28, v23, v26
	v_max_u32_e32 v23, v23, v26
	v_min_u32_e32 v22, v21, v20
	v_max_u32_e32 v20, v21, v20
	v_min_u32_e32 v21, v18, v19
	v_max_u32_e32 v18, v18, v19
	v_min_u32_e32 v19, v16, v17
	v_max_u32_e32 v16, v16, v17
	v_min_u32_e32 v17, v13, v14
	v_max_u32_e32 v13, v13, v14
	v_min_u32_e32 v14, v11, v12
	v_max_u32_e32 v11, v11, v12
	v_min_u32_e32 v12, v9, v10
	v_max_u32_e32 v9, v9, v10
	v_min_u32_e32 v10, v7, v8
	v_max_u32_e32 v7, v7, v8
	v_min_u32_e32 v8, v5, v6
	v_min_u32_e32 v67, v31, v66
	v_max_u32_e32 v31, v31, v66
	v_min_u32_e32 v64, v29, v30
	v_max_u32_e32 v29, v29, v30
	v_min_u32_e32 v30, v25, v28
	v_max_u32_e32 v25, v25, v28
	v_min_u32_e32 v24, v23, v22
	v_max_u32_e32 v22, v23, v22
	v_min_u32_e32 v23, v20, v21
	v_max_u32_e32 v20, v20, v21
	v_min_u32_e32 v21, v18, v19
	v_max_u32_e32 v18, v18, v19
	v_min_u32_e32 v19, v16, v17
	v_max_u32_e32 v16, v16, v17
	v_min_u32_e32 v17, v13, v14
	v_max_u32_e32 v13, v13, v14
	v_min_u32_e32 v14, v11, v12
	v_max_u32_e32 v11, v11, v12
	v_min_u32_e32 v12, v9, v10
	v_max_u32_e32 v9, v9, v10
	v_min_u32_e32 v10, v7, v8
	v_max_u32_e32 v3, v3, v4
	v_max_u32_e32 v0, v0, v2
	v_and_b32_e32 v2, 0x7fffff80, v15
	v_bitop3_b32 v4, v15, s52, v15 bitop3:0xcf
	v_cmp_gt_i32_e32 vcc, 0, v15
	v_min_u32_e32 v66, v31, v64
	v_max_u32_e32 v31, v31, v64
	v_min_u32_e32 v64, v27, v30
	v_max_u32_e32 v27, v27, v30
	v_min_u32_e32 v26, v25, v24
	v_max_u32_e32 v24, v25, v24
	v_min_u32_e32 v25, v22, v23
	v_max_u32_e32 v22, v22, v23
	v_min_u32_e32 v23, v20, v21
	v_max_u32_e32 v20, v20, v21
	v_min_u32_e32 v21, v18, v19
	v_max_u32_e32 v18, v18, v19
	v_min_u32_e32 v19, v16, v17
	v_max_u32_e32 v16, v16, v17
	v_min_u32_e32 v17, v13, v14
	v_max_u32_e32 v13, v13, v14
	v_min_u32_e32 v14, v11, v12
	v_max_u32_e32 v11, v11, v12
	v_min_u32_e32 v12, v9, v10
	v_cndmask_b32_e32 v2, v4, v2, vcc
	v_max3_u32 v65, v65, v67, v66
	v_min_u32_e32 v66, v29, v64
	v_max_u32_e32 v29, v29, v64
	v_min_u32_e32 v28, v27, v26
	v_max_u32_e32 v26, v27, v26
	v_min_u32_e32 v27, v24, v25
	v_max_u32_e32 v24, v24, v25
	v_min_u32_e32 v25, v22, v23
	v_max_u32_e32 v22, v22, v23
	v_min_u32_e32 v23, v20, v21
	v_max_u32_e32 v20, v20, v21
; DI unsigned f2ord(float f) { unsigned u = __float_as_uint(f); return (u & 0x80000000u) ? ~u : (u | 0x80000000u); }
; DI float ord2f(unsigned u) { return __uint_as_float((u & 0x80000000u) ? (u & 0x7fffffffu) : ~u); }
; #define INS32(T, X) { _Pragma("unroll") for (int jj = 0; jj < 16; ++jj) { unsigned t_ = max(T[jj], X); X = min(T[jj], X); T[jj] = t_; } }
; __device__ __forceinline__ void route_task(const Params& p, int layer, const u16* qg, int rb, int hd, int r, int h) {
;     ...
;     for (int a = 0; a < 16; ++a) {
;       const float va = ord2f(top[0][a] & ~127u);
; #pragma unroll
;       for (int b = 0; b < 16; ++b) {
;         if ((a + 1) * (b + 1) <= 16) {
;           const float vb = ord2f(top[1][b] & ~127u);
;           unsigned key = (f2ord(va + vb) & ~255u) | (unsigned)(255 - (a * 16 + b));
;           INS32(ct, key);
;         }
;       }
;     }
;     const float v0 = ord2f(ct[0] & ~255u);
;     float vs[16];
;     float den = 0.f;
; #pragma unroll
;     for (int jj = 0; jj < 16; ++jj) { vs[jj] = __expf(ord2f(ct[jj] & ~255u) - v0); den += vs[jj]; }
	v_min_u32_e32 v21, v18, v19
	v_max_u32_e32 v18, v18, v19
	v_min_u32_e32 v19, v16, v17
	v_max_u32_e32 v16, v16, v17
	v_min_u32_e32 v17, v13, v14
	v_max_u32_e32 v13, v13, v14
	v_min_u32_e32 v14, v11, v12
	v_add_f32_e32 v1, v2, v1
	v_min_u32_e32 v67, v31, v66
	v_max_u32_e32 v31, v31, v66
	v_min_u32_e32 v30, v29, v28
	v_max_u32_e32 v28, v29, v28
	v_min_u32_e32 v29, v26, v27
	v_max_u32_e32 v26, v26, v27
	v_min_u32_e32 v27, v24, v25
	v_max_u32_e32 v24, v24, v25
	v_min_u32_e32 v25, v22, v23
	v_max_u32_e32 v22, v22, v23
	v_min_u32_e32 v23, v20, v21
	v_max_u32_e32 v20, v20, v21
	v_min_u32_e32 v21, v18, v19
	v_max_u32_e32 v18, v18, v19
	v_min_u32_e32 v19, v16, v17
	v_max_u32_e32 v16, v16, v17
	v_min_u32_e32 v17, v13, v14
	v_not_b32_e32 v2, v1
	v_or_b32_e32 v4, 0x80000000, v1
	v_cmp_gt_i32_e32 vcc, 0, v1
	v_min_u32_e32 v64, v31, v30
	v_max_u32_e32 v30, v31, v30
	v_min_u32_e32 v31, v28, v29
	v_max_u32_e32 v28, v28, v29
	v_min_u32_e32 v29, v26, v27
	v_max_u32_e32 v26, v26, v27
	v_min_u32_e32 v27, v24, v25
	v_max_u32_e32 v24, v24, v25
	v_min_u32_e32 v25, v22, v23
	v_max_u32_e32 v22, v22, v23
	v_min_u32_e32 v23, v20, v21
	v_max_u32_e32 v20, v20, v21
	v_min_u32_e32 v21, v18, v19
	v_max_u32_e32 v18, v18, v19
	v_min_u32_e32 v19, v16, v17
	v_cndmask_b32_e32 v1, v4, v2, vcc
	v_max3_u32 v64, v65, v67, v64
	v_min_u32_e32 v65, v30, v31
	v_max_u32_e32 v30, v30, v31
	v_min_u32_e32 v31, v28, v29
	v_max_u32_e32 v28, v28, v29
	v_min_u32_e32 v29, v26, v27
	v_max_u32_e32 v26, v26, v27
	v_min_u32_e32 v27, v24, v25
	v_max_u32_e32 v24, v24, v25
	v_min_u32_e32 v25, v22, v23
	v_max_u32_e32 v22, v22, v23
	v_min_u32_e32 v23, v20, v21
	v_max_u32_e32 v20, v20, v21
	v_min_u32_e32 v21, v18, v19
	v_and_or_b32 v1, v1, s69, 15
	v_min_u32_e32 v66, v30, v31
	v_max_u32_e32 v30, v30, v31
	v_min_u32_e32 v31, v28, v29
	v_max_u32_e32 v28, v28, v29
	v_min_u32_e32 v29, v26, v27
	v_max_u32_e32 v26, v26, v27
	v_min_u32_e32 v27, v24, v25
	v_max_u32_e32 v24, v24, v25
	v_min_u32_e32 v25, v22, v23
	v_max_u32_e32 v22, v22, v23
	v_min_u32_e32 v23, v20, v21
	v_min_u32_e32 v2, v0, v1
	v_max3_u32 v64, v64, v65, v66
	v_min_u32_e32 v65, v30, v31
	v_max_u32_e32 v30, v30, v31
	v_min_u32_e32 v31, v28, v29
	v_max_u32_e32 v28, v28, v29
	v_min_u32_e32 v29, v26, v27
	v_max_u32_e32 v26, v26, v27
	v_min_u32_e32 v27, v24, v25
	v_max_u32_e32 v24, v24, v25
	v_min_u32_e32 v25, v22, v23
	v_max_u32_e32 v5, v5, v6
	v_min_u32_e32 v4, v3, v2
	v_min_u32_e32 v66, v30, v31
	v_max_u32_e32 v30, v30, v31
	v_min_u32_e32 v31, v28, v29
	v_max_u32_e32 v28, v28, v29
	v_min_u32_e32 v29, v26, v27
	v_max_u32_e32 v26, v26, v27
	v_min_u32_e32 v27, v24, v25
	v_max_u32_e32 v24, v24, v25
	v_max_u32_e32 v22, v22, v23
	v_max_u32_e32 v23, v7, v8
	v_min_u32_e32 v25, v5, v4
	v_max3_u32 v64, v64, v65, v66
	v_min_u32_e32 v65, v30, v31
	v_max_u32_e32 v30, v30, v31
	v_min_u32_e32 v31, v28, v29
	v_max_u32_e32 v28, v28, v29
	v_min_u32_e32 v29, v26, v27
	v_max_u32_e32 v26, v26, v27
	v_max_u32_e32 v20, v20, v21
	v_max_u32_e32 v21, v9, v10
	v_min_u32_e32 v27, v23, v25
	v_min_u32_e32 v66, v30, v31
	v_max_u32_e32 v30, v30, v31
	v_min_u32_e32 v31, v28, v29
	v_max_u32_e32 v28, v28, v29
	v_max_u32_e32 v18, v18, v19
	v_max_u32_e32 v19, v11, v12
	v_min_u32_e32 v29, v21, v27
	v_max_u32_e32 v16, v16, v17
	v_max_u32_e32 v17, v13, v14
	v_min_u32_e32 v6, v19, v29
	v_min_u32_e32 v7, v17, v6
	v_min_u32_e32 v8, v16, v7
	v_min_u32_e32 v9, v18, v8
	v_min_u32_e32 v10, v20, v9
	v_min_u32_e32 v11, v22, v10
	v_min_u32_e32 v12, v24, v11
	v_min_u32_e32 v13, v26, v12
	v_max3_u32 v64, v64, v65, v66
	v_min_u32_e32 v65, v30, v31
	v_max_u32_e32 v30, v30, v31
	v_min_u32_e32 v14, v28, v13
	v_max_u32_e32 v0, v0, v1
	v_min_u32_e32 v31, v30, v14
	v_max_u32_e32 v7, v16, v7
	v_max_u32_e32 v6, v17, v6
	v_max_u32_e32 v2, v3, v2
	v_and_b32_e32 v16, 0x7fffff00, v0
	v_bitop3_b32 v17, v0, s68, v0 bitop3:0xcf
	v_cmp_gt_i32_e32 vcc, 0, v0
	v_max3_u32 v64, v64, v65, v31
	v_max_u32_e32 v8, v18, v8
	v_max_u32_e32 v4, v5, v4
	v_cndmask_b32_e32 v31, v17, v16, vcc
	v_and_b32_e32 v17, 0x7fffff00, v2
	v_bitop3_b32 v18, v2, s68, v2 bitop3:0xcf
	v_cmp_gt_i32_e32 vcc, 0, v2
	v_max_u32_e32 v76, v19, v29
	v_max_u32_e32 v80, v23, v25
	v_sub_f32_e32 v16, v31, v31
	v_cndmask_b32_e32 v17, v18, v17, vcc
	v_and_b32_e32 v18, 0x7fffff00, v4
	v_bitop3_b32 v19, v4, s68, v4 bitop3:0xcf
	v_cmp_gt_i32_e32 vcc, 0, v4
	v_max_u32_e32 v9, v20, v9
	v_mul_f32_e32 v16, 0x3fb8aa3b, v16
	v_sub_f32_e32 v17, v17, v31
	v_cndmask_b32_e32 v18, v19, v18, vcc
	v_and_b32_e32 v19, 0x7fffff00, v80
	v_bitop3_b32 v20, v80, s68, v80 bitop3:0xcf
	v_cmp_gt_i32_e32 vcc, 0, v80
	v_exp_f32_e32 v16, v16
	v_mul_f32_e32 v17, 0x3fb8aa3b, v17
	v_sub_f32_e32 v18, v18, v31
	v_cndmask_b32_e32 v19, v20, v19, vcc
	v_exp_f32_e32 v17, v17
	v_mul_f32_e32 v18, 0x3fb8aa3b, v18
	v_sub_f32_e32 v19, v19, v31
	v_exp_f32_e32 v18, v18
	v_mul_f32_e32 v19, 0x3fb8aa3b, v19
	v_exp_f32_e32 v19, v19
	v_add_f32_e32 v20, 0, v16
	v_add_f32_e32 v20, v17, v20
	v_max_u32_e32 v78, v21, v27
	v_add_f32_e32 v20, v18, v20
	v_max_u32_e32 v11, v24, v11
	v_add_f32_e32 v24, v19, v20
	v_and_b32_e32 v20, 0x7fffff00, v78
	v_bitop3_b32 v21, v78, s68, v78 bitop3:0xcf
	v_cmp_gt_i32_e32 vcc, 0, v78
	v_max_u32_e32 v10, v22, v10
	v_bitop3_b32 v22, v76, s68, v76 bitop3:0xcf
	v_cndmask_b32_e32 v20, v21, v20, vcc
	v_and_b32_e32 v21, 0x7fffff00, v76
	v_cmp_gt_i32_e32 vcc, 0, v76
	v_sub_f32_e32 v20, v20, v31
	v_bitop3_b32 v23, v6, s68, v6 bitop3:0xcf
	v_cndmask_b32_e32 v21, v22, v21, vcc
	v_and_b32_e32 v22, 0x7fffff00, v6
	v_cmp_gt_i32_e32 vcc, 0, v6
	v_mul_f32_e32 v20, 0x3fb8aa3b, v20
	v_sub_f32_e32 v21, v21, v31
	v_cndmask_b32_e32 v22, v23, v22, vcc
	v_and_b32_e32 v23, 0x7fffff00, v7
; DI float ord2f(unsigned u) { return __uint_as_float((u & 0x80000000u) ? (u & 0x7fffffffu) : ~u); }
; __device__ __forceinline__ void route_task(const Params& p, int layer, const u16* qg, int rb, int hd, int r, int h) {
;     ...
;     const float v0 = ord2f(ct[0] & ~255u);
;     float vs[16];
;     float den = 0.f;
; #pragma unroll
;     for (int jj = 0; jj < 16; ++jj) { vs[jj] = __expf(ord2f(ct[jj] & ~255u) - v0); den += vs[jj]; }
;     const float inv = 1.f / den;
;     unsigned eo[16];
; #pragma unroll
;     for (int jj = 0; jj < 16; ++jj) {
;       const unsigned flat = 255u - (ct[jj] & 255u);
;       const unsigned a = flat >> 4, b = flat & 15u;
;       unsigned ka = top[0][0], kb = top[1][0];
; #pragma unroll
;       for (int k = 1; k < 16; ++k) { ka = (a == (unsigned)k) ? top[0][k] : ka; kb = (b == (unsigned)k) ? top[1][k] : kb; }
	v_bitop3_b32 v25, v7, s68, v7 bitop3:0xcf
	v_cmp_gt_i32_e32 vcc, 0, v7
	v_exp_f32_e32 v20, v20
	v_mul_f32_e32 v21, 0x3fb8aa3b, v21
	v_sub_f32_e32 v22, v22, v31
	v_cndmask_b32_e32 v23, v25, v23, vcc
	v_exp_f32_e32 v21, v21
	v_mul_f32_e32 v22, 0x3fb8aa3b, v22
	v_sub_f32_e32 v23, v23, v31
	v_exp_f32_e32 v22, v22
	v_mul_f32_e32 v23, 0x3fb8aa3b, v23
	v_exp_f32_e32 v23, v23
	v_add_f32_e32 v24, v20, v24
	v_add_f32_e32 v24, v21, v24
	v_add_f32_e32 v24, v22, v24
	v_max_u32_e32 v13, v28, v13
	v_add_f32_e32 v28, v23, v24
	v_and_b32_e32 v24, 0x7fffff00, v8
	v_bitop3_b32 v25, v8, s68, v8 bitop3:0xcf
	v_cmp_gt_i32_e32 vcc, 0, v8
	v_max_u32_e32 v12, v26, v12
	v_bitop3_b32 v26, v9, s68, v9 bitop3:0xcf
	v_cndmask_b32_e32 v24, v25, v24, vcc
	v_and_b32_e32 v25, 0x7fffff00, v9
	v_cmp_gt_i32_e32 vcc, 0, v9
	v_sub_f32_e32 v24, v24, v31
	v_bitop3_b32 v27, v10, s68, v10 bitop3:0xcf
	v_cndmask_b32_e32 v25, v26, v25, vcc
	v_and_b32_e32 v26, 0x7fffff00, v10
	v_cmp_gt_i32_e32 vcc, 0, v10
	v_mul_f32_e32 v24, 0x3fb8aa3b, v24
	v_sub_f32_e32 v25, v25, v31
	v_cndmask_b32_e32 v26, v27, v26, vcc
	v_and_b32_e32 v27, 0x7fffff00, v11
	v_bitop3_b32 v29, v11, s68, v11 bitop3:0xcf
	v_cmp_gt_i32_e32 vcc, 0, v11
	v_exp_f32_e32 v24, v24
	v_mul_f32_e32 v25, 0x3fb8aa3b, v25
	v_sub_f32_e32 v26, v26, v31
	v_cndmask_b32_e32 v27, v29, v27, vcc
	v_exp_f32_e32 v25, v25
	v_mul_f32_e32 v26, 0x3fb8aa3b, v26
	v_sub_f32_e32 v27, v27, v31
	v_exp_f32_e32 v26, v26
	v_mul_f32_e32 v27, 0x3fb8aa3b, v27
	v_exp_f32_e32 v27, v27
	v_add_f32_e32 v28, v24, v28
	v_add_f32_e32 v28, v25, v28
	v_add_f32_e32 v28, v26, v28
	v_add_f32_e32 v67, v27, v28
	v_and_b32_e32 v28, 0x7fffff00, v12
	v_bitop3_b32 v29, v12, s68, v12 bitop3:0xcf
	v_cmp_gt_i32_e32 vcc, 0, v12
	v_max_u32_e32 v14, v30, v14
	v_bitop3_b32 v30, v13, s68, v13 bitop3:0xcf
	v_cndmask_b32_e32 v28, v29, v28, vcc
	v_and_b32_e32 v29, 0x7fffff00, v13
	v_cmp_gt_i32_e32 vcc, 0, v13
	v_not_b32_e32 v1, v0
	v_bitop3_b32 v82, v14, s68, v14 bitop3:0xcf
	v_cndmask_b32_e32 v29, v30, v29, vcc
	v_and_b32_e32 v30, 0x7fffff00, v14
	v_cmp_gt_i32_e32 vcc, 0, v14
	v_bitop3_b32 v83, v64, s68, v64 bitop3:0xcf
	v_bfe_u32 v1, v1, 4, 4
	v_cndmask_b32_e32 v30, v82, v30, vcc
	v_and_b32_e32 v82, 0x7fffff00, v64
	v_cmp_gt_i32_e32 vcc, 0, v64
	v_bitop3_b32 v0, v0, 15, v0 bitop3:0xc
	v_sub_f32_e32 v28, v28, v31
	v_cndmask_b32_e32 v82, v83, v82, vcc
	v_cmp_eq_u32_e32 vcc, 1, v1
	v_sub_f32_e32 v29, v29, v31
	v_sub_f32_e32 v30, v30, v31
	v_sub_f32_e32 v31, v82, v31
	v_cndmask_b32_e32 v82, v50, v46, vcc
	v_cmp_eq_u32_e32 vcc, 1, v0
	v_not_b32_e32 v3, v2
	v_bitop3_b32 v2, v2, 15, v2 bitop3:0xc
	v_cndmask_b32_e32 v83, v63, v62, vcc
	v_cmp_eq_u32_e32 vcc, 2, v1
	v_not_b32_e32 v5, v4
	v_not_b32_e32 v81, v80
	v_cndmask_b32_e32 v82, v82, v45, vcc
	v_cmp_eq_u32_e32 vcc, 2, v0
	v_not_b32_e32 v79, v78
	v_not_b32_e32 v77, v76
	v_cndmask_b32_e32 v83, v83, v61, vcc
	v_cmp_eq_u32_e32 vcc, 3, v1
	v_bitop3_b32 v76, v76, 15, v76 bitop3:0xc
	v_not_b32_e32 v75, v6
	v_cndmask_b32_e32 v82, v82, v44, vcc
	v_cmp_eq_u32_e32 vcc, 3, v0
	v_bfe_u32 v75, v75, 4, 4
	v_bitop3_b32 v6, v6, 15, v6 bitop3:0xc
	v_cndmask_b32_e32 v83, v83, v60, vcc
	v_cmp_eq_u32_e32 vcc, 4, v1
	v_not_b32_e32 v74, v7
	v_bfe_u32 v74, v74, 4, 4
	v_cndmask_b32_e32 v82, v82, v43, vcc
	v_cmp_eq_u32_e32 vcc, 4, v0
	v_bitop3_b32 v7, v7, 15, v7 bitop3:0xc
	v_not_b32_e32 v73, v8
	v_cndmask_b32_e32 v83, v83, v59, vcc
	v_cmp_eq_u32_e32 vcc, 5, v1
	v_bfe_u32 v73, v73, 4, 4
	v_bitop3_b32 v8, v8, 15, v8 bitop3:0xc
	v_cndmask_b32_e32 v82, v82, v42, vcc
	v_cmp_eq_u32_e32 vcc, 5, v0
	v_not_b32_e32 v72, v9
	v_bfe_u32 v72, v72, 4, 4
	v_cndmask_b32_e32 v83, v83, v58, vcc
	v_cmp_eq_u32_e32 vcc, 6, v1
	v_bitop3_b32 v9, v9, 15, v9 bitop3:0xc
	v_not_b32_e32 v71, v10
	v_cndmask_b32_e32 v82, v82, v41, vcc
	v_cmp_eq_u32_e32 vcc, 6, v0
	v_bfe_u32 v71, v71, 4, 4
	v_bitop3_b32 v10, v10, 15, v10 bitop3:0xc
	v_cndmask_b32_e32 v83, v83, v57, vcc
	v_cmp_eq_u32_e32 vcc, 7, v1
	v_not_b32_e32 v70, v11
	v_bfe_u32 v70, v70, 4, 4
	v_cndmask_b32_e32 v82, v82, v40, vcc
	v_cmp_eq_u32_e32 vcc, 7, v0
	v_bitop3_b32 v11, v11, 15, v11 bitop3:0xc
	v_not_b32_e32 v69, v12
	v_cndmask_b32_e32 v83, v83, v56, vcc
	v_cmp_eq_u32_e32 vcc, 8, v1
	v_bfe_u32 v69, v69, 4, 4
	v_bitop3_b32 v12, v12, 15, v12 bitop3:0xc
	v_cndmask_b32_e32 v82, v82, v39, vcc
	v_cmp_eq_u32_e32 vcc, 8, v0
	v_not_b32_e32 v68, v13
	v_bfe_u32 v68, v68, 4, 4
	v_cndmask_b32_e32 v83, v83, v55, vcc
	v_cmp_eq_u32_e32 vcc, 9, v1
	v_bitop3_b32 v13, v13, 15, v13 bitop3:0xc
	v_not_b32_e32 v66, v14
	v_cndmask_b32_e32 v82, v82, v38, vcc
	v_cmp_eq_u32_e32 vcc, 9, v0
	v_bfe_u32 v66, v66, 4, 4
	v_bitop3_b32 v14, v14, 15, v14 bitop3:0xc
	v_cndmask_b32_e32 v83, v83, v54, vcc
	v_cmp_eq_u32_e32 vcc, 10, v1
	v_not_b32_e32 v65, v64
	v_bfe_u32 v65, v65, 4, 4
	v_cndmask_b32_e32 v82, v82, v37, vcc
	v_cmp_eq_u32_e32 vcc, 10, v0
	v_bitop3_b32 v64, v64, 15, v64 bitop3:0xc
	v_mul_f32_e32 v28, 0x3fb8aa3b, v28
	v_cndmask_b32_e32 v83, v83, v53, vcc
	v_cmp_eq_u32_e32 vcc, 11, v1
	v_exp_f32_e32 v28, v28
	v_mul_f32_e32 v29, 0x3fb8aa3b, v29
	v_cndmask_b32_e32 v82, v82, v36, vcc
	v_cmp_eq_u32_e32 vcc, 11, v0
	v_exp_f32_e32 v29, v29
	v_mul_f32_e32 v30, 0x3fb8aa3b, v30
	v_cndmask_b32_e32 v83, v83, v52, vcc
	v_cmp_eq_u32_e32 vcc, 12, v1
	v_exp_f32_e32 v30, v30
	v_mul_f32_e32 v31, 0x3fb8aa3b, v31
	v_cndmask_b32_e32 v82, v82, v35, vcc
	v_cmp_eq_u32_e32 vcc, 12, v0
	v_exp_f32_e32 v31, v31
	v_add_f32_e32 v67, v28, v67
	v_cndmask_b32_e32 v83, v83, v51, vcc
	v_cmp_eq_u32_e32 vcc, 13, v1
	v_add_f32_e32 v67, v29, v67
	v_add_f32_e32 v67, v30, v67
	v_cndmask_b32_e32 v82, v82, v34, vcc
	v_cmp_eq_u32_e32 vcc, 13, v0
	v_add_f32_e32 v67, v31, v67
	v_or_b32_e32 v32, v32, v138
; __device__ __forceinline__ void route_task(const Params& p, int layer, const u16* qg, int rb, int hd, int r, int h) {
;     ...
;     unsigned eo[16];
; #pragma unroll
;     for (int jj = 0; jj < 16; ++jj) {
;       const unsigned flat = 255u - (ct[jj] & 255u);
;       const unsigned a = flat >> 4, b = flat & 15u;
;       unsigned ka = top[0][0], kb = top[1][0];
; #pragma unroll
;       for (int k = 1; k < 16; ++k) { ka = (a == (unsigned)k) ? top[0][k] : ka; kb = (b == (unsigned)k) ? top[1][k] : kb; }
;       eo[jj] = (127u - (ka & 127u)) * 128u + (127u - (kb & 127u));
	v_cndmask_b32_e32 v83, v83, v49, vcc
	v_cmp_eq_u32_e32 vcc, 14, v1
	s_nop 1
	v_cndmask_b32_e32 v82, v82, v33, vcc
	v_cmp_eq_u32_e32 vcc, 14, v0
	s_nop 1
	v_cndmask_b32_e32 v83, v83, v48, vcc
	v_cmp_eq_u32_e32 vcc, 15, v1
	s_nop 1
	v_cndmask_b32_e32 v1, v82, v15, vcc
	v_cmp_eq_u32_e32 vcc, 15, v0
	v_lshlrev_b32_e32 v1, 7, v1
	v_and_b32_e32 v1, 0x3f80, v1
	v_cndmask_b32_e32 v0, v83, v47, vcc
	v_and_b32_e32 v0, 0x7f, v0
	v_bitop3_b32 v0, v1, s70, v0 bitop3:0x36
	v_bfe_u32 v1, v3, 4, 4
	v_cmp_eq_u32_e32 vcc, 1, v1
	s_nop 1
	v_cndmask_b32_e32 v3, v50, v46, vcc
	v_cmp_eq_u32_e32 vcc, 1, v2
	s_nop 1
	v_cndmask_b32_e32 v82, v63, v62, vcc
	v_cmp_eq_u32_e32 vcc, 2, v1
	s_nop 1
	v_cndmask_b32_e32 v3, v3, v45, vcc
	v_cmp_eq_u32_e32 vcc, 2, v2
	s_nop 1
	v_cndmask_b32_e32 v82, v82, v61, vcc
	v_cmp_eq_u32_e32 vcc, 3, v1
	s_nop 1
	v_cndmask_b32_e32 v3, v3, v44, vcc
	v_cmp_eq_u32_e32 vcc, 3, v2
	s_nop 1
	v_cndmask_b32_e32 v82, v82, v60, vcc
	v_cmp_eq_u32_e32 vcc, 4, v1
	s_nop 1
	v_cndmask_b32_e32 v3, v3, v43, vcc
	v_cmp_eq_u32_e32 vcc, 4, v2
	s_nop 1
	v_cndmask_b32_e32 v82, v82, v59, vcc
	v_cmp_eq_u32_e32 vcc, 5, v1
	s_nop 1
	v_cndmask_b32_e32 v3, v3, v42, vcc
	v_cmp_eq_u32_e32 vcc, 5, v2
	s_nop 1
	v_cndmask_b32_e32 v82, v82, v58, vcc
	v_cmp_eq_u32_e32 vcc, 6, v1
	s_nop 1
	v_cndmask_b32_e32 v3, v3, v41, vcc
	v_cmp_eq_u32_e32 vcc, 6, v2
	s_nop 1
	v_cndmask_b32_e32 v82, v82, v57, vcc
	v_cmp_eq_u32_e32 vcc, 7, v1
	s_nop 1
	v_cndmask_b32_e32 v3, v3, v40, vcc
	v_cmp_eq_u32_e32 vcc, 7, v2
	s_nop 1
	v_cndmask_b32_e32 v82, v82, v56, vcc
	v_cmp_eq_u32_e32 vcc, 8, v1
	s_nop 1
	v_cndmask_b32_e32 v3, v3, v39, vcc
	v_cmp_eq_u32_e32 vcc, 8, v2
	s_nop 1
	v_cndmask_b32_e32 v82, v82, v55, vcc
	v_cmp_eq_u32_e32 vcc, 9, v1
	s_nop 1
	v_cndmask_b32_e32 v3, v3, v38, vcc
	v_cmp_eq_u32_e32 vcc, 9, v2
	s_nop 1
	v_cndmask_b32_e32 v82, v82, v54, vcc
	v_cmp_eq_u32_e32 vcc, 10, v1
	s_nop 1
	v_cndmask_b32_e32 v3, v3, v37, vcc
	v_cmp_eq_u32_e32 vcc, 10, v2
	s_nop 1
	v_cndmask_b32_e32 v82, v82, v53, vcc
	v_cmp_eq_u32_e32 vcc, 11, v1
	s_nop 1
	v_cndmask_b32_e32 v3, v3, v36, vcc
	v_cmp_eq_u32_e32 vcc, 11, v2
	s_nop 1
	v_cndmask_b32_e32 v82, v82, v52, vcc
	v_cmp_eq_u32_e32 vcc, 12, v1
	s_nop 1
	v_cndmask_b32_e32 v3, v3, v35, vcc
	v_cmp_eq_u32_e32 vcc, 12, v2
	s_nop 1
	v_cndmask_b32_e32 v82, v82, v51, vcc
	v_cmp_eq_u32_e32 vcc, 13, v1
	s_nop 1
	v_cndmask_b32_e32 v3, v3, v34, vcc
	v_cmp_eq_u32_e32 vcc, 13, v2
	s_nop 1
	v_cndmask_b32_e32 v82, v82, v49, vcc
	v_cmp_eq_u32_e32 vcc, 14, v1
	s_nop 1
	v_cndmask_b32_e32 v3, v3, v33, vcc
	v_cmp_eq_u32_e32 vcc, 14, v2
	s_nop 1
	v_cndmask_b32_e32 v82, v82, v48, vcc
	v_cmp_eq_u32_e32 vcc, 15, v1
	s_nop 1
	v_cndmask_b32_e32 v1, v3, v15, vcc
	v_cmp_eq_u32_e32 vcc, 15, v2
	v_lshlrev_b32_e32 v1, 7, v1
	v_and_b32_e32 v1, 0x3f80, v1
	v_cndmask_b32_e32 v2, v82, v47, vcc
	v_and_b32_e32 v2, 0x7f, v2
	v_bitop3_b32 v1, v1, s70, v2 bitop3:0x36
	v_bfe_u32 v2, v5, 4, 4
	v_bitop3_b32 v3, v4, 15, v4 bitop3:0xc
	v_cmp_eq_u32_e32 vcc, 1, v2
	s_nop 1
	v_cndmask_b32_e32 v4, v50, v46, vcc
	v_cmp_eq_u32_e32 vcc, 1, v3
	s_nop 1
	v_cndmask_b32_e32 v5, v63, v62, vcc
	v_cmp_eq_u32_e32 vcc, 2, v2
	s_nop 1
	v_cndmask_b32_e32 v4, v4, v45, vcc
	v_cmp_eq_u32_e32 vcc, 2, v3
	s_nop 1
	v_cndmask_b32_e32 v5, v5, v61, vcc
	v_cmp_eq_u32_e32 vcc, 3, v2
	s_nop 1
	v_cndmask_b32_e32 v4, v4, v44, vcc
	v_cmp_eq_u32_e32 vcc, 3, v3
	s_nop 1
	v_cndmask_b32_e32 v5, v5, v60, vcc
	v_cmp_eq_u32_e32 vcc, 4, v2
	s_nop 1
	v_cndmask_b32_e32 v4, v4, v43, vcc
	v_cmp_eq_u32_e32 vcc, 4, v3
	s_nop 1
	v_cndmask_b32_e32 v5, v5, v59, vcc
	v_cmp_eq_u32_e32 vcc, 5, v2
	s_nop 1
	v_cndmask_b32_e32 v4, v4, v42, vcc
	v_cmp_eq_u32_e32 vcc, 5, v3
	s_nop 1
	v_cndmask_b32_e32 v5, v5, v58, vcc
	v_cmp_eq_u32_e32 vcc, 6, v2
	s_nop 1
	v_cndmask_b32_e32 v4, v4, v41, vcc
	v_cmp_eq_u32_e32 vcc, 6, v3
	s_nop 1
	v_cndmask_b32_e32 v5, v5, v57, vcc
	v_cmp_eq_u32_e32 vcc, 7, v2
	s_nop 1
	v_cndmask_b32_e32 v4, v4, v40, vcc
	v_cmp_eq_u32_e32 vcc, 7, v3
	s_nop 1
	v_cndmask_b32_e32 v5, v5, v56, vcc
	v_cmp_eq_u32_e32 vcc, 8, v2
	s_nop 1
	v_cndmask_b32_e32 v4, v4, v39, vcc
	v_cmp_eq_u32_e32 vcc, 8, v3
	s_nop 1
	v_cndmask_b32_e32 v5, v5, v55, vcc
	v_cmp_eq_u32_e32 vcc, 9, v2
	s_nop 1
	v_cndmask_b32_e32 v4, v4, v38, vcc
	v_cmp_eq_u32_e32 vcc, 9, v3
	s_nop 1
	v_cndmask_b32_e32 v5, v5, v54, vcc
	v_cmp_eq_u32_e32 vcc, 10, v2
	s_nop 1
	v_cndmask_b32_e32 v4, v4, v37, vcc
	v_cmp_eq_u32_e32 vcc, 10, v3
	s_nop 1
	v_cndmask_b32_e32 v5, v5, v53, vcc
	v_cmp_eq_u32_e32 vcc, 11, v2
	s_nop 1
	v_cndmask_b32_e32 v4, v4, v36, vcc
	v_cmp_eq_u32_e32 vcc, 11, v3
	s_nop 1
	v_cndmask_b32_e32 v5, v5, v52, vcc
	v_cmp_eq_u32_e32 vcc, 12, v2
	s_nop 1
	v_cndmask_b32_e32 v4, v4, v35, vcc
	v_cmp_eq_u32_e32 vcc, 12, v3
	s_nop 1
	v_cndmask_b32_e32 v5, v5, v51, vcc
	v_cmp_eq_u32_e32 vcc, 13, v2
	s_nop 1
	v_cndmask_b32_e32 v4, v4, v34, vcc
	v_cmp_eq_u32_e32 vcc, 13, v3
	s_nop 1
	v_cndmask_b32_e32 v5, v5, v49, vcc
	v_cmp_eq_u32_e32 vcc, 14, v2
	s_nop 1
	v_cndmask_b32_e32 v4, v4, v33, vcc
	v_cmp_eq_u32_e32 vcc, 14, v3
	s_nop 1
	v_cndmask_b32_e32 v5, v5, v48, vcc
	v_cmp_eq_u32_e32 vcc, 15, v2
	s_nop 1
	v_cndmask_b32_e32 v2, v4, v15, vcc
	v_cmp_eq_u32_e32 vcc, 15, v3
	v_lshlrev_b32_e32 v2, 7, v2
	v_and_b32_e32 v2, 0x3f80, v2
	v_cndmask_b32_e32 v3, v5, v47, vcc
	v_and_b32_e32 v3, 0x7f, v3
	v_bitop3_b32 v2, v2, s70, v3 bitop3:0x36
	v_bfe_u32 v3, v81, 4, 4
	v_bitop3_b32 v4, v80, 15, v80 bitop3:0xc
	v_cmp_eq_u32_e32 vcc, 1, v3
	s_nop 1
	v_cndmask_b32_e32 v5, v50, v46, vcc
	v_cmp_eq_u32_e32 vcc, 1, v4
	s_nop 1
	v_cndmask_b32_e32 v80, v63, v62, vcc
	v_cmp_eq_u32_e32 vcc, 2, v3
	s_nop 1
	v_cndmask_b32_e32 v5, v5, v45, vcc
	v_cmp_eq_u32_e32 vcc, 2, v4
	s_nop 1
	v_cndmask_b32_e32 v80, v80, v61, vcc
; __device__ __forceinline__ void route_task(const Params& p, int layer, const u16* qg, int rb, int hd, int r, int h) {
;     ...
;     for (int jj = 0; jj < 16; ++jj) {
;       const unsigned flat = 255u - (ct[jj] & 255u);
;       const unsigned a = flat >> 4, b = flat & 15u;
;       unsigned ka = top[0][0], kb = top[1][0];
; #pragma unroll
;       for (int k = 1; k < 16; ++k) { ka = (a == (unsigned)k) ? top[0][k] : ka; kb = (b == (unsigned)k) ? top[1][k] : kb; }
;       eo[jj] = (127u - (ka & 127u)) * 128u + (127u - (kb & 127u));
;     }
	v_cmp_eq_u32_e32 vcc, 3, v3
	s_nop 1
	v_cndmask_b32_e32 v5, v5, v44, vcc
	v_cmp_eq_u32_e32 vcc, 3, v4
	s_nop 1
	v_cndmask_b32_e32 v80, v80, v60, vcc
	v_cmp_eq_u32_e32 vcc, 4, v3
	s_nop 1
	v_cndmask_b32_e32 v5, v5, v43, vcc
	v_cmp_eq_u32_e32 vcc, 4, v4
	s_nop 1
	v_cndmask_b32_e32 v80, v80, v59, vcc
	v_cmp_eq_u32_e32 vcc, 5, v3
	s_nop 1
	v_cndmask_b32_e32 v5, v5, v42, vcc
	v_cmp_eq_u32_e32 vcc, 5, v4
	s_nop 1
	v_cndmask_b32_e32 v80, v80, v58, vcc
	v_cmp_eq_u32_e32 vcc, 6, v3
	s_nop 1
	v_cndmask_b32_e32 v5, v5, v41, vcc
	v_cmp_eq_u32_e32 vcc, 6, v4
	s_nop 1
	v_cndmask_b32_e32 v80, v80, v57, vcc
	v_cmp_eq_u32_e32 vcc, 7, v3
	s_nop 1
	v_cndmask_b32_e32 v5, v5, v40, vcc
	v_cmp_eq_u32_e32 vcc, 7, v4
	s_nop 1
	v_cndmask_b32_e32 v80, v80, v56, vcc
	v_cmp_eq_u32_e32 vcc, 8, v3
	s_nop 1
	v_cndmask_b32_e32 v5, v5, v39, vcc
	v_cmp_eq_u32_e32 vcc, 8, v4
	s_nop 1
	v_cndmask_b32_e32 v80, v80, v55, vcc
	v_cmp_eq_u32_e32 vcc, 9, v3
	s_nop 1
	v_cndmask_b32_e32 v5, v5, v38, vcc
	v_cmp_eq_u32_e32 vcc, 9, v4
	s_nop 1
	v_cndmask_b32_e32 v80, v80, v54, vcc
	v_cmp_eq_u32_e32 vcc, 10, v3
	s_nop 1
	v_cndmask_b32_e32 v5, v5, v37, vcc
	v_cmp_eq_u32_e32 vcc, 10, v4
	s_nop 1
	v_cndmask_b32_e32 v80, v80, v53, vcc
	v_cmp_eq_u32_e32 vcc, 11, v3
	s_nop 1
	v_cndmask_b32_e32 v5, v5, v36, vcc
	v_cmp_eq_u32_e32 vcc, 11, v4
	s_nop 1
	v_cndmask_b32_e32 v80, v80, v52, vcc
	v_cmp_eq_u32_e32 vcc, 12, v3
	s_nop 1
	v_cndmask_b32_e32 v5, v5, v35, vcc
	v_cmp_eq_u32_e32 vcc, 12, v4
	s_nop 1
	v_cndmask_b32_e32 v80, v80, v51, vcc
	v_cmp_eq_u32_e32 vcc, 13, v3
	s_nop 1
	v_cndmask_b32_e32 v5, v5, v34, vcc
	v_cmp_eq_u32_e32 vcc, 13, v4
	s_nop 1
	v_cndmask_b32_e32 v80, v80, v49, vcc
	v_cmp_eq_u32_e32 vcc, 14, v3
	s_nop 1
	v_cndmask_b32_e32 v5, v5, v33, vcc
	v_cmp_eq_u32_e32 vcc, 14, v4
	s_nop 1
	v_cndmask_b32_e32 v80, v80, v48, vcc
	v_cmp_eq_u32_e32 vcc, 15, v3
	s_nop 1
	v_cndmask_b32_e32 v3, v5, v15, vcc
	v_cmp_eq_u32_e32 vcc, 15, v4
	v_lshlrev_b32_e32 v3, 7, v3
	v_and_b32_e32 v3, 0x3f80, v3
	v_cndmask_b32_e32 v4, v80, v47, vcc
	v_and_b32_e32 v4, 0x7f, v4
	v_bitop3_b32 v3, v3, s70, v4 bitop3:0x36
	v_bfe_u32 v4, v79, 4, 4
	v_bitop3_b32 v5, v78, 15, v78 bitop3:0xc
	v_cmp_eq_u32_e32 vcc, 1, v4
	s_nop 1
	v_cndmask_b32_e32 v78, v50, v46, vcc
	v_cmp_eq_u32_e32 vcc, 1, v5
	s_nop 1
	v_cndmask_b32_e32 v79, v63, v62, vcc
	v_cmp_eq_u32_e32 vcc, 2, v4
	s_nop 1
	v_cndmask_b32_e32 v78, v78, v45, vcc
	v_cmp_eq_u32_e32 vcc, 2, v5
	s_nop 1
	v_cndmask_b32_e32 v79, v79, v61, vcc
	v_cmp_eq_u32_e32 vcc, 3, v4
	s_nop 1
	v_cndmask_b32_e32 v78, v78, v44, vcc
	v_cmp_eq_u32_e32 vcc, 3, v5
	s_nop 1
	v_cndmask_b32_e32 v79, v79, v60, vcc
	v_cmp_eq_u32_e32 vcc, 4, v4
	s_nop 1
	v_cndmask_b32_e32 v78, v78, v43, vcc
	v_cmp_eq_u32_e32 vcc, 4, v5
	s_nop 1
	v_cndmask_b32_e32 v79, v79, v59, vcc
	v_cmp_eq_u32_e32 vcc, 5, v4
	s_nop 1
	v_cndmask_b32_e32 v78, v78, v42, vcc
	v_cmp_eq_u32_e32 vcc, 5, v5
	s_nop 1
	v_cndmask_b32_e32 v79, v79, v58, vcc
	v_cmp_eq_u32_e32 vcc, 6, v4
	s_nop 1
	v_cndmask_b32_e32 v78, v78, v41, vcc
	v_cmp_eq_u32_e32 vcc, 6, v5
	s_nop 1
	v_cndmask_b32_e32 v79, v79, v57, vcc
	v_cmp_eq_u32_e32 vcc, 7, v4
	s_nop 1
	v_cndmask_b32_e32 v78, v78, v40, vcc
	v_cmp_eq_u32_e32 vcc, 7, v5
	s_nop 1
	v_cndmask_b32_e32 v79, v79, v56, vcc
	v_cmp_eq_u32_e32 vcc, 8, v4
	s_nop 1
	v_cndmask_b32_e32 v78, v78, v39, vcc
	v_cmp_eq_u32_e32 vcc, 8, v5
	s_nop 1
	v_cndmask_b32_e32 v79, v79, v55, vcc
	v_cmp_eq_u32_e32 vcc, 9, v4
	s_nop 1
	v_cndmask_b32_e32 v78, v78, v38, vcc
	v_cmp_eq_u32_e32 vcc, 9, v5
	s_nop 1
	v_cndmask_b32_e32 v79, v79, v54, vcc
	v_cmp_eq_u32_e32 vcc, 10, v4
	s_nop 1
	v_cndmask_b32_e32 v78, v78, v37, vcc
	v_cmp_eq_u32_e32 vcc, 10, v5
	s_nop 1
	v_cndmask_b32_e32 v79, v79, v53, vcc
	v_cmp_eq_u32_e32 vcc, 11, v4
	s_nop 1
	v_cndmask_b32_e32 v78, v78, v36, vcc
	v_cmp_eq_u32_e32 vcc, 11, v5
	s_nop 1
	v_cndmask_b32_e32 v79, v79, v52, vcc
	v_cmp_eq_u32_e32 vcc, 12, v4
	s_nop 1
	v_cndmask_b32_e32 v78, v78, v35, vcc
	v_cmp_eq_u32_e32 vcc, 12, v5
	s_nop 1
	v_cndmask_b32_e32 v79, v79, v51, vcc
	v_cmp_eq_u32_e32 vcc, 13, v4
	s_nop 1
	v_cndmask_b32_e32 v78, v78, v34, vcc
	v_cmp_eq_u32_e32 vcc, 13, v5
	s_nop 1
	v_cndmask_b32_e32 v79, v79, v49, vcc
	v_cmp_eq_u32_e32 vcc, 14, v4
	s_nop 1
	v_cndmask_b32_e32 v78, v78, v33, vcc
	v_cmp_eq_u32_e32 vcc, 14, v5
	s_nop 1
	v_cndmask_b32_e32 v79, v79, v48, vcc
	v_cmp_eq_u32_e32 vcc, 15, v4
	s_nop 1
	v_cndmask_b32_e32 v4, v78, v15, vcc
	v_cmp_eq_u32_e32 vcc, 15, v5
	v_lshlrev_b32_e32 v4, 7, v4
	v_and_b32_e32 v4, 0x3f80, v4
	v_cndmask_b32_e32 v5, v79, v47, vcc
	v_and_b32_e32 v5, 0x7f, v5
	v_bitop3_b32 v4, v4, s70, v5 bitop3:0x36
	v_bfe_u32 v5, v77, 4, 4
	v_cmp_eq_u32_e32 vcc, 1, v5
	s_nop 1
	v_cndmask_b32_e32 v77, v50, v46, vcc
	v_cmp_eq_u32_e32 vcc, 1, v76
	s_nop 1
	v_cndmask_b32_e32 v78, v63, v62, vcc
	v_cmp_eq_u32_e32 vcc, 2, v5
	s_nop 1
	v_cndmask_b32_e32 v77, v77, v45, vcc
	v_cmp_eq_u32_e32 vcc, 2, v76
	s_nop 1
	v_cndmask_b32_e32 v78, v78, v61, vcc
	v_cmp_eq_u32_e32 vcc, 3, v5
	s_nop 1
	v_cndmask_b32_e32 v77, v77, v44, vcc
	v_cmp_eq_u32_e32 vcc, 3, v76
	s_nop 1
	v_cndmask_b32_e32 v78, v78, v60, vcc
	v_cmp_eq_u32_e32 vcc, 4, v5
	s_nop 1
	v_cndmask_b32_e32 v77, v77, v43, vcc
	v_cmp_eq_u32_e32 vcc, 4, v76
	s_nop 1
	v_cndmask_b32_e32 v78, v78, v59, vcc
	v_cmp_eq_u32_e32 vcc, 5, v5
	s_nop 1
	v_cndmask_b32_e32 v77, v77, v42, vcc
	v_cmp_eq_u32_e32 vcc, 5, v76
	s_nop 1
	v_cndmask_b32_e32 v78, v78, v58, vcc
	v_cmp_eq_u32_e32 vcc, 6, v5
	s_nop 1
	v_cndmask_b32_e32 v77, v77, v41, vcc
	v_cmp_eq_u32_e32 vcc, 6, v76
	s_nop 1
	v_cndmask_b32_e32 v78, v78, v57, vcc
	v_cmp_eq_u32_e32 vcc, 7, v5
	s_nop 1
	v_cndmask_b32_e32 v77, v77, v40, vcc
	v_cmp_eq_u32_e32 vcc, 7, v76
	s_nop 1
	v_cndmask_b32_e32 v78, v78, v56, vcc
; __device__ __forceinline__ void route_task(const Params& p, int layer, const u16* qg, int rb, int hd, int r, int h) {
;     ...
;     for (int jj = 0; jj < 16; ++jj) {
;       const unsigned flat = 255u - (ct[jj] & 255u);
;       const unsigned a = flat >> 4, b = flat & 15u;
;       unsigned ka = top[0][0], kb = top[1][0];
; #pragma unroll
;       for (int k = 1; k < 16; ++k) { ka = (a == (unsigned)k) ? top[0][k] : ka; kb = (b == (unsigned)k) ? top[1][k] : kb; }
;       eo[jj] = (127u - (ka & 127u)) * 128u + (127u - (kb & 127u));
;     }
	v_cmp_eq_u32_e32 vcc, 8, v5
	s_nop 1
	v_cndmask_b32_e32 v77, v77, v39, vcc
	v_cmp_eq_u32_e32 vcc, 8, v76
	s_nop 1
	v_cndmask_b32_e32 v78, v78, v55, vcc
	v_cmp_eq_u32_e32 vcc, 9, v5
	s_nop 1
	v_cndmask_b32_e32 v77, v77, v38, vcc
	v_cmp_eq_u32_e32 vcc, 9, v76
	s_nop 1
	v_cndmask_b32_e32 v78, v78, v54, vcc
	v_cmp_eq_u32_e32 vcc, 10, v5
	s_nop 1
	v_cndmask_b32_e32 v77, v77, v37, vcc
	v_cmp_eq_u32_e32 vcc, 10, v76
	s_nop 1
	v_cndmask_b32_e32 v78, v78, v53, vcc
	v_cmp_eq_u32_e32 vcc, 11, v5
	s_nop 1
	v_cndmask_b32_e32 v77, v77, v36, vcc
	v_cmp_eq_u32_e32 vcc, 11, v76
	s_nop 1
	v_cndmask_b32_e32 v78, v78, v52, vcc
	v_cmp_eq_u32_e32 vcc, 12, v5
	s_nop 1
	v_cndmask_b32_e32 v77, v77, v35, vcc
	v_cmp_eq_u32_e32 vcc, 12, v76
	s_nop 1
	v_cndmask_b32_e32 v78, v78, v51, vcc
	v_cmp_eq_u32_e32 vcc, 13, v5
	s_nop 1
	v_cndmask_b32_e32 v77, v77, v34, vcc
	v_cmp_eq_u32_e32 vcc, 13, v76
	s_nop 1
	v_cndmask_b32_e32 v78, v78, v49, vcc
	v_cmp_eq_u32_e32 vcc, 14, v5
	s_nop 1
	v_cndmask_b32_e32 v77, v77, v33, vcc
	v_cmp_eq_u32_e32 vcc, 14, v76
	s_nop 1
	v_cndmask_b32_e32 v78, v78, v48, vcc
	v_cmp_eq_u32_e32 vcc, 15, v5
	s_nop 1
	v_cndmask_b32_e32 v5, v77, v15, vcc
	v_cmp_eq_u32_e32 vcc, 15, v76
	v_lshlrev_b32_e32 v5, 7, v5
	v_and_b32_e32 v5, 0x3f80, v5
	v_cndmask_b32_e32 v76, v78, v47, vcc
	v_and_b32_e32 v76, 0x7f, v76
	v_cmp_eq_u32_e32 vcc, 1, v75
	v_bitop3_b32 v5, v5, s70, v76 bitop3:0x36
	s_nop 0
	v_cndmask_b32_e32 v76, v50, v46, vcc
	v_cmp_eq_u32_e32 vcc, 1, v6
	s_nop 1
	v_cndmask_b32_e32 v77, v63, v62, vcc
	v_cmp_eq_u32_e32 vcc, 2, v75
	s_nop 1
	v_cndmask_b32_e32 v76, v76, v45, vcc
	v_cmp_eq_u32_e32 vcc, 2, v6
	s_nop 1
	v_cndmask_b32_e32 v77, v77, v61, vcc
	v_cmp_eq_u32_e32 vcc, 3, v75
	s_nop 1
	v_cndmask_b32_e32 v76, v76, v44, vcc
	v_cmp_eq_u32_e32 vcc, 3, v6
	s_nop 1
	v_cndmask_b32_e32 v77, v77, v60, vcc
	v_cmp_eq_u32_e32 vcc, 4, v75
	s_nop 1
	v_cndmask_b32_e32 v76, v76, v43, vcc
	v_cmp_eq_u32_e32 vcc, 4, v6
	s_nop 1
	v_cndmask_b32_e32 v77, v77, v59, vcc
	v_cmp_eq_u32_e32 vcc, 5, v75
	s_nop 1
	v_cndmask_b32_e32 v76, v76, v42, vcc
	v_cmp_eq_u32_e32 vcc, 5, v6
	s_nop 1
	v_cndmask_b32_e32 v77, v77, v58, vcc
	v_cmp_eq_u32_e32 vcc, 6, v75
	s_nop 1
	v_cndmask_b32_e32 v76, v76, v41, vcc
	v_cmp_eq_u32_e32 vcc, 6, v6
	s_nop 1
	v_cndmask_b32_e32 v77, v77, v57, vcc
	v_cmp_eq_u32_e32 vcc, 7, v75
	s_nop 1
	v_cndmask_b32_e32 v76, v76, v40, vcc
	v_cmp_eq_u32_e32 vcc, 7, v6
	s_nop 1
	v_cndmask_b32_e32 v77, v77, v56, vcc
	v_cmp_eq_u32_e32 vcc, 8, v75
	s_nop 1
	v_cndmask_b32_e32 v76, v76, v39, vcc
	v_cmp_eq_u32_e32 vcc, 8, v6
	s_nop 1
	v_cndmask_b32_e32 v77, v77, v55, vcc
	v_cmp_eq_u32_e32 vcc, 9, v75
	s_nop 1
	v_cndmask_b32_e32 v76, v76, v38, vcc
	v_cmp_eq_u32_e32 vcc, 9, v6
	s_nop 1
	v_cndmask_b32_e32 v77, v77, v54, vcc
	v_cmp_eq_u32_e32 vcc, 10, v75
	s_nop 1
	v_cndmask_b32_e32 v76, v76, v37, vcc
	v_cmp_eq_u32_e32 vcc, 10, v6
	s_nop 1
	v_cndmask_b32_e32 v77, v77, v53, vcc
	v_cmp_eq_u32_e32 vcc, 11, v75
	s_nop 1
	v_cndmask_b32_e32 v76, v76, v36, vcc
	v_cmp_eq_u32_e32 vcc, 11, v6
	s_nop 1
	v_cndmask_b32_e32 v77, v77, v52, vcc
	v_cmp_eq_u32_e32 vcc, 12, v75
	s_nop 1
	v_cndmask_b32_e32 v76, v76, v35, vcc
	v_cmp_eq_u32_e32 vcc, 12, v6
	s_nop 1
	v_cndmask_b32_e32 v77, v77, v51, vcc
	v_cmp_eq_u32_e32 vcc, 13, v75
	s_nop 1
	v_cndmask_b32_e32 v76, v76, v34, vcc
	v_cmp_eq_u32_e32 vcc, 13, v6
	s_nop 1
	v_cndmask_b32_e32 v77, v77, v49, vcc
	v_cmp_eq_u32_e32 vcc, 14, v75
	s_nop 1
	v_cndmask_b32_e32 v76, v76, v33, vcc
	v_cmp_eq_u32_e32 vcc, 14, v6
	s_nop 1
	v_cndmask_b32_e32 v77, v77, v48, vcc
	v_cmp_eq_u32_e32 vcc, 15, v75
	s_nop 1
	v_cndmask_b32_e32 v75, v76, v15, vcc
	v_cmp_eq_u32_e32 vcc, 15, v6
	v_lshlrev_b32_e32 v75, 7, v75
	v_and_b32_e32 v75, 0x3f80, v75
	v_cndmask_b32_e32 v6, v77, v47, vcc
	v_and_b32_e32 v6, 0x7f, v6
	v_cmp_eq_u32_e32 vcc, 1, v74
	v_bitop3_b32 v6, v75, s70, v6 bitop3:0x36
	s_nop 0
	v_cndmask_b32_e32 v75, v50, v46, vcc
	v_cmp_eq_u32_e32 vcc, 1, v7
	s_nop 1
	v_cndmask_b32_e32 v76, v63, v62, vcc
	v_cmp_eq_u32_e32 vcc, 2, v74
	s_nop 1
	v_cndmask_b32_e32 v75, v75, v45, vcc
	v_cmp_eq_u32_e32 vcc, 2, v7
	s_nop 1
	v_cndmask_b32_e32 v76, v76, v61, vcc
	v_cmp_eq_u32_e32 vcc, 3, v74
	s_nop 1
	v_cndmask_b32_e32 v75, v75, v44, vcc
	v_cmp_eq_u32_e32 vcc, 3, v7
	s_nop 1
	v_cndmask_b32_e32 v76, v76, v60, vcc
	v_cmp_eq_u32_e32 vcc, 4, v74
	s_nop 1
	v_cndmask_b32_e32 v75, v75, v43, vcc
	v_cmp_eq_u32_e32 vcc, 4, v7
	s_nop 1
	v_cndmask_b32_e32 v76, v76, v59, vcc
	v_cmp_eq_u32_e32 vcc, 5, v74
	s_nop 1
	v_cndmask_b32_e32 v75, v75, v42, vcc
	v_cmp_eq_u32_e32 vcc, 5, v7
	s_nop 1
	v_cndmask_b32_e32 v76, v76, v58, vcc
	v_cmp_eq_u32_e32 vcc, 6, v74
	s_nop 1
	v_cndmask_b32_e32 v75, v75, v41, vcc
	v_cmp_eq_u32_e32 vcc, 6, v7
	s_nop 1
	v_cndmask_b32_e32 v76, v76, v57, vcc
	v_cmp_eq_u32_e32 vcc, 7, v74
	s_nop 1
	v_cndmask_b32_e32 v75, v75, v40, vcc
	v_cmp_eq_u32_e32 vcc, 7, v7
	s_nop 1
	v_cndmask_b32_e32 v76, v76, v56, vcc
	v_cmp_eq_u32_e32 vcc, 8, v74
	s_nop 1
	v_cndmask_b32_e32 v75, v75, v39, vcc
	v_cmp_eq_u32_e32 vcc, 8, v7
	s_nop 1
	v_cndmask_b32_e32 v76, v76, v55, vcc
	v_cmp_eq_u32_e32 vcc, 9, v74
	s_nop 1
	v_cndmask_b32_e32 v75, v75, v38, vcc
	v_cmp_eq_u32_e32 vcc, 9, v7
	s_nop 1
	v_cndmask_b32_e32 v76, v76, v54, vcc
	v_cmp_eq_u32_e32 vcc, 10, v74
	s_nop 1
	v_cndmask_b32_e32 v75, v75, v37, vcc
	v_cmp_eq_u32_e32 vcc, 10, v7
	s_nop 1
	v_cndmask_b32_e32 v76, v76, v53, vcc
	v_cmp_eq_u32_e32 vcc, 11, v74
	s_nop 1
	v_cndmask_b32_e32 v75, v75, v36, vcc
	v_cmp_eq_u32_e32 vcc, 11, v7
	s_nop 1
	v_cndmask_b32_e32 v76, v76, v52, vcc
	v_cmp_eq_u32_e32 vcc, 12, v74
	s_nop 1
	v_cndmask_b32_e32 v75, v75, v35, vcc
	v_cmp_eq_u32_e32 vcc, 12, v7
	s_nop 1
	v_cndmask_b32_e32 v76, v76, v51, vcc
; __device__ __forceinline__ void route_task(const Params& p, int layer, const u16* qg, int rb, int hd, int r, int h) {
;     ...
;     for (int jj = 0; jj < 16; ++jj) {
;       const unsigned flat = 255u - (ct[jj] & 255u);
;       const unsigned a = flat >> 4, b = flat & 15u;
;       unsigned ka = top[0][0], kb = top[1][0];
; #pragma unroll
;       for (int k = 1; k < 16; ++k) { ka = (a == (unsigned)k) ? top[0][k] : ka; kb = (b == (unsigned)k) ? top[1][k] : kb; }
;       eo[jj] = (127u - (ka & 127u)) * 128u + (127u - (kb & 127u));
;     }
	v_cmp_eq_u32_e32 vcc, 13, v74
	s_nop 1
	v_cndmask_b32_e32 v75, v75, v34, vcc
	v_cmp_eq_u32_e32 vcc, 13, v7
	s_nop 1
	v_cndmask_b32_e32 v76, v76, v49, vcc
	v_cmp_eq_u32_e32 vcc, 14, v74
	s_nop 1
	v_cndmask_b32_e32 v75, v75, v33, vcc
	v_cmp_eq_u32_e32 vcc, 14, v7
	s_nop 1
	v_cndmask_b32_e32 v76, v76, v48, vcc
	v_cmp_eq_u32_e32 vcc, 15, v74
	s_nop 1
	v_cndmask_b32_e32 v74, v75, v15, vcc
	v_cmp_eq_u32_e32 vcc, 15, v7
	v_lshlrev_b32_e32 v74, 7, v74
	v_and_b32_e32 v74, 0x3f80, v74
	v_cndmask_b32_e32 v7, v76, v47, vcc
	v_and_b32_e32 v7, 0x7f, v7
	v_cmp_eq_u32_e32 vcc, 1, v73
	v_bitop3_b32 v7, v74, s70, v7 bitop3:0x36
	s_nop 0
	v_cndmask_b32_e32 v74, v50, v46, vcc
	v_cmp_eq_u32_e32 vcc, 1, v8
	s_nop 1
	v_cndmask_b32_e32 v75, v63, v62, vcc
	v_cmp_eq_u32_e32 vcc, 2, v73
	s_nop 1
	v_cndmask_b32_e32 v74, v74, v45, vcc
	v_cmp_eq_u32_e32 vcc, 2, v8
	s_nop 1
	v_cndmask_b32_e32 v75, v75, v61, vcc
	v_cmp_eq_u32_e32 vcc, 3, v73
	s_nop 1
	v_cndmask_b32_e32 v74, v74, v44, vcc
	v_cmp_eq_u32_e32 vcc, 3, v8
	s_nop 1
	v_cndmask_b32_e32 v75, v75, v60, vcc
	v_cmp_eq_u32_e32 vcc, 4, v73
	s_nop 1
	v_cndmask_b32_e32 v74, v74, v43, vcc
	v_cmp_eq_u32_e32 vcc, 4, v8
	s_nop 1
	v_cndmask_b32_e32 v75, v75, v59, vcc
	v_cmp_eq_u32_e32 vcc, 5, v73
	s_nop 1
	v_cndmask_b32_e32 v74, v74, v42, vcc
	v_cmp_eq_u32_e32 vcc, 5, v8
	s_nop 1
	v_cndmask_b32_e32 v75, v75, v58, vcc
	v_cmp_eq_u32_e32 vcc, 6, v73
	s_nop 1
	v_cndmask_b32_e32 v74, v74, v41, vcc
	v_cmp_eq_u32_e32 vcc, 6, v8
	s_nop 1
	v_cndmask_b32_e32 v75, v75, v57, vcc
	v_cmp_eq_u32_e32 vcc, 7, v73
	s_nop 1
	v_cndmask_b32_e32 v74, v74, v40, vcc
	v_cmp_eq_u32_e32 vcc, 7, v8
	s_nop 1
	v_cndmask_b32_e32 v75, v75, v56, vcc
	v_cmp_eq_u32_e32 vcc, 8, v73
	s_nop 1
	v_cndmask_b32_e32 v74, v74, v39, vcc
	v_cmp_eq_u32_e32 vcc, 8, v8
	s_nop 1
	v_cndmask_b32_e32 v75, v75, v55, vcc
	v_cmp_eq_u32_e32 vcc, 9, v73
	s_nop 1
	v_cndmask_b32_e32 v74, v74, v38, vcc
	v_cmp_eq_u32_e32 vcc, 9, v8
	s_nop 1
	v_cndmask_b32_e32 v75, v75, v54, vcc
	v_cmp_eq_u32_e32 vcc, 10, v73
	s_nop 1
	v_cndmask_b32_e32 v74, v74, v37, vcc
	v_cmp_eq_u32_e32 vcc, 10, v8
	s_nop 1
	v_cndmask_b32_e32 v75, v75, v53, vcc
	v_cmp_eq_u32_e32 vcc, 11, v73
	s_nop 1
	v_cndmask_b32_e32 v74, v74, v36, vcc
	v_cmp_eq_u32_e32 vcc, 11, v8
	s_nop 1
	v_cndmask_b32_e32 v75, v75, v52, vcc
	v_cmp_eq_u32_e32 vcc, 12, v73
	s_nop 1
	v_cndmask_b32_e32 v74, v74, v35, vcc
	v_cmp_eq_u32_e32 vcc, 12, v8
	s_nop 1
	v_cndmask_b32_e32 v75, v75, v51, vcc
	v_cmp_eq_u32_e32 vcc, 13, v73
	s_nop 1
	v_cndmask_b32_e32 v74, v74, v34, vcc
	v_cmp_eq_u32_e32 vcc, 13, v8
	s_nop 1
	v_cndmask_b32_e32 v75, v75, v49, vcc
	v_cmp_eq_u32_e32 vcc, 14, v73
	s_nop 1
	v_cndmask_b32_e32 v74, v74, v33, vcc
	v_cmp_eq_u32_e32 vcc, 14, v8
	s_nop 1
	v_cndmask_b32_e32 v75, v75, v48, vcc
	v_cmp_eq_u32_e32 vcc, 15, v73
	s_nop 1
	v_cndmask_b32_e32 v73, v74, v15, vcc
	v_cmp_eq_u32_e32 vcc, 15, v8
	v_lshlrev_b32_e32 v73, 7, v73
	v_and_b32_e32 v73, 0x3f80, v73
	v_cndmask_b32_e32 v8, v75, v47, vcc
	v_and_b32_e32 v8, 0x7f, v8
	v_cmp_eq_u32_e32 vcc, 1, v72
	v_bitop3_b32 v8, v73, s70, v8 bitop3:0x36
	s_nop 0
	v_cndmask_b32_e32 v73, v50, v46, vcc
	v_cmp_eq_u32_e32 vcc, 1, v9
	s_nop 1
	v_cndmask_b32_e32 v74, v63, v62, vcc
	v_cmp_eq_u32_e32 vcc, 2, v72
	s_nop 1
	v_cndmask_b32_e32 v73, v73, v45, vcc
	v_cmp_eq_u32_e32 vcc, 2, v9
	s_nop 1
	v_cndmask_b32_e32 v74, v74, v61, vcc
	v_cmp_eq_u32_e32 vcc, 3, v72
	s_nop 1
	v_cndmask_b32_e32 v73, v73, v44, vcc
	v_cmp_eq_u32_e32 vcc, 3, v9
	s_nop 1
	v_cndmask_b32_e32 v74, v74, v60, vcc
	v_cmp_eq_u32_e32 vcc, 4, v72
	s_nop 1
	v_cndmask_b32_e32 v73, v73, v43, vcc
	v_cmp_eq_u32_e32 vcc, 4, v9
	s_nop 1
	v_cndmask_b32_e32 v74, v74, v59, vcc
	v_cmp_eq_u32_e32 vcc, 5, v72
	s_nop 1
	v_cndmask_b32_e32 v73, v73, v42, vcc
	v_cmp_eq_u32_e32 vcc, 5, v9
	s_nop 1
	v_cndmask_b32_e32 v74, v74, v58, vcc
	v_cmp_eq_u32_e32 vcc, 6, v72
	s_nop 1
	v_cndmask_b32_e32 v73, v73, v41, vcc
	v_cmp_eq_u32_e32 vcc, 6, v9
	s_nop 1
	v_cndmask_b32_e32 v74, v74, v57, vcc
	v_cmp_eq_u32_e32 vcc, 7, v72
	s_nop 1
	v_cndmask_b32_e32 v73, v73, v40, vcc
	v_cmp_eq_u32_e32 vcc, 7, v9
	s_nop 1
	v_cndmask_b32_e32 v74, v74, v56, vcc
	v_cmp_eq_u32_e32 vcc, 8, v72
	s_nop 1
	v_cndmask_b32_e32 v73, v73, v39, vcc
	v_cmp_eq_u32_e32 vcc, 8, v9
	s_nop 1
	v_cndmask_b32_e32 v74, v74, v55, vcc
	v_cmp_eq_u32_e32 vcc, 9, v72
	s_nop 1
	v_cndmask_b32_e32 v73, v73, v38, vcc
	v_cmp_eq_u32_e32 vcc, 9, v9
	s_nop 1
	v_cndmask_b32_e32 v74, v74, v54, vcc
	v_cmp_eq_u32_e32 vcc, 10, v72
	s_nop 1
	v_cndmask_b32_e32 v73, v73, v37, vcc
	v_cmp_eq_u32_e32 vcc, 10, v9
	s_nop 1
	v_cndmask_b32_e32 v74, v74, v53, vcc
	v_cmp_eq_u32_e32 vcc, 11, v72
	s_nop 1
	v_cndmask_b32_e32 v73, v73, v36, vcc
	v_cmp_eq_u32_e32 vcc, 11, v9
	s_nop 1
	v_cndmask_b32_e32 v74, v74, v52, vcc
	v_cmp_eq_u32_e32 vcc, 12, v72
	s_nop 1
	v_cndmask_b32_e32 v73, v73, v35, vcc
	v_cmp_eq_u32_e32 vcc, 12, v9
	s_nop 1
	v_cndmask_b32_e32 v74, v74, v51, vcc
	v_cmp_eq_u32_e32 vcc, 13, v72
	s_nop 1
	v_cndmask_b32_e32 v73, v73, v34, vcc
	v_cmp_eq_u32_e32 vcc, 13, v9
	s_nop 1
	v_cndmask_b32_e32 v74, v74, v49, vcc
	v_cmp_eq_u32_e32 vcc, 14, v72
	s_nop 1
	v_cndmask_b32_e32 v73, v73, v33, vcc
	v_cmp_eq_u32_e32 vcc, 14, v9
	s_nop 1
	v_cndmask_b32_e32 v74, v74, v48, vcc
	v_cmp_eq_u32_e32 vcc, 15, v72
	s_nop 1
	v_cndmask_b32_e32 v72, v73, v15, vcc
	v_cmp_eq_u32_e32 vcc, 15, v9
	v_lshlrev_b32_e32 v72, 7, v72
	v_and_b32_e32 v72, 0x3f80, v72
	v_cndmask_b32_e32 v9, v74, v47, vcc
	v_and_b32_e32 v9, 0x7f, v9
	v_cmp_eq_u32_e32 vcc, 1, v71
	v_bitop3_b32 v9, v72, s70, v9 bitop3:0x36
	s_nop 0
	v_cndmask_b32_e32 v72, v50, v46, vcc
	v_cmp_eq_u32_e32 vcc, 1, v10
	s_nop 1
	v_cndmask_b32_e32 v73, v63, v62, vcc
	v_cmp_eq_u32_e32 vcc, 2, v71
	s_nop 1
; __device__ __forceinline__ void route_task(const Params& p, int layer, const u16* qg, int rb, int hd, int r, int h) {
;     ...
;     for (int jj = 0; jj < 16; ++jj) {
;       const unsigned flat = 255u - (ct[jj] & 255u);
;       const unsigned a = flat >> 4, b = flat & 15u;
;       unsigned ka = top[0][0], kb = top[1][0];
; #pragma unroll
;       for (int k = 1; k < 16; ++k) { ka = (a == (unsigned)k) ? top[0][k] : ka; kb = (b == (unsigned)k) ? top[1][k] : kb; }
;       eo[jj] = (127u - (ka & 127u)) * 128u + (127u - (kb & 127u));
;     }
	v_cndmask_b32_e32 v72, v72, v45, vcc
	v_cmp_eq_u32_e32 vcc, 2, v10
	s_nop 1
	v_cndmask_b32_e32 v73, v73, v61, vcc
	v_cmp_eq_u32_e32 vcc, 3, v71
	s_nop 1
	v_cndmask_b32_e32 v72, v72, v44, vcc
	v_cmp_eq_u32_e32 vcc, 3, v10
	s_nop 1
	v_cndmask_b32_e32 v73, v73, v60, vcc
	v_cmp_eq_u32_e32 vcc, 4, v71
	s_nop 1
	v_cndmask_b32_e32 v72, v72, v43, vcc
	v_cmp_eq_u32_e32 vcc, 4, v10
	s_nop 1
	v_cndmask_b32_e32 v73, v73, v59, vcc
	v_cmp_eq_u32_e32 vcc, 5, v71
	s_nop 1
	v_cndmask_b32_e32 v72, v72, v42, vcc
	v_cmp_eq_u32_e32 vcc, 5, v10
	s_nop 1
	v_cndmask_b32_e32 v73, v73, v58, vcc
	v_cmp_eq_u32_e32 vcc, 6, v71
	s_nop 1
	v_cndmask_b32_e32 v72, v72, v41, vcc
	v_cmp_eq_u32_e32 vcc, 6, v10
	s_nop 1
	v_cndmask_b32_e32 v73, v73, v57, vcc
	v_cmp_eq_u32_e32 vcc, 7, v71
	s_nop 1
	v_cndmask_b32_e32 v72, v72, v40, vcc
	v_cmp_eq_u32_e32 vcc, 7, v10
	s_nop 1
	v_cndmask_b32_e32 v73, v73, v56, vcc
	v_cmp_eq_u32_e32 vcc, 8, v71
	s_nop 1
	v_cndmask_b32_e32 v72, v72, v39, vcc
	v_cmp_eq_u32_e32 vcc, 8, v10
	s_nop 1
	v_cndmask_b32_e32 v73, v73, v55, vcc
	v_cmp_eq_u32_e32 vcc, 9, v71
	s_nop 1
	v_cndmask_b32_e32 v72, v72, v38, vcc
	v_cmp_eq_u32_e32 vcc, 9, v10
	s_nop 1
	v_cndmask_b32_e32 v73, v73, v54, vcc
	v_cmp_eq_u32_e32 vcc, 10, v71
	s_nop 1
	v_cndmask_b32_e32 v72, v72, v37, vcc
	v_cmp_eq_u32_e32 vcc, 10, v10
	s_nop 1
	v_cndmask_b32_e32 v73, v73, v53, vcc
	v_cmp_eq_u32_e32 vcc, 11, v71
	s_nop 1
	v_cndmask_b32_e32 v72, v72, v36, vcc
	v_cmp_eq_u32_e32 vcc, 11, v10
	s_nop 1
	v_cndmask_b32_e32 v73, v73, v52, vcc
	v_cmp_eq_u32_e32 vcc, 12, v71
	s_nop 1
	v_cndmask_b32_e32 v72, v72, v35, vcc
	v_cmp_eq_u32_e32 vcc, 12, v10
	s_nop 1
	v_cndmask_b32_e32 v73, v73, v51, vcc
	v_cmp_eq_u32_e32 vcc, 13, v71
	s_nop 1
	v_cndmask_b32_e32 v72, v72, v34, vcc
	v_cmp_eq_u32_e32 vcc, 13, v10
	s_nop 1
	v_cndmask_b32_e32 v73, v73, v49, vcc
	v_cmp_eq_u32_e32 vcc, 14, v71
	s_nop 1
	v_cndmask_b32_e32 v72, v72, v33, vcc
	v_cmp_eq_u32_e32 vcc, 14, v10
	s_nop 1
	v_cndmask_b32_e32 v73, v73, v48, vcc
	v_cmp_eq_u32_e32 vcc, 15, v71
	s_nop 1
	v_cndmask_b32_e32 v71, v72, v15, vcc
	v_cmp_eq_u32_e32 vcc, 15, v10
	v_lshlrev_b32_e32 v71, 7, v71
	v_and_b32_e32 v71, 0x3f80, v71
	v_cndmask_b32_e32 v10, v73, v47, vcc
	v_and_b32_e32 v10, 0x7f, v10
	v_cmp_eq_u32_e32 vcc, 1, v70
	v_bitop3_b32 v10, v71, s70, v10 bitop3:0x36
	s_nop 0
	v_cndmask_b32_e32 v71, v50, v46, vcc
	v_cmp_eq_u32_e32 vcc, 1, v11
	s_nop 1
	v_cndmask_b32_e32 v72, v63, v62, vcc
	v_cmp_eq_u32_e32 vcc, 2, v70
	s_nop 1
	v_cndmask_b32_e32 v71, v71, v45, vcc
	v_cmp_eq_u32_e32 vcc, 2, v11
	s_nop 1
	v_cndmask_b32_e32 v72, v72, v61, vcc
	v_cmp_eq_u32_e32 vcc, 3, v70
	s_nop 1
	v_cndmask_b32_e32 v71, v71, v44, vcc
	v_cmp_eq_u32_e32 vcc, 3, v11
	s_nop 1
	v_cndmask_b32_e32 v72, v72, v60, vcc
	v_cmp_eq_u32_e32 vcc, 4, v70
	s_nop 1
	v_cndmask_b32_e32 v71, v71, v43, vcc
	v_cmp_eq_u32_e32 vcc, 4, v11
	s_nop 1
	v_cndmask_b32_e32 v72, v72, v59, vcc
	v_cmp_eq_u32_e32 vcc, 5, v70
	s_nop 1
	v_cndmask_b32_e32 v71, v71, v42, vcc
	v_cmp_eq_u32_e32 vcc, 5, v11
	s_nop 1
	v_cndmask_b32_e32 v72, v72, v58, vcc
	v_cmp_eq_u32_e32 vcc, 6, v70
	s_nop 1
	v_cndmask_b32_e32 v71, v71, v41, vcc
	v_cmp_eq_u32_e32 vcc, 6, v11
	s_nop 1
	v_cndmask_b32_e32 v72, v72, v57, vcc
	v_cmp_eq_u32_e32 vcc, 7, v70
	s_nop 1
	v_cndmask_b32_e32 v71, v71, v40, vcc
	v_cmp_eq_u32_e32 vcc, 7, v11
	s_nop 1
	v_cndmask_b32_e32 v72, v72, v56, vcc
	v_cmp_eq_u32_e32 vcc, 8, v70
	s_nop 1
	v_cndmask_b32_e32 v71, v71, v39, vcc
	v_cmp_eq_u32_e32 vcc, 8, v11
	s_nop 1
	v_cndmask_b32_e32 v72, v72, v55, vcc
	v_cmp_eq_u32_e32 vcc, 9, v70
	s_nop 1
	v_cndmask_b32_e32 v71, v71, v38, vcc
	v_cmp_eq_u32_e32 vcc, 9, v11
	s_nop 1
	v_cndmask_b32_e32 v72, v72, v54, vcc
	v_cmp_eq_u32_e32 vcc, 10, v70
	s_nop 1
	v_cndmask_b32_e32 v71, v71, v37, vcc
	v_cmp_eq_u32_e32 vcc, 10, v11
	s_nop 1
	v_cndmask_b32_e32 v72, v72, v53, vcc
	v_cmp_eq_u32_e32 vcc, 11, v70
	s_nop 1
	v_cndmask_b32_e32 v71, v71, v36, vcc
	v_cmp_eq_u32_e32 vcc, 11, v11
	s_nop 1
	v_cndmask_b32_e32 v72, v72, v52, vcc
	v_cmp_eq_u32_e32 vcc, 12, v70
	s_nop 1
	v_cndmask_b32_e32 v71, v71, v35, vcc
	v_cmp_eq_u32_e32 vcc, 12, v11
	s_nop 1
	v_cndmask_b32_e32 v72, v72, v51, vcc
	v_cmp_eq_u32_e32 vcc, 13, v70
	s_nop 1
	v_cndmask_b32_e32 v71, v71, v34, vcc
	v_cmp_eq_u32_e32 vcc, 13, v11
	s_nop 1
	v_cndmask_b32_e32 v72, v72, v49, vcc
	v_cmp_eq_u32_e32 vcc, 14, v70
	s_nop 1
	v_cndmask_b32_e32 v71, v71, v33, vcc
	v_cmp_eq_u32_e32 vcc, 14, v11
	s_nop 1
	v_cndmask_b32_e32 v72, v72, v48, vcc
	v_cmp_eq_u32_e32 vcc, 15, v70
	s_nop 1
	v_cndmask_b32_e32 v70, v71, v15, vcc
	v_cmp_eq_u32_e32 vcc, 15, v11
	v_lshlrev_b32_e32 v70, 7, v70
	v_and_b32_e32 v70, 0x3f80, v70
	v_cndmask_b32_e32 v11, v72, v47, vcc
	v_and_b32_e32 v11, 0x7f, v11
	v_cmp_eq_u32_e32 vcc, 1, v69
	v_bitop3_b32 v11, v70, s70, v11 bitop3:0x36
	s_nop 0
	v_cndmask_b32_e32 v70, v50, v46, vcc
	v_cmp_eq_u32_e32 vcc, 1, v12
	s_nop 1
	v_cndmask_b32_e32 v71, v63, v62, vcc
	v_cmp_eq_u32_e32 vcc, 2, v69
	s_nop 1
	v_cndmask_b32_e32 v70, v70, v45, vcc
	v_cmp_eq_u32_e32 vcc, 2, v12
	s_nop 1
	v_cndmask_b32_e32 v71, v71, v61, vcc
	v_cmp_eq_u32_e32 vcc, 3, v69
	s_nop 1
	v_cndmask_b32_e32 v70, v70, v44, vcc
	v_cmp_eq_u32_e32 vcc, 3, v12
	s_nop 1
	v_cndmask_b32_e32 v71, v71, v60, vcc
	v_cmp_eq_u32_e32 vcc, 4, v69
	s_nop 1
	v_cndmask_b32_e32 v70, v70, v43, vcc
	v_cmp_eq_u32_e32 vcc, 4, v12
	s_nop 1
	v_cndmask_b32_e32 v71, v71, v59, vcc
	v_cmp_eq_u32_e32 vcc, 5, v69
	s_nop 1
	v_cndmask_b32_e32 v70, v70, v42, vcc
	v_cmp_eq_u32_e32 vcc, 5, v12
	s_nop 1
	v_cndmask_b32_e32 v71, v71, v58, vcc
	v_cmp_eq_u32_e32 vcc, 6, v69
	s_nop 1
	v_cndmask_b32_e32 v70, v70, v41, vcc
	v_cmp_eq_u32_e32 vcc, 6, v12
	s_nop 1
	v_cndmask_b32_e32 v71, v71, v57, vcc
; __device__ __forceinline__ void route_task(const Params& p, int layer, const u16* qg, int rb, int hd, int r, int h) {
;     ...
;     for (int jj = 0; jj < 16; ++jj) {
;       const unsigned flat = 255u - (ct[jj] & 255u);
;       const unsigned a = flat >> 4, b = flat & 15u;
;       unsigned ka = top[0][0], kb = top[1][0];
; #pragma unroll
;       for (int k = 1; k < 16; ++k) { ka = (a == (unsigned)k) ? top[0][k] : ka; kb = (b == (unsigned)k) ? top[1][k] : kb; }
;       eo[jj] = (127u - (ka & 127u)) * 128u + (127u - (kb & 127u));
;     }
	v_cmp_eq_u32_e32 vcc, 7, v69
	s_nop 1
	v_cndmask_b32_e32 v70, v70, v40, vcc
	v_cmp_eq_u32_e32 vcc, 7, v12
	s_nop 1
	v_cndmask_b32_e32 v71, v71, v56, vcc
	v_cmp_eq_u32_e32 vcc, 8, v69
	s_nop 1
	v_cndmask_b32_e32 v70, v70, v39, vcc
	v_cmp_eq_u32_e32 vcc, 8, v12
	s_nop 1
	v_cndmask_b32_e32 v71, v71, v55, vcc
	v_cmp_eq_u32_e32 vcc, 9, v69
	s_nop 1
	v_cndmask_b32_e32 v70, v70, v38, vcc
	v_cmp_eq_u32_e32 vcc, 9, v12
	s_nop 1
	v_cndmask_b32_e32 v71, v71, v54, vcc
	v_cmp_eq_u32_e32 vcc, 10, v69
	s_nop 1
	v_cndmask_b32_e32 v70, v70, v37, vcc
	v_cmp_eq_u32_e32 vcc, 10, v12
	s_nop 1
	v_cndmask_b32_e32 v71, v71, v53, vcc
	v_cmp_eq_u32_e32 vcc, 11, v69
	s_nop 1
	v_cndmask_b32_e32 v70, v70, v36, vcc
	v_cmp_eq_u32_e32 vcc, 11, v12
	s_nop 1
	v_cndmask_b32_e32 v71, v71, v52, vcc
	v_cmp_eq_u32_e32 vcc, 12, v69
	s_nop 1
	v_cndmask_b32_e32 v70, v70, v35, vcc
	v_cmp_eq_u32_e32 vcc, 12, v12
	s_nop 1
	v_cndmask_b32_e32 v71, v71, v51, vcc
	v_cmp_eq_u32_e32 vcc, 13, v69
	s_nop 1
	v_cndmask_b32_e32 v70, v70, v34, vcc
	v_cmp_eq_u32_e32 vcc, 13, v12
	s_nop 1
	v_cndmask_b32_e32 v71, v71, v49, vcc
	v_cmp_eq_u32_e32 vcc, 14, v69
	s_nop 1
	v_cndmask_b32_e32 v70, v70, v33, vcc
	v_cmp_eq_u32_e32 vcc, 14, v12
	s_nop 1
	v_cndmask_b32_e32 v71, v71, v48, vcc
	v_cmp_eq_u32_e32 vcc, 15, v69
	s_nop 1
	v_cndmask_b32_e32 v69, v70, v15, vcc
	v_cmp_eq_u32_e32 vcc, 15, v12
	v_lshlrev_b32_e32 v69, 7, v69
	v_and_b32_e32 v69, 0x3f80, v69
	v_cndmask_b32_e32 v12, v71, v47, vcc
	v_and_b32_e32 v12, 0x7f, v12
	v_cmp_eq_u32_e32 vcc, 1, v68
	v_bitop3_b32 v12, v69, s70, v12 bitop3:0x36
	s_nop 0
	v_cndmask_b32_e32 v69, v50, v46, vcc
	v_cmp_eq_u32_e32 vcc, 1, v13
	s_nop 1
	v_cndmask_b32_e32 v70, v63, v62, vcc
	v_cmp_eq_u32_e32 vcc, 2, v68
	s_nop 1
	v_cndmask_b32_e32 v69, v69, v45, vcc
	v_cmp_eq_u32_e32 vcc, 2, v13
	s_nop 1
	v_cndmask_b32_e32 v70, v70, v61, vcc
	v_cmp_eq_u32_e32 vcc, 3, v68
	s_nop 1
	v_cndmask_b32_e32 v69, v69, v44, vcc
	v_cmp_eq_u32_e32 vcc, 3, v13
	s_nop 1
	v_cndmask_b32_e32 v70, v70, v60, vcc
	v_cmp_eq_u32_e32 vcc, 4, v68
	s_nop 1
	v_cndmask_b32_e32 v69, v69, v43, vcc
	v_cmp_eq_u32_e32 vcc, 4, v13
	s_nop 1
	v_cndmask_b32_e32 v70, v70, v59, vcc
	v_cmp_eq_u32_e32 vcc, 5, v68
	s_nop 1
	v_cndmask_b32_e32 v69, v69, v42, vcc
	v_cmp_eq_u32_e32 vcc, 5, v13
	s_nop 1
	v_cndmask_b32_e32 v70, v70, v58, vcc
	v_cmp_eq_u32_e32 vcc, 6, v68
	s_nop 1
	v_cndmask_b32_e32 v69, v69, v41, vcc
	v_cmp_eq_u32_e32 vcc, 6, v13
	s_nop 1
	v_cndmask_b32_e32 v70, v70, v57, vcc
	v_cmp_eq_u32_e32 vcc, 7, v68
	s_nop 1
	v_cndmask_b32_e32 v69, v69, v40, vcc
	v_cmp_eq_u32_e32 vcc, 7, v13
	s_nop 1
	v_cndmask_b32_e32 v70, v70, v56, vcc
	v_cmp_eq_u32_e32 vcc, 8, v68
	s_nop 1
	v_cndmask_b32_e32 v69, v69, v39, vcc
	v_cmp_eq_u32_e32 vcc, 8, v13
	s_nop 1
	v_cndmask_b32_e32 v70, v70, v55, vcc
	v_cmp_eq_u32_e32 vcc, 9, v68
	s_nop 1
	v_cndmask_b32_e32 v69, v69, v38, vcc
	v_cmp_eq_u32_e32 vcc, 9, v13
	s_nop 1
	v_cndmask_b32_e32 v70, v70, v54, vcc
	v_cmp_eq_u32_e32 vcc, 10, v68
	s_nop 1
	v_cndmask_b32_e32 v69, v69, v37, vcc
	v_cmp_eq_u32_e32 vcc, 10, v13
	s_nop 1
	v_cndmask_b32_e32 v70, v70, v53, vcc
	v_cmp_eq_u32_e32 vcc, 11, v68
	s_nop 1
	v_cndmask_b32_e32 v69, v69, v36, vcc
	v_cmp_eq_u32_e32 vcc, 11, v13
	s_nop 1
	v_cndmask_b32_e32 v70, v70, v52, vcc
	v_cmp_eq_u32_e32 vcc, 12, v68
	s_nop 1
	v_cndmask_b32_e32 v69, v69, v35, vcc
	v_cmp_eq_u32_e32 vcc, 12, v13
	s_nop 1
	v_cndmask_b32_e32 v70, v70, v51, vcc
	v_cmp_eq_u32_e32 vcc, 13, v68
	s_nop 1
	v_cndmask_b32_e32 v69, v69, v34, vcc
	v_cmp_eq_u32_e32 vcc, 13, v13
	s_nop 1
	v_cndmask_b32_e32 v70, v70, v49, vcc
	v_cmp_eq_u32_e32 vcc, 14, v68
	s_nop 1
	v_cndmask_b32_e32 v69, v69, v33, vcc
	v_cmp_eq_u32_e32 vcc, 14, v13
	s_nop 1
	v_cndmask_b32_e32 v70, v70, v48, vcc
	v_cmp_eq_u32_e32 vcc, 15, v68
	s_nop 1
	v_cndmask_b32_e32 v68, v69, v15, vcc
	v_cmp_eq_u32_e32 vcc, 15, v13
	v_lshlrev_b32_e32 v68, 7, v68
	v_and_b32_e32 v68, 0x3f80, v68
	v_cndmask_b32_e32 v13, v70, v47, vcc
	v_and_b32_e32 v13, 0x7f, v13
	v_cmp_eq_u32_e32 vcc, 1, v66
	v_bitop3_b32 v13, v68, s70, v13 bitop3:0x36
	s_nop 0
	v_cndmask_b32_e32 v68, v50, v46, vcc
	v_cmp_eq_u32_e32 vcc, 1, v14
	s_nop 1
	v_cndmask_b32_e32 v69, v63, v62, vcc
	v_cmp_eq_u32_e32 vcc, 2, v66
	s_nop 1
	v_cndmask_b32_e32 v68, v68, v45, vcc
	v_cmp_eq_u32_e32 vcc, 2, v14
	s_nop 1
	v_cndmask_b32_e32 v69, v69, v61, vcc
	v_cmp_eq_u32_e32 vcc, 3, v66
	s_nop 1
	v_cndmask_b32_e32 v68, v68, v44, vcc
	v_cmp_eq_u32_e32 vcc, 3, v14
	s_nop 1
	v_cndmask_b32_e32 v69, v69, v60, vcc
	v_cmp_eq_u32_e32 vcc, 4, v66
	s_nop 1
	v_cndmask_b32_e32 v68, v68, v43, vcc
	v_cmp_eq_u32_e32 vcc, 4, v14
	s_nop 1
	v_cndmask_b32_e32 v69, v69, v59, vcc
	v_cmp_eq_u32_e32 vcc, 5, v66
	s_nop 1
	v_cndmask_b32_e32 v68, v68, v42, vcc
	v_cmp_eq_u32_e32 vcc, 5, v14
	s_nop 1
	v_cndmask_b32_e32 v69, v69, v58, vcc
	v_cmp_eq_u32_e32 vcc, 6, v66
	s_nop 1
	v_cndmask_b32_e32 v68, v68, v41, vcc
	v_cmp_eq_u32_e32 vcc, 6, v14
	s_nop 1
	v_cndmask_b32_e32 v69, v69, v57, vcc
	v_cmp_eq_u32_e32 vcc, 7, v66
	s_nop 1
	v_cndmask_b32_e32 v68, v68, v40, vcc
	v_cmp_eq_u32_e32 vcc, 7, v14
	s_nop 1
	v_cndmask_b32_e32 v69, v69, v56, vcc
	v_cmp_eq_u32_e32 vcc, 8, v66
	s_nop 1
	v_cndmask_b32_e32 v68, v68, v39, vcc
	v_cmp_eq_u32_e32 vcc, 8, v14
	s_nop 1
	v_cndmask_b32_e32 v69, v69, v55, vcc
	v_cmp_eq_u32_e32 vcc, 9, v66
; __device__ __forceinline__ void route_task(const Params& p, int layer, const u16* qg, int rb, int hd, int r, int h) {
;     ...
;     const float inv = 1.f / den;
;     unsigned eo[16];
; #pragma unroll
;     for (int jj = 0; jj < 16; ++jj) {
;       const unsigned flat = 255u - (ct[jj] & 255u);
;       const unsigned a = flat >> 4, b = flat & 15u;
;       unsigned ka = top[0][0], kb = top[1][0];
; #pragma unroll
;       for (int k = 1; k < 16; ++k) { ka = (a == (unsigned)k) ? top[0][k] : ka; kb = (b == (unsigned)k) ? top[1][k] : kb; }
;       eo[jj] = (127u - (ka & 127u)) * 128u + (127u - (kb & 127u));
;     }
;     const size_t ob = (size_t)(rb + r) * 128 + hd * 16;
; #pragma unroll
;     for (int g4 = 0; g4 < 4; ++g4) {
;       *(u32x4*)(EX + ob + g4 * 4) = u32x4{eo[g4 * 4], eo[g4 * 4 + 1], eo[g4 * 4 + 2], eo[g4 * 4 + 3]};
;       *(f32x4*)(GT + ob + g4 * 4) = f32x4{vs[g4 * 4] * inv, vs[g4 * 4 + 1] * inv, vs[g4 * 4 + 2] * inv, vs[g4 * 4 + 3] * inv};
;     }
	s_nop 1
	v_cndmask_b32_e32 v68, v68, v38, vcc
	v_cmp_eq_u32_e32 vcc, 9, v14
	s_nop 1
	v_cndmask_b32_e32 v69, v69, v54, vcc
	v_cmp_eq_u32_e32 vcc, 10, v66
	s_nop 1
	v_cndmask_b32_e32 v68, v68, v37, vcc
	v_cmp_eq_u32_e32 vcc, 10, v14
	s_nop 1
	v_cndmask_b32_e32 v69, v69, v53, vcc
	v_cmp_eq_u32_e32 vcc, 11, v66
	s_nop 1
	v_cndmask_b32_e32 v68, v68, v36, vcc
	v_cmp_eq_u32_e32 vcc, 11, v14
	s_nop 1
	v_cndmask_b32_e32 v69, v69, v52, vcc
	v_cmp_eq_u32_e32 vcc, 12, v66
	s_nop 1
	v_cndmask_b32_e32 v68, v68, v35, vcc
	v_cmp_eq_u32_e32 vcc, 12, v14
	s_nop 1
	v_cndmask_b32_e32 v69, v69, v51, vcc
	v_cmp_eq_u32_e32 vcc, 13, v66
	s_nop 1
	v_cndmask_b32_e32 v68, v68, v34, vcc
	v_cmp_eq_u32_e32 vcc, 13, v14
	s_nop 1
	v_cndmask_b32_e32 v69, v69, v49, vcc
	v_cmp_eq_u32_e32 vcc, 14, v66
	s_nop 1
	v_cndmask_b32_e32 v68, v68, v33, vcc
	v_cmp_eq_u32_e32 vcc, 14, v14
	s_nop 1
	v_cndmask_b32_e32 v69, v69, v48, vcc
	v_cmp_eq_u32_e32 vcc, 15, v66
	s_nop 1
	v_cndmask_b32_e32 v66, v68, v15, vcc
	v_cmp_eq_u32_e32 vcc, 15, v14
	v_lshlrev_b32_e32 v66, 7, v66
	v_and_b32_e32 v66, 0x3f80, v66
	v_cndmask_b32_e32 v14, v69, v47, vcc
	v_cmp_eq_u32_e32 vcc, 1, v65
	v_and_b32_e32 v14, 0x7f, v14
	v_bitop3_b32 v14, v66, s70, v14 bitop3:0x36
	v_cndmask_b32_e32 v46, v50, v46, vcc
	v_cmp_eq_u32_e32 vcc, 1, v64
	s_nop 1
	v_cndmask_b32_e32 v50, v63, v62, vcc
	v_cmp_eq_u32_e32 vcc, 2, v65
	s_nop 1
	v_cndmask_b32_e32 v45, v46, v45, vcc
	v_cmp_eq_u32_e32 vcc, 2, v64
	s_nop 1
	v_cndmask_b32_e32 v46, v50, v61, vcc
	v_cmp_eq_u32_e32 vcc, 3, v65
	s_nop 1
	v_cndmask_b32_e32 v44, v45, v44, vcc
	v_cmp_eq_u32_e32 vcc, 3, v64
	s_nop 1
	v_cndmask_b32_e32 v45, v46, v60, vcc
	v_cmp_eq_u32_e32 vcc, 4, v65
	s_nop 1
	v_cndmask_b32_e32 v43, v44, v43, vcc
	v_cmp_eq_u32_e32 vcc, 4, v64
	s_nop 1
	v_cndmask_b32_e32 v44, v45, v59, vcc
	v_cmp_eq_u32_e32 vcc, 5, v65
	s_nop 1
	v_cndmask_b32_e32 v42, v43, v42, vcc
	v_cmp_eq_u32_e32 vcc, 5, v64
	s_nop 1
	v_cndmask_b32_e32 v43, v44, v58, vcc
	v_cmp_eq_u32_e32 vcc, 6, v65
	s_nop 1
	v_cndmask_b32_e32 v41, v42, v41, vcc
	v_cmp_eq_u32_e32 vcc, 6, v64
	s_nop 1
	v_cndmask_b32_e32 v42, v43, v57, vcc
	v_cmp_eq_u32_e32 vcc, 7, v65
	s_nop 1
	v_cndmask_b32_e32 v40, v41, v40, vcc
	v_cmp_eq_u32_e32 vcc, 7, v64
	s_nop 1
	v_cndmask_b32_e32 v41, v42, v56, vcc
	v_cmp_eq_u32_e32 vcc, 8, v65
	s_nop 1
	v_cndmask_b32_e32 v39, v40, v39, vcc
	v_cmp_eq_u32_e32 vcc, 8, v64
	s_nop 1
	v_cndmask_b32_e32 v40, v41, v55, vcc
	v_cmp_eq_u32_e32 vcc, 9, v65
	s_nop 1
	v_cndmask_b32_e32 v38, v39, v38, vcc
	v_cmp_eq_u32_e32 vcc, 9, v64
	s_nop 1
	v_cndmask_b32_e32 v39, v40, v54, vcc
	v_cmp_eq_u32_e32 vcc, 10, v65
	s_nop 1
	v_cndmask_b32_e32 v37, v38, v37, vcc
	v_cmp_eq_u32_e32 vcc, 10, v64
	s_nop 1
	v_cndmask_b32_e32 v38, v39, v53, vcc
	v_cmp_eq_u32_e32 vcc, 11, v65
	s_nop 1
	v_cndmask_b32_e32 v36, v37, v36, vcc
	v_cmp_eq_u32_e32 vcc, 11, v64
	s_nop 1
	v_cndmask_b32_e32 v37, v38, v52, vcc
	v_cmp_eq_u32_e32 vcc, 12, v65
	s_nop 1
	v_cndmask_b32_e32 v35, v36, v35, vcc
	v_cmp_eq_u32_e32 vcc, 12, v64
	s_nop 1
	v_cndmask_b32_e32 v36, v37, v51, vcc
	v_cmp_eq_u32_e32 vcc, 13, v65
	s_nop 1
	v_cndmask_b32_e32 v34, v35, v34, vcc
	v_cmp_eq_u32_e32 vcc, 13, v64
	s_nop 1
	v_cndmask_b32_e32 v35, v36, v49, vcc
	v_cmp_eq_u32_e32 vcc, 14, v65
	s_nop 1
	v_cndmask_b32_e32 v33, v34, v33, vcc
	v_cmp_eq_u32_e32 vcc, 14, v64
	s_nop 1
	v_cndmask_b32_e32 v34, v35, v48, vcc
	v_cmp_eq_u32_e32 vcc, 15, v65
	s_nop 1
	v_cndmask_b32_e32 v15, v33, v15, vcc
	v_cmp_eq_u32_e32 vcc, 15, v64
	v_lshlrev_b32_e32 v15, 7, v15
	v_and_b32_e32 v15, 0x3f80, v15
	v_cndmask_b32_e32 v33, v34, v47, vcc
	v_div_scale_f32 v34, s[34:35], v67, v67, 1.0
	v_rcp_f32_e32 v35, v34
	v_and_b32_e32 v33, 0x7f, v33
	v_bitop3_b32 v15, v15, s70, v33 bitop3:0x36
	s_lshl_b32 s34, s72, 4
	v_fma_f32 v33, -v34, v35, 1.0
	v_fmac_f32_e32 v35, v33, v35
	v_div_scale_f32 v33, vcc, 1.0, v67, 1.0
	v_mul_f32_e32 v36, v33, v35
	v_fma_f32 v37, -v34, v36, v33
	v_fmac_f32_e32 v36, v37, v35
	v_fma_f32 v33, -v34, v36, v33
	v_div_fmas_f32 v33, v33, v35, v36
	v_div_fixup_f32 v34, v33, v67, 1.0
	v_ashrrev_i32_e32 v33, 31, v32
	v_lshlrev_b64 v[32:33], 7, v[32:33]
	s_ashr_i32 s35, s34, 31
	v_lshl_add_u64 v[32:33], v[32:33], 0, s[34:35]
	v_lshlrev_b64 v[32:33], 2, v[32:33]
	v_lshl_add_u64 v[36:37], s[8:9], 0, v[32:33]
	v_lshl_add_u64 v[32:33], s[6:7], 0, v[32:33]
	global_store_dwordx4 v[36:37], v[0:3], off
	s_nop 1
	v_pk_mul_f32 v[2:3], v[18:19], v[34:35] op_sel_hi:[1,0]
	v_pk_mul_f32 v[0:1], v[16:17], v[34:35] op_sel_hi:[1,0]
	global_store_dwordx4 v[32:33], v[0:3], off
	global_store_dwordx4 v[36:37], v[4:7], off offset:16
	s_nop 0
	v_pk_mul_f32 v[2:3], v[22:23], v[34:35] op_sel_hi:[1,0]
	v_pk_mul_f32 v[0:1], v[20:21], v[34:35] op_sel_hi:[1,0]
	global_store_dwordx4 v[32:33], v[0:3], off offset:16
	global_store_dwordx4 v[36:37], v[8:11], off offset:32
	s_nop 0
	v_pk_mul_f32 v[2:3], v[26:27], v[34:35] op_sel_hi:[1,0]
	v_pk_mul_f32 v[0:1], v[24:25], v[34:35] op_sel_hi:[1,0]
	global_store_dwordx4 v[32:33], v[0:3], off offset:32
	global_store_dwordx4 v[36:37], v[12:15], off offset:48
	s_nop 0
	v_pk_mul_f32 v[2:3], v[30:31], v[34:35] op_sel_hi:[1,0]
	v_pk_mul_f32 v[0:1], v[28:29], v[34:35] op_sel_hi:[1,0]
	global_store_dwordx4 v[32:33], v[0:3], off offset:48
	s_branch .LBB0_2495
